# sign-splat fold added inside the pad-rule-compliant pipeline (hazpad + operand swap after it)
# baseline (speedup 1.0000x reference)
.LBB0_134:
	global_load_dword v6, v[22:23], off
	v_lshrrev_b32_e32 v26, 2, v11
	v_add_u32_e32 v25, 0x200, v25
	v_and_b32_e32 v26, 0x3ffffff8, v26
	v_cmp_lt_u32_e32 vcc, s34, v25
	v_add_u32_e32 v11, 8, v11
	v_lshl_add_u64 v[22:23], v[22:23], 0, s[26:27]
	v_add_u32_e32 v26, v24, v26
	v_add_u32_e32 v24, 64, v24
	s_or_b64 s[62:63], vcc, s[62:63]
	s_waitcnt vmcnt(0)
	ds_write_b64 v26, v[6:7]
	s_andn2_b64 exec, exec, s[62:63]
	s_cbranch_execnz .LBB0_134
	s_or_b64 exec, exec, s[62:63]
	v_mov_b32_e32 v6, v62
	s_waitcnt lgkmcnt(0)
	s_barrier
	s_mov_b32 s43, s40
	v_and_b32_e32 v11, 15, v6
	v_cvt_f32_ubyte0_e32 v22, v11
	v_mul_f32_e32 v23, 0x3b800000, v22
	v_sin_f32_e32 v22, v23
	v_cos_f32_e32 v24, v23
	v_lshlrev_b32_e32 v6, 4, v6
	v_and_b32_e32 v6, 0xffffff00, v6
	v_xor_b32_e32 v25, 0x80000000, v22
	v_mov_b32_e32 v23, v25
	v_pk_mul_f32 v[26:27], v[24:25], v[22:23] op_sel:[1,0] op_sel_hi:[0,1]
	v_pk_fma_f32 v[26:27], v[24:25], v[24:25], v[26:27] op_sel_hi:[1,0,1]
	v_lshlrev_b32_e32 v11, 3, v11
	v_pk_mul_f32 v[30:31], v[26:27], v[26:27] op_sel:[1,1] op_sel_hi:[0,1] neg_lo:[0,1]
	v_pk_fma_f32 v[30:31], v[26:27], v[26:27], v[30:31] op_sel_hi:[1,0,1]
	v_pk_mul_f32 v[28:29], v[22:23], v[26:27] op_sel:[0,1] op_sel_hi:[1,0]
	v_pk_mul_f32 v[50:51], v[30:31], v[30:31] op_sel:[1,1] op_sel_hi:[0,1] neg_lo:[0,1]
	v_pk_fma_f32 v[50:51], v[30:31], v[30:31], v[50:51] op_sel_hi:[1,0,1]
	v_pk_mul_f32 v[36:37], v[22:23], v[30:31] op_sel:[0,1] op_sel_hi:[1,0]
	v_pk_mul_f32 v[70:71], v[30:31], v[50:51] op_sel:[1,1] op_sel_hi:[1,0] neg_lo:[1,0]
	v_pk_mul_f32 v[54:55], v[22:23], v[50:51] op_sel:[0,1] op_sel_hi:[1,0]
	v_pk_fma_f32 v[70:71], v[30:31], v[50:51], v[70:71] op_sel_hi:[0,1,1]
	v_pk_mul_f32 v[74:75], v[22:23], v[70:71] op_sel:[0,1] op_sel_hi:[1,0]
	v_pk_fma_f32 v[28:29], v[24:25], v[26:27], v[28:29] op_sel_hi:[0,1,1]
	v_pk_fma_f32 v[36:37], v[24:25], v[30:31], v[36:37] op_sel_hi:[0,1,1]
	v_pk_fma_f32 v[54:55], v[24:25], v[50:51], v[54:55] op_sel_hi:[0,1,1]
	v_pk_fma_f32 v[74:75], v[24:25], v[70:71], v[74:75] op_sel_hi:[0,1,1]
	v_lshlrev_b32_e32 v25, 3, v6
	v_add3_u32 v11, 0, v11, v25
	v_ashrrev_i32_e32 v25, 2, v6
	v_add_u32_e32 v25, v11, v25
	ds_read2_b64 v[92:95], v25 offset1:16
	ds_read2_b64 v[96:99], v25 offset0:33 offset1:49
	ds_read2_b64 v[100:103], v25 offset0:66 offset1:82
	ds_read2_b64 v[104:107], v25 offset0:132 offset1:148
	ds_read2_b64 v[108:111], v25 offset0:99 offset1:115
	ds_read2_b64 v[112:115], v25 offset0:165 offset1:181
	ds_read2_b64 v[116:119], v25 offset0:198 offset1:214
	ds_read2_b64 v[120:123], v25 offset0:231 offset1:247
	s_waitcnt lgkmcnt(4)
	v_pk_add_f32 v[124:125], v[92:93], v[104:105]
	v_pk_add_f32 v[92:93], v[92:93], v[104:105] neg_lo:[0,1] neg_hi:[0,1]
	v_pk_add_f32 v[104:105], v[94:95], v[106:107]
	v_pk_add_f32 v[94:95], v[94:95], v[106:107] neg_lo:[0,1] neg_hi:[0,1]
	s_mov_b32 s45, s36
	v_pk_mul_f32 v[106:107], v[94:95], s[38:39]
	s_waitcnt lgkmcnt(1)
	v_pk_add_f32 v[126:127], v[102:103], v[118:119]
	v_pk_fma_f32 v[94:95], v[94:95], s[36:37], v[106:107] op_sel:[0,0,1] op_sel_hi:[1,0,0]
	v_pk_add_f32 v[106:107], v[96:97], v[112:113]
	v_pk_add_f32 v[96:97], v[96:97], v[112:113] neg_lo:[0,1] neg_hi:[0,1]
	v_pk_add_f32 v[102:103], v[102:103], v[118:119] neg_lo:[0,1] neg_hi:[0,1]
	v_pk_mul_f32 v[112:113], v[96:97], s[42:43]
	s_mov_b32 s62, s39
	v_pk_mul_f32 v[118:119], v[102:103], s[44:45]
	v_pk_fma_f32 v[96:97], v[96:97], s[40:41], v[112:113] op_sel:[0,0,1] op_sel_hi:[1,0,0]
	v_pk_add_f32 v[112:113], v[98:99], v[114:115]
	v_pk_add_f32 v[98:99], v[98:99], v[114:115] neg_lo:[0,1] neg_hi:[0,1]
	v_pk_fma_f32 v[102:103], v[102:103], s[62:63], v[118:119] op_sel:[0,0,1] op_sel_hi:[1,0,0] neg_lo:[1,0,0] neg_hi:[1,0,0]
	s_waitcnt lgkmcnt(0)
	v_pk_add_f32 v[118:119], v[108:109], v[120:121]
	v_pk_add_f32 v[108:109], v[108:109], v[120:121] neg_lo:[0,1] neg_hi:[0,1]
	v_pk_mul_f32 v[114:115], v[98:99], s[44:45]
	v_pk_mul_f32 v[120:121], v[108:109], s[42:43]
	v_pk_fma_f32 v[98:99], v[98:99], s[62:63], v[114:115] op_sel:[0,0,1] op_sel_hi:[1,0,0]
	v_pk_add_f32 v[114:115], v[100:101], v[116:117]
	v_pk_add_f32 v[116:117], v[100:101], v[116:117] neg_lo:[0,1] neg_hi:[0,1]
	v_pk_fma_f32 v[108:109], v[108:109], s[40:41], v[120:121] op_sel:[0,0,1] op_sel_hi:[1,0,0] neg_lo:[1,0,0] neg_hi:[1,0,0]
	v_pk_add_f32 v[120:121], v[110:111], v[122:123]
	v_pk_add_f32 v[110:111], v[110:111], v[122:123] neg_lo:[0,1] neg_hi:[0,1]
	s_nop 0
	v_pk_mul_f32 v[122:123], v[110:111], s[38:39]
	s_nop 0
	v_pk_fma_f32 v[110:111], v[110:111], s[36:37], v[122:123] op_sel:[0,0,1] op_sel_hi:[1,0,0] neg_lo:[1,0,0] neg_hi:[1,0,0]
	v_pk_add_f32 v[122:123], v[124:125], v[114:115]
	v_pk_add_f32 v[114:115], v[124:125], v[114:115] neg_lo:[0,1] neg_hi:[0,1]
	v_pk_add_f32 v[124:125], v[104:105], v[126:127]
	v_pk_add_f32 v[104:105], v[104:105], v[126:127] neg_lo:[0,1] neg_hi:[0,1]
	v_pk_add_f32 v[128:129], v[112:113], v[120:121]
	v_pk_add_f32 v[112:113], v[112:113], v[120:121] neg_lo:[0,1] neg_hi:[0,1]
	v_pk_add_f32 v[100:101], v[92:93], v[116:117] op_sel:[0,1] op_sel_hi:[1,0] neg_hi:[0,1]
	v_pk_add_f32 v[92:93], v[92:93], v[116:117] op_sel:[0,1] op_sel_hi:[1,0] neg_lo:[0,1]
	v_pk_add_f32 v[116:117], v[94:95], v[102:103]
	v_pk_add_f32 v[94:95], v[94:95], v[102:103] neg_lo:[0,1] neg_hi:[0,1]
	v_pk_mul_f32 v[126:127], v[104:105], s[42:43]
	v_pk_mul_f32 v[120:121], v[112:113], s[42:43]
	v_pk_mul_f32 v[102:103], v[94:95], s[42:43]
	v_pk_fma_f32 v[104:105], v[104:105], s[40:41], v[126:127] op_sel:[0,0,1] op_sel_hi:[1,0,0]
	v_pk_add_f32 v[126:127], v[106:107], v[118:119]
	v_pk_add_f32 v[118:119], v[106:107], v[118:119] neg_lo:[0,1] neg_hi:[0,1]
	v_pk_fma_f32 v[112:113], v[112:113], s[40:41], v[120:121] op_sel:[0,0,1] op_sel_hi:[1,0,0] neg_lo:[1,0,0] neg_hi:[1,0,0]
	v_pk_fma_f32 v[94:95], v[94:95], s[40:41], v[102:103] op_sel:[0,0,1] op_sel_hi:[1,0,0]
	v_pk_add_f32 v[102:103], v[96:97], v[108:109]
	v_pk_add_f32 v[120:121], v[98:99], v[110:111]
	v_pk_add_f32 v[98:99], v[98:99], v[110:111] neg_lo:[0,1] neg_hi:[0,1]
	v_pk_add_f32 v[96:97], v[96:97], v[108:109] neg_lo:[0,1] neg_hi:[0,1]
	v_pk_mul_f32 v[110:111], v[98:99], s[42:43]
	v_pk_add_f32 v[130:131], v[100:101], v[102:103]
	v_pk_add_f32 v[100:101], v[100:101], v[102:103] neg_lo:[0,1] neg_hi:[0,1]
	v_pk_add_f32 v[102:103], v[116:117], v[120:121]
	v_pk_add_f32 v[120:121], v[116:117], v[120:121] neg_lo:[0,1] neg_hi:[0,1]
	v_pk_mul_f32 v[42:43], v[26:27], v[30:31] op_sel:[1,1] op_sel_hi:[1,0] neg_lo:[1,0]
	v_xor_b32_e32 v109, 0x80000000, v96
	v_pk_fma_f32 v[98:99], v[98:99], s[40:41], v[110:111] op_sel:[0,0,1] op_sel_hi:[1,0,0] neg_lo:[1,0,0] neg_hi:[1,0,0]
	v_pk_add_f32 v[106:107], v[114:115], v[118:119] op_sel:[0,1] op_sel_hi:[1,0] neg_hi:[0,1]
	v_pk_add_f32 v[114:115], v[114:115], v[118:119] op_sel:[0,1] op_sel_hi:[1,0] neg_lo:[0,1]
	v_pk_add_f32 v[118:119], v[104:105], v[112:113]
	v_pk_add_f32 v[112:113], v[104:105], v[112:113] neg_lo:[0,1] neg_hi:[0,1]
	v_mov_b32_e32 v108, v97
	v_pk_fma_f32 v[42:43], v[26:27], v[30:31], v[42:43] op_sel_hi:[0,1,1]
	v_pk_mul_f32 v[46:47], v[30:31], v[28:29] op_sel:[1,1] op_sel_hi:[0,1] neg_lo:[0,1]
	v_pk_add_f32 v[96:97], v[92:93], v[108:109]
	v_pk_add_f32 v[92:93], v[92:93], v[108:109] neg_lo:[0,1] neg_hi:[0,1]
	v_pk_add_f32 v[108:109], v[94:95], v[98:99]
	v_pk_add_f32 v[98:99], v[94:95], v[98:99] neg_lo:[0,1] neg_hi:[0,1]
	v_pk_add_f32 v[116:117], v[100:101], v[120:121] op_sel:[0,1] op_sel_hi:[1,0] neg_hi:[0,1]
	v_pk_fma_f32 v[46:47], v[30:31], v[28:29], v[46:47] op_sel_hi:[1,0,1]
	v_pk_add_f32 v[104:105], v[114:115], v[112:113] op_sel:[0,1] op_sel_hi:[1,0] neg_hi:[0,1]
	v_pk_add_f32 v[100:101], v[100:101], v[120:121] op_sel:[0,1] op_sel_hi:[1,0] neg_lo:[0,1]
	v_pk_mul_f32 v[120:121], v[36:37], v[116:117] op_sel:[1,1] op_sel_hi:[1,0] neg_lo:[1,0]
	v_pk_add_f32 v[110:111], v[122:123], v[126:127]
	v_pk_add_f32 v[122:123], v[122:123], v[126:127] neg_lo:[0,1] neg_hi:[0,1]
	v_pk_add_f32 v[126:127], v[124:125], v[128:129]
	v_pk_add_f32 v[94:95], v[92:93], v[98:99] op_sel:[0,1] op_sel_hi:[1,0] neg_hi:[0,1]
	v_pk_fma_f32 v[116:117], v[36:37], v[116:117], v[120:121] op_sel_hi:[0,1,1]
	v_pk_mul_f32 v[120:121], v[42:43], v[104:105] op_sel:[1,1] op_sel_hi:[1,0] neg_lo:[1,0]
	v_pk_mul_f32 v[58:59], v[26:27], v[50:51] op_sel:[1,1] op_sel_hi:[1,0] neg_lo:[1,0]
	v_pk_add_f32 v[132:133], v[110:111], v[126:127]
	v_pk_add_f32 v[110:111], v[110:111], v[126:127] neg_lo:[0,1] neg_hi:[0,1]
	v_pk_fma_f32 v[104:105], v[42:43], v[104:105], v[120:121] op_sel_hi:[0,1,1]
	v_pk_mul_f32 v[120:121], v[46:47], v[94:95] op_sel:[1,1] op_sel_hi:[1,0] neg_lo:[1,0]
	v_pk_fma_f32 v[58:59], v[26:27], v[50:51], v[58:59] op_sel_hi:[0,1,1]
	v_pk_mul_f32 v[66:67], v[28:29], v[50:51] op_sel:[1,1] op_sel_hi:[1,0] neg_lo:[1,0]
	v_pk_add_f32 v[112:113], v[114:115], v[112:113] op_sel:[0,1] op_sel_hi:[1,0] neg_lo:[0,1]
	v_pk_add_f32 v[114:115], v[130:131], v[102:103]
	v_pk_add_f32 v[102:103], v[130:131], v[102:103] neg_lo:[0,1] neg_hi:[0,1]
	v_pk_fma_f32 v[94:95], v[46:47], v[94:95], v[120:121] op_sel_hi:[0,1,1]
	v_pk_mul_f32 v[120:121], v[50:51], v[110:111] op_sel:[1,1] op_sel_hi:[1,0] neg_lo:[1,0]
	v_pk_fma_f32 v[66:67], v[28:29], v[50:51], v[66:67] op_sel_hi:[0,1,1]
	v_pk_add_f32 v[128:129], v[124:125], v[128:129] neg_lo:[0,1] neg_hi:[0,1]
	v_pk_add_f32 v[126:127], v[106:107], v[118:119]
	v_pk_add_f32 v[106:107], v[106:107], v[118:119] neg_lo:[0,1] neg_hi:[0,1]
	v_pk_fma_f32 v[110:111], v[50:51], v[110:111], v[120:121] op_sel_hi:[0,1,1]
	v_pk_mul_f32 v[120:121], v[54:55], v[102:103] op_sel:[1,1] op_sel_hi:[1,0] neg_lo:[1,0]
	v_xor_b32_e32 v68, 0x80000000, v67
	v_mov_b32_e32 v69, v67
	v_pk_add_f32 v[118:119], v[96:97], v[108:109]
	v_pk_add_f32 v[96:97], v[96:97], v[108:109] neg_lo:[0,1] neg_hi:[0,1]
	v_pk_fma_f32 v[102:103], v[54:55], v[102:103], v[120:121] op_sel_hi:[0,1,1]
	v_pk_mul_f32 v[120:121], v[58:59], v[106:107] op_sel:[1,1] op_sel_hi:[1,0] neg_lo:[1,0]
	v_xor_b32_e32 v72, 0x80000000, v71
	v_mov_b32_e32 v73, v71
	v_pk_mul_f32 v[78:79], v[26:27], v[70:71] op_sel:[1,1] op_sel_hi:[1,0] neg_lo:[1,0]
	v_pk_add_f32 v[124:125], v[122:123], v[128:129] op_sel:[0,1] op_sel_hi:[1,0] neg_hi:[0,1]
	v_pk_add_f32 v[122:123], v[122:123], v[128:129] op_sel:[0,1] op_sel_hi:[1,0] neg_lo:[0,1]
	v_pk_fma_f32 v[106:107], v[58:59], v[106:107], v[120:121] op_sel_hi:[0,1,1]
	v_pk_mul_f32 v[120:121], v[68:69], v[96:97] op_sel:[0,1] op_sel_hi:[1,0]
	v_xor_b32_e32 v76, 0x80000000, v75
	v_mov_b32_e32 v77, v75
	v_pk_fma_f32 v[78:79], v[26:27], v[70:71], v[78:79] op_sel_hi:[0,1,1]
	v_pk_mul_f32 v[82:83], v[28:29], v[70:71] op_sel:[1,1] op_sel_hi:[1,0] neg_lo:[1,0]
	v_pk_fma_f32 v[96:97], v[66:67], v[96:97], v[120:121] op_sel_hi:[0,1,1]
	v_pk_mul_f32 v[120:121], v[72:73], v[122:123] op_sel:[0,1] op_sel_hi:[1,0]
	v_xor_b32_e32 v80, 0x80000000, v79
	v_mov_b32_e32 v81, v79
	v_pk_fma_f32 v[82:83], v[28:29], v[70:71], v[82:83] op_sel_hi:[0,1,1]
	v_pk_add_f32 v[92:93], v[92:93], v[98:99] op_sel:[0,1] op_sel_hi:[1,0] neg_lo:[0,1]
	v_pk_mul_f32 v[98:99], v[22:23], v[114:115] op_sel:[0,1] op_sel_hi:[1,0]
	v_pk_fma_f32 v[120:121], v[70:71], v[122:123], v[120:121] op_sel_hi:[0,1,1]
	v_pk_mul_f32 v[122:123], v[76:77], v[100:101] op_sel:[0,1] op_sel_hi:[1,0]
	v_xor_b32_e32 v84, 0x80000000, v83
	v_mov_b32_e32 v85, v83
	v_pk_fma_f32 v[98:99], v[24:25], v[114:115], v[98:99] op_sel_hi:[0,1,1]
	v_pk_mul_f32 v[114:115], v[28:29], v[118:119] op_sel:[1,1] op_sel_hi:[1,0] neg_lo:[1,0]
	v_pk_fma_f32 v[100:101], v[74:75], v[100:101], v[122:123] op_sel_hi:[0,1,1]
	v_pk_mul_f32 v[122:123], v[80:81], v[112:113] op_sel:[0,1] op_sel_hi:[1,0]
	v_add_u32_e32 v6, 0x2000, v6
	v_pk_mul_f32 v[108:109], v[26:27], v[126:127] op_sel:[1,1] op_sel_hi:[1,0] neg_lo:[1,0]
	v_pk_fma_f32 v[114:115], v[28:29], v[118:119], v[114:115] op_sel_hi:[0,1,1]
	v_pk_mul_f32 v[118:119], v[30:31], v[124:125] op_sel:[1,1] op_sel_hi:[1,0] neg_lo:[1,0]
	v_pk_fma_f32 v[112:113], v[78:79], v[112:113], v[122:123] op_sel_hi:[0,1,1]
	v_pk_mul_f32 v[122:123], v[84:85], v[92:93] op_sel:[0,1] op_sel_hi:[1,0]
	v_ashrrev_i32_e32 v6, 2, v6
	v_pk_fma_f32 v[108:109], v[26:27], v[126:127], v[108:109] op_sel_hi:[0,1,1]
	v_pk_fma_f32 v[118:119], v[30:31], v[124:125], v[118:119] op_sel_hi:[0,1,1]
	v_pk_fma_f32 v[92:93], v[82:83], v[92:93], v[122:123] op_sel_hi:[0,1,1]
	ds_write2_b64 v25, v[132:133], v[110:111] offset1:16
	ds_write2_b64 v25, v[118:119], v[120:121] offset0:33 offset1:49
	ds_write2_b64 v25, v[108:109], v[106:107] offset0:66 offset1:82
	ds_write2_b64 v25, v[104:105], v[112:113] offset0:99 offset1:115
	ds_write2_b64 v25, v[98:99], v[102:103] offset0:132 offset1:148
	ds_write2_b64 v25, v[116:117], v[100:101] offset0:165 offset1:181
	ds_write2_b64 v25, v[114:115], v[96:97] offset0:198 offset1:214
	ds_write2_b64 v25, v[94:95], v[92:93] offset0:231 offset1:247
	v_add3_u32 v6, v11, v6, s35
	ds_read2_b64 v[92:95], v6 offset1:16
	ds_read2_b64 v[96:99], v6 offset0:33 offset1:49
	ds_read2_b64 v[100:103], v6 offset0:66 offset1:82
	ds_read2_b64 v[104:107], v6 offset0:132 offset1:148
	ds_read2_b64 v[108:111], v6 offset0:99 offset1:115
	ds_read2_b64 v[112:115], v6 offset0:165 offset1:181
	ds_read2_b64 v[116:119], v6 offset0:198 offset1:214
	ds_read2_b64 v[120:123], v6 offset0:231 offset1:247
	s_waitcnt lgkmcnt(4)
	v_pk_add_f32 v[124:125], v[92:93], v[104:105]
	v_pk_add_f32 v[92:93], v[92:93], v[104:105] neg_lo:[0,1] neg_hi:[0,1]
	v_pk_add_f32 v[104:105], v[94:95], v[106:107]
	v_pk_add_f32 v[94:95], v[94:95], v[106:107] neg_lo:[0,1] neg_hi:[0,1]
	s_waitcnt lgkmcnt(1)
	v_pk_add_f32 v[126:127], v[102:103], v[118:119]
	v_pk_mul_f32 v[106:107], v[94:95], s[38:39]
	v_pk_add_f32 v[102:103], v[102:103], v[118:119] neg_lo:[0,1] neg_hi:[0,1]
	v_pk_fma_f32 v[94:95], v[94:95], s[36:37], v[106:107] op_sel:[0,0,1] op_sel_hi:[1,0,0]
	v_pk_add_f32 v[106:107], v[96:97], v[112:113]
	v_pk_add_f32 v[96:97], v[96:97], v[112:113] neg_lo:[0,1] neg_hi:[0,1]
	v_pk_mul_f32 v[118:119], v[102:103], s[44:45]
	v_pk_mul_f32 v[112:113], v[96:97], s[42:43]
	v_pk_fma_f32 v[102:103], v[102:103], s[62:63], v[118:119] op_sel:[0,0,1] op_sel_hi:[1,0,0] neg_lo:[1,0,0] neg_hi:[1,0,0]
	s_waitcnt lgkmcnt(0)
	v_pk_add_f32 v[118:119], v[108:109], v[120:121]
	v_pk_add_f32 v[108:109], v[108:109], v[120:121] neg_lo:[0,1] neg_hi:[0,1]
	v_pk_fma_f32 v[96:97], v[96:97], s[40:41], v[112:113] op_sel:[0,0,1] op_sel_hi:[1,0,0]
	v_pk_add_f32 v[112:113], v[98:99], v[114:115]
	v_pk_add_f32 v[98:99], v[98:99], v[114:115] neg_lo:[0,1] neg_hi:[0,1]
	v_pk_mul_f32 v[120:121], v[108:109], s[42:43]
	v_pk_mul_f32 v[114:115], v[98:99], s[44:45]
	v_pk_fma_f32 v[108:109], v[108:109], s[40:41], v[120:121] op_sel:[0,0,1] op_sel_hi:[1,0,0] neg_lo:[1,0,0] neg_hi:[1,0,0]
	v_pk_add_f32 v[120:121], v[110:111], v[122:123]
	v_pk_add_f32 v[110:111], v[110:111], v[122:123] neg_lo:[0,1] neg_hi:[0,1]
	v_pk_fma_f32 v[98:99], v[98:99], s[62:63], v[114:115] op_sel:[0,0,1] op_sel_hi:[1,0,0]
	v_pk_add_f32 v[114:115], v[100:101], v[116:117]
	v_pk_mul_f32 v[122:123], v[110:111], s[38:39]
	v_pk_add_f32 v[116:117], v[100:101], v[116:117] neg_lo:[0,1] neg_hi:[0,1]
	v_pk_fma_f32 v[110:111], v[110:111], s[36:37], v[122:123] op_sel:[0,0,1] op_sel_hi:[1,0,0] neg_lo:[1,0,0] neg_hi:[1,0,0]
	v_pk_add_f32 v[122:123], v[124:125], v[114:115]
	v_pk_add_f32 v[114:115], v[124:125], v[114:115] neg_lo:[0,1] neg_hi:[0,1]
	v_pk_add_f32 v[124:125], v[104:105], v[126:127]
	v_pk_add_f32 v[104:105], v[104:105], v[126:127] neg_lo:[0,1] neg_hi:[0,1]
	s_nop 0
	v_pk_mul_f32 v[126:127], v[104:105], s[42:43]
	v_pk_add_f32 v[128:129], v[112:113], v[120:121]
	v_pk_add_f32 v[112:113], v[112:113], v[120:121] neg_lo:[0,1] neg_hi:[0,1]
	v_pk_fma_f32 v[104:105], v[104:105], s[40:41], v[126:127] op_sel:[0,0,1] op_sel_hi:[1,0,0]
	v_pk_add_f32 v[126:127], v[106:107], v[118:119]
	v_pk_add_f32 v[118:119], v[106:107], v[118:119] neg_lo:[0,1] neg_hi:[0,1]
	v_pk_mul_f32 v[120:121], v[112:113], s[42:43]
	v_pk_add_f32 v[100:101], v[92:93], v[116:117] op_sel:[0,1] op_sel_hi:[1,0] neg_hi:[0,1]
	v_pk_add_f32 v[92:93], v[92:93], v[116:117] op_sel:[0,1] op_sel_hi:[1,0] neg_lo:[0,1]
	v_pk_add_f32 v[116:117], v[94:95], v[102:103]
	v_pk_add_f32 v[94:95], v[94:95], v[102:103] neg_lo:[0,1] neg_hi:[0,1]
	v_pk_fma_f32 v[112:113], v[112:113], s[40:41], v[120:121] op_sel:[0,0,1] op_sel_hi:[1,0,0] neg_lo:[1,0,0] neg_hi:[1,0,0]
	v_pk_mul_f32 v[102:103], v[94:95], s[42:43]
	s_nop 0
	v_pk_fma_f32 v[94:95], v[94:95], s[40:41], v[102:103] op_sel:[0,0,1] op_sel_hi:[1,0,0]
	v_pk_add_f32 v[102:103], v[96:97], v[108:109]
	v_pk_add_f32 v[120:121], v[98:99], v[110:111]
	v_pk_add_f32 v[98:99], v[98:99], v[110:111] neg_lo:[0,1] neg_hi:[0,1]
	v_pk_add_f32 v[106:107], v[114:115], v[118:119] op_sel:[0,1] op_sel_hi:[1,0] neg_hi:[0,1]
	v_pk_add_f32 v[114:115], v[114:115], v[118:119] op_sel:[0,1] op_sel_hi:[1,0] neg_lo:[0,1]
	v_pk_add_f32 v[118:119], v[104:105], v[112:113]
	v_pk_add_f32 v[112:113], v[104:105], v[112:113] neg_lo:[0,1] neg_hi:[0,1]
	v_pk_add_f32 v[108:109], v[96:97], v[108:109] neg_lo:[0,1] neg_hi:[0,1]
	v_pk_mul_f32 v[110:111], v[98:99], s[42:43]
	v_pk_add_f32 v[130:131], v[100:101], v[102:103]
	v_pk_add_f32 v[100:101], v[100:101], v[102:103] neg_lo:[0,1] neg_hi:[0,1]
	v_pk_add_f32 v[102:103], v[116:117], v[120:121]
	v_pk_fma_f32 v[98:99], v[98:99], s[40:41], v[110:111] op_sel:[0,0,1] op_sel_hi:[1,0,0] neg_lo:[1,0,0] neg_hi:[1,0,0]
	v_pk_add_f32 v[110:111], v[122:123], v[126:127]
	v_pk_add_f32 v[122:123], v[122:123], v[126:127] neg_lo:[0,1] neg_hi:[0,1]
	v_pk_add_f32 v[126:127], v[124:125], v[128:129]
	v_pk_add_f32 v[104:105], v[114:115], v[112:113] op_sel:[0,1] op_sel_hi:[1,0] neg_hi:[0,1]
	v_pk_add_f32 v[112:113], v[114:115], v[112:113] op_sel:[0,1] op_sel_hi:[1,0] neg_lo:[0,1]
	v_pk_add_f32 v[114:115], v[130:131], v[102:103]
	v_pk_add_f32 v[124:125], v[124:125], v[128:129] neg_lo:[0,1] neg_hi:[0,1]
	v_pk_add_f32 v[96:97], v[92:93], v[108:109] op_sel:[0,1] op_sel_hi:[1,0] neg_hi:[0,1]
	v_pk_add_f32 v[92:93], v[92:93], v[108:109] op_sel:[0,1] op_sel_hi:[1,0] neg_lo:[0,1]
	v_pk_add_f32 v[108:109], v[94:95], v[98:99]
	v_pk_add_f32 v[132:133], v[110:111], v[126:127]
	v_pk_add_f32 v[110:111], v[110:111], v[126:127] neg_lo:[0,1] neg_hi:[0,1]
	v_pk_add_f32 v[126:127], v[106:107], v[118:119]
	v_pk_mul_f32 v[22:23], v[22:23], v[114:115] op_sel:[0,1] op_sel_hi:[1,0]
	v_xor_b32_e32 v129, 0x80000000, v124
	v_pk_add_f32 v[116:117], v[116:117], v[120:121] neg_lo:[0,1] neg_hi:[0,1]
	v_mov_b32_e32 v128, v125
	v_pk_add_f32 v[106:107], v[106:107], v[118:119] neg_lo:[0,1] neg_hi:[0,1]
	v_pk_add_f32 v[118:119], v[96:97], v[108:109]
	v_pk_fma_f32 v[22:23], v[24:25], v[114:115], v[22:23] op_sel_hi:[0,1,1]
	v_pk_mul_f32 v[24:25], v[26:27], v[126:127] op_sel:[1,1] op_sel_hi:[1,0] neg_lo:[1,0]
	v_xor_b32_e32 v121, 0x80000000, v116
	v_pk_add_f32 v[94:95], v[94:95], v[98:99] neg_lo:[0,1] neg_hi:[0,1]
	v_pk_add_f32 v[124:125], v[122:123], v[128:129]
	v_mov_b32_e32 v120, v117
	v_pk_fma_f32 v[24:25], v[26:27], v[126:127], v[24:25] op_sel_hi:[0,1,1]
	v_pk_mul_f32 v[26:27], v[28:29], v[118:119] op_sel:[1,1] op_sel_hi:[1,0] neg_lo:[1,0]
	v_xor_b32_e32 v99, 0x80000000, v94
	v_pk_add_f32 v[116:117], v[100:101], v[120:121]
	v_mov_b32_e32 v98, v95
	v_pk_fma_f32 v[26:27], v[28:29], v[118:119], v[26:27] op_sel_hi:[0,1,1]
	v_pk_mul_f32 v[28:29], v[30:31], v[124:125] op_sel:[1,1] op_sel_hi:[1,0] neg_lo:[1,0]
	v_pk_add_f32 v[94:95], v[92:93], v[98:99]
	v_pk_fma_f32 v[28:29], v[30:31], v[124:125], v[28:29] op_sel_hi:[0,1,1]
	v_pk_mul_f32 v[30:31], v[36:37], v[116:117] op_sel:[1,1] op_sel_hi:[1,0] neg_lo:[1,0]
	v_pk_add_f32 v[122:123], v[122:123], v[128:129] neg_lo:[0,1] neg_hi:[0,1]
	v_pk_add_f32 v[102:103], v[130:131], v[102:103] neg_lo:[0,1] neg_hi:[0,1]
	v_pk_add_f32 v[100:101], v[100:101], v[120:121] neg_lo:[0,1] neg_hi:[0,1]
	v_pk_add_f32 v[96:97], v[96:97], v[108:109] neg_lo:[0,1] neg_hi:[0,1]
	v_pk_add_f32 v[92:93], v[92:93], v[98:99] neg_lo:[0,1] neg_hi:[0,1]
	v_pk_fma_f32 v[30:31], v[36:37], v[116:117], v[30:31] op_sel_hi:[0,1,1]
	v_pk_mul_f32 v[32:33], v[42:43], v[104:105] op_sel:[1,1] op_sel_hi:[1,0] neg_lo:[1,0]
	v_pk_mul_f32 v[34:35], v[46:47], v[94:95] op_sel:[1,1] op_sel_hi:[1,0] neg_lo:[1,0]
	v_pk_mul_f32 v[36:37], v[50:51], v[110:111] op_sel:[1,1] op_sel_hi:[1,0] neg_lo:[1,0]
	v_pk_fma_f32 v[32:33], v[42:43], v[104:105], v[32:33] op_sel_hi:[0,1,1]
	v_pk_fma_f32 v[34:35], v[46:47], v[94:95], v[34:35] op_sel_hi:[0,1,1]
	v_pk_fma_f32 v[36:37], v[50:51], v[110:111], v[36:37] op_sel_hi:[0,1,1]
	v_pk_mul_f32 v[38:39], v[54:55], v[102:103] op_sel:[1,1] op_sel_hi:[1,0] neg_lo:[1,0]
	v_pk_mul_f32 v[40:41], v[58:59], v[106:107] op_sel:[1,1] op_sel_hi:[1,0] neg_lo:[1,0]
	v_pk_mul_f32 v[42:43], v[68:69], v[96:97] op_sel:[0,1] op_sel_hi:[1,0]
	v_pk_mul_f32 v[44:45], v[72:73], v[122:123] op_sel:[0,1] op_sel_hi:[1,0]
	v_pk_mul_f32 v[46:47], v[76:77], v[100:101] op_sel:[0,1] op_sel_hi:[1,0]
	v_pk_mul_f32 v[48:49], v[80:81], v[112:113] op_sel:[0,1] op_sel_hi:[1,0]
	v_pk_mul_f32 v[50:51], v[84:85], v[92:93] op_sel:[0,1] op_sel_hi:[1,0]
	v_pk_fma_f32 v[38:39], v[54:55], v[102:103], v[38:39] op_sel_hi:[0,1,1]
	v_pk_fma_f32 v[40:41], v[58:59], v[106:107], v[40:41] op_sel_hi:[0,1,1]
	v_pk_fma_f32 v[42:43], v[66:67], v[96:97], v[42:43] op_sel_hi:[0,1,1]
	v_pk_fma_f32 v[44:45], v[70:71], v[122:123], v[44:45] op_sel_hi:[0,1,1]
	v_pk_fma_f32 v[46:47], v[74:75], v[100:101], v[46:47] op_sel_hi:[0,1,1]
	v_pk_fma_f32 v[48:49], v[78:79], v[112:113], v[48:49] op_sel_hi:[0,1,1]
	v_pk_fma_f32 v[50:51], v[82:83], v[92:93], v[50:51] op_sel_hi:[0,1,1]
	ds_write2_b64 v6, v[132:133], v[36:37] offset1:16
	ds_write2_b64 v6, v[28:29], v[44:45] offset0:33 offset1:49
	ds_write2_b64 v6, v[24:25], v[40:41] offset0:66 offset1:82
	ds_write2_b64 v6, v[32:33], v[48:49] offset0:99 offset1:115
	ds_write2_b64 v6, v[22:23], v[38:39] offset0:132 offset1:148
	ds_write2_b64 v6, v[30:31], v[46:47] offset0:165 offset1:181
	ds_write2_b64 v6, v[26:27], v[42:43] offset0:198 offset1:214
	ds_write2_b64 v6, v[34:35], v[50:51] offset0:231 offset1:247
	v_mov_b32_e32 v6, v62
	s_waitcnt lgkmcnt(0)
	s_barrier
	s_lshl_b32 s24, s71, 6
	v_bfe_i32 v11, v6, 1, 27
	v_lshl_add_u32 v68, v6, 7, 0
	v_lshl_add_u32 v11, v11, 3, v68
	ds_read2_b64 v[22:25], v11 offset1:1
	ds_read2_b64 v[26:29], v11 offset0:2 offset1:3
	ds_read2_b64 v[30:33], v11 offset0:8 offset1:9
	ds_read2_b64 v[34:37], v11 offset0:4 offset1:5
	ds_read2_b64 v[38:41], v11 offset0:6 offset1:7
	ds_read2_b64 v[42:45], v11 offset0:10 offset1:11
	ds_read2_b64 v[46:49], v11 offset0:12 offset1:13
	ds_read2_b64 v[50:53], v11 offset0:14 offset1:15
	s_waitcnt lgkmcnt(5)
	v_pk_add_f32 v[54:55], v[22:23], v[30:31]
	v_pk_add_f32 v[22:23], v[22:23], v[30:31] neg_lo:[0,1] neg_hi:[0,1]
	v_pk_add_f32 v[30:31], v[24:25], v[32:33]
	v_pk_add_f32 v[24:25], v[24:25], v[32:33] neg_lo:[0,1] neg_hi:[0,1]
	s_waitcnt lgkmcnt(1)
	v_pk_add_f32 v[56:57], v[36:37], v[48:49]
	v_pk_mul_f32 v[32:33], v[24:25], s[38:39]
	v_pk_add_f32 v[36:37], v[36:37], v[48:49] neg_lo:[0,1] neg_hi:[0,1]
	v_pk_fma_f32 v[24:25], v[24:25], s[36:37], v[32:33] op_sel:[0,0,1] op_sel_hi:[1,0,0]
	v_pk_add_f32 v[32:33], v[26:27], v[42:43]
	v_pk_add_f32 v[26:27], v[26:27], v[42:43] neg_lo:[0,1] neg_hi:[0,1]
	v_pk_mul_f32 v[48:49], v[36:37], s[44:45]
	v_pk_mul_f32 v[42:43], v[26:27], s[42:43]
	v_pk_fma_f32 v[36:37], v[36:37], s[62:63], v[48:49] op_sel:[0,0,1] op_sel_hi:[1,0,0] neg_lo:[1,0,0] neg_hi:[1,0,0]
	v_pk_fma_f32 v[26:27], v[26:27], s[40:41], v[42:43] op_sel:[0,0,1] op_sel_hi:[1,0,0]
	v_pk_add_f32 v[42:43], v[28:29], v[44:45]
	v_pk_add_f32 v[28:29], v[28:29], v[44:45] neg_lo:[0,1] neg_hi:[0,1]
	s_waitcnt lgkmcnt(0)
	v_pk_add_f32 v[48:49], v[38:39], v[50:51]
	v_pk_add_f32 v[38:39], v[38:39], v[50:51] neg_lo:[0,1] neg_hi:[0,1]
	v_pk_mul_f32 v[44:45], v[28:29], s[44:45]
	v_pk_mul_f32 v[50:51], v[38:39], s[42:43]
	v_pk_fma_f32 v[28:29], v[28:29], s[62:63], v[44:45] op_sel:[0,0,1] op_sel_hi:[1,0,0]
	v_pk_add_f32 v[44:45], v[34:35], v[46:47]
	v_pk_add_f32 v[46:47], v[34:35], v[46:47] neg_lo:[0,1] neg_hi:[0,1]
	v_pk_fma_f32 v[38:39], v[38:39], s[40:41], v[50:51] op_sel:[0,0,1] op_sel_hi:[1,0,0] neg_lo:[1,0,0] neg_hi:[1,0,0]
	v_pk_add_f32 v[50:51], v[40:41], v[52:53]
	v_pk_add_f32 v[40:41], v[40:41], v[52:53] neg_lo:[0,1] neg_hi:[0,1]
	s_nop 0
	v_pk_mul_f32 v[52:53], v[40:41], s[38:39]
	v_pk_add_f32 v[58:59], v[42:43], v[50:51]
	v_pk_add_f32 v[42:43], v[42:43], v[50:51] neg_lo:[0,1] neg_hi:[0,1]
	v_pk_fma_f32 v[40:41], v[40:41], s[36:37], v[52:53] op_sel:[0,0,1] op_sel_hi:[1,0,0] neg_lo:[1,0,0] neg_hi:[1,0,0]
	v_pk_add_f32 v[52:53], v[54:55], v[44:45]
	v_pk_add_f32 v[44:45], v[54:55], v[44:45] neg_lo:[0,1] neg_hi:[0,1]
	v_pk_add_f32 v[54:55], v[30:31], v[56:57]
	v_pk_add_f32 v[30:31], v[30:31], v[56:57] neg_lo:[0,1] neg_hi:[0,1]
	v_pk_mul_f32 v[50:51], v[42:43], s[42:43]
	v_pk_add_f32 v[34:35], v[22:23], v[46:47] op_sel:[0,1] op_sel_hi:[1,0] neg_hi:[0,1]
	v_pk_add_f32 v[22:23], v[22:23], v[46:47] op_sel:[0,1] op_sel_hi:[1,0] neg_lo:[0,1]
	v_pk_add_f32 v[46:47], v[24:25], v[36:37]
	v_pk_add_f32 v[24:25], v[24:25], v[36:37] neg_lo:[0,1] neg_hi:[0,1]
	v_pk_mul_f32 v[56:57], v[30:31], s[42:43]
	v_pk_fma_f32 v[42:43], v[42:43], s[40:41], v[50:51] op_sel:[0,0,1] op_sel_hi:[1,0,0] neg_lo:[1,0,0] neg_hi:[1,0,0]
	v_pk_mul_f32 v[36:37], v[24:25], s[42:43]
	v_pk_add_f32 v[50:51], v[28:29], v[40:41]
	v_pk_add_f32 v[28:29], v[28:29], v[40:41] neg_lo:[0,1] neg_hi:[0,1]
	v_pk_fma_f32 v[30:31], v[30:31], s[40:41], v[56:57] op_sel:[0,0,1] op_sel_hi:[1,0,0]
	v_pk_add_f32 v[56:57], v[32:33], v[48:49]
	v_pk_add_f32 v[48:49], v[32:33], v[48:49] neg_lo:[0,1] neg_hi:[0,1]
	v_pk_fma_f32 v[24:25], v[24:25], s[40:41], v[36:37] op_sel:[0,0,1] op_sel_hi:[1,0,0]
	v_pk_add_f32 v[36:37], v[26:27], v[38:39]
	v_pk_add_f32 v[38:39], v[26:27], v[38:39] neg_lo:[0,1] neg_hi:[0,1]
	v_pk_mul_f32 v[40:41], v[28:29], s[42:43]
	s_nop 0
	v_pk_fma_f32 v[28:29], v[28:29], s[40:41], v[40:41] op_sel:[0,0,1] op_sel_hi:[1,0,0] neg_lo:[1,0,0] neg_hi:[1,0,0]
	v_lshl_add_u32 v6, v6, 4, v90
	v_pk_add_f32 v[40:41], v[52:53], v[56:57]
	v_pk_add_f32 v[52:53], v[52:53], v[56:57] neg_lo:[0,1] neg_hi:[0,1]
	v_pk_add_f32 v[56:57], v[54:55], v[58:59]
	v_pk_add_f32 v[58:59], v[54:55], v[58:59] neg_lo:[0,1] neg_hi:[0,1]
	v_pk_add_f32 v[32:33], v[44:45], v[48:49] op_sel:[0,1] op_sel_hi:[1,0] neg_hi:[0,1]
	v_pk_add_f32 v[44:45], v[44:45], v[48:49] op_sel:[0,1] op_sel_hi:[1,0] neg_lo:[0,1]
	v_pk_add_f32 v[48:49], v[30:31], v[42:43]
	v_pk_add_f32 v[42:43], v[30:31], v[42:43] neg_lo:[0,1] neg_hi:[0,1]
	v_pk_add_f32 v[60:61], v[34:35], v[36:37]
	v_pk_add_f32 v[34:35], v[34:35], v[36:37] neg_lo:[0,1] neg_hi:[0,1]
	v_pk_add_f32 v[36:37], v[46:47], v[50:51]
	v_pk_add_f32 v[50:51], v[46:47], v[50:51] neg_lo:[0,1] neg_hi:[0,1]
	v_pk_add_f32 v[26:27], v[22:23], v[38:39] op_sel:[0,1] op_sel_hi:[1,0] neg_hi:[0,1]
	v_pk_add_f32 v[22:23], v[22:23], v[38:39] op_sel:[0,1] op_sel_hi:[1,0] neg_lo:[0,1]
	v_pk_add_f32 v[38:39], v[24:25], v[28:29]
	v_pk_add_f32 v[28:29], v[24:25], v[28:29] neg_lo:[0,1] neg_hi:[0,1]
	v_ashrrev_i32_e32 v6, 5, v6
	v_pk_add_f32 v[66:67], v[40:41], v[56:57]
	v_pk_add_f32 v[40:41], v[40:41], v[56:57] neg_lo:[0,1] neg_hi:[0,1]
	v_lshlrev_b32_e32 v6, 3, v6
	v_pk_add_f32 v[54:55], v[52:53], v[58:59] op_sel:[0,1] op_sel_hi:[1,0] neg_hi:[0,1]
	v_pk_add_f32 v[52:53], v[52:53], v[58:59] op_sel:[0,1] op_sel_hi:[1,0] neg_lo:[0,1]
	v_pk_add_f32 v[56:57], v[32:33], v[48:49]
	v_pk_add_f32 v[32:33], v[32:33], v[48:49] neg_lo:[0,1] neg_hi:[0,1]
	v_pk_add_f32 v[30:31], v[44:45], v[42:43] op_sel:[0,1] op_sel_hi:[1,0] neg_hi:[0,1]
	v_pk_add_f32 v[42:43], v[44:45], v[42:43] op_sel:[0,1] op_sel_hi:[1,0] neg_lo:[0,1]
	v_pk_add_f32 v[44:45], v[60:61], v[36:37]
	v_pk_add_f32 v[36:37], v[60:61], v[36:37] neg_lo:[0,1] neg_hi:[0,1]
	v_pk_add_f32 v[46:47], v[34:35], v[50:51] op_sel:[0,1] op_sel_hi:[1,0] neg_hi:[0,1]
	v_pk_add_f32 v[34:35], v[34:35], v[50:51] op_sel:[0,1] op_sel_hi:[1,0] neg_lo:[0,1]
	v_pk_add_f32 v[48:49], v[26:27], v[38:39]
	v_pk_add_f32 v[26:27], v[26:27], v[38:39] neg_lo:[0,1] neg_hi:[0,1]
	v_pk_add_f32 v[24:25], v[22:23], v[28:29] op_sel:[0,1] op_sel_hi:[1,0] neg_hi:[0,1]
	v_pk_add_f32 v[22:23], v[22:23], v[28:29] op_sel:[0,1] op_sel_hi:[1,0] neg_lo:[0,1]
	ds_write2_b64 v11, v[66:67], v[40:41] offset1:1
	ds_write2_b64 v11, v[54:55], v[52:53] offset0:2 offset1:3
	ds_write2_b64 v11, v[56:57], v[32:33] offset0:4 offset1:5
	ds_write2_b64 v11, v[30:31], v[42:43] offset0:6 offset1:7
	ds_write2_b64 v11, v[44:45], v[36:37] offset0:8 offset1:9
	ds_write2_b64 v11, v[46:47], v[34:35] offset0:10 offset1:11
	ds_write2_b64 v11, v[48:49], v[26:27] offset0:12 offset1:13
	ds_write2_b64 v11, v[24:25], v[22:23] offset0:14 offset1:15
	v_add3_u32 v6, v68, v6, s35
	ds_read2_b64 v[22:25], v6 offset1:1
	ds_read2_b64 v[26:29], v6 offset0:2 offset1:3
	ds_read2_b64 v[30:33], v6 offset0:8 offset1:9
	ds_read2_b64 v[34:37], v6 offset0:4 offset1:5
	ds_read2_b64 v[38:41], v6 offset0:6 offset1:7
	ds_read2_b64 v[42:45], v6 offset0:10 offset1:11
	ds_read2_b64 v[46:49], v6 offset0:12 offset1:13
	ds_read2_b64 v[50:53], v6 offset0:14 offset1:15
	s_waitcnt lgkmcnt(5)
	v_pk_add_f32 v[54:55], v[22:23], v[30:31]
	v_pk_add_f32 v[22:23], v[22:23], v[30:31] neg_lo:[0,1] neg_hi:[0,1]
	v_pk_add_f32 v[30:31], v[24:25], v[32:33]
	v_pk_add_f32 v[24:25], v[24:25], v[32:33] neg_lo:[0,1] neg_hi:[0,1]
	s_waitcnt lgkmcnt(1)
	v_pk_add_f32 v[56:57], v[36:37], v[48:49]
	v_pk_mul_f32 v[32:33], v[24:25], s[38:39]
	v_pk_add_f32 v[36:37], v[36:37], v[48:49] neg_lo:[0,1] neg_hi:[0,1]
	v_pk_fma_f32 v[24:25], v[24:25], s[36:37], v[32:33] op_sel:[0,0,1] op_sel_hi:[1,0,0]
	v_pk_add_f32 v[32:33], v[26:27], v[42:43]
	v_pk_add_f32 v[26:27], v[26:27], v[42:43] neg_lo:[0,1] neg_hi:[0,1]
	v_pk_mul_f32 v[48:49], v[36:37], s[44:45]
	v_pk_mul_f32 v[42:43], v[26:27], s[42:43]
	v_pk_fma_f32 v[36:37], v[36:37], s[62:63], v[48:49] op_sel:[0,0,1] op_sel_hi:[1,0,0] neg_lo:[1,0,0] neg_hi:[1,0,0]
	v_pk_fma_f32 v[26:27], v[26:27], s[40:41], v[42:43] op_sel:[0,0,1] op_sel_hi:[1,0,0]
	v_pk_add_f32 v[42:43], v[28:29], v[44:45]
	v_pk_add_f32 v[28:29], v[28:29], v[44:45] neg_lo:[0,1] neg_hi:[0,1]
	s_waitcnt lgkmcnt(0)
	v_pk_add_f32 v[48:49], v[38:39], v[50:51]
	v_pk_add_f32 v[38:39], v[38:39], v[50:51] neg_lo:[0,1] neg_hi:[0,1]
	v_pk_mul_f32 v[44:45], v[28:29], s[44:45]
	v_pk_mul_f32 v[50:51], v[38:39], s[42:43]
	v_pk_fma_f32 v[28:29], v[28:29], s[62:63], v[44:45] op_sel:[0,0,1] op_sel_hi:[1,0,0]
	v_pk_add_f32 v[44:45], v[34:35], v[46:47]
	v_pk_add_f32 v[46:47], v[34:35], v[46:47] neg_lo:[0,1] neg_hi:[0,1]
	v_pk_fma_f32 v[38:39], v[38:39], s[40:41], v[50:51] op_sel:[0,0,1] op_sel_hi:[1,0,0] neg_lo:[1,0,0] neg_hi:[1,0,0]
	v_pk_add_f32 v[50:51], v[40:41], v[52:53]
	v_pk_add_f32 v[40:41], v[40:41], v[52:53] neg_lo:[0,1] neg_hi:[0,1]
	s_nop 0
	v_pk_mul_f32 v[52:53], v[40:41], s[38:39]
	v_pk_add_f32 v[58:59], v[42:43], v[50:51]
	v_pk_add_f32 v[42:43], v[42:43], v[50:51] neg_lo:[0,1] neg_hi:[0,1]
	v_pk_fma_f32 v[40:41], v[40:41], s[36:37], v[52:53] op_sel:[0,0,1] op_sel_hi:[1,0,0] neg_lo:[1,0,0] neg_hi:[1,0,0]
	v_pk_mul_f32 v[50:51], v[42:43], s[42:43]
	v_pk_add_f32 v[34:35], v[22:23], v[46:47] op_sel:[0,1] op_sel_hi:[1,0] neg_hi:[0,1]
	v_pk_add_f32 v[22:23], v[22:23], v[46:47] op_sel:[0,1] op_sel_hi:[1,0] neg_lo:[0,1]
	v_pk_add_f32 v[46:47], v[24:25], v[36:37]
	v_pk_add_f32 v[24:25], v[24:25], v[36:37] neg_lo:[0,1] neg_hi:[0,1]
	v_pk_add_f32 v[52:53], v[54:55], v[44:45]
	v_pk_add_f32 v[44:45], v[54:55], v[44:45] neg_lo:[0,1] neg_hi:[0,1]
	v_pk_add_f32 v[54:55], v[30:31], v[56:57]
	v_pk_add_f32 v[30:31], v[30:31], v[56:57] neg_lo:[0,1] neg_hi:[0,1]
	v_pk_fma_f32 v[42:43], v[42:43], s[40:41], v[50:51] op_sel:[0,0,1] op_sel_hi:[1,0,0] neg_lo:[1,0,0] neg_hi:[1,0,0]
	v_pk_mul_f32 v[36:37], v[24:25], s[42:43]
	v_pk_add_f32 v[50:51], v[28:29], v[40:41]
	v_pk_add_f32 v[28:29], v[28:29], v[40:41] neg_lo:[0,1] neg_hi:[0,1]
	s_and_b32 s24, s24, 0xc0
	v_pk_mul_f32 v[56:57], v[30:31], s[42:43]
	v_pk_fma_f32 v[24:25], v[24:25], s[40:41], v[36:37] op_sel:[0,0,1] op_sel_hi:[1,0,0]
	v_pk_add_f32 v[36:37], v[26:27], v[38:39]
	v_pk_add_f32 v[38:39], v[26:27], v[38:39] neg_lo:[0,1] neg_hi:[0,1]
	v_pk_mul_f32 v[40:41], v[28:29], s[42:43]
	s_lshl_b64 s[62:63], s[50:51], 19
	v_pk_fma_f32 v[30:31], v[30:31], s[40:41], v[56:57] op_sel:[0,0,1] op_sel_hi:[1,0,0]
	v_pk_add_f32 v[56:57], v[32:33], v[48:49]
	v_pk_add_f32 v[48:49], v[32:33], v[48:49] neg_lo:[0,1] neg_hi:[0,1]
	s_nop 0
	v_pk_fma_f32 v[28:29], v[28:29], s[40:41], v[40:41] op_sel:[0,0,1] op_sel_hi:[1,0,0] neg_lo:[1,0,0] neg_hi:[1,0,0]
	s_add_u32 s43, s3, s62
	s_nop 0
	s_nop 0
	v_pk_add_f32 v[26:27], v[22:23], v[38:39] op_sel:[0,1] op_sel_hi:[1,0] neg_hi:[0,1]
	v_pk_add_f32 v[22:23], v[22:23], v[38:39] op_sel:[0,1] op_sel_hi:[1,0] neg_lo:[0,1]
	v_pk_add_f32 v[38:39], v[24:25], v[28:29]
	v_pk_add_f32 v[24:25], v[24:25], v[28:29] neg_lo:[0,1] neg_hi:[0,1]
	s_addc_u32 s45, s29, s63
	s_lshl_b32 s64, s24, 2
	v_pk_add_f32 v[40:41], v[52:53], v[56:57]
	v_pk_add_f32 v[52:53], v[52:53], v[56:57] neg_lo:[0,1] neg_hi:[0,1]
	v_pk_add_f32 v[56:57], v[54:55], v[58:59]
	v_pk_add_f32 v[54:55], v[54:55], v[58:59] neg_lo:[0,1] neg_hi:[0,1]
	v_pk_add_f32 v[32:33], v[44:45], v[48:49] op_sel:[0,1] op_sel_hi:[1,0] neg_hi:[0,1]
	v_pk_add_f32 v[44:45], v[44:45], v[48:49] op_sel:[0,1] op_sel_hi:[1,0] neg_lo:[0,1]
	v_pk_add_f32 v[48:49], v[30:31], v[42:43]
	v_pk_add_f32 v[42:43], v[30:31], v[42:43] neg_lo:[0,1] neg_hi:[0,1]
	v_pk_add_f32 v[60:61], v[34:35], v[36:37]
	v_pk_add_f32 v[34:35], v[34:35], v[36:37] neg_lo:[0,1] neg_hi:[0,1]
	v_pk_add_f32 v[36:37], v[46:47], v[50:51]
	v_pk_add_f32 v[46:47], v[46:47], v[50:51] neg_lo:[0,1] neg_hi:[0,1]
	v_xor_b32_e32 v29, 0x80000000, v24
	v_mov_b32_e32 v28, v25
	s_add_u32 s64, s43, s64
	v_xor_b32_e32 v59, 0x80000000, v54
	s_nop 0
	v_xor_b32_e32 v51, 0x80000000, v46
	v_pk_add_f32 v[66:67], v[40:41], v[56:57]
	v_pk_add_f32 v[40:41], v[40:41], v[56:57] neg_lo:[0,1] neg_hi:[0,1]
	v_mov_b32_e32 v58, v55
	v_mov_b32_e32 v50, v47
	v_pk_add_f32 v[24:25], v[22:23], v[28:29]
	v_pk_add_f32 v[22:23], v[22:23], v[28:29] neg_lo:[0,1] neg_hi:[0,1]
	s_addc_u32 s65, s45, 0
	v_pk_add_f32 v[54:55], v[52:53], v[58:59]
	v_pk_add_f32 v[52:53], v[52:53], v[58:59] neg_lo:[0,1] neg_hi:[0,1]
	v_pk_add_f32 v[56:57], v[32:33], v[48:49]
	v_pk_add_f32 v[32:33], v[32:33], v[48:49] neg_lo:[0,1] neg_hi:[0,1]
	v_pk_add_f32 v[30:31], v[44:45], v[42:43] op_sel:[0,1] op_sel_hi:[1,0] neg_hi:[0,1]
	v_pk_add_f32 v[42:43], v[44:45], v[42:43] op_sel:[0,1] op_sel_hi:[1,0] neg_lo:[0,1]
	v_pk_add_f32 v[44:45], v[60:61], v[36:37]
	v_pk_add_f32 v[36:37], v[60:61], v[36:37] neg_lo:[0,1] neg_hi:[0,1]
	v_pk_add_f32 v[46:47], v[34:35], v[50:51]
	v_pk_add_f32 v[34:35], v[34:35], v[50:51] neg_lo:[0,1] neg_hi:[0,1]
	v_pk_add_f32 v[48:49], v[26:27], v[38:39]
	v_pk_add_f32 v[26:27], v[26:27], v[38:39] neg_lo:[0,1] neg_hi:[0,1]
	ds_write2_b64 v6, v[66:67], v[40:41] offset1:1
	ds_write2_b64 v6, v[54:55], v[52:53] offset0:2 offset1:3
	ds_write2_b64 v6, v[56:57], v[32:33] offset0:4 offset1:5
	ds_write2_b64 v6, v[30:31], v[42:43] offset0:6 offset1:7
	ds_write2_b64 v6, v[44:45], v[36:37] offset0:8 offset1:9
	ds_write2_b64 v6, v[46:47], v[34:35] offset0:10 offset1:11
	ds_write2_b64 v6, v[48:49], v[26:27] offset0:12 offset1:13
	ds_write2_b64 v6, v[24:25], v[22:23] offset0:14 offset1:15
	v_lshl_add_u64 v[22:23], s[64:65], 0, v[20:21]
	s_mov_b64 s[64:65], 0
	v_mov_b32_e32 v11, v9
	v_mov_b64_e32 v[24:25], v[62:63]
	s_waitcnt lgkmcnt(0)
	s_barrier

.LBB0_271:
	global_load_dword v40, v35, s[18:19]
	v_lshl_add_u64 v[44:45], s[18:19], 0, v[34:35]
	global_load_dword v42, v[44:45], off
	s_waitcnt vmcnt(9)
	v_cvt_f32_f16_e32 v62, v6
	v_cvt_f32_f16_sdwa v44, v6 dst_sel:DWORD dst_unused:UNUSED_PAD src0_sel:WORD_1
	v_cvt_f32_f16_e32 v45, v7
	v_cvt_f32_f16_e32 v47, v8
	v_cvt_f32_f16_sdwa v48, v8 dst_sel:DWORD dst_unused:UNUSED_PAD src0_sel:WORD_1
	v_cvt_f32_f16_e32 v49, v9
	v_cvt_f32_f16_sdwa v8, v9 dst_sel:DWORD dst_unused:UNUSED_PAD src0_sel:WORD_1
	s_waitcnt vmcnt(8)
	v_cvt_f32_f16_e32 v9, v30
	s_waitcnt vmcnt(7)
	v_cvt_f32_f16_sdwa v52, v26 dst_sel:DWORD dst_unused:UNUSED_PAD src0_sel:WORD_1
	v_cvt_f32_f16_e32 v53, v27
	v_cvt_f32_f16_sdwa v46, v7 dst_sel:DWORD dst_unused:UNUSED_PAD src0_sel:WORD_1
	v_cvt_f32_f16_sdwa v50, v30 dst_sel:DWORD dst_unused:UNUSED_PAD src0_sel:WORD_1
	v_cvt_f32_f16_e32 v51, v31
	v_cvt_f32_f16_sdwa v30, v31 dst_sel:DWORD dst_unused:UNUSED_PAD src0_sel:WORD_1
	v_cvt_f32_f16_e32 v31, v32
	v_cvt_f32_f16_sdwa v7, v33 dst_sel:DWORD dst_unused:UNUSED_PAD src0_sel:WORD_1
	v_cvt_f32_f16_sdwa v32, v32 dst_sel:DWORD dst_unused:UNUSED_PAD src0_sel:WORD_1
	v_cvt_f32_f16_e32 v33, v33
	v_cvt_f32_f16_sdwa v26, v27 dst_sel:DWORD dst_unused:UNUSED_PAD src0_sel:WORD_1
	v_cvt_f32_f16_e32 v27, v28
	v_cvt_f32_f16_sdwa v54, v28 dst_sel:DWORD dst_unused:UNUSED_PAD src0_sel:WORD_1
	v_cvt_f32_f16_e32 v55, v29
	s_waitcnt vmcnt(6)
	v_cvt_f32_f16_e32 v28, v18
	v_cvt_f32_f16_sdwa v56, v18 dst_sel:DWORD dst_unused:UNUSED_PAD src0_sel:WORD_1
	v_cvt_f32_f16_e32 v57, v19
	v_cvt_f32_f16_sdwa v18, v19 dst_sel:DWORD dst_unused:UNUSED_PAD src0_sel:WORD_1
	v_cvt_f32_f16_e32 v19, v20
	v_cvt_f32_f16_sdwa v58, v20 dst_sel:DWORD dst_unused:UNUSED_PAD src0_sel:WORD_1
	v_cvt_f32_f16_e32 v59, v21
	v_cvt_f32_f16_sdwa v29, v29 dst_sel:DWORD dst_unused:UNUSED_PAD src0_sel:WORD_1
	v_cvt_f32_f16_sdwa v21, v21 dst_sel:DWORD dst_unused:UNUSED_PAD src0_sel:WORD_1
	v_cvt_f32_f16_e32 v20, v120
	s_waitcnt vmcnt(5)
	v_cvt_f32_f16_e32 v63, v22
	v_mul_f32_e32 v62, 0x3b800000, v62
	v_pk_mul_f32 v[44:45], v[44:45], s[38:39] op_sel_hi:[1,0]
	v_pk_mul_f32 v[8:9], v[8:9], s[38:39] op_sel_hi:[1,0]
	v_pk_mul_f32 v[52:53], v[52:53], s[38:39] op_sel_hi:[1,0]
	v_pk_mul_f32 v[46:47], v[46:47], s[38:39] op_sel_hi:[1,0]
	v_pk_mul_f32 v[48:49], v[48:49], s[38:39] op_sel_hi:[1,0]
	v_pk_mul_f32 v[50:51], v[50:51], s[38:39] op_sel_hi:[1,0]
	v_pk_mul_f32 v[30:31], v[30:31], s[38:39] op_sel_hi:[1,0]
	v_mul_f32_e32 v7, 0x3b800000, v7
	v_pk_mul_f32 v[32:33], v[32:33], s[38:39] op_sel_hi:[1,0]
	v_pk_mul_f32 v[26:27], v[26:27], s[38:39] op_sel_hi:[1,0]
	v_pk_mul_f32 v[54:55], v[54:55], s[38:39] op_sel_hi:[1,0]
	v_pk_mul_f32 v[56:57], v[56:57], s[38:39] op_sel_hi:[1,0]
	v_pk_mul_f32 v[18:19], v[18:19], s[38:39] op_sel_hi:[1,0]
	v_pk_mul_f32 v[58:59], v[58:59], s[38:39] op_sel_hi:[1,0]
	ds_write2_b32 v135, v44, v45 offset0:1 offset1:2
	ds_write2_b32 v135, v46, v47 offset0:3 offset1:4
	ds_write2_b32 v135, v48, v49 offset0:5 offset1:6
	ds_write2_b32 v135, v8, v9 offset0:7 offset1:8
	ds_write2_b32 v135, v50, v51 offset0:9 offset1:10
	ds_write2_b32 v135, v30, v31 offset0:11 offset1:12
	ds_write2_b32 v135, v32, v33 offset0:13 offset1:14
	v_pk_mov_b32 v[8:9], v[52:53], v[52:53] op_sel:[1,0]
	v_pk_mul_f32 v[28:29], v[28:29], s[38:39] op_sel_hi:[1,0]
	v_pk_mul_f32 v[20:21], v[20:21], s[38:39] op_sel_hi:[1,0]
	v_mul_f32_e32 v63, 0x3b800000, v63
	v_pk_mov_b32 v[26:27], v[26:27], v[26:27] op_sel:[1,0]
	v_pk_mov_b32 v[30:31], v[54:55], v[54:55] op_sel:[1,0]
	v_pk_mov_b32 v[32:33], v[56:57], v[56:57] op_sel:[1,0]
	v_pk_mov_b32 v[18:19], v[18:19], v[18:19] op_sel:[1,0]
	v_pk_mov_b32 v[44:45], v[58:59], v[58:59] op_sel:[1,0]
	ds_write_b64 v136, v[8:9]
	ds_write_b64 v137, v[26:27]
	ds_write_b64 v138, v[30:31]
	ds_write_b64 v139, v[28:29]
	ds_write_b64 v140, v[32:33]
	ds_write_b64 v141, v[18:19]
	ds_write_b64 v142, v[44:45]
	ds_write_b64 v143, v[20:21]
	v_cvt_f32_f16_e32 v9, v25
	s_waitcnt vmcnt(4)
	v_cvt_f32_f16_sdwa v18, v14 dst_sel:DWORD dst_unused:UNUSED_PAD src0_sel:WORD_1
	v_cvt_f32_f16_e32 v19, v15
	v_cvt_f32_f16_sdwa v60, v22 dst_sel:DWORD dst_unused:UNUSED_PAD src0_sel:WORD_1
	v_cvt_f32_f16_e32 v61, v23
	s_mov_b32 s10, s69
	s_mov_b32 s71, s64
	s_mov_b32 s78, s67
	v_pk_mul_f32 v[60:61], v[60:61], s[38:39] op_sel_hi:[1,0]
	s_mov_b32 s73, s50
	s_mov_b32 s76, s63
	s_waitcnt vmcnt(1)
	v_fma_mix_f32 v6, v6, s38, v40 op_sel_hi:[1,0,0]
	s_nop 0
	v_cndmask_b32_e64 v6, v62, v6, s[6:7]
	s_waitcnt vmcnt(0)
	v_fma_mix_f32 v8, v22, s38, v42 op_sel_hi:[1,0,0]
	ds_write2_b32 v135, v6, v7 offset1:15
	v_cvt_f32_f16_sdwa v6, v23 dst_sel:DWORD dst_unused:UNUSED_PAD src0_sel:WORD_1
	v_cvt_f32_f16_e32 v7, v24
	v_cndmask_b32_e64 v20, v63, v8, s[8:9]
	v_cvt_f32_f16_sdwa v8, v24 dst_sel:DWORD dst_unused:UNUSED_PAD src0_sel:WORD_1
	ds_write2_b32 v144, v60, v61 offset0:1 offset1:2
	v_pk_mul_f32 v[6:7], v[6:7], s[38:39] op_sel_hi:[1,0]
	ds_write2_b32 v144, v6, v7 offset0:3 offset1:4
	v_pk_mul_f32 v[6:7], v[8:9], s[38:39] op_sel_hi:[1,0]
	v_cvt_f32_f16_sdwa v8, v25 dst_sel:DWORD dst_unused:UNUSED_PAD src0_sel:WORD_1
	v_cvt_f32_f16_e32 v9, v14
	ds_write2_b32 v144, v6, v7 offset0:5 offset1:6
	v_cvt_f32_f16_sdwa v14, v17 dst_sel:DWORD dst_unused:UNUSED_PAD src0_sel:WORD_1
	v_pk_mul_f32 v[6:7], v[8:9], s[38:39] op_sel_hi:[1,0]
	ds_write2_b32 v144, v6, v7 offset0:7 offset1:8
	v_pk_mul_f32 v[6:7], v[18:19], s[38:39] op_sel_hi:[1,0]
	ds_write2_b32 v144, v6, v7 offset0:9 offset1:10
	v_cvt_f32_f16_sdwa v6, v15 dst_sel:DWORD dst_unused:UNUSED_PAD src0_sel:WORD_1
	v_cvt_f32_f16_e32 v7, v16
	v_cvt_f32_f16_sdwa v8, v16 dst_sel:DWORD dst_unused:UNUSED_PAD src0_sel:WORD_1
	v_cvt_f32_f16_e32 v9, v17
	v_mul_f32_e32 v14, 0x3b800000, v14
	v_pk_mul_f32 v[6:7], v[6:7], s[38:39] op_sel_hi:[1,0]
	ds_write2_b32 v144, v6, v7 offset0:11 offset1:12
	v_pk_mul_f32 v[6:7], v[8:9], s[38:39] op_sel_hi:[1,0]
	ds_write2_b32 v144, v6, v7 offset0:13 offset1:14
	v_cvt_f32_f16_sdwa v6, v10 dst_sel:DWORD dst_unused:UNUSED_PAD src0_sel:WORD_1
	v_cvt_f32_f16_e32 v7, v11
	v_cvt_f32_f16_sdwa v8, v11 dst_sel:DWORD dst_unused:UNUSED_PAD src0_sel:WORD_1
	v_cvt_f32_f16_e32 v9, v12
	ds_write2_b32 v144, v20, v14 offset1:15
	v_pk_mul_f32 v[6:7], v[6:7], s[38:39] op_sel_hi:[1,0]
	s_nop 0
	v_pk_mov_b32 v[6:7], v[6:7], v[6:7] op_sel:[1,0]
	ds_write_b64 v145, v[6:7]
	v_pk_mul_f32 v[6:7], v[8:9], s[38:39] op_sel_hi:[1,0]
	v_cvt_f32_f16_sdwa v8, v12 dst_sel:DWORD dst_unused:UNUSED_PAD src0_sel:WORD_1
	v_cvt_f32_f16_e32 v9, v13
	v_pk_mov_b32 v[6:7], v[6:7], v[6:7] op_sel:[1,0]
	ds_write_b64 v147, v[6:7]
	v_cvt_f32_f16_sdwa v7, v13 dst_sel:DWORD dst_unused:UNUSED_PAD src0_sel:WORD_1
	v_pk_mul_f32 v[8:9], v[8:9], s[38:39] op_sel_hi:[1,0]
	v_cvt_f32_f16_e32 v6, v2
	v_pk_mov_b32 v[8:9], v[8:9], v[8:9] op_sel:[1,0]
	ds_write_b64 v148, v[8:9]
	v_cvt_f32_f16_sdwa v8, v2 dst_sel:DWORD dst_unused:UNUSED_PAD src0_sel:WORD_1
	v_cvt_f32_f16_e32 v9, v3
	v_cvt_f32_f16_sdwa v2, v3 dst_sel:DWORD dst_unused:UNUSED_PAD src0_sel:WORD_1
	v_cvt_f32_f16_e32 v3, v4
	v_pk_mul_f32 v[6:7], v[6:7], s[38:39] op_sel_hi:[1,0]
	ds_write_b64 v149, v[6:7]
	v_pk_mul_f32 v[6:7], v[8:9], s[38:39] op_sel_hi:[1,0]
	v_pk_mul_f32 v[2:3], v[2:3], s[38:39] op_sel_hi:[1,0]
	v_pk_mov_b32 v[6:7], v[6:7], v[6:7] op_sel:[1,0]
	ds_write_b64 v150, v[6:7]
	v_pk_mov_b32 v[2:3], v[2:3], v[2:3] op_sel:[1,0]
	v_cvt_f32_f16_sdwa v6, v4 dst_sel:DWORD dst_unused:UNUSED_PAD src0_sel:WORD_1
	v_cvt_f32_f16_e32 v7, v5
	ds_write_b64 v151, v[2:3]
	v_cvt_f32_f16_sdwa v3, v5 dst_sel:DWORD dst_unused:UNUSED_PAD src0_sel:WORD_1
	v_cvt_f32_f16_e32 v2, v43
	v_pk_mul_f32 v[4:5], v[6:7], s[38:39] op_sel_hi:[1,0]
	v_pk_mul_f32 v[2:3], v[2:3], s[38:39] op_sel_hi:[1,0]
	v_pk_mov_b32 v[4:5], v[4:5], v[4:5] op_sel:[1,0]
	ds_write_b64 v152, v[4:5]
	ds_write_b64 v153, v[2:3]
	v_mov_b32_e32 v2, v1
	s_waitcnt lgkmcnt(0)
	s_barrier
	s_nop 0
	v_and_b32_e32 v3, 0x1ff, v2
	v_lshlrev_b32_e32 v2, 5, v2
	v_and_or_b32 v2, v2, s3, v3
	v_cvt_f32_u32_e32 v4, v3
	v_ashrrev_i32_e32 v3, 5, v2
	v_lshlrev_b32_e32 v5, 3, v2
	v_lshlrev_b32_e32 v3, 3, v3
	v_add3_u32 v40, 0, v5, v3
	v_add_u32_e32 v155, 0x10800, v40
	ds_read_b64 v[156:157], v40
	ds_read_b64 v[158:159], v40 offset:4224
	ds_read_b64 v[160:161], v40 offset:8448
	ds_read_b64 v[162:163], v40 offset:12672
	ds_read_b64 v[164:165], v40 offset:16896
	ds_read_b64 v[166:167], v40 offset:21120
	ds_read_b64 v[168:169], v40 offset:25344
	ds_read_b64 v[170:171], v40 offset:29568
	ds_read_b64 v[172:173], v40 offset:33792
	ds_read_b64 v[174:175], v40 offset:38016
	ds_read_b64 v[176:177], v40 offset:42240
	ds_read_b64 v[178:179], v40 offset:46464
	ds_read_b64 v[180:181], v40 offset:50688
	ds_read_b64 v[182:183], v40 offset:54912
	ds_read_b64 v[184:185], v40 offset:59136
	ds_read_b64 v[186:187], v40 offset:63360
	v_add_u32_e32 v201, 0x11880, v40
	v_add_u32_e32 v224, 0x12900, v40
	v_add_u32_e32 v225, 0x13980, v40
	ds_read_b64 v[188:189], v155
	ds_read_b64 v[190:191], v201
	ds_read_b64 v[192:193], v224
	ds_read_b64 v[194:195], v225
	v_add_u32_e32 v226, 0x14a00, v40
	s_waitcnt lgkmcnt(3)
	v_pk_add_f32 v[222:223], v[156:157], v[188:189]
	v_pk_add_f32 v[156:157], v[156:157], v[188:189] neg_lo:[0,1] neg_hi:[0,1]
	s_waitcnt lgkmcnt(2)
	v_pk_add_f32 v[188:189], v[158:159], v[190:191]
	v_pk_add_f32 v[158:159], v[158:159], v[190:191] neg_lo:[0,1] neg_hi:[0,1]
	v_add_u32_e32 v227, 0x15a80, v40
	v_pk_mul_f32 v[190:191], v[158:159], s[46:47]
	v_add_u32_e32 v228, 0x16b00, v40
	v_pk_fma_f32 v[158:159], v[158:159], s[42:43], v[190:191] op_sel:[0,0,1] op_sel_hi:[1,0,0]
	s_waitcnt lgkmcnt(1)
	v_pk_add_f32 v[190:191], v[160:161], v[192:193]
	v_pk_add_f32 v[160:161], v[160:161], v[192:193] neg_lo:[0,1] neg_hi:[0,1]
	v_add_u32_e32 v229, 0x17b80, v40
	v_pk_mul_f32 v[192:193], v[160:161], s[62:63]
	ds_read_b64 v[196:197], v226
	ds_read_b64 v[198:199], v227
	ds_read_b64 v[202:203], v228
	ds_read_b64 v[204:205], v229
	v_pk_fma_f32 v[160:161], v[160:161], s[50:51], v[192:193] op_sel:[0,0,1] op_sel_hi:[1,0,0]
	s_waitcnt lgkmcnt(4)
	v_pk_add_f32 v[192:193], v[162:163], v[194:195]
	v_pk_add_f32 v[162:163], v[162:163], v[194:195] neg_lo:[0,1] neg_hi:[0,1]
	v_add_u32_e32 v230, 0x18c00, v40
	v_pk_mul_f32 v[194:195], v[162:163], s[66:67]
	v_add_u32_e32 v231, 0x19c80, v40
	v_pk_fma_f32 v[162:163], v[162:163], s[64:65], v[194:195] op_sel:[0,0,1] op_sel_hi:[1,0,0]
	s_waitcnt lgkmcnt(3)
	v_pk_add_f32 v[194:195], v[164:165], v[196:197]
	v_pk_add_f32 v[164:165], v[164:165], v[196:197] neg_lo:[0,1] neg_hi:[0,1]
	v_add_u32_e32 v232, 0x1ad00, v40
	v_pk_mul_f32 v[196:197], v[164:165], s[68:69]
	v_add_u32_e32 v233, 0x1bd80, v40
	v_pk_fma_f32 v[164:165], v[164:165], s[10:11], v[196:197] op_sel:[0,0,1] op_sel_hi:[1,0,0]
	s_waitcnt lgkmcnt(2)
	v_pk_add_f32 v[196:197], v[166:167], v[198:199]
	v_pk_add_f32 v[166:167], v[166:167], v[198:199] neg_lo:[0,1] neg_hi:[0,1]
	ds_read_b64 v[206:207], v230
	ds_read_b64 v[208:209], v231
	ds_read_b64 v[210:211], v232
	ds_read_b64 v[212:213], v233
	v_pk_mul_f32 v[198:199], v[166:167], s[70:71]
	v_add_u32_e32 v234, 0x1ce00, v40
	v_pk_fma_f32 v[166:167], v[166:167], s[78:79], v[198:199] op_sel:[0,0,1] op_sel_hi:[1,0,0]
	s_waitcnt lgkmcnt(5)
	v_pk_add_f32 v[198:199], v[168:169], v[202:203]
	v_pk_add_f32 v[168:169], v[168:169], v[202:203] neg_lo:[0,1] neg_hi:[0,1]
	v_add_u32_e32 v235, 0x1de80, v40
	v_pk_mul_f32 v[202:203], v[168:169], s[72:73]
	v_add_u32_e32 v236, 0x1ef00, v40
	v_pk_fma_f32 v[168:169], v[168:169], s[76:77], v[202:203] op_sel:[0,0,1] op_sel_hi:[1,0,0]
	s_waitcnt lgkmcnt(4)
	v_pk_add_f32 v[202:203], v[170:171], v[204:205]
	v_pk_add_f32 v[170:171], v[170:171], v[204:205] neg_lo:[0,1] neg_hi:[0,1]
	v_add_u32_e32 v237, 0x1ff80, v40
	v_pk_mul_f32 v[204:205], v[170:171], s[40:41]
	ds_read_b64 v[214:215], v234
	ds_read_b64 v[216:217], v235
	ds_read_b64 v[218:219], v236
	ds_read_b64 v[220:221], v237
	v_pk_fma_f32 v[170:171], v[170:171], s[44:45], v[204:205] op_sel:[0,0,1] op_sel_hi:[1,0,0]
	s_waitcnt lgkmcnt(7)
	v_pk_add_f32 v[204:205], v[172:173], v[206:207]
	v_pk_add_f32 v[206:207], v[172:173], v[206:207] neg_lo:[0,1] neg_hi:[0,1]
	v_mul_f32_e32 v4, 0x38800000, v4
	s_waitcnt lgkmcnt(6)
	v_pk_add_f32 v[172:173], v[174:175], v[208:209]
	v_pk_add_f32 v[174:175], v[174:175], v[208:209] neg_lo:[0,1] neg_hi:[0,1]
	v_sin_f32_e32 v2, v4
	v_pk_mul_f32 v[208:209], v[174:175], s[40:41]
	v_cos_f32_e32 v4, v4
	v_pk_fma_f32 v[174:175], v[174:175], s[44:45], v[208:209] op_sel:[0,0,1] op_sel_hi:[1,0,0] neg_lo:[1,0,0] neg_hi:[1,0,0]
	s_waitcnt lgkmcnt(5)
	v_pk_add_f32 v[208:209], v[176:177], v[210:211]
	v_pk_add_f32 v[176:177], v[176:177], v[210:211] neg_lo:[0,1] neg_hi:[0,1]
	v_xor_b32_e32 v5, 0x80000000, v2
	v_pk_mul_f32 v[210:211], v[176:177], s[72:73]
	v_mov_b32_e32 v3, v5
	v_pk_fma_f32 v[176:177], v[176:177], s[76:77], v[210:211] op_sel:[0,0,1] op_sel_hi:[1,0,0] neg_lo:[1,0,0] neg_hi:[1,0,0]
	s_waitcnt lgkmcnt(4)
	v_pk_add_f32 v[210:211], v[178:179], v[212:213]
	v_pk_add_f32 v[178:179], v[178:179], v[212:213] neg_lo:[0,1] neg_hi:[0,1]
	v_pk_mul_f32 v[6:7], v[4:5], v[2:3] op_sel:[1,0] op_sel_hi:[0,1]
	v_pk_mul_f32 v[212:213], v[178:179], s[70:71]
	v_pk_fma_f32 v[6:7], v[4:5], v[4:5], v[6:7] op_sel_hi:[1,0,1]
	v_pk_fma_f32 v[178:179], v[178:179], s[78:79], v[212:213] op_sel:[0,0,1] op_sel_hi:[1,0,0] neg_lo:[1,0,0] neg_hi:[1,0,0]
	s_waitcnt lgkmcnt(3)
	v_pk_add_f32 v[212:213], v[180:181], v[214:215]
	v_pk_add_f32 v[180:181], v[180:181], v[214:215] neg_lo:[0,1] neg_hi:[0,1]
	s_nop 0
	v_pk_mul_f32 v[214:215], v[180:181], s[68:69]
	s_nop 0
	v_pk_fma_f32 v[180:181], v[180:181], s[10:11], v[214:215] op_sel:[0,0,1] op_sel_hi:[1,0,0] neg_lo:[1,0,0] neg_hi:[1,0,0]
	s_waitcnt lgkmcnt(2)
	v_pk_add_f32 v[214:215], v[182:183], v[216:217]
	v_pk_add_f32 v[182:183], v[182:183], v[216:217] neg_lo:[0,1] neg_hi:[0,1]
	v_pk_mul_f32 v[10:11], v[6:7], v[6:7] op_sel:[1,1] op_sel_hi:[0,1] neg_lo:[0,1]
	v_pk_mul_f32 v[216:217], v[182:183], s[66:67]
	v_pk_fma_f32 v[10:11], v[6:7], v[6:7], v[10:11] op_sel_hi:[1,0,1]
	v_pk_fma_f32 v[182:183], v[182:183], s[64:65], v[216:217] op_sel:[0,0,1] op_sel_hi:[1,0,0] neg_lo:[1,0,0] neg_hi:[1,0,0]
	s_waitcnt lgkmcnt(1)
	v_pk_add_f32 v[216:217], v[184:185], v[218:219]
	v_pk_add_f32 v[184:185], v[184:185], v[218:219] neg_lo:[0,1] neg_hi:[0,1]
	s_nop 0
	v_pk_mul_f32 v[218:219], v[184:185], s[62:63]
	s_nop 0
	v_pk_fma_f32 v[184:185], v[184:185], s[50:51], v[218:219] op_sel:[0,0,1] op_sel_hi:[1,0,0] neg_lo:[1,0,0] neg_hi:[1,0,0]
	s_waitcnt lgkmcnt(0)
	v_pk_add_f32 v[218:219], v[186:187], v[220:221]
	v_pk_add_f32 v[186:187], v[186:187], v[220:221] neg_lo:[0,1] neg_hi:[0,1]
	v_pk_mul_f32 v[26:27], v[10:11], v[10:11] op_sel:[1,1] op_sel_hi:[0,1] neg_lo:[0,1]
	v_pk_mul_f32 v[220:221], v[186:187], s[46:47]
	v_pk_fma_f32 v[26:27], v[10:11], v[10:11], v[26:27] op_sel_hi:[1,0,1]
	v_pk_fma_f32 v[186:187], v[186:187], s[42:43], v[220:221] op_sel:[0,0,1] op_sel_hi:[1,0,0] neg_lo:[1,0,0] neg_hi:[1,0,0]
	v_pk_add_f32 v[220:221], v[222:223], v[204:205]
	v_pk_add_f32 v[204:205], v[222:223], v[204:205] neg_lo:[0,1] neg_hi:[0,1]
	v_pk_add_f32 v[222:223], v[188:189], v[172:173]
	v_pk_add_f32 v[172:173], v[188:189], v[172:173] neg_lo:[0,1] neg_hi:[0,1]
	v_pk_mul_f32 v[50:51], v[10:11], v[26:27] op_sel:[1,1] op_sel_hi:[1,0] neg_lo:[1,0]
	v_pk_mul_f32 v[188:189], v[172:173], s[62:63]
	v_pk_fma_f32 v[50:51], v[10:11], v[26:27], v[50:51] op_sel_hi:[0,1,1]
	v_pk_fma_f32 v[172:173], v[172:173], s[50:51], v[188:189] op_sel:[0,0,1] op_sel_hi:[1,0,0]
	v_pk_add_f32 v[188:189], v[190:191], v[208:209]
	v_pk_add_f32 v[190:191], v[190:191], v[208:209] neg_lo:[0,1] neg_hi:[0,1]
	v_pk_mul_f32 v[66:67], v[10:11], v[50:51] op_sel:[1,1] op_sel_hi:[1,0] neg_lo:[1,0]
	v_pk_mul_f32 v[208:209], v[190:191], s[68:69]
	v_pk_fma_f32 v[66:67], v[10:11], v[50:51], v[66:67] op_sel_hi:[0,1,1]
	v_pk_fma_f32 v[190:191], v[190:191], s[10:11], v[208:209] op_sel:[0,0,1] op_sel_hi:[1,0,0]
	v_pk_add_f32 v[208:209], v[192:193], v[210:211]
	v_pk_add_f32 v[192:193], v[192:193], v[210:211] neg_lo:[0,1] neg_hi:[0,1]
	v_pk_mul_f32 v[82:83], v[10:11], v[66:67] op_sel:[1,1] op_sel_hi:[1,0] neg_lo:[1,0]
	v_pk_mul_f32 v[210:211], v[192:193], s[72:73]
	v_pk_fma_f32 v[82:83], v[10:11], v[66:67], v[82:83] op_sel_hi:[0,1,1]
	v_pk_fma_f32 v[192:193], v[192:193], s[76:77], v[210:211] op_sel:[0,0,1] op_sel_hi:[1,0,0]
	v_pk_add_f32 v[210:211], v[194:195], v[212:213]
	v_pk_add_f32 v[212:213], v[194:195], v[212:213] neg_lo:[0,1] neg_hi:[0,1]
	v_pk_mul_f32 v[98:99], v[10:11], v[82:83] op_sel:[1,1] op_sel_hi:[1,0] neg_lo:[1,0]
	v_pk_add_f32 v[194:195], v[196:197], v[214:215]
	v_pk_add_f32 v[196:197], v[196:197], v[214:215] neg_lo:[0,1] neg_hi:[0,1]
	v_pk_fma_f32 v[98:99], v[10:11], v[82:83], v[98:99] op_sel_hi:[0,1,1]
	v_pk_mul_f32 v[214:215], v[196:197], s[72:73]
	v_pk_mul_f32 v[114:115], v[10:11], v[98:99] op_sel:[1,1] op_sel_hi:[1,0] neg_lo:[1,0]
	v_pk_fma_f32 v[196:197], v[196:197], s[76:77], v[214:215] op_sel:[0,0,1] op_sel_hi:[1,0,0] neg_lo:[1,0,0] neg_hi:[1,0,0]
	v_pk_add_f32 v[214:215], v[198:199], v[216:217]
	v_pk_add_f32 v[198:199], v[198:199], v[216:217] neg_lo:[0,1] neg_hi:[0,1]
	v_pk_mul_f32 v[8:9], v[2:3], v[6:7] op_sel:[0,1] op_sel_hi:[1,0]
	v_pk_mul_f32 v[216:217], v[198:199], s[68:69]
	v_pk_fma_f32 v[114:115], v[10:11], v[98:99], v[114:115] op_sel_hi:[0,1,1]
	v_pk_fma_f32 v[198:199], v[198:199], s[10:11], v[216:217] op_sel:[0,0,1] op_sel_hi:[1,0,0] neg_lo:[1,0,0] neg_hi:[1,0,0]
	v_pk_add_f32 v[216:217], v[202:203], v[218:219]
	v_pk_add_f32 v[202:203], v[202:203], v[218:219] neg_lo:[0,1] neg_hi:[0,1]
	v_pk_fma_f32 v[8:9], v[4:5], v[6:7], v[8:9] op_sel_hi:[0,1,1]
	v_pk_mul_f32 v[218:219], v[202:203], s[62:63]
	v_pk_mul_f32 v[16:17], v[2:3], v[10:11] op_sel:[0,1] op_sel_hi:[1,0]
	v_pk_fma_f32 v[202:203], v[202:203], s[50:51], v[218:219] op_sel:[0,0,1] op_sel_hi:[1,0,0] neg_lo:[1,0,0] neg_hi:[1,0,0]
	v_pk_add_f32 v[218:219], v[156:157], v[206:207] op_sel:[0,1] op_sel_hi:[1,0] neg_hi:[0,1]
	v_pk_add_f32 v[156:157], v[156:157], v[206:207] op_sel:[0,1] op_sel_hi:[1,0] neg_lo:[0,1]
	v_pk_add_f32 v[206:207], v[158:159], v[174:175]
	v_pk_add_f32 v[158:159], v[158:159], v[174:175] neg_lo:[0,1] neg_hi:[0,1]
	v_pk_mul_f32 v[30:31], v[2:3], v[26:27] op_sel:[0,1] op_sel_hi:[1,0]
	v_pk_mul_f32 v[174:175], v[158:159], s[62:63]
	v_pk_mul_f32 v[54:55], v[2:3], v[50:51] op_sel:[0,1] op_sel_hi:[1,0]
	v_pk_fma_f32 v[158:159], v[158:159], s[50:51], v[174:175] op_sel:[0,0,1] op_sel_hi:[1,0,0]
	v_pk_add_f32 v[174:175], v[160:161], v[176:177]
	v_pk_add_f32 v[160:161], v[160:161], v[176:177] neg_lo:[0,1] neg_hi:[0,1]
	v_pk_mul_f32 v[70:71], v[2:3], v[66:67] op_sel:[0,1] op_sel_hi:[1,0]
	v_pk_mul_f32 v[176:177], v[160:161], s[68:69]
	v_pk_mul_f32 v[86:87], v[2:3], v[82:83] op_sel:[0,1] op_sel_hi:[1,0]
	v_pk_fma_f32 v[160:161], v[160:161], s[10:11], v[176:177] op_sel:[0,0,1] op_sel_hi:[1,0,0]
	v_pk_add_f32 v[176:177], v[162:163], v[178:179]
	v_pk_add_f32 v[162:163], v[162:163], v[178:179] neg_lo:[0,1] neg_hi:[0,1]
	v_pk_mul_f32 v[102:103], v[2:3], v[98:99] op_sel:[0,1] op_sel_hi:[1,0]
	v_pk_mul_f32 v[178:179], v[162:163], s[72:73]
	v_pk_mul_f32 v[118:119], v[2:3], v[114:115] op_sel:[0,1] op_sel_hi:[1,0]
	v_pk_fma_f32 v[162:163], v[162:163], s[76:77], v[178:179] op_sel:[0,0,1] op_sel_hi:[1,0,0]
	v_pk_add_f32 v[178:179], v[164:165], v[180:181]
	v_pk_add_f32 v[180:181], v[164:165], v[180:181] neg_lo:[0,1] neg_hi:[0,1]
	v_pk_add_f32 v[164:165], v[166:167], v[182:183]
	v_pk_add_f32 v[166:167], v[166:167], v[182:183] neg_lo:[0,1] neg_hi:[0,1]
	s_nop 0
	v_pk_mul_f32 v[182:183], v[166:167], s[72:73]
	v_pk_fma_f32 v[16:17], v[4:5], v[10:11], v[16:17] op_sel_hi:[0,1,1]
	v_pk_fma_f32 v[166:167], v[166:167], s[76:77], v[182:183] op_sel:[0,0,1] op_sel_hi:[1,0,0] neg_lo:[1,0,0] neg_hi:[1,0,0]
	v_pk_add_f32 v[182:183], v[168:169], v[184:185]
	v_pk_add_f32 v[168:169], v[168:169], v[184:185] neg_lo:[0,1] neg_hi:[0,1]
	v_pk_mul_f32 v[18:19], v[6:7], v[10:11] op_sel:[1,1] op_sel_hi:[1,0] neg_lo:[1,0]
	v_pk_mul_f32 v[184:185], v[168:169], s[68:69]
	v_pk_fma_f32 v[30:31], v[4:5], v[26:27], v[30:31] op_sel_hi:[0,1,1]
	v_pk_fma_f32 v[168:169], v[168:169], s[10:11], v[184:185] op_sel:[0,0,1] op_sel_hi:[1,0,0] neg_lo:[1,0,0] neg_hi:[1,0,0]
	v_pk_add_f32 v[184:185], v[170:171], v[186:187]
	v_pk_add_f32 v[170:171], v[170:171], v[186:187] neg_lo:[0,1] neg_hi:[0,1]
	v_pk_mul_f32 v[42:43], v[6:7], v[26:27] op_sel:[1,1] op_sel_hi:[1,0] neg_lo:[1,0]
	v_pk_mul_f32 v[186:187], v[170:171], s[62:63]
	v_pk_fma_f32 v[54:55], v[4:5], v[50:51], v[54:55] op_sel_hi:[0,1,1]
	v_pk_fma_f32 v[170:171], v[170:171], s[50:51], v[186:187] op_sel:[0,0,1] op_sel_hi:[1,0,0] neg_lo:[1,0,0] neg_hi:[1,0,0]
	v_pk_add_f32 v[186:187], v[220:221], v[210:211]
	v_pk_add_f32 v[210:211], v[220:221], v[210:211] neg_lo:[0,1] neg_hi:[0,1]
	v_pk_add_f32 v[220:221], v[222:223], v[194:195]
	v_pk_add_f32 v[194:195], v[222:223], v[194:195] neg_lo:[0,1] neg_hi:[0,1]
	v_pk_mul_f32 v[58:59], v[6:7], v[50:51] op_sel:[1,1] op_sel_hi:[1,0] neg_lo:[1,0]
	v_pk_mul_f32 v[222:223], v[194:195], s[68:69]
	v_pk_fma_f32 v[70:71], v[4:5], v[66:67], v[70:71] op_sel_hi:[0,1,1]
	v_pk_fma_f32 v[194:195], v[194:195], s[10:11], v[222:223] op_sel:[0,0,1] op_sel_hi:[1,0,0]
	v_pk_add_f32 v[222:223], v[188:189], v[214:215]
	v_pk_add_f32 v[214:215], v[188:189], v[214:215] neg_lo:[0,1] neg_hi:[0,1]
	v_pk_mul_f32 v[74:75], v[6:7], v[66:67] op_sel:[1,1] op_sel_hi:[1,0] neg_lo:[1,0]
	v_pk_add_f32 v[188:189], v[208:209], v[216:217]
	v_pk_add_f32 v[208:209], v[208:209], v[216:217] neg_lo:[0,1] neg_hi:[0,1]
	v_pk_fma_f32 v[86:87], v[4:5], v[82:83], v[86:87] op_sel_hi:[0,1,1]
	v_pk_mul_f32 v[216:217], v[208:209], s[68:69]
	v_pk_mul_f32 v[90:91], v[6:7], v[82:83] op_sel:[1,1] op_sel_hi:[1,0] neg_lo:[1,0]
	v_pk_fma_f32 v[208:209], v[208:209], s[10:11], v[216:217] op_sel:[0,0,1] op_sel_hi:[1,0,0] neg_lo:[1,0,0] neg_hi:[1,0,0]
	v_pk_add_f32 v[216:217], v[204:205], v[212:213] op_sel:[0,1] op_sel_hi:[1,0] neg_hi:[0,1]
	v_pk_add_f32 v[204:205], v[204:205], v[212:213] op_sel:[0,1] op_sel_hi:[1,0] neg_lo:[0,1]
	v_pk_add_f32 v[212:213], v[172:173], v[196:197]
	v_pk_add_f32 v[172:173], v[172:173], v[196:197] neg_lo:[0,1] neg_hi:[0,1]
	v_pk_fma_f32 v[102:103], v[4:5], v[98:99], v[102:103] op_sel_hi:[0,1,1]
	v_pk_mul_f32 v[196:197], v[172:173], s[68:69]
	v_pk_mul_f32 v[106:107], v[6:7], v[98:99] op_sel:[1,1] op_sel_hi:[1,0] neg_lo:[1,0]
	v_pk_fma_f32 v[172:173], v[172:173], s[10:11], v[196:197] op_sel:[0,0,1] op_sel_hi:[1,0,0]
	v_pk_add_f32 v[196:197], v[190:191], v[198:199]
	v_pk_add_f32 v[198:199], v[190:191], v[198:199] neg_lo:[0,1] neg_hi:[0,1]
	v_pk_fma_f32 v[118:119], v[4:5], v[114:115], v[118:119] op_sel_hi:[0,1,1]
	v_pk_add_f32 v[190:191], v[192:193], v[202:203]
	v_pk_add_f32 v[192:193], v[192:193], v[202:203] neg_lo:[0,1] neg_hi:[0,1]
	v_pk_mul_f32 v[122:123], v[6:7], v[114:115] op_sel:[1,1] op_sel_hi:[1,0] neg_lo:[1,0]
	v_pk_mul_f32 v[202:203], v[192:193], s[68:69]
	v_pk_fma_f32 v[18:19], v[6:7], v[10:11], v[18:19] op_sel_hi:[0,1,1]
	v_pk_fma_f32 v[192:193], v[192:193], s[10:11], v[202:203] op_sel:[0,0,1] op_sel_hi:[1,0,0] neg_lo:[1,0,0] neg_hi:[1,0,0]
	v_pk_add_f32 v[202:203], v[218:219], v[178:179]
	v_pk_add_f32 v[178:179], v[218:219], v[178:179] neg_lo:[0,1] neg_hi:[0,1]
	v_pk_add_f32 v[218:219], v[206:207], v[164:165]
	v_pk_add_f32 v[164:165], v[206:207], v[164:165] neg_lo:[0,1] neg_hi:[0,1]
	v_pk_mul_f32 v[22:23], v[10:11], v[8:9] op_sel:[1,1] op_sel_hi:[0,1] neg_lo:[0,1]
	v_pk_mul_f32 v[206:207], v[164:165], s[68:69]
	v_pk_fma_f32 v[42:43], v[6:7], v[26:27], v[42:43] op_sel_hi:[0,1,1]
	v_pk_fma_f32 v[164:165], v[164:165], s[10:11], v[206:207] op_sel:[0,0,1] op_sel_hi:[1,0,0]
	v_pk_add_f32 v[206:207], v[174:175], v[182:183]
	v_pk_add_f32 v[182:183], v[174:175], v[182:183] neg_lo:[0,1] neg_hi:[0,1]
	v_pk_mul_f32 v[46:47], v[8:9], v[26:27] op_sel:[1,1] op_sel_hi:[1,0] neg_lo:[1,0]
	v_pk_add_f32 v[174:175], v[176:177], v[184:185]
	v_pk_add_f32 v[176:177], v[176:177], v[184:185] neg_lo:[0,1] neg_hi:[0,1]
	v_pk_fma_f32 v[58:59], v[6:7], v[50:51], v[58:59] op_sel_hi:[0,1,1]
	v_pk_mul_f32 v[184:185], v[176:177], s[68:69]
	v_pk_mul_f32 v[62:63], v[8:9], v[50:51] op_sel:[1,1] op_sel_hi:[1,0] neg_lo:[1,0]
	v_pk_fma_f32 v[176:177], v[176:177], s[10:11], v[184:185] op_sel:[0,0,1] op_sel_hi:[1,0,0] neg_lo:[1,0,0] neg_hi:[1,0,0]
	v_pk_add_f32 v[184:185], v[156:157], v[180:181] op_sel:[0,1] op_sel_hi:[1,0] neg_hi:[0,1]
	v_pk_add_f32 v[156:157], v[156:157], v[180:181] op_sel:[0,1] op_sel_hi:[1,0] neg_lo:[0,1]
	v_pk_add_f32 v[180:181], v[158:159], v[166:167]
	v_pk_add_f32 v[158:159], v[158:159], v[166:167] neg_lo:[0,1] neg_hi:[0,1]
	v_pk_fma_f32 v[74:75], v[6:7], v[66:67], v[74:75] op_sel_hi:[0,1,1]
	v_pk_mul_f32 v[166:167], v[158:159], s[68:69]
	v_pk_mul_f32 v[78:79], v[8:9], v[66:67] op_sel:[1,1] op_sel_hi:[1,0] neg_lo:[1,0]
	v_pk_fma_f32 v[158:159], v[158:159], s[10:11], v[166:167] op_sel:[0,0,1] op_sel_hi:[1,0,0]
	v_pk_add_f32 v[166:167], v[160:161], v[168:169]
	v_pk_add_f32 v[168:169], v[160:161], v[168:169] neg_lo:[0,1] neg_hi:[0,1]
	v_pk_fma_f32 v[90:91], v[6:7], v[82:83], v[90:91] op_sel_hi:[0,1,1]
	v_pk_add_f32 v[160:161], v[162:163], v[170:171]
	v_pk_add_f32 v[162:163], v[162:163], v[170:171] neg_lo:[0,1] neg_hi:[0,1]
	v_pk_mul_f32 v[94:95], v[8:9], v[82:83] op_sel:[1,1] op_sel_hi:[1,0] neg_lo:[1,0]
	v_pk_mul_f32 v[170:171], v[162:163], s[68:69]
	v_pk_fma_f32 v[106:107], v[6:7], v[98:99], v[106:107] op_sel_hi:[0,1,1]
	v_pk_fma_f32 v[162:163], v[162:163], s[10:11], v[170:171] op_sel:[0,0,1] op_sel_hi:[1,0,0] neg_lo:[1,0,0] neg_hi:[1,0,0]
	v_pk_add_f32 v[170:171], v[186:187], v[222:223]
	v_pk_add_f32 v[186:187], v[186:187], v[222:223] neg_lo:[0,1] neg_hi:[0,1]
	v_pk_add_f32 v[222:223], v[220:221], v[188:189]
	v_pk_add_f32 v[220:221], v[220:221], v[188:189] neg_lo:[0,1] neg_hi:[0,1]
	v_pk_mul_f32 v[110:111], v[8:9], v[98:99] op_sel:[1,1] op_sel_hi:[1,0] neg_lo:[1,0]
	v_pk_add_f32 v[188:189], v[210:211], v[214:215] op_sel:[0,1] op_sel_hi:[1,0] neg_hi:[0,1]
	v_pk_add_f32 v[210:211], v[210:211], v[214:215] op_sel:[0,1] op_sel_hi:[1,0] neg_lo:[0,1]
	v_pk_add_f32 v[214:215], v[194:195], v[208:209]
	v_pk_add_f32 v[208:209], v[194:195], v[208:209] neg_lo:[0,1] neg_hi:[0,1]
	v_pk_fma_f32 v[122:123], v[6:7], v[114:115], v[122:123] op_sel_hi:[0,1,1]
	v_pk_add_f32 v[194:195], v[216:217], v[196:197]
	v_pk_add_f32 v[196:197], v[216:217], v[196:197] neg_lo:[0,1] neg_hi:[0,1]
	v_pk_add_f32 v[216:217], v[212:213], v[190:191]
	v_pk_add_f32 v[212:213], v[212:213], v[190:191] neg_lo:[0,1] neg_hi:[0,1]
	v_pk_mul_f32 v[126:127], v[8:9], v[114:115] op_sel:[1,1] op_sel_hi:[1,0] neg_lo:[1,0]
	v_pk_add_f32 v[190:191], v[204:205], v[198:199] op_sel:[0,1] op_sel_hi:[1,0] neg_hi:[0,1]
	v_pk_add_f32 v[198:199], v[204:205], v[198:199] op_sel:[0,1] op_sel_hi:[1,0] neg_lo:[0,1]
	v_pk_add_f32 v[204:205], v[172:173], v[192:193]
	v_pk_add_f32 v[192:193], v[172:173], v[192:193] neg_lo:[0,1] neg_hi:[0,1]
	v_xor_b32_e32 v24, 0x80000000, v17
	v_pk_add_f32 v[172:173], v[202:203], v[206:207]
	v_pk_add_f32 v[202:203], v[202:203], v[206:207] neg_lo:[0,1] neg_hi:[0,1]
	v_pk_add_f32 v[206:207], v[218:219], v[174:175]
	v_pk_add_f32 v[218:219], v[218:219], v[174:175] neg_lo:[0,1] neg_hi:[0,1]
	v_xor_b32_e32 v28, 0x80000000, v19
	v_pk_add_f32 v[174:175], v[178:179], v[182:183] op_sel:[0,1] op_sel_hi:[1,0] neg_hi:[0,1]
	v_pk_add_f32 v[178:179], v[178:179], v[182:183] op_sel:[0,1] op_sel_hi:[1,0] neg_lo:[0,1]
	v_pk_add_f32 v[182:183], v[164:165], v[176:177]
	v_pk_add_f32 v[176:177], v[164:165], v[176:177] neg_lo:[0,1] neg_hi:[0,1]
	v_pk_fma_f32 v[22:23], v[10:11], v[8:9], v[22:23] op_sel_hi:[1,0,1]
	v_pk_add_f32 v[164:165], v[184:185], v[166:167]
	v_pk_add_f32 v[166:167], v[184:185], v[166:167] neg_lo:[0,1] neg_hi:[0,1]
	v_pk_add_f32 v[184:185], v[180:181], v[160:161]
	v_pk_add_f32 v[180:181], v[180:181], v[160:161] neg_lo:[0,1] neg_hi:[0,1]
	v_pk_fma_f32 v[46:47], v[8:9], v[26:27], v[46:47] op_sel_hi:[0,1,1]
	v_pk_add_f32 v[160:161], v[156:157], v[168:169] op_sel:[0,1] op_sel_hi:[1,0] neg_hi:[0,1]
	v_pk_add_f32 v[156:157], v[156:157], v[168:169] op_sel:[0,1] op_sel_hi:[1,0] neg_lo:[0,1]
	v_pk_add_f32 v[168:169], v[158:159], v[162:163]
	v_pk_add_f32 v[162:163], v[158:159], v[162:163] neg_lo:[0,1] neg_hi:[0,1]
	v_pk_fma_f32 v[62:63], v[8:9], v[50:51], v[62:63] op_sel_hi:[0,1,1]
	v_pk_add_f32 v[158:159], v[170:171], v[222:223]
	v_pk_add_f32 v[170:171], v[170:171], v[222:223] neg_lo:[0,1] neg_hi:[0,1]
	v_pk_add_f32 v[222:223], v[186:187], v[220:221] op_sel:[0,1] op_sel_hi:[1,0] neg_hi:[0,1]
	v_pk_add_f32 v[186:187], v[186:187], v[220:221] op_sel:[0,1] op_sel_hi:[1,0] neg_lo:[0,1]
	v_pk_add_f32 v[220:221], v[188:189], v[214:215]
	v_pk_add_f32 v[188:189], v[188:189], v[214:215] neg_lo:[0,1] neg_hi:[0,1]
	v_pk_add_f32 v[214:215], v[210:211], v[208:209] op_sel:[0,1] op_sel_hi:[1,0] neg_hi:[0,1]
	v_pk_add_f32 v[208:209], v[210:211], v[208:209] op_sel:[0,1] op_sel_hi:[1,0] neg_lo:[0,1]
	v_pk_add_f32 v[210:211], v[194:195], v[216:217]
	v_pk_add_f32 v[194:195], v[194:195], v[216:217] neg_lo:[0,1] neg_hi:[0,1]
	v_pk_add_f32 v[216:217], v[196:197], v[212:213] op_sel:[0,1] op_sel_hi:[1,0] neg_hi:[0,1]
	v_pk_add_f32 v[196:197], v[196:197], v[212:213] op_sel:[0,1] op_sel_hi:[1,0] neg_lo:[0,1]
	v_pk_add_f32 v[212:213], v[190:191], v[204:205]
	v_pk_add_f32 v[190:191], v[190:191], v[204:205] neg_lo:[0,1] neg_hi:[0,1]
	v_pk_add_f32 v[204:205], v[198:199], v[192:193] op_sel:[0,1] op_sel_hi:[1,0] neg_hi:[0,1]
	v_pk_add_f32 v[192:193], v[198:199], v[192:193] op_sel:[0,1] op_sel_hi:[1,0] neg_lo:[0,1]
	v_pk_add_f32 v[198:199], v[172:173], v[206:207]
	v_pk_add_f32 v[172:173], v[172:173], v[206:207] neg_lo:[0,1] neg_hi:[0,1]
	v_pk_mul_f32 v[2:3], v[2:3], v[198:199] op_sel:[0,1] op_sel_hi:[1,0]
	v_pk_add_f32 v[206:207], v[202:203], v[218:219] op_sel:[0,1] op_sel_hi:[1,0] neg_hi:[0,1]
	v_pk_add_f32 v[202:203], v[202:203], v[218:219] op_sel:[0,1] op_sel_hi:[1,0] neg_lo:[0,1]
	v_pk_add_f32 v[218:219], v[174:175], v[182:183]
	v_pk_add_f32 v[174:175], v[174:175], v[182:183] neg_lo:[0,1] neg_hi:[0,1]
	v_pk_add_f32 v[182:183], v[178:179], v[176:177] op_sel:[0,1] op_sel_hi:[1,0] neg_hi:[0,1]
	v_pk_add_f32 v[176:177], v[178:179], v[176:177] op_sel:[0,1] op_sel_hi:[1,0] neg_lo:[0,1]
	v_pk_add_f32 v[178:179], v[164:165], v[184:185]
	v_pk_fma_f32 v[2:3], v[4:5], v[198:199], v[2:3] op_sel_hi:[0,1,1]
	v_pk_mul_f32 v[4:5], v[6:7], v[210:211] op_sel:[1,1] op_sel_hi:[1,0] neg_lo:[1,0]
	v_pk_fma_f32 v[78:79], v[8:9], v[66:67], v[78:79] op_sel_hi:[0,1,1]
	v_pk_fma_f32 v[4:5], v[6:7], v[210:211], v[4:5] op_sel_hi:[0,1,1]
	v_pk_mul_f32 v[6:7], v[8:9], v[178:179] op_sel:[1,1] op_sel_hi:[1,0] neg_lo:[1,0]
	v_pk_fma_f32 v[94:95], v[8:9], v[82:83], v[94:95] op_sel_hi:[0,1,1]
	v_pk_fma_f32 v[110:111], v[8:9], v[98:99], v[110:111] op_sel_hi:[0,1,1]
	v_pk_fma_f32 v[126:127], v[8:9], v[114:115], v[126:127] op_sel_hi:[0,1,1]
	v_mov_b32_e32 v25, v17
	v_mov_b32_e32 v29, v19
	v_pk_fma_f32 v[6:7], v[8:9], v[178:179], v[6:7] op_sel_hi:[0,1,1]
	v_pk_mul_f32 v[8:9], v[10:11], v[220:221] op_sel:[1,1] op_sel_hi:[1,0] neg_lo:[1,0]
	v_pk_add_f32 v[164:165], v[164:165], v[184:185] neg_lo:[0,1] neg_hi:[0,1]
	v_pk_add_f32 v[184:185], v[166:167], v[180:181] op_sel:[0,1] op_sel_hi:[1,0] neg_hi:[0,1]
	v_pk_add_f32 v[166:167], v[166:167], v[180:181] op_sel:[0,1] op_sel_hi:[1,0] neg_lo:[0,1]
	v_pk_add_f32 v[180:181], v[160:161], v[168:169]
	v_pk_fma_f32 v[8:9], v[10:11], v[220:221], v[8:9] op_sel_hi:[0,1,1]
	v_pk_mul_f32 v[10:11], v[24:25], v[218:219] op_sel:[0,1] op_sel_hi:[1,0]
	v_pk_mul_f32 v[12:13], v[28:29], v[212:213] op_sel:[0,1] op_sel_hi:[1,0]
	v_pk_add_f32 v[160:161], v[160:161], v[168:169] neg_lo:[0,1] neg_hi:[0,1]
	v_pk_add_f32 v[168:169], v[156:157], v[162:163] op_sel:[0,1] op_sel_hi:[1,0] neg_hi:[0,1]
	v_pk_fma_f32 v[10:11], v[16:17], v[218:219], v[10:11] op_sel_hi:[0,1,1]
	v_pk_fma_f32 v[12:13], v[18:19], v[212:213], v[12:13] op_sel_hi:[0,1,1]
	v_pk_mul_f32 v[14:15], v[22:23], v[180:181] op_sel:[1,1] op_sel_hi:[1,0] neg_lo:[1,0]
	v_pk_mul_f32 v[16:17], v[26:27], v[222:223] op_sel:[1,1] op_sel_hi:[1,0] neg_lo:[1,0]
	v_pk_mul_f32 v[18:19], v[30:31], v[206:207] op_sel:[1,1] op_sel_hi:[1,0] neg_lo:[1,0]
	v_pk_mul_f32 v[20:21], v[42:43], v[216:217] op_sel:[1,1] op_sel_hi:[1,0] neg_lo:[1,0]
	v_xor_b32_e32 v84, 0x80000000, v75
	v_xor_b32_e32 v88, 0x80000000, v79
	v_xor_b32_e32 v92, 0x80000000, v83
	v_xor_b32_e32 v96, 0x80000000, v87
	v_xor_b32_e32 v100, 0x80000000, v91
	v_xor_b32_e32 v104, 0x80000000, v95
	v_xor_b32_e32 v108, 0x80000000, v99
	v_xor_b32_e32 v112, 0x80000000, v103
	v_xor_b32_e32 v116, 0x80000000, v107
	v_xor_b32_e32 v120, 0x80000000, v111
	v_xor_b32_e32 v124, 0x80000000, v115
	v_xor_b32_e32 v128, 0x80000000, v119
	v_xor_b32_e32 v130, 0x80000000, v123
	v_xor_b32_e32 v132, 0x80000000, v127
	v_mov_b32_e32 v85, v75
	v_mov_b32_e32 v89, v79
	v_mov_b32_e32 v93, v83
	v_mov_b32_e32 v97, v87
	v_mov_b32_e32 v101, v91
	v_mov_b32_e32 v105, v95
	v_mov_b32_e32 v109, v99
	v_mov_b32_e32 v113, v103
	v_mov_b32_e32 v117, v107
	v_mov_b32_e32 v121, v111
	v_mov_b32_e32 v125, v115
	v_mov_b32_e32 v129, v119
	v_mov_b32_e32 v131, v123
	v_mov_b32_e32 v133, v127
	v_pk_add_f32 v[156:157], v[156:157], v[162:163] op_sel:[0,1] op_sel_hi:[1,0] neg_lo:[0,1]
	v_pk_fma_f32 v[14:15], v[22:23], v[180:181], v[14:15] op_sel_hi:[0,1,1]
	v_pk_fma_f32 v[16:17], v[26:27], v[222:223], v[16:17] op_sel_hi:[0,1,1]
	v_pk_fma_f32 v[18:19], v[30:31], v[206:207], v[18:19] op_sel_hi:[0,1,1]
	v_pk_fma_f32 v[20:21], v[42:43], v[216:217], v[20:21] op_sel_hi:[0,1,1]
	v_pk_mul_f32 v[22:23], v[46:47], v[184:185] op_sel:[1,1] op_sel_hi:[1,0] neg_lo:[1,0]
	v_pk_mul_f32 v[24:25], v[50:51], v[214:215] op_sel:[1,1] op_sel_hi:[1,0] neg_lo:[1,0]
	v_pk_mul_f32 v[26:27], v[54:55], v[182:183] op_sel:[1,1] op_sel_hi:[1,0] neg_lo:[1,0]
	v_pk_mul_f32 v[28:29], v[58:59], v[204:205] op_sel:[1,1] op_sel_hi:[1,0] neg_lo:[1,0]
	v_pk_mul_f32 v[30:31], v[62:63], v[168:169] op_sel:[1,1] op_sel_hi:[1,0] neg_lo:[1,0]
	v_pk_mul_f32 v[32:33], v[66:67], v[170:171] op_sel:[1,1] op_sel_hi:[1,0] neg_lo:[1,0]
	v_pk_mul_f32 v[42:43], v[70:71], v[172:173] op_sel:[1,1] op_sel_hi:[1,0] neg_lo:[1,0]
	v_pk_fma_f32 v[22:23], v[46:47], v[184:185], v[22:23] op_sel_hi:[0,1,1]
	v_pk_fma_f32 v[24:25], v[50:51], v[214:215], v[24:25] op_sel_hi:[0,1,1]
	v_pk_fma_f32 v[26:27], v[54:55], v[182:183], v[26:27] op_sel_hi:[0,1,1]
	v_pk_fma_f32 v[28:29], v[58:59], v[204:205], v[28:29] op_sel_hi:[0,1,1]
	v_pk_fma_f32 v[30:31], v[62:63], v[168:169], v[30:31] op_sel_hi:[0,1,1]
	v_pk_fma_f32 v[32:33], v[66:67], v[170:171], v[32:33] op_sel_hi:[0,1,1]
	v_pk_fma_f32 v[42:43], v[70:71], v[172:173], v[42:43] op_sel_hi:[0,1,1]
	v_pk_mul_f32 v[44:45], v[84:85], v[194:195] op_sel:[0,1] op_sel_hi:[1,0]
	v_pk_mul_f32 v[46:47], v[88:89], v[164:165] op_sel:[0,1] op_sel_hi:[1,0]
	v_pk_mul_f32 v[48:49], v[92:93], v[188:189] op_sel:[0,1] op_sel_hi:[1,0]
	v_pk_mul_f32 v[50:51], v[96:97], v[174:175] op_sel:[0,1] op_sel_hi:[1,0]
	v_pk_mul_f32 v[52:53], v[100:101], v[190:191] op_sel:[0,1] op_sel_hi:[1,0]
	v_pk_mul_f32 v[54:55], v[104:105], v[160:161] op_sel:[0,1] op_sel_hi:[1,0]
	v_pk_mul_f32 v[56:57], v[108:109], v[186:187] op_sel:[0,1] op_sel_hi:[1,0]
	v_pk_mul_f32 v[58:59], v[112:113], v[202:203] op_sel:[0,1] op_sel_hi:[1,0]
	v_pk_mul_f32 v[60:61], v[116:117], v[196:197] op_sel:[0,1] op_sel_hi:[1,0]
	v_pk_mul_f32 v[62:63], v[120:121], v[166:167] op_sel:[0,1] op_sel_hi:[1,0]
	v_pk_mul_f32 v[64:65], v[124:125], v[208:209] op_sel:[0,1] op_sel_hi:[1,0]
	v_pk_mul_f32 v[66:67], v[128:129], v[176:177] op_sel:[0,1] op_sel_hi:[1,0]
	v_pk_mul_f32 v[68:69], v[130:131], v[192:193] op_sel:[0,1] op_sel_hi:[1,0]
	v_pk_mul_f32 v[70:71], v[132:133], v[156:157] op_sel:[0,1] op_sel_hi:[1,0]
	v_pk_fma_f32 v[44:45], v[74:75], v[194:195], v[44:45] op_sel_hi:[0,1,1]
	v_pk_fma_f32 v[46:47], v[78:79], v[164:165], v[46:47] op_sel_hi:[0,1,1]
	v_pk_fma_f32 v[48:49], v[82:83], v[188:189], v[48:49] op_sel_hi:[0,1,1]
	v_pk_fma_f32 v[50:51], v[86:87], v[174:175], v[50:51] op_sel_hi:[0,1,1]
	v_pk_fma_f32 v[52:53], v[90:91], v[190:191], v[52:53] op_sel_hi:[0,1,1]
	v_pk_fma_f32 v[54:55], v[94:95], v[160:161], v[54:55] op_sel_hi:[0,1,1]
	v_pk_fma_f32 v[56:57], v[98:99], v[186:187], v[56:57] op_sel_hi:[0,1,1]
	v_pk_fma_f32 v[58:59], v[102:103], v[202:203], v[58:59] op_sel_hi:[0,1,1]
	v_pk_fma_f32 v[60:61], v[106:107], v[196:197], v[60:61] op_sel_hi:[0,1,1]
	v_pk_fma_f32 v[62:63], v[110:111], v[166:167], v[62:63] op_sel_hi:[0,1,1]
	v_pk_fma_f32 v[64:65], v[114:115], v[208:209], v[64:65] op_sel_hi:[0,1,1]
	v_pk_fma_f32 v[66:67], v[118:119], v[176:177], v[66:67] op_sel_hi:[0,1,1]
	v_pk_fma_f32 v[68:69], v[122:123], v[192:193], v[68:69] op_sel_hi:[0,1,1]
	v_pk_fma_f32 v[70:71], v[126:127], v[156:157], v[70:71] op_sel_hi:[0,1,1]
	ds_write_b64 v40, v[158:159]
	ds_write_b64 v40, v[32:33] offset:4224
	ds_write_b64 v40, v[16:17] offset:8448
	ds_write_b64 v40, v[56:57] offset:12672
	ds_write_b64 v40, v[8:9] offset:16896
	ds_write_b64 v40, v[48:49] offset:21120
	ds_write_b64 v40, v[24:25] offset:25344
	ds_write_b64 v40, v[64:65] offset:29568
	ds_write_b64 v40, v[4:5] offset:33792
	ds_write_b64 v40, v[44:45] offset:38016
	ds_write_b64 v40, v[20:21] offset:42240
	ds_write_b64 v40, v[60:61] offset:46464
	ds_write_b64 v40, v[12:13] offset:50688
	ds_write_b64 v40, v[52:53] offset:54912
	ds_write_b64 v40, v[28:29] offset:59136
	ds_write_b64 v40, v[68:69] offset:63360
	ds_write_b64 v155, v[2:3]
	ds_write_b64 v201, v[42:43]
	ds_write_b64 v224, v[18:19]
	ds_write_b64 v225, v[58:59]
	ds_write_b64 v226, v[10:11]
	ds_write_b64 v227, v[50:51]
	ds_write_b64 v228, v[26:27]
	ds_write_b64 v229, v[66:67]
	ds_write_b64 v230, v[6:7]
	ds_write_b64 v231, v[46:47]
	ds_write_b64 v232, v[22:23]
	ds_write_b64 v233, v[62:63]
	ds_write_b64 v234, v[14:15]
	ds_write_b64 v235, v[54:55]
	ds_write_b64 v236, v[30:31]
	ds_write_b64 v237, v[70:71]
	v_mov_b32_e32 v2, v1
	s_waitcnt lgkmcnt(0)
	s_barrier
	s_nop 0
	v_and_b32_e32 v3, 15, v2
	v_lshlrev_b32_e32 v2, 5, v2
	v_and_b32_e32 v4, 0xfffffe00, v2
	v_lshl_add_u32 v5, v4, 3, 0
	v_lshlrev_b32_e32 v6, 3, v3
	v_ashrrev_i32_e32 v7, 2, v4
	v_add3_u32 v40, v5, v6, v7
	v_add_u32_e32 v155, 0x800, v40
	ds_read2_b64 v[156:159], v40 offset1:16
	ds_read2_b64 v[160:163], v40 offset0:33 offset1:49
	ds_read2_b64 v[164:167], v40 offset0:66 offset1:82
	ds_read2_b64 v[168:171], v40 offset0:99 offset1:115
	ds_read2_b64 v[172:175], v40 offset0:132 offset1:148
	ds_read2_b64 v[176:179], v40 offset0:165 offset1:181
	ds_read2_b64 v[180:183], v40 offset0:198 offset1:214
	ds_read2_b64 v[184:187], v40 offset0:231 offset1:247
	ds_read2_b64 v[188:191], v155 offset0:8 offset1:24
	ds_read2_b64 v[192:195], v155 offset0:41 offset1:57
	ds_read2_b64 v[196:199], v155 offset0:74 offset1:90
	ds_read2_b64 v[202:205], v155 offset0:107 offset1:123
	ds_read2_b64 v[206:209], v155 offset0:140 offset1:156
	ds_read2_b64 v[210:213], v155 offset0:173 offset1:189
	ds_read2_b64 v[214:217], v155 offset0:206 offset1:222
	ds_read2_b64 v[218:221], v155 offset0:239 offset1:255
	s_waitcnt lgkmcnt(7)
	v_pk_add_f32 v[222:223], v[156:157], v[188:189]
	v_pk_add_f32 v[156:157], v[156:157], v[188:189] neg_lo:[0,1] neg_hi:[0,1]
	v_pk_add_f32 v[188:189], v[158:159], v[190:191]
	v_pk_add_f32 v[158:159], v[158:159], v[190:191] neg_lo:[0,1] neg_hi:[0,1]
	v_cvt_f32_ubyte0_e32 v2, v3
	v_pk_mul_f32 v[190:191], v[158:159], s[46:47]
	v_mul_f32_e32 v3, 0x3b000000, v2
	v_pk_fma_f32 v[158:159], v[158:159], s[42:43], v[190:191] op_sel:[0,0,1] op_sel_hi:[1,0,0]
	s_waitcnt lgkmcnt(6)
	v_pk_add_f32 v[190:191], v[160:161], v[192:193]
	v_pk_add_f32 v[160:161], v[160:161], v[192:193] neg_lo:[0,1] neg_hi:[0,1]
	v_sin_f32_e32 v2, v3
	v_pk_mul_f32 v[192:193], v[160:161], s[62:63]
	v_cos_f32_e32 v4, v3
	v_pk_fma_f32 v[160:161], v[160:161], s[50:51], v[192:193] op_sel:[0,0,1] op_sel_hi:[1,0,0]
	v_pk_add_f32 v[192:193], v[162:163], v[194:195]
	v_pk_add_f32 v[162:163], v[162:163], v[194:195] neg_lo:[0,1] neg_hi:[0,1]
	v_xor_b32_e32 v5, 0x80000000, v2
	v_pk_mul_f32 v[194:195], v[162:163], s[66:67]
	v_mov_b32_e32 v3, v5
	v_pk_fma_f32 v[162:163], v[162:163], s[64:65], v[194:195] op_sel:[0,0,1] op_sel_hi:[1,0,0]
	s_waitcnt lgkmcnt(5)
	v_pk_add_f32 v[194:195], v[164:165], v[196:197]
	v_pk_add_f32 v[164:165], v[164:165], v[196:197] neg_lo:[0,1] neg_hi:[0,1]
	v_pk_mul_f32 v[6:7], v[4:5], v[2:3] op_sel:[1,0] op_sel_hi:[0,1]
	v_pk_mul_f32 v[196:197], v[164:165], s[68:69]
	v_pk_fma_f32 v[6:7], v[4:5], v[4:5], v[6:7] op_sel_hi:[1,0,1]
	v_pk_fma_f32 v[164:165], v[164:165], s[10:11], v[196:197] op_sel:[0,0,1] op_sel_hi:[1,0,0]
	v_pk_add_f32 v[196:197], v[166:167], v[198:199]
	v_pk_add_f32 v[166:167], v[166:167], v[198:199] neg_lo:[0,1] neg_hi:[0,1]
	s_nop 0
	v_pk_mul_f32 v[198:199], v[166:167], s[70:71]
	s_nop 0
	v_pk_fma_f32 v[166:167], v[166:167], s[78:79], v[198:199] op_sel:[0,0,1] op_sel_hi:[1,0,0]
	s_waitcnt lgkmcnt(4)
	v_pk_add_f32 v[198:199], v[168:169], v[202:203]
	v_pk_add_f32 v[168:169], v[168:169], v[202:203] neg_lo:[0,1] neg_hi:[0,1]
	v_pk_mul_f32 v[10:11], v[6:7], v[6:7] op_sel:[1,1] op_sel_hi:[0,1] neg_lo:[0,1]
	v_pk_mul_f32 v[202:203], v[168:169], s[72:73]
	v_pk_fma_f32 v[10:11], v[6:7], v[6:7], v[10:11] op_sel_hi:[1,0,1]
	v_pk_fma_f32 v[168:169], v[168:169], s[76:77], v[202:203] op_sel:[0,0,1] op_sel_hi:[1,0,0]
	v_pk_add_f32 v[202:203], v[170:171], v[204:205]
	v_pk_add_f32 v[170:171], v[170:171], v[204:205] neg_lo:[0,1] neg_hi:[0,1]
	s_nop 0
	v_pk_mul_f32 v[204:205], v[170:171], s[40:41]
	s_nop 0
	v_pk_fma_f32 v[170:171], v[170:171], s[44:45], v[204:205] op_sel:[0,0,1] op_sel_hi:[1,0,0]
	s_waitcnt lgkmcnt(3)
	v_pk_add_f32 v[204:205], v[172:173], v[206:207]
	v_pk_add_f32 v[206:207], v[172:173], v[206:207] neg_lo:[0,1] neg_hi:[0,1]
	v_pk_mul_f32 v[26:27], v[10:11], v[10:11] op_sel:[1,1] op_sel_hi:[0,1] neg_lo:[0,1]
	v_pk_add_f32 v[172:173], v[174:175], v[208:209]
	v_pk_add_f32 v[174:175], v[174:175], v[208:209] neg_lo:[0,1] neg_hi:[0,1]
	v_pk_fma_f32 v[26:27], v[10:11], v[10:11], v[26:27] op_sel_hi:[1,0,1]
	v_pk_mul_f32 v[208:209], v[174:175], s[40:41]
	v_pk_mul_f32 v[50:51], v[10:11], v[26:27] op_sel:[1,1] op_sel_hi:[1,0] neg_lo:[1,0]
	v_pk_fma_f32 v[174:175], v[174:175], s[44:45], v[208:209] op_sel:[0,0,1] op_sel_hi:[1,0,0] neg_lo:[1,0,0] neg_hi:[1,0,0]
	s_waitcnt lgkmcnt(2)
	v_pk_add_f32 v[208:209], v[176:177], v[210:211]
	v_pk_add_f32 v[176:177], v[176:177], v[210:211] neg_lo:[0,1] neg_hi:[0,1]
	v_pk_fma_f32 v[50:51], v[10:11], v[26:27], v[50:51] op_sel_hi:[0,1,1]
	v_pk_mul_f32 v[210:211], v[176:177], s[72:73]
	v_pk_mul_f32 v[66:67], v[10:11], v[50:51] op_sel:[1,1] op_sel_hi:[1,0] neg_lo:[1,0]
	v_pk_fma_f32 v[176:177], v[176:177], s[76:77], v[210:211] op_sel:[0,0,1] op_sel_hi:[1,0,0] neg_lo:[1,0,0] neg_hi:[1,0,0]
	v_pk_add_f32 v[210:211], v[178:179], v[212:213]
	v_pk_add_f32 v[178:179], v[178:179], v[212:213] neg_lo:[0,1] neg_hi:[0,1]
	v_pk_fma_f32 v[66:67], v[10:11], v[50:51], v[66:67] op_sel_hi:[0,1,1]
	v_pk_mul_f32 v[212:213], v[178:179], s[70:71]
	v_pk_mul_f32 v[82:83], v[10:11], v[66:67] op_sel:[1,1] op_sel_hi:[1,0] neg_lo:[1,0]
	v_pk_fma_f32 v[178:179], v[178:179], s[78:79], v[212:213] op_sel:[0,0,1] op_sel_hi:[1,0,0] neg_lo:[1,0,0] neg_hi:[1,0,0]
	s_waitcnt lgkmcnt(1)
	v_pk_add_f32 v[212:213], v[180:181], v[214:215]
	v_pk_add_f32 v[180:181], v[180:181], v[214:215] neg_lo:[0,1] neg_hi:[0,1]
	v_pk_fma_f32 v[82:83], v[10:11], v[66:67], v[82:83] op_sel_hi:[0,1,1]
	v_pk_mul_f32 v[214:215], v[180:181], s[68:69]
	v_pk_mul_f32 v[98:99], v[10:11], v[82:83] op_sel:[1,1] op_sel_hi:[1,0] neg_lo:[1,0]
	v_pk_fma_f32 v[180:181], v[180:181], s[10:11], v[214:215] op_sel:[0,0,1] op_sel_hi:[1,0,0] neg_lo:[1,0,0] neg_hi:[1,0,0]
	v_pk_add_f32 v[214:215], v[182:183], v[216:217]
	v_pk_add_f32 v[182:183], v[182:183], v[216:217] neg_lo:[0,1] neg_hi:[0,1]
	v_pk_fma_f32 v[98:99], v[10:11], v[82:83], v[98:99] op_sel_hi:[0,1,1]
	v_pk_mul_f32 v[216:217], v[182:183], s[66:67]
	v_pk_mul_f32 v[114:115], v[10:11], v[98:99] op_sel:[1,1] op_sel_hi:[1,0] neg_lo:[1,0]
	v_pk_fma_f32 v[182:183], v[182:183], s[64:65], v[216:217] op_sel:[0,0,1] op_sel_hi:[1,0,0] neg_lo:[1,0,0] neg_hi:[1,0,0]
	s_waitcnt lgkmcnt(0)
	v_pk_add_f32 v[216:217], v[184:185], v[218:219]
	v_pk_add_f32 v[184:185], v[184:185], v[218:219] neg_lo:[0,1] neg_hi:[0,1]
	v_pk_mul_f32 v[8:9], v[2:3], v[6:7] op_sel:[0,1] op_sel_hi:[1,0]
	v_pk_mul_f32 v[218:219], v[184:185], s[62:63]
	v_pk_fma_f32 v[114:115], v[10:11], v[98:99], v[114:115] op_sel_hi:[0,1,1]
	v_pk_fma_f32 v[184:185], v[184:185], s[50:51], v[218:219] op_sel:[0,0,1] op_sel_hi:[1,0,0] neg_lo:[1,0,0] neg_hi:[1,0,0]
	v_pk_add_f32 v[218:219], v[186:187], v[220:221]
	v_pk_add_f32 v[186:187], v[186:187], v[220:221] neg_lo:[0,1] neg_hi:[0,1]
	v_pk_fma_f32 v[8:9], v[4:5], v[6:7], v[8:9] op_sel_hi:[0,1,1]
	v_pk_mul_f32 v[220:221], v[186:187], s[46:47]
	v_pk_mul_f32 v[16:17], v[2:3], v[10:11] op_sel:[0,1] op_sel_hi:[1,0]
	v_pk_fma_f32 v[186:187], v[186:187], s[42:43], v[220:221] op_sel:[0,0,1] op_sel_hi:[1,0,0] neg_lo:[1,0,0] neg_hi:[1,0,0]
	v_pk_add_f32 v[220:221], v[222:223], v[204:205]
	v_pk_add_f32 v[204:205], v[222:223], v[204:205] neg_lo:[0,1] neg_hi:[0,1]
	v_pk_add_f32 v[222:223], v[188:189], v[172:173]
	v_pk_add_f32 v[172:173], v[188:189], v[172:173] neg_lo:[0,1] neg_hi:[0,1]
	v_pk_mul_f32 v[30:31], v[2:3], v[26:27] op_sel:[0,1] op_sel_hi:[1,0]
	v_pk_mul_f32 v[188:189], v[172:173], s[62:63]
	v_pk_mul_f32 v[54:55], v[2:3], v[50:51] op_sel:[0,1] op_sel_hi:[1,0]
	v_pk_fma_f32 v[172:173], v[172:173], s[50:51], v[188:189] op_sel:[0,0,1] op_sel_hi:[1,0,0]
	v_pk_add_f32 v[188:189], v[190:191], v[208:209]
	v_pk_add_f32 v[190:191], v[190:191], v[208:209] neg_lo:[0,1] neg_hi:[0,1]
	v_pk_mul_f32 v[70:71], v[2:3], v[66:67] op_sel:[0,1] op_sel_hi:[1,0]
	v_pk_mul_f32 v[208:209], v[190:191], s[68:69]
	v_pk_mul_f32 v[86:87], v[2:3], v[82:83] op_sel:[0,1] op_sel_hi:[1,0]
	v_pk_fma_f32 v[190:191], v[190:191], s[10:11], v[208:209] op_sel:[0,0,1] op_sel_hi:[1,0,0]
	v_pk_add_f32 v[208:209], v[192:193], v[210:211]
	v_pk_add_f32 v[192:193], v[192:193], v[210:211] neg_lo:[0,1] neg_hi:[0,1]
	v_pk_mul_f32 v[102:103], v[2:3], v[98:99] op_sel:[0,1] op_sel_hi:[1,0]
	v_pk_mul_f32 v[210:211], v[192:193], s[72:73]
	v_pk_mul_f32 v[118:119], v[2:3], v[114:115] op_sel:[0,1] op_sel_hi:[1,0]
	v_pk_fma_f32 v[192:193], v[192:193], s[76:77], v[210:211] op_sel:[0,0,1] op_sel_hi:[1,0,0]
	v_pk_add_f32 v[210:211], v[194:195], v[212:213]
	v_pk_add_f32 v[212:213], v[194:195], v[212:213] neg_lo:[0,1] neg_hi:[0,1]
	v_pk_add_f32 v[194:195], v[196:197], v[214:215]
	v_pk_add_f32 v[196:197], v[196:197], v[214:215] neg_lo:[0,1] neg_hi:[0,1]
	s_nop 0
	v_pk_mul_f32 v[214:215], v[196:197], s[72:73]
	v_pk_fma_f32 v[16:17], v[4:5], v[10:11], v[16:17] op_sel_hi:[0,1,1]
	v_pk_fma_f32 v[196:197], v[196:197], s[76:77], v[214:215] op_sel:[0,0,1] op_sel_hi:[1,0,0] neg_lo:[1,0,0] neg_hi:[1,0,0]
	v_pk_add_f32 v[214:215], v[198:199], v[216:217]
	v_pk_add_f32 v[198:199], v[198:199], v[216:217] neg_lo:[0,1] neg_hi:[0,1]
	v_pk_mul_f32 v[18:19], v[6:7], v[10:11] op_sel:[1,1] op_sel_hi:[1,0] neg_lo:[1,0]
	v_pk_mul_f32 v[216:217], v[198:199], s[68:69]
	v_pk_fma_f32 v[30:31], v[4:5], v[26:27], v[30:31] op_sel_hi:[0,1,1]
	v_pk_fma_f32 v[198:199], v[198:199], s[10:11], v[216:217] op_sel:[0,0,1] op_sel_hi:[1,0,0] neg_lo:[1,0,0] neg_hi:[1,0,0]
	v_pk_add_f32 v[216:217], v[202:203], v[218:219]
	v_pk_add_f32 v[202:203], v[202:203], v[218:219] neg_lo:[0,1] neg_hi:[0,1]
	v_pk_mul_f32 v[42:43], v[6:7], v[26:27] op_sel:[1,1] op_sel_hi:[1,0] neg_lo:[1,0]
	v_pk_mul_f32 v[218:219], v[202:203], s[62:63]
	v_pk_fma_f32 v[54:55], v[4:5], v[50:51], v[54:55] op_sel_hi:[0,1,1]
	v_pk_fma_f32 v[202:203], v[202:203], s[50:51], v[218:219] op_sel:[0,0,1] op_sel_hi:[1,0,0] neg_lo:[1,0,0] neg_hi:[1,0,0]
	v_pk_add_f32 v[218:219], v[156:157], v[206:207] op_sel:[0,1] op_sel_hi:[1,0] neg_hi:[0,1]
	v_pk_add_f32 v[156:157], v[156:157], v[206:207] op_sel:[0,1] op_sel_hi:[1,0] neg_lo:[0,1]
	v_pk_add_f32 v[206:207], v[158:159], v[174:175]
	v_pk_add_f32 v[158:159], v[158:159], v[174:175] neg_lo:[0,1] neg_hi:[0,1]
	v_pk_mul_f32 v[58:59], v[6:7], v[50:51] op_sel:[1,1] op_sel_hi:[1,0] neg_lo:[1,0]
	v_pk_mul_f32 v[174:175], v[158:159], s[62:63]
	v_pk_fma_f32 v[70:71], v[4:5], v[66:67], v[70:71] op_sel_hi:[0,1,1]
	v_pk_fma_f32 v[158:159], v[158:159], s[50:51], v[174:175] op_sel:[0,0,1] op_sel_hi:[1,0,0]
	v_pk_add_f32 v[174:175], v[160:161], v[176:177]
	v_pk_add_f32 v[160:161], v[160:161], v[176:177] neg_lo:[0,1] neg_hi:[0,1]
	v_pk_mul_f32 v[74:75], v[6:7], v[66:67] op_sel:[1,1] op_sel_hi:[1,0] neg_lo:[1,0]
	v_pk_mul_f32 v[176:177], v[160:161], s[68:69]
	v_pk_fma_f32 v[86:87], v[4:5], v[82:83], v[86:87] op_sel_hi:[0,1,1]
	v_pk_fma_f32 v[160:161], v[160:161], s[10:11], v[176:177] op_sel:[0,0,1] op_sel_hi:[1,0,0]
	v_pk_add_f32 v[176:177], v[162:163], v[178:179]
	v_pk_add_f32 v[162:163], v[162:163], v[178:179] neg_lo:[0,1] neg_hi:[0,1]
	v_pk_mul_f32 v[90:91], v[6:7], v[82:83] op_sel:[1,1] op_sel_hi:[1,0] neg_lo:[1,0]
	v_pk_mul_f32 v[178:179], v[162:163], s[72:73]
	v_pk_fma_f32 v[102:103], v[4:5], v[98:99], v[102:103] op_sel_hi:[0,1,1]
	v_pk_fma_f32 v[162:163], v[162:163], s[76:77], v[178:179] op_sel:[0,0,1] op_sel_hi:[1,0,0]
	v_pk_add_f32 v[178:179], v[164:165], v[180:181]
	v_pk_add_f32 v[180:181], v[164:165], v[180:181] neg_lo:[0,1] neg_hi:[0,1]
	v_pk_mul_f32 v[106:107], v[6:7], v[98:99] op_sel:[1,1] op_sel_hi:[1,0] neg_lo:[1,0]
	v_pk_add_f32 v[164:165], v[166:167], v[182:183]
	v_pk_add_f32 v[166:167], v[166:167], v[182:183] neg_lo:[0,1] neg_hi:[0,1]
	v_pk_fma_f32 v[118:119], v[4:5], v[114:115], v[118:119] op_sel_hi:[0,1,1]
	v_pk_mul_f32 v[182:183], v[166:167], s[72:73]
	v_pk_mul_f32 v[122:123], v[6:7], v[114:115] op_sel:[1,1] op_sel_hi:[1,0] neg_lo:[1,0]
	v_pk_fma_f32 v[166:167], v[166:167], s[76:77], v[182:183] op_sel:[0,0,1] op_sel_hi:[1,0,0] neg_lo:[1,0,0] neg_hi:[1,0,0]
	v_pk_add_f32 v[182:183], v[168:169], v[184:185]
	v_pk_add_f32 v[168:169], v[168:169], v[184:185] neg_lo:[0,1] neg_hi:[0,1]
	v_pk_fma_f32 v[18:19], v[6:7], v[10:11], v[18:19] op_sel_hi:[0,1,1]
	v_pk_mul_f32 v[184:185], v[168:169], s[68:69]
	v_pk_mul_f32 v[22:23], v[10:11], v[8:9] op_sel:[1,1] op_sel_hi:[0,1] neg_lo:[0,1]
	v_pk_fma_f32 v[168:169], v[168:169], s[10:11], v[184:185] op_sel:[0,0,1] op_sel_hi:[1,0,0] neg_lo:[1,0,0] neg_hi:[1,0,0]
	v_pk_add_f32 v[184:185], v[170:171], v[186:187]
	v_pk_add_f32 v[170:171], v[170:171], v[186:187] neg_lo:[0,1] neg_hi:[0,1]
	v_pk_fma_f32 v[42:43], v[6:7], v[26:27], v[42:43] op_sel_hi:[0,1,1]
	v_pk_mul_f32 v[186:187], v[170:171], s[62:63]
	v_pk_mul_f32 v[46:47], v[8:9], v[26:27] op_sel:[1,1] op_sel_hi:[1,0] neg_lo:[1,0]
	v_pk_fma_f32 v[170:171], v[170:171], s[50:51], v[186:187] op_sel:[0,0,1] op_sel_hi:[1,0,0] neg_lo:[1,0,0] neg_hi:[1,0,0]
	v_pk_add_f32 v[186:187], v[220:221], v[210:211]
	v_pk_add_f32 v[210:211], v[220:221], v[210:211] neg_lo:[0,1] neg_hi:[0,1]
	v_pk_add_f32 v[220:221], v[222:223], v[194:195]
	v_pk_add_f32 v[194:195], v[222:223], v[194:195] neg_lo:[0,1] neg_hi:[0,1]
	v_pk_fma_f32 v[58:59], v[6:7], v[50:51], v[58:59] op_sel_hi:[0,1,1]
	v_pk_mul_f32 v[222:223], v[194:195], s[68:69]
	v_pk_mul_f32 v[62:63], v[8:9], v[50:51] op_sel:[1,1] op_sel_hi:[1,0] neg_lo:[1,0]
	v_pk_fma_f32 v[194:195], v[194:195], s[10:11], v[222:223] op_sel:[0,0,1] op_sel_hi:[1,0,0]
	v_pk_add_f32 v[222:223], v[188:189], v[214:215]
	v_pk_add_f32 v[214:215], v[188:189], v[214:215] neg_lo:[0,1] neg_hi:[0,1]
	v_pk_fma_f32 v[74:75], v[6:7], v[66:67], v[74:75] op_sel_hi:[0,1,1]
	v_pk_add_f32 v[188:189], v[208:209], v[216:217]
	v_pk_add_f32 v[208:209], v[208:209], v[216:217] neg_lo:[0,1] neg_hi:[0,1]
	v_pk_mul_f32 v[78:79], v[8:9], v[66:67] op_sel:[1,1] op_sel_hi:[1,0] neg_lo:[1,0]
	v_pk_mul_f32 v[216:217], v[208:209], s[68:69]
	v_pk_fma_f32 v[90:91], v[6:7], v[82:83], v[90:91] op_sel_hi:[0,1,1]
	v_pk_fma_f32 v[208:209], v[208:209], s[10:11], v[216:217] op_sel:[0,0,1] op_sel_hi:[1,0,0] neg_lo:[1,0,0] neg_hi:[1,0,0]
	v_pk_add_f32 v[216:217], v[204:205], v[212:213] op_sel:[0,1] op_sel_hi:[1,0] neg_hi:[0,1]
	v_pk_add_f32 v[204:205], v[204:205], v[212:213] op_sel:[0,1] op_sel_hi:[1,0] neg_lo:[0,1]
	v_pk_add_f32 v[212:213], v[172:173], v[196:197]
	v_pk_add_f32 v[172:173], v[172:173], v[196:197] neg_lo:[0,1] neg_hi:[0,1]
	v_pk_mul_f32 v[94:95], v[8:9], v[82:83] op_sel:[1,1] op_sel_hi:[1,0] neg_lo:[1,0]
	v_pk_mul_f32 v[196:197], v[172:173], s[68:69]
	v_pk_fma_f32 v[106:107], v[6:7], v[98:99], v[106:107] op_sel_hi:[0,1,1]
	v_pk_fma_f32 v[172:173], v[172:173], s[10:11], v[196:197] op_sel:[0,0,1] op_sel_hi:[1,0,0]
	v_pk_add_f32 v[196:197], v[190:191], v[198:199]
	v_pk_add_f32 v[198:199], v[190:191], v[198:199] neg_lo:[0,1] neg_hi:[0,1]
	v_pk_mul_f32 v[110:111], v[8:9], v[98:99] op_sel:[1,1] op_sel_hi:[1,0] neg_lo:[1,0]
	v_pk_add_f32 v[190:191], v[192:193], v[202:203]
	v_pk_add_f32 v[192:193], v[192:193], v[202:203] neg_lo:[0,1] neg_hi:[0,1]
	v_pk_fma_f32 v[122:123], v[6:7], v[114:115], v[122:123] op_sel_hi:[0,1,1]
	v_pk_mul_f32 v[202:203], v[192:193], s[68:69]
	v_pk_mul_f32 v[126:127], v[8:9], v[114:115] op_sel:[1,1] op_sel_hi:[1,0] neg_lo:[1,0]
	v_pk_fma_f32 v[192:193], v[192:193], s[10:11], v[202:203] op_sel:[0,0,1] op_sel_hi:[1,0,0] neg_lo:[1,0,0] neg_hi:[1,0,0]
	v_pk_add_f32 v[202:203], v[218:219], v[178:179]
	v_pk_add_f32 v[178:179], v[218:219], v[178:179] neg_lo:[0,1] neg_hi:[0,1]
	v_pk_add_f32 v[218:219], v[206:207], v[164:165]
	v_pk_add_f32 v[164:165], v[206:207], v[164:165] neg_lo:[0,1] neg_hi:[0,1]
	v_xor_b32_e32 v24, 0x80000000, v17
	v_pk_mul_f32 v[206:207], v[164:165], s[68:69]
	v_xor_b32_e32 v28, 0x80000000, v19
	v_pk_fma_f32 v[164:165], v[164:165], s[10:11], v[206:207] op_sel:[0,0,1] op_sel_hi:[1,0,0]
	v_pk_add_f32 v[206:207], v[174:175], v[182:183]
	v_pk_add_f32 v[182:183], v[174:175], v[182:183] neg_lo:[0,1] neg_hi:[0,1]
	v_pk_fma_f32 v[22:23], v[10:11], v[8:9], v[22:23] op_sel_hi:[1,0,1]
	v_pk_add_f32 v[174:175], v[176:177], v[184:185]
	v_pk_add_f32 v[176:177], v[176:177], v[184:185] neg_lo:[0,1] neg_hi:[0,1]
	v_pk_fma_f32 v[46:47], v[8:9], v[26:27], v[46:47] op_sel_hi:[0,1,1]
	v_pk_mul_f32 v[184:185], v[176:177], s[68:69]
	v_pk_fma_f32 v[62:63], v[8:9], v[50:51], v[62:63] op_sel_hi:[0,1,1]
	v_pk_fma_f32 v[176:177], v[176:177], s[10:11], v[184:185] op_sel:[0,0,1] op_sel_hi:[1,0,0] neg_lo:[1,0,0] neg_hi:[1,0,0]
	v_pk_add_f32 v[184:185], v[156:157], v[180:181] op_sel:[0,1] op_sel_hi:[1,0] neg_hi:[0,1]
	v_pk_add_f32 v[156:157], v[156:157], v[180:181] op_sel:[0,1] op_sel_hi:[1,0] neg_lo:[0,1]
	v_pk_add_f32 v[180:181], v[158:159], v[166:167]
	v_pk_add_f32 v[158:159], v[158:159], v[166:167] neg_lo:[0,1] neg_hi:[0,1]
	v_pk_fma_f32 v[78:79], v[8:9], v[66:67], v[78:79] op_sel_hi:[0,1,1]
	v_pk_mul_f32 v[166:167], v[158:159], s[68:69]
	v_pk_fma_f32 v[94:95], v[8:9], v[82:83], v[94:95] op_sel_hi:[0,1,1]
	v_pk_fma_f32 v[158:159], v[158:159], s[10:11], v[166:167] op_sel:[0,0,1] op_sel_hi:[1,0,0]
	v_pk_add_f32 v[166:167], v[160:161], v[168:169]
	v_pk_add_f32 v[168:169], v[160:161], v[168:169] neg_lo:[0,1] neg_hi:[0,1]
	v_pk_fma_f32 v[110:111], v[8:9], v[98:99], v[110:111] op_sel_hi:[0,1,1]
	v_pk_add_f32 v[160:161], v[162:163], v[170:171]
	v_pk_add_f32 v[162:163], v[162:163], v[170:171] neg_lo:[0,1] neg_hi:[0,1]
	v_pk_fma_f32 v[126:127], v[8:9], v[114:115], v[126:127] op_sel_hi:[0,1,1]
	v_pk_mul_f32 v[170:171], v[162:163], s[68:69]
	v_mov_b32_e32 v25, v17
	v_pk_fma_f32 v[162:163], v[162:163], s[10:11], v[170:171] op_sel:[0,0,1] op_sel_hi:[1,0,0] neg_lo:[1,0,0] neg_hi:[1,0,0]
	v_pk_add_f32 v[170:171], v[186:187], v[222:223]
	v_pk_add_f32 v[186:187], v[186:187], v[222:223] neg_lo:[0,1] neg_hi:[0,1]
	v_pk_add_f32 v[222:223], v[220:221], v[188:189]
	v_pk_add_f32 v[220:221], v[220:221], v[188:189] neg_lo:[0,1] neg_hi:[0,1]
	s_mov_b32 s10, s60
	s_nop 0
	s_nop 0
	v_pk_add_f32 v[188:189], v[210:211], v[214:215] op_sel:[0,1] op_sel_hi:[1,0] neg_hi:[0,1]
	v_pk_add_f32 v[210:211], v[210:211], v[214:215] op_sel:[0,1] op_sel_hi:[1,0] neg_lo:[0,1]
	v_pk_add_f32 v[214:215], v[194:195], v[208:209]
	v_pk_add_f32 v[208:209], v[194:195], v[208:209] neg_lo:[0,1] neg_hi:[0,1]
	s_add_i32 s60, s60, s28
	s_nop 0
	s_nop 0
	v_pk_add_f32 v[194:195], v[216:217], v[196:197]
	v_pk_add_f32 v[196:197], v[216:217], v[196:197] neg_lo:[0,1] neg_hi:[0,1]
	v_pk_add_f32 v[216:217], v[212:213], v[190:191]
	v_pk_add_f32 v[212:213], v[212:213], v[190:191] neg_lo:[0,1] neg_hi:[0,1]
	s_cmpk_gt_i32 s60, 0x7ff
	s_nop 0
	s_nop 0
	v_pk_add_f32 v[190:191], v[204:205], v[198:199] op_sel:[0,1] op_sel_hi:[1,0] neg_hi:[0,1]
	v_pk_add_f32 v[198:199], v[204:205], v[198:199] op_sel:[0,1] op_sel_hi:[1,0] neg_lo:[0,1]
	v_pk_add_f32 v[204:205], v[172:173], v[192:193]
	v_pk_add_f32 v[192:193], v[172:173], v[192:193] neg_lo:[0,1] neg_hi:[0,1]
	s_cselect_b64 s[76:77], -1, 0
	s_nop 0
	s_nop 0
	v_pk_add_f32 v[172:173], v[202:203], v[206:207]
	v_pk_add_f32 v[202:203], v[202:203], v[206:207] neg_lo:[0,1] neg_hi:[0,1]
	v_pk_add_f32 v[206:207], v[218:219], v[174:175]
	v_pk_add_f32 v[218:219], v[218:219], v[174:175] neg_lo:[0,1] neg_hi:[0,1]
	s_cmpk_lt_i32 s60, 0x800
	s_nop 0
	s_nop 0
	v_pk_add_f32 v[174:175], v[178:179], v[182:183] op_sel:[0,1] op_sel_hi:[1,0] neg_hi:[0,1]
	v_pk_add_f32 v[178:179], v[178:179], v[182:183] op_sel:[0,1] op_sel_hi:[1,0] neg_lo:[0,1]
	v_pk_add_f32 v[182:183], v[164:165], v[176:177]
	v_pk_add_f32 v[176:177], v[164:165], v[176:177] neg_lo:[0,1] neg_hi:[0,1]
	s_cselect_b32 s45, s60, s10
	s_nop 0
	s_nop 0
	v_pk_add_f32 v[164:165], v[184:185], v[166:167]
	v_pk_add_f32 v[166:167], v[184:185], v[166:167] neg_lo:[0,1] neg_hi:[0,1]
	v_pk_add_f32 v[184:185], v[180:181], v[160:161]
	v_pk_add_f32 v[180:181], v[180:181], v[160:161] neg_lo:[0,1] neg_hi:[0,1]
	s_lshl_b32 s11, s45, 1
	s_nop 0
	s_nop 0
	v_pk_add_f32 v[160:161], v[156:157], v[168:169] op_sel:[0,1] op_sel_hi:[1,0] neg_hi:[0,1]
	v_pk_add_f32 v[156:157], v[156:157], v[168:169] op_sel:[0,1] op_sel_hi:[1,0] neg_lo:[0,1]
	v_pk_add_f32 v[168:169], v[158:159], v[162:163]
	v_pk_add_f32 v[158:159], v[158:159], v[162:163] neg_lo:[0,1] neg_hi:[0,1]
	v_mov_b32_e32 v29, v19
	v_xor_b32_e32 v163, 0x80000000, v158
	v_mov_b32_e32 v162, v159
	v_pk_add_f32 v[158:159], v[170:171], v[222:223]
	v_pk_add_f32 v[170:171], v[170:171], v[222:223] neg_lo:[0,1] neg_hi:[0,1]
	v_pk_add_f32 v[222:223], v[186:187], v[220:221] op_sel:[0,1] op_sel_hi:[1,0] neg_hi:[0,1]
	v_pk_add_f32 v[186:187], v[186:187], v[220:221] op_sel:[0,1] op_sel_hi:[1,0] neg_lo:[0,1]
	v_pk_add_f32 v[220:221], v[188:189], v[214:215]
	v_pk_add_f32 v[188:189], v[188:189], v[214:215] neg_lo:[0,1] neg_hi:[0,1]
	v_pk_add_f32 v[214:215], v[210:211], v[208:209] op_sel:[0,1] op_sel_hi:[1,0] neg_hi:[0,1]
	v_pk_add_f32 v[208:209], v[210:211], v[208:209] op_sel:[0,1] op_sel_hi:[1,0] neg_lo:[0,1]
	v_pk_add_f32 v[210:211], v[194:195], v[216:217]
	v_pk_add_f32 v[194:195], v[194:195], v[216:217] neg_lo:[0,1] neg_hi:[0,1]
	v_pk_add_f32 v[216:217], v[196:197], v[212:213] op_sel:[0,1] op_sel_hi:[1,0] neg_hi:[0,1]
	v_pk_add_f32 v[196:197], v[196:197], v[212:213] op_sel:[0,1] op_sel_hi:[1,0] neg_lo:[0,1]
	v_pk_add_f32 v[212:213], v[190:191], v[204:205]
	v_pk_add_f32 v[190:191], v[190:191], v[204:205] neg_lo:[0,1] neg_hi:[0,1]
	v_pk_add_f32 v[204:205], v[198:199], v[192:193] op_sel:[0,1] op_sel_hi:[1,0] neg_hi:[0,1]
	v_pk_add_f32 v[192:193], v[198:199], v[192:193] op_sel:[0,1] op_sel_hi:[1,0] neg_lo:[0,1]
	v_pk_add_f32 v[198:199], v[172:173], v[206:207]
	v_pk_add_f32 v[172:173], v[172:173], v[206:207] neg_lo:[0,1] neg_hi:[0,1]
	v_pk_mul_f32 v[2:3], v[2:3], v[198:199] op_sel:[0,1] op_sel_hi:[1,0]
	v_pk_add_f32 v[206:207], v[202:203], v[218:219] op_sel:[0,1] op_sel_hi:[1,0] neg_hi:[0,1]
	v_pk_add_f32 v[202:203], v[202:203], v[218:219] op_sel:[0,1] op_sel_hi:[1,0] neg_lo:[0,1]
	v_pk_add_f32 v[218:219], v[174:175], v[182:183]
	v_pk_add_f32 v[174:175], v[174:175], v[182:183] neg_lo:[0,1] neg_hi:[0,1]
	v_pk_add_f32 v[182:183], v[178:179], v[176:177] op_sel:[0,1] op_sel_hi:[1,0] neg_hi:[0,1]
	v_pk_add_f32 v[176:177], v[178:179], v[176:177] op_sel:[0,1] op_sel_hi:[1,0] neg_lo:[0,1]
	v_pk_add_f32 v[178:179], v[164:165], v[184:185]
	v_pk_fma_f32 v[2:3], v[4:5], v[198:199], v[2:3] op_sel_hi:[0,1,1]
	v_pk_mul_f32 v[4:5], v[6:7], v[210:211] op_sel:[1,1] op_sel_hi:[1,0] neg_lo:[1,0]
	s_and_b32 s10, s45, 0x3ff
	v_pk_fma_f32 v[4:5], v[6:7], v[210:211], v[4:5] op_sel_hi:[0,1,1]
	v_pk_mul_f32 v[6:7], v[8:9], v[178:179] op_sel:[1,1] op_sel_hi:[1,0] neg_lo:[1,0]
	s_and_b32 s11, s11, 0xfffff800
	v_pk_fma_f32 v[6:7], v[8:9], v[178:179], v[6:7] op_sel_hi:[0,1,1]
	v_pk_mul_f32 v[8:9], v[10:11], v[220:221] op_sel:[1,1] op_sel_hi:[1,0] neg_lo:[1,0]
	s_nop 0
	s_nop 0
	s_nop 0
	v_pk_add_f32 v[164:165], v[164:165], v[184:185] neg_lo:[0,1] neg_hi:[0,1]
	v_pk_add_f32 v[184:185], v[166:167], v[180:181] op_sel:[0,1] op_sel_hi:[1,0] neg_hi:[0,1]
	v_pk_add_f32 v[166:167], v[166:167], v[180:181] op_sel:[0,1] op_sel_hi:[1,0] neg_lo:[0,1]
	v_pk_add_f32 v[180:181], v[160:161], v[168:169]
	v_pk_fma_f32 v[8:9], v[10:11], v[220:221], v[8:9] op_sel_hi:[0,1,1]
	v_pk_mul_f32 v[10:11], v[24:25], v[218:219] op_sel:[0,1] op_sel_hi:[1,0]
	v_pk_mul_f32 v[12:13], v[28:29], v[212:213] op_sel:[0,1] op_sel_hi:[1,0]
	s_or_b32 s10, s11, s10
	s_nop 0
	s_nop 0
	s_nop 0
	s_nop 0
	v_xor_b32_e32 v72, 0x80000000, v63
	v_xor_b32_e32 v76, 0x80000000, v67
	v_xor_b32_e32 v80, 0x80000000, v71
	v_mov_b32_e32 v73, v63
	v_mov_b32_e32 v77, v67
	v_mov_b32_e32 v81, v71
	v_pk_add_f32 v[160:161], v[160:161], v[168:169] neg_lo:[0,1] neg_hi:[0,1]
	v_pk_add_f32 v[168:169], v[156:157], v[162:163]
	v_pk_fma_f32 v[10:11], v[16:17], v[218:219], v[10:11] op_sel_hi:[0,1,1]
	v_pk_fma_f32 v[12:13], v[18:19], v[212:213], v[12:13] op_sel_hi:[0,1,1]
	v_pk_mul_f32 v[14:15], v[22:23], v[180:181] op_sel:[1,1] op_sel_hi:[1,0] neg_lo:[1,0]
	v_pk_mul_f32 v[16:17], v[26:27], v[222:223] op_sel:[1,1] op_sel_hi:[1,0] neg_lo:[1,0]
	v_pk_mul_f32 v[18:19], v[30:31], v[206:207] op_sel:[1,1] op_sel_hi:[1,0] neg_lo:[1,0]
	v_pk_mul_f32 v[20:21], v[42:43], v[216:217] op_sel:[1,1] op_sel_hi:[1,0] neg_lo:[1,0]
	s_ashr_i32 s11, s10, 31
	v_xor_b32_e32 v84, 0x80000000, v75
	v_xor_b32_e32 v88, 0x80000000, v79
	v_xor_b32_e32 v92, 0x80000000, v83
	v_xor_b32_e32 v96, 0x80000000, v87
	v_xor_b32_e32 v100, 0x80000000, v91
	v_xor_b32_e32 v104, 0x80000000, v95
	v_xor_b32_e32 v108, 0x80000000, v99
	v_xor_b32_e32 v112, 0x80000000, v103
	v_xor_b32_e32 v116, 0x80000000, v107
	v_xor_b32_e32 v120, 0x80000000, v111
	v_xor_b32_e32 v124, 0x80000000, v115
	v_xor_b32_e32 v128, 0x80000000, v119
	v_xor_b32_e32 v130, 0x80000000, v123
	v_xor_b32_e32 v132, 0x80000000, v127
	v_mov_b32_e32 v85, v75
	v_mov_b32_e32 v89, v79
	v_mov_b32_e32 v93, v83
	v_mov_b32_e32 v97, v87
	v_mov_b32_e32 v101, v91
	v_mov_b32_e32 v105, v95
	v_mov_b32_e32 v109, v99
	v_mov_b32_e32 v113, v103
	v_mov_b32_e32 v117, v107
	v_mov_b32_e32 v121, v111
	v_mov_b32_e32 v125, v115
	v_mov_b32_e32 v129, v119
	v_mov_b32_e32 v131, v123
	v_mov_b32_e32 v133, v127
	v_pk_add_f32 v[156:157], v[156:157], v[162:163] neg_lo:[0,1] neg_hi:[0,1]
	v_pk_fma_f32 v[14:15], v[22:23], v[180:181], v[14:15] op_sel_hi:[0,1,1]
	v_pk_fma_f32 v[16:17], v[26:27], v[222:223], v[16:17] op_sel_hi:[0,1,1]
	v_pk_fma_f32 v[18:19], v[30:31], v[206:207], v[18:19] op_sel_hi:[0,1,1]
	v_pk_fma_f32 v[20:21], v[42:43], v[216:217], v[20:21] op_sel_hi:[0,1,1]
	v_pk_mul_f32 v[22:23], v[46:47], v[184:185] op_sel:[1,1] op_sel_hi:[1,0] neg_lo:[1,0]
	v_pk_mul_f32 v[24:25], v[50:51], v[214:215] op_sel:[1,1] op_sel_hi:[1,0] neg_lo:[1,0]
	v_pk_mul_f32 v[26:27], v[54:55], v[182:183] op_sel:[1,1] op_sel_hi:[1,0] neg_lo:[1,0]
	v_pk_mul_f32 v[28:29], v[58:59], v[204:205] op_sel:[1,1] op_sel_hi:[1,0] neg_lo:[1,0]
	v_pk_mul_f32 v[30:31], v[72:73], v[168:169] op_sel:[0,1] op_sel_hi:[1,0]
	v_pk_mul_f32 v[32:33], v[76:77], v[170:171] op_sel:[0,1] op_sel_hi:[1,0]
	v_pk_mul_f32 v[42:43], v[80:81], v[172:173] op_sel:[0,1] op_sel_hi:[1,0]
	s_lshl_b64 s[78:79], s[10:11], 15
	s_bitset1_b32 s10, 10
	v_pk_fma_f32 v[22:23], v[46:47], v[184:185], v[22:23] op_sel_hi:[0,1,1]
	v_pk_fma_f32 v[24:25], v[50:51], v[214:215], v[24:25] op_sel_hi:[0,1,1]
	v_pk_fma_f32 v[26:27], v[54:55], v[182:183], v[26:27] op_sel_hi:[0,1,1]
	v_pk_fma_f32 v[28:29], v[58:59], v[204:205], v[28:29] op_sel_hi:[0,1,1]
	v_pk_fma_f32 v[30:31], v[62:63], v[168:169], v[30:31] op_sel_hi:[0,1,1]
	v_pk_fma_f32 v[32:33], v[66:67], v[170:171], v[32:33] op_sel_hi:[0,1,1]
	v_pk_fma_f32 v[42:43], v[70:71], v[172:173], v[42:43] op_sel_hi:[0,1,1]
	v_pk_mul_f32 v[44:45], v[84:85], v[194:195] op_sel:[0,1] op_sel_hi:[1,0]
	v_pk_mul_f32 v[46:47], v[88:89], v[164:165] op_sel:[0,1] op_sel_hi:[1,0]
	v_pk_mul_f32 v[48:49], v[92:93], v[188:189] op_sel:[0,1] op_sel_hi:[1,0]
	v_pk_mul_f32 v[50:51], v[96:97], v[174:175] op_sel:[0,1] op_sel_hi:[1,0]
	v_pk_mul_f32 v[52:53], v[100:101], v[190:191] op_sel:[0,1] op_sel_hi:[1,0]
	v_pk_mul_f32 v[54:55], v[104:105], v[160:161] op_sel:[0,1] op_sel_hi:[1,0]
	v_pk_mul_f32 v[56:57], v[108:109], v[186:187] op_sel:[0,1] op_sel_hi:[1,0]
	v_pk_mul_f32 v[58:59], v[112:113], v[202:203] op_sel:[0,1] op_sel_hi:[1,0]
	v_pk_mul_f32 v[60:61], v[116:117], v[196:197] op_sel:[0,1] op_sel_hi:[1,0]
	v_pk_mul_f32 v[62:63], v[120:121], v[166:167] op_sel:[0,1] op_sel_hi:[1,0]
	v_pk_mul_f32 v[64:65], v[124:125], v[208:209] op_sel:[0,1] op_sel_hi:[1,0]
	v_pk_mul_f32 v[66:67], v[128:129], v[176:177] op_sel:[0,1] op_sel_hi:[1,0]
	v_pk_mul_f32 v[68:69], v[130:131], v[192:193] op_sel:[0,1] op_sel_hi:[1,0]
	v_pk_mul_f32 v[70:71], v[132:133], v[156:157] op_sel:[0,1] op_sel_hi:[1,0]
	s_ashr_i32 s11, s10, 31
	v_pk_fma_f32 v[44:45], v[74:75], v[194:195], v[44:45] op_sel_hi:[0,1,1]
	v_pk_fma_f32 v[46:47], v[78:79], v[164:165], v[46:47] op_sel_hi:[0,1,1]
	v_pk_fma_f32 v[48:49], v[82:83], v[188:189], v[48:49] op_sel_hi:[0,1,1]
	v_pk_fma_f32 v[50:51], v[86:87], v[174:175], v[50:51] op_sel_hi:[0,1,1]
	v_pk_fma_f32 v[52:53], v[90:91], v[190:191], v[52:53] op_sel_hi:[0,1,1]
	v_pk_fma_f32 v[54:55], v[94:95], v[160:161], v[54:55] op_sel_hi:[0,1,1]
	v_pk_fma_f32 v[56:57], v[98:99], v[186:187], v[56:57] op_sel_hi:[0,1,1]
	v_pk_fma_f32 v[58:59], v[102:103], v[202:203], v[58:59] op_sel_hi:[0,1,1]
	v_pk_fma_f32 v[60:61], v[106:107], v[196:197], v[60:61] op_sel_hi:[0,1,1]
	v_pk_fma_f32 v[62:63], v[110:111], v[166:167], v[62:63] op_sel_hi:[0,1,1]
	v_pk_fma_f32 v[64:65], v[114:115], v[208:209], v[64:65] op_sel_hi:[0,1,1]
	v_pk_fma_f32 v[66:67], v[118:119], v[176:177], v[66:67] op_sel_hi:[0,1,1]
	v_pk_fma_f32 v[68:69], v[122:123], v[192:193], v[68:69] op_sel_hi:[0,1,1]
	v_pk_fma_f32 v[70:71], v[126:127], v[156:157], v[70:71] op_sel_hi:[0,1,1]
	ds_write2_b64 v40, v[158:159], v[32:33] offset1:16
	ds_write2_b64 v40, v[16:17], v[56:57] offset0:33 offset1:49
	ds_write2_b64 v40, v[8:9], v[48:49] offset0:66 offset1:82
	ds_write2_b64 v40, v[24:25], v[64:65] offset0:99 offset1:115
	ds_write2_b64 v40, v[4:5], v[44:45] offset0:132 offset1:148
	ds_write2_b64 v40, v[20:21], v[60:61] offset0:165 offset1:181
	ds_write2_b64 v40, v[12:13], v[52:53] offset0:198 offset1:214
	ds_write2_b64 v40, v[28:29], v[68:69] offset0:231 offset1:247
	ds_write2_b64 v155, v[2:3], v[42:43] offset0:8 offset1:24
	ds_write2_b64 v155, v[18:19], v[58:59] offset0:41 offset1:57
	ds_write2_b64 v155, v[10:11], v[50:51] offset0:74 offset1:90
	ds_write2_b64 v155, v[26:27], v[66:67] offset0:107 offset1:123
	ds_write2_b64 v155, v[6:7], v[46:47] offset0:140 offset1:156
	ds_write2_b64 v155, v[22:23], v[62:63] offset0:173 offset1:189
	ds_write2_b64 v155, v[14:15], v[54:55] offset0:206 offset1:222
	ds_write2_b64 v155, v[30:31], v[70:71] offset0:239 offset1:255
	s_lshl_b64 s[10:11], s[10:11], 15
	v_lshl_add_u64 v[2:3], v[36:37], 0, s[78:79]
	s_waitcnt lgkmcnt(0)
	s_barrier
	global_load_dwordx4 v[6:9], v[2:3], off nt
	global_load_dwordx4 v[30:33], v[2:3], off offset:16 nt
	v_lshl_add_u64 v[2:3], v[36:37], 0, s[10:11]
	global_load_dwordx4 v[26:29], v[2:3], off nt
	global_load_dwordx4 v[18:21], v[2:3], off offset:16 nt
	v_mov_b32_e32 v120, 0
	s_and_saveexec_b64 s[10:11], s[0:1]
	s_cbranch_execz .LBB0_273
	global_load_ushort v120, v[2:3], off offset:32

.LBB0_428:
	s_ashr_i32 s17, s16, 31
	s_lshl_b64 s[6:7], s[16:17], 2
	s_add_u32 s6, s48, s6
	s_addc_u32 s7, s49, s7
	global_load_dwordx2 v[40:41], v151, s[6:7]
	s_waitcnt vmcnt(0)
	v_cvt_f32_f16_e32 v36, v10
	v_cvt_f32_f16_sdwa v42, v10 dst_sel:DWORD dst_unused:UNUSED_PAD src0_sel:WORD_1
	v_cvt_f32_f16_e32 v43, v11
	v_cvt_f32_f16_e32 v45, v12
	v_cvt_f32_f16_sdwa v46, v12 dst_sel:DWORD dst_unused:UNUSED_PAD src0_sel:WORD_1
	v_cvt_f32_f16_e32 v47, v13
	v_cvt_f32_f16_sdwa v12, v13 dst_sel:DWORD dst_unused:UNUSED_PAD src0_sel:WORD_1
	v_cvt_f32_f16_e32 v13, v30
	v_cvt_f32_f16_sdwa v50, v26 dst_sel:DWORD dst_unused:UNUSED_PAD src0_sel:WORD_1
	v_cvt_f32_f16_e32 v51, v27
	v_cvt_f32_f16_sdwa v44, v11 dst_sel:DWORD dst_unused:UNUSED_PAD src0_sel:WORD_1
	v_cvt_f32_f16_sdwa v48, v30 dst_sel:DWORD dst_unused:UNUSED_PAD src0_sel:WORD_1
	v_cvt_f32_f16_e32 v49, v31
	v_cvt_f32_f16_sdwa v30, v31 dst_sel:DWORD dst_unused:UNUSED_PAD src0_sel:WORD_1
	v_cvt_f32_f16_e32 v31, v32
	v_cvt_f32_f16_sdwa v11, v33 dst_sel:DWORD dst_unused:UNUSED_PAD src0_sel:WORD_1
	v_cvt_f32_f16_sdwa v32, v32 dst_sel:DWORD dst_unused:UNUSED_PAD src0_sel:WORD_1
	v_cvt_f32_f16_e32 v33, v33
	v_cvt_f32_f16_sdwa v26, v27 dst_sel:DWORD dst_unused:UNUSED_PAD src0_sel:WORD_1
	v_cvt_f32_f16_e32 v27, v28
	v_cvt_f32_f16_sdwa v52, v28 dst_sel:DWORD dst_unused:UNUSED_PAD src0_sel:WORD_1
	v_cvt_f32_f16_e32 v53, v29
	v_cvt_f32_f16_e32 v28, v22
	v_cvt_f32_f16_sdwa v54, v22 dst_sel:DWORD dst_unused:UNUSED_PAD src0_sel:WORD_1
	v_cvt_f32_f16_e32 v55, v23
	v_cvt_f32_f16_sdwa v22, v23 dst_sel:DWORD dst_unused:UNUSED_PAD src0_sel:WORD_1
	v_cvt_f32_f16_e32 v23, v24
	v_cvt_f32_f16_sdwa v56, v24 dst_sel:DWORD dst_unused:UNUSED_PAD src0_sel:WORD_1
	v_cvt_f32_f16_e32 v57, v25
	v_cvt_f32_f16_sdwa v29, v29 dst_sel:DWORD dst_unused:UNUSED_PAD src0_sel:WORD_1
	v_cvt_f32_f16_sdwa v25, v25 dst_sel:DWORD dst_unused:UNUSED_PAD src0_sel:WORD_1
	v_cvt_f32_f16_e32 v24, v38
	v_cvt_f32_f16_sdwa v60, v19 dst_sel:DWORD dst_unused:UNUSED_PAD src0_sel:WORD_1
	v_cvt_f32_f16_e32 v61, v20
	v_cvt_f32_f16_e32 v38, v18
	v_cvt_f32_f16_e32 v59, v19
	v_mul_f32_e32 v19, 0x3b800000, v36
	v_pk_mul_f32 v[42:43], v[42:43], s[24:25] op_sel_hi:[1,0]
	v_pk_mul_f32 v[12:13], v[12:13], s[24:25] op_sel_hi:[1,0]
	v_pk_mul_f32 v[50:51], v[50:51], s[24:25] op_sel_hi:[1,0]
	v_pk_mul_f32 v[44:45], v[44:45], s[24:25] op_sel_hi:[1,0]
	v_pk_mul_f32 v[46:47], v[46:47], s[24:25] op_sel_hi:[1,0]
	v_pk_mul_f32 v[48:49], v[48:49], s[24:25] op_sel_hi:[1,0]
	v_pk_mul_f32 v[30:31], v[30:31], s[24:25] op_sel_hi:[1,0]
	v_mul_f32_e32 v11, 0x3b800000, v11
	v_pk_mul_f32 v[32:33], v[32:33], s[24:25] op_sel_hi:[1,0]
	v_pk_mul_f32 v[26:27], v[26:27], s[24:25] op_sel_hi:[1,0]
	v_pk_mul_f32 v[52:53], v[52:53], s[24:25] op_sel_hi:[1,0]
	v_pk_mul_f32 v[54:55], v[54:55], s[24:25] op_sel_hi:[1,0]
	v_pk_mul_f32 v[22:23], v[22:23], s[24:25] op_sel_hi:[1,0]
	v_pk_mul_f32 v[56:57], v[56:57], s[24:25] op_sel_hi:[1,0]
	ds_write2_b32 v131, v42, v43 offset0:1 offset1:2
	ds_write2_b32 v131, v44, v45 offset0:3 offset1:4
	ds_write2_b32 v131, v46, v47 offset0:5 offset1:6
	ds_write2_b32 v131, v12, v13 offset0:7 offset1:8
	ds_write2_b32 v131, v48, v49 offset0:9 offset1:10
	ds_write2_b32 v131, v30, v31 offset0:11 offset1:12
	ds_write2_b32 v131, v32, v33 offset0:13 offset1:14
	v_pk_mov_b32 v[12:13], v[50:51], v[50:51] op_sel:[1,0]
	v_pk_mul_f32 v[28:29], v[28:29], s[24:25] op_sel_hi:[1,0]
	v_pk_mul_f32 v[24:25], v[24:25], s[24:25] op_sel_hi:[1,0]
	v_pk_mov_b32 v[26:27], v[26:27], v[26:27] op_sel:[1,0]
	v_pk_mov_b32 v[30:31], v[52:53], v[52:53] op_sel:[1,0]
	v_pk_mov_b32 v[32:33], v[54:55], v[54:55] op_sel:[1,0]
	v_pk_mov_b32 v[22:23], v[22:23], v[22:23] op_sel:[1,0]
	v_pk_mov_b32 v[42:43], v[56:57], v[56:57] op_sel:[1,0]
	v_cvt_f32_f16_sdwa v58, v18 dst_sel:DWORD dst_unused:UNUSED_PAD src0_sel:WORD_1
	v_mul_f32_e32 v36, 0x3b800000, v38
	s_mov_b32 s6, s65
	v_pk_mul_f32 v[58:59], v[58:59], s[24:25] op_sel_hi:[1,0]
	v_fma_mix_f32 v10, v10, s24, v40 op_sel_hi:[1,0,0]
	s_nop 0
	v_cndmask_b32_e64 v10, v19, v10, s[4:5]
	ds_write2_b32 v131, v10, v11 offset1:15
	ds_write_b64 v132, v[12:13] offset:32824
	ds_write_b64 v133, v[26:27] offset:32824
	ds_write_b64 v134, v[30:31] offset:32824
	ds_write_b64 v135, v[28:29] offset:32824
	ds_write_b64 v136, v[32:33] offset:32824
	ds_write_b64 v137, v[22:23] offset:32824
	ds_write_b64 v138, v[42:43] offset:32824
	ds_write_b64 v139, v[24:25] offset:32824
	v_cvt_f32_f16_sdwa v10, v20 dst_sel:DWORD dst_unused:UNUSED_PAD src0_sel:WORD_1
	v_cvt_f32_f16_e32 v11, v21
	v_pk_mul_f32 v[12:13], v[60:61], s[24:25] op_sel_hi:[1,0]
	v_fma_mix_f32 v18, v18, s24, v41 op_sel_hi:[1,0,0]
	ds_write2_b32 v140, v12, v13 offset0:3 offset1:4
	v_cvt_f32_f16_sdwa v12, v21 dst_sel:DWORD dst_unused:UNUSED_PAD src0_sel:WORD_1
	v_cvt_f32_f16_e32 v13, v14
	v_cndmask_b32_e64 v36, v36, v18, s[4:5]
	v_cvt_f32_f16_sdwa v18, v14 dst_sel:DWORD dst_unused:UNUSED_PAD src0_sel:WORD_1
	v_cvt_f32_f16_e32 v19, v15
	v_pk_mul_f32 v[10:11], v[10:11], s[24:25] op_sel_hi:[1,0]
	ds_write2_b32 v140, v10, v11 offset0:5 offset1:6
	v_pk_mul_f32 v[10:11], v[12:13], s[24:25] op_sel_hi:[1,0]
	ds_write2_b32 v140, v10, v11 offset0:7 offset1:8
	v_pk_mul_f32 v[10:11], v[18:19], s[24:25] op_sel_hi:[1,0]
	ds_write2_b32 v140, v10, v11 offset0:9 offset1:10
	v_cvt_f32_f16_sdwa v10, v15 dst_sel:DWORD dst_unused:UNUSED_PAD src0_sel:WORD_1
	v_cvt_f32_f16_e32 v11, v16
	v_cvt_f32_f16_sdwa v12, v16 dst_sel:DWORD dst_unused:UNUSED_PAD src0_sel:WORD_1
	v_cvt_f32_f16_e32 v13, v17
	v_cvt_f32_f16_sdwa v14, v17 dst_sel:DWORD dst_unused:UNUSED_PAD src0_sel:WORD_1
	v_pk_mul_f32 v[10:11], v[10:11], s[24:25] op_sel_hi:[1,0]
	ds_write2_b32 v140, v10, v11 offset0:11 offset1:12
	v_pk_mul_f32 v[10:11], v[12:13], s[24:25] op_sel_hi:[1,0]
	ds_write2_b32 v140, v10, v11 offset0:13 offset1:14
	v_cvt_f32_f16_sdwa v10, v6 dst_sel:DWORD dst_unused:UNUSED_PAD src0_sel:WORD_1
	v_cvt_f32_f16_e32 v11, v7
	v_cvt_f32_f16_sdwa v6, v7 dst_sel:DWORD dst_unused:UNUSED_PAD src0_sel:WORD_1
	v_cvt_f32_f16_e32 v7, v8
	v_mul_f32_e32 v14, 0x3b800000, v14
	v_pk_mul_f32 v[10:11], v[10:11], s[24:25] op_sel_hi:[1,0]
	ds_write2_b32 v140, v58, v59 offset0:1 offset1:2
	v_pk_mov_b32 v[10:11], v[10:11], v[10:11] op_sel:[1,0]
	ds_write2_b32 v140, v36, v14 offset1:15
	ds_write_b64 v141, v[10:11] offset:32824
	v_cvt_f32_f16_sdwa v10, v8 dst_sel:DWORD dst_unused:UNUSED_PAD src0_sel:WORD_1
	v_cvt_f32_f16_e32 v11, v9
	v_pk_mul_f32 v[6:7], v[6:7], s[24:25] op_sel_hi:[1,0]
	s_nop 0
	v_pk_mov_b32 v[6:7], v[6:7], v[6:7] op_sel:[1,0]
	ds_write_b64 v142, v[6:7] offset:32824
	v_cvt_f32_f16_sdwa v7, v9 dst_sel:DWORD dst_unused:UNUSED_PAD src0_sel:WORD_1
	v_pk_mul_f32 v[8:9], v[10:11], s[24:25] op_sel_hi:[1,0]
	v_cvt_f32_f16_e32 v6, v2
	v_pk_mov_b32 v[8:9], v[8:9], v[8:9] op_sel:[1,0]
	ds_write_b64 v143, v[8:9] offset:32824
	v_cvt_f32_f16_sdwa v8, v2 dst_sel:DWORD dst_unused:UNUSED_PAD src0_sel:WORD_1
	v_cvt_f32_f16_e32 v9, v3
	v_cvt_f32_f16_sdwa v2, v3 dst_sel:DWORD dst_unused:UNUSED_PAD src0_sel:WORD_1
	v_cvt_f32_f16_e32 v3, v4
	v_pk_mul_f32 v[6:7], v[6:7], s[24:25] op_sel_hi:[1,0]
	ds_write_b64 v144, v[6:7] offset:32824
	v_pk_mul_f32 v[6:7], v[8:9], s[24:25] op_sel_hi:[1,0]
	v_pk_mul_f32 v[2:3], v[2:3], s[24:25] op_sel_hi:[1,0]
	v_pk_mov_b32 v[6:7], v[6:7], v[6:7] op_sel:[1,0]
	ds_write_b64 v145, v[6:7] offset:32824
	v_pk_mov_b32 v[2:3], v[2:3], v[2:3] op_sel:[1,0]
	v_cvt_f32_f16_sdwa v6, v4 dst_sel:DWORD dst_unused:UNUSED_PAD src0_sel:WORD_1
	v_cvt_f32_f16_e32 v7, v5
	ds_write_b64 v148, v[2:3] offset:32824
	v_cvt_f32_f16_sdwa v3, v5 dst_sel:DWORD dst_unused:UNUSED_PAD src0_sel:WORD_1
	v_cvt_f32_f16_e32 v2, v39
	v_pk_mul_f32 v[4:5], v[6:7], s[24:25] op_sel_hi:[1,0]
	v_pk_mul_f32 v[2:3], v[2:3], s[24:25] op_sel_hi:[1,0]
	v_pk_mov_b32 v[4:5], v[4:5], v[4:5] op_sel:[1,0]
	ds_write_b64 v149, v[4:5] offset:32824
	ds_write_b64 v150, v[2:3] offset:32824
	v_mov_b32_e32 v2, v130
	s_waitcnt lgkmcnt(0)
	s_barrier
	s_nop 0
	v_and_b32_e32 v3, 0xff, v2
	v_lshlrev_b32_e32 v4, 5, v2
	v_and_or_b32 v3, v4, s29, v3
	v_ashrrev_i32_e32 v4, 5, v3
	v_lshlrev_b32_e32 v3, 3, v3
	v_lshlrev_b32_e32 v6, 3, v4
	v_add3_u32 v36, 0, v3, v6
	ds_read_b64 v[154:155], v36
	ds_read_b64 v[156:157], v36 offset:2112
	ds_read_b64 v[158:159], v36 offset:4224
	ds_read_b64 v[160:161], v36 offset:6336
	ds_read_b64 v[162:163], v36 offset:8448
	ds_read_b64 v[164:165], v36 offset:10560
	ds_read_b64 v[166:167], v36 offset:12672
	ds_read_b64 v[168:169], v36 offset:14784
	ds_read_b64 v[170:171], v36 offset:16896
	ds_read_b64 v[172:173], v36 offset:19008
	ds_read_b64 v[174:175], v36 offset:21120
	ds_read_b64 v[176:177], v36 offset:23232
	ds_read_b64 v[178:179], v36 offset:25344
	ds_read_b64 v[180:181], v36 offset:27456
	ds_read_b64 v[182:183], v36 offset:29568
	ds_read_b64 v[184:185], v36 offset:31680
	ds_read_b64 v[186:187], v36 offset:33792
	ds_read_b64 v[188:189], v36 offset:35904
	ds_read_b64 v[190:191], v36 offset:38016
	ds_read_b64 v[192:193], v36 offset:40128
	ds_read_b64 v[194:195], v36 offset:42240
	ds_read_b64 v[196:197], v36 offset:44352
	ds_read_b64 v[198:199], v36 offset:46464
	ds_read_b64 v[204:205], v36 offset:48576
	ds_read_b64 v[206:207], v36 offset:50688
	ds_read_b64 v[208:209], v36 offset:52800
	ds_read_b64 v[210:211], v36 offset:54912
	ds_read_b64 v[212:213], v36 offset:57024
	ds_read_b64 v[214:215], v36 offset:59136
	ds_read_b64 v[216:217], v36 offset:61248
	ds_read_b64 v[218:219], v36 offset:63360
	ds_read_b64 v[220:221], v36 offset:65472
	s_waitcnt lgkmcnt(14)
	v_pk_add_f32 v[222:223], v[154:155], v[186:187]
	v_pk_add_f32 v[154:155], v[154:155], v[186:187] neg_lo:[0,1] neg_hi:[0,1]
	v_pk_add_f32 v[186:187], v[156:157], v[188:189]
	v_pk_add_f32 v[156:157], v[156:157], v[188:189] neg_lo:[0,1] neg_hi:[0,1]
	v_cvt_f32_ubyte0_e32 v2, v2
	v_pk_mul_f32 v[188:189], v[156:157], s[40:41]
	v_mul_f32_e32 v5, 0x39000000, v2
	v_pk_fma_f32 v[156:157], v[156:157], s[36:37], v[188:189] op_sel:[0,0,1] op_sel_hi:[1,0,0]
	s_waitcnt lgkmcnt(13)
	v_pk_add_f32 v[188:189], v[158:159], v[190:191]
	v_pk_add_f32 v[158:159], v[158:159], v[190:191] neg_lo:[0,1] neg_hi:[0,1]
	v_sin_f32_e32 v2, v5
	v_pk_mul_f32 v[190:191], v[158:159], s[44:45]
	v_cos_f32_e32 v4, v5
	v_pk_fma_f32 v[158:159], v[158:159], s[42:43], v[190:191] op_sel:[0,0,1] op_sel_hi:[1,0,0]
	s_waitcnt lgkmcnt(12)
	v_pk_add_f32 v[190:191], v[160:161], v[192:193]
	v_pk_add_f32 v[160:161], v[160:161], v[192:193] neg_lo:[0,1] neg_hi:[0,1]
	v_xor_b32_e32 v5, 0x80000000, v2
	v_pk_mul_f32 v[192:193], v[160:161], s[62:63]
	v_mov_b32_e32 v3, v5
	v_pk_fma_f32 v[160:161], v[160:161], s[50:51], v[192:193] op_sel:[0,0,1] op_sel_hi:[1,0,0]
	s_waitcnt lgkmcnt(11)
	v_pk_add_f32 v[192:193], v[162:163], v[194:195]
	v_pk_add_f32 v[162:163], v[162:163], v[194:195] neg_lo:[0,1] neg_hi:[0,1]
	v_pk_mul_f32 v[6:7], v[4:5], v[2:3] op_sel:[1,0] op_sel_hi:[0,1]
	v_pk_mul_f32 v[194:195], v[162:163], s[68:69]
	v_pk_fma_f32 v[6:7], v[4:5], v[4:5], v[6:7] op_sel_hi:[1,0,1]
	v_pk_fma_f32 v[162:163], v[162:163], s[64:65], v[194:195] op_sel:[0,0,1] op_sel_hi:[1,0,0]
	s_waitcnt lgkmcnt(10)
	v_pk_add_f32 v[194:195], v[164:165], v[196:197]
	v_pk_add_f32 v[164:165], v[164:165], v[196:197] neg_lo:[0,1] neg_hi:[0,1]
	s_nop 0
	v_pk_mul_f32 v[196:197], v[164:165], s[70:71]
	s_nop 0
	v_pk_fma_f32 v[164:165], v[164:165], s[46:47], v[196:197] op_sel:[0,0,1] op_sel_hi:[1,0,0]
	s_waitcnt lgkmcnt(9)
	v_pk_add_f32 v[196:197], v[166:167], v[198:199]
	v_pk_add_f32 v[166:167], v[166:167], v[198:199] neg_lo:[0,1] neg_hi:[0,1]
	v_pk_mul_f32 v[10:11], v[6:7], v[6:7] op_sel:[1,1] op_sel_hi:[0,1] neg_lo:[0,1]
	v_pk_mul_f32 v[198:199], v[166:167], s[76:77]
	v_pk_fma_f32 v[10:11], v[6:7], v[6:7], v[10:11] op_sel_hi:[1,0,1]
	v_pk_fma_f32 v[166:167], v[166:167], s[72:73], v[198:199] op_sel:[0,0,1] op_sel_hi:[1,0,0]
	s_waitcnt lgkmcnt(8)
	v_pk_add_f32 v[198:199], v[168:169], v[204:205]
	v_pk_add_f32 v[168:169], v[168:169], v[204:205] neg_lo:[0,1] neg_hi:[0,1]
	s_nop 0
	v_pk_mul_f32 v[204:205], v[168:169], s[26:27]
	s_nop 0
	v_pk_fma_f32 v[168:169], v[168:169], s[38:39], v[204:205] op_sel:[0,0,1] op_sel_hi:[1,0,0]
	s_waitcnt lgkmcnt(7)
	v_pk_add_f32 v[204:205], v[170:171], v[206:207]
	v_pk_add_f32 v[206:207], v[170:171], v[206:207] neg_lo:[0,1] neg_hi:[0,1]
	v_pk_mul_f32 v[26:27], v[10:11], v[10:11] op_sel:[1,1] op_sel_hi:[0,1] neg_lo:[0,1]
	s_waitcnt lgkmcnt(6)
	v_pk_add_f32 v[170:171], v[172:173], v[208:209]
	v_pk_add_f32 v[172:173], v[172:173], v[208:209] neg_lo:[0,1] neg_hi:[0,1]
	v_pk_fma_f32 v[26:27], v[10:11], v[10:11], v[26:27] op_sel_hi:[1,0,1]
	v_pk_mul_f32 v[208:209], v[172:173], s[26:27]
	v_pk_mul_f32 v[46:47], v[10:11], v[26:27] op_sel:[1,1] op_sel_hi:[1,0] neg_lo:[1,0]
	v_pk_fma_f32 v[172:173], v[172:173], s[38:39], v[208:209] op_sel:[0,0,1] op_sel_hi:[1,0,0] neg_lo:[1,0,0] neg_hi:[1,0,0]
	s_waitcnt lgkmcnt(5)
	v_pk_add_f32 v[208:209], v[174:175], v[210:211]
	v_pk_add_f32 v[174:175], v[174:175], v[210:211] neg_lo:[0,1] neg_hi:[0,1]
	v_pk_fma_f32 v[46:47], v[10:11], v[26:27], v[46:47] op_sel_hi:[0,1,1]
	v_pk_mul_f32 v[210:211], v[174:175], s[76:77]
	v_pk_mul_f32 v[62:63], v[10:11], v[46:47] op_sel:[1,1] op_sel_hi:[1,0] neg_lo:[1,0]
	v_pk_fma_f32 v[174:175], v[174:175], s[72:73], v[210:211] op_sel:[0,0,1] op_sel_hi:[1,0,0] neg_lo:[1,0,0] neg_hi:[1,0,0]
	s_waitcnt lgkmcnt(4)
	v_pk_add_f32 v[210:211], v[176:177], v[212:213]
	v_pk_add_f32 v[176:177], v[176:177], v[212:213] neg_lo:[0,1] neg_hi:[0,1]
	v_pk_fma_f32 v[62:63], v[10:11], v[46:47], v[62:63] op_sel_hi:[0,1,1]
	v_pk_mul_f32 v[212:213], v[176:177], s[70:71]
	v_pk_mul_f32 v[78:79], v[10:11], v[62:63] op_sel:[1,1] op_sel_hi:[1,0] neg_lo:[1,0]
	v_pk_fma_f32 v[176:177], v[176:177], s[46:47], v[212:213] op_sel:[0,0,1] op_sel_hi:[1,0,0] neg_lo:[1,0,0] neg_hi:[1,0,0]
	s_waitcnt lgkmcnt(3)
	v_pk_add_f32 v[212:213], v[178:179], v[214:215]
	v_pk_add_f32 v[178:179], v[178:179], v[214:215] neg_lo:[0,1] neg_hi:[0,1]
	v_pk_fma_f32 v[78:79], v[10:11], v[62:63], v[78:79] op_sel_hi:[0,1,1]
	v_pk_mul_f32 v[214:215], v[178:179], s[68:69]
	v_pk_mul_f32 v[94:95], v[10:11], v[78:79] op_sel:[1,1] op_sel_hi:[1,0] neg_lo:[1,0]
	v_pk_fma_f32 v[178:179], v[178:179], s[64:65], v[214:215] op_sel:[0,0,1] op_sel_hi:[1,0,0] neg_lo:[1,0,0] neg_hi:[1,0,0]
	s_waitcnt lgkmcnt(2)
	v_pk_add_f32 v[214:215], v[180:181], v[216:217]
	v_pk_add_f32 v[180:181], v[180:181], v[216:217] neg_lo:[0,1] neg_hi:[0,1]
	v_pk_fma_f32 v[94:95], v[10:11], v[78:79], v[94:95] op_sel_hi:[0,1,1]
	v_pk_mul_f32 v[216:217], v[180:181], s[62:63]
	v_pk_mul_f32 v[110:111], v[10:11], v[94:95] op_sel:[1,1] op_sel_hi:[1,0] neg_lo:[1,0]
	v_pk_fma_f32 v[180:181], v[180:181], s[50:51], v[216:217] op_sel:[0,0,1] op_sel_hi:[1,0,0] neg_lo:[1,0,0] neg_hi:[1,0,0]
	s_waitcnt lgkmcnt(1)
	v_pk_add_f32 v[216:217], v[182:183], v[218:219]
	v_pk_add_f32 v[182:183], v[182:183], v[218:219] neg_lo:[0,1] neg_hi:[0,1]
	v_pk_mul_f32 v[8:9], v[2:3], v[6:7] op_sel:[0,1] op_sel_hi:[1,0]
	v_pk_mul_f32 v[218:219], v[182:183], s[44:45]
	v_pk_fma_f32 v[110:111], v[10:11], v[94:95], v[110:111] op_sel_hi:[0,1,1]
	v_pk_fma_f32 v[182:183], v[182:183], s[42:43], v[218:219] op_sel:[0,0,1] op_sel_hi:[1,0,0] neg_lo:[1,0,0] neg_hi:[1,0,0]
	s_waitcnt lgkmcnt(0)
	v_pk_add_f32 v[218:219], v[184:185], v[220:221]
	v_pk_add_f32 v[184:185], v[184:185], v[220:221] neg_lo:[0,1] neg_hi:[0,1]
	v_pk_fma_f32 v[8:9], v[4:5], v[6:7], v[8:9] op_sel_hi:[0,1,1]
	v_pk_mul_f32 v[220:221], v[184:185], s[40:41]
	v_pk_mul_f32 v[16:17], v[2:3], v[10:11] op_sel:[0,1] op_sel_hi:[1,0]
	v_pk_fma_f32 v[184:185], v[184:185], s[36:37], v[220:221] op_sel:[0,0,1] op_sel_hi:[1,0,0] neg_lo:[1,0,0] neg_hi:[1,0,0]
	v_pk_add_f32 v[220:221], v[222:223], v[204:205]
	v_pk_add_f32 v[204:205], v[222:223], v[204:205] neg_lo:[0,1] neg_hi:[0,1]
	v_pk_add_f32 v[222:223], v[186:187], v[170:171]
	v_pk_add_f32 v[170:171], v[186:187], v[170:171] neg_lo:[0,1] neg_hi:[0,1]
	v_pk_mul_f32 v[30:31], v[2:3], v[26:27] op_sel:[0,1] op_sel_hi:[1,0]
	v_pk_mul_f32 v[186:187], v[170:171], s[44:45]
	v_pk_mul_f32 v[50:51], v[2:3], v[46:47] op_sel:[0,1] op_sel_hi:[1,0]
	v_pk_fma_f32 v[170:171], v[170:171], s[42:43], v[186:187] op_sel:[0,0,1] op_sel_hi:[1,0,0]
	v_pk_add_f32 v[186:187], v[188:189], v[208:209]
	v_pk_add_f32 v[188:189], v[188:189], v[208:209] neg_lo:[0,1] neg_hi:[0,1]
	v_pk_mul_f32 v[66:67], v[2:3], v[62:63] op_sel:[0,1] op_sel_hi:[1,0]
	v_pk_mul_f32 v[208:209], v[188:189], s[68:69]
	v_pk_mul_f32 v[82:83], v[2:3], v[78:79] op_sel:[0,1] op_sel_hi:[1,0]
	v_pk_fma_f32 v[188:189], v[188:189], s[64:65], v[208:209] op_sel:[0,0,1] op_sel_hi:[1,0,0]
	v_pk_add_f32 v[208:209], v[190:191], v[210:211]
	v_pk_add_f32 v[190:191], v[190:191], v[210:211] neg_lo:[0,1] neg_hi:[0,1]
	v_pk_mul_f32 v[98:99], v[2:3], v[94:95] op_sel:[0,1] op_sel_hi:[1,0]
	v_pk_mul_f32 v[210:211], v[190:191], s[76:77]
	v_pk_mul_f32 v[114:115], v[2:3], v[110:111] op_sel:[0,1] op_sel_hi:[1,0]
	v_pk_fma_f32 v[190:191], v[190:191], s[72:73], v[210:211] op_sel:[0,0,1] op_sel_hi:[1,0,0]
	v_pk_add_f32 v[210:211], v[192:193], v[212:213]
	v_pk_add_f32 v[212:213], v[192:193], v[212:213] neg_lo:[0,1] neg_hi:[0,1]
	v_pk_add_f32 v[192:193], v[194:195], v[214:215]
	v_pk_add_f32 v[194:195], v[194:195], v[214:215] neg_lo:[0,1] neg_hi:[0,1]
	s_nop 0
	v_pk_mul_f32 v[214:215], v[194:195], s[76:77]
	v_pk_fma_f32 v[16:17], v[4:5], v[10:11], v[16:17] op_sel_hi:[0,1,1]
	v_pk_fma_f32 v[194:195], v[194:195], s[72:73], v[214:215] op_sel:[0,0,1] op_sel_hi:[1,0,0] neg_lo:[1,0,0] neg_hi:[1,0,0]
	v_pk_add_f32 v[214:215], v[196:197], v[216:217]
	v_pk_add_f32 v[196:197], v[196:197], v[216:217] neg_lo:[0,1] neg_hi:[0,1]
	v_pk_mul_f32 v[18:19], v[6:7], v[10:11] op_sel:[1,1] op_sel_hi:[1,0] neg_lo:[1,0]
	v_pk_mul_f32 v[216:217], v[196:197], s[68:69]
	v_pk_fma_f32 v[30:31], v[4:5], v[26:27], v[30:31] op_sel_hi:[0,1,1]
	v_pk_fma_f32 v[196:197], v[196:197], s[64:65], v[216:217] op_sel:[0,0,1] op_sel_hi:[1,0,0] neg_lo:[1,0,0] neg_hi:[1,0,0]
	v_pk_add_f32 v[216:217], v[198:199], v[218:219]
	v_pk_add_f32 v[198:199], v[198:199], v[218:219] neg_lo:[0,1] neg_hi:[0,1]
	v_pk_mul_f32 v[38:39], v[6:7], v[26:27] op_sel:[1,1] op_sel_hi:[1,0] neg_lo:[1,0]
	v_pk_mul_f32 v[218:219], v[198:199], s[44:45]
	v_pk_fma_f32 v[50:51], v[4:5], v[46:47], v[50:51] op_sel_hi:[0,1,1]
	v_pk_fma_f32 v[198:199], v[198:199], s[42:43], v[218:219] op_sel:[0,0,1] op_sel_hi:[1,0,0] neg_lo:[1,0,0] neg_hi:[1,0,0]
	v_pk_add_f32 v[218:219], v[154:155], v[206:207] op_sel:[0,1] op_sel_hi:[1,0] neg_hi:[0,1]
	v_pk_add_f32 v[154:155], v[154:155], v[206:207] op_sel:[0,1] op_sel_hi:[1,0] neg_lo:[0,1]
	v_pk_add_f32 v[206:207], v[156:157], v[172:173]
	v_pk_add_f32 v[156:157], v[156:157], v[172:173] neg_lo:[0,1] neg_hi:[0,1]
	v_pk_mul_f32 v[54:55], v[6:7], v[46:47] op_sel:[1,1] op_sel_hi:[1,0] neg_lo:[1,0]
	v_pk_mul_f32 v[172:173], v[156:157], s[44:45]
	v_pk_fma_f32 v[66:67], v[4:5], v[62:63], v[66:67] op_sel_hi:[0,1,1]
	v_pk_fma_f32 v[156:157], v[156:157], s[42:43], v[172:173] op_sel:[0,0,1] op_sel_hi:[1,0,0]
	v_pk_add_f32 v[172:173], v[158:159], v[174:175]
	v_pk_add_f32 v[158:159], v[158:159], v[174:175] neg_lo:[0,1] neg_hi:[0,1]
	v_pk_mul_f32 v[70:71], v[6:7], v[62:63] op_sel:[1,1] op_sel_hi:[1,0] neg_lo:[1,0]
	v_pk_mul_f32 v[174:175], v[158:159], s[68:69]
	v_pk_fma_f32 v[82:83], v[4:5], v[78:79], v[82:83] op_sel_hi:[0,1,1]
	v_pk_fma_f32 v[158:159], v[158:159], s[64:65], v[174:175] op_sel:[0,0,1] op_sel_hi:[1,0,0]
	v_pk_add_f32 v[174:175], v[160:161], v[176:177]
	v_pk_add_f32 v[160:161], v[160:161], v[176:177] neg_lo:[0,1] neg_hi:[0,1]
	v_pk_mul_f32 v[86:87], v[6:7], v[78:79] op_sel:[1,1] op_sel_hi:[1,0] neg_lo:[1,0]
	v_pk_mul_f32 v[176:177], v[160:161], s[76:77]
	v_pk_fma_f32 v[98:99], v[4:5], v[94:95], v[98:99] op_sel_hi:[0,1,1]
	v_pk_fma_f32 v[160:161], v[160:161], s[72:73], v[176:177] op_sel:[0,0,1] op_sel_hi:[1,0,0]
	v_pk_add_f32 v[176:177], v[162:163], v[178:179]
	v_pk_add_f32 v[178:179], v[162:163], v[178:179] neg_lo:[0,1] neg_hi:[0,1]
	v_pk_mul_f32 v[102:103], v[6:7], v[94:95] op_sel:[1,1] op_sel_hi:[1,0] neg_lo:[1,0]
	v_pk_add_f32 v[162:163], v[164:165], v[180:181]
	v_pk_add_f32 v[164:165], v[164:165], v[180:181] neg_lo:[0,1] neg_hi:[0,1]
	v_pk_fma_f32 v[114:115], v[4:5], v[110:111], v[114:115] op_sel_hi:[0,1,1]
	v_pk_mul_f32 v[180:181], v[164:165], s[76:77]
	v_pk_mul_f32 v[118:119], v[6:7], v[110:111] op_sel:[1,1] op_sel_hi:[1,0] neg_lo:[1,0]
	v_pk_fma_f32 v[164:165], v[164:165], s[72:73], v[180:181] op_sel:[0,0,1] op_sel_hi:[1,0,0] neg_lo:[1,0,0] neg_hi:[1,0,0]
	v_pk_add_f32 v[180:181], v[166:167], v[182:183]
	v_pk_add_f32 v[166:167], v[166:167], v[182:183] neg_lo:[0,1] neg_hi:[0,1]
	v_pk_fma_f32 v[18:19], v[6:7], v[10:11], v[18:19] op_sel_hi:[0,1,1]
	v_pk_mul_f32 v[182:183], v[166:167], s[68:69]
	v_pk_mul_f32 v[22:23], v[10:11], v[8:9] op_sel:[1,1] op_sel_hi:[0,1] neg_lo:[0,1]
	v_pk_fma_f32 v[166:167], v[166:167], s[64:65], v[182:183] op_sel:[0,0,1] op_sel_hi:[1,0,0] neg_lo:[1,0,0] neg_hi:[1,0,0]
	v_pk_add_f32 v[182:183], v[168:169], v[184:185]
	v_pk_add_f32 v[168:169], v[168:169], v[184:185] neg_lo:[0,1] neg_hi:[0,1]
	v_pk_fma_f32 v[38:39], v[6:7], v[26:27], v[38:39] op_sel_hi:[0,1,1]
	v_pk_mul_f32 v[184:185], v[168:169], s[44:45]
	v_pk_mul_f32 v[42:43], v[8:9], v[26:27] op_sel:[1,1] op_sel_hi:[1,0] neg_lo:[1,0]
	v_pk_fma_f32 v[168:169], v[168:169], s[42:43], v[184:185] op_sel:[0,0,1] op_sel_hi:[1,0,0] neg_lo:[1,0,0] neg_hi:[1,0,0]
	v_pk_add_f32 v[184:185], v[220:221], v[210:211]
	v_pk_add_f32 v[210:211], v[220:221], v[210:211] neg_lo:[0,1] neg_hi:[0,1]
	v_pk_add_f32 v[220:221], v[222:223], v[192:193]
	v_pk_add_f32 v[192:193], v[222:223], v[192:193] neg_lo:[0,1] neg_hi:[0,1]
	v_pk_fma_f32 v[54:55], v[6:7], v[46:47], v[54:55] op_sel_hi:[0,1,1]
	v_pk_mul_f32 v[222:223], v[192:193], s[68:69]
	v_pk_mul_f32 v[58:59], v[8:9], v[46:47] op_sel:[1,1] op_sel_hi:[1,0] neg_lo:[1,0]
	v_pk_fma_f32 v[192:193], v[192:193], s[64:65], v[222:223] op_sel:[0,0,1] op_sel_hi:[1,0,0]
	v_pk_add_f32 v[222:223], v[186:187], v[214:215]
	v_pk_add_f32 v[214:215], v[186:187], v[214:215] neg_lo:[0,1] neg_hi:[0,1]
	v_pk_fma_f32 v[70:71], v[6:7], v[62:63], v[70:71] op_sel_hi:[0,1,1]
	v_pk_add_f32 v[186:187], v[208:209], v[216:217]
	v_pk_add_f32 v[208:209], v[208:209], v[216:217] neg_lo:[0,1] neg_hi:[0,1]
	v_pk_mul_f32 v[74:75], v[8:9], v[62:63] op_sel:[1,1] op_sel_hi:[1,0] neg_lo:[1,0]
	v_pk_mul_f32 v[216:217], v[208:209], s[68:69]
	v_pk_fma_f32 v[86:87], v[6:7], v[78:79], v[86:87] op_sel_hi:[0,1,1]
	v_pk_fma_f32 v[208:209], v[208:209], s[64:65], v[216:217] op_sel:[0,0,1] op_sel_hi:[1,0,0] neg_lo:[1,0,0] neg_hi:[1,0,0]
	v_pk_add_f32 v[216:217], v[204:205], v[212:213] op_sel:[0,1] op_sel_hi:[1,0] neg_hi:[0,1]
	v_pk_add_f32 v[204:205], v[204:205], v[212:213] op_sel:[0,1] op_sel_hi:[1,0] neg_lo:[0,1]
	v_pk_add_f32 v[212:213], v[170:171], v[194:195]
	v_pk_add_f32 v[170:171], v[170:171], v[194:195] neg_lo:[0,1] neg_hi:[0,1]
	v_pk_mul_f32 v[90:91], v[8:9], v[78:79] op_sel:[1,1] op_sel_hi:[1,0] neg_lo:[1,0]
	v_pk_mul_f32 v[194:195], v[170:171], s[68:69]
	v_pk_fma_f32 v[102:103], v[6:7], v[94:95], v[102:103] op_sel_hi:[0,1,1]
	v_pk_fma_f32 v[170:171], v[170:171], s[64:65], v[194:195] op_sel:[0,0,1] op_sel_hi:[1,0,0]
	v_pk_add_f32 v[194:195], v[188:189], v[196:197]
	v_pk_add_f32 v[196:197], v[188:189], v[196:197] neg_lo:[0,1] neg_hi:[0,1]
	v_pk_mul_f32 v[106:107], v[8:9], v[94:95] op_sel:[1,1] op_sel_hi:[1,0] neg_lo:[1,0]
	v_pk_add_f32 v[188:189], v[190:191], v[198:199]
	v_pk_add_f32 v[190:191], v[190:191], v[198:199] neg_lo:[0,1] neg_hi:[0,1]
	v_pk_fma_f32 v[118:119], v[6:7], v[110:111], v[118:119] op_sel_hi:[0,1,1]
	v_pk_mul_f32 v[198:199], v[190:191], s[68:69]
	v_pk_mul_f32 v[122:123], v[8:9], v[110:111] op_sel:[1,1] op_sel_hi:[1,0] neg_lo:[1,0]
	v_pk_fma_f32 v[190:191], v[190:191], s[64:65], v[198:199] op_sel:[0,0,1] op_sel_hi:[1,0,0] neg_lo:[1,0,0] neg_hi:[1,0,0]
	v_pk_add_f32 v[198:199], v[218:219], v[176:177]
	v_pk_add_f32 v[176:177], v[218:219], v[176:177] neg_lo:[0,1] neg_hi:[0,1]
	v_pk_add_f32 v[218:219], v[206:207], v[162:163]
	v_pk_add_f32 v[162:163], v[206:207], v[162:163] neg_lo:[0,1] neg_hi:[0,1]
	v_xor_b32_e32 v24, 0x80000000, v17
	v_pk_mul_f32 v[206:207], v[162:163], s[68:69]
	v_xor_b32_e32 v28, 0x80000000, v19
	v_pk_fma_f32 v[162:163], v[162:163], s[64:65], v[206:207] op_sel:[0,0,1] op_sel_hi:[1,0,0]
	v_pk_add_f32 v[206:207], v[172:173], v[180:181]
	v_pk_add_f32 v[180:181], v[172:173], v[180:181] neg_lo:[0,1] neg_hi:[0,1]
	v_pk_fma_f32 v[22:23], v[10:11], v[8:9], v[22:23] op_sel_hi:[1,0,1]
	v_pk_add_f32 v[172:173], v[174:175], v[182:183]
	v_pk_add_f32 v[174:175], v[174:175], v[182:183] neg_lo:[0,1] neg_hi:[0,1]
	v_pk_fma_f32 v[42:43], v[8:9], v[26:27], v[42:43] op_sel_hi:[0,1,1]
	v_pk_mul_f32 v[182:183], v[174:175], s[68:69]
	v_pk_fma_f32 v[58:59], v[8:9], v[46:47], v[58:59] op_sel_hi:[0,1,1]
	v_pk_fma_f32 v[174:175], v[174:175], s[64:65], v[182:183] op_sel:[0,0,1] op_sel_hi:[1,0,0] neg_lo:[1,0,0] neg_hi:[1,0,0]
	v_pk_add_f32 v[182:183], v[154:155], v[178:179] op_sel:[0,1] op_sel_hi:[1,0] neg_hi:[0,1]
	v_pk_add_f32 v[154:155], v[154:155], v[178:179] op_sel:[0,1] op_sel_hi:[1,0] neg_lo:[0,1]
	v_pk_add_f32 v[178:179], v[156:157], v[164:165]
	v_pk_add_f32 v[156:157], v[156:157], v[164:165] neg_lo:[0,1] neg_hi:[0,1]
	v_pk_fma_f32 v[74:75], v[8:9], v[62:63], v[74:75] op_sel_hi:[0,1,1]
	v_pk_mul_f32 v[164:165], v[156:157], s[68:69]
	v_pk_fma_f32 v[90:91], v[8:9], v[78:79], v[90:91] op_sel_hi:[0,1,1]
	v_pk_fma_f32 v[156:157], v[156:157], s[64:65], v[164:165] op_sel:[0,0,1] op_sel_hi:[1,0,0]
	v_pk_add_f32 v[164:165], v[158:159], v[166:167]
	v_pk_add_f32 v[166:167], v[158:159], v[166:167] neg_lo:[0,1] neg_hi:[0,1]
	v_pk_fma_f32 v[106:107], v[8:9], v[94:95], v[106:107] op_sel_hi:[0,1,1]
	v_pk_add_f32 v[158:159], v[160:161], v[168:169]
	v_pk_add_f32 v[160:161], v[160:161], v[168:169] neg_lo:[0,1] neg_hi:[0,1]
	v_pk_fma_f32 v[122:123], v[8:9], v[110:111], v[122:123] op_sel_hi:[0,1,1]
	v_pk_mul_f32 v[168:169], v[160:161], s[68:69]
	v_mov_b32_e32 v25, v17
	v_pk_fma_f32 v[160:161], v[160:161], s[64:65], v[168:169] op_sel:[0,0,1] op_sel_hi:[1,0,0] neg_lo:[1,0,0] neg_hi:[1,0,0]
	v_pk_add_f32 v[168:169], v[184:185], v[222:223]
	v_pk_add_f32 v[184:185], v[184:185], v[222:223] neg_lo:[0,1] neg_hi:[0,1]
	v_pk_add_f32 v[222:223], v[220:221], v[186:187]
	v_pk_add_f32 v[220:221], v[220:221], v[186:187] neg_lo:[0,1] neg_hi:[0,1]
	v_mov_b32_e32 v29, v19
	v_pk_add_f32 v[186:187], v[210:211], v[214:215] op_sel:[0,1] op_sel_hi:[1,0] neg_hi:[0,1]
	v_pk_add_f32 v[210:211], v[210:211], v[214:215] op_sel:[0,1] op_sel_hi:[1,0] neg_lo:[0,1]
	v_pk_add_f32 v[214:215], v[192:193], v[208:209]
	v_pk_add_f32 v[208:209], v[192:193], v[208:209] neg_lo:[0,1] neg_hi:[0,1]
	v_xor_b32_e32 v32, 0x80000000, v23
	v_pk_add_f32 v[192:193], v[216:217], v[194:195]
	v_pk_add_f32 v[194:195], v[216:217], v[194:195] neg_lo:[0,1] neg_hi:[0,1]
	v_pk_add_f32 v[216:217], v[212:213], v[188:189]
	v_pk_add_f32 v[212:213], v[212:213], v[188:189] neg_lo:[0,1] neg_hi:[0,1]
	v_xor_b32_e32 v40, 0x80000000, v27
	v_pk_add_f32 v[188:189], v[204:205], v[196:197] op_sel:[0,1] op_sel_hi:[1,0] neg_hi:[0,1]
	v_pk_add_f32 v[196:197], v[204:205], v[196:197] op_sel:[0,1] op_sel_hi:[1,0] neg_lo:[0,1]
	v_pk_add_f32 v[204:205], v[170:171], v[190:191]
	v_pk_add_f32 v[190:191], v[170:171], v[190:191] neg_lo:[0,1] neg_hi:[0,1]
	v_xor_b32_e32 v44, 0x80000000, v31
	v_pk_add_f32 v[170:171], v[198:199], v[206:207]
	v_pk_add_f32 v[198:199], v[198:199], v[206:207] neg_lo:[0,1] neg_hi:[0,1]
	v_pk_add_f32 v[206:207], v[218:219], v[172:173]
	v_pk_add_f32 v[218:219], v[218:219], v[172:173] neg_lo:[0,1] neg_hi:[0,1]
	v_xor_b32_e32 v48, 0x80000000, v39
	v_pk_add_f32 v[172:173], v[176:177], v[180:181] op_sel:[0,1] op_sel_hi:[1,0] neg_hi:[0,1]
	v_pk_add_f32 v[176:177], v[176:177], v[180:181] op_sel:[0,1] op_sel_hi:[1,0] neg_lo:[0,1]
	v_pk_add_f32 v[180:181], v[162:163], v[174:175]
	v_pk_add_f32 v[174:175], v[162:163], v[174:175] neg_lo:[0,1] neg_hi:[0,1]
	v_mov_b32_e32 v33, v23
	v_pk_add_f32 v[162:163], v[182:183], v[164:165]
	v_pk_add_f32 v[164:165], v[182:183], v[164:165] neg_lo:[0,1] neg_hi:[0,1]
	v_pk_add_f32 v[182:183], v[178:179], v[158:159]
	v_pk_add_f32 v[178:179], v[178:179], v[158:159] neg_lo:[0,1] neg_hi:[0,1]
	v_mov_b32_e32 v41, v27
	v_pk_add_f32 v[158:159], v[154:155], v[166:167] op_sel:[0,1] op_sel_hi:[1,0] neg_hi:[0,1]
	v_pk_add_f32 v[154:155], v[154:155], v[166:167] op_sel:[0,1] op_sel_hi:[1,0] neg_lo:[0,1]
	v_pk_add_f32 v[166:167], v[156:157], v[160:161]
	v_pk_add_f32 v[156:157], v[156:157], v[160:161] neg_lo:[0,1] neg_hi:[0,1]
	v_mov_b32_e32 v45, v31
	v_xor_b32_e32 v161, 0x80000000, v156
	v_mov_b32_e32 v160, v157
	v_pk_add_f32 v[156:157], v[168:169], v[222:223]
	v_pk_add_f32 v[168:169], v[168:169], v[222:223] neg_lo:[0,1] neg_hi:[0,1]
	v_pk_add_f32 v[222:223], v[184:185], v[220:221] op_sel:[0,1] op_sel_hi:[1,0] neg_hi:[0,1]
	v_pk_add_f32 v[184:185], v[184:185], v[220:221] op_sel:[0,1] op_sel_hi:[1,0] neg_lo:[0,1]
	v_pk_add_f32 v[220:221], v[186:187], v[214:215]
	v_pk_add_f32 v[186:187], v[186:187], v[214:215] neg_lo:[0,1] neg_hi:[0,1]
	v_pk_add_f32 v[214:215], v[210:211], v[208:209] op_sel:[0,1] op_sel_hi:[1,0] neg_hi:[0,1]
	v_pk_add_f32 v[208:209], v[210:211], v[208:209] op_sel:[0,1] op_sel_hi:[1,0] neg_lo:[0,1]
	v_pk_add_f32 v[210:211], v[192:193], v[216:217]
	v_pk_add_f32 v[192:193], v[192:193], v[216:217] neg_lo:[0,1] neg_hi:[0,1]
	v_pk_add_f32 v[216:217], v[194:195], v[212:213] op_sel:[0,1] op_sel_hi:[1,0] neg_hi:[0,1]
	v_pk_add_f32 v[194:195], v[194:195], v[212:213] op_sel:[0,1] op_sel_hi:[1,0] neg_lo:[0,1]
	v_pk_add_f32 v[212:213], v[188:189], v[204:205]
	v_pk_add_f32 v[188:189], v[188:189], v[204:205] neg_lo:[0,1] neg_hi:[0,1]
	v_pk_add_f32 v[204:205], v[196:197], v[190:191] op_sel:[0,1] op_sel_hi:[1,0] neg_hi:[0,1]
	v_pk_add_f32 v[190:191], v[196:197], v[190:191] op_sel:[0,1] op_sel_hi:[1,0] neg_lo:[0,1]
	v_pk_add_f32 v[196:197], v[170:171], v[206:207]
	v_pk_add_f32 v[170:171], v[170:171], v[206:207] neg_lo:[0,1] neg_hi:[0,1]
	v_pk_mul_f32 v[2:3], v[2:3], v[196:197] op_sel:[0,1] op_sel_hi:[1,0]
	v_pk_add_f32 v[206:207], v[198:199], v[218:219] op_sel:[0,1] op_sel_hi:[1,0] neg_hi:[0,1]
	v_pk_add_f32 v[198:199], v[198:199], v[218:219] op_sel:[0,1] op_sel_hi:[1,0] neg_lo:[0,1]
	v_pk_add_f32 v[218:219], v[172:173], v[180:181]
	v_pk_add_f32 v[172:173], v[172:173], v[180:181] neg_lo:[0,1] neg_hi:[0,1]
	v_pk_add_f32 v[180:181], v[176:177], v[174:175] op_sel:[0,1] op_sel_hi:[1,0] neg_hi:[0,1]
	v_pk_add_f32 v[174:175], v[176:177], v[174:175] op_sel:[0,1] op_sel_hi:[1,0] neg_lo:[0,1]
	v_pk_add_f32 v[176:177], v[162:163], v[182:183]
	v_pk_fma_f32 v[2:3], v[4:5], v[196:197], v[2:3] op_sel_hi:[0,1,1]
	v_pk_mul_f32 v[4:5], v[6:7], v[210:211] op_sel:[1,1] op_sel_hi:[1,0] neg_lo:[1,0]
	v_mov_b32_e32 v49, v39
	v_pk_fma_f32 v[4:5], v[6:7], v[210:211], v[4:5] op_sel_hi:[0,1,1]
	v_pk_mul_f32 v[6:7], v[8:9], v[176:177] op_sel:[1,1] op_sel_hi:[1,0] neg_lo:[1,0]
	v_pk_add_f32 v[162:163], v[162:163], v[182:183] neg_lo:[0,1] neg_hi:[0,1]
	v_pk_fma_f32 v[6:7], v[8:9], v[176:177], v[6:7] op_sel_hi:[0,1,1]
	v_pk_mul_f32 v[8:9], v[10:11], v[220:221] op_sel:[1,1] op_sel_hi:[1,0] neg_lo:[1,0]
	v_pk_add_f32 v[182:183], v[164:165], v[178:179] op_sel:[0,1] op_sel_hi:[1,0] neg_hi:[0,1]
	v_pk_add_f32 v[164:165], v[164:165], v[178:179] op_sel:[0,1] op_sel_hi:[1,0] neg_lo:[0,1]
	v_pk_add_f32 v[178:179], v[158:159], v[166:167]
	v_pk_fma_f32 v[8:9], v[10:11], v[220:221], v[8:9] op_sel_hi:[0,1,1]
	v_pk_mul_f32 v[10:11], v[24:25], v[218:219] op_sel:[0,1] op_sel_hi:[1,0]
	v_pk_mul_f32 v[12:13], v[28:29], v[212:213] op_sel:[0,1] op_sel_hi:[1,0]
	v_pk_add_f32 v[158:159], v[158:159], v[166:167] neg_lo:[0,1] neg_hi:[0,1]
	v_pk_add_f32 v[166:167], v[154:155], v[160:161]
	v_pk_fma_f32 v[10:11], v[16:17], v[218:219], v[10:11] op_sel_hi:[0,1,1]
	v_pk_fma_f32 v[12:13], v[18:19], v[212:213], v[12:13] op_sel_hi:[0,1,1]
	v_pk_mul_f32 v[14:15], v[32:33], v[178:179] op_sel:[0,1] op_sel_hi:[1,0]
	v_pk_mul_f32 v[16:17], v[40:41], v[222:223] op_sel:[0,1] op_sel_hi:[1,0]
	v_pk_mul_f32 v[18:19], v[44:45], v[206:207] op_sel:[0,1] op_sel_hi:[1,0]
	v_pk_mul_f32 v[20:21], v[48:49], v[216:217] op_sel:[0,1] op_sel_hi:[1,0]
	v_xor_b32_e32 v80, 0x80000000, v71
	v_xor_b32_e32 v84, 0x80000000, v75
	v_xor_b32_e32 v88, 0x80000000, v79
	v_xor_b32_e32 v92, 0x80000000, v83
	v_xor_b32_e32 v96, 0x80000000, v87
	v_xor_b32_e32 v100, 0x80000000, v91
	v_xor_b32_e32 v104, 0x80000000, v95
	v_xor_b32_e32 v108, 0x80000000, v99
	v_xor_b32_e32 v112, 0x80000000, v103
	v_xor_b32_e32 v116, 0x80000000, v107
	v_xor_b32_e32 v120, 0x80000000, v111
	v_xor_b32_e32 v124, 0x80000000, v115
	v_xor_b32_e32 v126, 0x80000000, v119
	v_xor_b32_e32 v128, 0x80000000, v123
	v_mov_b32_e32 v81, v71
	v_mov_b32_e32 v85, v75
	v_mov_b32_e32 v89, v79
	v_mov_b32_e32 v93, v83
	v_mov_b32_e32 v97, v87
	v_mov_b32_e32 v101, v91
	v_mov_b32_e32 v105, v95
	v_mov_b32_e32 v109, v99
	v_mov_b32_e32 v113, v103
	v_mov_b32_e32 v117, v107
	v_mov_b32_e32 v121, v111
	v_mov_b32_e32 v125, v115
	v_mov_b32_e32 v127, v119
	v_mov_b32_e32 v129, v123
	v_pk_add_f32 v[154:155], v[154:155], v[160:161] neg_lo:[0,1] neg_hi:[0,1]
	v_pk_fma_f32 v[14:15], v[22:23], v[178:179], v[14:15] op_sel_hi:[0,1,1]
	v_pk_fma_f32 v[16:17], v[26:27], v[222:223], v[16:17] op_sel_hi:[0,1,1]
	v_pk_fma_f32 v[18:19], v[30:31], v[206:207], v[18:19] op_sel_hi:[0,1,1]
	v_pk_fma_f32 v[20:21], v[38:39], v[216:217], v[20:21] op_sel_hi:[0,1,1]
	v_pk_mul_f32 v[22:23], v[42:43], v[182:183] op_sel:[1,1] op_sel_hi:[1,0] neg_lo:[1,0]
	v_pk_mul_f32 v[24:25], v[46:47], v[214:215] op_sel:[1,1] op_sel_hi:[1,0] neg_lo:[1,0]
	v_pk_mul_f32 v[26:27], v[50:51], v[180:181] op_sel:[1,1] op_sel_hi:[1,0] neg_lo:[1,0]
	v_pk_mul_f32 v[28:29], v[54:55], v[204:205] op_sel:[1,1] op_sel_hi:[1,0] neg_lo:[1,0]
	v_pk_mul_f32 v[30:31], v[58:59], v[166:167] op_sel:[1,1] op_sel_hi:[1,0] neg_lo:[1,0]
	v_pk_mul_f32 v[32:33], v[62:63], v[168:169] op_sel:[1,1] op_sel_hi:[1,0] neg_lo:[1,0]
	v_pk_mul_f32 v[38:39], v[66:67], v[170:171] op_sel:[1,1] op_sel_hi:[1,0] neg_lo:[1,0]
	v_pk_fma_f32 v[22:23], v[42:43], v[182:183], v[22:23] op_sel_hi:[0,1,1]
	v_pk_fma_f32 v[24:25], v[46:47], v[214:215], v[24:25] op_sel_hi:[0,1,1]
	v_pk_fma_f32 v[26:27], v[50:51], v[180:181], v[26:27] op_sel_hi:[0,1,1]
	v_pk_fma_f32 v[28:29], v[54:55], v[204:205], v[28:29] op_sel_hi:[0,1,1]
	v_pk_fma_f32 v[30:31], v[58:59], v[166:167], v[30:31] op_sel_hi:[0,1,1]
	v_pk_fma_f32 v[32:33], v[62:63], v[168:169], v[32:33] op_sel_hi:[0,1,1]
	v_pk_fma_f32 v[38:39], v[66:67], v[170:171], v[38:39] op_sel_hi:[0,1,1]
	v_pk_mul_f32 v[40:41], v[80:81], v[192:193] op_sel:[0,1] op_sel_hi:[1,0]
	v_pk_mul_f32 v[42:43], v[84:85], v[162:163] op_sel:[0,1] op_sel_hi:[1,0]
	v_pk_mul_f32 v[44:45], v[88:89], v[186:187] op_sel:[0,1] op_sel_hi:[1,0]
	v_pk_mul_f32 v[46:47], v[92:93], v[172:173] op_sel:[0,1] op_sel_hi:[1,0]
	v_pk_mul_f32 v[48:49], v[96:97], v[188:189] op_sel:[0,1] op_sel_hi:[1,0]
	v_pk_mul_f32 v[50:51], v[100:101], v[158:159] op_sel:[0,1] op_sel_hi:[1,0]
	v_pk_mul_f32 v[52:53], v[104:105], v[184:185] op_sel:[0,1] op_sel_hi:[1,0]
	v_pk_mul_f32 v[54:55], v[108:109], v[198:199] op_sel:[0,1] op_sel_hi:[1,0]
	v_pk_mul_f32 v[56:57], v[112:113], v[194:195] op_sel:[0,1] op_sel_hi:[1,0]
	v_pk_mul_f32 v[58:59], v[116:117], v[164:165] op_sel:[0,1] op_sel_hi:[1,0]
	v_pk_mul_f32 v[60:61], v[120:121], v[208:209] op_sel:[0,1] op_sel_hi:[1,0]
	v_pk_mul_f32 v[62:63], v[124:125], v[174:175] op_sel:[0,1] op_sel_hi:[1,0]
	v_pk_mul_f32 v[64:65], v[126:127], v[190:191] op_sel:[0,1] op_sel_hi:[1,0]
	v_pk_mul_f32 v[66:67], v[128:129], v[154:155] op_sel:[0,1] op_sel_hi:[1,0]
	v_pk_fma_f32 v[40:41], v[70:71], v[192:193], v[40:41] op_sel_hi:[0,1,1]
	v_pk_fma_f32 v[42:43], v[74:75], v[162:163], v[42:43] op_sel_hi:[0,1,1]
	v_pk_fma_f32 v[44:45], v[78:79], v[186:187], v[44:45] op_sel_hi:[0,1,1]
	v_pk_fma_f32 v[46:47], v[82:83], v[172:173], v[46:47] op_sel_hi:[0,1,1]
	v_pk_fma_f32 v[48:49], v[86:87], v[188:189], v[48:49] op_sel_hi:[0,1,1]
	v_pk_fma_f32 v[50:51], v[90:91], v[158:159], v[50:51] op_sel_hi:[0,1,1]
	v_pk_fma_f32 v[52:53], v[94:95], v[184:185], v[52:53] op_sel_hi:[0,1,1]
	v_pk_fma_f32 v[54:55], v[98:99], v[198:199], v[54:55] op_sel_hi:[0,1,1]
	v_pk_fma_f32 v[56:57], v[102:103], v[194:195], v[56:57] op_sel_hi:[0,1,1]
	v_pk_fma_f32 v[58:59], v[106:107], v[164:165], v[58:59] op_sel_hi:[0,1,1]
	v_pk_fma_f32 v[60:61], v[110:111], v[208:209], v[60:61] op_sel_hi:[0,1,1]
	v_pk_fma_f32 v[62:63], v[114:115], v[174:175], v[62:63] op_sel_hi:[0,1,1]
	v_pk_fma_f32 v[64:65], v[118:119], v[190:191], v[64:65] op_sel_hi:[0,1,1]
	v_pk_fma_f32 v[66:67], v[122:123], v[154:155], v[66:67] op_sel_hi:[0,1,1]
	ds_write_b64 v36, v[156:157]
	ds_write_b64 v36, v[32:33] offset:2112
	ds_write_b64 v36, v[16:17] offset:4224
	ds_write_b64 v36, v[52:53] offset:6336
	ds_write_b64 v36, v[8:9] offset:8448
	ds_write_b64 v36, v[44:45] offset:10560
	ds_write_b64 v36, v[24:25] offset:12672
	ds_write_b64 v36, v[60:61] offset:14784
	ds_write_b64 v36, v[4:5] offset:16896
	ds_write_b64 v36, v[40:41] offset:19008
	ds_write_b64 v36, v[20:21] offset:21120
	ds_write_b64 v36, v[56:57] offset:23232
	ds_write_b64 v36, v[12:13] offset:25344
	ds_write_b64 v36, v[48:49] offset:27456
	ds_write_b64 v36, v[28:29] offset:29568
	ds_write_b64 v36, v[64:65] offset:31680
	ds_write_b64 v36, v[2:3] offset:33792
	ds_write_b64 v36, v[38:39] offset:35904
	ds_write_b64 v36, v[18:19] offset:38016
	ds_write_b64 v36, v[54:55] offset:40128
	ds_write_b64 v36, v[10:11] offset:42240
	ds_write_b64 v36, v[46:47] offset:44352
	ds_write_b64 v36, v[26:27] offset:46464
	ds_write_b64 v36, v[62:63] offset:48576
	ds_write_b64 v36, v[6:7] offset:50688
	ds_write_b64 v36, v[42:43] offset:52800
	ds_write_b64 v36, v[22:23] offset:54912
	ds_write_b64 v36, v[58:59] offset:57024
	ds_write_b64 v36, v[14:15] offset:59136
	ds_write_b64 v36, v[50:51] offset:61248
	ds_write_b64 v36, v[30:31] offset:63360
	ds_write_b64 v36, v[66:67] offset:65472
	v_mov_b32_e32 v3, v130
	s_waitcnt lgkmcnt(0)
	s_barrier
	s_nop 0
	v_and_b32_e32 v5, 15, v3
	v_cvt_f32_ubyte0_e32 v2, v5
	v_mul_f32_e32 v4, 0x3b800000, v2
	v_sin_f32_e32 v2, v4
	v_cos_f32_e32 v4, v4
	v_lshlrev_b32_e32 v66, 3, v5
	v_lshlrev_b32_e32 v36, 4, v3
	v_xor_b32_e32 v5, 0x80000000, v2
	v_mov_b32_e32 v3, v5
	v_pk_mul_f32 v[6:7], v[4:5], v[2:3] op_sel:[1,0] op_sel_hi:[0,1]
	v_pk_fma_f32 v[6:7], v[4:5], v[4:5], v[6:7] op_sel_hi:[0,1,1]
	v_pk_mul_f32 v[10:11], v[6:7], v[6:7] op_sel:[1,1] op_sel_hi:[0,1] neg_lo:[0,1]
	v_pk_fma_f32 v[10:11], v[6:7], v[6:7], v[10:11] op_sel_hi:[1,0,1]
	v_pk_mul_f32 v[8:9], v[2:3], v[6:7] op_sel:[0,1] op_sel_hi:[1,0]
	v_pk_mul_f32 v[30:31], v[10:11], v[10:11] op_sel:[1,1] op_sel_hi:[0,1] neg_lo:[0,1]
	v_pk_fma_f32 v[30:31], v[10:11], v[10:11], v[30:31] op_sel_hi:[1,0,1]
	v_pk_mul_f32 v[16:17], v[2:3], v[10:11] op_sel:[0,1] op_sel_hi:[1,0]
	v_pk_mul_f32 v[50:51], v[10:11], v[30:31] op_sel:[1,1] op_sel_hi:[1,0] neg_lo:[1,0]
	v_pk_mul_f32 v[38:39], v[2:3], v[30:31] op_sel:[0,1] op_sel_hi:[1,0]
	v_pk_fma_f32 v[50:51], v[10:11], v[30:31], v[50:51] op_sel_hi:[0,1,1]
	v_pk_mul_f32 v[54:55], v[2:3], v[50:51] op_sel:[0,1] op_sel_hi:[1,0]
	v_pk_fma_f32 v[8:9], v[4:5], v[6:7], v[8:9] op_sel_hi:[0,1,1]
	v_pk_fma_f32 v[16:17], v[4:5], v[10:11], v[16:17] op_sel_hi:[0,1,1]
	v_pk_fma_f32 v[38:39], v[4:5], v[30:31], v[38:39] op_sel_hi:[0,1,1]
	v_pk_fma_f32 v[54:55], v[4:5], v[50:51], v[54:55] op_sel_hi:[0,1,1]
	v_and_b32_e32 v5, 0xffffff00, v36
	v_lshlrev_b32_e32 v36, 3, v5
	v_add3_u32 v36, 0, v66, v36
	v_ashrrev_i32_e32 v66, 2, v5
	v_add_u32_e32 v108, v36, v66
	ds_read2_b64 v[66:69], v108 offset1:16
	ds_read2_b64 v[70:73], v108 offset0:33 offset1:49
	ds_read2_b64 v[74:77], v108 offset0:66 offset1:82
	ds_read2_b64 v[78:81], v108 offset0:132 offset1:148
	ds_read2_b64 v[82:85], v108 offset0:99 offset1:115
	ds_read2_b64 v[86:89], v108 offset0:165 offset1:181
	ds_read2_b64 v[90:93], v108 offset0:198 offset1:214
	ds_read2_b64 v[94:97], v108 offset0:231 offset1:247
	s_waitcnt lgkmcnt(4)
	v_pk_add_f32 v[98:99], v[66:67], v[78:79]
	v_pk_add_f32 v[66:67], v[66:67], v[78:79] neg_lo:[0,1] neg_hi:[0,1]
	v_pk_add_f32 v[78:79], v[68:69], v[80:81]
	v_pk_add_f32 v[68:69], v[68:69], v[80:81] neg_lo:[0,1] neg_hi:[0,1]
	s_waitcnt lgkmcnt(1)
	v_pk_add_f32 v[100:101], v[76:77], v[92:93]
	v_pk_mul_f32 v[80:81], v[68:69], s[44:45]
	v_pk_add_f32 v[76:77], v[76:77], v[92:93] neg_lo:[0,1] neg_hi:[0,1]
	v_pk_fma_f32 v[68:69], v[68:69], s[42:43], v[80:81] op_sel:[0,0,1] op_sel_hi:[1,0,0]
	v_pk_add_f32 v[80:81], v[70:71], v[86:87]
	v_pk_add_f32 v[70:71], v[70:71], v[86:87] neg_lo:[0,1] neg_hi:[0,1]
	v_pk_mul_f32 v[92:93], v[76:77], s[76:77]
	v_pk_mul_f32 v[86:87], v[70:71], s[68:69]
	v_pk_fma_f32 v[76:77], v[76:77], s[72:73], v[92:93] op_sel:[0,0,1] op_sel_hi:[1,0,0] neg_lo:[1,0,0] neg_hi:[1,0,0]
	v_pk_fma_f32 v[70:71], v[70:71], s[64:65], v[86:87] op_sel:[0,0,1] op_sel_hi:[1,0,0]
	v_pk_add_f32 v[86:87], v[72:73], v[88:89]
	v_pk_add_f32 v[72:73], v[72:73], v[88:89] neg_lo:[0,1] neg_hi:[0,1]
	s_waitcnt lgkmcnt(0)
	v_pk_add_f32 v[92:93], v[82:83], v[94:95]
	v_pk_add_f32 v[82:83], v[82:83], v[94:95] neg_lo:[0,1] neg_hi:[0,1]
	v_pk_mul_f32 v[88:89], v[72:73], s[76:77]
	v_pk_mul_f32 v[94:95], v[82:83], s[68:69]
	v_pk_fma_f32 v[72:73], v[72:73], s[72:73], v[88:89] op_sel:[0,0,1] op_sel_hi:[1,0,0]
	v_pk_add_f32 v[88:89], v[74:75], v[90:91]
	v_pk_add_f32 v[90:91], v[74:75], v[90:91] neg_lo:[0,1] neg_hi:[0,1]
	v_pk_fma_f32 v[82:83], v[82:83], s[64:65], v[94:95] op_sel:[0,0,1] op_sel_hi:[1,0,0] neg_lo:[1,0,0] neg_hi:[1,0,0]
	v_pk_add_f32 v[94:95], v[84:85], v[96:97]
	v_pk_add_f32 v[84:85], v[84:85], v[96:97] neg_lo:[0,1] neg_hi:[0,1]
	s_nop 0
	v_pk_mul_f32 v[96:97], v[84:85], s[44:45]
	s_nop 0
	v_pk_fma_f32 v[84:85], v[84:85], s[42:43], v[96:97] op_sel:[0,0,1] op_sel_hi:[1,0,0] neg_lo:[1,0,0] neg_hi:[1,0,0]
	v_pk_add_f32 v[96:97], v[98:99], v[88:89]
	v_pk_add_f32 v[88:89], v[98:99], v[88:89] neg_lo:[0,1] neg_hi:[0,1]
	v_pk_add_f32 v[98:99], v[78:79], v[100:101]
	v_pk_add_f32 v[78:79], v[78:79], v[100:101] neg_lo:[0,1] neg_hi:[0,1]
	v_pk_add_f32 v[102:103], v[86:87], v[94:95]
	v_pk_add_f32 v[86:87], v[86:87], v[94:95] neg_lo:[0,1] neg_hi:[0,1]
	v_pk_add_f32 v[74:75], v[66:67], v[90:91] op_sel:[0,1] op_sel_hi:[1,0] neg_hi:[0,1]
	v_pk_add_f32 v[66:67], v[66:67], v[90:91] op_sel:[0,1] op_sel_hi:[1,0] neg_lo:[0,1]
	v_pk_add_f32 v[90:91], v[68:69], v[76:77]
	v_pk_add_f32 v[68:69], v[68:69], v[76:77] neg_lo:[0,1] neg_hi:[0,1]
	v_pk_mul_f32 v[100:101], v[78:79], s[68:69]
	v_pk_mul_f32 v[94:95], v[86:87], s[68:69]
	v_pk_mul_f32 v[76:77], v[68:69], s[68:69]
	v_pk_fma_f32 v[78:79], v[78:79], s[64:65], v[100:101] op_sel:[0,0,1] op_sel_hi:[1,0,0]
	v_pk_add_f32 v[100:101], v[80:81], v[92:93]
	v_pk_add_f32 v[92:93], v[80:81], v[92:93] neg_lo:[0,1] neg_hi:[0,1]
	v_pk_fma_f32 v[86:87], v[86:87], s[64:65], v[94:95] op_sel:[0,0,1] op_sel_hi:[1,0,0] neg_lo:[1,0,0] neg_hi:[1,0,0]
	v_pk_fma_f32 v[68:69], v[68:69], s[64:65], v[76:77] op_sel:[0,0,1] op_sel_hi:[1,0,0]
	v_pk_add_f32 v[76:77], v[70:71], v[82:83]
	v_pk_add_f32 v[94:95], v[72:73], v[84:85]
	v_pk_add_f32 v[72:73], v[72:73], v[84:85] neg_lo:[0,1] neg_hi:[0,1]
	v_pk_add_f32 v[70:71], v[70:71], v[82:83] neg_lo:[0,1] neg_hi:[0,1]
	v_pk_mul_f32 v[84:85], v[72:73], s[68:69]
	v_pk_add_f32 v[104:105], v[74:75], v[76:77]
	v_pk_add_f32 v[74:75], v[74:75], v[76:77] neg_lo:[0,1] neg_hi:[0,1]
	v_pk_add_f32 v[76:77], v[90:91], v[94:95]
	v_pk_add_f32 v[94:95], v[90:91], v[94:95] neg_lo:[0,1] neg_hi:[0,1]
	v_pk_mul_f32 v[22:23], v[6:7], v[10:11] op_sel:[1,1] op_sel_hi:[1,0] neg_lo:[1,0]
	v_xor_b32_e32 v83, 0x80000000, v70
	v_pk_fma_f32 v[72:73], v[72:73], s[64:65], v[84:85] op_sel:[0,0,1] op_sel_hi:[1,0,0] neg_lo:[1,0,0] neg_hi:[1,0,0]
	v_pk_add_f32 v[80:81], v[88:89], v[92:93] op_sel:[0,1] op_sel_hi:[1,0] neg_hi:[0,1]
	v_pk_add_f32 v[88:89], v[88:89], v[92:93] op_sel:[0,1] op_sel_hi:[1,0] neg_lo:[0,1]
	v_pk_add_f32 v[92:93], v[78:79], v[86:87]
	v_pk_add_f32 v[86:87], v[78:79], v[86:87] neg_lo:[0,1] neg_hi:[0,1]
	v_mov_b32_e32 v82, v71
	v_pk_fma_f32 v[22:23], v[6:7], v[10:11], v[22:23] op_sel_hi:[0,1,1]
	v_pk_mul_f32 v[26:27], v[10:11], v[8:9] op_sel:[1,1] op_sel_hi:[0,1] neg_lo:[0,1]
	v_pk_add_f32 v[70:71], v[66:67], v[82:83]
	v_pk_add_f32 v[66:67], v[66:67], v[82:83] neg_lo:[0,1] neg_hi:[0,1]
	v_pk_add_f32 v[82:83], v[68:69], v[72:73]
	v_pk_add_f32 v[72:73], v[68:69], v[72:73] neg_lo:[0,1] neg_hi:[0,1]
	v_pk_add_f32 v[90:91], v[74:75], v[94:95] op_sel:[0,1] op_sel_hi:[1,0] neg_hi:[0,1]
	v_pk_fma_f32 v[26:27], v[10:11], v[8:9], v[26:27] op_sel_hi:[1,0,1]
	v_pk_add_f32 v[78:79], v[88:89], v[86:87] op_sel:[0,1] op_sel_hi:[1,0] neg_hi:[0,1]
	v_pk_add_f32 v[74:75], v[74:75], v[94:95] op_sel:[0,1] op_sel_hi:[1,0] neg_lo:[0,1]
	v_pk_mul_f32 v[94:95], v[16:17], v[90:91] op_sel:[1,1] op_sel_hi:[1,0] neg_lo:[1,0]
	v_pk_add_f32 v[84:85], v[96:97], v[100:101]
	v_pk_add_f32 v[96:97], v[96:97], v[100:101] neg_lo:[0,1] neg_hi:[0,1]
	v_pk_add_f32 v[100:101], v[98:99], v[102:103]
	v_pk_add_f32 v[68:69], v[66:67], v[72:73] op_sel:[0,1] op_sel_hi:[1,0] neg_hi:[0,1]
	v_pk_fma_f32 v[90:91], v[16:17], v[90:91], v[94:95] op_sel_hi:[0,1,1]
	v_pk_mul_f32 v[94:95], v[22:23], v[78:79] op_sel:[1,1] op_sel_hi:[1,0] neg_lo:[1,0]
	v_pk_mul_f32 v[42:43], v[6:7], v[30:31] op_sel:[1,1] op_sel_hi:[1,0] neg_lo:[1,0]
	v_pk_add_f32 v[106:107], v[84:85], v[100:101]
	v_pk_add_f32 v[84:85], v[84:85], v[100:101] neg_lo:[0,1] neg_hi:[0,1]
	v_pk_fma_f32 v[78:79], v[22:23], v[78:79], v[94:95] op_sel_hi:[0,1,1]
	v_pk_mul_f32 v[94:95], v[26:27], v[68:69] op_sel:[1,1] op_sel_hi:[1,0] neg_lo:[1,0]
	v_xor_b32_e32 v40, 0x80000000, v39
	v_mov_b32_e32 v41, v39
	v_pk_fma_f32 v[42:43], v[6:7], v[30:31], v[42:43] op_sel_hi:[0,1,1]
	v_pk_mul_f32 v[46:47], v[8:9], v[30:31] op_sel:[1,1] op_sel_hi:[1,0] neg_lo:[1,0]
	v_pk_add_f32 v[86:87], v[88:89], v[86:87] op_sel:[0,1] op_sel_hi:[1,0] neg_lo:[0,1]
	v_pk_add_f32 v[88:89], v[104:105], v[76:77]
	v_pk_add_f32 v[76:77], v[104:105], v[76:77] neg_lo:[0,1] neg_hi:[0,1]
	v_pk_fma_f32 v[68:69], v[26:27], v[68:69], v[94:95] op_sel_hi:[0,1,1]
	v_pk_mul_f32 v[94:95], v[30:31], v[84:85] op_sel:[1,1] op_sel_hi:[1,0] neg_lo:[1,0]
	v_xor_b32_e32 v44, 0x80000000, v43
	v_mov_b32_e32 v45, v43
	v_pk_fma_f32 v[46:47], v[8:9], v[30:31], v[46:47] op_sel_hi:[0,1,1]
	v_pk_add_f32 v[102:103], v[98:99], v[102:103] neg_lo:[0,1] neg_hi:[0,1]
	v_pk_add_f32 v[100:101], v[80:81], v[92:93]
	v_pk_add_f32 v[80:81], v[80:81], v[92:93] neg_lo:[0,1] neg_hi:[0,1]
	v_pk_fma_f32 v[84:85], v[30:31], v[84:85], v[94:95] op_sel_hi:[0,1,1]
	v_pk_mul_f32 v[94:95], v[40:41], v[76:77] op_sel:[0,1] op_sel_hi:[1,0]
	v_xor_b32_e32 v48, 0x80000000, v47
	v_mov_b32_e32 v49, v47
	v_pk_add_f32 v[92:93], v[70:71], v[82:83]
	v_pk_add_f32 v[70:71], v[70:71], v[82:83] neg_lo:[0,1] neg_hi:[0,1]
	v_pk_fma_f32 v[76:77], v[38:39], v[76:77], v[94:95] op_sel_hi:[0,1,1]
	v_pk_mul_f32 v[94:95], v[44:45], v[80:81] op_sel:[0,1] op_sel_hi:[1,0]
	v_xor_b32_e32 v52, 0x80000000, v51
	v_mov_b32_e32 v53, v51
	v_pk_mul_f32 v[58:59], v[6:7], v[50:51] op_sel:[1,1] op_sel_hi:[1,0] neg_lo:[1,0]
	v_pk_add_f32 v[98:99], v[96:97], v[102:103] op_sel:[0,1] op_sel_hi:[1,0] neg_hi:[0,1]
	v_pk_add_f32 v[96:97], v[96:97], v[102:103] op_sel:[0,1] op_sel_hi:[1,0] neg_lo:[0,1]
	v_pk_fma_f32 v[80:81], v[42:43], v[80:81], v[94:95] op_sel_hi:[0,1,1]
	v_pk_mul_f32 v[94:95], v[48:49], v[70:71] op_sel:[0,1] op_sel_hi:[1,0]
	v_xor_b32_e32 v56, 0x80000000, v55
	v_mov_b32_e32 v57, v55
	v_pk_fma_f32 v[58:59], v[6:7], v[50:51], v[58:59] op_sel_hi:[0,1,1]
	v_pk_mul_f32 v[62:63], v[8:9], v[50:51] op_sel:[1,1] op_sel_hi:[1,0] neg_lo:[1,0]
	v_pk_fma_f32 v[70:71], v[46:47], v[70:71], v[94:95] op_sel_hi:[0,1,1]
	v_pk_mul_f32 v[94:95], v[52:53], v[96:97] op_sel:[0,1] op_sel_hi:[1,0]
	v_xor_b32_e32 v60, 0x80000000, v59
	v_mov_b32_e32 v61, v59
	v_pk_fma_f32 v[62:63], v[8:9], v[50:51], v[62:63] op_sel_hi:[0,1,1]
	v_pk_add_f32 v[66:67], v[66:67], v[72:73] op_sel:[0,1] op_sel_hi:[1,0] neg_lo:[0,1]
	v_pk_mul_f32 v[72:73], v[2:3], v[88:89] op_sel:[0,1] op_sel_hi:[1,0]
	v_pk_fma_f32 v[94:95], v[50:51], v[96:97], v[94:95] op_sel_hi:[0,1,1]
	v_pk_mul_f32 v[96:97], v[56:57], v[74:75] op_sel:[0,1] op_sel_hi:[1,0]
	v_xor_b32_e32 v64, 0x80000000, v63
	v_mov_b32_e32 v65, v63
	v_pk_fma_f32 v[72:73], v[4:5], v[88:89], v[72:73] op_sel_hi:[0,1,1]
	v_pk_mul_f32 v[88:89], v[8:9], v[92:93] op_sel:[1,1] op_sel_hi:[1,0] neg_lo:[1,0]
	v_pk_fma_f32 v[74:75], v[54:55], v[74:75], v[96:97] op_sel_hi:[0,1,1]
	v_pk_mul_f32 v[96:97], v[60:61], v[86:87] op_sel:[0,1] op_sel_hi:[1,0]
	v_add_u32_e32 v5, 0x2000, v5
	v_pk_mul_f32 v[82:83], v[6:7], v[100:101] op_sel:[1,1] op_sel_hi:[1,0] neg_lo:[1,0]
	v_pk_fma_f32 v[88:89], v[8:9], v[92:93], v[88:89] op_sel_hi:[0,1,1]
	v_pk_mul_f32 v[92:93], v[10:11], v[98:99] op_sel:[1,1] op_sel_hi:[1,0] neg_lo:[1,0]
	v_pk_fma_f32 v[86:87], v[58:59], v[86:87], v[96:97] op_sel_hi:[0,1,1]
	v_pk_mul_f32 v[96:97], v[64:65], v[66:67] op_sel:[0,1] op_sel_hi:[1,0]
	v_ashrrev_i32_e32 v5, 2, v5
	v_pk_fma_f32 v[82:83], v[6:7], v[100:101], v[82:83] op_sel_hi:[0,1,1]
	v_pk_fma_f32 v[92:93], v[10:11], v[98:99], v[92:93] op_sel_hi:[0,1,1]
	v_pk_fma_f32 v[66:67], v[62:63], v[66:67], v[96:97] op_sel_hi:[0,1,1]
	ds_write2_b64 v108, v[106:107], v[84:85] offset1:16
	ds_write2_b64 v108, v[92:93], v[94:95] offset0:33 offset1:49
	ds_write2_b64 v108, v[82:83], v[80:81] offset0:66 offset1:82
	ds_write2_b64 v108, v[78:79], v[86:87] offset0:99 offset1:115
	ds_write2_b64 v108, v[72:73], v[76:77] offset0:132 offset1:148
	ds_write2_b64 v108, v[90:91], v[74:75] offset0:165 offset1:181
	ds_write2_b64 v108, v[88:89], v[70:71] offset0:198 offset1:214
	ds_write2_b64 v108, v[68:69], v[66:67] offset0:231 offset1:247
	v_add3_u32 v36, v36, v5, s30
	ds_read2_b64 v[66:69], v36 offset1:16
	ds_read2_b64 v[70:73], v36 offset0:33 offset1:49
	ds_read2_b64 v[74:77], v36 offset0:66 offset1:82
	ds_read2_b64 v[78:81], v36 offset0:132 offset1:148
	ds_read2_b64 v[82:85], v36 offset0:99 offset1:115
	ds_read2_b64 v[86:89], v36 offset0:165 offset1:181
	ds_read2_b64 v[90:93], v36 offset0:198 offset1:214
	ds_read2_b64 v[94:97], v36 offset0:231 offset1:247
	s_waitcnt lgkmcnt(4)
	v_pk_add_f32 v[98:99], v[66:67], v[78:79]
	v_pk_add_f32 v[66:67], v[66:67], v[78:79] neg_lo:[0,1] neg_hi:[0,1]
	v_pk_add_f32 v[78:79], v[68:69], v[80:81]
	v_pk_add_f32 v[68:69], v[68:69], v[80:81] neg_lo:[0,1] neg_hi:[0,1]
	s_waitcnt lgkmcnt(1)
	v_pk_add_f32 v[100:101], v[76:77], v[92:93]
	v_pk_mul_f32 v[80:81], v[68:69], s[44:45]
	v_pk_add_f32 v[76:77], v[76:77], v[92:93] neg_lo:[0,1] neg_hi:[0,1]
	v_pk_fma_f32 v[68:69], v[68:69], s[42:43], v[80:81] op_sel:[0,0,1] op_sel_hi:[1,0,0]
	v_pk_add_f32 v[80:81], v[70:71], v[86:87]
	v_pk_add_f32 v[70:71], v[70:71], v[86:87] neg_lo:[0,1] neg_hi:[0,1]
	v_pk_mul_f32 v[92:93], v[76:77], s[76:77]
	v_pk_mul_f32 v[86:87], v[70:71], s[68:69]
	v_pk_fma_f32 v[76:77], v[76:77], s[72:73], v[92:93] op_sel:[0,0,1] op_sel_hi:[1,0,0] neg_lo:[1,0,0] neg_hi:[1,0,0]
	s_waitcnt lgkmcnt(0)
	v_pk_add_f32 v[92:93], v[82:83], v[94:95]
	v_pk_add_f32 v[82:83], v[82:83], v[94:95] neg_lo:[0,1] neg_hi:[0,1]
	v_pk_fma_f32 v[70:71], v[70:71], s[64:65], v[86:87] op_sel:[0,0,1] op_sel_hi:[1,0,0]
	v_pk_add_f32 v[86:87], v[72:73], v[88:89]
	v_pk_add_f32 v[72:73], v[72:73], v[88:89] neg_lo:[0,1] neg_hi:[0,1]
	v_pk_mul_f32 v[94:95], v[82:83], s[68:69]
	v_pk_mul_f32 v[88:89], v[72:73], s[76:77]
	v_pk_fma_f32 v[82:83], v[82:83], s[64:65], v[94:95] op_sel:[0,0,1] op_sel_hi:[1,0,0] neg_lo:[1,0,0] neg_hi:[1,0,0]
	v_pk_add_f32 v[94:95], v[84:85], v[96:97]
	v_pk_add_f32 v[84:85], v[84:85], v[96:97] neg_lo:[0,1] neg_hi:[0,1]
	v_pk_fma_f32 v[72:73], v[72:73], s[72:73], v[88:89] op_sel:[0,0,1] op_sel_hi:[1,0,0]
	v_pk_add_f32 v[88:89], v[74:75], v[90:91]
	v_pk_mul_f32 v[96:97], v[84:85], s[44:45]
	v_pk_add_f32 v[90:91], v[74:75], v[90:91] neg_lo:[0,1] neg_hi:[0,1]
	v_pk_fma_f32 v[84:85], v[84:85], s[42:43], v[96:97] op_sel:[0,0,1] op_sel_hi:[1,0,0] neg_lo:[1,0,0] neg_hi:[1,0,0]
	v_pk_add_f32 v[96:97], v[98:99], v[88:89]
	v_pk_add_f32 v[88:89], v[98:99], v[88:89] neg_lo:[0,1] neg_hi:[0,1]
	v_pk_add_f32 v[98:99], v[78:79], v[100:101]
	v_pk_add_f32 v[78:79], v[78:79], v[100:101] neg_lo:[0,1] neg_hi:[0,1]
	v_pk_add_f32 v[102:103], v[86:87], v[94:95]
	v_pk_add_f32 v[86:87], v[86:87], v[94:95] neg_lo:[0,1] neg_hi:[0,1]
	v_pk_mul_f32 v[100:101], v[78:79], s[68:69]
	v_pk_mul_f32 v[94:95], v[86:87], s[68:69]
	v_pk_fma_f32 v[78:79], v[78:79], s[64:65], v[100:101] op_sel:[0,0,1] op_sel_hi:[1,0,0]
	v_pk_add_f32 v[100:101], v[80:81], v[92:93]
	v_pk_add_f32 v[92:93], v[80:81], v[92:93] neg_lo:[0,1] neg_hi:[0,1]
	v_pk_fma_f32 v[86:87], v[86:87], s[64:65], v[94:95] op_sel:[0,0,1] op_sel_hi:[1,0,0] neg_lo:[1,0,0] neg_hi:[1,0,0]
	v_pk_add_f32 v[74:75], v[66:67], v[90:91] op_sel:[0,1] op_sel_hi:[1,0] neg_hi:[0,1]
	v_pk_add_f32 v[66:67], v[66:67], v[90:91] op_sel:[0,1] op_sel_hi:[1,0] neg_lo:[0,1]
	v_pk_add_f32 v[90:91], v[68:69], v[76:77]
	v_pk_add_f32 v[68:69], v[68:69], v[76:77] neg_lo:[0,1] neg_hi:[0,1]
	v_pk_add_f32 v[94:95], v[72:73], v[84:85]
	v_pk_add_f32 v[72:73], v[72:73], v[84:85] neg_lo:[0,1] neg_hi:[0,1]
	v_pk_mul_f32 v[76:77], v[68:69], s[68:69]
	v_pk_mul_f32 v[84:85], v[72:73], s[68:69]
	v_pk_fma_f32 v[68:69], v[68:69], s[64:65], v[76:77] op_sel:[0,0,1] op_sel_hi:[1,0,0]
	v_pk_add_f32 v[76:77], v[70:71], v[82:83]
	v_pk_fma_f32 v[72:73], v[72:73], s[64:65], v[84:85] op_sel:[0,0,1] op_sel_hi:[1,0,0] neg_lo:[1,0,0] neg_hi:[1,0,0]
	v_pk_add_f32 v[80:81], v[88:89], v[92:93] op_sel:[0,1] op_sel_hi:[1,0] neg_hi:[0,1]
	v_pk_add_f32 v[88:89], v[88:89], v[92:93] op_sel:[0,1] op_sel_hi:[1,0] neg_lo:[0,1]
	v_pk_add_f32 v[92:93], v[78:79], v[86:87]
	v_pk_add_f32 v[86:87], v[78:79], v[86:87] neg_lo:[0,1] neg_hi:[0,1]
	s_add_i32 s65, s65, s28
	v_pk_add_f32 v[82:83], v[70:71], v[82:83] neg_lo:[0,1] neg_hi:[0,1]
	s_nop 0
	v_pk_add_f32 v[104:105], v[74:75], v[76:77]
	v_pk_add_f32 v[74:75], v[74:75], v[76:77] neg_lo:[0,1] neg_hi:[0,1]
	v_pk_add_f32 v[76:77], v[90:91], v[94:95]
	s_cmpk_gt_i32 s65, 0x3ff
	s_nop 0
	v_pk_add_f32 v[84:85], v[96:97], v[100:101]
	v_pk_add_f32 v[96:97], v[96:97], v[100:101] neg_lo:[0,1] neg_hi:[0,1]
	v_pk_add_f32 v[100:101], v[98:99], v[102:103]
	s_nop 0
	v_pk_add_f32 v[78:79], v[88:89], v[86:87] op_sel:[0,1] op_sel_hi:[1,0] neg_hi:[0,1]
	v_pk_add_f32 v[86:87], v[88:89], v[86:87] op_sel:[0,1] op_sel_hi:[1,0] neg_lo:[0,1]
	v_pk_add_f32 v[88:89], v[104:105], v[76:77]
	s_cselect_b64 s[80:81], -1, 0
	s_cmpk_lt_i32 s65, 0x400
	v_pk_add_f32 v[98:99], v[98:99], v[102:103] neg_lo:[0,1] neg_hi:[0,1]
	v_pk_add_f32 v[70:71], v[66:67], v[82:83] op_sel:[0,1] op_sel_hi:[1,0] neg_hi:[0,1]
	v_pk_add_f32 v[66:67], v[66:67], v[82:83] op_sel:[0,1] op_sel_hi:[1,0] neg_lo:[0,1]
	v_pk_add_f32 v[82:83], v[68:69], v[72:73]
	v_pk_add_f32 v[106:107], v[84:85], v[100:101]
	v_pk_add_f32 v[84:85], v[84:85], v[100:101] neg_lo:[0,1] neg_hi:[0,1]
	v_pk_add_f32 v[100:101], v[80:81], v[92:93]
	v_pk_mul_f32 v[2:3], v[2:3], v[88:89] op_sel:[0,1] op_sel_hi:[1,0]
	s_cselect_b32 s6, s65, s6
	v_xor_b32_e32 v103, 0x80000000, v98
	v_pk_add_f32 v[90:91], v[90:91], v[94:95] neg_lo:[0,1] neg_hi:[0,1]
	v_mov_b32_e32 v102, v99
	v_pk_add_f32 v[80:81], v[80:81], v[92:93] neg_lo:[0,1] neg_hi:[0,1]
	v_pk_add_f32 v[92:93], v[70:71], v[82:83]
	v_pk_fma_f32 v[2:3], v[4:5], v[88:89], v[2:3] op_sel_hi:[0,1,1]
	v_pk_mul_f32 v[4:5], v[6:7], v[100:101] op_sel:[1,1] op_sel_hi:[1,0] neg_lo:[1,0]
	s_lshl_b32 s8, s6, 1
	s_lshl_b32 s6, s6, 2
	v_xor_b32_e32 v95, 0x80000000, v90
	v_pk_add_f32 v[68:69], v[68:69], v[72:73] neg_lo:[0,1] neg_hi:[0,1]
	v_pk_add_f32 v[98:99], v[96:97], v[102:103]
	v_mov_b32_e32 v94, v91
	v_pk_fma_f32 v[4:5], v[6:7], v[100:101], v[4:5] op_sel_hi:[0,1,1]
	v_pk_mul_f32 v[6:7], v[8:9], v[92:93] op_sel:[1,1] op_sel_hi:[1,0] neg_lo:[1,0]
	s_and_b32 s7, s8, 0x3fe
	s_and_b32 s6, s6, 0xfffff800
	v_xor_b32_e32 v73, 0x80000000, v68
	v_pk_add_f32 v[90:91], v[74:75], v[94:95]
	v_mov_b32_e32 v72, v69
	v_pk_fma_f32 v[6:7], v[8:9], v[92:93], v[6:7] op_sel_hi:[0,1,1]
	v_pk_mul_f32 v[8:9], v[10:11], v[98:99] op_sel:[1,1] op_sel_hi:[1,0] neg_lo:[1,0]
	s_or_b32 s6, s7, s6
	v_pk_add_f32 v[68:69], v[66:67], v[72:73]
	v_pk_fma_f32 v[8:9], v[10:11], v[98:99], v[8:9] op_sel_hi:[0,1,1]
	v_pk_mul_f32 v[10:11], v[16:17], v[90:91] op_sel:[1,1] op_sel_hi:[1,0] neg_lo:[1,0]
	s_ashr_i32 s7, s6, 31
	v_pk_add_f32 v[96:97], v[96:97], v[102:103] neg_lo:[0,1] neg_hi:[0,1]
	v_pk_add_f32 v[76:77], v[104:105], v[76:77] neg_lo:[0,1] neg_hi:[0,1]
	v_pk_add_f32 v[74:75], v[74:75], v[94:95] neg_lo:[0,1] neg_hi:[0,1]
	v_pk_add_f32 v[70:71], v[70:71], v[82:83] neg_lo:[0,1] neg_hi:[0,1]
	v_pk_add_f32 v[66:67], v[66:67], v[72:73] neg_lo:[0,1] neg_hi:[0,1]
	v_pk_fma_f32 v[10:11], v[16:17], v[90:91], v[10:11] op_sel_hi:[0,1,1]
	v_pk_mul_f32 v[12:13], v[22:23], v[78:79] op_sel:[1,1] op_sel_hi:[1,0] neg_lo:[1,0]
	v_pk_mul_f32 v[14:15], v[26:27], v[68:69] op_sel:[1,1] op_sel_hi:[1,0] neg_lo:[1,0]
	v_pk_mul_f32 v[16:17], v[30:31], v[84:85] op_sel:[1,1] op_sel_hi:[1,0] neg_lo:[1,0]
	s_lshl_b64 s[82:83], s[6:7], 14
	s_bitset1_b32 s6, 10
	v_pk_fma_f32 v[12:13], v[22:23], v[78:79], v[12:13] op_sel_hi:[0,1,1]
	v_pk_fma_f32 v[14:15], v[26:27], v[68:69], v[14:15] op_sel_hi:[0,1,1]
	v_pk_fma_f32 v[16:17], v[30:31], v[84:85], v[16:17] op_sel_hi:[0,1,1]
	v_pk_mul_f32 v[18:19], v[40:41], v[76:77] op_sel:[0,1] op_sel_hi:[1,0]
	v_pk_mul_f32 v[20:21], v[44:45], v[80:81] op_sel:[0,1] op_sel_hi:[1,0]
	v_pk_mul_f32 v[22:23], v[48:49], v[70:71] op_sel:[0,1] op_sel_hi:[1,0]
	v_pk_mul_f32 v[24:25], v[52:53], v[96:97] op_sel:[0,1] op_sel_hi:[1,0]
	v_pk_mul_f32 v[26:27], v[56:57], v[74:75] op_sel:[0,1] op_sel_hi:[1,0]
	v_pk_mul_f32 v[28:29], v[60:61], v[86:87] op_sel:[0,1] op_sel_hi:[1,0]
	v_pk_mul_f32 v[30:31], v[64:65], v[66:67] op_sel:[0,1] op_sel_hi:[1,0]
	s_ashr_i32 s7, s6, 31
	v_pk_fma_f32 v[18:19], v[38:39], v[76:77], v[18:19] op_sel_hi:[0,1,1]
	v_pk_fma_f32 v[20:21], v[42:43], v[80:81], v[20:21] op_sel_hi:[0,1,1]
	v_pk_fma_f32 v[22:23], v[46:47], v[70:71], v[22:23] op_sel_hi:[0,1,1]
	v_pk_fma_f32 v[24:25], v[50:51], v[96:97], v[24:25] op_sel_hi:[0,1,1]
	v_pk_fma_f32 v[26:27], v[54:55], v[74:75], v[26:27] op_sel_hi:[0,1,1]
	v_pk_fma_f32 v[28:29], v[58:59], v[86:87], v[28:29] op_sel_hi:[0,1,1]
	v_pk_fma_f32 v[30:31], v[62:63], v[66:67], v[30:31] op_sel_hi:[0,1,1]
	ds_write2_b64 v36, v[106:107], v[16:17] offset1:16
	ds_write2_b64 v36, v[8:9], v[24:25] offset0:33 offset1:49
	ds_write2_b64 v36, v[4:5], v[20:21] offset0:66 offset1:82
	ds_write2_b64 v36, v[12:13], v[28:29] offset0:99 offset1:115
	ds_write2_b64 v36, v[2:3], v[18:19] offset0:132 offset1:148
	ds_write2_b64 v36, v[10:11], v[26:27] offset0:165 offset1:181
	ds_write2_b64 v36, v[6:7], v[22:23] offset0:198 offset1:214
	ds_write2_b64 v36, v[14:15], v[30:31] offset0:231 offset1:247
	s_lshl_b64 s[6:7], s[6:7], 14
	v_lshl_add_u64 v[2:3], v[34:35], 0, s[82:83]
	s_waitcnt lgkmcnt(0)
	s_barrier
	global_load_dwordx4 v[10:13], v[2:3], off nt
	global_load_dwordx4 v[30:33], v[2:3], off offset:16 nt
	v_lshl_add_u64 v[2:3], v[34:35], 0, s[6:7]
	global_load_dwordx4 v[26:29], v[2:3], off nt
	global_load_dwordx4 v[22:25], v[2:3], off offset:16 nt
	v_mov_b32_e32 v38, 0
	s_and_saveexec_b64 s[6:7], s[0:1]
	s_cbranch_execz .LBB0_430
	global_load_ushort v38, v[2:3], off offset:32

.LBB0_499:
	v_mov_b32_e32 v2, v210
	s_mov_b32 s43, s8
	v_and_b32_e32 v3, 0x1ff, v2
	v_lshlrev_b32_e32 v2, 5, v2
	v_and_or_b32 v2, v2, s94, v3
	v_ashrrev_i32_e32 v4, 5, v2
	v_lshlrev_b32_e32 v2, 3, v2
	v_lshlrev_b32_e32 v4, 3, v4
	v_add3_u32 v18, 0, v2, v4
	ds_read_b64 v[128:129], v18
	ds_read_b64 v[134:135], v18 offset:4224
	ds_read_b64 v[136:137], v18 offset:8448
	ds_read_b64 v[138:139], v18 offset:12672
	ds_read_b64 v[140:141], v18 offset:16896
	ds_read_b64 v[142:143], v18 offset:21120
	ds_read_b64 v[132:133], v18 offset:25344
	ds_read_b64 v[130:131], v18 offset:29568
	ds_read_b64 v[144:145], v18 offset:33792
	ds_read_b64 v[148:149], v18 offset:38016
	ds_read_b64 v[150:151], v18 offset:42240
	ds_read_b64 v[152:153], v18 offset:46464
	s_waitcnt lgkmcnt(10)
	v_pk_mul_f32 v[162:163], v[134:135], s[10:11]
	s_mov_b32 s74, s11
	v_pk_fma_f32 v[162:163], v[134:135], s[8:9], v[162:163] op_sel:[0,0,1] op_sel_hi:[1,0,0]
	s_waitcnt lgkmcnt(2)
	v_pk_mul_f32 v[178:179], v[148:149], s[42:43]
	v_pk_add_f32 v[194:195], v[134:135], v[148:149]
	v_pk_add_f32 v[134:135], v[134:135], v[148:149] neg_lo:[0,1] neg_hi:[0,1]
	v_pk_mul_f32 v[164:165], v[136:137], s[18:19]
	s_mov_b32 s41, s16
	v_pk_fma_f32 v[178:179], v[148:149], s[74:75], v[178:179] op_sel:[0,0,1] op_sel_hi:[1,0,0] neg_lo:[1,0,0] neg_hi:[1,0,0]
	v_pk_mul_f32 v[148:149], v[134:135], s[18:19]
	v_pk_fma_f32 v[164:165], v[136:137], s[16:17], v[164:165] op_sel:[0,0,1] op_sel_hi:[1,0,0]
	s_mov_b32 s80, s19
	s_waitcnt lgkmcnt(1)
	v_pk_mul_f32 v[180:181], v[150:151], s[40:41]
	v_pk_fma_f32 v[134:135], v[134:135], s[16:17], v[148:149] op_sel:[0,0,1] op_sel_hi:[1,0,0]
	v_pk_add_f32 v[148:149], v[136:137], v[150:151]
	v_pk_add_f32 v[136:137], v[136:137], v[150:151] neg_lo:[0,1] neg_hi:[0,1]
	v_pk_mul_f32 v[166:167], v[138:139], s[26:27]
	s_mov_b32 s78, s37
	s_mov_b32 s39, s24
	v_pk_fma_f32 v[180:181], v[150:151], s[80:81], v[180:181] op_sel:[0,0,1] op_sel_hi:[1,0,0] neg_lo:[1,0,0] neg_hi:[1,0,0]
	v_pk_mul_f32 v[150:151], v[136:137], s[36:37]
	ds_read_b64 v[154:155], v18 offset:50688
	ds_read_b64 v[156:157], v18 offset:54912
	ds_read_b64 v[158:159], v18 offset:59136
	ds_read_b64 v[160:161], v18 offset:63360
	v_pk_fma_f32 v[166:167], v[138:139], s[24:25], v[166:167] op_sel:[0,0,1] op_sel_hi:[1,0,0]
	s_mov_b32 s0, s27
	s_waitcnt lgkmcnt(4)
	v_pk_mul_f32 v[182:183], v[152:153], s[38:39]
	v_pk_fma_f32 v[136:137], v[136:137], s[78:79], v[150:151] op_sel:[0,0,1] op_sel_hi:[1,0,0]
	v_pk_add_f32 v[150:151], v[138:139], v[152:153]
	v_pk_add_f32 v[138:139], v[138:139], v[152:153] neg_lo:[0,1] neg_hi:[0,1]
	v_pk_mul_f32 v[168:169], v[140:141], s[36:37]
	v_pk_fma_f32 v[182:183], v[152:153], s[0:1], v[182:183] op_sel:[0,0,1] op_sel_hi:[1,0,0] neg_lo:[1,0,0] neg_hi:[1,0,0]
	v_pk_mul_f32 v[152:153], v[138:139], s[40:41]
	v_pk_fma_f32 v[168:169], v[140:141], s[78:79], v[168:169] op_sel:[0,0,1] op_sel_hi:[1,0,0]
	v_pk_mul_f32 v[170:171], v[142:143], s[38:39]
	s_waitcnt lgkmcnt(3)
	v_pk_mul_f32 v[184:185], v[154:155], s[36:37]
	v_pk_fma_f32 v[138:139], v[138:139], s[80:81], v[152:153] op_sel:[0,0,1] op_sel_hi:[1,0,0]
	v_pk_add_f32 v[152:153], v[140:141], v[154:155]
	v_pk_add_f32 v[140:141], v[140:141], v[154:155] neg_lo:[0,1] neg_hi:[0,1]
	v_pk_fma_f32 v[170:171], v[142:143], s[0:1], v[170:171] op_sel:[0,0,1] op_sel_hi:[1,0,0]
	v_pk_fma_f32 v[184:185], v[154:155], s[78:79], v[184:185] op_sel:[0,0,1] op_sel_hi:[1,0,0] neg_lo:[1,0,0] neg_hi:[1,0,0]
	s_waitcnt lgkmcnt(2)
	v_pk_mul_f32 v[186:187], v[156:157], s[26:27]
	v_xor_b32_e32 v155, 0x80000000, v140
	v_mov_b32_e32 v154, v141
	v_pk_add_f32 v[140:141], v[142:143], v[156:157]
	v_pk_add_f32 v[142:143], v[142:143], v[156:157] neg_lo:[0,1] neg_hi:[0,1]
	v_pk_mul_f32 v[172:173], v[132:133], s[40:41]
	v_pk_fma_f32 v[186:187], v[156:157], s[24:25], v[186:187] op_sel:[0,0,1] op_sel_hi:[1,0,0] neg_lo:[1,0,0] neg_hi:[1,0,0]
	v_pk_mul_f32 v[156:157], v[142:143], s[40:41]
	v_pk_fma_f32 v[172:173], v[132:133], s[80:81], v[172:173] op_sel:[0,0,1] op_sel_hi:[1,0,0]
	s_waitcnt lgkmcnt(1)
	v_pk_mul_f32 v[188:189], v[158:159], s[18:19]
	v_pk_fma_f32 v[142:143], v[142:143], s[80:81], v[156:157] op_sel:[0,0,1] op_sel_hi:[1,0,0] neg_lo:[1,0,0] neg_hi:[1,0,0]
	v_pk_add_f32 v[156:157], v[132:133], v[158:159]
	v_pk_add_f32 v[132:133], v[132:133], v[158:159] neg_lo:[0,1] neg_hi:[0,1]
	v_pk_mul_f32 v[174:175], v[130:131], s[42:43]
	v_pk_fma_f32 v[188:189], v[158:159], s[16:17], v[188:189] op_sel:[0,0,1] op_sel_hi:[1,0,0] neg_lo:[1,0,0] neg_hi:[1,0,0]
	v_pk_mul_f32 v[158:159], v[132:133], s[36:37]
	v_pk_fma_f32 v[174:175], v[130:131], s[74:75], v[174:175] op_sel:[0,0,1] op_sel_hi:[1,0,0]
	s_waitcnt lgkmcnt(0)
	v_pk_mul_f32 v[190:191], v[160:161], s[10:11]
	v_pk_fma_f32 v[132:133], v[132:133], s[78:79], v[158:159] op_sel:[0,0,1] op_sel_hi:[1,0,0] neg_lo:[1,0,0] neg_hi:[1,0,0]
	v_pk_add_f32 v[158:159], v[130:131], v[160:161]
	v_pk_add_f32 v[130:131], v[130:131], v[160:161] neg_lo:[0,1] neg_hi:[0,1]
	v_xor_b32_e32 v177, 0x80000000, v144
	v_mov_b32_e32 v176, v145
	v_pk_fma_f32 v[190:191], v[160:161], s[8:9], v[190:191] op_sel:[0,0,1] op_sel_hi:[1,0,0] neg_lo:[1,0,0] neg_hi:[1,0,0]
	v_pk_mul_f32 v[160:161], v[130:131], s[18:19]
	v_pk_add_f32 v[192:193], v[128:129], v[144:145]
	v_pk_add_f32 v[144:145], v[128:129], v[144:145] neg_lo:[0,1] neg_hi:[0,1]
	v_pk_fma_f32 v[130:131], v[130:131], s[16:17], v[160:161] op_sel:[0,0,1] op_sel_hi:[1,0,0] neg_lo:[1,0,0] neg_hi:[1,0,0]
	v_pk_add_f32 v[160:161], v[128:129], v[176:177]
	v_pk_add_f32 v[128:129], v[128:129], v[176:177] neg_lo:[0,1] neg_hi:[0,1]
	v_pk_add_f32 v[176:177], v[162:163], v[178:179]
	v_pk_add_f32 v[162:163], v[162:163], v[178:179] neg_lo:[0,1] neg_hi:[0,1]
	v_cvt_f32_u32_e32 v2, v3
	v_pk_mul_f32 v[178:179], v[162:163], s[18:19]
	s_add_i32 s76, s72, s48
	v_pk_fma_f32 v[162:163], v[162:163], s[16:17], v[178:179] op_sel:[0,0,1] op_sel_hi:[1,0,0]
	v_pk_add_f32 v[178:179], v[164:165], v[180:181]
	v_pk_add_f32 v[164:165], v[164:165], v[180:181] neg_lo:[0,1] neg_hi:[0,1]
	v_mul_f32_e32 v2, 0x38800000, v2
	v_pk_mul_f32 v[180:181], v[164:165], s[36:37]
	v_sin_f32_e32 v34, v2
	v_pk_fma_f32 v[164:165], v[164:165], s[78:79], v[180:181] op_sel:[0,0,1] op_sel_hi:[1,0,0]
	v_pk_add_f32 v[180:181], v[166:167], v[182:183]
	v_pk_add_f32 v[166:167], v[166:167], v[182:183] neg_lo:[0,1] neg_hi:[0,1]
	v_cos_f32_e32 v30, v2
	v_pk_mul_f32 v[182:183], v[166:167], s[40:41]
	v_xor_b32_e32 v31, 0x80000000, v34
	v_pk_fma_f32 v[166:167], v[166:167], s[80:81], v[182:183] op_sel:[0,0,1] op_sel_hi:[1,0,0]
	v_pk_add_f32 v[182:183], v[168:169], v[184:185]
	v_pk_add_f32 v[184:185], v[168:169], v[184:185] neg_lo:[0,1] neg_hi:[0,1]
	v_mov_b32_e32 v35, v31
	v_pk_add_f32 v[168:169], v[170:171], v[186:187]
	v_pk_add_f32 v[170:171], v[170:171], v[186:187] neg_lo:[0,1] neg_hi:[0,1]
	v_pk_mul_f32 v[2:3], v[30:31], v[34:35] op_sel:[1,0] op_sel_hi:[0,1]
	v_pk_mul_f32 v[186:187], v[170:171], s[40:41]
	v_pk_fma_f32 v[44:45], v[30:31], v[30:31], v[2:3] op_sel_hi:[1,0,1]
	v_pk_fma_f32 v[170:171], v[170:171], s[80:81], v[186:187] op_sel:[0,0,1] op_sel_hi:[1,0,0] neg_lo:[1,0,0] neg_hi:[1,0,0]
	v_pk_add_f32 v[186:187], v[172:173], v[188:189]
	v_pk_add_f32 v[172:173], v[172:173], v[188:189] neg_lo:[0,1] neg_hi:[0,1]
	v_pk_mul_f32 v[2:3], v[34:35], v[44:45] op_sel:[0,1] op_sel_hi:[1,0]
	v_pk_mul_f32 v[188:189], v[172:173], s[36:37]
	s_nop 0
	v_pk_fma_f32 v[172:173], v[172:173], s[78:79], v[188:189] op_sel:[0,0,1] op_sel_hi:[1,0,0] neg_lo:[1,0,0] neg_hi:[1,0,0]
	v_pk_add_f32 v[188:189], v[174:175], v[190:191]
	v_pk_add_f32 v[174:175], v[174:175], v[190:191] neg_lo:[0,1] neg_hi:[0,1]
	s_nop 0
	v_pk_mul_f32 v[190:191], v[174:175], s[18:19]
	v_pk_fma_f32 v[46:47], v[30:31], v[44:45], v[2:3] op_sel_hi:[0,1,1]
	v_pk_fma_f32 v[174:175], v[174:175], s[16:17], v[190:191] op_sel:[0,0,1] op_sel_hi:[1,0,0] neg_lo:[1,0,0] neg_hi:[1,0,0]
	v_pk_add_f32 v[190:191], v[192:193], v[152:153]
	v_pk_add_f32 v[152:153], v[192:193], v[152:153] neg_lo:[0,1] neg_hi:[0,1]
	v_pk_add_f32 v[192:193], v[194:195], v[140:141]
	v_pk_add_f32 v[140:141], v[194:195], v[140:141] neg_lo:[0,1] neg_hi:[0,1]
	v_pk_mul_f32 v[2:3], v[44:45], v[44:45] op_sel:[1,1] op_sel_hi:[0,1] neg_lo:[0,1]
	v_pk_mul_f32 v[194:195], v[140:141], s[36:37]
	v_pk_fma_f32 v[52:53], v[44:45], v[44:45], v[2:3] op_sel_hi:[1,0,1]
	v_pk_fma_f32 v[140:141], v[140:141], s[78:79], v[194:195] op_sel:[0,0,1] op_sel_hi:[1,0,0]
	v_pk_add_f32 v[194:195], v[148:149], v[156:157]
	v_pk_add_f32 v[156:157], v[148:149], v[156:157] neg_lo:[0,1] neg_hi:[0,1]
	v_pk_add_f32 v[148:149], v[150:151], v[158:159]
	v_pk_add_f32 v[150:151], v[150:151], v[158:159] neg_lo:[0,1] neg_hi:[0,1]
	s_nop 0
	v_pk_mul_f32 v[158:159], v[150:151], s[36:37]
	v_pk_mul_f32 v[2:3], v[52:53], v[52:53] op_sel:[1,1] op_sel_hi:[0,1] neg_lo:[0,1]
	v_pk_fma_f32 v[150:151], v[150:151], s[78:79], v[158:159] op_sel:[0,0,1] op_sel_hi:[1,0,0] neg_lo:[1,0,0] neg_hi:[1,0,0]
	v_pk_add_f32 v[158:159], v[144:145], v[154:155]
	v_pk_add_f32 v[144:145], v[144:145], v[154:155] neg_lo:[0,1] neg_hi:[0,1]
	v_pk_add_f32 v[154:155], v[134:135], v[142:143]
	v_pk_add_f32 v[134:135], v[134:135], v[142:143] neg_lo:[0,1] neg_hi:[0,1]
	v_pk_fma_f32 v[48:49], v[52:53], v[52:53], v[2:3] op_sel_hi:[1,0,1]
	v_pk_mul_f32 v[142:143], v[134:135], s[36:37]
	v_pk_mul_f32 v[2:3], v[52:53], v[48:49] op_sel:[1,1] op_sel_hi:[1,0] neg_lo:[1,0]
	v_pk_fma_f32 v[134:135], v[134:135], s[78:79], v[142:143] op_sel:[0,0,1] op_sel_hi:[1,0,0]
	v_pk_add_f32 v[142:143], v[136:137], v[132:133]
	v_pk_add_f32 v[136:137], v[136:137], v[132:133] neg_lo:[0,1] neg_hi:[0,1]
	v_pk_fma_f32 v[36:37], v[52:53], v[48:49], v[2:3] op_sel_hi:[0,1,1]
	v_pk_add_f32 v[132:133], v[138:139], v[130:131]
	v_pk_add_f32 v[130:131], v[138:139], v[130:131] neg_lo:[0,1] neg_hi:[0,1]
	v_pk_mul_f32 v[2:3], v[52:53], v[36:37] op_sel:[1,1] op_sel_hi:[1,0] neg_lo:[1,0]
	v_pk_mul_f32 v[138:139], v[130:131], s[36:37]
	v_pk_fma_f32 v[26:27], v[52:53], v[36:37], v[2:3] op_sel_hi:[0,1,1]
	v_pk_fma_f32 v[130:131], v[130:131], s[78:79], v[138:139] op_sel:[0,0,1] op_sel_hi:[1,0,0] neg_lo:[1,0,0] neg_hi:[1,0,0]
	v_pk_add_f32 v[138:139], v[160:161], v[182:183]
	v_pk_add_f32 v[160:161], v[160:161], v[182:183] neg_lo:[0,1] neg_hi:[0,1]
	v_pk_add_f32 v[182:183], v[176:177], v[168:169]
	v_pk_add_f32 v[168:169], v[176:177], v[168:169] neg_lo:[0,1] neg_hi:[0,1]
	v_pk_mul_f32 v[2:3], v[52:53], v[26:27] op_sel:[1,1] op_sel_hi:[1,0] neg_lo:[1,0]
	v_pk_mul_f32 v[176:177], v[168:169], s[36:37]
	v_pk_fma_f32 v[20:21], v[52:53], v[26:27], v[2:3] op_sel_hi:[0,1,1]
	v_pk_fma_f32 v[168:169], v[168:169], s[78:79], v[176:177] op_sel:[0,0,1] op_sel_hi:[1,0,0]
	v_pk_add_f32 v[176:177], v[178:179], v[186:187]
	v_pk_add_f32 v[186:187], v[178:179], v[186:187] neg_lo:[0,1] neg_hi:[0,1]
	v_pk_mul_f32 v[2:3], v[52:53], v[20:21] op_sel:[1,1] op_sel_hi:[1,0] neg_lo:[1,0]
	v_pk_add_f32 v[178:179], v[180:181], v[188:189]
	v_pk_add_f32 v[180:181], v[180:181], v[188:189] neg_lo:[0,1] neg_hi:[0,1]
	v_pk_fma_f32 v[10:11], v[52:53], v[20:21], v[2:3] op_sel_hi:[0,1,1]
	v_pk_mul_f32 v[188:189], v[180:181], s[36:37]
	v_pk_mul_f32 v[2:3], v[52:53], v[10:11] op_sel:[1,1] op_sel_hi:[1,0] neg_lo:[1,0]
	v_pk_fma_f32 v[180:181], v[180:181], s[78:79], v[188:189] op_sel:[0,0,1] op_sel_hi:[1,0,0] neg_lo:[1,0,0] neg_hi:[1,0,0]
	v_pk_add_f32 v[188:189], v[128:129], v[184:185] op_sel:[0,1] op_sel_hi:[1,0] neg_hi:[0,1]
	v_pk_add_f32 v[128:129], v[128:129], v[184:185] op_sel:[0,1] op_sel_hi:[1,0] neg_lo:[0,1]
	v_pk_add_f32 v[184:185], v[162:163], v[170:171]
	v_pk_add_f32 v[162:163], v[162:163], v[170:171] neg_lo:[0,1] neg_hi:[0,1]
	v_pk_fma_f32 v[4:5], v[52:53], v[10:11], v[2:3] op_sel_hi:[0,1,1]
	v_pk_mul_f32 v[170:171], v[162:163], s[36:37]
	v_pk_mul_f32 v[8:9], v[44:45], v[4:5] op_sel:[1,1] op_sel_hi:[1,0] neg_lo:[1,0]
	v_pk_fma_f32 v[162:163], v[162:163], s[78:79], v[170:171] op_sel:[0,0,1] op_sel_hi:[1,0,0]
	v_pk_add_f32 v[170:171], v[164:165], v[172:173]
	v_pk_add_f32 v[172:173], v[164:165], v[172:173] neg_lo:[0,1] neg_hi:[0,1]
	v_pk_mul_f32 v[14:15], v[34:35], v[4:5] op_sel:[0,1] op_sel_hi:[1,0]
	v_pk_add_f32 v[164:165], v[166:167], v[174:175]
	v_pk_add_f32 v[166:167], v[166:167], v[174:175] neg_lo:[0,1] neg_hi:[0,1]
	v_pk_mul_f32 v[32:33], v[44:45], v[10:11] op_sel:[1,1] op_sel_hi:[1,0] neg_lo:[1,0]
	v_pk_mul_f32 v[174:175], v[166:167], s[36:37]
	v_pk_mul_f32 v[40:41], v[34:35], v[10:11] op_sel:[0,1] op_sel_hi:[1,0]
	v_pk_fma_f32 v[166:167], v[166:167], s[78:79], v[174:175] op_sel:[0,0,1] op_sel_hi:[1,0,0] neg_lo:[1,0,0] neg_hi:[1,0,0]
	v_pk_add_f32 v[174:175], v[190:191], v[194:195]
	v_pk_add_f32 v[190:191], v[190:191], v[194:195] neg_lo:[0,1] neg_hi:[0,1]
	v_pk_add_f32 v[194:195], v[192:193], v[148:149]
	v_pk_add_f32 v[192:193], v[192:193], v[148:149] neg_lo:[0,1] neg_hi:[0,1]
	v_pk_mul_f32 v[62:63], v[44:45], v[20:21] op_sel:[1,1] op_sel_hi:[1,0] neg_lo:[1,0]
	v_pk_add_f32 v[148:149], v[152:153], v[156:157] op_sel:[0,1] op_sel_hi:[1,0] neg_hi:[0,1]
	v_pk_add_f32 v[152:153], v[152:153], v[156:157] op_sel:[0,1] op_sel_hi:[1,0] neg_lo:[0,1]
	v_pk_add_f32 v[156:157], v[140:141], v[150:151]
	v_pk_add_f32 v[150:151], v[140:141], v[150:151] neg_lo:[0,1] neg_hi:[0,1]
	v_pk_mul_f32 v[66:67], v[34:35], v[20:21] op_sel:[0,1] op_sel_hi:[1,0]
	v_pk_add_f32 v[140:141], v[158:159], v[142:143]
	v_pk_add_f32 v[142:143], v[158:159], v[142:143] neg_lo:[0,1] neg_hi:[0,1]
	v_pk_add_f32 v[158:159], v[154:155], v[132:133]
	v_pk_add_f32 v[154:155], v[154:155], v[132:133] neg_lo:[0,1] neg_hi:[0,1]
	v_pk_mul_f32 v[78:79], v[44:45], v[26:27] op_sel:[1,1] op_sel_hi:[1,0] neg_lo:[1,0]
	v_pk_add_f32 v[132:133], v[144:145], v[136:137] op_sel:[0,1] op_sel_hi:[1,0] neg_hi:[0,1]
	v_pk_add_f32 v[136:137], v[144:145], v[136:137] op_sel:[0,1] op_sel_hi:[1,0] neg_lo:[0,1]
	v_pk_add_f32 v[144:145], v[134:135], v[130:131]
	v_pk_add_f32 v[134:135], v[134:135], v[130:131] neg_lo:[0,1] neg_hi:[0,1]
	v_pk_mul_f32 v[82:83], v[34:35], v[26:27] op_sel:[0,1] op_sel_hi:[1,0]
	v_pk_add_f32 v[130:131], v[138:139], v[176:177]
	v_pk_add_f32 v[138:139], v[138:139], v[176:177] neg_lo:[0,1] neg_hi:[0,1]
	v_pk_add_f32 v[176:177], v[182:183], v[178:179]
	v_pk_add_f32 v[182:183], v[182:183], v[178:179] neg_lo:[0,1] neg_hi:[0,1]
	v_pk_mul_f32 v[92:93], v[44:45], v[36:37] op_sel:[1,1] op_sel_hi:[1,0] neg_lo:[1,0]
	v_pk_add_f32 v[178:179], v[160:161], v[186:187] op_sel:[0,1] op_sel_hi:[1,0] neg_hi:[0,1]
	v_pk_add_f32 v[160:161], v[160:161], v[186:187] op_sel:[0,1] op_sel_hi:[1,0] neg_lo:[0,1]
	v_pk_add_f32 v[186:187], v[168:169], v[180:181]
	v_pk_add_f32 v[180:181], v[168:169], v[180:181] neg_lo:[0,1] neg_hi:[0,1]
	v_pk_mul_f32 v[96:97], v[34:35], v[36:37] op_sel:[0,1] op_sel_hi:[1,0]
	v_pk_add_f32 v[168:169], v[188:189], v[170:171]
	v_pk_add_f32 v[170:171], v[188:189], v[170:171] neg_lo:[0,1] neg_hi:[0,1]
	v_pk_add_f32 v[188:189], v[184:185], v[164:165]
	v_pk_add_f32 v[184:185], v[184:185], v[164:165] neg_lo:[0,1] neg_hi:[0,1]
	v_pk_mul_f32 v[106:107], v[44:45], v[48:49] op_sel:[1,1] op_sel_hi:[1,0] neg_lo:[1,0]
	v_pk_add_f32 v[164:165], v[128:129], v[172:173] op_sel:[0,1] op_sel_hi:[1,0] neg_hi:[0,1]
	v_pk_add_f32 v[128:129], v[128:129], v[172:173] op_sel:[0,1] op_sel_hi:[1,0] neg_lo:[0,1]
	v_pk_add_f32 v[172:173], v[162:163], v[166:167]
	v_pk_add_f32 v[166:167], v[162:163], v[166:167] neg_lo:[0,1] neg_hi:[0,1]
	v_pk_mul_f32 v[110:111], v[34:35], v[48:49] op_sel:[0,1] op_sel_hi:[1,0]
	v_pk_add_f32 v[162:163], v[174:175], v[194:195]
	v_pk_add_f32 v[174:175], v[174:175], v[194:195] neg_lo:[0,1] neg_hi:[0,1]
	v_pk_add_f32 v[194:195], v[190:191], v[192:193] op_sel:[0,1] op_sel_hi:[1,0] neg_hi:[0,1]
	v_pk_add_f32 v[190:191], v[190:191], v[192:193] op_sel:[0,1] op_sel_hi:[1,0] neg_lo:[0,1]
	v_pk_add_f32 v[192:193], v[148:149], v[156:157]
	v_pk_add_f32 v[148:149], v[148:149], v[156:157] neg_lo:[0,1] neg_hi:[0,1]
	v_pk_add_f32 v[156:157], v[152:153], v[150:151] op_sel:[0,1] op_sel_hi:[1,0] neg_hi:[0,1]
	v_pk_add_f32 v[150:151], v[152:153], v[150:151] op_sel:[0,1] op_sel_hi:[1,0] neg_lo:[0,1]
	v_pk_add_f32 v[152:153], v[140:141], v[158:159]
	v_pk_add_f32 v[140:141], v[140:141], v[158:159] neg_lo:[0,1] neg_hi:[0,1]
	v_pk_add_f32 v[158:159], v[142:143], v[154:155] op_sel:[0,1] op_sel_hi:[1,0] neg_hi:[0,1]
	v_pk_add_f32 v[142:143], v[142:143], v[154:155] op_sel:[0,1] op_sel_hi:[1,0] neg_lo:[0,1]
	v_pk_add_f32 v[154:155], v[132:133], v[144:145]
	v_pk_add_f32 v[132:133], v[132:133], v[144:145] neg_lo:[0,1] neg_hi:[0,1]
	v_pk_add_f32 v[144:145], v[136:137], v[134:135] op_sel:[0,1] op_sel_hi:[1,0] neg_hi:[0,1]
	v_pk_add_f32 v[134:135], v[136:137], v[134:135] op_sel:[0,1] op_sel_hi:[1,0] neg_lo:[0,1]
	v_pk_add_f32 v[136:137], v[130:131], v[176:177]
	v_pk_mul_f32 v[120:121], v[44:45], v[52:53] op_sel:[1,1] op_sel_hi:[1,0] neg_lo:[1,0]
	v_pk_mul_f32 v[124:125], v[34:35], v[52:53] op_sel:[0,1] op_sel_hi:[1,0]
	v_pk_mul_f32 v[34:35], v[34:35], v[136:137] op_sel:[0,1] op_sel_hi:[1,0]
	v_pk_fma_f32 v[8:9], v[44:45], v[4:5], v[8:9] op_sel_hi:[0,1,1]
	v_pk_fma_f32 v[14:15], v[30:31], v[4:5], v[14:15] op_sel_hi:[0,1,1]
	v_xor_b32_e32 v22, 0x80000000, v5
	v_pk_fma_f32 v[32:33], v[44:45], v[10:11], v[32:33] op_sel_hi:[0,1,1]
	v_pk_fma_f32 v[40:41], v[30:31], v[10:11], v[40:41] op_sel_hi:[0,1,1]
	v_pk_fma_f32 v[62:63], v[44:45], v[20:21], v[62:63] op_sel_hi:[0,1,1]
	v_pk_fma_f32 v[66:67], v[30:31], v[20:21], v[66:67] op_sel_hi:[0,1,1]
	v_pk_fma_f32 v[78:79], v[44:45], v[26:27], v[78:79] op_sel_hi:[0,1,1]
	v_pk_fma_f32 v[82:83], v[30:31], v[26:27], v[82:83] op_sel_hi:[0,1,1]
	v_pk_fma_f32 v[92:93], v[44:45], v[36:37], v[92:93] op_sel_hi:[0,1,1]
	v_pk_fma_f32 v[96:97], v[30:31], v[36:37], v[96:97] op_sel_hi:[0,1,1]
	v_pk_fma_f32 v[106:107], v[44:45], v[48:49], v[106:107] op_sel_hi:[0,1,1]
	v_pk_fma_f32 v[110:111], v[30:31], v[48:49], v[110:111] op_sel_hi:[0,1,1]
	v_pk_fma_f32 v[120:121], v[44:45], v[52:53], v[120:121] op_sel_hi:[0,1,1]
	v_pk_fma_f32 v[124:125], v[30:31], v[52:53], v[124:125] op_sel_hi:[0,1,1]
	v_mov_b32_e32 v23, v5
	v_pk_add_f32 v[130:131], v[130:131], v[176:177] neg_lo:[0,1] neg_hi:[0,1]
	v_pk_add_f32 v[176:177], v[138:139], v[182:183] op_sel:[0,1] op_sel_hi:[1,0] neg_hi:[0,1]
	v_pk_add_f32 v[138:139], v[138:139], v[182:183] op_sel:[0,1] op_sel_hi:[1,0] neg_lo:[0,1]
	v_pk_add_f32 v[182:183], v[178:179], v[186:187]
	v_pk_add_f32 v[178:179], v[178:179], v[186:187] neg_lo:[0,1] neg_hi:[0,1]
	v_pk_add_f32 v[186:187], v[160:161], v[180:181] op_sel:[0,1] op_sel_hi:[1,0] neg_hi:[0,1]
	v_pk_add_f32 v[160:161], v[160:161], v[180:181] op_sel:[0,1] op_sel_hi:[1,0] neg_lo:[0,1]
	v_pk_add_f32 v[180:181], v[168:169], v[188:189]
	v_pk_fma_f32 v[30:31], v[30:31], v[136:137], v[34:35] op_sel_hi:[0,1,1]
	v_pk_mul_f32 v[34:35], v[44:45], v[152:153] op_sel:[1,1] op_sel_hi:[1,0] neg_lo:[1,0]
	v_pk_mul_f32 v[2:3], v[46:47], v[4:5] op_sel:[1,1] op_sel_hi:[1,0] neg_lo:[1,0]
	v_xor_b32_e32 v12, 0x80000000, v9
	v_pk_mul_f32 v[24:25], v[46:47], v[10:11] op_sel:[1,1] op_sel_hi:[1,0] neg_lo:[1,0]
	v_xor_b32_e32 v38, 0x80000000, v33
	v_xor_b32_e32 v50, 0x80000000, v11
	v_pk_mul_f32 v[56:57], v[46:47], v[20:21] op_sel:[1,1] op_sel_hi:[1,0] neg_lo:[1,0]
	v_xor_b32_e32 v64, 0x80000000, v63
	v_xor_b32_e32 v70, 0x80000000, v21
	v_pk_mul_f32 v[74:75], v[46:47], v[26:27] op_sel:[1,1] op_sel_hi:[1,0] neg_lo:[1,0]
	v_xor_b32_e32 v80, 0x80000000, v79
	v_xor_b32_e32 v86, 0x80000000, v27
	v_pk_mul_f32 v[88:89], v[46:47], v[36:37] op_sel:[1,1] op_sel_hi:[1,0] neg_lo:[1,0]
	v_xor_b32_e32 v94, 0x80000000, v93
	v_xor_b32_e32 v100, 0x80000000, v37
	v_pk_mul_f32 v[102:103], v[46:47], v[48:49] op_sel:[1,1] op_sel_hi:[1,0] neg_lo:[1,0]
	v_pk_mul_f32 v[116:117], v[52:53], v[46:47] op_sel:[1,1] op_sel_hi:[0,1] neg_lo:[0,1]
	v_mov_b32_e32 v101, v37
	v_mov_b32_e32 v95, v93
	v_mov_b32_e32 v87, v27
	v_mov_b32_e32 v81, v79
	v_mov_b32_e32 v71, v21
	v_mov_b32_e32 v65, v63
	v_mov_b32_e32 v51, v11
	v_mov_b32_e32 v39, v33
	v_mov_b32_e32 v13, v9
	v_pk_fma_f32 v[34:35], v[44:45], v[152:153], v[34:35] op_sel_hi:[0,1,1]
	v_pk_mul_f32 v[44:45], v[46:47], v[180:181] op_sel:[1,1] op_sel_hi:[1,0] neg_lo:[1,0]
	v_pk_mul_f32 v[22:23], v[150:151], v[22:23] op_sel:[1,0] op_sel_hi:[0,1]
	v_pk_fma_f32 v[2:3], v[46:47], v[4:5], v[2:3] op_sel_hi:[0,1,1]
	v_pk_fma_f32 v[24:25], v[46:47], v[10:11], v[24:25] op_sel_hi:[0,1,1]
	v_pk_fma_f32 v[56:57], v[46:47], v[20:21], v[56:57] op_sel_hi:[0,1,1]
	v_pk_fma_f32 v[74:75], v[46:47], v[26:27], v[74:75] op_sel_hi:[0,1,1]
	v_pk_fma_f32 v[88:89], v[46:47], v[36:37], v[88:89] op_sel_hi:[0,1,1]
	v_pk_fma_f32 v[102:103], v[46:47], v[48:49], v[102:103] op_sel_hi:[0,1,1]
	v_pk_fma_f32 v[116:117], v[52:53], v[46:47], v[116:117] op_sel_hi:[1,0,1]
	v_pk_fma_f32 v[44:45], v[46:47], v[180:181], v[44:45] op_sel_hi:[0,1,1]
	v_pk_mul_f32 v[46:47], v[52:53], v[192:193] op_sel:[1,1] op_sel_hi:[1,0] neg_lo:[1,0]
	v_pk_mul_f32 v[54:55], v[120:121], v[154:155] op_sel:[1,1] op_sel_hi:[1,0] neg_lo:[1,0]
	v_pk_mul_f32 v[72:73], v[48:49], v[194:195] op_sel:[1,1] op_sel_hi:[1,0] neg_lo:[1,0]
	v_pk_mul_f32 v[108:109], v[106:107], v[158:159] op_sel:[1,1] op_sel_hi:[1,0] neg_lo:[1,0]
	v_pk_mul_f32 v[100:101], v[100:101], v[156:157] op_sel:[0,1] op_sel_hi:[1,0]
	v_pk_mul_f32 v[94:95], v[94:95], v[144:145] op_sel:[0,1] op_sel_hi:[1,0]
	v_pk_mul_f32 v[86:87], v[174:175], v[86:87] op_sel:[1,0] op_sel_hi:[0,1]
	v_pk_mul_f32 v[80:81], v[140:141], v[80:81] op_sel:[1,0] op_sel_hi:[0,1]
	v_pk_mul_f32 v[70:71], v[148:149], v[70:71] op_sel:[1,0] op_sel_hi:[0,1]
	v_pk_mul_f32 v[64:65], v[132:133], v[64:65] op_sel:[1,0] op_sel_hi:[0,1]
	v_pk_mul_f32 v[50:51], v[190:191], v[50:51] op_sel:[1,0] op_sel_hi:[0,1]
	v_pk_mul_f32 v[38:39], v[142:143], v[38:39] op_sel:[1,0] op_sel_hi:[0,1]
	v_pk_fma_f32 v[4:5], v[150:151], v[4:5], v[22:23] op_sel_hi:[1,0,1]
	v_pk_mul_f32 v[12:13], v[134:135], v[12:13] op_sel:[1,0] op_sel_hi:[0,1]
	v_pk_fma_f32 v[46:47], v[52:53], v[192:193], v[46:47] op_sel_hi:[0,1,1]
	v_pk_fma_f32 v[54:55], v[120:121], v[154:155], v[54:55] op_sel_hi:[0,1,1]
	v_pk_fma_f32 v[48:49], v[48:49], v[194:195], v[72:73] op_sel_hi:[0,1,1]
	v_pk_fma_f32 v[106:107], v[106:107], v[158:159], v[108:109] op_sel_hi:[0,1,1]
	v_pk_fma_f32 v[36:37], v[36:37], v[156:157], v[100:101] op_sel_hi:[0,1,1]
	v_pk_fma_f32 v[92:93], v[92:93], v[144:145], v[94:95] op_sel_hi:[0,1,1]
	v_pk_fma_f32 v[26:27], v[174:175], v[26:27], v[86:87] op_sel_hi:[1,0,1]
	v_pk_mul_f32 v[84:85], v[130:131], v[82:83] op_sel:[1,1] op_sel_hi:[0,1] neg_lo:[0,1]
	v_pk_fma_f32 v[78:79], v[140:141], v[78:79], v[80:81] op_sel_hi:[1,0,1]
	v_pk_fma_f32 v[20:21], v[148:149], v[20:21], v[70:71] op_sel_hi:[1,0,1]
	v_pk_fma_f32 v[62:63], v[132:133], v[62:63], v[64:65] op_sel_hi:[1,0,1]
	v_pk_fma_f32 v[10:11], v[190:191], v[10:11], v[50:51] op_sel_hi:[1,0,1]
	v_pk_fma_f32 v[32:33], v[142:143], v[32:33], v[38:39] op_sel_hi:[1,0,1]
	v_pk_fma_f32 v[8:9], v[134:135], v[8:9], v[12:13] op_sel_hi:[1,0,1]
	ds_write_b64 v18, v[162:163]
	ds_write_b64 v18, v[26:27] offset:4224
	ds_write_b64 v18, v[48:49] offset:8448
	ds_write_b64 v18, v[10:11] offset:12672
	ds_write_b64 v18, v[46:47] offset:16896
	ds_write_b64 v18, v[20:21] offset:21120
	ds_write_b64 v18, v[36:37] offset:25344
	ds_write_b64 v18, v[4:5] offset:29568
	ds_write_b64 v18, v[34:35] offset:33792
	ds_write_b64 v18, v[78:79] offset:38016
	ds_write_b64 v18, v[106:107] offset:42240
	ds_write_b64 v18, v[32:33] offset:46464
	ds_write_b64 v18, v[54:55] offset:50688
	ds_write_b64 v18, v[62:63] offset:54912
	ds_write_b64 v18, v[92:93] offset:59136
	ds_write_b64 v18, v[8:9] offset:63360
	v_add_u32_e32 v4, 0x10800, v18
	v_pk_mul_f32 v[72:73], v[110:111], v[176:177] op_sel:[1,1] op_sel_hi:[1,0] neg_lo:[1,0]
	v_pk_fma_f32 v[82:83], v[130:131], v[82:83], v[84:85] op_sel_hi:[1,0,1]
	ds_write_b64 v4, v[30:31]
	v_add_u32_e32 v4, 0x11880, v18
	v_pk_fma_f32 v[72:73], v[110:111], v[176:177], v[72:73] op_sel_hi:[0,1,1]
	v_pk_mul_f32 v[42:43], v[138:139], v[40:41] op_sel:[1,1] op_sel_hi:[0,1] neg_lo:[0,1]
	ds_write_b64 v4, v[82:83]
	v_add_u32_e32 v4, 0x12900, v18
	v_pk_mul_f32 v[52:53], v[124:125], v[182:183] op_sel:[1,1] op_sel_hi:[1,0] neg_lo:[1,0]
	v_pk_fma_f32 v[40:41], v[138:139], v[40:41], v[42:43] op_sel_hi:[1,0,1]
	ds_write_b64 v4, v[72:73]
	v_add_u32_e32 v4, 0x13980, v18
	v_pk_fma_f32 v[52:53], v[124:125], v[182:183], v[52:53] op_sel_hi:[0,1,1]
	v_pk_mul_f32 v[68:69], v[178:179], v[66:67] op_sel:[1,1] op_sel_hi:[0,1] neg_lo:[0,1]
	ds_write_b64 v4, v[40:41]
	v_add_u32_e32 v4, 0x14a00, v18
	v_pk_mul_f32 v[98:99], v[96:97], v[186:187] op_sel:[1,1] op_sel_hi:[1,0] neg_lo:[1,0]
	v_pk_fma_f32 v[66:67], v[178:179], v[66:67], v[68:69] op_sel_hi:[1,0,1]
	ds_write_b64 v4, v[52:53]
	v_add_u32_e32 v4, 0x15a80, v18
	v_pk_fma_f32 v[96:97], v[96:97], v[186:187], v[98:99] op_sel_hi:[0,1,1]
	v_pk_mul_f32 v[16:17], v[160:161], v[14:15] op_sel:[1,1] op_sel_hi:[0,1] neg_lo:[0,1]
	ds_write_b64 v4, v[66:67]
	v_add_u32_e32 v4, 0x16b00, v18
	v_pk_add_f32 v[168:169], v[168:169], v[188:189] neg_lo:[0,1] neg_hi:[0,1]
	v_pk_fma_f32 v[14:15], v[160:161], v[14:15], v[16:17] op_sel_hi:[1,0,1]
	ds_write_b64 v4, v[96:97]
	v_add_u32_e32 v4, 0x17b80, v18
	v_pk_add_f32 v[188:189], v[170:171], v[184:185] op_sel:[0,1] op_sel_hi:[1,0] neg_hi:[0,1]
	v_pk_mul_f32 v[76:77], v[168:169], v[74:75] op_sel:[1,1] op_sel_hi:[0,1] neg_lo:[0,1]
	ds_write_b64 v4, v[14:15]
	v_add_u32_e32 v4, 0x18c00, v18
	v_pk_add_f32 v[170:171], v[170:171], v[184:185] op_sel:[0,1] op_sel_hi:[1,0] neg_lo:[0,1]
	v_pk_mul_f32 v[104:105], v[102:103], v[188:189] op_sel:[1,1] op_sel_hi:[1,0] neg_lo:[1,0]
	v_pk_fma_f32 v[74:75], v[168:169], v[74:75], v[76:77] op_sel_hi:[1,0,1]
	ds_write_b64 v4, v[44:45]
	v_add_u32_e32 v4, 0x19c80, v18
	v_pk_add_f32 v[184:185], v[164:165], v[172:173]
	v_pk_fma_f32 v[102:103], v[102:103], v[188:189], v[104:105] op_sel_hi:[0,1,1]
	v_pk_mul_f32 v[28:29], v[170:171], v[24:25] op_sel:[1,1] op_sel_hi:[0,1] neg_lo:[0,1]
	ds_write_b64 v4, v[74:75]
	v_add_u32_e32 v4, 0x1ad00, v18
	v_pk_add_f32 v[164:165], v[164:165], v[172:173] neg_lo:[0,1] neg_hi:[0,1]
	v_pk_mul_f32 v[58:59], v[116:117], v[184:185] op_sel:[1,1] op_sel_hi:[1,0] neg_lo:[1,0]
	v_pk_fma_f32 v[24:25], v[170:171], v[24:25], v[28:29] op_sel_hi:[1,0,1]
	ds_write_b64 v4, v[102:103]
	v_add_u32_e32 v4, 0x1bd80, v18
	v_pk_add_f32 v[172:173], v[128:129], v[166:167] op_sel:[0,1] op_sel_hi:[1,0] neg_hi:[0,1]
	v_pk_fma_f32 v[58:59], v[116:117], v[184:185], v[58:59] op_sel_hi:[0,1,1]
	v_pk_mul_f32 v[60:61], v[164:165], v[56:57] op_sel:[1,1] op_sel_hi:[0,1] neg_lo:[0,1]
	ds_write_b64 v4, v[24:25]
	v_add_u32_e32 v4, 0x1ce00, v18
	v_pk_add_f32 v[128:129], v[128:129], v[166:167] op_sel:[0,1] op_sel_hi:[1,0] neg_lo:[0,1]
	v_pk_mul_f32 v[90:91], v[88:89], v[172:173] op_sel:[1,1] op_sel_hi:[1,0] neg_lo:[1,0]
	v_pk_fma_f32 v[56:57], v[164:165], v[56:57], v[60:61] op_sel_hi:[1,0,1]
	ds_write_b64 v4, v[58:59]
	v_add_u32_e32 v4, 0x1de80, v18
	v_pk_fma_f32 v[88:89], v[88:89], v[172:173], v[90:91] op_sel_hi:[0,1,1]
	v_pk_mul_f32 v[6:7], v[128:129], v[2:3] op_sel:[1,1] op_sel_hi:[0,1] neg_lo:[0,1]
	ds_write_b64 v4, v[56:57]
	v_add_u32_e32 v4, 0x1ef00, v18
	v_pk_fma_f32 v[2:3], v[128:129], v[2:3], v[6:7] op_sel_hi:[1,0,1]
	ds_write_b64 v4, v[88:89]
	v_add_u32_e32 v4, 0x1ff80, v18
	ds_write_b64 v4, v[2:3]
	v_mov_b32_e32 v2, v210
	s_waitcnt lgkmcnt(0)
	s_barrier
	s_ashr_i32 s77, s76, 31
	v_and_b32_e32 v3, 15, v2
	v_lshlrev_b32_e32 v2, 5, v2
	v_and_b32_e32 v4, 0xfffffe00, v2
	v_lshl_add_u32 v5, v4, 3, 0
	v_lshlrev_b32_e32 v6, 3, v3
	v_ashrrev_i32_e32 v7, 2, v4
	v_add3_u32 v18, v5, v6, v7
	v_add_u32_e32 v196, 0x800, v18
	ds_read2_b64 v[128:131], v18 offset1:16
	ds_read2_b64 v[132:135], v18 offset0:33 offset1:49
	ds_read2_b64 v[136:139], v18 offset0:66 offset1:82
	ds_read2_b64 v[140:143], v18 offset0:99 offset1:115
	ds_read2_b64 v[148:151], v18 offset0:132 offset1:148
	ds_read2_b64 v[152:155], v18 offset0:165 offset1:181
	ds_read2_b64 v[156:159], v18 offset0:198 offset1:214
	ds_read2_b64 v[160:163], v18 offset0:231 offset1:247
	ds_read2_b64 v[164:167], v196 offset0:8 offset1:24
	ds_read2_b64 v[168:171], v196 offset0:41 offset1:57
	ds_read2_b64 v[172:175], v196 offset0:74 offset1:90
	ds_read2_b64 v[176:179], v196 offset0:107 offset1:123
	ds_read2_b64 v[180:183], v196 offset0:140 offset1:156
	ds_read2_b64 v[184:187], v196 offset0:173 offset1:189
	ds_read2_b64 v[188:191], v196 offset0:206 offset1:222
	ds_read2_b64 v[192:195], v196 offset0:239 offset1:255
	s_waitcnt lgkmcnt(7)
	v_pk_add_f32 v[144:145], v[128:129], v[164:165]
	v_pk_add_f32 v[128:129], v[128:129], v[164:165] neg_lo:[0,1] neg_hi:[0,1]
	v_pk_add_f32 v[164:165], v[130:131], v[166:167]
	v_pk_add_f32 v[130:131], v[130:131], v[166:167] neg_lo:[0,1] neg_hi:[0,1]
	v_cvt_f32_ubyte0_e32 v2, v3
	v_pk_mul_f32 v[166:167], v[130:131], s[10:11]
	v_mul_f32_e32 v3, 0x3b000000, v2
	v_pk_fma_f32 v[130:131], v[130:131], s[8:9], v[166:167] op_sel:[0,0,1] op_sel_hi:[1,0,0]
	s_waitcnt lgkmcnt(6)
	v_pk_add_f32 v[166:167], v[132:133], v[168:169]
	v_pk_add_f32 v[132:133], v[132:133], v[168:169] neg_lo:[0,1] neg_hi:[0,1]
	v_sin_f32_e32 v2, v3
	v_pk_mul_f32 v[168:169], v[132:133], s[18:19]
	v_cos_f32_e32 v4, v3
	v_pk_fma_f32 v[132:133], v[132:133], s[16:17], v[168:169] op_sel:[0,0,1] op_sel_hi:[1,0,0]
	v_pk_add_f32 v[168:169], v[134:135], v[170:171]
	v_pk_add_f32 v[134:135], v[134:135], v[170:171] neg_lo:[0,1] neg_hi:[0,1]
	v_xor_b32_e32 v5, 0x80000000, v2
	v_pk_mul_f32 v[170:171], v[134:135], s[26:27]
	v_mov_b32_e32 v3, v5
	v_pk_fma_f32 v[134:135], v[134:135], s[24:25], v[170:171] op_sel:[0,0,1] op_sel_hi:[1,0,0]
	s_waitcnt lgkmcnt(5)
	v_pk_add_f32 v[170:171], v[136:137], v[172:173]
	v_pk_add_f32 v[136:137], v[136:137], v[172:173] neg_lo:[0,1] neg_hi:[0,1]
	v_pk_mul_f32 v[6:7], v[4:5], v[2:3] op_sel:[1,0] op_sel_hi:[0,1]
	v_pk_mul_f32 v[172:173], v[136:137], s[36:37]
	v_pk_fma_f32 v[6:7], v[4:5], v[4:5], v[6:7] op_sel_hi:[1,0,1]
	v_pk_fma_f32 v[136:137], v[136:137], s[78:79], v[172:173] op_sel:[0,0,1] op_sel_hi:[1,0,0]
	v_pk_add_f32 v[172:173], v[138:139], v[174:175]
	v_pk_add_f32 v[138:139], v[138:139], v[174:175] neg_lo:[0,1] neg_hi:[0,1]
	s_nop 0
	v_pk_mul_f32 v[174:175], v[138:139], s[38:39]
	s_nop 0
	v_pk_fma_f32 v[138:139], v[138:139], s[0:1], v[174:175] op_sel:[0,0,1] op_sel_hi:[1,0,0]
	s_waitcnt lgkmcnt(4)
	v_pk_add_f32 v[174:175], v[140:141], v[176:177]
	v_pk_add_f32 v[140:141], v[140:141], v[176:177] neg_lo:[0,1] neg_hi:[0,1]
	v_pk_mul_f32 v[10:11], v[6:7], v[6:7] op_sel:[1,1] op_sel_hi:[0,1] neg_lo:[0,1]
	v_pk_mul_f32 v[176:177], v[140:141], s[40:41]
	v_pk_fma_f32 v[10:11], v[6:7], v[6:7], v[10:11] op_sel_hi:[1,0,1]
	v_pk_fma_f32 v[140:141], v[140:141], s[80:81], v[176:177] op_sel:[0,0,1] op_sel_hi:[1,0,0]
	v_pk_add_f32 v[176:177], v[142:143], v[178:179]
	v_pk_add_f32 v[142:143], v[142:143], v[178:179] neg_lo:[0,1] neg_hi:[0,1]
	s_nop 0
	v_pk_mul_f32 v[178:179], v[142:143], s[42:43]
	s_nop 0
	v_pk_fma_f32 v[142:143], v[142:143], s[74:75], v[178:179] op_sel:[0,0,1] op_sel_hi:[1,0,0]
	s_waitcnt lgkmcnt(3)
	v_pk_add_f32 v[178:179], v[148:149], v[180:181]
	v_pk_add_f32 v[180:181], v[148:149], v[180:181] neg_lo:[0,1] neg_hi:[0,1]
	v_pk_mul_f32 v[28:29], v[10:11], v[10:11] op_sel:[1,1] op_sel_hi:[0,1] neg_lo:[0,1]
	v_pk_add_f32 v[148:149], v[150:151], v[182:183]
	v_pk_add_f32 v[150:151], v[150:151], v[182:183] neg_lo:[0,1] neg_hi:[0,1]
	v_pk_fma_f32 v[28:29], v[10:11], v[10:11], v[28:29] op_sel_hi:[1,0,1]
	v_pk_mul_f32 v[182:183], v[150:151], s[42:43]
	v_pk_mul_f32 v[44:45], v[10:11], v[28:29] op_sel:[1,1] op_sel_hi:[1,0] neg_lo:[1,0]
	v_pk_fma_f32 v[150:151], v[150:151], s[74:75], v[182:183] op_sel:[0,0,1] op_sel_hi:[1,0,0] neg_lo:[1,0,0] neg_hi:[1,0,0]
	s_waitcnt lgkmcnt(2)
	v_pk_add_f32 v[182:183], v[152:153], v[184:185]
	v_pk_add_f32 v[152:153], v[152:153], v[184:185] neg_lo:[0,1] neg_hi:[0,1]
	v_pk_fma_f32 v[44:45], v[10:11], v[28:29], v[44:45] op_sel_hi:[0,1,1]
	v_pk_mul_f32 v[184:185], v[152:153], s[40:41]
	v_pk_mul_f32 v[60:61], v[10:11], v[44:45] op_sel:[1,1] op_sel_hi:[1,0] neg_lo:[1,0]
	v_pk_fma_f32 v[152:153], v[152:153], s[80:81], v[184:185] op_sel:[0,0,1] op_sel_hi:[1,0,0] neg_lo:[1,0,0] neg_hi:[1,0,0]
	v_pk_add_f32 v[184:185], v[154:155], v[186:187]
	v_pk_add_f32 v[154:155], v[154:155], v[186:187] neg_lo:[0,1] neg_hi:[0,1]
	v_pk_fma_f32 v[60:61], v[10:11], v[44:45], v[60:61] op_sel_hi:[0,1,1]
	v_pk_mul_f32 v[186:187], v[154:155], s[38:39]
	v_pk_mul_f32 v[76:77], v[10:11], v[60:61] op_sel:[1,1] op_sel_hi:[1,0] neg_lo:[1,0]
	v_pk_fma_f32 v[154:155], v[154:155], s[0:1], v[186:187] op_sel:[0,0,1] op_sel_hi:[1,0,0] neg_lo:[1,0,0] neg_hi:[1,0,0]
	s_waitcnt lgkmcnt(1)
	v_pk_add_f32 v[186:187], v[156:157], v[188:189]
	v_pk_add_f32 v[156:157], v[156:157], v[188:189] neg_lo:[0,1] neg_hi:[0,1]
	v_pk_fma_f32 v[76:77], v[10:11], v[60:61], v[76:77] op_sel_hi:[0,1,1]
	v_pk_mul_f32 v[188:189], v[156:157], s[36:37]
	v_pk_mul_f32 v[92:93], v[10:11], v[76:77] op_sel:[1,1] op_sel_hi:[1,0] neg_lo:[1,0]
	v_pk_fma_f32 v[156:157], v[156:157], s[78:79], v[188:189] op_sel:[0,0,1] op_sel_hi:[1,0,0] neg_lo:[1,0,0] neg_hi:[1,0,0]
	v_pk_add_f32 v[188:189], v[158:159], v[190:191]
	v_pk_add_f32 v[158:159], v[158:159], v[190:191] neg_lo:[0,1] neg_hi:[0,1]
	v_pk_fma_f32 v[92:93], v[10:11], v[76:77], v[92:93] op_sel_hi:[0,1,1]
	v_pk_mul_f32 v[190:191], v[158:159], s[26:27]
	v_pk_mul_f32 v[108:109], v[10:11], v[92:93] op_sel:[1,1] op_sel_hi:[1,0] neg_lo:[1,0]
	v_pk_fma_f32 v[158:159], v[158:159], s[24:25], v[190:191] op_sel:[0,0,1] op_sel_hi:[1,0,0] neg_lo:[1,0,0] neg_hi:[1,0,0]
	s_waitcnt lgkmcnt(0)
	v_pk_add_f32 v[190:191], v[160:161], v[192:193]
	v_pk_add_f32 v[160:161], v[160:161], v[192:193] neg_lo:[0,1] neg_hi:[0,1]
	v_pk_mul_f32 v[8:9], v[2:3], v[6:7] op_sel:[0,1] op_sel_hi:[1,0]
	v_pk_mul_f32 v[192:193], v[160:161], s[18:19]
	v_pk_fma_f32 v[108:109], v[10:11], v[92:93], v[108:109] op_sel_hi:[0,1,1]
	v_pk_fma_f32 v[160:161], v[160:161], s[16:17], v[192:193] op_sel:[0,0,1] op_sel_hi:[1,0,0] neg_lo:[1,0,0] neg_hi:[1,0,0]
	v_pk_add_f32 v[192:193], v[162:163], v[194:195]
	v_pk_add_f32 v[162:163], v[162:163], v[194:195] neg_lo:[0,1] neg_hi:[0,1]
	v_pk_fma_f32 v[8:9], v[4:5], v[6:7], v[8:9] op_sel_hi:[0,1,1]
	v_pk_mul_f32 v[194:195], v[162:163], s[10:11]
	v_pk_mul_f32 v[16:17], v[2:3], v[10:11] op_sel:[0,1] op_sel_hi:[1,0]
	v_pk_fma_f32 v[162:163], v[162:163], s[8:9], v[194:195] op_sel:[0,0,1] op_sel_hi:[1,0,0] neg_lo:[1,0,0] neg_hi:[1,0,0]
	v_pk_add_f32 v[194:195], v[144:145], v[178:179]
	v_pk_add_f32 v[144:145], v[144:145], v[178:179] neg_lo:[0,1] neg_hi:[0,1]
	v_pk_add_f32 v[178:179], v[164:165], v[148:149]
	v_pk_add_f32 v[148:149], v[164:165], v[148:149] neg_lo:[0,1] neg_hi:[0,1]
	v_pk_mul_f32 v[32:33], v[2:3], v[28:29] op_sel:[0,1] op_sel_hi:[1,0]
	v_pk_mul_f32 v[164:165], v[148:149], s[18:19]
	v_pk_mul_f32 v[48:49], v[2:3], v[44:45] op_sel:[0,1] op_sel_hi:[1,0]
	v_pk_fma_f32 v[148:149], v[148:149], s[16:17], v[164:165] op_sel:[0,0,1] op_sel_hi:[1,0,0]
	v_pk_add_f32 v[164:165], v[166:167], v[182:183]
	v_pk_add_f32 v[166:167], v[166:167], v[182:183] neg_lo:[0,1] neg_hi:[0,1]
	v_pk_mul_f32 v[64:65], v[2:3], v[60:61] op_sel:[0,1] op_sel_hi:[1,0]
	v_pk_mul_f32 v[182:183], v[166:167], s[36:37]
	v_pk_mul_f32 v[80:81], v[2:3], v[76:77] op_sel:[0,1] op_sel_hi:[1,0]
	v_pk_fma_f32 v[166:167], v[166:167], s[78:79], v[182:183] op_sel:[0,0,1] op_sel_hi:[1,0,0]
	v_pk_add_f32 v[182:183], v[168:169], v[184:185]
	v_pk_add_f32 v[168:169], v[168:169], v[184:185] neg_lo:[0,1] neg_hi:[0,1]
	v_pk_mul_f32 v[96:97], v[2:3], v[92:93] op_sel:[0,1] op_sel_hi:[1,0]
	v_pk_mul_f32 v[184:185], v[168:169], s[40:41]
	v_pk_mul_f32 v[112:113], v[2:3], v[108:109] op_sel:[0,1] op_sel_hi:[1,0]
	v_pk_fma_f32 v[168:169], v[168:169], s[80:81], v[184:185] op_sel:[0,0,1] op_sel_hi:[1,0,0]
	v_pk_add_f32 v[184:185], v[170:171], v[186:187]
	v_pk_add_f32 v[186:187], v[170:171], v[186:187] neg_lo:[0,1] neg_hi:[0,1]
	v_pk_add_f32 v[170:171], v[172:173], v[188:189]
	v_pk_add_f32 v[172:173], v[172:173], v[188:189] neg_lo:[0,1] neg_hi:[0,1]
	s_nop 0
	v_pk_mul_f32 v[188:189], v[172:173], s[40:41]
	v_pk_fma_f32 v[16:17], v[4:5], v[10:11], v[16:17] op_sel_hi:[0,1,1]
	v_pk_fma_f32 v[172:173], v[172:173], s[80:81], v[188:189] op_sel:[0,0,1] op_sel_hi:[1,0,0] neg_lo:[1,0,0] neg_hi:[1,0,0]
	v_pk_add_f32 v[188:189], v[174:175], v[190:191]
	v_pk_add_f32 v[174:175], v[174:175], v[190:191] neg_lo:[0,1] neg_hi:[0,1]
	v_pk_mul_f32 v[20:21], v[6:7], v[10:11] op_sel:[1,1] op_sel_hi:[1,0] neg_lo:[1,0]
	v_pk_mul_f32 v[190:191], v[174:175], s[36:37]
	v_pk_fma_f32 v[32:33], v[4:5], v[28:29], v[32:33] op_sel_hi:[0,1,1]
	v_pk_fma_f32 v[174:175], v[174:175], s[78:79], v[190:191] op_sel:[0,0,1] op_sel_hi:[1,0,0] neg_lo:[1,0,0] neg_hi:[1,0,0]
	v_pk_add_f32 v[190:191], v[176:177], v[192:193]
	v_pk_add_f32 v[176:177], v[176:177], v[192:193] neg_lo:[0,1] neg_hi:[0,1]
	v_pk_mul_f32 v[36:37], v[6:7], v[28:29] op_sel:[1,1] op_sel_hi:[1,0] neg_lo:[1,0]
	v_pk_mul_f32 v[192:193], v[176:177], s[18:19]
	v_pk_fma_f32 v[48:49], v[4:5], v[44:45], v[48:49] op_sel_hi:[0,1,1]
	v_pk_fma_f32 v[176:177], v[176:177], s[16:17], v[192:193] op_sel:[0,0,1] op_sel_hi:[1,0,0] neg_lo:[1,0,0] neg_hi:[1,0,0]
	v_pk_add_f32 v[192:193], v[128:129], v[180:181] op_sel:[0,1] op_sel_hi:[1,0] neg_hi:[0,1]
	v_pk_add_f32 v[128:129], v[128:129], v[180:181] op_sel:[0,1] op_sel_hi:[1,0] neg_lo:[0,1]
	v_pk_add_f32 v[180:181], v[130:131], v[150:151]
	v_pk_add_f32 v[130:131], v[130:131], v[150:151] neg_lo:[0,1] neg_hi:[0,1]
	v_pk_mul_f32 v[52:53], v[6:7], v[44:45] op_sel:[1,1] op_sel_hi:[1,0] neg_lo:[1,0]
	v_pk_mul_f32 v[150:151], v[130:131], s[18:19]
	v_pk_fma_f32 v[64:65], v[4:5], v[60:61], v[64:65] op_sel_hi:[0,1,1]
	v_pk_fma_f32 v[130:131], v[130:131], s[16:17], v[150:151] op_sel:[0,0,1] op_sel_hi:[1,0,0]
	v_pk_add_f32 v[150:151], v[132:133], v[152:153]
	v_pk_add_f32 v[132:133], v[132:133], v[152:153] neg_lo:[0,1] neg_hi:[0,1]
	v_pk_mul_f32 v[68:69], v[6:7], v[60:61] op_sel:[1,1] op_sel_hi:[1,0] neg_lo:[1,0]
	v_pk_mul_f32 v[152:153], v[132:133], s[36:37]
	v_pk_fma_f32 v[80:81], v[4:5], v[76:77], v[80:81] op_sel_hi:[0,1,1]
	v_pk_fma_f32 v[132:133], v[132:133], s[78:79], v[152:153] op_sel:[0,0,1] op_sel_hi:[1,0,0]
	v_pk_add_f32 v[152:153], v[134:135], v[154:155]
	v_pk_add_f32 v[134:135], v[134:135], v[154:155] neg_lo:[0,1] neg_hi:[0,1]
	v_pk_mul_f32 v[84:85], v[6:7], v[76:77] op_sel:[1,1] op_sel_hi:[1,0] neg_lo:[1,0]
	v_pk_mul_f32 v[154:155], v[134:135], s[40:41]
	v_pk_fma_f32 v[96:97], v[4:5], v[92:93], v[96:97] op_sel_hi:[0,1,1]
	v_pk_fma_f32 v[134:135], v[134:135], s[80:81], v[154:155] op_sel:[0,0,1] op_sel_hi:[1,0,0]
	v_pk_add_f32 v[154:155], v[136:137], v[156:157]
	v_pk_add_f32 v[156:157], v[136:137], v[156:157] neg_lo:[0,1] neg_hi:[0,1]
	v_pk_mul_f32 v[100:101], v[6:7], v[92:93] op_sel:[1,1] op_sel_hi:[1,0] neg_lo:[1,0]
	v_pk_add_f32 v[136:137], v[138:139], v[158:159]
	v_pk_add_f32 v[138:139], v[138:139], v[158:159] neg_lo:[0,1] neg_hi:[0,1]
	v_pk_fma_f32 v[112:113], v[4:5], v[108:109], v[112:113] op_sel_hi:[0,1,1]
	v_pk_mul_f32 v[158:159], v[138:139], s[40:41]
	v_pk_mul_f32 v[116:117], v[6:7], v[108:109] op_sel:[1,1] op_sel_hi:[1,0] neg_lo:[1,0]
	v_pk_fma_f32 v[138:139], v[138:139], s[80:81], v[158:159] op_sel:[0,0,1] op_sel_hi:[1,0,0] neg_lo:[1,0,0] neg_hi:[1,0,0]
	v_pk_add_f32 v[158:159], v[140:141], v[160:161]
	v_pk_add_f32 v[140:141], v[140:141], v[160:161] neg_lo:[0,1] neg_hi:[0,1]
	v_pk_fma_f32 v[20:21], v[6:7], v[10:11], v[20:21] op_sel_hi:[0,1,1]
	v_pk_mul_f32 v[160:161], v[140:141], s[36:37]
	v_pk_mul_f32 v[24:25], v[10:11], v[8:9] op_sel:[1,1] op_sel_hi:[0,1] neg_lo:[0,1]
	v_pk_fma_f32 v[140:141], v[140:141], s[78:79], v[160:161] op_sel:[0,0,1] op_sel_hi:[1,0,0] neg_lo:[1,0,0] neg_hi:[1,0,0]
	v_pk_add_f32 v[160:161], v[142:143], v[162:163]
	v_pk_add_f32 v[142:143], v[142:143], v[162:163] neg_lo:[0,1] neg_hi:[0,1]
	v_pk_fma_f32 v[36:37], v[6:7], v[28:29], v[36:37] op_sel_hi:[0,1,1]
	v_pk_mul_f32 v[162:163], v[142:143], s[18:19]
	v_pk_mul_f32 v[40:41], v[8:9], v[28:29] op_sel:[1,1] op_sel_hi:[1,0] neg_lo:[1,0]
	v_pk_fma_f32 v[142:143], v[142:143], s[16:17], v[162:163] op_sel:[0,0,1] op_sel_hi:[1,0,0] neg_lo:[1,0,0] neg_hi:[1,0,0]
	v_pk_add_f32 v[162:163], v[194:195], v[184:185]
	v_pk_add_f32 v[184:185], v[194:195], v[184:185] neg_lo:[0,1] neg_hi:[0,1]
	v_pk_add_f32 v[194:195], v[178:179], v[170:171]
	v_pk_add_f32 v[170:171], v[178:179], v[170:171] neg_lo:[0,1] neg_hi:[0,1]
	v_pk_fma_f32 v[52:53], v[6:7], v[44:45], v[52:53] op_sel_hi:[0,1,1]
	v_pk_mul_f32 v[178:179], v[170:171], s[36:37]
	v_pk_mul_f32 v[56:57], v[8:9], v[44:45] op_sel:[1,1] op_sel_hi:[1,0] neg_lo:[1,0]
	v_pk_fma_f32 v[170:171], v[170:171], s[78:79], v[178:179] op_sel:[0,0,1] op_sel_hi:[1,0,0]
	v_pk_add_f32 v[178:179], v[164:165], v[188:189]
	v_pk_add_f32 v[188:189], v[164:165], v[188:189] neg_lo:[0,1] neg_hi:[0,1]
	v_pk_fma_f32 v[68:69], v[6:7], v[60:61], v[68:69] op_sel_hi:[0,1,1]
	v_pk_add_f32 v[164:165], v[182:183], v[190:191]
	v_pk_add_f32 v[182:183], v[182:183], v[190:191] neg_lo:[0,1] neg_hi:[0,1]
	v_pk_mul_f32 v[72:73], v[8:9], v[60:61] op_sel:[1,1] op_sel_hi:[1,0] neg_lo:[1,0]
	v_pk_mul_f32 v[190:191], v[182:183], s[36:37]
	v_pk_fma_f32 v[84:85], v[6:7], v[76:77], v[84:85] op_sel_hi:[0,1,1]
	v_pk_fma_f32 v[182:183], v[182:183], s[78:79], v[190:191] op_sel:[0,0,1] op_sel_hi:[1,0,0] neg_lo:[1,0,0] neg_hi:[1,0,0]
	v_pk_add_f32 v[190:191], v[144:145], v[186:187] op_sel:[0,1] op_sel_hi:[1,0] neg_hi:[0,1]
	v_pk_add_f32 v[144:145], v[144:145], v[186:187] op_sel:[0,1] op_sel_hi:[1,0] neg_lo:[0,1]
	v_pk_add_f32 v[186:187], v[148:149], v[172:173]
	v_pk_add_f32 v[148:149], v[148:149], v[172:173] neg_lo:[0,1] neg_hi:[0,1]
	v_pk_mul_f32 v[88:89], v[8:9], v[76:77] op_sel:[1,1] op_sel_hi:[1,0] neg_lo:[1,0]
	v_pk_mul_f32 v[172:173], v[148:149], s[36:37]
	v_pk_fma_f32 v[100:101], v[6:7], v[92:93], v[100:101] op_sel_hi:[0,1,1]
	v_pk_fma_f32 v[148:149], v[148:149], s[78:79], v[172:173] op_sel:[0,0,1] op_sel_hi:[1,0,0]
	v_pk_add_f32 v[172:173], v[166:167], v[174:175]
	v_pk_add_f32 v[174:175], v[166:167], v[174:175] neg_lo:[0,1] neg_hi:[0,1]
	v_pk_mul_f32 v[104:105], v[8:9], v[92:93] op_sel:[1,1] op_sel_hi:[1,0] neg_lo:[1,0]
	v_pk_add_f32 v[166:167], v[168:169], v[176:177]
	v_pk_add_f32 v[168:169], v[168:169], v[176:177] neg_lo:[0,1] neg_hi:[0,1]
	v_pk_fma_f32 v[116:117], v[6:7], v[108:109], v[116:117] op_sel_hi:[0,1,1]
	v_pk_mul_f32 v[176:177], v[168:169], s[36:37]
	v_pk_mul_f32 v[120:121], v[8:9], v[108:109] op_sel:[1,1] op_sel_hi:[1,0] neg_lo:[1,0]
	v_pk_fma_f32 v[168:169], v[168:169], s[78:79], v[176:177] op_sel:[0,0,1] op_sel_hi:[1,0,0] neg_lo:[1,0,0] neg_hi:[1,0,0]
	v_pk_add_f32 v[176:177], v[192:193], v[154:155]
	v_pk_add_f32 v[154:155], v[192:193], v[154:155] neg_lo:[0,1] neg_hi:[0,1]
	v_pk_add_f32 v[192:193], v[180:181], v[136:137]
	v_pk_add_f32 v[136:137], v[180:181], v[136:137] neg_lo:[0,1] neg_hi:[0,1]
	v_xor_b32_e32 v26, 0x80000000, v17
	v_pk_mul_f32 v[180:181], v[136:137], s[36:37]
	v_xor_b32_e32 v30, 0x80000000, v21
	v_pk_fma_f32 v[136:137], v[136:137], s[78:79], v[180:181] op_sel:[0,0,1] op_sel_hi:[1,0,0]
	v_pk_add_f32 v[180:181], v[150:151], v[158:159]
	v_pk_add_f32 v[158:159], v[150:151], v[158:159] neg_lo:[0,1] neg_hi:[0,1]
	v_pk_fma_f32 v[24:25], v[10:11], v[8:9], v[24:25] op_sel_hi:[1,0,1]
	v_pk_add_f32 v[150:151], v[152:153], v[160:161]
	v_pk_add_f32 v[152:153], v[152:153], v[160:161] neg_lo:[0,1] neg_hi:[0,1]
	v_pk_fma_f32 v[40:41], v[8:9], v[28:29], v[40:41] op_sel_hi:[0,1,1]
	v_pk_mul_f32 v[160:161], v[152:153], s[36:37]
	v_pk_fma_f32 v[56:57], v[8:9], v[44:45], v[56:57] op_sel_hi:[0,1,1]
	v_pk_fma_f32 v[152:153], v[152:153], s[78:79], v[160:161] op_sel:[0,0,1] op_sel_hi:[1,0,0] neg_lo:[1,0,0] neg_hi:[1,0,0]
	v_pk_add_f32 v[160:161], v[128:129], v[156:157] op_sel:[0,1] op_sel_hi:[1,0] neg_hi:[0,1]
	v_pk_add_f32 v[128:129], v[128:129], v[156:157] op_sel:[0,1] op_sel_hi:[1,0] neg_lo:[0,1]
	v_pk_add_f32 v[156:157], v[130:131], v[138:139]
	v_pk_add_f32 v[130:131], v[130:131], v[138:139] neg_lo:[0,1] neg_hi:[0,1]
	v_pk_fma_f32 v[72:73], v[8:9], v[60:61], v[72:73] op_sel_hi:[0,1,1]
	v_pk_mul_f32 v[138:139], v[130:131], s[36:37]
	v_pk_fma_f32 v[88:89], v[8:9], v[76:77], v[88:89] op_sel_hi:[0,1,1]
	v_pk_fma_f32 v[130:131], v[130:131], s[78:79], v[138:139] op_sel:[0,0,1] op_sel_hi:[1,0,0]
	v_pk_add_f32 v[138:139], v[132:133], v[140:141]
	v_pk_add_f32 v[140:141], v[132:133], v[140:141] neg_lo:[0,1] neg_hi:[0,1]
	v_pk_fma_f32 v[104:105], v[8:9], v[92:93], v[104:105] op_sel_hi:[0,1,1]
	v_pk_add_f32 v[132:133], v[134:135], v[142:143]
	v_pk_add_f32 v[134:135], v[134:135], v[142:143] neg_lo:[0,1] neg_hi:[0,1]
	v_pk_fma_f32 v[120:121], v[8:9], v[108:109], v[120:121] op_sel_hi:[0,1,1]
	v_pk_mul_f32 v[142:143], v[134:135], s[36:37]
	v_mov_b32_e32 v27, v17
	v_pk_fma_f32 v[134:135], v[134:135], s[78:79], v[142:143] op_sel:[0,0,1] op_sel_hi:[1,0,0] neg_lo:[1,0,0] neg_hi:[1,0,0]
	v_pk_add_f32 v[142:143], v[162:163], v[178:179]
	v_pk_add_f32 v[162:163], v[162:163], v[178:179] neg_lo:[0,1] neg_hi:[0,1]
	v_pk_add_f32 v[178:179], v[194:195], v[164:165]
	v_pk_add_f32 v[194:195], v[194:195], v[164:165] neg_lo:[0,1] neg_hi:[0,1]
	v_mov_b32_e32 v31, v21
	v_pk_add_f32 v[164:165], v[184:185], v[188:189] op_sel:[0,1] op_sel_hi:[1,0] neg_hi:[0,1]
	v_pk_add_f32 v[184:185], v[184:185], v[188:189] op_sel:[0,1] op_sel_hi:[1,0] neg_lo:[0,1]
	v_pk_add_f32 v[188:189], v[170:171], v[182:183]
	v_pk_add_f32 v[182:183], v[170:171], v[182:183] neg_lo:[0,1] neg_hi:[0,1]
	v_xor_b32_e32 v34, 0x80000000, v25
	v_pk_add_f32 v[170:171], v[190:191], v[172:173]
	v_pk_add_f32 v[172:173], v[190:191], v[172:173] neg_lo:[0,1] neg_hi:[0,1]
	v_pk_add_f32 v[190:191], v[186:187], v[166:167]
	v_pk_add_f32 v[186:187], v[186:187], v[166:167] neg_lo:[0,1] neg_hi:[0,1]
	v_xor_b32_e32 v38, 0x80000000, v29
	v_pk_add_f32 v[166:167], v[144:145], v[174:175] op_sel:[0,1] op_sel_hi:[1,0] neg_hi:[0,1]
	v_pk_add_f32 v[144:145], v[144:145], v[174:175] op_sel:[0,1] op_sel_hi:[1,0] neg_lo:[0,1]
	v_pk_add_f32 v[174:175], v[148:149], v[168:169]
	v_pk_add_f32 v[168:169], v[148:149], v[168:169] neg_lo:[0,1] neg_hi:[0,1]
	v_xor_b32_e32 v42, 0x80000000, v33
	v_pk_add_f32 v[148:149], v[176:177], v[180:181]
	v_pk_add_f32 v[176:177], v[176:177], v[180:181] neg_lo:[0,1] neg_hi:[0,1]
	v_pk_add_f32 v[180:181], v[192:193], v[150:151]
	v_pk_add_f32 v[192:193], v[192:193], v[150:151] neg_lo:[0,1] neg_hi:[0,1]
	v_xor_b32_e32 v46, 0x80000000, v37
	v_pk_add_f32 v[150:151], v[154:155], v[158:159] op_sel:[0,1] op_sel_hi:[1,0] neg_hi:[0,1]
	v_pk_add_f32 v[154:155], v[154:155], v[158:159] op_sel:[0,1] op_sel_hi:[1,0] neg_lo:[0,1]
	v_pk_add_f32 v[158:159], v[136:137], v[152:153]
	v_pk_add_f32 v[152:153], v[136:137], v[152:153] neg_lo:[0,1] neg_hi:[0,1]
	v_mov_b32_e32 v35, v25
	v_pk_add_f32 v[136:137], v[160:161], v[138:139]
	v_pk_add_f32 v[138:139], v[160:161], v[138:139] neg_lo:[0,1] neg_hi:[0,1]
	v_pk_add_f32 v[160:161], v[156:157], v[132:133]
	v_pk_add_f32 v[156:157], v[156:157], v[132:133] neg_lo:[0,1] neg_hi:[0,1]
	v_mov_b32_e32 v39, v29
	v_pk_add_f32 v[132:133], v[128:129], v[140:141] op_sel:[0,1] op_sel_hi:[1,0] neg_hi:[0,1]
	v_pk_add_f32 v[128:129], v[128:129], v[140:141] op_sel:[0,1] op_sel_hi:[1,0] neg_lo:[0,1]
	v_pk_add_f32 v[140:141], v[130:131], v[134:135]
	v_pk_add_f32 v[134:135], v[130:131], v[134:135] neg_lo:[0,1] neg_hi:[0,1]
	v_mov_b32_e32 v43, v33
	v_pk_add_f32 v[130:131], v[142:143], v[178:179]
	v_pk_add_f32 v[142:143], v[142:143], v[178:179] neg_lo:[0,1] neg_hi:[0,1]
	v_pk_add_f32 v[178:179], v[162:163], v[194:195] op_sel:[0,1] op_sel_hi:[1,0] neg_hi:[0,1]
	v_pk_add_f32 v[162:163], v[162:163], v[194:195] op_sel:[0,1] op_sel_hi:[1,0] neg_lo:[0,1]
	v_pk_add_f32 v[194:195], v[164:165], v[188:189]
	v_pk_add_f32 v[164:165], v[164:165], v[188:189] neg_lo:[0,1] neg_hi:[0,1]
	v_pk_add_f32 v[188:189], v[184:185], v[182:183] op_sel:[0,1] op_sel_hi:[1,0] neg_hi:[0,1]
	v_pk_add_f32 v[182:183], v[184:185], v[182:183] op_sel:[0,1] op_sel_hi:[1,0] neg_lo:[0,1]
	v_pk_add_f32 v[184:185], v[170:171], v[190:191]
	v_pk_add_f32 v[170:171], v[170:171], v[190:191] neg_lo:[0,1] neg_hi:[0,1]
	v_pk_add_f32 v[190:191], v[172:173], v[186:187] op_sel:[0,1] op_sel_hi:[1,0] neg_hi:[0,1]
	v_pk_add_f32 v[172:173], v[172:173], v[186:187] op_sel:[0,1] op_sel_hi:[1,0] neg_lo:[0,1]
	v_pk_add_f32 v[186:187], v[166:167], v[174:175]
	v_pk_add_f32 v[166:167], v[166:167], v[174:175] neg_lo:[0,1] neg_hi:[0,1]
	v_pk_add_f32 v[174:175], v[144:145], v[168:169] op_sel:[0,1] op_sel_hi:[1,0] neg_hi:[0,1]
	v_pk_add_f32 v[144:145], v[144:145], v[168:169] op_sel:[0,1] op_sel_hi:[1,0] neg_lo:[0,1]
	v_pk_add_f32 v[168:169], v[148:149], v[180:181]
	v_pk_add_f32 v[148:149], v[148:149], v[180:181] neg_lo:[0,1] neg_hi:[0,1]
	v_pk_mul_f32 v[2:3], v[2:3], v[168:169] op_sel:[0,1] op_sel_hi:[1,0]
	v_pk_add_f32 v[180:181], v[176:177], v[192:193] op_sel:[0,1] op_sel_hi:[1,0] neg_hi:[0,1]
	v_pk_add_f32 v[176:177], v[176:177], v[192:193] op_sel:[0,1] op_sel_hi:[1,0] neg_lo:[0,1]
	v_pk_add_f32 v[192:193], v[150:151], v[158:159]
	v_pk_add_f32 v[150:151], v[150:151], v[158:159] neg_lo:[0,1] neg_hi:[0,1]
	v_pk_add_f32 v[158:159], v[154:155], v[152:153] op_sel:[0,1] op_sel_hi:[1,0] neg_hi:[0,1]
	v_pk_add_f32 v[152:153], v[154:155], v[152:153] op_sel:[0,1] op_sel_hi:[1,0] neg_lo:[0,1]
	v_pk_add_f32 v[154:155], v[136:137], v[160:161]
	v_pk_fma_f32 v[2:3], v[4:5], v[168:169], v[2:3] op_sel_hi:[0,1,1]
	v_pk_mul_f32 v[4:5], v[6:7], v[184:185] op_sel:[1,1] op_sel_hi:[1,0] neg_lo:[1,0]
	v_mov_b32_e32 v47, v37
	v_pk_fma_f32 v[4:5], v[6:7], v[184:185], v[4:5] op_sel_hi:[0,1,1]
	v_pk_mul_f32 v[6:7], v[8:9], v[154:155] op_sel:[1,1] op_sel_hi:[1,0] neg_lo:[1,0]
	v_pk_add_f32 v[136:137], v[136:137], v[160:161] neg_lo:[0,1] neg_hi:[0,1]
	v_pk_fma_f32 v[6:7], v[8:9], v[154:155], v[6:7] op_sel_hi:[0,1,1]
	v_pk_mul_f32 v[8:9], v[10:11], v[194:195] op_sel:[1,1] op_sel_hi:[1,0] neg_lo:[1,0]
	v_pk_add_f32 v[160:161], v[138:139], v[156:157] op_sel:[0,1] op_sel_hi:[1,0] neg_hi:[0,1]
	v_pk_add_f32 v[138:139], v[138:139], v[156:157] op_sel:[0,1] op_sel_hi:[1,0] neg_lo:[0,1]
	v_pk_add_f32 v[156:157], v[132:133], v[140:141]
	v_pk_fma_f32 v[8:9], v[10:11], v[194:195], v[8:9] op_sel_hi:[0,1,1]
	v_pk_mul_f32 v[10:11], v[26:27], v[192:193] op_sel:[0,1] op_sel_hi:[1,0]
	v_pk_mul_f32 v[12:13], v[30:31], v[186:187] op_sel:[0,1] op_sel_hi:[1,0]
	v_pk_add_f32 v[132:133], v[132:133], v[140:141] neg_lo:[0,1] neg_hi:[0,1]
	v_pk_add_f32 v[140:141], v[128:129], v[134:135] op_sel:[0,1] op_sel_hi:[1,0] neg_hi:[0,1]
	v_pk_fma_f32 v[10:11], v[16:17], v[192:193], v[10:11] op_sel_hi:[0,1,1]
	v_pk_fma_f32 v[12:13], v[20:21], v[186:187], v[12:13] op_sel_hi:[0,1,1]
	v_pk_mul_f32 v[14:15], v[34:35], v[156:157] op_sel:[0,1] op_sel_hi:[1,0]
	v_pk_mul_f32 v[16:17], v[38:39], v[178:179] op_sel:[0,1] op_sel_hi:[1,0]
	v_pk_mul_f32 v[20:21], v[42:43], v[180:181] op_sel:[0,1] op_sel_hi:[1,0]
	v_pk_mul_f32 v[22:23], v[46:47], v[190:191] op_sel:[0,1] op_sel_hi:[1,0]
	v_xor_b32_e32 v78, 0x80000000, v69
	v_xor_b32_e32 v82, 0x80000000, v73
	v_xor_b32_e32 v86, 0x80000000, v77
	v_xor_b32_e32 v90, 0x80000000, v81
	v_xor_b32_e32 v94, 0x80000000, v85
	v_xor_b32_e32 v98, 0x80000000, v89
	v_xor_b32_e32 v102, 0x80000000, v93
	v_xor_b32_e32 v106, 0x80000000, v97
	v_xor_b32_e32 v110, 0x80000000, v101
	v_xor_b32_e32 v114, 0x80000000, v105
	v_xor_b32_e32 v118, 0x80000000, v109
	v_xor_b32_e32 v122, 0x80000000, v113
	v_xor_b32_e32 v124, 0x80000000, v117
	v_xor_b32_e32 v126, 0x80000000, v121
	v_mov_b32_e32 v79, v69
	v_mov_b32_e32 v83, v73
	v_mov_b32_e32 v87, v77
	v_mov_b32_e32 v91, v81
	v_mov_b32_e32 v95, v85
	v_mov_b32_e32 v99, v89
	v_mov_b32_e32 v103, v93
	v_mov_b32_e32 v107, v97
	v_mov_b32_e32 v111, v101
	v_mov_b32_e32 v115, v105
	v_mov_b32_e32 v119, v109
	v_mov_b32_e32 v123, v113
	v_mov_b32_e32 v125, v117
	v_mov_b32_e32 v127, v121
	v_pk_add_f32 v[128:129], v[128:129], v[134:135] op_sel:[0,1] op_sel_hi:[1,0] neg_lo:[0,1]
	v_pk_fma_f32 v[14:15], v[24:25], v[156:157], v[14:15] op_sel_hi:[0,1,1]
	v_pk_fma_f32 v[16:17], v[28:29], v[178:179], v[16:17] op_sel_hi:[0,1,1]
	v_pk_fma_f32 v[20:21], v[32:33], v[180:181], v[20:21] op_sel_hi:[0,1,1]
	v_pk_fma_f32 v[22:23], v[36:37], v[190:191], v[22:23] op_sel_hi:[0,1,1]
	v_pk_mul_f32 v[24:25], v[40:41], v[160:161] op_sel:[1,1] op_sel_hi:[1,0] neg_lo:[1,0]
	v_pk_mul_f32 v[26:27], v[44:45], v[188:189] op_sel:[1,1] op_sel_hi:[1,0] neg_lo:[1,0]
	v_pk_mul_f32 v[28:29], v[48:49], v[158:159] op_sel:[1,1] op_sel_hi:[1,0] neg_lo:[1,0]
	v_pk_mul_f32 v[30:31], v[52:53], v[174:175] op_sel:[1,1] op_sel_hi:[1,0] neg_lo:[1,0]
	v_pk_mul_f32 v[32:33], v[56:57], v[140:141] op_sel:[1,1] op_sel_hi:[1,0] neg_lo:[1,0]
	v_pk_mul_f32 v[34:35], v[60:61], v[142:143] op_sel:[1,1] op_sel_hi:[1,0] neg_lo:[1,0]
	v_pk_mul_f32 v[36:37], v[64:65], v[148:149] op_sel:[1,1] op_sel_hi:[1,0] neg_lo:[1,0]
	v_pk_fma_f32 v[24:25], v[40:41], v[160:161], v[24:25] op_sel_hi:[0,1,1]
	v_pk_fma_f32 v[26:27], v[44:45], v[188:189], v[26:27] op_sel_hi:[0,1,1]
	v_pk_fma_f32 v[28:29], v[48:49], v[158:159], v[28:29] op_sel_hi:[0,1,1]
	v_pk_fma_f32 v[30:31], v[52:53], v[174:175], v[30:31] op_sel_hi:[0,1,1]
	v_pk_fma_f32 v[32:33], v[56:57], v[140:141], v[32:33] op_sel_hi:[0,1,1]
	v_pk_fma_f32 v[34:35], v[60:61], v[142:143], v[34:35] op_sel_hi:[0,1,1]
	v_pk_fma_f32 v[36:37], v[64:65], v[148:149], v[36:37] op_sel_hi:[0,1,1]
	v_pk_mul_f32 v[38:39], v[78:79], v[170:171] op_sel:[0,1] op_sel_hi:[1,0]
	v_pk_mul_f32 v[40:41], v[82:83], v[136:137] op_sel:[0,1] op_sel_hi:[1,0]
	v_pk_mul_f32 v[42:43], v[86:87], v[164:165] op_sel:[0,1] op_sel_hi:[1,0]
	v_pk_mul_f32 v[44:45], v[90:91], v[150:151] op_sel:[0,1] op_sel_hi:[1,0]
	v_pk_mul_f32 v[46:47], v[94:95], v[166:167] op_sel:[0,1] op_sel_hi:[1,0]
	v_pk_mul_f32 v[48:49], v[98:99], v[132:133] op_sel:[0,1] op_sel_hi:[1,0]
	v_pk_mul_f32 v[50:51], v[102:103], v[162:163] op_sel:[0,1] op_sel_hi:[1,0]
	v_pk_mul_f32 v[52:53], v[106:107], v[176:177] op_sel:[0,1] op_sel_hi:[1,0]
	v_pk_mul_f32 v[54:55], v[110:111], v[172:173] op_sel:[0,1] op_sel_hi:[1,0]
	v_pk_mul_f32 v[56:57], v[114:115], v[138:139] op_sel:[0,1] op_sel_hi:[1,0]
	v_pk_mul_f32 v[58:59], v[118:119], v[182:183] op_sel:[0,1] op_sel_hi:[1,0]
	v_pk_mul_f32 v[60:61], v[122:123], v[152:153] op_sel:[0,1] op_sel_hi:[1,0]
	v_pk_mul_f32 v[62:63], v[124:125], v[144:145] op_sel:[0,1] op_sel_hi:[1,0]
	v_pk_mul_f32 v[64:65], v[126:127], v[128:129] op_sel:[0,1] op_sel_hi:[1,0]
	v_pk_fma_f32 v[38:39], v[68:69], v[170:171], v[38:39] op_sel_hi:[0,1,1]
	v_pk_fma_f32 v[40:41], v[72:73], v[136:137], v[40:41] op_sel_hi:[0,1,1]
	v_pk_fma_f32 v[42:43], v[76:77], v[164:165], v[42:43] op_sel_hi:[0,1,1]
	v_pk_fma_f32 v[44:45], v[80:81], v[150:151], v[44:45] op_sel_hi:[0,1,1]
	v_pk_fma_f32 v[46:47], v[84:85], v[166:167], v[46:47] op_sel_hi:[0,1,1]
	v_pk_fma_f32 v[48:49], v[88:89], v[132:133], v[48:49] op_sel_hi:[0,1,1]
	v_pk_fma_f32 v[50:51], v[92:93], v[162:163], v[50:51] op_sel_hi:[0,1,1]
	v_pk_fma_f32 v[52:53], v[96:97], v[176:177], v[52:53] op_sel_hi:[0,1,1]
	v_pk_fma_f32 v[54:55], v[100:101], v[172:173], v[54:55] op_sel_hi:[0,1,1]
	v_pk_fma_f32 v[56:57], v[104:105], v[138:139], v[56:57] op_sel_hi:[0,1,1]
	v_pk_fma_f32 v[58:59], v[108:109], v[182:183], v[58:59] op_sel_hi:[0,1,1]
	v_pk_fma_f32 v[60:61], v[112:113], v[152:153], v[60:61] op_sel_hi:[0,1,1]
	v_pk_fma_f32 v[62:63], v[116:117], v[144:145], v[62:63] op_sel_hi:[0,1,1]
	v_pk_fma_f32 v[64:65], v[120:121], v[128:129], v[64:65] op_sel_hi:[0,1,1]
	ds_write2_b64 v18, v[130:131], v[34:35] offset1:16
	ds_write2_b64 v18, v[16:17], v[50:51] offset0:33 offset1:49
	ds_write2_b64 v18, v[8:9], v[42:43] offset0:66 offset1:82
	ds_write2_b64 v18, v[26:27], v[58:59] offset0:99 offset1:115
	ds_write2_b64 v18, v[4:5], v[38:39] offset0:132 offset1:148
	ds_write2_b64 v18, v[22:23], v[54:55] offset0:165 offset1:181
	ds_write2_b64 v18, v[12:13], v[46:47] offset0:198 offset1:214
	ds_write2_b64 v18, v[30:31], v[62:63] offset0:231 offset1:247
	ds_write2_b64 v196, v[2:3], v[36:37] offset0:8 offset1:24
	ds_write2_b64 v196, v[20:21], v[52:53] offset0:41 offset1:57
	ds_write2_b64 v196, v[10:11], v[44:45] offset0:74 offset1:90
	ds_write2_b64 v196, v[28:29], v[60:61] offset0:107 offset1:123
	ds_write2_b64 v196, v[6:7], v[40:41] offset0:140 offset1:156
	ds_write2_b64 v196, v[24:25], v[56:57] offset0:173 offset1:189
	ds_write2_b64 v196, v[14:15], v[48:49] offset0:206 offset1:222
	ds_write2_b64 v196, v[32:33], v[64:65] offset0:239 offset1:255
	v_ashrrev_i32_e32 v2, 31, v210
	v_lshrrev_b32_e32 v2, 23, v2
	v_add_u32_e32 v2, v210, v2
	s_lshl_b64 s[74:75], s[76:77], 16
	v_and_b32_e32 v2, 0xfffffe00, v2
	s_add_u32 s0, s54, s74
	v_sub_u32_e32 v2, v210, v2
	s_addc_u32 s1, s55, s75
	v_ashrrev_i32_e32 v3, 31, v2
	v_lshl_add_u64 v[14:15], v[2:3], 3, s[0:1]
	v_add_co_u32_e32 v2, vcc, s92, v14
	s_mov_b32 s0, 0x8000
	s_nop 0
	v_addc_co_u32_e32 v3, vcc, 0, v15, vcc
	v_add_co_u32_e32 v4, vcc, s95, v14
	s_waitcnt lgkmcnt(0)
	s_nop 0
	v_addc_co_u32_e32 v5, vcc, 0, v15, vcc
	v_add_co_u32_e32 v8, vcc, s96, v14
	s_barrier
	s_nop 0
	v_addc_co_u32_e32 v9, vcc, 0, v15, vcc
	global_load_dwordx2 v[24:25], v[4:5], off offset:-4096 nt
	global_load_dwordx2 v[12:13], v[4:5], off nt
	global_load_dwordx2 v[6:7], v[8:9], off offset:-4096 nt
	s_nop 0
	global_load_dwordx2 v[4:5], v[8:9], off nt
	v_add_co_u32_e32 v8, vcc, s0, v14
	s_waitcnt vmcnt(3)
	v_cvt_f32_f16_sdwa v174, v24 dst_sel:DWORD dst_unused:UNUSED_PAD src0_sel:WORD_1
	v_addc_co_u32_e32 v9, vcc, 0, v15, vcc
	v_add_co_u32_e32 v10, vcc, s34, v14
	v_cvt_f32_f16_e32 v175, v25
	s_nop 0
	v_addc_co_u32_e32 v11, vcc, 0, v15, vcc
	global_load_dwordx2 v[16:17], v[8:9], off offset:-4096 nt
	global_load_dwordx2 v[122:123], v[8:9], off nt
	global_load_dwordx2 v[46:47], v[10:11], off offset:-4096 nt
	global_load_dwordx2 v[36:37], v[10:11], off nt
	v_add_co_u32_e32 v8, vcc, s35, v14
	v_cvt_f32_f16_sdwa v177, v25 dst_sel:DWORD dst_unused:UNUSED_PAD src0_sel:WORD_1
	s_nop 0
	v_addc_co_u32_e32 v9, vcc, 0, v15, vcc
	v_add_co_u32_e32 v22, vcc, s30, v14
	v_cvt_f32_f16_e32 v176, v24
	s_nop 0
	v_addc_co_u32_e32 v23, vcc, 0, v15, vcc
	global_load_dwordx2 v[26:27], v[8:9], off offset:-4096 nt
	global_load_dwordx2 v[20:21], v[8:9], off nt
	global_load_dwordx2 v[10:11], v[22:23], off offset:-4096 nt
	s_nop 0
	global_load_dwordx2 v[8:9], v[22:23], off nt
	v_add_co_u32_e32 v22, vcc, s31, v14
	s_waitcnt vmcnt(10)
	v_cvt_f32_f16_sdwa v164, v12 dst_sel:DWORD dst_unused:UNUSED_PAD src0_sel:WORD_1
	v_addc_co_u32_e32 v23, vcc, 0, v15, vcc
	global_load_dwordx2 v[30:31], v[2:3], off offset:-4096 nt
	global_load_dwordx2 v[28:29], v[2:3], off nt
	s_nop 0
	global_load_dwordx2 v[2:3], v[22:23], off nt
	global_load_dwordx2 v[32:33], v[14:15], off nt
	v_mov_b32_e32 v14, v210
	v_cvt_f32_f16_e32 v165, v13
	v_ashrrev_i32_e32 v15, 31, v14
	v_lshrrev_b32_e32 v15, 23, v15
	v_add_u32_e32 v15, v14, v15
	v_ashrrev_i32_e32 v15, 9, v15
	v_mul_i32_i24_e32 v18, 0x200, v15
	v_sub_u32_e32 v18, v14, v18
	v_lshlrev_b32_e32 v14, 14, v15
	v_lshlrev_b32_e32 v15, 1, v18
	v_bfrev_b32_e32 v15, v15
	v_lshrrev_b32_e32 v15, 22, v15
	v_sub_u32_e32 v15, 0x400, v15
	v_bfrev_b32_e32 v15, v15
	v_lshrrev_b32_e32 v15, 18, v15
	v_and_b32_e32 v15, 0x3ff0, v15
	v_cmp_eq_u32_e64 s[0:1], 0, v18
	v_lshl_add_u32 v22, v18, 5, v14
	v_lshl_add_u32 v23, v22, 3, 0
	v_cndmask_b32_e64 v15, v15, 16, s[0:1]
	v_or_b32_e32 v14, v15, v14
	v_ashrrev_i32_e32 v22, 2, v22
	v_ashrrev_i32_e32 v15, 5, v14
	v_add_u32_e32 v211, v23, v22
	v_lshlrev_b32_e32 v14, 3, v14
	v_lshlrev_b32_e32 v15, 3, v15
	v_add3_u32 v212, 0, v14, v15
	ds_read2_b64 v[38:41], v211 offset1:1
	ds_read2_b64 v[42:45], v211 offset0:2 offset1:3
	ds_read2_b64 v[48:51], v212 offset1:1
	ds_read2_b64 v[52:55], v212 offset0:2 offset1:3
	ds_read2_b64 v[56:59], v211 offset0:4 offset1:5
	ds_read2_b64 v[60:63], v211 offset0:6 offset1:7
	ds_read2_b64 v[68:71], v212 offset0:4 offset1:5
	ds_read2_b64 v[72:75], v212 offset0:6 offset1:7
	ds_read2_b64 v[64:67], v211 offset0:8 offset1:9
	ds_read2_b64 v[76:79], v211 offset0:10 offset1:11
	ds_read2_b64 v[80:83], v212 offset0:8 offset1:9
	ds_read2_b64 v[98:101], v212 offset0:10 offset1:11
	ds_read2_b64 v[84:87], v211 offset0:12 offset1:13
	ds_read2_b64 v[88:91], v211 offset0:14 offset1:15
	ds_read2_b64 v[102:105], v212 offset0:12 offset1:13
	ds_read2_b64 v[106:109], v212 offset0:14 offset1:15
	s_waitcnt lgkmcnt(7)
	v_pk_add_f32 v[14:15], v[38:39], v[64:65]
	v_pk_add_f32 v[22:23], v[38:39], v[64:65] neg_lo:[0,1] neg_hi:[0,1]
	v_pk_add_f32 v[38:39], v[40:41], v[66:67] neg_lo:[0,1] neg_hi:[0,1]
	v_pk_add_f32 v[34:35], v[40:41], v[66:67]
	v_pk_mul_f32 v[40:41], v[38:39], s[18:19]
	v_cmp_ne_u32_e32 vcc, 0, v18
	v_pk_fma_f32 v[38:39], v[38:39], s[16:17], v[40:41] op_sel:[0,0,1] op_sel_hi:[1,0,0]
	s_waitcnt lgkmcnt(6)
	v_pk_add_f32 v[40:41], v[42:43], v[76:77]
	v_pk_add_f32 v[42:43], v[42:43], v[76:77] neg_lo:[0,1] neg_hi:[0,1]
	v_bfrev_b32_e32 v18, v18
	v_pk_mul_f32 v[64:65], v[42:43], s[36:37]
	v_lshrrev_b32_e32 v18, 23, v18
	v_pk_fma_f32 v[42:43], v[42:43], s[78:79], v[64:65] op_sel:[0,0,1] op_sel_hi:[1,0,0]
	v_pk_add_f32 v[64:65], v[44:45], v[78:79]
	v_pk_add_f32 v[44:45], v[44:45], v[78:79] neg_lo:[0,1] neg_hi:[0,1]
	s_waitcnt lgkmcnt(3)
	v_pk_add_f32 v[78:79], v[58:59], v[86:87]
	v_pk_mul_f32 v[66:67], v[44:45], s[40:41]
	v_pk_add_f32 v[58:59], v[58:59], v[86:87] neg_lo:[0,1] neg_hi:[0,1]
	v_pk_fma_f32 v[44:45], v[44:45], s[80:81], v[66:67] op_sel:[0,0,1] op_sel_hi:[1,0,0]
	v_pk_add_f32 v[66:67], v[56:57], v[84:85]
	v_pk_add_f32 v[76:77], v[56:57], v[84:85] neg_lo:[0,1] neg_hi:[0,1]
	v_pk_mul_f32 v[84:85], v[58:59], s[40:41]
	s_nop 0
	v_pk_fma_f32 v[58:59], v[58:59], s[80:81], v[84:85] op_sel:[0,0,1] op_sel_hi:[1,0,0] neg_lo:[1,0,0] neg_hi:[1,0,0]
	s_waitcnt lgkmcnt(2)
	v_pk_add_f32 v[84:85], v[60:61], v[88:89]
	v_pk_add_f32 v[60:61], v[60:61], v[88:89] neg_lo:[0,1] neg_hi:[0,1]
	s_nop 0
	v_pk_mul_f32 v[86:87], v[60:61], s[36:37]
	v_pk_add_f32 v[56:57], v[22:23], v[76:77] op_sel:[0,1] op_sel_hi:[1,0] neg_hi:[0,1]
	v_pk_fma_f32 v[60:61], v[60:61], s[78:79], v[86:87] op_sel:[0,0,1] op_sel_hi:[1,0,0] neg_lo:[1,0,0] neg_hi:[1,0,0]
	v_pk_add_f32 v[86:87], v[62:63], v[90:91]
	v_pk_add_f32 v[62:63], v[62:63], v[90:91] neg_lo:[0,1] neg_hi:[0,1]
	v_pk_add_f32 v[90:91], v[64:65], v[86:87]
	v_pk_mul_f32 v[88:89], v[62:63], s[18:19]
	v_pk_add_f32 v[64:65], v[64:65], v[86:87] neg_lo:[0,1] neg_hi:[0,1]
	v_pk_fma_f32 v[62:63], v[62:63], s[16:17], v[88:89] op_sel:[0,0,1] op_sel_hi:[1,0,0] neg_lo:[1,0,0] neg_hi:[1,0,0]
	v_pk_add_f32 v[88:89], v[14:15], v[66:67]
	v_pk_add_f32 v[14:15], v[14:15], v[66:67] neg_lo:[0,1] neg_hi:[0,1]
	v_pk_add_f32 v[66:67], v[34:35], v[78:79]
	v_pk_add_f32 v[34:35], v[34:35], v[78:79] neg_lo:[0,1] neg_hi:[0,1]
	v_pk_add_f32 v[22:23], v[22:23], v[76:77] op_sel:[0,1] op_sel_hi:[1,0] neg_lo:[0,1]
	v_pk_mul_f32 v[78:79], v[34:35], s[36:37]
	v_pk_add_f32 v[76:77], v[38:39], v[58:59]
	v_pk_add_f32 v[38:39], v[38:39], v[58:59] neg_lo:[0,1] neg_hi:[0,1]
	v_pk_fma_f32 v[34:35], v[34:35], s[78:79], v[78:79] op_sel:[0,0,1] op_sel_hi:[1,0,0]
	v_pk_add_f32 v[78:79], v[40:41], v[84:85]
	v_pk_add_f32 v[84:85], v[40:41], v[84:85] neg_lo:[0,1] neg_hi:[0,1]
	v_pk_mul_f32 v[86:87], v[64:65], s[36:37]
	v_pk_mul_f32 v[58:59], v[38:39], s[36:37]
	v_pk_fma_f32 v[64:65], v[64:65], s[78:79], v[86:87] op_sel:[0,0,1] op_sel_hi:[1,0,0] neg_lo:[1,0,0] neg_hi:[1,0,0]
	v_pk_fma_f32 v[38:39], v[38:39], s[78:79], v[58:59] op_sel:[0,0,1] op_sel_hi:[1,0,0]
	v_pk_add_f32 v[58:59], v[42:43], v[60:61]
	v_pk_add_f32 v[86:87], v[44:45], v[62:63]
	v_pk_add_f32 v[44:45], v[44:45], v[62:63] neg_lo:[0,1] neg_hi:[0,1]
	s_nop 0
	v_pk_mul_f32 v[62:63], v[44:45], s[36:37]
	v_pk_add_f32 v[40:41], v[14:15], v[84:85] op_sel:[0,1] op_sel_hi:[1,0] neg_hi:[0,1]
	v_pk_add_f32 v[14:15], v[14:15], v[84:85] op_sel:[0,1] op_sel_hi:[1,0] neg_lo:[0,1]
	v_pk_add_f32 v[84:85], v[34:35], v[64:65]
	v_pk_add_f32 v[64:65], v[34:35], v[64:65] neg_lo:[0,1] neg_hi:[0,1]
	v_pk_add_f32 v[94:95], v[56:57], v[58:59]
	v_pk_add_f32 v[56:57], v[56:57], v[58:59] neg_lo:[0,1] neg_hi:[0,1]
	v_pk_add_f32 v[58:59], v[76:77], v[86:87]
	v_pk_fma_f32 v[44:45], v[44:45], s[78:79], v[62:63] op_sel:[0,0,1] op_sel_hi:[1,0,0] neg_lo:[1,0,0] neg_hi:[1,0,0]
	v_pk_add_f32 v[62:63], v[88:89], v[78:79]
	v_pk_add_f32 v[78:79], v[88:89], v[78:79] neg_lo:[0,1] neg_hi:[0,1]
	v_pk_add_f32 v[88:89], v[66:67], v[90:91]
	v_pk_add_f32 v[110:111], v[76:77], v[86:87] neg_lo:[0,1] neg_hi:[0,1]
	v_pk_add_f32 v[86:87], v[94:95], v[58:59]
	v_pk_add_f32 v[34:35], v[94:95], v[58:59] neg_lo:[0,1] neg_hi:[0,1]
	v_pk_add_f32 v[58:59], v[50:51], v[82:83]
	v_pk_add_f32 v[50:51], v[50:51], v[82:83] neg_lo:[0,1] neg_hi:[0,1]
	v_pk_add_f32 v[60:61], v[42:43], v[60:61] neg_lo:[0,1] neg_hi:[0,1]
	v_pk_add_f32 v[148:149], v[62:63], v[88:89]
	v_pk_add_f32 v[138:139], v[62:63], v[88:89] neg_lo:[0,1] neg_hi:[0,1]
	v_pk_mul_f32 v[62:63], v[50:51], s[18:19]
	v_pk_add_f32 v[90:91], v[66:67], v[90:91] neg_lo:[0,1] neg_hi:[0,1]
	v_pk_fma_f32 v[50:51], v[50:51], s[16:17], v[62:63] op_sel:[0,0,1] op_sel_hi:[1,0,0]
	v_pk_add_f32 v[62:63], v[52:53], v[98:99]
	v_pk_add_f32 v[52:53], v[52:53], v[98:99] neg_lo:[0,1] neg_hi:[0,1]
	v_pk_add_f32 v[112:113], v[22:23], v[60:61] op_sel:[0,1] op_sel_hi:[1,0] neg_hi:[0,1]
	v_pk_add_f32 v[114:115], v[22:23], v[60:61] op_sel:[0,1] op_sel_hi:[1,0] neg_lo:[0,1]
	v_pk_add_f32 v[96:97], v[40:41], v[84:85]
	v_pk_add_f32 v[66:67], v[40:41], v[84:85] neg_lo:[0,1] neg_hi:[0,1]
	v_pk_add_f32 v[60:61], v[14:15], v[64:65] op_sel:[0,1] op_sel_hi:[1,0] neg_hi:[0,1]
	v_pk_add_f32 v[84:85], v[14:15], v[64:65] op_sel:[0,1] op_sel_hi:[1,0] neg_lo:[0,1]
	v_pk_mul_f32 v[64:65], v[52:53], s[36:37]
	s_nop 0
	v_pk_fma_f32 v[52:53], v[52:53], s[78:79], v[64:65] op_sel:[0,0,1] op_sel_hi:[1,0,0]
	v_pk_add_f32 v[64:65], v[54:55], v[100:101]
	v_pk_add_f32 v[54:55], v[54:55], v[100:101] neg_lo:[0,1] neg_hi:[0,1]
	s_nop 0
	v_pk_mul_f32 v[76:77], v[54:55], s[40:41]
	v_pk_add_f32 v[92:93], v[78:79], v[90:91] op_sel:[0,1] op_sel_hi:[1,0] neg_hi:[0,1]
	v_pk_fma_f32 v[54:55], v[54:55], s[80:81], v[76:77] op_sel:[0,0,1] op_sel_hi:[1,0,0]
	s_waitcnt lgkmcnt(1)
	v_pk_add_f32 v[76:77], v[68:69], v[102:103]
	v_pk_add_f32 v[68:69], v[68:69], v[102:103] neg_lo:[0,1] neg_hi:[0,1]
	v_pk_add_f32 v[88:89], v[78:79], v[90:91] op_sel:[0,1] op_sel_hi:[1,0] neg_lo:[0,1]
	v_xor_b32_e32 v79, 0x80000000, v68
	v_mov_b32_e32 v78, v69
	v_pk_add_f32 v[68:69], v[70:71], v[104:105]
	v_pk_add_f32 v[70:71], v[70:71], v[104:105] neg_lo:[0,1] neg_hi:[0,1]
	v_pk_add_f32 v[22:23], v[38:39], v[44:45]
	v_pk_add_f32 v[116:117], v[38:39], v[44:45] neg_lo:[0,1] neg_hi:[0,1]
	v_pk_add_f32 v[40:41], v[56:57], v[110:111] op_sel:[0,1] op_sel_hi:[1,0] neg_hi:[0,1]
	v_pk_add_f32 v[44:45], v[56:57], v[110:111] op_sel:[0,1] op_sel_hi:[1,0] neg_lo:[0,1]
	v_pk_add_f32 v[56:57], v[48:49], v[80:81]
	v_pk_add_f32 v[48:49], v[48:49], v[80:81] neg_lo:[0,1] neg_hi:[0,1]
	v_pk_mul_f32 v[80:81], v[70:71], s[40:41]
	v_cvt_f32_u32_e32 v18, v18
	v_pk_fma_f32 v[70:71], v[70:71], s[80:81], v[80:81] op_sel:[0,0,1] op_sel_hi:[1,0,0] neg_lo:[1,0,0] neg_hi:[1,0,0]
	s_waitcnt lgkmcnt(0)
	v_pk_add_f32 v[80:81], v[72:73], v[106:107]
	v_pk_add_f32 v[72:73], v[72:73], v[106:107] neg_lo:[0,1] neg_hi:[0,1]
	v_mul_f32_e32 v18, 0x38000000, v18
	v_pk_mul_f32 v[82:83], v[72:73], s[36:37]
	v_cndmask_b32_e64 v18, v18, v208, s[0:1]
	v_pk_fma_f32 v[72:73], v[72:73], s[78:79], v[82:83] op_sel:[0,0,1] op_sel_hi:[1,0,0] neg_lo:[1,0,0] neg_hi:[1,0,0]
	v_pk_add_f32 v[82:83], v[74:75], v[108:109]
	v_pk_add_f32 v[74:75], v[74:75], v[108:109] neg_lo:[0,1] neg_hi:[0,1]
	s_nop 0
	v_pk_mul_f32 v[90:91], v[74:75], s[18:19]
	s_nop 0
	v_pk_fma_f32 v[74:75], v[74:75], s[16:17], v[90:91] op_sel:[0,0,1] op_sel_hi:[1,0,0] neg_lo:[1,0,0] neg_hi:[1,0,0]
	v_pk_add_f32 v[90:91], v[56:57], v[76:77]
	v_pk_add_f32 v[56:57], v[56:57], v[76:77] neg_lo:[0,1] neg_hi:[0,1]
	v_pk_add_f32 v[76:77], v[58:59], v[68:69]
	v_pk_add_f32 v[58:59], v[58:59], v[68:69] neg_lo:[0,1] neg_hi:[0,1]
	v_pk_add_f32 v[14:15], v[114:115], v[116:117] op_sel:[0,1] op_sel_hi:[1,0] neg_hi:[0,1]
	v_pk_mul_f32 v[68:69], v[58:59], s[36:37]
	v_pk_add_f32 v[38:39], v[114:115], v[116:117] op_sel:[0,1] op_sel_hi:[1,0] neg_lo:[0,1]
	v_pk_fma_f32 v[58:59], v[58:59], s[78:79], v[68:69] op_sel:[0,0,1] op_sel_hi:[1,0,0]
	v_pk_add_f32 v[68:69], v[62:63], v[80:81]
	v_pk_add_f32 v[80:81], v[62:63], v[80:81] neg_lo:[0,1] neg_hi:[0,1]
	s_waitcnt vmcnt(0)
	v_cvt_f32_f16_e32 v193, v33
	s_nop 0
	s_nop 0
	v_pk_add_f32 v[62:63], v[64:65], v[82:83]
	v_pk_add_f32 v[64:65], v[64:65], v[82:83] neg_lo:[0,1] neg_hi:[0,1]
	v_cvt_f32_f16_sdwa v192, v32 dst_sel:DWORD dst_unused:UNUSED_PAD src0_sel:WORD_1
	v_pk_mul_f32 v[82:83], v[64:65], s[36:37]
	v_cvt_f32_f16_e32 v194, v32
	v_pk_fma_f32 v[64:65], v[64:65], s[78:79], v[82:83] op_sel:[0,0,1] op_sel_hi:[1,0,0] neg_lo:[1,0,0] neg_hi:[1,0,0]
	v_pk_add_f32 v[82:83], v[48:49], v[78:79]
	v_pk_add_f32 v[48:49], v[48:49], v[78:79] neg_lo:[0,1] neg_hi:[0,1]
	v_pk_add_f32 v[78:79], v[50:51], v[70:71]
	v_pk_add_f32 v[50:51], v[50:51], v[70:71] neg_lo:[0,1] neg_hi:[0,1]
	v_cvt_f32_f16_sdwa v195, v33 dst_sel:DWORD dst_unused:UNUSED_PAD src0_sel:WORD_1
	v_pk_mul_f32 v[70:71], v[50:51], s[36:37]
	v_cvt_f32_f16_sdwa v170, v30 dst_sel:DWORD dst_unused:UNUSED_PAD src0_sel:WORD_1
	v_pk_fma_f32 v[50:51], v[50:51], s[78:79], v[70:71] op_sel:[0,0,1] op_sel_hi:[1,0,0]
	v_pk_add_f32 v[70:71], v[52:53], v[72:73]
	v_pk_add_f32 v[72:73], v[52:53], v[72:73] neg_lo:[0,1] neg_hi:[0,1]
	v_cvt_f32_f16_e32 v171, v31
	s_nop 0
	s_nop 0
	v_pk_add_f32 v[52:53], v[54:55], v[74:75]
	v_pk_add_f32 v[54:55], v[54:55], v[74:75] neg_lo:[0,1] neg_hi:[0,1]
	v_cvt_f32_f16_sdwa v185, v31 dst_sel:DWORD dst_unused:UNUSED_PAD src0_sel:WORD_1
	v_pk_mul_f32 v[74:75], v[54:55], s[36:37]
	v_cvt_f32_f16_e32 v184, v30
	v_pk_fma_f32 v[54:55], v[54:55], s[78:79], v[74:75] op_sel:[0,0,1] op_sel_hi:[1,0,0] neg_lo:[1,0,0] neg_hi:[1,0,0]
	v_pk_add_f32 v[74:75], v[90:91], v[68:69]
	v_pk_add_f32 v[68:69], v[90:91], v[68:69] neg_lo:[0,1] neg_hi:[0,1]
	v_pk_add_f32 v[90:91], v[76:77], v[62:63]
	v_pk_add_f32 v[62:63], v[76:77], v[62:63] neg_lo:[0,1] neg_hi:[0,1]
	v_cvt_f32_f16_sdwa v172, v28 dst_sel:DWORD dst_unused:UNUSED_PAD src0_sel:WORD_1
	v_xor_b32_e32 v77, 0x80000000, v62
	v_mov_b32_e32 v76, v63
	v_pk_add_f32 v[62:63], v[56:57], v[80:81] op_sel:[0,1] op_sel_hi:[1,0] neg_hi:[0,1]
	v_pk_add_f32 v[56:57], v[56:57], v[80:81] op_sel:[0,1] op_sel_hi:[1,0] neg_lo:[0,1]
	v_pk_add_f32 v[80:81], v[58:59], v[64:65]
	v_pk_add_f32 v[58:59], v[58:59], v[64:65] neg_lo:[0,1] neg_hi:[0,1]
	v_cvt_f32_f16_e32 v173, v29
	v_xor_b32_e32 v65, 0x80000000, v58
	v_mov_b32_e32 v64, v59
	v_pk_add_f32 v[58:59], v[82:83], v[70:71]
	v_pk_add_f32 v[70:71], v[82:83], v[70:71] neg_lo:[0,1] neg_hi:[0,1]
	v_pk_add_f32 v[82:83], v[78:79], v[52:53]
	v_pk_add_f32 v[52:53], v[78:79], v[52:53] neg_lo:[0,1] neg_hi:[0,1]
	v_pk_add_f32 v[118:119], v[58:59], v[82:83]
	v_pk_add_f32 v[134:135], v[58:59], v[82:83] neg_lo:[0,1] neg_hi:[0,1]
	v_cos_f32_e32 v83, v18
	v_sin_f32_e32 v82, v18
	v_cvt_f32_f16_sdwa v181, v29 dst_sel:DWORD dst_unused:UNUSED_PAD src0_sel:WORD_1
	v_cvt_f32_f16_e32 v180, v28
	v_cvt_f32_f16_sdwa v167, v13 dst_sel:DWORD dst_unused:UNUSED_PAD src0_sel:WORD_1
	v_cvt_f32_f16_e32 v166, v12
	v_cvt_f32_f16_e32 v154, v6
	v_cvt_f32_f16_e32 v155, v7
	v_cvt_f32_f16_sdwa v157, v7 dst_sel:DWORD dst_unused:UNUSED_PAD src0_sel:WORD_1
	v_cvt_f32_f16_sdwa v156, v6 dst_sel:DWORD dst_unused:UNUSED_PAD src0_sel:WORD_1
	v_cvt_f32_f16_sdwa v140, v4 dst_sel:DWORD dst_unused:UNUSED_PAD src0_sel:WORD_1
	v_cvt_f32_f16_e32 v141, v5
	v_cvt_f32_f16_sdwa v143, v5 dst_sel:DWORD dst_unused:UNUSED_PAD src0_sel:WORD_1
	v_cvt_f32_f16_e32 v142, v4
	v_cvt_f32_f16_e32 v124, v16
	v_cvt_f32_f16_e32 v125, v17
	v_cvt_f32_f16_sdwa v127, v17 dst_sel:DWORD dst_unused:UNUSED_PAD src0_sel:WORD_1
	v_cvt_f32_f16_sdwa v126, v16 dst_sel:DWORD dst_unused:UNUSED_PAD src0_sel:WORD_1
	v_cvt_f32_f16_sdwa v114, v122 dst_sel:DWORD dst_unused:UNUSED_PAD src0_sel:WORD_1
	v_cvt_f32_f16_e32 v115, v123
	v_cvt_f32_f16_sdwa v117, v123 dst_sel:DWORD dst_unused:UNUSED_PAD src0_sel:WORD_1
	v_cvt_f32_f16_e32 v116, v122
	v_xor_b32_e32 v79, 0x80000000, v52
	v_mov_b32_e32 v78, v53
	v_pk_add_f32 v[52:53], v[48:49], v[72:73] op_sel:[0,1] op_sel_hi:[1,0] neg_hi:[0,1]
	v_pk_add_f32 v[48:49], v[48:49], v[72:73] op_sel:[0,1] op_sel_hi:[1,0] neg_lo:[0,1]
	v_pk_add_f32 v[72:73], v[50:51], v[54:55]
	v_pk_add_f32 v[50:51], v[50:51], v[54:55] neg_lo:[0,1] neg_hi:[0,1]
	v_pk_fma_f32 v[160:161], v[82:83], 0, v[82:83] op_sel:[0,0,1] op_sel_hi:[1,0,0] neg_lo:[1,0,0] neg_hi:[1,0,0]
	v_xor_b32_e32 v55, 0x80000000, v50
	v_mov_b32_e32 v54, v51
	v_pk_fma_f32 v[198:199], v[82:83], 0, v[82:83] op_sel:[0,0,1] op_sel_hi:[1,0,0]
	v_pk_add_f32 v[42:43], v[112:113], v[22:23]
	v_pk_add_f32 v[22:23], v[112:113], v[22:23] neg_lo:[0,1] neg_hi:[0,1]
	v_pk_add_f32 v[98:99], v[74:75], v[90:91]
	v_pk_add_f32 v[100:101], v[74:75], v[90:91] neg_lo:[0,1] neg_hi:[0,1]
	v_pk_add_f32 v[102:103], v[68:69], v[76:77]
	v_pk_add_f32 v[106:107], v[68:69], v[76:77] neg_lo:[0,1] neg_hi:[0,1]
	v_pk_add_f32 v[104:105], v[62:63], v[80:81]
	v_pk_add_f32 v[108:109], v[62:63], v[80:81] neg_lo:[0,1] neg_hi:[0,1]
	v_pk_add_f32 v[110:111], v[56:57], v[64:65]
	v_pk_add_f32 v[112:113], v[56:57], v[64:65] neg_lo:[0,1] neg_hi:[0,1]
	v_pk_add_f32 v[152:153], v[70:71], v[78:79]
	v_pk_add_f32 v[162:163], v[70:71], v[78:79] neg_lo:[0,1] neg_hi:[0,1]
	v_pk_add_f32 v[178:179], v[52:53], v[72:73]
	v_pk_add_f32 v[182:183], v[52:53], v[72:73] neg_lo:[0,1] neg_hi:[0,1]
	v_pk_add_f32 v[188:189], v[48:49], v[54:55]
	v_pk_add_f32 v[196:197], v[48:49], v[54:55] neg_lo:[0,1] neg_hi:[0,1]
	v_pk_mul_f32 v[186:187], v[82:83], 0 op_sel_hi:[1,0]
	v_mov_b32_e32 v190, v160
	v_mov_b32_e32 v191, v199
	v_mul_f32_e32 v18, 0x3f3504f3, v83
	v_mul_f32_e32 v158, 0xbec3ef15, v83
	v_mul_f32_e32 v132, 0xbf6c835e, v83
	s_and_saveexec_b64 s[0:1], vcc
	s_xor_b64 s[0:1], exec, s[0:1]
	s_cbranch_execz .LBB0_501
	v_pk_add_f32 v[4:5], v[148:149], v[196:197]
	v_pk_add_f32 v[6:7], v[148:149], v[196:197] neg_lo:[0,1] neg_hi:[0,1]
	v_mul_f32_e32 v4, 0.5, v4
	v_mul_f32_e32 v12, 0.5, v7
	v_mov_b32_e32 v7, v5
	v_pk_mul_f32 v[6:7], v[6:7], s[44:45]
	v_pk_mov_b32 v[16:17], v[198:199], v[160:161] op_sel:[1,0]
	v_pk_mul_f32 v[24:25], v[190:191], v[6:7] op_sel:[0,1] op_sel_hi:[1,0]
	v_pk_mul_f32 v[6:7], v[190:191], v[6:7]
	v_pk_add_f32 v[24:25], v[24:25], v[24:25] op_sel:[0,1] op_sel_hi:[0,1]
	v_pk_add_f32 v[28:29], v[4:5], v[24:25] op_sel_hi:[0,1] neg_hi:[0,1]
	v_pk_add_f32 v[4:5], v[6:7], v[6:7] op_sel:[0,1] op_sel_hi:[0,1] neg_lo:[0,1] neg_hi:[0,1]
	v_pk_add_f32 v[6:7], v[12:13], v[4:5] op_sel_hi:[0,1] neg_hi:[0,1]
	v_pk_mul_f32 v[4:5], v[6:7], v[194:195]
	v_pk_mul_f32 v[6:7], v[6:7], v[192:193]
	v_pk_fma_f32 v[4:5], v[28:29], v[192:193], v[4:5]
	v_pk_fma_f32 v[6:7], v[28:29], v[194:195], v[6:7] neg_lo:[0,0,1] neg_hi:[0,0,1]
	s_mov_b32 s78, s19
	v_pk_add_f32 v[12:13], v[6:7], v[4:5] op_sel:[0,1] op_sel_hi:[1,0] neg_lo:[0,1]
	v_pk_add_f32 v[28:29], v[6:7], v[4:5] op_sel:[0,1] op_sel_hi:[1,0]
	v_pk_add_f32 v[4:5], v[4:5], v[6:7] op_sel:[1,0] op_sel_hi:[0,1] neg_lo:[0,1] neg_hi:[0,1]
	s_nop 0
	v_pk_mul_f32 v[12:13], v[12:13], 0.5 op_sel_hi:[1,0]
	v_mov_b32_e32 v29, v5
	v_mul_f32_e32 v24, v190, v12
	v_pk_fma_f32 v[30:31], v[190:191], v[12:13], v[24:25] op_sel_hi:[1,1,0] neg_lo:[1,0,0] neg_hi:[1,0,0]
	v_mul_f32_e32 v24, v160, v13
	v_pk_fma_f32 v[12:13], v[16:17], v[12:13], v[24:25] op_sel_hi:[1,1,0]
	v_mov_b32_e32 v16, v83
	v_mov_b32_e32 v30, v12
	v_pk_fma_f32 v[4:5], v[28:29], 0.5, v[12:13] op_sel_hi:[1,0,1] neg_lo:[0,0,1] neg_hi:[0,0,1]
	v_pk_fma_f32 v[122:123], v[28:29], 0.5, v[30:31] op_sel_hi:[1,0,1]
	v_pk_fma_f32 v[6:7], v[28:29], 0.5, v[30:31] op_sel_hi:[1,0,1] neg_lo:[1,0,0] neg_hi:[1,0,0]
	v_mov_b32_e32 v5, v123
	v_pk_mul_f32 v[24:25], v[4:5], s[6:7] op_sel_hi:[1,0]
	v_pk_add_f32 v[4:5], v[138:139], v[188:189]
	v_pk_add_f32 v[12:13], v[138:139], v[188:189] neg_lo:[0,1] neg_hi:[0,1]
	v_mov_b32_e32 v17, v82
	v_mul_f32_e32 v6, 0.5, v13
	v_pk_add_f32 v[28:29], v[186:187], v[16:17] neg_lo:[0,1] neg_hi:[0,1]
	v_pk_add_f32 v[30:31], v[186:187], v[16:17]
	v_mov_b32_e32 v13, v5
	v_pk_mov_b32 v[32:33], v[28:29], v[30:31] op_sel:[1,0]
	v_pk_mul_f32 v[12:13], v[12:13], s[44:45]
	v_mul_f32_e32 v4, 0.5, v4
	v_pk_mul_f32 v[48:49], v[32:33], v[12:13] op_sel:[0,1] op_sel_hi:[1,0]
	v_pk_mul_f32 v[12:13], v[32:33], v[12:13]
	v_pk_add_f32 v[48:49], v[48:49], v[48:49] op_sel:[0,1] op_sel_hi:[0,1]
	v_pk_add_f32 v[50:51], v[4:5], v[48:49] op_sel_hi:[0,1] neg_hi:[0,1]
	v_pk_add_f32 v[4:5], v[12:13], v[12:13] op_sel:[0,1] op_sel_hi:[0,1] neg_lo:[0,1] neg_hi:[0,1]
	v_pk_add_f32 v[12:13], v[6:7], v[4:5] op_sel_hi:[0,1] neg_hi:[0,1]
	v_pk_mul_f32 v[4:5], v[12:13], v[184:185]
	v_pk_mul_f32 v[12:13], v[12:13], v[170:171]
	v_pk_fma_f32 v[4:5], v[50:51], v[170:171], v[4:5]
	v_pk_fma_f32 v[12:13], v[50:51], v[184:185], v[12:13] neg_lo:[0,0,1] neg_hi:[0,0,1]
	v_mov_b32_e32 v31, v29
	v_pk_add_f32 v[48:49], v[12:13], v[4:5] op_sel:[0,1] op_sel_hi:[1,0] neg_lo:[0,1]
	v_pk_add_f32 v[50:51], v[12:13], v[4:5] op_sel:[0,1] op_sel_hi:[1,0]
	v_pk_add_f32 v[4:5], v[4:5], v[12:13] op_sel:[1,0] op_sel_hi:[0,1] neg_lo:[0,1] neg_hi:[0,1]
	v_pk_mul_f32 v[48:49], v[48:49], 0.5 op_sel_hi:[1,0]
	v_mov_b32_e32 v51, v5
	v_mul_f32_e32 v6, v29, v48
	v_pk_fma_f32 v[32:33], v[32:33], v[48:49], v[6:7] op_sel_hi:[1,1,0] neg_lo:[1,0,0] neg_hi:[1,0,0]
	v_mul_f32_e32 v6, v29, v49
	v_pk_fma_f32 v[28:29], v[30:31], v[48:49], v[6:7] op_sel_hi:[1,1,0]
	v_pk_mul_f32 v[12:13], v[16:17], s[36:37]
	v_mov_b32_e32 v32, v28
	v_pk_fma_f32 v[4:5], v[50:51], 0.5, v[28:29] op_sel_hi:[1,0,1] neg_lo:[0,0,1] neg_hi:[0,0,1]
	v_pk_fma_f32 v[138:139], v[50:51], 0.5, v[32:33] op_sel_hi:[1,0,1]
	v_pk_add_f32 v[16:17], v[92:93], v[182:183]
	v_mov_b32_e32 v5, v139
	v_pk_add_f32 v[28:29], v[92:93], v[182:183] neg_lo:[0,1] neg_hi:[0,1]
	v_pk_mul_f32 v[30:31], v[4:5], s[6:7] op_sel_hi:[1,0]
	v_pk_fma_f32 v[4:5], v[50:51], 0.5, v[32:33] op_sel_hi:[1,0,1] neg_lo:[1,0,0] neg_hi:[1,0,0]
	v_mul_f32_e32 v6, 0.5, v29
	v_pk_add_f32 v[32:33], v[18:19], v[12:13] op_sel:[0,1] op_sel_hi:[0,1] neg_lo:[0,1] neg_hi:[0,1]
	v_pk_add_f32 v[48:49], v[18:19], v[12:13] op_sel:[0,1] op_sel_hi:[0,1]
	v_mov_b32_e32 v29, v17
	v_mul_f32_e32 v4, 0.5, v16
	v_mov_b32_e32 v50, v32
	v_mov_b32_e32 v51, v49
	v_pk_mul_f32 v[16:17], v[28:29], s[44:45]
	v_pk_mov_b32 v[48:49], v[48:49], v[32:33] op_sel:[1,0]
	v_pk_mul_f32 v[28:29], v[50:51], v[16:17] op_sel:[0,1] op_sel_hi:[1,0]
	v_pk_mul_f32 v[16:17], v[50:51], v[16:17]
	v_pk_add_f32 v[28:29], v[28:29], v[28:29] op_sel:[0,1] op_sel_hi:[0,1]
	v_pk_add_f32 v[52:53], v[4:5], v[28:29] op_sel_hi:[0,1] neg_hi:[0,1]
	v_pk_add_f32 v[16:17], v[16:17], v[16:17] op_sel:[0,1] op_sel_hi:[0,1] neg_lo:[0,1] neg_hi:[0,1]
	v_pk_add_f32 v[28:29], v[6:7], v[16:17] op_sel_hi:[0,1] neg_hi:[0,1]
	v_pk_mul_f32 v[16:17], v[28:29], v[180:181]
	v_pk_mul_f32 v[28:29], v[28:29], v[172:173]
	v_pk_fma_f32 v[16:17], v[52:53], v[172:173], v[16:17]
	v_pk_fma_f32 v[28:29], v[52:53], v[180:181], v[28:29] neg_lo:[0,0,1] neg_hi:[0,0,1]
	v_sub_f32_e32 v6, v89, v179
	v_pk_add_f32 v[52:53], v[28:29], v[16:17] op_sel:[0,1] op_sel_hi:[1,0] neg_lo:[0,1]
	v_pk_add_f32 v[54:55], v[28:29], v[16:17] op_sel:[0,1] op_sel_hi:[1,0]
	v_pk_add_f32 v[16:17], v[16:17], v[28:29] op_sel:[1,0] op_sel_hi:[0,1] neg_lo:[0,1] neg_hi:[0,1]
	v_pk_mul_f32 v[52:53], v[52:53], 0.5 op_sel_hi:[1,0]
	v_mov_b32_e32 v55, v17
	v_mul_f32_e32 v4, v32, v52
	v_pk_fma_f32 v[56:57], v[50:51], v[52:53], v[4:5] op_sel_hi:[1,1,0] neg_lo:[1,0,0] neg_hi:[1,0,0]
	v_mul_f32_e32 v4, v32, v53
	v_pk_fma_f32 v[48:49], v[48:49], v[52:53], v[4:5] op_sel_hi:[1,1,0]
	v_pk_add_f32 v[28:29], v[88:89], v[178:179]
	v_mov_b32_e32 v56, v48
	v_pk_fma_f32 v[16:17], v[54:55], 0.5, v[48:49] op_sel_hi:[1,0,1] neg_lo:[0,0,1] neg_hi:[0,0,1]
	v_mov_b32_e32 v48, v12
	v_mov_b32_e32 v49, v88
	v_pk_mov_b32 v[12:13], v[12:13], v[178:179] op_sel:[1,0]
	v_mul_f32_e32 v18, 0.5, v29
	v_pk_add_f32 v[12:13], v[48:49], v[12:13] neg_lo:[0,1] neg_hi:[0,1]
	v_mul_f32_e32 v4, 0.5, v28
	v_pk_mul_f32 v[48:49], v[12:13], v[18:19]
	v_mov_b32_e32 v13, v32
	v_pk_fma_f32 v[50:51], v[50:51], v[48:49], v[48:49] op_sel:[0,1,0] op_sel_hi:[1,0,1]
	v_mov_b32_e32 v48, v49
	v_mov_b32_e32 v49, v18
	v_pk_mul_f32 v[48:49], v[12:13], v[48:49]
	v_pk_add_f32 v[52:53], v[4:5], v[50:51]
	v_mul_f32_e32 v6, 0.5, v6
	v_fma_f32 v53, v28, 0.5, -v50
	v_pk_add_f32 v[28:29], v[48:49], v[48:49] op_sel:[0,1] op_sel_hi:[0,1] neg_lo:[0,1] neg_hi:[0,1]
	v_pk_add_f32 v[48:49], v[6:7], v[28:29] op_sel_hi:[0,1] neg_hi:[0,1]
	v_pk_mul_f32 v[28:29], v[48:49], v[176:177]
	v_pk_mul_f32 v[48:49], v[48:49], v[174:175]
	v_pk_fma_f32 v[28:29], v[52:53], v[174:175], v[28:29]
	v_pk_fma_f32 v[48:49], v[52:53], v[176:177], v[48:49] neg_lo:[0,0,1] neg_hi:[0,0,1]
	v_pk_fma_f32 v[92:93], v[54:55], 0.5, v[56:57] op_sel_hi:[1,0,1]
	v_pk_add_f32 v[50:51], v[48:49], v[28:29] op_sel:[0,1] op_sel_hi:[1,0] neg_lo:[0,1]
	v_pk_add_f32 v[52:53], v[48:49], v[28:29] op_sel:[0,1] op_sel_hi:[1,0]
	v_mov_b32_e32 v17, v93
	v_pk_mul_f32 v[50:51], v[50:51], 0.5 op_sel_hi:[1,0]
	v_pk_mul_f32 v[64:65], v[16:17], s[6:7] op_sel_hi:[1,0]
	v_mul_f32_e32 v4, v12, v50
	v_pk_fma_f32 v[16:17], v[54:55], 0.5, v[56:57] op_sel_hi:[1,0,1] neg_lo:[1,0,0] neg_hi:[1,0,0]
	v_pk_fma_f32 v[54:55], v[12:13], v[50:51], v[4:5] op_sel_hi:[1,1,0] neg_lo:[1,0,0] neg_hi:[1,0,0]
	v_mov_b32_e32 v33, v12
	v_mul_f32_e32 v4, v12, v51
	v_pk_fma_f32 v[12:13], v[32:33], v[50:51], v[4:5] op_sel_hi:[1,1,0]
	v_pk_add_f32 v[28:29], v[28:29], v[48:49] op_sel:[1,0] op_sel_hi:[0,1] neg_lo:[0,1] neg_hi:[0,1]
	v_mov_b32_e32 v53, v29
	v_mov_b32_e32 v54, v12
	v_pk_fma_f32 v[12:13], v[52:53], 0.5, v[12:13] op_sel_hi:[1,0,1] neg_lo:[0,0,1] neg_hi:[0,0,1]
	v_pk_fma_f32 v[88:89], v[52:53], 0.5, v[54:55] op_sel_hi:[1,0,1]
	s_mov_b32 s79, s16
	v_mov_b32_e32 v13, v89
	v_pk_mul_f32 v[68:69], v[12:13], s[6:7] op_sel_hi:[1,0]
	v_pk_fma_f32 v[12:13], v[52:53], 0.5, v[54:55] op_sel_hi:[1,0,1] neg_lo:[1,0,0] neg_hi:[1,0,0]
	v_mov_b32_e32 v4, v83
	s_mov_b32 s17, s19
	v_pk_mul_f32 v[48:49], v[82:83], s[78:79] op_sel_hi:[0,1]
	v_pk_add_f32 v[28:29], v[96:97], v[162:163]
	v_pk_add_f32 v[32:33], v[96:97], v[162:163] neg_lo:[0,1] neg_hi:[0,1]
	v_pk_fma_f32 v[52:53], v[4:5], s[16:17], v[48:49] op_sel_hi:[0,1,1] neg_lo:[0,0,1] neg_hi:[0,0,1]
	v_mul_f32_e32 v12, 0.5, v33
	v_pk_fma_f32 v[50:51], v[4:5], s[16:17], v[48:49] op_sel_hi:[0,1,1]
	v_mov_b32_e32 v33, v29
	v_mul_f32_e32 v6, 0.5, v28
	v_mov_b32_e32 v54, v52
	v_mov_b32_e32 v55, v51
	v_pk_mul_f32 v[28:29], v[32:33], s[44:45]
	v_pk_mov_b32 v[56:57], v[50:51], v[52:53] op_sel:[1,0]
	v_pk_mul_f32 v[32:33], v[54:55], v[28:29] op_sel:[0,1] op_sel_hi:[1,0]
	v_pk_mul_f32 v[28:29], v[54:55], v[28:29]
	v_pk_add_f32 v[32:33], v[32:33], v[32:33] op_sel:[0,1] op_sel_hi:[0,1]
	v_pk_add_f32 v[58:59], v[6:7], v[32:33] op_sel_hi:[0,1] neg_hi:[0,1]
	v_pk_add_f32 v[28:29], v[28:29], v[28:29] op_sel:[0,1] op_sel_hi:[0,1] neg_lo:[0,1] neg_hi:[0,1]
	v_pk_add_f32 v[32:33], v[12:13], v[28:29] op_sel_hi:[0,1] neg_hi:[0,1]
	v_pk_mul_f32 v[28:29], v[32:33], v[166:167]
	v_pk_mul_f32 v[32:33], v[32:33], v[164:165]
	v_pk_fma_f32 v[28:29], v[58:59], v[164:165], v[28:29]
	v_pk_fma_f32 v[32:33], v[58:59], v[166:167], v[32:33] neg_lo:[0,0,1] neg_hi:[0,0,1]
	v_mov_b32_e32 v159, v66
	v_pk_add_f32 v[58:59], v[32:33], v[28:29] op_sel:[0,1] op_sel_hi:[1,0] neg_lo:[0,1]
	v_pk_add_f32 v[70:71], v[32:33], v[28:29] op_sel:[0,1] op_sel_hi:[1,0]
	v_pk_add_f32 v[28:29], v[28:29], v[32:33] op_sel:[1,0] op_sel_hi:[0,1] neg_lo:[0,1] neg_hi:[0,1]
	v_pk_mul_f32 v[58:59], v[58:59], 0.5 op_sel_hi:[1,0]
	v_mov_b32_e32 v71, v29
	v_mul_f32_e32 v6, v52, v58
	v_pk_fma_f32 v[72:73], v[54:55], v[58:59], v[6:7] op_sel_hi:[1,1,0] neg_lo:[1,0,0] neg_hi:[1,0,0]
	v_mul_f32_e32 v6, v52, v59
	v_pk_fma_f32 v[56:57], v[56:57], v[58:59], v[6:7] op_sel_hi:[1,1,0]
	v_sub_f32_e32 v12, v67, v153
	v_mov_b32_e32 v72, v56
	v_pk_fma_f32 v[28:29], v[70:71], 0.5, v[56:57] op_sel_hi:[1,0,1] neg_lo:[0,0,1] neg_hi:[0,0,1]
	v_pk_fma_f32 v[96:97], v[70:71], 0.5, v[72:73] op_sel_hi:[1,0,1]
	v_pk_mov_b32 v[56:57], v[48:49], v[152:153] op_sel:[1,0]
	v_mov_b32_e32 v29, v97
	v_pk_mul_f32 v[62:63], v[28:29], s[6:7] op_sel_hi:[1,0]
	v_pk_add_f32 v[28:29], v[66:67], v[152:153]
	v_pk_add_f32 v[56:57], v[158:159], v[56:57] neg_lo:[0,1] neg_hi:[0,1]
	v_mul_f32_e32 v18, 0.5, v29
	v_pk_mul_f32 v[58:59], v[56:57], v[18:19]
	v_mul_f32_e32 v6, 0.5, v28
	v_pk_fma_f32 v[54:55], v[54:55], v[58:59], v[58:59] op_sel:[0,1,0] op_sel_hi:[1,0,1]
	v_mov_b32_e32 v66, v56
	v_mov_b32_e32 v67, v52
	v_mov_b32_e32 v58, v59
	v_mov_b32_e32 v59, v18
	v_pk_mul_f32 v[58:59], v[66:67], v[58:59]
	v_pk_add_f32 v[66:67], v[6:7], v[54:55]
	v_mul_f32_e32 v12, 0.5, v12
	v_fma_f32 v67, v28, 0.5, -v54
	v_pk_add_f32 v[28:29], v[58:59], v[58:59] op_sel:[0,1] op_sel_hi:[0,1] neg_lo:[0,1] neg_hi:[0,1]
	v_pk_add_f32 v[54:55], v[12:13], v[28:29] op_sel_hi:[0,1] neg_hi:[0,1]
	v_pk_mul_f32 v[28:29], v[54:55], v[156:157]
	v_pk_mul_f32 v[54:55], v[54:55], v[154:155]
	v_pk_fma_f32 v[32:33], v[70:71], 0.5, v[72:73] op_sel_hi:[1,0,1] neg_lo:[1,0,0] neg_hi:[1,0,0]
	v_pk_fma_f32 v[58:59], v[66:67], v[154:155], v[28:29] neg_lo:[0,0,1] neg_hi:[0,0,1]
	v_pk_fma_f32 v[28:29], v[66:67], v[154:155], v[28:29]
	v_pk_fma_f32 v[70:71], v[66:67], v[156:157], v[54:55]
	v_pk_fma_f32 v[54:55], v[66:67], v[156:157], v[54:55] neg_lo:[0,0,1] neg_hi:[0,0,1]
	v_pk_add_f32 v[72:73], v[58:59], v[28:29] op_sel:[0,1] op_sel_hi:[1,0]
	v_pk_add_f32 v[66:67], v[70:71], v[54:55] op_sel_hi:[0,1] neg_lo:[0,1] neg_hi:[0,1]
	v_pk_add_f32 v[28:29], v[58:59], v[28:29] op_sel_hi:[0,1] neg_lo:[0,1] neg_hi:[0,1]
	v_pk_add_f32 v[54:55], v[70:71], v[54:55] op_sel:[0,1] op_sel_hi:[1,0]
	v_mov_b32_e32 v73, v67
	v_mov_b32_e32 v55, v29
	v_pk_mul_f32 v[28:29], v[54:55], 0.5 op_sel_hi:[1,0]
	v_mov_b32_e32 v133, v84
	v_pk_mul_f32 v[54:55], v[52:53], v[28:29] op_sel:[0,1] op_sel_hi:[0,0]
	v_pk_fma_f32 v[58:59], v[56:57], v[28:29], v[54:55] op_sel_hi:[0,1,1]
	v_pk_fma_f32 v[28:29], v[56:57], v[28:29], v[54:55] op_sel_hi:[0,1,1] neg_hi:[0,0,1]
	v_pk_fma_f32 v[54:55], v[72:73], 0.5, v[58:59] op_sel_hi:[1,0,1] neg_lo:[0,0,1] neg_hi:[0,0,1]
	v_pk_fma_f32 v[66:67], v[72:73], 0.5, v[28:29] op_sel_hi:[1,0,1]
	v_pk_add_f32 v[56:57], v[60:61], v[134:135] neg_lo:[0,1] neg_hi:[0,1]
	v_mov_b32_e32 v55, v67
	v_pk_mul_f32 v[90:91], v[54:55], s[6:7] op_sel_hi:[1,0]
	v_pk_add_f32 v[54:55], v[134:135], v[60:61]
	v_mul_f32_e32 v12, 0.5, v57
	v_mov_b32_e32 v57, v55
	v_mul_f32_e32 v6, 0.5, v54
	v_pk_mov_b32 v[58:59], v[52:53], v[50:51] op_sel:[1,0]
	v_pk_mul_f32 v[54:55], v[56:57], s[44:45]
	v_pk_fma_f32 v[28:29], v[72:73], 0.5, v[28:29] op_sel_hi:[1,0,1] neg_lo:[1,0,0] neg_hi:[1,0,0]
	v_pk_mul_f32 v[56:57], v[58:59], v[54:55] op_sel:[0,1] op_sel_hi:[1,0]
	v_pk_mul_f32 v[54:55], v[58:59], v[54:55]
	v_pk_add_f32 v[56:57], v[56:57], v[56:57] op_sel:[0,1] op_sel_hi:[0,1]
	v_pk_add_f32 v[60:61], v[6:7], v[56:57] op_sel_hi:[0,1] neg_hi:[0,1]
	v_pk_add_f32 v[54:55], v[54:55], v[54:55] op_sel:[0,1] op_sel_hi:[0,1] neg_lo:[0,1] neg_hi:[0,1]
	v_pk_add_f32 v[56:57], v[12:13], v[54:55] op_sel_hi:[0,1] neg_hi:[0,1]
	v_pk_mul_f32 v[54:55], v[56:57], v[142:143]
	v_pk_mul_f32 v[56:57], v[56:57], v[140:141]
	v_pk_fma_f32 v[54:55], v[60:61], v[140:141], v[54:55]
	v_pk_fma_f32 v[56:57], v[60:61], v[142:143], v[56:57] neg_lo:[0,0,1] neg_hi:[0,0,1]
	v_mov_b32_e32 v51, v53
	v_pk_add_f32 v[60:61], v[56:57], v[54:55] op_sel:[0,1] op_sel_hi:[1,0] neg_lo:[0,1]
	v_pk_add_f32 v[70:71], v[56:57], v[54:55] op_sel:[0,1] op_sel_hi:[1,0]
	v_pk_add_f32 v[54:55], v[54:55], v[56:57] op_sel:[1,0] op_sel_hi:[0,1] neg_lo:[0,1] neg_hi:[0,1]
	v_pk_mul_f32 v[60:61], v[60:61], 0.5 op_sel_hi:[1,0]
	v_mov_b32_e32 v71, v55
	v_mul_f32_e32 v6, v53, v60
	v_pk_fma_f32 v[72:73], v[58:59], v[60:61], v[6:7] op_sel_hi:[1,1,0] neg_lo:[1,0,0] neg_hi:[1,0,0]
	v_mul_f32_e32 v6, v53, v61
	v_pk_fma_f32 v[50:51], v[50:51], v[60:61], v[6:7] op_sel_hi:[1,1,0]
	v_pk_add_f32 v[54:55], v[118:119], v[84:85]
	v_mov_b32_e32 v72, v50
	v_mov_b32_e32 v49, v118
	v_pk_fma_f32 v[50:51], v[70:71], 0.5, v[50:51] op_sel_hi:[1,0,1] neg_lo:[0,0,1] neg_hi:[0,0,1]
	v_pk_fma_f32 v[60:61], v[70:71], 0.5, v[72:73] op_sel_hi:[1,0,1]
	v_mul_f32_e32 v18, 0.5, v55
	v_pk_add_f32 v[48:49], v[132:133], v[48:49] neg_lo:[0,1] neg_hi:[0,1]
	v_mov_b32_e32 v51, v61
	v_pk_mul_f32 v[56:57], v[48:49], v[18:19]
	v_pk_mul_f32 v[94:95], v[50:51], s[6:7] op_sel_hi:[1,0]
	v_pk_fma_f32 v[50:51], v[70:71], 0.5, v[72:73] op_sel_hi:[1,0,1] neg_lo:[1,0,0] neg_hi:[1,0,0]
	v_mul_f32_e32 v6, 0.5, v54
	v_pk_fma_f32 v[58:59], v[58:59], v[56:57], v[56:57] op_sel:[0,1,0] op_sel_hi:[1,0,1]
	v_mov_b32_e32 v70, v48
	v_mov_b32_e32 v71, v53
	v_mov_b32_e32 v56, v57
	v_mov_b32_e32 v57, v18
	v_sub_f32_e32 v12, v85, v119
	v_pk_mul_f32 v[56:57], v[70:71], v[56:57]
	v_pk_add_f32 v[70:71], v[6:7], v[58:59]
	v_mul_f32_e32 v12, 0.5, v12
	v_fma_f32 v71, v54, 0.5, -v58
	v_pk_add_f32 v[54:55], v[56:57], v[56:57] op_sel:[0,1] op_sel_hi:[0,1] neg_lo:[0,1] neg_hi:[0,1]
	v_pk_add_f32 v[56:57], v[12:13], v[54:55] op_sel_hi:[0,1] neg_hi:[0,1]
	v_pk_mul_f32 v[54:55], v[56:57], v[126:127]
	v_pk_mul_f32 v[56:57], v[56:57], v[124:125]
	v_pk_fma_f32 v[58:59], v[70:71], v[124:125], v[54:55] neg_lo:[0,0,1] neg_hi:[0,0,1]
	v_pk_fma_f32 v[54:55], v[70:71], v[124:125], v[54:55]
	v_pk_fma_f32 v[72:73], v[70:71], v[126:127], v[56:57]
	v_pk_fma_f32 v[56:57], v[70:71], v[126:127], v[56:57] neg_lo:[0,0,1] neg_hi:[0,0,1]
	v_pk_add_f32 v[70:71], v[58:59], v[54:55] op_sel:[0,1] op_sel_hi:[1,0]
	v_pk_add_f32 v[74:75], v[72:73], v[56:57] op_sel_hi:[0,1] neg_lo:[0,1] neg_hi:[0,1]
	v_pk_add_f32 v[54:55], v[58:59], v[54:55] op_sel_hi:[0,1] neg_lo:[0,1] neg_hi:[0,1]
	v_pk_add_f32 v[56:57], v[72:73], v[56:57] op_sel:[0,1] op_sel_hi:[1,0]
	v_mov_b32_e32 v71, v75
	v_mov_b32_e32 v57, v55
	v_pk_mul_f32 v[54:55], v[56:57], 0.5 op_sel_hi:[1,0]
	s_mov_b32 s78, s11
	v_pk_mul_f32 v[52:53], v[52:53], v[54:55] op_sel:[1,1] op_sel_hi:[1,0]
	s_mov_b32 s79, s8
	v_pk_fma_f32 v[56:57], v[48:49], v[54:55], v[52:53] op_sel_hi:[0,1,1]
	v_pk_fma_f32 v[48:49], v[48:49], v[54:55], v[52:53] op_sel_hi:[0,1,1] neg_hi:[0,0,1]
	s_nop 0
	v_pk_fma_f32 v[52:53], v[70:71], 0.5, v[56:57] op_sel_hi:[1,0,1] neg_lo:[0,0,1] neg_hi:[0,0,1]
	v_pk_fma_f32 v[84:85], v[70:71], 0.5, v[48:49] op_sel_hi:[1,0,1]
	s_mov_b32 s9, s11
	v_mov_b32_e32 v53, v85
	v_pk_mul_f32 v[80:81], v[52:53], s[6:7] op_sel_hi:[1,0]
	v_pk_mul_f32 v[118:119], v[82:83], s[78:79] op_sel_hi:[0,1]
	v_pk_add_f32 v[52:53], v[86:87], v[112:113]
	v_pk_add_f32 v[54:55], v[86:87], v[112:113] neg_lo:[0,1] neg_hi:[0,1]
	v_pk_fma_f32 v[58:59], v[4:5], s[8:9], v[118:119] op_sel_hi:[0,1,1] neg_lo:[0,0,1] neg_hi:[0,0,1]
	v_mul_f32_e32 v12, 0.5, v55
	v_pk_fma_f32 v[72:73], v[4:5], s[8:9], v[118:119] op_sel_hi:[0,1,1]
	v_mov_b32_e32 v55, v53
	v_mul_f32_e32 v6, 0.5, v52
	v_mov_b32_e32 v56, v58
	v_mov_b32_e32 v57, v73
	v_pk_mul_f32 v[52:53], v[54:55], s[44:45]
	v_pk_fma_f32 v[48:49], v[70:71], 0.5, v[48:49] op_sel_hi:[1,0,1] neg_lo:[1,0,0] neg_hi:[1,0,0]
	v_pk_mul_f32 v[54:55], v[56:57], v[52:53] op_sel:[0,1] op_sel_hi:[1,0]
	v_pk_mul_f32 v[52:53], v[56:57], v[52:53]
	v_pk_add_f32 v[54:55], v[54:55], v[54:55] op_sel:[0,1] op_sel_hi:[0,1]
	v_pk_add_f32 v[74:75], v[6:7], v[54:55] op_sel_hi:[0,1] neg_hi:[0,1]
	v_pk_add_f32 v[52:53], v[52:53], v[52:53] op_sel:[0,1] op_sel_hi:[0,1] neg_lo:[0,1] neg_hi:[0,1]
	v_pk_add_f32 v[54:55], v[12:13], v[52:53] op_sel_hi:[0,1] neg_hi:[0,1]
	v_pk_mul_f32 v[52:53], v[54:55], v[116:117]
	v_pk_mul_f32 v[54:55], v[54:55], v[114:115]
	v_pk_fma_f32 v[52:53], v[74:75], v[114:115], v[52:53]
	v_pk_fma_f32 v[54:55], v[74:75], v[116:117], v[54:55] neg_lo:[0,0,1] neg_hi:[0,0,1]
	v_pk_mov_b32 v[70:71], v[72:73], v[58:59] op_sel:[1,0]
	v_pk_add_f32 v[74:75], v[54:55], v[52:53] op_sel:[0,1] op_sel_hi:[1,0] neg_lo:[0,1]
	v_pk_add_f32 v[76:77], v[54:55], v[52:53] op_sel:[0,1] op_sel_hi:[1,0]
	v_pk_add_f32 v[52:53], v[52:53], v[54:55] op_sel:[1,0] op_sel_hi:[0,1] neg_lo:[0,1] neg_hi:[0,1]
	v_pk_mul_f32 v[74:75], v[74:75], 0.5 op_sel_hi:[1,0]
	v_mov_b32_e32 v77, v53
	v_mul_f32_e32 v6, v58, v74
	v_pk_fma_f32 v[112:113], v[56:57], v[74:75], v[6:7] op_sel_hi:[1,1,0] neg_lo:[1,0,0] neg_hi:[1,0,0]
	v_mul_f32_e32 v6, v58, v75
	v_pk_fma_f32 v[70:71], v[70:71], v[74:75], v[6:7] op_sel_hi:[1,1,0]
	v_pk_add_f32 v[54:55], v[34:35], v[110:111]
	v_mov_b32_e32 v112, v70
	v_pk_fma_f32 v[52:53], v[76:77], 0.5, v[70:71] op_sel_hi:[1,0,1] neg_lo:[0,0,1] neg_hi:[0,0,1]
	v_pk_fma_f32 v[86:87], v[76:77], 0.5, v[112:113] op_sel_hi:[1,0,1]
	v_sub_f32_e32 v12, v35, v111
	v_mov_b32_e32 v53, v87
	v_pk_mul_f32 v[78:79], v[52:53], s[6:7] op_sel_hi:[1,0]
	v_mul_f32_e32 v52, 0xbe47c5c2, v83
	v_mov_b32_e32 v53, v34
	v_pk_mov_b32 v[34:35], v[118:119], v[110:111] op_sel:[1,0]
	v_mul_f32_e32 v18, 0.5, v55
	v_pk_add_f32 v[34:35], v[52:53], v[34:35] neg_lo:[0,1] neg_hi:[0,1]
	v_mov_b32_e32 v71, v58
	v_pk_mul_f32 v[52:53], v[34:35], v[18:19]
	v_mov_b32_e32 v70, v34
	v_pk_fma_f32 v[56:57], v[56:57], v[52:53], v[52:53] op_sel:[0,1,0] op_sel_hi:[1,0,1]
	v_mov_b32_e32 v52, v53
	v_mov_b32_e32 v53, v18
	v_mul_f32_e32 v6, 0.5, v54
	v_pk_mul_f32 v[52:53], v[70:71], v[52:53]
	v_cvt_f32_f16_e32 v70, v46
	v_cvt_f32_f16_e32 v71, v47
	v_cvt_f32_f16_sdwa v47, v47 dst_sel:DWORD dst_unused:UNUSED_PAD src0_sel:WORD_1
	v_cvt_f32_f16_sdwa v46, v46 dst_sel:DWORD dst_unused:UNUSED_PAD src0_sel:WORD_1
	v_pk_fma_f32 v[74:75], v[76:77], 0.5, v[112:113] op_sel_hi:[1,0,1] neg_lo:[1,0,0] neg_hi:[1,0,0]
	v_mul_f32_e32 v12, 0.5, v12
	v_pk_add_f32 v[76:77], v[6:7], v[56:57]
	v_pk_add_f32 v[52:53], v[52:53], v[52:53] op_sel:[0,1] op_sel_hi:[0,1] neg_lo:[0,1] neg_hi:[0,1]
	v_fma_f32 v77, v54, 0.5, -v56
	v_pk_add_f32 v[54:55], v[12:13], v[52:53] op_sel_hi:[0,1] neg_hi:[0,1]
	v_pk_mul_f32 v[52:53], v[54:55], v[46:47]
	v_pk_mul_f32 v[54:55], v[54:55], v[70:71]
	v_pk_fma_f32 v[56:57], v[76:77], v[70:71], v[52:53] neg_lo:[0,0,1] neg_hi:[0,0,1]
	v_pk_fma_f32 v[52:53], v[76:77], v[70:71], v[52:53]
	v_pk_fma_f32 v[70:71], v[76:77], v[46:47], v[54:55]
	v_pk_fma_f32 v[46:47], v[76:77], v[46:47], v[54:55] neg_lo:[0,0,1] neg_hi:[0,0,1]
	v_pk_add_f32 v[54:55], v[56:57], v[52:53] op_sel:[0,1] op_sel_hi:[1,0]
	v_pk_add_f32 v[76:77], v[70:71], v[46:47] op_sel_hi:[0,1] neg_lo:[0,1] neg_hi:[0,1]
	v_pk_add_f32 v[52:53], v[56:57], v[52:53] op_sel_hi:[0,1] neg_lo:[0,1] neg_hi:[0,1]
	v_pk_add_f32 v[46:47], v[70:71], v[46:47] op_sel:[0,1] op_sel_hi:[1,0]
	v_mov_b32_e32 v55, v77
	v_mov_b32_e32 v47, v53
	v_pk_mul_f32 v[46:47], v[46:47], 0.5 op_sel_hi:[1,0]
	s_mov_b32 s25, s27
	v_pk_mul_f32 v[52:53], v[58:59], v[46:47] op_sel:[0,1] op_sel_hi:[0,0]
	v_pk_fma_f32 v[56:57], v[34:35], v[46:47], v[52:53] op_sel_hi:[0,1,1]
	v_pk_fma_f32 v[46:47], v[34:35], v[46:47], v[52:53] op_sel_hi:[0,1,1] neg_hi:[0,0,1]
	s_nop 0
	v_pk_fma_f32 v[52:53], v[54:55], 0.5, v[56:57] op_sel_hi:[1,0,1] neg_lo:[0,0,1] neg_hi:[0,0,1]
	v_pk_fma_f32 v[34:35], v[54:55], 0.5, v[46:47] op_sel_hi:[1,0,1]
	s_mov_b32 s78, s27
	v_mov_b32_e32 v53, v35
	v_pk_mul_f32 v[136:137], v[52:53], s[6:7] op_sel_hi:[1,0]
	v_pk_fma_f32 v[52:53], v[54:55], 0.5, v[46:47] op_sel_hi:[1,0,1] neg_lo:[1,0,0] neg_hi:[1,0,0]
	s_mov_b32 s79, s24
	v_pk_mul_f32 v[46:47], v[82:83], s[24:25] op_sel_hi:[0,1]
	v_pk_add_f32 v[54:55], v[108:109], v[40:41]
	v_pk_add_f32 v[40:41], v[40:41], v[108:109] neg_lo:[0,1] neg_hi:[0,1]
	v_pk_fma_f32 v[108:109], v[4:5], s[78:79], v[46:47] op_sel_hi:[0,1,1] neg_lo:[0,0,1] neg_hi:[0,0,1]
	v_mul_f32_e32 v12, 0.5, v41
	v_pk_fma_f32 v[70:71], v[4:5], s[78:79], v[46:47] op_sel_hi:[0,1,1]
	v_mov_b32_e32 v41, v55
	v_mov_b32_e32 v56, v108
	v_mov_b32_e32 v57, v71
	v_pk_mul_f32 v[40:41], v[40:41], s[44:45]
	v_mul_f32_e32 v6, 0.5, v54
	v_pk_mul_f32 v[54:55], v[56:57], v[40:41] op_sel:[0,1] op_sel_hi:[1,0]
	v_cvt_f32_f16_sdwa v76, v36 dst_sel:DWORD dst_unused:UNUSED_PAD src0_sel:WORD_1
	v_cvt_f32_f16_e32 v77, v37
	v_cvt_f32_f16_sdwa v37, v37 dst_sel:DWORD dst_unused:UNUSED_PAD src0_sel:WORD_1
	v_cvt_f32_f16_e32 v36, v36
	v_pk_mul_f32 v[40:41], v[56:57], v[40:41]
	v_pk_add_f32 v[54:55], v[54:55], v[54:55] op_sel:[0,1] op_sel_hi:[0,1]
	v_pk_add_f32 v[112:113], v[6:7], v[54:55] op_sel_hi:[0,1] neg_hi:[0,1]
	s_nop 0
	v_pk_add_f32 v[40:41], v[40:41], v[40:41] op_sel:[0,1] op_sel_hi:[0,1] neg_lo:[0,1] neg_hi:[0,1]
	v_pk_add_f32 v[54:55], v[12:13], v[40:41] op_sel_hi:[0,1] neg_hi:[0,1]
	v_pk_mul_f32 v[40:41], v[54:55], v[36:37]
	v_pk_mul_f32 v[54:55], v[54:55], v[76:77]
	v_pk_fma_f32 v[40:41], v[112:113], v[76:77], v[40:41]
	v_pk_fma_f32 v[36:37], v[112:113], v[36:37], v[54:55] neg_lo:[0,0,1] neg_hi:[0,0,1]
	v_pk_mov_b32 v[110:111], v[70:71], v[108:109] op_sel:[1,0]
	v_pk_add_f32 v[54:55], v[36:37], v[40:41] op_sel:[0,1] op_sel_hi:[1,0] neg_lo:[0,1]
	v_pk_add_f32 v[76:77], v[36:37], v[40:41] op_sel:[0,1] op_sel_hi:[1,0]
	v_pk_add_f32 v[36:37], v[40:41], v[36:37] op_sel:[1,0] op_sel_hi:[0,1] neg_lo:[0,1] neg_hi:[0,1]
	v_pk_mul_f32 v[54:55], v[54:55], 0.5 op_sel_hi:[1,0]
	v_mov_b32_e32 v77, v37
	v_mul_f32_e32 v4, v108, v54
	v_pk_fma_f32 v[112:113], v[56:57], v[54:55], v[4:5] op_sel_hi:[1,1,0] neg_lo:[1,0,0] neg_hi:[1,0,0]
	v_mul_f32_e32 v4, v108, v55
	v_pk_fma_f32 v[54:55], v[110:111], v[54:55], v[4:5] op_sel_hi:[1,1,0]
	v_sub_f32_e32 v6, v45, v105
	v_mov_b32_e32 v112, v54
	v_pk_fma_f32 v[40:41], v[76:77], 0.5, v[54:55] op_sel_hi:[1,0,1] neg_lo:[0,0,1] neg_hi:[0,0,1]
	v_pk_fma_f32 v[36:37], v[76:77], 0.5, v[112:113] op_sel_hi:[1,0,1]
	v_pk_add_f32 v[54:55], v[104:105], v[44:45]
	v_mov_b32_e32 v41, v37
	v_pk_mul_f32 v[130:131], v[40:41], s[6:7] op_sel_hi:[1,0]
	v_mul_f32_e32 v40, 0xbf54db31, v83
	v_mov_b32_e32 v41, v44
	v_pk_mov_b32 v[44:45], v[46:47], v[104:105] op_sel:[1,0]
	v_mul_f32_e32 v18, 0.5, v55
	v_pk_add_f32 v[40:41], v[40:41], v[44:45] neg_lo:[0,1] neg_hi:[0,1]
	v_mov_b32_e32 v105, v108
	v_pk_mul_f32 v[44:45], v[40:41], v[18:19]
	v_mov_b32_e32 v104, v40
	v_pk_fma_f32 v[56:57], v[56:57], v[44:45], v[44:45] op_sel:[0,1,0] op_sel_hi:[1,0,1]
	v_mov_b32_e32 v44, v45
	v_mov_b32_e32 v45, v18
	v_mul_f32_e32 v4, 0.5, v54
	v_pk_mul_f32 v[44:45], v[104:105], v[44:45]
	v_cvt_f32_f16_e32 v104, v26
	v_cvt_f32_f16_e32 v105, v27
	v_cvt_f32_f16_sdwa v27, v27 dst_sel:DWORD dst_unused:UNUSED_PAD src0_sel:WORD_1
	v_cvt_f32_f16_sdwa v26, v26 dst_sel:DWORD dst_unused:UNUSED_PAD src0_sel:WORD_1
	v_mul_f32_e32 v6, 0.5, v6
	v_pk_add_f32 v[110:111], v[4:5], v[56:57]
	v_pk_add_f32 v[44:45], v[44:45], v[44:45] op_sel:[0,1] op_sel_hi:[0,1] neg_lo:[0,1] neg_hi:[0,1]
	v_fma_f32 v111, v54, 0.5, -v56
	v_pk_add_f32 v[54:55], v[6:7], v[44:45] op_sel_hi:[0,1] neg_hi:[0,1]
	v_pk_mul_f32 v[44:45], v[54:55], v[26:27]
	v_pk_mul_f32 v[54:55], v[54:55], v[104:105]
	v_pk_fma_f32 v[56:57], v[110:111], v[104:105], v[44:45] neg_lo:[0,0,1] neg_hi:[0,0,1]
	v_pk_fma_f32 v[44:45], v[110:111], v[104:105], v[44:45]
	v_pk_fma_f32 v[104:105], v[110:111], v[26:27], v[54:55]
	v_pk_fma_f32 v[26:27], v[110:111], v[26:27], v[54:55] neg_lo:[0,0,1] neg_hi:[0,0,1]
	v_pk_add_f32 v[54:55], v[56:57], v[44:45] op_sel:[0,1] op_sel_hi:[1,0]
	v_pk_add_f32 v[110:111], v[104:105], v[26:27] op_sel_hi:[0,1] neg_lo:[0,1] neg_hi:[0,1]
	v_pk_add_f32 v[44:45], v[56:57], v[44:45] op_sel_hi:[0,1] neg_lo:[0,1] neg_hi:[0,1]
	v_pk_add_f32 v[26:27], v[104:105], v[26:27] op_sel:[0,1] op_sel_hi:[1,0]
	v_mov_b32_e32 v55, v111
	v_mov_b32_e32 v27, v45
	v_pk_mul_f32 v[26:27], v[26:27], 0.5 op_sel_hi:[1,0]
	v_mov_b32_e32 v47, v102
	v_pk_mul_f32 v[44:45], v[108:109], v[26:27] op_sel:[0,1] op_sel_hi:[0,0]
	v_pk_fma_f32 v[56:57], v[40:41], v[26:27], v[44:45] op_sel_hi:[0,1,1]
	v_pk_fma_f32 v[40:41], v[40:41], v[26:27], v[44:45] op_sel_hi:[0,1,1] neg_hi:[0,0,1]
	v_pk_fma_f32 v[44:45], v[54:55], 0.5, v[56:57] op_sel_hi:[1,0,1] neg_lo:[0,0,1] neg_hi:[0,0,1]
	v_pk_fma_f32 v[26:27], v[54:55], 0.5, v[40:41] op_sel_hi:[1,0,1]
	v_pk_fma_f32 v[56:57], v[54:55], 0.5, v[40:41] op_sel_hi:[1,0,1] neg_lo:[1,0,0] neg_hi:[1,0,0]
	v_pk_add_f32 v[40:41], v[106:107], v[42:43]
	v_pk_add_f32 v[42:43], v[42:43], v[106:107] neg_lo:[0,1] neg_hi:[0,1]
	v_mov_b32_e32 v45, v27
	v_mul_f32_e32 v6, 0.5, v43
	v_mov_b32_e32 v43, v41
	v_pk_mul_f32 v[120:121], v[44:45], s[6:7] op_sel_hi:[1,0]
	v_mul_f32_e32 v4, 0.5, v40
	v_pk_mov_b32 v[44:45], v[108:109], v[70:71] op_sel:[1,0]
	v_pk_mul_f32 v[40:41], v[42:43], s[44:45]
	v_cvt_f32_f16_sdwa v54, v20 dst_sel:DWORD dst_unused:UNUSED_PAD src0_sel:WORD_1
	v_pk_mul_f32 v[42:43], v[44:45], v[40:41] op_sel:[0,1] op_sel_hi:[1,0]
	v_cvt_f32_f16_e32 v55, v21
	v_cvt_f32_f16_sdwa v21, v21 dst_sel:DWORD dst_unused:UNUSED_PAD src0_sel:WORD_1
	v_cvt_f32_f16_e32 v20, v20
	v_pk_mul_f32 v[40:41], v[44:45], v[40:41]
	v_pk_add_f32 v[42:43], v[42:43], v[42:43] op_sel:[0,1] op_sel_hi:[0,1]
	v_pk_add_f32 v[104:105], v[4:5], v[42:43] op_sel_hi:[0,1] neg_hi:[0,1]
	s_nop 0
	v_pk_add_f32 v[40:41], v[40:41], v[40:41] op_sel:[0,1] op_sel_hi:[0,1] neg_lo:[0,1] neg_hi:[0,1]
	v_pk_add_f32 v[42:43], v[6:7], v[40:41] op_sel_hi:[0,1] neg_hi:[0,1]
	v_pk_mul_f32 v[40:41], v[42:43], v[20:21]
	v_pk_mul_f32 v[42:43], v[42:43], v[54:55]
	v_pk_fma_f32 v[40:41], v[104:105], v[54:55], v[40:41]
	v_pk_fma_f32 v[20:21], v[104:105], v[20:21], v[42:43] neg_lo:[0,0,1] neg_hi:[0,0,1]
	v_mov_b32_e32 v71, v109
	v_pk_add_f32 v[42:43], v[20:21], v[40:41] op_sel:[0,1] op_sel_hi:[1,0] neg_lo:[0,1]
	v_pk_add_f32 v[54:55], v[20:21], v[40:41] op_sel:[0,1] op_sel_hi:[1,0]
	v_pk_add_f32 v[20:21], v[40:41], v[20:21] op_sel:[1,0] op_sel_hi:[0,1] neg_lo:[0,1] neg_hi:[0,1]
	v_pk_mul_f32 v[42:43], v[42:43], 0.5 op_sel_hi:[1,0]
	v_mov_b32_e32 v55, v21
	v_mul_f32_e32 v4, v109, v42
	v_pk_fma_f32 v[104:105], v[44:45], v[42:43], v[4:5] op_sel_hi:[1,1,0] neg_lo:[1,0,0] neg_hi:[1,0,0]
	v_mul_f32_e32 v4, v109, v43
	v_pk_fma_f32 v[42:43], v[70:71], v[42:43], v[4:5] op_sel_hi:[1,1,0]
	v_sub_f32_e32 v6, v23, v103
	v_mov_b32_e32 v104, v42
	v_pk_fma_f32 v[40:41], v[54:55], 0.5, v[42:43] op_sel_hi:[1,0,1] neg_lo:[0,0,1] neg_hi:[0,0,1]
	v_pk_fma_f32 v[20:21], v[54:55], 0.5, v[104:105] op_sel_hi:[1,0,1]
	v_pk_add_f32 v[42:43], v[102:103], v[22:23]
	v_mov_b32_e32 v41, v21
	v_pk_mul_f32 v[128:129], v[40:41], s[6:7] op_sel_hi:[1,0]
	v_mul_f32_e32 v40, 0xbf0e39da, v83
	v_mov_b32_e32 v41, v22
	v_mul_f32_e32 v18, 0.5, v43
	v_pk_add_f32 v[22:23], v[40:41], v[46:47] neg_lo:[0,1] neg_hi:[0,1]
	v_mov_b32_e32 v47, v109
	v_pk_mul_f32 v[40:41], v[22:23], v[18:19]
	v_mov_b32_e32 v46, v22
	v_pk_fma_f32 v[44:45], v[44:45], v[40:41], v[40:41] op_sel:[0,1,0] op_sel_hi:[1,0,1]
	v_mov_b32_e32 v40, v41
	v_mov_b32_e32 v41, v18
	v_mul_f32_e32 v4, 0.5, v42
	v_pk_mul_f32 v[40:41], v[46:47], v[40:41]
	v_cvt_f32_f16_e32 v46, v10
	v_cvt_f32_f16_e32 v47, v11
	v_cvt_f32_f16_sdwa v11, v11 dst_sel:DWORD dst_unused:UNUSED_PAD src0_sel:WORD_1
	v_cvt_f32_f16_sdwa v10, v10 dst_sel:DWORD dst_unused:UNUSED_PAD src0_sel:WORD_1
	v_pk_fma_f32 v[70:71], v[54:55], 0.5, v[104:105] op_sel_hi:[1,0,1] neg_lo:[1,0,0] neg_hi:[1,0,0]
	v_mul_f32_e32 v6, 0.5, v6
	v_pk_add_f32 v[54:55], v[4:5], v[44:45]
	v_pk_add_f32 v[40:41], v[40:41], v[40:41] op_sel:[0,1] op_sel_hi:[0,1] neg_lo:[0,1] neg_hi:[0,1]
	v_fma_f32 v55, v42, 0.5, -v44
	v_pk_add_f32 v[42:43], v[6:7], v[40:41] op_sel_hi:[0,1] neg_hi:[0,1]
	v_pk_mul_f32 v[40:41], v[42:43], v[10:11]
	v_pk_mul_f32 v[42:43], v[42:43], v[46:47]
	v_pk_fma_f32 v[44:45], v[54:55], v[46:47], v[40:41] neg_lo:[0,0,1] neg_hi:[0,0,1]
	v_pk_fma_f32 v[40:41], v[54:55], v[46:47], v[40:41]
	v_pk_fma_f32 v[46:47], v[54:55], v[10:11], v[42:43]
	v_pk_fma_f32 v[10:11], v[54:55], v[10:11], v[42:43] neg_lo:[0,0,1] neg_hi:[0,0,1]
	v_pk_add_f32 v[42:43], v[44:45], v[40:41] op_sel:[0,1] op_sel_hi:[1,0]
	v_pk_add_f32 v[54:55], v[46:47], v[10:11] op_sel_hi:[0,1] neg_lo:[0,1] neg_hi:[0,1]
	v_pk_add_f32 v[40:41], v[44:45], v[40:41] op_sel_hi:[0,1] neg_lo:[0,1] neg_hi:[0,1]
	v_pk_add_f32 v[10:11], v[46:47], v[10:11] op_sel:[0,1] op_sel_hi:[1,0]
	v_mov_b32_e32 v43, v55
	v_mov_b32_e32 v11, v41
	v_pk_mul_f32 v[10:11], v[10:11], 0.5 op_sel_hi:[1,0]
	v_mov_b32_e32 v119, v98
	v_pk_mul_f32 v[40:41], v[108:109], v[10:11] op_sel:[1,1] op_sel_hi:[1,0]
	v_pk_fma_f32 v[76:77], v[76:77], 0.5, v[112:113] op_sel_hi:[1,0,1] neg_lo:[1,0,0] neg_hi:[1,0,0]
	v_pk_fma_f32 v[44:45], v[22:23], v[10:11], v[40:41] op_sel_hi:[0,1,1]
	v_pk_fma_f32 v[10:11], v[22:23], v[10:11], v[40:41] op_sel_hi:[0,1,1] neg_hi:[0,0,1]
	v_pk_fma_f32 v[22:23], v[42:43], 0.5, v[44:45] op_sel_hi:[1,0,1] neg_lo:[0,0,1] neg_hi:[0,0,1]
	v_pk_fma_f32 v[40:41], v[42:43], 0.5, v[10:11] op_sel_hi:[1,0,1]
	v_pk_fma_f32 v[54:55], v[42:43], 0.5, v[10:11] op_sel_hi:[1,0,1] neg_lo:[1,0,0] neg_hi:[1,0,0]
	v_pk_add_f32 v[10:11], v[100:101], v[14:15]
	v_pk_add_f32 v[14:15], v[14:15], v[100:101] neg_lo:[0,1] neg_hi:[0,1]
	v_mov_b32_e32 v23, v41
	v_mul_f32_e32 v6, 0.5, v15
	v_mov_b32_e32 v15, v11
	v_pk_mul_f32 v[150:151], v[22:23], s[6:7] op_sel_hi:[1,0]
	v_mul_f32_e32 v4, 0.5, v10
	v_pk_mov_b32 v[22:23], v[58:59], v[72:73] op_sel:[1,0]
	v_pk_mul_f32 v[10:11], v[14:15], s[44:45]
	v_cvt_f32_f16_sdwa v42, v8 dst_sel:DWORD dst_unused:UNUSED_PAD src0_sel:WORD_1
	v_pk_mul_f32 v[14:15], v[22:23], v[10:11] op_sel:[0,1] op_sel_hi:[1,0]
	v_cvt_f32_f16_e32 v43, v9
	v_cvt_f32_f16_sdwa v9, v9 dst_sel:DWORD dst_unused:UNUSED_PAD src0_sel:WORD_1
	v_cvt_f32_f16_e32 v8, v8
	v_pk_mul_f32 v[10:11], v[22:23], v[10:11]
	v_pk_add_f32 v[14:15], v[14:15], v[14:15] op_sel:[0,1] op_sel_hi:[0,1]
	v_pk_add_f32 v[44:45], v[4:5], v[14:15] op_sel_hi:[0,1] neg_hi:[0,1]
	s_nop 0
	v_pk_add_f32 v[10:11], v[10:11], v[10:11] op_sel:[0,1] op_sel_hi:[0,1] neg_lo:[0,1] neg_hi:[0,1]
	v_pk_add_f32 v[14:15], v[6:7], v[10:11] op_sel_hi:[0,1] neg_hi:[0,1]
	v_pk_mul_f32 v[10:11], v[14:15], v[8:9]
	v_pk_mul_f32 v[14:15], v[14:15], v[42:43]
	v_pk_fma_f32 v[10:11], v[44:45], v[42:43], v[10:11]
	v_pk_fma_f32 v[8:9], v[44:45], v[8:9], v[14:15] neg_lo:[0,0,1] neg_hi:[0,0,1]
	v_mov_b32_e32 v73, v59
	v_pk_add_f32 v[14:15], v[8:9], v[10:11] op_sel:[0,1] op_sel_hi:[1,0] neg_lo:[0,1]
	v_pk_add_f32 v[42:43], v[8:9], v[10:11] op_sel:[0,1] op_sel_hi:[1,0]
	v_pk_add_f32 v[8:9], v[10:11], v[8:9] op_sel:[1,0] op_sel_hi:[0,1] neg_lo:[0,1] neg_hi:[0,1]
	v_pk_mul_f32 v[14:15], v[14:15], 0.5 op_sel_hi:[1,0]
	v_mov_b32_e32 v43, v9
	v_mul_f32_e32 v4, v59, v14
	v_pk_fma_f32 v[44:45], v[22:23], v[14:15], v[4:5] op_sel_hi:[1,1,0] neg_lo:[1,0,0] neg_hi:[1,0,0]
	v_mul_f32_e32 v4, v59, v15
	v_pk_fma_f32 v[14:15], v[72:73], v[14:15], v[4:5] op_sel_hi:[1,1,0]
	v_sub_f32_e32 v6, v39, v99
	v_mov_b32_e32 v44, v14
	v_pk_fma_f32 v[8:9], v[42:43], 0.5, v[14:15] op_sel_hi:[1,0,1] neg_lo:[0,0,1] neg_hi:[0,0,1]
	v_pk_fma_f32 v[10:11], v[42:43], 0.5, v[44:45] op_sel_hi:[1,0,1]
	v_pk_add_f32 v[14:15], v[98:99], v[38:39]
	v_mov_b32_e32 v9, v11
	v_pk_mul_f32 v[168:169], v[8:9], s[6:7] op_sel_hi:[1,0]
	v_mul_f32_e32 v8, 0xbf7b14be, v83
	v_mov_b32_e32 v9, v38
	v_mul_f32_e32 v18, 0.5, v15
	v_pk_add_f32 v[8:9], v[8:9], v[118:119] neg_lo:[0,1] neg_hi:[0,1]
	v_pk_fma_f32 v[72:73], v[42:43], 0.5, v[44:45] op_sel_hi:[1,0,1] neg_lo:[1,0,0] neg_hi:[1,0,0]
	v_pk_mul_f32 v[38:39], v[8:9], v[18:19]
	v_mov_b32_e32 v42, v8
	v_pk_fma_f32 v[22:23], v[22:23], v[38:39], v[38:39] op_sel:[0,1,0] op_sel_hi:[1,0,1]
	v_mov_b32_e32 v43, v59
	v_mov_b32_e32 v38, v39
	v_mov_b32_e32 v39, v18
	v_mul_f32_e32 v4, 0.5, v14
	v_pk_mul_f32 v[38:39], v[42:43], v[38:39]
	v_cvt_f32_f16_e32 v44, v2
	v_cvt_f32_f16_e32 v45, v3
	v_cvt_f32_f16_sdwa v3, v3 dst_sel:DWORD dst_unused:UNUSED_PAD src0_sel:WORD_1
	v_cvt_f32_f16_sdwa v2, v2 dst_sel:DWORD dst_unused:UNUSED_PAD src0_sel:WORD_1
	v_mul_f32_e32 v6, 0.5, v6
	v_pk_add_f32 v[46:47], v[4:5], v[22:23]
	v_fma_f32 v4, v14, 0.5, -v22
	v_pk_add_f32 v[22:23], v[38:39], v[38:39] op_sel:[0,1] op_sel_hi:[0,1] neg_lo:[0,1] neg_hi:[0,1]
	v_pk_add_f32 v[38:39], v[6:7], v[22:23] op_sel_hi:[0,1] neg_hi:[0,1]
	v_mov_b32_e32 v14, v46
	v_mov_b32_e32 v15, v4
	v_pk_mul_f32 v[22:23], v[4:5], v[44:45] op_sel_hi:[0,1]
	v_pk_mul_f32 v[82:83], v[38:39], v[2:3]
	v_pk_mul_f32 v[46:47], v[46:47], v[2:3]
	v_pk_mul_f32 v[38:39], v[38:39], v[44:45]
	v_pk_fma_f32 v[98:99], v[14:15], v[44:45], v[82:83] neg_lo:[0,0,1] neg_hi:[0,0,1]
	v_pk_fma_f32 v[2:3], v[14:15], v[2:3], v[38:39] neg_lo:[0,0,1] neg_hi:[0,0,1]
	v_add_f32_e32 v4, v23, v83
	v_add_f32_e32 v6, v46, v38
	v_pk_add_f32 v[22:23], v[6:7], v[2:3] op_sel_hi:[0,1] neg_lo:[0,1] neg_hi:[0,1]
	v_pk_add_f32 v[38:39], v[98:99], v[4:5] op_sel_hi:[1,0] neg_lo:[0,1] neg_hi:[0,1]
	v_pk_add_f32 v[2:3], v[6:7], v[2:3] op_sel_hi:[0,1]
	v_mov_b32_e32 v39, v3
	v_pk_mul_f32 v[2:3], v[38:39], 0.5 op_sel_hi:[1,0]
	v_pk_add_f32 v[14:15], v[98:99], v[4:5] op_sel_hi:[1,0]
	v_mul_f32_e32 v4, v59, v3
	v_pk_fma_f32 v[38:39], v[42:43], v[2:3], v[4:5] op_sel_hi:[1,1,0] neg_lo:[0,0,1] neg_hi:[0,0,1]
	v_pk_mov_b32 v[42:43], v[58:59], v[8:9] op_sel:[1,0]
	v_mul_f32_e32 v4, v8, v3
	v_pk_fma_f32 v[2:3], v[42:43], v[2:3], v[4:5] op_sel_hi:[1,1,0]
	v_mov_b32_e32 v15, v23
	v_pk_fma_f32 v[8:9], v[14:15], 0.5, v[2:3] op_sel_hi:[1,0,1] neg_lo:[0,0,1] neg_hi:[0,0,1]
	v_pk_fma_f32 v[42:43], v[14:15], 0.5, v[38:39] op_sel_hi:[1,0,0]
	v_pk_fma_f32 v[2:3], v[14:15], 0.5, v[2:3] op_sel_hi:[1,0,1]
	v_mov_b32_e32 v9, v43
	v_pk_fma_f32 v[58:59], v[22:23], 0.5, v[38:39] op_sel_hi:[1,0,0] neg_lo:[1,0,0] neg_hi:[1,0,0]
	v_pk_mul_f32 v[144:145], v[8:9], s[6:7] op_sel_hi:[1,0]
	v_mov_b32_e32 v58, v2
	v_mov_b32_e32 v72, v10
	v_mov_b32_e32 v54, v40
	v_mov_b32_e32 v70, v20
	v_mov_b32_e32 v56, v26
	v_mov_b32_e32 v76, v36
	v_mov_b32_e32 v52, v34
	v_mov_b32_e32 v74, v86
	v_mov_b32_e32 v48, v84
	v_mov_b32_e32 v50, v60
	v_mov_b32_e32 v28, v66
	v_mov_b32_e32 v32, v96
	v_mov_b32_e32 v12, v88
	v_mov_b32_e32 v16, v92
	v_mov_b32_e32 v4, v138
	v_mov_b32_e32 v6, v122

.LBB0_503:
	s_or_b64 exec, exec, s[0:1]
	v_pk_mul_f32 v[22:23], v[32:33], s[6:7] op_sel_hi:[1,0]
	v_pk_add_f32 v[26:27], v[24:25], v[30:31]
	v_pk_add_f32 v[24:25], v[24:25], v[30:31] neg_lo:[0,1] neg_hi:[0,1]
	v_pk_add_f32 v[30:31], v[64:65], v[68:69]
	v_pk_add_f32 v[32:33], v[64:65], v[68:69] neg_lo:[0,1] neg_hi:[0,1]
	v_pk_add_f32 v[34:35], v[62:63], v[90:91]
	v_pk_add_f32 v[38:39], v[94:95], v[80:81]
	v_pk_add_f32 v[40:41], v[94:95], v[80:81] neg_lo:[0,1] neg_hi:[0,1]
	v_pk_add_f32 v[68:69], v[26:27], v[30:31]
	v_pk_add_f32 v[26:27], v[26:27], v[30:31] neg_lo:[0,1] neg_hi:[0,1]
	v_xor_b32_e32 v30, 0x80000000, v33
	v_mov_b32_e32 v31, v32
	v_pk_mul_f32 v[20:21], v[50:51], s[6:7] op_sel_hi:[1,0]
	v_pk_add_f32 v[36:37], v[62:63], v[90:91] neg_lo:[0,1] neg_hi:[0,1]
	v_pk_add_f32 v[42:43], v[78:79], v[136:137]
	v_pk_add_f32 v[46:47], v[130:131], v[120:121]
	v_pk_add_f32 v[50:51], v[130:131], v[120:121] neg_lo:[0,1] neg_hi:[0,1]
	v_pk_add_f32 v[32:33], v[24:25], v[30:31]
	v_pk_add_f32 v[24:25], v[24:25], v[30:31] neg_lo:[0,1] neg_hi:[0,1]
	v_pk_add_f32 v[30:31], v[34:35], v[38:39]
	v_pk_add_f32 v[34:35], v[34:35], v[38:39] neg_lo:[0,1] neg_hi:[0,1]
	v_xor_b32_e32 v38, 0x80000000, v41
	v_mov_b32_e32 v39, v40
	v_pk_add_f32 v[44:45], v[78:79], v[136:137] neg_lo:[0,1] neg_hi:[0,1]
	v_pk_add_f32 v[60:61], v[128:129], v[150:151]
	v_pk_add_f32 v[64:65], v[168:169], v[144:145]
	v_pk_add_f32 v[66:67], v[168:169], v[144:145] neg_lo:[0,1] neg_hi:[0,1]
	v_pk_add_f32 v[40:41], v[36:37], v[38:39]
	v_pk_add_f32 v[36:37], v[36:37], v[38:39] neg_lo:[0,1] neg_hi:[0,1]
	v_pk_add_f32 v[38:39], v[42:43], v[46:47]
	v_pk_add_f32 v[42:43], v[42:43], v[46:47] neg_lo:[0,1] neg_hi:[0,1]
	v_xor_b32_e32 v46, 0x80000000, v51
	v_mov_b32_e32 v47, v50
	v_pk_add_f32 v[62:63], v[128:129], v[150:151] neg_lo:[0,1] neg_hi:[0,1]
	v_pk_add_f32 v[50:51], v[44:45], v[46:47]
	v_pk_add_f32 v[44:45], v[44:45], v[46:47] neg_lo:[0,1] neg_hi:[0,1]
	v_pk_add_f32 v[46:47], v[60:61], v[64:65]
	v_pk_add_f32 v[60:61], v[60:61], v[64:65] neg_lo:[0,1] neg_hi:[0,1]
	v_xor_b32_e32 v64, 0x80000000, v67
	v_mov_b32_e32 v65, v66
	s_mov_b32 s78, s37
	s_mov_b32 s79, s36
	v_pk_add_f32 v[66:67], v[62:63], v[64:65]
	v_pk_add_f32 v[62:63], v[62:63], v[64:65] neg_lo:[0,1] neg_hi:[0,1]
	v_pk_add_f32 v[64:65], v[68:69], v[30:31]
	v_pk_add_f32 v[30:31], v[68:69], v[30:31] neg_lo:[0,1] neg_hi:[0,1]
	s_mov_b32 s0, s37
	v_pk_mul_f32 v[68:69], v[40:41], s[78:79]
	s_mov_b32 s80, s19
	v_pk_fma_f32 v[40:41], v[40:41], s[0:1], v[68:69] op_sel:[0,0,1] op_sel_hi:[1,0,0]
	s_mov_b32 s81, s18
	v_pk_add_f32 v[68:69], v[32:33], v[40:41]
	v_pk_add_f32 v[32:33], v[32:33], v[40:41] neg_lo:[0,1] neg_hi:[0,1]
	v_xor_b32_e32 v40, 0x80000000, v35
	v_mov_b32_e32 v41, v34
	v_pk_add_f32 v[34:35], v[26:27], v[40:41]
	v_pk_add_f32 v[26:27], v[26:27], v[40:41] neg_lo:[0,1] neg_hi:[0,1]
	v_pk_mul_f32 v[40:41], v[36:37], s[78:79]
	s_mov_b32 s82, s19
	v_pk_fma_f32 v[36:37], v[36:37], s[0:1], v[40:41] op_sel:[0,0,1] op_sel_hi:[1,0,0] neg_lo:[1,0,0] neg_hi:[1,0,0]
	v_pk_mul_f32 v[2:3], v[72:73], s[6:7] op_sel_hi:[1,0]
	v_pk_add_f32 v[40:41], v[24:25], v[36:37]
	v_pk_add_f32 v[24:25], v[24:25], v[36:37] neg_lo:[0,1] neg_hi:[0,1]
	v_pk_add_f32 v[36:37], v[38:39], v[46:47]
	v_pk_add_f32 v[38:39], v[38:39], v[46:47] neg_lo:[0,1] neg_hi:[0,1]
	v_pk_mul_f32 v[46:47], v[66:67], s[78:79]
	v_pk_mul_f32 v[8:9], v[70:71], s[6:7] op_sel_hi:[1,0]
	v_pk_fma_f32 v[46:47], v[66:67], s[0:1], v[46:47] op_sel:[0,0,1] op_sel_hi:[1,0,0]
	v_pk_mul_f32 v[10:11], v[76:77], s[6:7] op_sel_hi:[1,0]
	v_pk_add_f32 v[66:67], v[50:51], v[46:47]
	v_pk_add_f32 v[46:47], v[50:51], v[46:47] neg_lo:[0,1] neg_hi:[0,1]
	v_xor_b32_e32 v50, 0x80000000, v61
	v_mov_b32_e32 v51, v60
	v_pk_add_f32 v[60:61], v[42:43], v[50:51]
	v_pk_add_f32 v[42:43], v[42:43], v[50:51] neg_lo:[0,1] neg_hi:[0,1]
	v_pk_mul_f32 v[50:51], v[62:63], s[78:79]
	v_pk_mul_f32 v[14:15], v[74:75], s[6:7] op_sel_hi:[1,0]
	v_pk_fma_f32 v[50:51], v[62:63], s[0:1], v[50:51] op_sel:[0,0,1] op_sel_hi:[1,0,0] neg_lo:[1,0,0] neg_hi:[1,0,0]
	v_pk_mul_f32 v[16:17], v[16:17], s[6:7] op_sel_hi:[1,0]
	v_pk_add_f32 v[62:63], v[44:45], v[50:51]
	v_pk_add_f32 v[44:45], v[44:45], v[50:51] neg_lo:[0,1] neg_hi:[0,1]
	v_pk_add_f32 v[50:51], v[64:65], v[36:37]
	v_pk_add_f32 v[36:37], v[64:65], v[36:37] neg_lo:[0,1] neg_hi:[0,1]
	v_pk_mul_f32 v[64:65], v[66:67], s[80:81]
	v_pk_mul_f32 v[6:7], v[6:7], s[6:7] op_sel_hi:[1,0]
	v_pk_fma_f32 v[64:65], v[66:67], s[16:17], v[64:65] op_sel:[0,0,1] op_sel_hi:[1,0,0]
	s_mov_b32 s17, s40
	v_pk_add_f32 v[66:67], v[68:69], v[64:65]
	v_pk_add_f32 v[64:65], v[68:69], v[64:65] neg_lo:[0,1] neg_hi:[0,1]
	v_pk_mul_f32 v[68:69], v[60:61], s[78:79]
	s_mov_b32 s88, s11
	v_pk_fma_f32 v[60:61], v[60:61], s[0:1], v[68:69] op_sel:[0,0,1] op_sel_hi:[1,0,0]
	s_mov_b32 s89, s10
	v_pk_add_f32 v[68:69], v[34:35], v[60:61]
	v_pk_add_f32 v[34:35], v[34:35], v[60:61] neg_lo:[0,1] neg_hi:[0,1]
	v_pk_mul_f32 v[60:61], v[62:63], s[16:17]
	s_mov_b32 s62, s27
	v_pk_fma_f32 v[60:61], v[62:63], s[82:83], v[60:61] op_sel:[0,0,1] op_sel_hi:[1,0,0]
	s_mov_b32 s63, s26
	v_pk_add_f32 v[62:63], v[40:41], v[60:61]
	v_pk_add_f32 v[40:41], v[40:41], v[60:61] neg_lo:[0,1] neg_hi:[0,1]
	v_xor_b32_e32 v60, 0x80000000, v39
	v_mov_b32_e32 v61, v38
	v_pk_add_f32 v[38:39], v[30:31], v[60:61]
	v_pk_add_f32 v[30:31], v[30:31], v[60:61] neg_lo:[0,1] neg_hi:[0,1]
	v_pk_mul_f32 v[60:61], v[46:47], s[16:17]
	s_mov_b32 s84, s27
	v_pk_fma_f32 v[46:47], v[46:47], s[82:83], v[60:61] op_sel:[0,0,1] op_sel_hi:[1,0,0] neg_lo:[1,0,0] neg_hi:[1,0,0]
	s_mov_b32 s86, s11
	v_pk_add_f32 v[60:61], v[32:33], v[46:47]
	v_pk_add_f32 v[32:33], v[32:33], v[46:47] neg_lo:[0,1] neg_hi:[0,1]
	v_pk_mul_f32 v[46:47], v[42:43], s[78:79]
	s_ashr_i32 s73, s72, 31
	v_pk_fma_f32 v[42:43], s[0:1], v[42:43], v[46:47] op_sel:[0,0,1] op_sel_hi:[0,1,0] neg_lo:[0,1,0] neg_hi:[0,1,0]
	v_pk_add_f32 v[46:47], v[26:27], v[42:43]
	v_pk_add_f32 v[26:27], v[26:27], v[42:43] neg_lo:[0,1] neg_hi:[0,1]
	v_pk_mul_f32 v[42:43], v[44:45], s[80:81]
	s_nop 0
	v_pk_fma_f32 v[42:43], s[16:17], v[44:45], v[42:43] op_sel:[0,0,1] op_sel_hi:[0,1,0] neg_lo:[0,1,0] neg_hi:[0,1,0]
	v_pk_add_f32 v[44:45], v[24:25], v[42:43]
	v_pk_add_f32 v[24:25], v[24:25], v[42:43] neg_lo:[0,1] neg_hi:[0,1]
	v_pk_fma_f32 v[42:43], v[58:59], s[6:7], v[2:3] op_sel_hi:[1,0,1]
	v_pk_fma_f32 v[2:3], v[58:59], s[6:7], v[2:3] op_sel_hi:[1,0,1] neg_lo:[0,0,1] neg_hi:[0,0,1]
	v_pk_fma_f32 v[58:59], v[54:55], s[6:7], v[8:9] op_sel_hi:[1,0,1]
	v_pk_fma_f32 v[8:9], v[54:55], s[6:7], v[8:9] op_sel_hi:[1,0,1] neg_lo:[0,0,1] neg_hi:[0,0,1]
	v_pk_fma_f32 v[54:55], v[56:57], s[6:7], v[10:11] op_sel_hi:[1,0,1]
	v_pk_fma_f32 v[10:11], v[56:57], s[6:7], v[10:11] op_sel_hi:[1,0,1] neg_lo:[0,0,1] neg_hi:[0,0,1]
	v_pk_fma_f32 v[56:57], v[52:53], s[6:7], v[14:15] op_sel_hi:[1,0,1]
	v_pk_fma_f32 v[14:15], v[52:53], s[6:7], v[14:15] op_sel_hi:[1,0,1] neg_lo:[0,0,1] neg_hi:[0,0,1]
	v_pk_fma_f32 v[52:53], v[48:49], s[6:7], v[20:21] op_sel_hi:[1,0,1]
	v_pk_fma_f32 v[20:21], v[48:49], s[6:7], v[20:21] op_sel_hi:[1,0,1] neg_lo:[0,0,1] neg_hi:[0,0,1]
	v_pk_fma_f32 v[48:49], v[28:29], s[6:7], v[22:23] op_sel_hi:[1,0,1]
	v_pk_fma_f32 v[22:23], v[28:29], s[6:7], v[22:23] op_sel_hi:[1,0,1] neg_lo:[0,0,1] neg_hi:[0,0,1]
	v_pk_fma_f32 v[28:29], v[12:13], s[6:7], v[16:17] op_sel_hi:[1,0,1]
	v_pk_fma_f32 v[12:13], v[12:13], s[6:7], v[16:17] op_sel_hi:[1,0,1] neg_lo:[0,0,1] neg_hi:[0,0,1]
	v_pk_fma_f32 v[16:17], v[4:5], s[6:7], v[6:7] op_sel_hi:[1,0,1]
	v_pk_fma_f32 v[4:5], v[4:5], s[6:7], v[6:7] op_sel_hi:[1,0,1] neg_lo:[0,0,1] neg_hi:[0,0,1]
	v_pk_add_f32 v[6:7], v[58:59], v[42:43]
	v_pk_add_f32 v[42:43], v[42:43], v[58:59] neg_lo:[0,1] neg_hi:[0,1]
	v_xor_b32_e32 v58, 0x80000000, v9
	v_mov_b32_e32 v59, v8
	v_pk_add_f32 v[8:9], v[2:3], v[58:59]
	v_pk_add_f32 v[2:3], v[2:3], v[58:59] neg_lo:[0,1] neg_hi:[0,1]
	v_pk_add_f32 v[58:59], v[56:57], v[54:55]
	v_pk_add_f32 v[54:55], v[54:55], v[56:57] neg_lo:[0,1] neg_hi:[0,1]
	v_xor_b32_e32 v56, 0x80000000, v15
	v_mov_b32_e32 v57, v14
	v_pk_add_f32 v[14:15], v[10:11], v[56:57]
	v_pk_add_f32 v[10:11], v[10:11], v[56:57] neg_lo:[0,1] neg_hi:[0,1]
	v_pk_add_f32 v[56:57], v[48:49], v[52:53]
	v_pk_add_f32 v[48:49], v[52:53], v[48:49] neg_lo:[0,1] neg_hi:[0,1]
	v_xor_b32_e32 v52, 0x80000000, v23
	v_mov_b32_e32 v53, v22
	v_pk_add_f32 v[22:23], v[20:21], v[52:53]
	v_pk_add_f32 v[20:21], v[20:21], v[52:53] neg_lo:[0,1] neg_hi:[0,1]
	v_pk_add_f32 v[52:53], v[16:17], v[28:29]
	v_pk_add_f32 v[16:17], v[28:29], v[16:17] neg_lo:[0,1] neg_hi:[0,1]
	v_xor_b32_e32 v28, 0x80000000, v5
	v_mov_b32_e32 v29, v4
	v_pk_add_f32 v[4:5], v[12:13], v[28:29]
	v_pk_add_f32 v[12:13], v[12:13], v[28:29] neg_lo:[0,1] neg_hi:[0,1]
	v_pk_add_f32 v[28:29], v[58:59], v[6:7]
	v_pk_add_f32 v[6:7], v[6:7], v[58:59] neg_lo:[0,1] neg_hi:[0,1]
	v_pk_mul_f32 v[58:59], v[14:15], s[78:79]
	s_nop 0
	v_pk_fma_f32 v[14:15], s[0:1], v[14:15], v[58:59] op_sel:[0,0,1] op_sel_hi:[0,1,0]
	v_pk_add_f32 v[58:59], v[14:15], v[8:9]
	v_pk_add_f32 v[8:9], v[8:9], v[14:15] neg_lo:[0,1] neg_hi:[0,1]
	v_xor_b32_e32 v14, 0x80000000, v55
	v_mov_b32_e32 v15, v54
	v_pk_add_f32 v[54:55], v[14:15], v[42:43]
	v_pk_add_f32 v[14:15], v[42:43], v[14:15] neg_lo:[0,1] neg_hi:[0,1]
	v_pk_mul_f32 v[42:43], v[10:11], s[78:79]
	s_nop 0
	v_pk_fma_f32 v[10:11], s[0:1], v[10:11], v[42:43] op_sel:[0,0,1] op_sel_hi:[0,1,0] neg_lo:[0,1,0] neg_hi:[0,1,0]
	v_pk_add_f32 v[42:43], v[10:11], v[2:3]
	v_pk_add_f32 v[2:3], v[2:3], v[10:11] neg_lo:[0,1] neg_hi:[0,1]
	v_pk_add_f32 v[10:11], v[52:53], v[56:57]
	v_pk_add_f32 v[52:53], v[56:57], v[52:53] neg_lo:[0,1] neg_hi:[0,1]
	v_pk_mul_f32 v[56:57], v[4:5], s[78:79]
	s_nop 0
	v_pk_fma_f32 v[4:5], s[0:1], v[4:5], v[56:57] op_sel:[0,0,1] op_sel_hi:[0,1,0]
	v_pk_add_f32 v[56:57], v[4:5], v[22:23]
	v_pk_add_f32 v[4:5], v[22:23], v[4:5] neg_lo:[0,1] neg_hi:[0,1]
	v_xor_b32_e32 v22, 0x80000000, v17
	v_mov_b32_e32 v23, v16
	v_pk_add_f32 v[16:17], v[22:23], v[48:49]
	v_pk_add_f32 v[22:23], v[48:49], v[22:23] neg_lo:[0,1] neg_hi:[0,1]
	v_pk_mul_f32 v[48:49], v[12:13], s[78:79]
	s_nop 0
	v_pk_fma_f32 v[12:13], s[0:1], v[12:13], v[48:49] op_sel:[0,0,1] op_sel_hi:[0,1,0] neg_lo:[0,1,0] neg_hi:[0,1,0]
	v_pk_add_f32 v[48:49], v[12:13], v[20:21]
	v_pk_add_f32 v[12:13], v[20:21], v[12:13] neg_lo:[0,1] neg_hi:[0,1]
	v_pk_add_f32 v[20:21], v[10:11], v[28:29]
	v_pk_add_f32 v[10:11], v[28:29], v[10:11] neg_lo:[0,1] neg_hi:[0,1]
	v_pk_mul_f32 v[28:29], v[56:57], s[80:81]
	s_nop 0
	v_pk_fma_f32 v[28:29], s[16:17], v[56:57], v[28:29] op_sel:[0,0,1] op_sel_hi:[0,1,0]
	v_pk_add_f32 v[56:57], v[28:29], v[58:59]
	v_pk_add_f32 v[28:29], v[58:59], v[28:29] neg_lo:[0,1] neg_hi:[0,1]
	v_pk_mul_f32 v[58:59], v[16:17], s[78:79]
	s_nop 0
	v_pk_fma_f32 v[16:17], s[0:1], v[16:17], v[58:59] op_sel:[0,0,1] op_sel_hi:[0,1,0]
	v_pk_add_f32 v[58:59], v[16:17], v[54:55]
	v_pk_add_f32 v[16:17], v[54:55], v[16:17] neg_lo:[0,1] neg_hi:[0,1]
	v_pk_mul_f32 v[54:55], v[48:49], s[16:17]
	s_nop 0
	v_pk_fma_f32 v[48:49], s[82:83], v[48:49], v[54:55] op_sel:[0,0,1] op_sel_hi:[0,1,0]
	v_pk_add_f32 v[54:55], v[48:49], v[42:43]
	v_pk_add_f32 v[42:43], v[42:43], v[48:49] neg_lo:[0,1] neg_hi:[0,1]
	v_xor_b32_e32 v48, 0x80000000, v53
	v_mov_b32_e32 v49, v52
	v_pk_add_f32 v[52:53], v[48:49], v[6:7]
	v_pk_add_f32 v[6:7], v[6:7], v[48:49] neg_lo:[0,1] neg_hi:[0,1]
	v_pk_mul_f32 v[48:49], v[4:5], s[16:17]
	s_nop 0
	v_pk_fma_f32 v[4:5], s[82:83], v[4:5], v[48:49] op_sel:[0,0,1] op_sel_hi:[0,1,0] neg_lo:[0,1,0] neg_hi:[0,1,0]
	v_pk_add_f32 v[48:49], v[4:5], v[8:9]
	v_pk_add_f32 v[4:5], v[8:9], v[4:5] neg_lo:[0,1] neg_hi:[0,1]
	v_pk_mul_f32 v[8:9], v[22:23], s[78:79]
	s_nop 0
	v_pk_fma_f32 v[8:9], s[0:1], v[22:23], v[8:9] op_sel:[0,0,1] op_sel_hi:[0,1,0] neg_lo:[0,1,0] neg_hi:[0,1,0]
	v_pk_add_f32 v[22:23], v[8:9], v[14:15]
	v_pk_add_f32 v[8:9], v[14:15], v[8:9] neg_lo:[0,1] neg_hi:[0,1]
	v_pk_mul_f32 v[14:15], v[12:13], s[80:81]
	s_nop 0
	v_pk_fma_f32 v[12:13], s[16:17], v[12:13], v[14:15] op_sel:[0,0,1] op_sel_hi:[0,1,0] neg_lo:[0,1,0] neg_hi:[0,1,0]
	v_pk_add_f32 v[14:15], v[12:13], v[2:3]
	v_pk_add_f32 v[2:3], v[2:3], v[12:13] neg_lo:[0,1] neg_hi:[0,1]
	ds_write_b64 v211, v[50:51]
	ds_write_b64 v212, v[20:21]
	ds_write_b64 v211, v[66:67] offset:8
	ds_write_b64 v212, v[56:57] offset:8
	ds_write_b64 v211, v[68:69] offset:16
	ds_write_b64 v212, v[58:59] offset:16
	ds_write_b64 v211, v[62:63] offset:24
	ds_write_b64 v212, v[54:55] offset:24
	ds_write_b64 v211, v[38:39] offset:32
	ds_write_b64 v212, v[52:53] offset:32
	ds_write_b64 v211, v[60:61] offset:40
	ds_write_b64 v212, v[48:49] offset:40
	ds_write_b64 v211, v[46:47] offset:48
	ds_write_b64 v212, v[22:23] offset:48
	ds_write_b64 v211, v[44:45] offset:56
	ds_write_b64 v212, v[14:15] offset:56
	ds_write_b64 v211, v[36:37] offset:64
	ds_write_b64 v212, v[10:11] offset:64
	ds_write_b64 v211, v[64:65] offset:72
	ds_write_b64 v212, v[28:29] offset:72
	ds_write_b64 v211, v[34:35] offset:80
	ds_write_b64 v212, v[16:17] offset:80
	ds_write_b64 v211, v[40:41] offset:88
	ds_write_b64 v212, v[42:43] offset:88
	ds_write_b64 v211, v[30:31] offset:96
	ds_write_b64 v212, v[6:7] offset:96
	ds_write_b64 v211, v[32:33] offset:104
	ds_write_b64 v212, v[4:5] offset:104
	ds_write_b64 v211, v[26:27] offset:112
	ds_write_b64 v212, v[8:9] offset:112
	ds_write_b64 v211, v[24:25] offset:120
	ds_write_b64 v212, v[2:3] offset:120
	v_mov_b32_e32 v2, v210
	s_waitcnt lgkmcnt(0)
	s_barrier
	s_nop 0
	v_and_b32_e32 v3, 15, v2
	v_lshlrev_b32_e32 v5, 3, v3
	v_cvt_f32_ubyte0_e32 v3, v3
	v_mul_f32_e32 v3, 0x3b000000, v3
	v_sin_f32_e32 v17, v3
	v_cos_f32_e32 v16, v3
	v_lshlrev_b32_e32 v2, 5, v2
	v_and_b32_e32 v2, 0xfffffe00, v2
	v_lshl_add_u32 v4, v2, 3, 0
	v_ashrrev_i32_e32 v2, 2, v2
	s_nop 0
	v_add3_u32 v2, v4, v5, v2
	v_pk_mul_f32 v[4:5], v[16:17], v[16:17] op_sel:[1,1] op_sel_hi:[0,1] neg_lo:[0,1]
	v_pk_fma_f32 v[74:75], v[16:17], v[16:17], v[4:5] op_sel_hi:[1,0,1]
	v_add_u32_e32 v3, 0x800, v2
	v_pk_mul_f32 v[4:5], v[16:17], v[74:75] op_sel:[1,1] op_sel_hi:[1,0] neg_lo:[1,0]
	v_xor_b32_e32 v78, 0x80000000, v75
	v_mov_b32_e32 v79, v75
	v_pk_fma_f32 v[76:77], v[16:17], v[74:75], v[4:5] op_sel_hi:[0,1,1]
	v_pk_mul_f32 v[4:5], v[74:75], v[78:79] op_sel:[1,0] op_sel_hi:[0,1]
	v_pk_fma_f32 v[80:81], v[74:75], v[74:75], v[4:5] op_sel_hi:[1,0,1]
	v_xor_b32_e32 v84, 0x80000000, v77
	v_pk_mul_f32 v[4:5], v[16:17], v[80:81] op_sel:[1,1] op_sel_hi:[1,0] neg_lo:[1,0]
	v_mov_b32_e32 v85, v77
	v_pk_fma_f32 v[86:87], v[16:17], v[80:81], v[4:5] op_sel_hi:[0,1,1]
	v_pk_mul_f32 v[4:5], v[78:79], v[80:81] op_sel:[0,1] op_sel_hi:[1,0]
	v_xor_b32_e32 v82, 0x80000000, v81
	v_mov_b32_e32 v83, v81
	v_pk_fma_f32 v[90:91], v[74:75], v[80:81], v[4:5] op_sel_hi:[0,1,1]
	v_pk_mul_f32 v[4:5], v[80:81], v[84:85] op_sel:[1,0] op_sel_hi:[0,1]
	v_pk_fma_f32 v[94:95], v[80:81], v[76:77], v[4:5] op_sel_hi:[1,0,1]
	v_pk_mul_f32 v[4:5], v[80:81], v[82:83] op_sel:[1,0] op_sel_hi:[0,1]
	v_pk_fma_f32 v[98:99], v[80:81], v[80:81], v[4:5] op_sel_hi:[1,0,1]
	v_xor_b32_e32 v88, 0x80000000, v87
	v_pk_mul_f32 v[4:5], v[16:17], v[98:99] op_sel:[1,1] op_sel_hi:[1,0] neg_lo:[1,0]
	v_mov_b32_e32 v89, v87
	v_pk_fma_f32 v[102:103], v[16:17], v[98:99], v[4:5] op_sel_hi:[0,1,1]
	v_pk_mul_f32 v[4:5], v[78:79], v[98:99] op_sel:[0,1] op_sel_hi:[1,0]
	v_xor_b32_e32 v92, 0x80000000, v91
	v_pk_fma_f32 v[106:107], v[74:75], v[98:99], v[4:5] op_sel_hi:[0,1,1]
	v_pk_mul_f32 v[4:5], v[84:85], v[98:99] op_sel:[0,1] op_sel_hi:[1,0]
	v_mov_b32_e32 v93, v91
	v_pk_fma_f32 v[110:111], v[76:77], v[98:99], v[4:5] op_sel_hi:[0,1,1]
	v_pk_mul_f32 v[4:5], v[82:83], v[98:99] op_sel:[0,1] op_sel_hi:[1,0]
	v_xor_b32_e32 v96, 0x80000000, v95
	v_pk_fma_f32 v[114:115], v[80:81], v[98:99], v[4:5] op_sel_hi:[0,1,1]
	v_pk_mul_f32 v[4:5], v[16:17], v[114:115] op_sel:[1,1] op_sel_hi:[1,0] neg_lo:[1,0]
	v_mov_b32_e32 v97, v95
	v_pk_fma_f32 v[118:119], v[16:17], v[114:115], v[4:5] op_sel_hi:[0,1,1]
	v_pk_mul_f32 v[4:5], v[78:79], v[114:115] op_sel:[0,1] op_sel_hi:[1,0]
	v_xor_b32_e32 v100, 0x80000000, v99
	v_pk_fma_f32 v[122:123], v[74:75], v[114:115], v[4:5] op_sel_hi:[0,1,1]
	v_pk_mul_f32 v[4:5], v[84:85], v[114:115] op_sel:[0,1] op_sel_hi:[1,0]
	v_mov_b32_e32 v101, v99
	v_pk_fma_f32 v[126:127], v[76:77], v[114:115], v[4:5] op_sel_hi:[0,1,1]
	v_pk_mul_f32 v[4:5], v[82:83], v[114:115] op_sel:[0,1] op_sel_hi:[1,0]
	v_xor_b32_e32 v104, 0x80000000, v103
	v_pk_fma_f32 v[130:131], v[80:81], v[114:115], v[4:5] op_sel_hi:[0,1,1]
	v_pk_mul_f32 v[4:5], v[16:17], v[130:131] op_sel:[1,1] op_sel_hi:[1,0] neg_lo:[1,0]
	v_mov_b32_e32 v105, v103
	v_pk_fma_f32 v[134:135], v[16:17], v[130:131], v[4:5] op_sel_hi:[0,1,1]
	v_pk_mul_f32 v[4:5], v[78:79], v[130:131] op_sel:[0,1] op_sel_hi:[1,0]
	v_xor_b32_e32 v108, 0x80000000, v107
	v_pk_fma_f32 v[138:139], v[74:75], v[130:131], v[4:5] op_sel_hi:[0,1,1]
	v_pk_mul_f32 v[4:5], v[84:85], v[130:131] op_sel:[0,1] op_sel_hi:[1,0]
	v_mov_b32_e32 v109, v107
	v_pk_fma_f32 v[142:143], v[76:77], v[130:131], v[4:5] op_sel_hi:[0,1,1]
	v_pk_mul_f32 v[4:5], v[82:83], v[130:131] op_sel:[0,1] op_sel_hi:[1,0]
	v_xor_b32_e32 v112, 0x80000000, v111
	v_pk_fma_f32 v[148:149], v[80:81], v[130:131], v[4:5] op_sel_hi:[0,1,1]
	v_pk_mul_f32 v[4:5], v[16:17], v[148:149] op_sel:[1,1] op_sel_hi:[1,0] neg_lo:[1,0]
	v_mov_b32_e32 v113, v111
	v_pk_fma_f32 v[152:153], v[16:17], v[148:149], v[4:5] op_sel_hi:[0,1,1]
	v_pk_mul_f32 v[4:5], v[78:79], v[148:149] op_sel:[0,1] op_sel_hi:[1,0]
	v_xor_b32_e32 v116, 0x80000000, v115
	v_pk_fma_f32 v[156:157], v[74:75], v[148:149], v[4:5] op_sel_hi:[0,1,1]
	v_pk_mul_f32 v[4:5], v[84:85], v[148:149] op_sel:[0,1] op_sel_hi:[1,0]
	v_mov_b32_e32 v117, v115
	v_pk_fma_f32 v[160:161], v[76:77], v[148:149], v[4:5] op_sel_hi:[0,1,1]
	v_pk_mul_f32 v[4:5], v[82:83], v[148:149] op_sel:[0,1] op_sel_hi:[1,0]
	v_xor_b32_e32 v120, 0x80000000, v119
	v_pk_fma_f32 v[164:165], v[80:81], v[148:149], v[4:5] op_sel_hi:[0,1,1]
	v_pk_mul_f32 v[4:5], v[16:17], v[164:165] op_sel:[1,1] op_sel_hi:[1,0] neg_lo:[1,0]
	v_mov_b32_e32 v121, v119
	v_pk_fma_f32 v[168:169], v[16:17], v[164:165], v[4:5] op_sel_hi:[0,1,1]
	v_pk_mul_f32 v[4:5], v[78:79], v[164:165] op_sel:[0,1] op_sel_hi:[1,0]
	v_xor_b32_e32 v124, 0x80000000, v123
	v_pk_fma_f32 v[172:173], v[74:75], v[164:165], v[4:5] op_sel_hi:[0,1,1]
	v_pk_mul_f32 v[4:5], v[84:85], v[164:165] op_sel:[0,1] op_sel_hi:[1,0]
	v_mov_b32_e32 v125, v123
	v_pk_fma_f32 v[176:177], v[76:77], v[164:165], v[4:5] op_sel_hi:[0,1,1]
	v_pk_mul_f32 v[4:5], v[82:83], v[164:165] op_sel:[0,1] op_sel_hi:[1,0]
	v_xor_b32_e32 v128, 0x80000000, v127
	v_pk_fma_f32 v[180:181], v[80:81], v[164:165], v[4:5] op_sel_hi:[0,1,1]
	v_pk_mul_f32 v[4:5], v[16:17], v[180:181] op_sel:[1,1] op_sel_hi:[1,0] neg_lo:[1,0]
	v_mov_b32_e32 v129, v127
	v_pk_fma_f32 v[184:185], v[16:17], v[180:181], v[4:5] op_sel_hi:[0,1,1]
	v_pk_mul_f32 v[4:5], v[78:79], v[180:181] op_sel:[0,1] op_sel_hi:[1,0]
	v_xor_b32_e32 v132, 0x80000000, v131
	v_pk_fma_f32 v[188:189], v[74:75], v[180:181], v[4:5] op_sel_hi:[0,1,1]
	v_pk_mul_f32 v[4:5], v[84:85], v[180:181] op_sel:[0,1] op_sel_hi:[1,0]
	v_mov_b32_e32 v133, v131
	v_pk_fma_f32 v[192:193], v[76:77], v[180:181], v[4:5] op_sel_hi:[0,1,1]
	ds_read2_b64 v[4:7], v2 offset1:16
	ds_read2_b64 v[8:11], v2 offset0:33 offset1:49
	ds_read2_b64 v[12:15], v2 offset0:66 offset1:82
	ds_read2_b64 v[20:23], v2 offset0:99 offset1:115
	ds_read2_b64 v[24:27], v2 offset0:132 offset1:148
	ds_read2_b64 v[28:31], v2 offset0:165 offset1:181
	ds_read2_b64 v[32:35], v2 offset0:198 offset1:214
	ds_read2_b64 v[36:39], v2 offset0:231 offset1:247
	ds_read2_b64 v[40:43], v3 offset0:8 offset1:24
	ds_read2_b64 v[44:47], v3 offset0:41 offset1:57
	ds_read2_b64 v[48:51], v3 offset0:74 offset1:90
	ds_read2_b64 v[52:55], v3 offset0:107 offset1:123
	ds_read2_b64 v[56:59], v3 offset0:140 offset1:156
	ds_read2_b64 v[60:63], v3 offset0:173 offset1:189
	ds_read2_b64 v[64:67], v3 offset0:206 offset1:222
	ds_read2_b64 v[68:71], v3 offset0:239 offset1:255
	s_waitcnt lgkmcnt(7)
	v_pk_mul_f32 v[72:73], v[16:17], v[40:41] op_sel:[1,1] op_sel_hi:[1,0] neg_lo:[1,0]
	v_xor_b32_e32 v136, 0x80000000, v135
	v_pk_fma_f32 v[16:17], v[16:17], v[40:41], v[72:73] op_sel_hi:[0,1,1]
	v_pk_mul_f32 v[40:41], v[24:25], v[78:79] op_sel:[1,0] op_sel_hi:[0,1]
	v_pk_fma_f32 v[24:25], v[24:25], v[74:75], v[40:41] op_sel_hi:[1,0,1]
	s_waitcnt lgkmcnt(3)
	v_pk_mul_f32 v[40:41], v[84:85], v[56:57] op_sel:[0,1] op_sel_hi:[1,0]
	v_mov_b32_e32 v137, v135
	v_pk_fma_f32 v[40:41], v[76:77], v[56:57], v[40:41] op_sel_hi:[0,1,1]
	v_pk_mul_f32 v[56:57], v[12:13], v[82:83] op_sel:[1,0] op_sel_hi:[0,1]
	v_pk_fma_f32 v[12:13], v[12:13], v[80:81], v[56:57] op_sel_hi:[1,0,1]
	v_pk_mul_f32 v[56:57], v[88:89], v[48:49] op_sel:[0,1] op_sel_hi:[1,0]
	v_xor_b32_e32 v140, 0x80000000, v139
	v_pk_fma_f32 v[48:49], v[86:87], v[48:49], v[56:57] op_sel_hi:[0,1,1]
	v_pk_mul_f32 v[56:57], v[32:33], v[92:93] op_sel:[1,0] op_sel_hi:[0,1]
	v_pk_fma_f32 v[32:33], v[32:33], v[90:91], v[56:57] op_sel_hi:[1,0,1]
	s_waitcnt lgkmcnt(1)
	v_pk_mul_f32 v[56:57], v[96:97], v[64:65] op_sel:[0,1] op_sel_hi:[1,0]
	v_mov_b32_e32 v141, v139
	v_pk_fma_f32 v[56:57], v[94:95], v[64:65], v[56:57] op_sel_hi:[0,1,1]
	v_pk_mul_f32 v[64:65], v[8:9], v[100:101] op_sel:[1,0] op_sel_hi:[0,1]
	v_pk_fma_f32 v[8:9], v[8:9], v[98:99], v[64:65] op_sel_hi:[1,0,1]
	v_pk_mul_f32 v[64:65], v[44:45], v[104:105] op_sel:[1,0] op_sel_hi:[0,1]
	v_pk_fma_f32 v[44:45], v[44:45], v[102:103], v[64:65] op_sel_hi:[1,0,1]
	v_pk_mul_f32 v[64:65], v[28:29], v[108:109] op_sel:[1,0] op_sel_hi:[0,1]
	v_pk_fma_f32 v[28:29], v[28:29], v[106:107], v[64:65] op_sel_hi:[1,0,1]
	v_pk_mul_f32 v[64:65], v[112:113], v[60:61] op_sel:[0,1] op_sel_hi:[1,0]
	v_xor_b32_e32 v144, 0x80000000, v143
	v_pk_fma_f32 v[60:61], v[110:111], v[60:61], v[64:65] op_sel_hi:[0,1,1]
	v_pk_mul_f32 v[64:65], v[20:21], v[116:117] op_sel:[1,0] op_sel_hi:[0,1]
	v_pk_fma_f32 v[20:21], v[20:21], v[114:115], v[64:65] op_sel_hi:[1,0,1]
	v_pk_mul_f32 v[64:65], v[52:53], v[120:121] op_sel:[1,0] op_sel_hi:[0,1]
	v_pk_fma_f32 v[52:53], v[52:53], v[118:119], v[64:65] op_sel_hi:[1,0,1]
	v_pk_mul_f32 v[64:65], v[36:37], v[124:125] op_sel:[1,0] op_sel_hi:[0,1]
	v_pk_fma_f32 v[36:37], v[36:37], v[122:123], v[64:65] op_sel_hi:[1,0,1]
	s_waitcnt lgkmcnt(0)
	v_pk_mul_f32 v[64:65], v[128:129], v[68:69] op_sel:[0,1] op_sel_hi:[1,0]
	v_mov_b32_e32 v145, v143
	v_pk_fma_f32 v[64:65], v[126:127], v[68:69], v[64:65] op_sel_hi:[0,1,1]
	v_pk_mul_f32 v[68:69], v[6:7], v[132:133] op_sel:[1,0] op_sel_hi:[0,1]
	v_pk_fma_f32 v[6:7], v[6:7], v[130:131], v[68:69] op_sel_hi:[1,0,1]
	v_pk_mul_f32 v[68:69], v[42:43], v[136:137] op_sel:[1,0] op_sel_hi:[0,1]
	v_pk_fma_f32 v[42:43], v[42:43], v[134:135], v[68:69] op_sel_hi:[1,0,1]
	v_pk_mul_f32 v[68:69], v[26:27], v[140:141] op_sel:[1,0] op_sel_hi:[0,1]
	v_xor_b32_e32 v150, 0x80000000, v149
	v_mov_b32_e32 v151, v149
	v_pk_fma_f32 v[26:27], v[26:27], v[138:139], v[68:69] op_sel_hi:[1,0,1]
	v_pk_mul_f32 v[68:69], v[58:59], v[144:145] op_sel:[1,0] op_sel_hi:[0,1]
	v_xor_b32_e32 v154, 0x80000000, v153
	v_mov_b32_e32 v155, v153
	v_pk_fma_f32 v[58:59], v[58:59], v[142:143], v[68:69] op_sel_hi:[1,0,1]
	v_pk_mul_f32 v[68:69], v[14:15], v[150:151] op_sel:[1,0] op_sel_hi:[0,1]
	v_xor_b32_e32 v158, 0x80000000, v157
	v_mov_b32_e32 v159, v157
	v_pk_fma_f32 v[14:15], v[14:15], v[148:149], v[68:69] op_sel_hi:[1,0,1]
	v_pk_mul_f32 v[68:69], v[50:51], v[154:155] op_sel:[1,0] op_sel_hi:[0,1]
	v_xor_b32_e32 v162, 0x80000000, v161
	v_mov_b32_e32 v163, v161
	v_pk_fma_f32 v[50:51], v[50:51], v[152:153], v[68:69] op_sel_hi:[1,0,1]
	v_pk_mul_f32 v[68:69], v[34:35], v[158:159] op_sel:[1,0] op_sel_hi:[0,1]
	v_xor_b32_e32 v166, 0x80000000, v165
	v_mov_b32_e32 v167, v165
	v_pk_fma_f32 v[34:35], v[34:35], v[156:157], v[68:69] op_sel_hi:[1,0,1]
	v_pk_mul_f32 v[68:69], v[162:163], v[66:67] op_sel:[0,1] op_sel_hi:[1,0]
	v_xor_b32_e32 v170, 0x80000000, v169
	v_mov_b32_e32 v171, v169
	v_pk_fma_f32 v[66:67], v[160:161], v[66:67], v[68:69] op_sel_hi:[0,1,1]
	v_pk_mul_f32 v[68:69], v[10:11], v[166:167] op_sel:[1,0] op_sel_hi:[0,1]
	v_xor_b32_e32 v174, 0x80000000, v173
	v_mov_b32_e32 v175, v173
	v_pk_fma_f32 v[10:11], v[10:11], v[164:165], v[68:69] op_sel_hi:[1,0,1]
	v_pk_mul_f32 v[68:69], v[46:47], v[170:171] op_sel:[1,0] op_sel_hi:[0,1]
	v_xor_b32_e32 v178, 0x80000000, v177
	v_mov_b32_e32 v179, v177
	v_pk_fma_f32 v[46:47], v[46:47], v[168:169], v[68:69] op_sel_hi:[1,0,1]
	v_pk_mul_f32 v[68:69], v[30:31], v[174:175] op_sel:[1,0] op_sel_hi:[0,1]
	v_xor_b32_e32 v182, 0x80000000, v181
	v_mov_b32_e32 v183, v181
	v_pk_fma_f32 v[30:31], v[30:31], v[172:173], v[68:69] op_sel_hi:[1,0,1]
	v_pk_mul_f32 v[68:69], v[62:63], v[178:179] op_sel:[1,0] op_sel_hi:[0,1]
	v_xor_b32_e32 v186, 0x80000000, v185
	v_mov_b32_e32 v187, v185
	v_pk_fma_f32 v[62:63], v[62:63], v[176:177], v[68:69] op_sel_hi:[1,0,1]
	v_pk_mul_f32 v[68:69], v[22:23], v[182:183] op_sel:[1,0] op_sel_hi:[0,1]
	v_xor_b32_e32 v190, 0x80000000, v189
	v_mov_b32_e32 v191, v189
	v_pk_fma_f32 v[22:23], v[22:23], v[180:181], v[68:69] op_sel_hi:[1,0,1]
	v_pk_mul_f32 v[68:69], v[54:55], v[186:187] op_sel:[1,0] op_sel_hi:[0,1]
	v_xor_b32_e32 v194, 0x80000000, v193
	v_mov_b32_e32 v195, v193
	v_pk_fma_f32 v[54:55], v[54:55], v[184:185], v[68:69] op_sel_hi:[1,0,1]
	v_pk_mul_f32 v[68:69], v[38:39], v[190:191] op_sel:[1,0] op_sel_hi:[0,1]
	v_pk_fma_f32 v[38:39], v[38:39], v[188:189], v[68:69] op_sel_hi:[1,0,1]
	v_pk_mul_f32 v[68:69], v[70:71], v[194:195] op_sel:[1,0] op_sel_hi:[0,1]
	v_pk_fma_f32 v[68:69], v[70:71], v[192:193], v[68:69] op_sel_hi:[1,0,1]
	v_pk_add_f32 v[70:71], v[4:5], v[6:7]
	v_pk_add_f32 v[4:5], v[4:5], v[6:7] neg_lo:[0,1] neg_hi:[0,1]
	v_pk_add_f32 v[6:7], v[8:9], v[10:11]
	v_pk_add_f32 v[8:9], v[8:9], v[10:11] neg_lo:[0,1] neg_hi:[0,1]
	v_pk_add_f32 v[10:11], v[12:13], v[14:15]
	v_pk_add_f32 v[12:13], v[12:13], v[14:15] neg_lo:[0,1] neg_hi:[0,1]
	v_pk_add_f32 v[14:15], v[20:21], v[22:23]
	v_pk_add_f32 v[20:21], v[20:21], v[22:23] neg_lo:[0,1] neg_hi:[0,1]
	v_pk_add_f32 v[22:23], v[24:25], v[26:27]
	v_pk_add_f32 v[24:25], v[24:25], v[26:27] neg_lo:[0,1] neg_hi:[0,1]
	v_pk_add_f32 v[26:27], v[28:29], v[30:31]
	v_pk_add_f32 v[28:29], v[28:29], v[30:31] neg_lo:[0,1] neg_hi:[0,1]
	v_pk_add_f32 v[30:31], v[32:33], v[34:35]
	v_pk_add_f32 v[32:33], v[32:33], v[34:35] neg_lo:[0,1] neg_hi:[0,1]
	v_pk_add_f32 v[34:35], v[36:37], v[38:39]
	v_pk_add_f32 v[36:37], v[36:37], v[38:39] neg_lo:[0,1] neg_hi:[0,1]
	v_pk_add_f32 v[38:39], v[16:17], v[42:43]
	v_pk_add_f32 v[16:17], v[16:17], v[42:43] neg_lo:[0,1] neg_hi:[0,1]
	v_pk_add_f32 v[42:43], v[44:45], v[46:47]
	v_pk_add_f32 v[44:45], v[44:45], v[46:47] neg_lo:[0,1] neg_hi:[0,1]
	v_pk_add_f32 v[46:47], v[48:49], v[50:51]
	v_pk_add_f32 v[48:49], v[48:49], v[50:51] neg_lo:[0,1] neg_hi:[0,1]
	v_pk_add_f32 v[50:51], v[52:53], v[54:55]
	v_pk_add_f32 v[52:53], v[52:53], v[54:55] neg_lo:[0,1] neg_hi:[0,1]
	v_pk_add_f32 v[54:55], v[40:41], v[58:59]
	v_pk_add_f32 v[40:41], v[40:41], v[58:59] neg_lo:[0,1] neg_hi:[0,1]
	v_pk_add_f32 v[58:59], v[60:61], v[62:63]
	v_pk_add_f32 v[60:61], v[60:61], v[62:63] neg_lo:[0,1] neg_hi:[0,1]
	v_pk_add_f32 v[62:63], v[56:57], v[66:67]
	v_pk_add_f32 v[56:57], v[56:57], v[66:67] neg_lo:[0,1] neg_hi:[0,1]
	v_pk_add_f32 v[66:67], v[64:65], v[68:69]
	v_pk_add_f32 v[64:65], v[64:65], v[68:69] neg_lo:[0,1] neg_hi:[0,1]
	v_pk_add_f32 v[68:69], v[70:71], v[6:7]
	v_pk_add_f32 v[6:7], v[70:71], v[6:7] neg_lo:[0,1] neg_hi:[0,1]
	v_xor_b32_e32 v70, 0x80000000, v9
	v_mov_b32_e32 v71, v8
	v_pk_add_f32 v[8:9], v[4:5], v[70:71]
	v_pk_add_f32 v[4:5], v[4:5], v[70:71] neg_lo:[0,1] neg_hi:[0,1]
	v_pk_add_f32 v[70:71], v[10:11], v[14:15]
	v_pk_add_f32 v[10:11], v[10:11], v[14:15] neg_lo:[0,1] neg_hi:[0,1]
	v_xor_b32_e32 v14, 0x80000000, v21
	v_mov_b32_e32 v15, v20
	v_pk_add_f32 v[20:21], v[12:13], v[14:15]
	v_pk_add_f32 v[12:13], v[12:13], v[14:15] neg_lo:[0,1] neg_hi:[0,1]
	v_pk_add_f32 v[14:15], v[22:23], v[26:27]
	v_pk_add_f32 v[22:23], v[22:23], v[26:27] neg_lo:[0,1] neg_hi:[0,1]
	v_xor_b32_e32 v26, 0x80000000, v29
	v_mov_b32_e32 v27, v28
	v_pk_add_f32 v[28:29], v[24:25], v[26:27]
	v_pk_add_f32 v[24:25], v[24:25], v[26:27] neg_lo:[0,1] neg_hi:[0,1]
	v_pk_add_f32 v[26:27], v[30:31], v[34:35]
	v_pk_add_f32 v[30:31], v[30:31], v[34:35] neg_lo:[0,1] neg_hi:[0,1]
	v_xor_b32_e32 v34, 0x80000000, v37
	v_mov_b32_e32 v35, v36
	v_pk_add_f32 v[36:37], v[32:33], v[34:35]
	v_pk_add_f32 v[32:33], v[32:33], v[34:35] neg_lo:[0,1] neg_hi:[0,1]
	v_pk_add_f32 v[34:35], v[38:39], v[42:43]
	v_pk_add_f32 v[38:39], v[38:39], v[42:43] neg_lo:[0,1] neg_hi:[0,1]
	v_xor_b32_e32 v42, 0x80000000, v45
	v_mov_b32_e32 v43, v44
	v_pk_add_f32 v[44:45], v[16:17], v[42:43]
	v_pk_add_f32 v[16:17], v[16:17], v[42:43] neg_lo:[0,1] neg_hi:[0,1]
	v_pk_add_f32 v[42:43], v[46:47], v[50:51]
	v_pk_add_f32 v[46:47], v[46:47], v[50:51] neg_lo:[0,1] neg_hi:[0,1]
	v_xor_b32_e32 v50, 0x80000000, v53
	v_mov_b32_e32 v51, v52
	v_pk_add_f32 v[52:53], v[48:49], v[50:51]
	v_pk_add_f32 v[48:49], v[48:49], v[50:51] neg_lo:[0,1] neg_hi:[0,1]
	v_pk_add_f32 v[50:51], v[54:55], v[58:59]
	v_pk_add_f32 v[54:55], v[54:55], v[58:59] neg_lo:[0,1] neg_hi:[0,1]
	v_xor_b32_e32 v58, 0x80000000, v61
	v_mov_b32_e32 v59, v60
	v_pk_add_f32 v[60:61], v[40:41], v[58:59]
	v_pk_add_f32 v[40:41], v[40:41], v[58:59] neg_lo:[0,1] neg_hi:[0,1]
	v_pk_add_f32 v[58:59], v[62:63], v[66:67]
	v_pk_add_f32 v[62:63], v[62:63], v[66:67] neg_lo:[0,1] neg_hi:[0,1]
	v_xor_b32_e32 v66, 0x80000000, v65
	v_mov_b32_e32 v67, v64
	v_pk_add_f32 v[64:65], v[56:57], v[66:67]
	v_pk_add_f32 v[56:57], v[56:57], v[66:67] neg_lo:[0,1] neg_hi:[0,1]
	v_pk_add_f32 v[66:67], v[68:69], v[70:71]
	v_pk_add_f32 v[68:69], v[68:69], v[70:71] neg_lo:[0,1] neg_hi:[0,1]
	v_pk_mul_f32 v[70:71], v[20:21], s[78:79]
	s_nop 0
	v_pk_fma_f32 v[20:21], s[0:1], v[20:21], v[70:71] op_sel:[0,0,1] op_sel_hi:[0,1,0]
	v_pk_add_f32 v[70:71], v[8:9], v[20:21]
	v_pk_add_f32 v[8:9], v[8:9], v[20:21] neg_lo:[0,1] neg_hi:[0,1]
	v_xor_b32_e32 v20, 0x80000000, v11
	v_mov_b32_e32 v21, v10
	v_pk_add_f32 v[10:11], v[6:7], v[20:21]
	v_pk_add_f32 v[6:7], v[6:7], v[20:21] neg_lo:[0,1] neg_hi:[0,1]
	v_pk_mul_f32 v[20:21], v[12:13], s[78:79]
	s_nop 0
	v_pk_fma_f32 v[12:13], s[0:1], v[12:13], v[20:21] op_sel:[0,0,1] op_sel_hi:[0,1,0] neg_lo:[0,1,0] neg_hi:[0,1,0]
	v_pk_add_f32 v[20:21], v[4:5], v[12:13]
	v_pk_add_f32 v[4:5], v[4:5], v[12:13] neg_lo:[0,1] neg_hi:[0,1]
	v_pk_add_f32 v[12:13], v[14:15], v[26:27]
	v_pk_add_f32 v[14:15], v[14:15], v[26:27] neg_lo:[0,1] neg_hi:[0,1]
	v_pk_mul_f32 v[26:27], v[36:37], s[78:79]
	s_nop 0
	v_pk_fma_f32 v[26:27], s[0:1], v[36:37], v[26:27] op_sel:[0,0,1] op_sel_hi:[0,1,0]
	v_pk_add_f32 v[36:37], v[28:29], v[26:27]
	v_pk_add_f32 v[26:27], v[28:29], v[26:27] neg_lo:[0,1] neg_hi:[0,1]
	v_xor_b32_e32 v28, 0x80000000, v31
	v_mov_b32_e32 v29, v30
	v_pk_add_f32 v[30:31], v[22:23], v[28:29]
	v_pk_add_f32 v[22:23], v[22:23], v[28:29] neg_lo:[0,1] neg_hi:[0,1]
	v_pk_mul_f32 v[28:29], v[32:33], s[78:79]
	s_nop 0
	v_pk_fma_f32 v[28:29], s[0:1], v[32:33], v[28:29] op_sel:[0,0,1] op_sel_hi:[0,1,0] neg_lo:[0,1,0] neg_hi:[0,1,0]
	v_pk_add_f32 v[32:33], v[24:25], v[28:29]
	v_pk_add_f32 v[24:25], v[24:25], v[28:29] neg_lo:[0,1] neg_hi:[0,1]
	v_pk_add_f32 v[28:29], v[34:35], v[42:43]
	v_pk_add_f32 v[34:35], v[34:35], v[42:43] neg_lo:[0,1] neg_hi:[0,1]
	v_pk_mul_f32 v[42:43], v[52:53], s[78:79]
	s_nop 0
	v_pk_fma_f32 v[42:43], s[0:1], v[52:53], v[42:43] op_sel:[0,0,1] op_sel_hi:[0,1,0]
	v_pk_add_f32 v[52:53], v[44:45], v[42:43]
	v_pk_add_f32 v[42:43], v[44:45], v[42:43] neg_lo:[0,1] neg_hi:[0,1]
	v_xor_b32_e32 v44, 0x80000000, v47
	v_mov_b32_e32 v45, v46
	v_pk_add_f32 v[46:47], v[38:39], v[44:45]
	v_pk_add_f32 v[38:39], v[38:39], v[44:45] neg_lo:[0,1] neg_hi:[0,1]
	v_pk_mul_f32 v[44:45], v[48:49], s[78:79]
	s_nop 0
	v_pk_fma_f32 v[44:45], s[0:1], v[48:49], v[44:45] op_sel:[0,0,1] op_sel_hi:[0,1,0] neg_lo:[0,1,0] neg_hi:[0,1,0]
	v_pk_add_f32 v[48:49], v[16:17], v[44:45]
	v_pk_add_f32 v[16:17], v[16:17], v[44:45] neg_lo:[0,1] neg_hi:[0,1]
	v_pk_add_f32 v[44:45], v[50:51], v[58:59]
	v_pk_add_f32 v[50:51], v[50:51], v[58:59] neg_lo:[0,1] neg_hi:[0,1]
	v_pk_mul_f32 v[58:59], v[64:65], s[78:79]
	s_nop 0
	v_pk_fma_f32 v[58:59], s[0:1], v[64:65], v[58:59] op_sel:[0,0,1] op_sel_hi:[0,1,0]
	v_pk_add_f32 v[64:65], v[60:61], v[58:59]
	v_pk_add_f32 v[58:59], v[60:61], v[58:59] neg_lo:[0,1] neg_hi:[0,1]
	v_xor_b32_e32 v60, 0x80000000, v63
	v_mov_b32_e32 v61, v62
	v_pk_add_f32 v[62:63], v[54:55], v[60:61]
	v_pk_add_f32 v[54:55], v[54:55], v[60:61] neg_lo:[0,1] neg_hi:[0,1]
	v_pk_mul_f32 v[60:61], v[56:57], s[78:79]
	s_nop 0
	v_pk_fma_f32 v[56:57], s[0:1], v[56:57], v[60:61] op_sel:[0,0,1] op_sel_hi:[0,1,0] neg_lo:[0,1,0] neg_hi:[0,1,0]
	v_pk_add_f32 v[60:61], v[40:41], v[56:57]
	v_pk_add_f32 v[40:41], v[40:41], v[56:57] neg_lo:[0,1] neg_hi:[0,1]
	v_pk_add_f32 v[56:57], v[66:67], v[12:13]
	v_pk_add_f32 v[12:13], v[66:67], v[12:13] neg_lo:[0,1] neg_hi:[0,1]
	v_pk_mul_f32 v[66:67], v[36:37], s[80:81]
	s_nop 0
	v_pk_fma_f32 v[36:37], s[16:17], v[36:37], v[66:67] op_sel:[0,0,1] op_sel_hi:[0,1,0]
	v_pk_add_f32 v[66:67], v[70:71], v[36:37]
	v_pk_add_f32 v[36:37], v[70:71], v[36:37] neg_lo:[0,1] neg_hi:[0,1]
	v_pk_mul_f32 v[70:71], v[30:31], s[78:79]
	s_nop 0
	v_pk_fma_f32 v[30:31], s[0:1], v[30:31], v[70:71] op_sel:[0,0,1] op_sel_hi:[0,1,0]
	v_pk_add_f32 v[70:71], v[10:11], v[30:31]
	v_pk_add_f32 v[10:11], v[10:11], v[30:31] neg_lo:[0,1] neg_hi:[0,1]
	v_pk_mul_f32 v[30:31], v[32:33], s[16:17]
	s_nop 0
	v_pk_fma_f32 v[30:31], s[82:83], v[32:33], v[30:31] op_sel:[0,0,1] op_sel_hi:[0,1,0]
	v_pk_add_f32 v[32:33], v[20:21], v[30:31]
	v_pk_add_f32 v[20:21], v[20:21], v[30:31] neg_lo:[0,1] neg_hi:[0,1]
	v_xor_b32_e32 v30, 0x80000000, v15
	v_mov_b32_e32 v31, v14
	v_pk_add_f32 v[14:15], v[68:69], v[30:31]
	v_pk_add_f32 v[30:31], v[68:69], v[30:31] neg_lo:[0,1] neg_hi:[0,1]
	v_pk_mul_f32 v[68:69], v[26:27], s[16:17]
	s_nop 0
	v_pk_fma_f32 v[26:27], s[82:83], v[26:27], v[68:69] op_sel:[0,0,1] op_sel_hi:[0,1,0] neg_lo:[0,1,0] neg_hi:[0,1,0]
	v_pk_add_f32 v[68:69], v[8:9], v[26:27]
	v_pk_add_f32 v[8:9], v[8:9], v[26:27] neg_lo:[0,1] neg_hi:[0,1]
	v_pk_mul_f32 v[26:27], v[22:23], s[78:79]
	s_nop 0
	v_pk_fma_f32 v[22:23], s[0:1], v[22:23], v[26:27] op_sel:[0,0,1] op_sel_hi:[0,1,0] neg_lo:[0,1,0] neg_hi:[0,1,0]
	v_pk_add_f32 v[26:27], v[6:7], v[22:23]
	v_pk_add_f32 v[6:7], v[6:7], v[22:23] neg_lo:[0,1] neg_hi:[0,1]
	v_pk_mul_f32 v[22:23], v[24:25], s[80:81]
	s_nop 0
	v_pk_fma_f32 v[22:23], s[16:17], v[24:25], v[22:23] op_sel:[0,0,1] op_sel_hi:[0,1,0] neg_lo:[0,1,0] neg_hi:[0,1,0]
	v_pk_add_f32 v[24:25], v[4:5], v[22:23]
	v_pk_add_f32 v[4:5], v[4:5], v[22:23] neg_lo:[0,1] neg_hi:[0,1]
	v_pk_add_f32 v[22:23], v[28:29], v[44:45]
	v_pk_add_f32 v[28:29], v[28:29], v[44:45] neg_lo:[0,1] neg_hi:[0,1]
	v_pk_mul_f32 v[44:45], v[64:65], s[80:81]
	s_nop 0
	v_pk_fma_f32 v[44:45], s[16:17], v[64:65], v[44:45] op_sel:[0,0,1] op_sel_hi:[0,1,0]
	v_pk_add_f32 v[64:65], v[52:53], v[44:45]
	v_pk_add_f32 v[44:45], v[52:53], v[44:45] neg_lo:[0,1] neg_hi:[0,1]
	v_pk_mul_f32 v[52:53], v[62:63], s[78:79]
	s_nop 0
	v_pk_fma_f32 v[52:53], s[0:1], v[62:63], v[52:53] op_sel:[0,0,1] op_sel_hi:[0,1,0]
	v_pk_add_f32 v[62:63], v[46:47], v[52:53]
	v_pk_add_f32 v[46:47], v[46:47], v[52:53] neg_lo:[0,1] neg_hi:[0,1]
	v_pk_mul_f32 v[52:53], v[60:61], s[16:17]
	s_nop 0
	v_pk_fma_f32 v[52:53], s[82:83], v[60:61], v[52:53] op_sel:[0,0,1] op_sel_hi:[0,1,0]
	v_pk_add_f32 v[60:61], v[48:49], v[52:53]
	v_pk_add_f32 v[48:49], v[48:49], v[52:53] neg_lo:[0,1] neg_hi:[0,1]
	v_xor_b32_e32 v52, 0x80000000, v51
	v_mov_b32_e32 v53, v50
	v_pk_add_f32 v[50:51], v[34:35], v[52:53]
	v_pk_add_f32 v[34:35], v[34:35], v[52:53] neg_lo:[0,1] neg_hi:[0,1]
	v_pk_mul_f32 v[52:53], v[58:59], s[16:17]
	s_nop 0
	v_pk_fma_f32 v[52:53], s[82:83], v[58:59], v[52:53] op_sel:[0,0,1] op_sel_hi:[0,1,0] neg_lo:[0,1,0] neg_hi:[0,1,0]
	v_pk_add_f32 v[58:59], v[42:43], v[52:53]
	v_pk_add_f32 v[42:43], v[42:43], v[52:53] neg_lo:[0,1] neg_hi:[0,1]
	v_pk_mul_f32 v[52:53], v[54:55], s[78:79]
	s_nop 0
	v_pk_fma_f32 v[52:53], s[0:1], v[54:55], v[52:53] op_sel:[0,0,1] op_sel_hi:[0,1,0] neg_lo:[0,1,0] neg_hi:[0,1,0]
	v_pk_add_f32 v[54:55], v[38:39], v[52:53]
	v_pk_add_f32 v[38:39], v[38:39], v[52:53] neg_lo:[0,1] neg_hi:[0,1]
	v_pk_mul_f32 v[52:53], v[40:41], s[80:81]
	s_nop 0
	v_pk_fma_f32 v[40:41], s[16:17], v[40:41], v[52:53] op_sel:[0,0,1] op_sel_hi:[0,1,0] neg_lo:[0,1,0] neg_hi:[0,1,0]
	v_pk_add_f32 v[52:53], v[16:17], v[40:41]
	v_pk_add_f32 v[16:17], v[16:17], v[40:41] neg_lo:[0,1] neg_hi:[0,1]
	v_pk_add_f32 v[40:41], v[56:57], v[22:23]
	v_pk_add_f32 v[22:23], v[56:57], v[22:23] neg_lo:[0,1] neg_hi:[0,1]
	v_pk_mul_f32 v[56:57], v[64:65], s[88:89]
	s_nop 0
	v_pk_fma_f32 v[56:57], v[64:65], s[8:9], v[56:57] op_sel:[0,0,1] op_sel_hi:[1,0,0]
	s_mov_b32 s9, s42
	v_pk_add_f32 v[64:65], v[66:67], v[56:57]
	v_pk_add_f32 v[56:57], v[66:67], v[56:57] neg_lo:[0,1] neg_hi:[0,1]
	v_pk_mul_f32 v[66:67], v[62:63], s[80:81]
	s_nop 0
	v_pk_fma_f32 v[62:63], s[16:17], v[62:63], v[66:67] op_sel:[0,0,1] op_sel_hi:[0,1,0]
	v_pk_add_f32 v[66:67], v[70:71], v[62:63]
	v_pk_add_f32 v[62:63], v[70:71], v[62:63] neg_lo:[0,1] neg_hi:[0,1]
	v_pk_mul_f32 v[70:71], v[60:61], s[62:63]
	s_nop 0
	v_pk_fma_f32 v[60:61], v[60:61], s[24:25], v[70:71] op_sel:[0,0,1] op_sel_hi:[1,0,0]
	s_mov_b32 s25, s38
	v_pk_add_f32 v[70:71], v[32:33], v[60:61]
	v_pk_add_f32 v[32:33], v[32:33], v[60:61] neg_lo:[0,1] neg_hi:[0,1]
	v_pk_mul_f32 v[60:61], v[50:51], s[78:79]
	s_nop 0
	v_pk_fma_f32 v[50:51], s[0:1], v[50:51], v[60:61] op_sel:[0,0,1] op_sel_hi:[0,1,0]
	v_pk_add_f32 v[60:61], v[14:15], v[50:51]
	v_pk_add_f32 v[14:15], v[14:15], v[50:51] neg_lo:[0,1] neg_hi:[0,1]
	v_pk_mul_f32 v[50:51], v[58:59], s[24:25]
	s_nop 0
	v_pk_fma_f32 v[50:51], s[84:85], v[58:59], v[50:51] op_sel:[0,0,1] op_sel_hi:[0,1,0]
	v_pk_add_f32 v[58:59], v[68:69], v[50:51]
	v_pk_add_f32 v[50:51], v[68:69], v[50:51] neg_lo:[0,1] neg_hi:[0,1]
	v_pk_mul_f32 v[68:69], v[54:55], s[16:17]
	s_nop 0
	v_pk_fma_f32 v[54:55], s[82:83], v[54:55], v[68:69] op_sel:[0,0,1] op_sel_hi:[0,1,0]
	v_pk_add_f32 v[68:69], v[26:27], v[54:55]
	v_pk_add_f32 v[26:27], v[26:27], v[54:55] neg_lo:[0,1] neg_hi:[0,1]
	v_pk_mul_f32 v[54:55], v[52:53], s[8:9]
	s_nop 0
	v_pk_fma_f32 v[52:53], s[86:87], v[52:53], v[54:55] op_sel:[0,0,1] op_sel_hi:[0,1,0]
	v_pk_add_f32 v[54:55], v[24:25], v[52:53]
	v_pk_add_f32 v[24:25], v[24:25], v[52:53] neg_lo:[0,1] neg_hi:[0,1]
	v_xor_b32_e32 v52, 0x80000000, v29
	v_mov_b32_e32 v53, v28
	v_pk_add_f32 v[28:29], v[12:13], v[52:53]
	v_pk_add_f32 v[12:13], v[12:13], v[52:53] neg_lo:[0,1] neg_hi:[0,1]
	v_pk_mul_f32 v[52:53], v[44:45], s[8:9]
	s_nop 0
	v_pk_fma_f32 v[44:45], s[86:87], v[44:45], v[52:53] op_sel:[0,0,1] op_sel_hi:[0,1,0] neg_lo:[0,1,0] neg_hi:[0,1,0]
	v_pk_add_f32 v[52:53], v[36:37], v[44:45]
	v_pk_add_f32 v[36:37], v[36:37], v[44:45] neg_lo:[0,1] neg_hi:[0,1]
	v_pk_mul_f32 v[44:45], v[46:47], s[16:17]
	s_nop 0
	v_pk_fma_f32 v[44:45], s[82:83], v[46:47], v[44:45] op_sel:[0,0,1] op_sel_hi:[0,1,0] neg_lo:[0,1,0] neg_hi:[0,1,0]
	v_pk_add_f32 v[46:47], v[10:11], v[44:45]
	v_pk_add_f32 v[10:11], v[10:11], v[44:45] neg_lo:[0,1] neg_hi:[0,1]
	v_pk_mul_f32 v[44:45], v[48:49], s[24:25]
	s_nop 0
	v_pk_fma_f32 v[44:45], s[84:85], v[48:49], v[44:45] op_sel:[0,0,1] op_sel_hi:[0,1,0] neg_lo:[0,1,0] neg_hi:[0,1,0]
	v_pk_add_f32 v[48:49], v[20:21], v[44:45]
	v_pk_add_f32 v[20:21], v[20:21], v[44:45] neg_lo:[0,1] neg_hi:[0,1]
	v_pk_mul_f32 v[44:45], v[34:35], s[78:79]
	s_nop 0
	v_pk_fma_f32 v[34:35], v[34:35], s[0:1], v[44:45] op_sel:[0,0,1] op_sel_hi:[1,0,0] neg_lo:[1,0,0] neg_hi:[1,0,0]
	s_lshl_b64 s[0:1], s[72:73], 2
	v_pk_add_f32 v[44:45], v[30:31], v[34:35]
	v_pk_add_f32 v[30:31], v[30:31], v[34:35] neg_lo:[0,1] neg_hi:[0,1]
	v_pk_mul_f32 v[34:35], v[42:43], s[62:63]
	s_add_u32 s0, s49, s0
	v_pk_fma_f32 v[34:35], v[42:43], s[24:25], v[34:35] op_sel:[0,0,1] op_sel_hi:[1,0,0] neg_lo:[1,0,0] neg_hi:[1,0,0]
	s_addc_u32 s1, s60, s1
	v_pk_add_f32 v[42:43], v[8:9], v[34:35]
	v_pk_add_f32 v[8:9], v[8:9], v[34:35] neg_lo:[0,1] neg_hi:[0,1]
	v_pk_mul_f32 v[34:35], v[38:39], s[80:81]
	s_lshl_b64 s[62:63], s[76:77], 2
	v_pk_fma_f32 v[34:35], v[38:39], s[16:17], v[34:35] op_sel:[0,0,1] op_sel_hi:[1,0,0] neg_lo:[1,0,0] neg_hi:[1,0,0]
	s_add_u32 s62, s22, s62
	v_pk_add_f32 v[38:39], v[6:7], v[34:35]
	v_pk_add_f32 v[6:7], v[6:7], v[34:35] neg_lo:[0,1] neg_hi:[0,1]
	v_pk_mul_f32 v[34:35], v[16:17], s[88:89]
	s_addc_u32 s63, s23, s63
	v_pk_fma_f32 v[16:17], s[8:9], v[16:17], v[34:35] op_sel:[0,0,1] op_sel_hi:[0,1,0] neg_lo:[0,1,0] neg_hi:[0,1,0]
	v_pk_add_f32 v[34:35], v[4:5], v[16:17]
	v_pk_add_f32 v[4:5], v[4:5], v[16:17] neg_lo:[0,1] neg_hi:[0,1]
	ds_write2_b64 v2, v[40:41], v[64:65] offset1:16
	ds_write2_b64 v2, v[66:67], v[70:71] offset0:33 offset1:49
	ds_write2_b64 v2, v[60:61], v[58:59] offset0:66 offset1:82
	ds_write2_b64 v2, v[68:69], v[54:55] offset0:99 offset1:115
	ds_write2_b64 v2, v[28:29], v[52:53] offset0:132 offset1:148
	ds_write2_b64 v2, v[46:47], v[48:49] offset0:165 offset1:181
	ds_write2_b64 v2, v[44:45], v[42:43] offset0:198 offset1:214
	ds_write2_b64 v2, v[38:39], v[34:35] offset0:231 offset1:247
	ds_write2_b64 v3, v[22:23], v[56:57] offset0:8 offset1:24
	ds_write2_b64 v3, v[62:63], v[32:33] offset0:41 offset1:57
	ds_write2_b64 v3, v[14:15], v[50:51] offset0:74 offset1:90
	ds_write2_b64 v3, v[26:27], v[24:25] offset0:107 offset1:123
	ds_write2_b64 v3, v[12:13], v[36:37] offset0:140 offset1:156
	ds_write2_b64 v3, v[10:11], v[20:21] offset0:173 offset1:189
	ds_write2_b64 v3, v[30:31], v[8:9] offset0:206 offset1:222
	ds_write2_b64 v3, v[6:7], v[4:5] offset0:239 offset1:255
	s_waitcnt lgkmcnt(0)
	s_barrier
	global_load_dword v30, v206, s[0:1]
	global_load_dword v20, v207, s[0:1]
	v_ashrrev_i32_e32 v2, 31, v210
	v_lshrrev_b32_e32 v2, 22, v2
	v_add_u32_e32 v2, v210, v2
	v_ashrrev_i32_e32 v2, 10, v2
	v_mul_i32_i24_e32 v3, 0x400, v2
	global_load_dword v31, v205, s[0:1]
	global_load_dword v24, v205, s[62:63]
	s_add_u32 s0, s87, s74
	v_sub_u32_e32 v21, v210, v3
	v_lshlrev_b32_e32 v36, 14, v2
	s_addc_u32 s1, s90, s75
	v_ashrrev_i32_e32 v37, 31, v36
	v_lshlrev_b32_e32 v32, 4, v21
	v_lshl_add_u64 v[2:3], v[36:37], 1, s[0:1]
	v_ashrrev_i32_e32 v33, 31, v32
	v_lshl_add_u64 v[2:3], v[32:33], 1, v[2:3]
	global_load_dwordx4 v[10:13], v[2:3], off offset:16 nt
	global_load_dwordx4 v[14:17], v[2:3], off nt
	v_cmp_lt_i32_e32 vcc, 0, v21
	v_mov_b32_e32 v39, 0
	v_mov_b32_e32 v41, 0
	s_and_saveexec_b64 s[72:73], vcc
	s_cbranch_execz .LBB0_505
	global_load_ushort v41, v[2:3], off offset:-2

.LBB0_534:
	v_mov_b32_e32 v2, v210
	s_mov_b32 s43, s8
	v_and_b32_e32 v3, 0xff, v2
	v_lshlrev_b32_e32 v4, 5, v2
	v_and_or_b32 v3, v4, s33, v3
	v_ashrrev_i32_e32 v4, 5, v3
	v_lshlrev_b32_e32 v3, 3, v3
	v_lshlrev_b32_e32 v4, 3, v4
	v_add3_u32 v18, 0, v3, v4
	ds_read_b64 v[128:129], v18
	ds_read_b64 v[132:133], v18 offset:2112
	ds_read_b64 v[134:135], v18 offset:4224
	ds_read_b64 v[136:137], v18 offset:6336
	ds_read_b64 v[138:139], v18 offset:8448
	ds_read_b64 v[140:141], v18 offset:10560
	ds_read_b64 v[142:143], v18 offset:12672
	ds_read_b64 v[130:131], v18 offset:14784
	ds_read_b64 v[144:145], v18 offset:16896
	ds_read_b64 v[148:149], v18 offset:19008
	ds_read_b64 v[150:151], v18 offset:21120
	ds_read_b64 v[152:153], v18 offset:23232
	s_waitcnt lgkmcnt(10)
	v_pk_mul_f32 v[162:163], v[132:133], s[10:11]
	s_mov_b32 s64, s11
	v_pk_fma_f32 v[162:163], v[132:133], s[8:9], v[162:163] op_sel:[0,0,1] op_sel_hi:[1,0,0]
	s_waitcnt lgkmcnt(2)
	v_pk_mul_f32 v[178:179], v[148:149], s[42:43]
	v_pk_add_f32 v[194:195], v[132:133], v[148:149]
	v_pk_add_f32 v[132:133], v[132:133], v[148:149] neg_lo:[0,1] neg_hi:[0,1]
	v_pk_mul_f32 v[164:165], v[134:135], s[18:19]
	s_mov_b32 s41, s16
	v_pk_fma_f32 v[178:179], v[148:149], s[64:65], v[178:179] op_sel:[0,0,1] op_sel_hi:[1,0,0] neg_lo:[1,0,0] neg_hi:[1,0,0]
	v_pk_mul_f32 v[148:149], v[132:133], s[18:19]
	v_pk_fma_f32 v[164:165], v[134:135], s[16:17], v[164:165] op_sel:[0,0,1] op_sel_hi:[1,0,0]
	s_mov_b32 s68, s19
	s_waitcnt lgkmcnt(1)
	v_pk_mul_f32 v[180:181], v[150:151], s[40:41]
	v_pk_fma_f32 v[132:133], v[132:133], s[16:17], v[148:149] op_sel:[0,0,1] op_sel_hi:[1,0,0]
	v_pk_add_f32 v[148:149], v[134:135], v[150:151]
	v_pk_add_f32 v[134:135], v[134:135], v[150:151] neg_lo:[0,1] neg_hi:[0,1]
	v_pk_mul_f32 v[166:167], v[136:137], s[26:27]
	s_mov_b32 s66, s37
	s_mov_b32 s39, s24
	v_pk_fma_f32 v[180:181], v[150:151], s[68:69], v[180:181] op_sel:[0,0,1] op_sel_hi:[1,0,0] neg_lo:[1,0,0] neg_hi:[1,0,0]
	v_pk_mul_f32 v[150:151], v[134:135], s[36:37]
	ds_read_b64 v[154:155], v18 offset:25344
	ds_read_b64 v[156:157], v18 offset:27456
	ds_read_b64 v[158:159], v18 offset:29568
	ds_read_b64 v[160:161], v18 offset:31680
	v_pk_fma_f32 v[166:167], v[136:137], s[24:25], v[166:167] op_sel:[0,0,1] op_sel_hi:[1,0,0]
	s_mov_b32 s0, s27
	s_waitcnt lgkmcnt(4)
	v_pk_mul_f32 v[182:183], v[152:153], s[38:39]
	v_pk_fma_f32 v[134:135], v[134:135], s[66:67], v[150:151] op_sel:[0,0,1] op_sel_hi:[1,0,0]
	v_pk_add_f32 v[150:151], v[136:137], v[152:153]
	v_pk_add_f32 v[136:137], v[136:137], v[152:153] neg_lo:[0,1] neg_hi:[0,1]
	v_pk_mul_f32 v[168:169], v[138:139], s[36:37]
	v_pk_fma_f32 v[182:183], v[152:153], s[0:1], v[182:183] op_sel:[0,0,1] op_sel_hi:[1,0,0] neg_lo:[1,0,0] neg_hi:[1,0,0]
	v_pk_mul_f32 v[152:153], v[136:137], s[40:41]
	v_pk_fma_f32 v[168:169], v[138:139], s[66:67], v[168:169] op_sel:[0,0,1] op_sel_hi:[1,0,0]
	v_pk_mul_f32 v[170:171], v[140:141], s[38:39]
	s_waitcnt lgkmcnt(3)
	v_pk_mul_f32 v[184:185], v[154:155], s[36:37]
	v_pk_fma_f32 v[136:137], v[136:137], s[68:69], v[152:153] op_sel:[0,0,1] op_sel_hi:[1,0,0]
	v_pk_add_f32 v[152:153], v[138:139], v[154:155]
	v_pk_add_f32 v[138:139], v[138:139], v[154:155] neg_lo:[0,1] neg_hi:[0,1]
	v_pk_fma_f32 v[170:171], v[140:141], s[0:1], v[170:171] op_sel:[0,0,1] op_sel_hi:[1,0,0]
	v_pk_fma_f32 v[184:185], v[154:155], s[66:67], v[184:185] op_sel:[0,0,1] op_sel_hi:[1,0,0] neg_lo:[1,0,0] neg_hi:[1,0,0]
	s_waitcnt lgkmcnt(2)
	v_pk_mul_f32 v[186:187], v[156:157], s[26:27]
	v_xor_b32_e32 v155, 0x80000000, v138
	v_mov_b32_e32 v154, v139
	v_pk_add_f32 v[138:139], v[140:141], v[156:157]
	v_pk_add_f32 v[140:141], v[140:141], v[156:157] neg_lo:[0,1] neg_hi:[0,1]
	v_pk_mul_f32 v[172:173], v[142:143], s[40:41]
	v_pk_fma_f32 v[186:187], v[156:157], s[24:25], v[186:187] op_sel:[0,0,1] op_sel_hi:[1,0,0] neg_lo:[1,0,0] neg_hi:[1,0,0]
	v_pk_mul_f32 v[156:157], v[140:141], s[40:41]
	v_pk_fma_f32 v[172:173], v[142:143], s[68:69], v[172:173] op_sel:[0,0,1] op_sel_hi:[1,0,0]
	s_waitcnt lgkmcnt(1)
	v_pk_mul_f32 v[188:189], v[158:159], s[18:19]
	v_pk_fma_f32 v[140:141], v[140:141], s[68:69], v[156:157] op_sel:[0,0,1] op_sel_hi:[1,0,0] neg_lo:[1,0,0] neg_hi:[1,0,0]
	v_pk_add_f32 v[156:157], v[142:143], v[158:159]
	v_pk_add_f32 v[142:143], v[142:143], v[158:159] neg_lo:[0,1] neg_hi:[0,1]
	v_pk_mul_f32 v[174:175], v[130:131], s[42:43]
	v_pk_fma_f32 v[188:189], v[158:159], s[16:17], v[188:189] op_sel:[0,0,1] op_sel_hi:[1,0,0] neg_lo:[1,0,0] neg_hi:[1,0,0]
	v_pk_mul_f32 v[158:159], v[142:143], s[36:37]
	v_pk_fma_f32 v[174:175], v[130:131], s[64:65], v[174:175] op_sel:[0,0,1] op_sel_hi:[1,0,0]
	s_waitcnt lgkmcnt(0)
	v_pk_mul_f32 v[190:191], v[160:161], s[10:11]
	v_pk_fma_f32 v[142:143], v[142:143], s[66:67], v[158:159] op_sel:[0,0,1] op_sel_hi:[1,0,0] neg_lo:[1,0,0] neg_hi:[1,0,0]
	v_pk_add_f32 v[158:159], v[130:131], v[160:161]
	v_pk_add_f32 v[130:131], v[130:131], v[160:161] neg_lo:[0,1] neg_hi:[0,1]
	v_xor_b32_e32 v177, 0x80000000, v144
	v_mov_b32_e32 v176, v145
	v_pk_fma_f32 v[190:191], v[160:161], s[8:9], v[190:191] op_sel:[0,0,1] op_sel_hi:[1,0,0] neg_lo:[1,0,0] neg_hi:[1,0,0]
	v_pk_mul_f32 v[160:161], v[130:131], s[18:19]
	v_pk_add_f32 v[192:193], v[128:129], v[144:145]
	v_pk_add_f32 v[144:145], v[128:129], v[144:145] neg_lo:[0,1] neg_hi:[0,1]
	v_pk_fma_f32 v[130:131], v[130:131], s[16:17], v[160:161] op_sel:[0,0,1] op_sel_hi:[1,0,0] neg_lo:[1,0,0] neg_hi:[1,0,0]
	v_pk_add_f32 v[160:161], v[128:129], v[176:177]
	v_pk_add_f32 v[128:129], v[128:129], v[176:177] neg_lo:[0,1] neg_hi:[0,1]
	v_pk_add_f32 v[176:177], v[162:163], v[178:179]
	v_pk_add_f32 v[162:163], v[162:163], v[178:179] neg_lo:[0,1] neg_hi:[0,1]
	v_cvt_f32_ubyte0_e32 v2, v2
	v_pk_mul_f32 v[178:179], v[162:163], s[18:19]
	v_mul_f32_e32 v2, 0x39000000, v2
	v_pk_fma_f32 v[162:163], v[162:163], s[16:17], v[178:179] op_sel:[0,0,1] op_sel_hi:[1,0,0]
	v_pk_add_f32 v[178:179], v[164:165], v[180:181]
	v_pk_add_f32 v[164:165], v[164:165], v[180:181] neg_lo:[0,1] neg_hi:[0,1]
	v_sin_f32_e32 v34, v2
	v_pk_mul_f32 v[180:181], v[164:165], s[36:37]
	v_cos_f32_e32 v30, v2
	v_pk_fma_f32 v[164:165], v[164:165], s[66:67], v[180:181] op_sel:[0,0,1] op_sel_hi:[1,0,0]
	v_pk_add_f32 v[180:181], v[166:167], v[182:183]
	v_pk_add_f32 v[166:167], v[166:167], v[182:183] neg_lo:[0,1] neg_hi:[0,1]
	v_xor_b32_e32 v31, 0x80000000, v34
	v_pk_mul_f32 v[182:183], v[166:167], s[40:41]
	v_mov_b32_e32 v35, v31
	v_pk_fma_f32 v[166:167], v[166:167], s[68:69], v[182:183] op_sel:[0,0,1] op_sel_hi:[1,0,0]
	v_pk_add_f32 v[182:183], v[168:169], v[184:185]
	v_pk_add_f32 v[184:185], v[168:169], v[184:185] neg_lo:[0,1] neg_hi:[0,1]
	v_pk_mul_f32 v[2:3], v[30:31], v[34:35] op_sel:[1,0] op_sel_hi:[0,1]
	v_pk_add_f32 v[168:169], v[170:171], v[186:187]
	v_pk_add_f32 v[170:171], v[170:171], v[186:187] neg_lo:[0,1] neg_hi:[0,1]
	v_pk_fma_f32 v[44:45], v[30:31], v[30:31], v[2:3] op_sel_hi:[1,0,1]
	v_pk_mul_f32 v[186:187], v[170:171], s[40:41]
	v_pk_mul_f32 v[2:3], v[34:35], v[44:45] op_sel:[0,1] op_sel_hi:[1,0]
	v_pk_fma_f32 v[170:171], v[170:171], s[68:69], v[186:187] op_sel:[0,0,1] op_sel_hi:[1,0,0] neg_lo:[1,0,0] neg_hi:[1,0,0]
	v_pk_add_f32 v[186:187], v[172:173], v[188:189]
	v_pk_add_f32 v[172:173], v[172:173], v[188:189] neg_lo:[0,1] neg_hi:[0,1]
	s_nop 0
	v_pk_mul_f32 v[188:189], v[172:173], s[36:37]
	s_nop 0
	v_pk_fma_f32 v[172:173], v[172:173], s[66:67], v[188:189] op_sel:[0,0,1] op_sel_hi:[1,0,0] neg_lo:[1,0,0] neg_hi:[1,0,0]
	v_pk_add_f32 v[188:189], v[174:175], v[190:191]
	v_pk_add_f32 v[174:175], v[174:175], v[190:191] neg_lo:[0,1] neg_hi:[0,1]
	v_pk_fma_f32 v[46:47], v[30:31], v[44:45], v[2:3] op_sel_hi:[0,1,1]
	v_pk_mul_f32 v[190:191], v[174:175], s[18:19]
	v_pk_mul_f32 v[2:3], v[44:45], v[44:45] op_sel:[1,1] op_sel_hi:[0,1] neg_lo:[0,1]
	v_pk_fma_f32 v[174:175], v[174:175], s[16:17], v[190:191] op_sel:[0,0,1] op_sel_hi:[1,0,0] neg_lo:[1,0,0] neg_hi:[1,0,0]
	v_pk_add_f32 v[190:191], v[192:193], v[152:153]
	v_pk_add_f32 v[152:153], v[192:193], v[152:153] neg_lo:[0,1] neg_hi:[0,1]
	v_pk_add_f32 v[192:193], v[194:195], v[138:139]
	v_pk_add_f32 v[138:139], v[194:195], v[138:139] neg_lo:[0,1] neg_hi:[0,1]
	v_pk_fma_f32 v[52:53], v[44:45], v[44:45], v[2:3] op_sel_hi:[1,0,1]
	v_pk_mul_f32 v[194:195], v[138:139], s[36:37]
	s_nop 0
	v_pk_fma_f32 v[138:139], v[138:139], s[66:67], v[194:195] op_sel:[0,0,1] op_sel_hi:[1,0,0]
	v_pk_add_f32 v[194:195], v[148:149], v[156:157]
	v_pk_add_f32 v[156:157], v[148:149], v[156:157] neg_lo:[0,1] neg_hi:[0,1]
	v_pk_add_f32 v[148:149], v[150:151], v[158:159]
	v_pk_add_f32 v[150:151], v[150:151], v[158:159] neg_lo:[0,1] neg_hi:[0,1]
	v_pk_mul_f32 v[2:3], v[52:53], v[52:53] op_sel:[1,1] op_sel_hi:[0,1] neg_lo:[0,1]
	v_pk_mul_f32 v[158:159], v[150:151], s[36:37]
	v_pk_fma_f32 v[48:49], v[52:53], v[52:53], v[2:3] op_sel_hi:[1,0,1]
	v_pk_fma_f32 v[150:151], v[150:151], s[66:67], v[158:159] op_sel:[0,0,1] op_sel_hi:[1,0,0] neg_lo:[1,0,0] neg_hi:[1,0,0]
	v_pk_add_f32 v[158:159], v[144:145], v[154:155]
	v_pk_add_f32 v[144:145], v[144:145], v[154:155] neg_lo:[0,1] neg_hi:[0,1]
	v_pk_add_f32 v[154:155], v[132:133], v[140:141]
	v_pk_add_f32 v[132:133], v[132:133], v[140:141] neg_lo:[0,1] neg_hi:[0,1]
	v_pk_mul_f32 v[2:3], v[52:53], v[48:49] op_sel:[1,1] op_sel_hi:[1,0] neg_lo:[1,0]
	v_pk_mul_f32 v[140:141], v[132:133], s[36:37]
	v_pk_fma_f32 v[36:37], v[52:53], v[48:49], v[2:3] op_sel_hi:[0,1,1]
	v_pk_fma_f32 v[132:133], v[132:133], s[66:67], v[140:141] op_sel:[0,0,1] op_sel_hi:[1,0,0]
	v_pk_add_f32 v[140:141], v[134:135], v[142:143]
	v_pk_add_f32 v[142:143], v[134:135], v[142:143] neg_lo:[0,1] neg_hi:[0,1]
	v_pk_mul_f32 v[2:3], v[52:53], v[36:37] op_sel:[1,1] op_sel_hi:[1,0] neg_lo:[1,0]
	v_pk_add_f32 v[134:135], v[136:137], v[130:131]
	v_pk_add_f32 v[130:131], v[136:137], v[130:131] neg_lo:[0,1] neg_hi:[0,1]
	v_pk_fma_f32 v[26:27], v[52:53], v[36:37], v[2:3] op_sel_hi:[0,1,1]
	v_pk_mul_f32 v[136:137], v[130:131], s[36:37]
	v_pk_mul_f32 v[2:3], v[52:53], v[26:27] op_sel:[1,1] op_sel_hi:[1,0] neg_lo:[1,0]
	v_pk_fma_f32 v[130:131], v[130:131], s[66:67], v[136:137] op_sel:[0,0,1] op_sel_hi:[1,0,0] neg_lo:[1,0,0] neg_hi:[1,0,0]
	v_pk_add_f32 v[136:137], v[160:161], v[182:183]
	v_pk_add_f32 v[160:161], v[160:161], v[182:183] neg_lo:[0,1] neg_hi:[0,1]
	v_pk_add_f32 v[182:183], v[176:177], v[168:169]
	v_pk_add_f32 v[168:169], v[176:177], v[168:169] neg_lo:[0,1] neg_hi:[0,1]
	v_pk_fma_f32 v[20:21], v[52:53], v[26:27], v[2:3] op_sel_hi:[0,1,1]
	v_pk_mul_f32 v[176:177], v[168:169], s[36:37]
	v_pk_mul_f32 v[2:3], v[52:53], v[20:21] op_sel:[1,1] op_sel_hi:[1,0] neg_lo:[1,0]
	v_pk_fma_f32 v[168:169], v[168:169], s[66:67], v[176:177] op_sel:[0,0,1] op_sel_hi:[1,0,0]
	v_pk_add_f32 v[176:177], v[178:179], v[186:187]
	v_pk_add_f32 v[186:187], v[178:179], v[186:187] neg_lo:[0,1] neg_hi:[0,1]
	v_pk_fma_f32 v[10:11], v[52:53], v[20:21], v[2:3] op_sel_hi:[0,1,1]
	v_pk_add_f32 v[178:179], v[180:181], v[188:189]
	v_pk_add_f32 v[180:181], v[180:181], v[188:189] neg_lo:[0,1] neg_hi:[0,1]
	v_pk_mul_f32 v[2:3], v[52:53], v[10:11] op_sel:[1,1] op_sel_hi:[1,0] neg_lo:[1,0]
	v_pk_mul_f32 v[188:189], v[180:181], s[36:37]
	v_pk_fma_f32 v[4:5], v[52:53], v[10:11], v[2:3] op_sel_hi:[0,1,1]
	v_pk_fma_f32 v[180:181], v[180:181], s[66:67], v[188:189] op_sel:[0,0,1] op_sel_hi:[1,0,0] neg_lo:[1,0,0] neg_hi:[1,0,0]
	v_pk_add_f32 v[188:189], v[128:129], v[184:185] op_sel:[0,1] op_sel_hi:[1,0] neg_hi:[0,1]
	v_pk_add_f32 v[128:129], v[128:129], v[184:185] op_sel:[0,1] op_sel_hi:[1,0] neg_lo:[0,1]
	v_pk_add_f32 v[184:185], v[162:163], v[170:171]
	v_pk_add_f32 v[162:163], v[162:163], v[170:171] neg_lo:[0,1] neg_hi:[0,1]
	s_nop 0
	v_pk_mul_f32 v[170:171], v[162:163], s[36:37]
	s_nop 0
	v_pk_fma_f32 v[162:163], v[162:163], s[66:67], v[170:171] op_sel:[0,0,1] op_sel_hi:[1,0,0]
	v_pk_add_f32 v[170:171], v[164:165], v[172:173]
	v_pk_add_f32 v[172:173], v[164:165], v[172:173] neg_lo:[0,1] neg_hi:[0,1]
	v_pk_mul_f32 v[2:3], v[46:47], v[4:5] op_sel:[1,1] op_sel_hi:[1,0] neg_lo:[1,0]
	v_pk_add_f32 v[164:165], v[166:167], v[174:175]
	v_pk_add_f32 v[166:167], v[166:167], v[174:175] neg_lo:[0,1] neg_hi:[0,1]
	v_pk_mul_f32 v[14:15], v[34:35], v[4:5] op_sel:[0,1] op_sel_hi:[1,0]
	v_pk_mul_f32 v[174:175], v[166:167], s[36:37]
	v_pk_mul_f32 v[40:41], v[34:35], v[10:11] op_sel:[0,1] op_sel_hi:[1,0]
	v_pk_fma_f32 v[166:167], v[166:167], s[66:67], v[174:175] op_sel:[0,0,1] op_sel_hi:[1,0,0] neg_lo:[1,0,0] neg_hi:[1,0,0]
	v_pk_add_f32 v[174:175], v[190:191], v[194:195]
	v_pk_add_f32 v[190:191], v[190:191], v[194:195] neg_lo:[0,1] neg_hi:[0,1]
	v_pk_add_f32 v[194:195], v[192:193], v[148:149]
	v_pk_add_f32 v[192:193], v[192:193], v[148:149] neg_lo:[0,1] neg_hi:[0,1]
	v_pk_mul_f32 v[66:67], v[34:35], v[20:21] op_sel:[0,1] op_sel_hi:[1,0]
	v_pk_add_f32 v[148:149], v[152:153], v[156:157] op_sel:[0,1] op_sel_hi:[1,0] neg_hi:[0,1]
	v_pk_add_f32 v[152:153], v[152:153], v[156:157] op_sel:[0,1] op_sel_hi:[1,0] neg_lo:[0,1]
	v_pk_add_f32 v[156:157], v[138:139], v[150:151]
	v_pk_add_f32 v[150:151], v[138:139], v[150:151] neg_lo:[0,1] neg_hi:[0,1]
	v_pk_mul_f32 v[82:83], v[34:35], v[26:27] op_sel:[0,1] op_sel_hi:[1,0]
	v_pk_add_f32 v[138:139], v[158:159], v[140:141]
	v_pk_add_f32 v[140:141], v[158:159], v[140:141] neg_lo:[0,1] neg_hi:[0,1]
	v_pk_add_f32 v[158:159], v[154:155], v[134:135]
	v_pk_add_f32 v[154:155], v[154:155], v[134:135] neg_lo:[0,1] neg_hi:[0,1]
	v_pk_mul_f32 v[96:97], v[34:35], v[36:37] op_sel:[0,1] op_sel_hi:[1,0]
	v_pk_add_f32 v[134:135], v[144:145], v[142:143] op_sel:[0,1] op_sel_hi:[1,0] neg_hi:[0,1]
	v_pk_add_f32 v[142:143], v[144:145], v[142:143] op_sel:[0,1] op_sel_hi:[1,0] neg_lo:[0,1]
	v_pk_add_f32 v[144:145], v[132:133], v[130:131]
	v_pk_add_f32 v[132:133], v[132:133], v[130:131] neg_lo:[0,1] neg_hi:[0,1]
	v_pk_mul_f32 v[110:111], v[34:35], v[48:49] op_sel:[0,1] op_sel_hi:[1,0]
	v_pk_add_f32 v[130:131], v[136:137], v[176:177]
	v_pk_add_f32 v[136:137], v[136:137], v[176:177] neg_lo:[0,1] neg_hi:[0,1]
	v_pk_add_f32 v[176:177], v[182:183], v[178:179]
	v_pk_add_f32 v[182:183], v[182:183], v[178:179] neg_lo:[0,1] neg_hi:[0,1]
	v_pk_mul_f32 v[124:125], v[34:35], v[52:53] op_sel:[0,1] op_sel_hi:[1,0]
	v_pk_add_f32 v[178:179], v[160:161], v[186:187] op_sel:[0,1] op_sel_hi:[1,0] neg_hi:[0,1]
	v_pk_add_f32 v[160:161], v[160:161], v[186:187] op_sel:[0,1] op_sel_hi:[1,0] neg_lo:[0,1]
	v_pk_add_f32 v[186:187], v[168:169], v[180:181]
	v_pk_add_f32 v[180:181], v[168:169], v[180:181] neg_lo:[0,1] neg_hi:[0,1]
	v_pk_fma_f32 v[2:3], v[46:47], v[4:5], v[2:3] op_sel_hi:[0,1,1]
	v_pk_add_f32 v[168:169], v[188:189], v[170:171]
	v_pk_add_f32 v[170:171], v[188:189], v[170:171] neg_lo:[0,1] neg_hi:[0,1]
	v_pk_add_f32 v[188:189], v[184:185], v[164:165]
	v_pk_add_f32 v[184:185], v[184:185], v[164:165] neg_lo:[0,1] neg_hi:[0,1]
	v_pk_mul_f32 v[8:9], v[44:45], v[4:5] op_sel:[1,1] op_sel_hi:[1,0] neg_lo:[1,0]
	v_pk_add_f32 v[164:165], v[128:129], v[172:173] op_sel:[0,1] op_sel_hi:[1,0] neg_hi:[0,1]
	v_pk_add_f32 v[128:129], v[128:129], v[172:173] op_sel:[0,1] op_sel_hi:[1,0] neg_lo:[0,1]
	v_pk_add_f32 v[172:173], v[162:163], v[166:167]
	v_pk_add_f32 v[166:167], v[162:163], v[166:167] neg_lo:[0,1] neg_hi:[0,1]
	v_pk_fma_f32 v[14:15], v[30:31], v[4:5], v[14:15] op_sel_hi:[0,1,1]
	v_pk_add_f32 v[162:163], v[174:175], v[194:195]
	v_pk_add_f32 v[174:175], v[174:175], v[194:195] neg_lo:[0,1] neg_hi:[0,1]
	v_pk_add_f32 v[194:195], v[190:191], v[192:193] op_sel:[0,1] op_sel_hi:[1,0] neg_hi:[0,1]
	v_pk_add_f32 v[190:191], v[190:191], v[192:193] op_sel:[0,1] op_sel_hi:[1,0] neg_lo:[0,1]
	v_pk_add_f32 v[192:193], v[148:149], v[156:157]
	v_pk_add_f32 v[148:149], v[148:149], v[156:157] neg_lo:[0,1] neg_hi:[0,1]
	v_pk_add_f32 v[156:157], v[152:153], v[150:151] op_sel:[0,1] op_sel_hi:[1,0] neg_hi:[0,1]
	v_pk_add_f32 v[150:151], v[152:153], v[150:151] op_sel:[0,1] op_sel_hi:[1,0] neg_lo:[0,1]
	v_pk_add_f32 v[152:153], v[138:139], v[158:159]
	v_pk_add_f32 v[138:139], v[138:139], v[158:159] neg_lo:[0,1] neg_hi:[0,1]
	v_pk_add_f32 v[158:159], v[140:141], v[154:155] op_sel:[0,1] op_sel_hi:[1,0] neg_hi:[0,1]
	v_pk_add_f32 v[140:141], v[140:141], v[154:155] op_sel:[0,1] op_sel_hi:[1,0] neg_lo:[0,1]
	v_pk_add_f32 v[154:155], v[134:135], v[144:145]
	v_pk_add_f32 v[134:135], v[134:135], v[144:145] neg_lo:[0,1] neg_hi:[0,1]
	v_pk_add_f32 v[144:145], v[142:143], v[132:133] op_sel:[0,1] op_sel_hi:[1,0] neg_hi:[0,1]
	v_pk_add_f32 v[132:133], v[142:143], v[132:133] op_sel:[0,1] op_sel_hi:[1,0] neg_lo:[0,1]
	v_pk_add_f32 v[142:143], v[130:131], v[176:177]
	v_pk_mul_f32 v[24:25], v[46:47], v[10:11] op_sel:[1,1] op_sel_hi:[1,0] neg_lo:[1,0]
	v_pk_mul_f32 v[34:35], v[34:35], v[142:143] op_sel:[0,1] op_sel_hi:[1,0]
	v_pk_mul_f32 v[32:33], v[44:45], v[10:11] op_sel:[1,1] op_sel_hi:[1,0] neg_lo:[1,0]
	v_pk_fma_f32 v[40:41], v[30:31], v[10:11], v[40:41] op_sel_hi:[0,1,1]
	v_pk_mul_f32 v[56:57], v[46:47], v[20:21] op_sel:[1,1] op_sel_hi:[1,0] neg_lo:[1,0]
	v_pk_mul_f32 v[62:63], v[44:45], v[20:21] op_sel:[1,1] op_sel_hi:[1,0] neg_lo:[1,0]
	v_pk_fma_f32 v[66:67], v[30:31], v[20:21], v[66:67] op_sel_hi:[0,1,1]
	v_pk_mul_f32 v[74:75], v[46:47], v[26:27] op_sel:[1,1] op_sel_hi:[1,0] neg_lo:[1,0]
	v_pk_mul_f32 v[78:79], v[44:45], v[26:27] op_sel:[1,1] op_sel_hi:[1,0] neg_lo:[1,0]
	v_pk_fma_f32 v[82:83], v[30:31], v[26:27], v[82:83] op_sel_hi:[0,1,1]
	v_pk_mul_f32 v[88:89], v[46:47], v[36:37] op_sel:[1,1] op_sel_hi:[1,0] neg_lo:[1,0]
	v_pk_mul_f32 v[92:93], v[44:45], v[36:37] op_sel:[1,1] op_sel_hi:[1,0] neg_lo:[1,0]
	v_pk_fma_f32 v[96:97], v[30:31], v[36:37], v[96:97] op_sel_hi:[0,1,1]
	v_pk_mul_f32 v[102:103], v[46:47], v[48:49] op_sel:[1,1] op_sel_hi:[1,0] neg_lo:[1,0]
	v_pk_mul_f32 v[106:107], v[44:45], v[48:49] op_sel:[1,1] op_sel_hi:[1,0] neg_lo:[1,0]
	v_pk_fma_f32 v[110:111], v[30:31], v[48:49], v[110:111] op_sel_hi:[0,1,1]
	v_pk_mul_f32 v[116:117], v[52:53], v[46:47] op_sel:[1,1] op_sel_hi:[0,1] neg_lo:[0,1]
	v_pk_mul_f32 v[120:121], v[44:45], v[52:53] op_sel:[1,1] op_sel_hi:[1,0] neg_lo:[1,0]
	v_pk_fma_f32 v[124:125], v[30:31], v[52:53], v[124:125] op_sel_hi:[0,1,1]
	v_pk_add_f32 v[130:131], v[130:131], v[176:177] neg_lo:[0,1] neg_hi:[0,1]
	v_pk_add_f32 v[176:177], v[136:137], v[182:183] op_sel:[0,1] op_sel_hi:[1,0] neg_hi:[0,1]
	v_pk_add_f32 v[136:137], v[136:137], v[182:183] op_sel:[0,1] op_sel_hi:[1,0] neg_lo:[0,1]
	v_pk_add_f32 v[182:183], v[178:179], v[186:187]
	v_pk_add_f32 v[178:179], v[178:179], v[186:187] neg_lo:[0,1] neg_hi:[0,1]
	v_pk_add_f32 v[186:187], v[160:161], v[180:181] op_sel:[0,1] op_sel_hi:[1,0] neg_hi:[0,1]
	v_pk_add_f32 v[160:161], v[160:161], v[180:181] op_sel:[0,1] op_sel_hi:[1,0] neg_lo:[0,1]
	v_pk_add_f32 v[180:181], v[168:169], v[188:189]
	v_pk_fma_f32 v[30:31], v[30:31], v[142:143], v[34:35] op_sel_hi:[0,1,1]
	v_pk_mul_f32 v[34:35], v[44:45], v[152:153] op_sel:[1,1] op_sel_hi:[1,0] neg_lo:[1,0]
	v_xor_b32_e32 v6, 0x80000000, v3
	v_pk_fma_f32 v[8:9], v[44:45], v[4:5], v[8:9] op_sel_hi:[0,1,1]
	v_pk_fma_f32 v[24:25], v[46:47], v[10:11], v[24:25] op_sel_hi:[0,1,1]
	v_pk_fma_f32 v[32:33], v[44:45], v[10:11], v[32:33] op_sel_hi:[0,1,1]
	v_pk_fma_f32 v[56:57], v[46:47], v[20:21], v[56:57] op_sel_hi:[0,1,1]
	v_pk_fma_f32 v[62:63], v[44:45], v[20:21], v[62:63] op_sel_hi:[0,1,1]
	v_pk_fma_f32 v[74:75], v[46:47], v[26:27], v[74:75] op_sel_hi:[0,1,1]
	v_pk_fma_f32 v[78:79], v[44:45], v[26:27], v[78:79] op_sel_hi:[0,1,1]
	v_pk_fma_f32 v[88:89], v[46:47], v[36:37], v[88:89] op_sel_hi:[0,1,1]
	v_pk_fma_f32 v[92:93], v[44:45], v[36:37], v[92:93] op_sel_hi:[0,1,1]
	v_pk_fma_f32 v[102:103], v[46:47], v[48:49], v[102:103] op_sel_hi:[0,1,1]
	v_pk_fma_f32 v[106:107], v[44:45], v[48:49], v[106:107] op_sel_hi:[0,1,1]
	v_pk_fma_f32 v[116:117], v[52:53], v[46:47], v[116:117] op_sel_hi:[1,0,1]
	v_pk_fma_f32 v[120:121], v[44:45], v[52:53], v[120:121] op_sel_hi:[0,1,1]
	v_mov_b32_e32 v7, v3
	v_pk_add_f32 v[168:169], v[168:169], v[188:189] neg_lo:[0,1] neg_hi:[0,1]
	v_pk_add_f32 v[188:189], v[170:171], v[184:185] op_sel:[0,1] op_sel_hi:[1,0] neg_hi:[0,1]
	v_pk_add_f32 v[170:171], v[170:171], v[184:185] op_sel:[0,1] op_sel_hi:[1,0] neg_lo:[0,1]
	v_pk_add_f32 v[184:185], v[164:165], v[172:173]
	v_pk_add_f32 v[164:165], v[164:165], v[172:173] neg_lo:[0,1] neg_hi:[0,1]
	v_pk_add_f32 v[172:173], v[128:129], v[166:167] op_sel:[0,1] op_sel_hi:[1,0] neg_hi:[0,1]
	v_pk_add_f32 v[128:129], v[128:129], v[166:167] op_sel:[0,1] op_sel_hi:[1,0] neg_lo:[0,1]
	v_pk_fma_f32 v[34:35], v[44:45], v[152:153], v[34:35] op_sel_hi:[0,1,1]
	v_pk_mul_f32 v[44:45], v[46:47], v[180:181] op_sel:[1,1] op_sel_hi:[1,0] neg_lo:[1,0]
	v_xor_b32_e32 v12, 0x80000000, v9
	v_xor_b32_e32 v16, 0x80000000, v15
	v_xor_b32_e32 v22, 0x80000000, v5
	v_xor_b32_e32 v28, 0x80000000, v25
	v_xor_b32_e32 v38, 0x80000000, v33
	v_xor_b32_e32 v42, 0x80000000, v41
	v_xor_b32_e32 v50, 0x80000000, v11
	v_xor_b32_e32 v60, 0x80000000, v57
	v_xor_b32_e32 v64, 0x80000000, v63
	v_xor_b32_e32 v68, 0x80000000, v67
	v_xor_b32_e32 v70, 0x80000000, v21
	v_xor_b32_e32 v76, 0x80000000, v75
	v_xor_b32_e32 v80, 0x80000000, v79
	v_xor_b32_e32 v84, 0x80000000, v83
	v_xor_b32_e32 v86, 0x80000000, v27
	v_xor_b32_e32 v90, 0x80000000, v89
	v_xor_b32_e32 v94, 0x80000000, v93
	v_xor_b32_e32 v98, 0x80000000, v97
	v_xor_b32_e32 v100, 0x80000000, v37
	v_xor_b32_e32 v104, 0x80000000, v103
	v_xor_b32_e32 v108, 0x80000000, v107
	v_mov_b32_e32 v109, v107
	v_mov_b32_e32 v105, v103
	v_mov_b32_e32 v101, v37
	v_mov_b32_e32 v99, v97
	v_mov_b32_e32 v95, v93
	v_mov_b32_e32 v91, v89
	v_mov_b32_e32 v87, v27
	v_mov_b32_e32 v85, v83
	v_mov_b32_e32 v81, v79
	v_mov_b32_e32 v77, v75
	v_mov_b32_e32 v71, v21
	v_mov_b32_e32 v69, v67
	v_mov_b32_e32 v65, v63
	v_mov_b32_e32 v61, v57
	v_mov_b32_e32 v51, v11
	v_mov_b32_e32 v43, v41
	v_mov_b32_e32 v39, v33
	v_mov_b32_e32 v29, v25
	v_mov_b32_e32 v23, v5
	v_mov_b32_e32 v17, v15
	v_mov_b32_e32 v13, v9
	v_pk_fma_f32 v[44:45], v[46:47], v[180:181], v[44:45] op_sel_hi:[0,1,1]
	v_pk_mul_f32 v[46:47], v[52:53], v[192:193] op_sel:[1,1] op_sel_hi:[1,0] neg_lo:[1,0]
	v_pk_mul_f32 v[72:73], v[48:49], v[194:195] op_sel:[1,1] op_sel_hi:[1,0] neg_lo:[1,0]
	v_pk_mul_f32 v[6:7], v[128:129], v[6:7] op_sel:[1,0] op_sel_hi:[0,1]
	v_pk_fma_f32 v[46:47], v[52:53], v[192:193], v[46:47] op_sel_hi:[0,1,1]
	v_pk_mul_f32 v[52:53], v[124:125], v[182:183] op_sel:[1,1] op_sel_hi:[1,0] neg_lo:[1,0]
	v_pk_mul_f32 v[54:55], v[120:121], v[154:155] op_sel:[1,1] op_sel_hi:[1,0] neg_lo:[1,0]
	v_pk_mul_f32 v[58:59], v[116:117], v[184:185] op_sel:[1,1] op_sel_hi:[1,0] neg_lo:[1,0]
	v_pk_fma_f32 v[48:49], v[48:49], v[194:195], v[72:73] op_sel_hi:[0,1,1]
	v_pk_mul_f32 v[72:73], v[110:111], v[176:177] op_sel:[1,1] op_sel_hi:[1,0] neg_lo:[1,0]
	v_pk_mul_f32 v[108:109], v[108:109], v[158:159] op_sel:[0,1] op_sel_hi:[1,0]
	v_pk_mul_f32 v[104:105], v[104:105], v[188:189] op_sel:[0,1] op_sel_hi:[1,0]
	v_pk_mul_f32 v[100:101], v[100:101], v[156:157] op_sel:[0,1] op_sel_hi:[1,0]
	v_pk_mul_f32 v[98:99], v[98:99], v[186:187] op_sel:[0,1] op_sel_hi:[1,0]
	v_pk_mul_f32 v[94:95], v[94:95], v[144:145] op_sel:[0,1] op_sel_hi:[1,0]
	v_pk_mul_f32 v[90:91], v[90:91], v[172:173] op_sel:[0,1] op_sel_hi:[1,0]
	v_pk_mul_f32 v[86:87], v[174:175], v[86:87] op_sel:[1,0] op_sel_hi:[0,1]
	v_pk_mul_f32 v[84:85], v[130:131], v[84:85] op_sel:[1,0] op_sel_hi:[0,1]
	v_pk_mul_f32 v[80:81], v[138:139], v[80:81] op_sel:[1,0] op_sel_hi:[0,1]
	v_pk_mul_f32 v[76:77], v[168:169], v[76:77] op_sel:[1,0] op_sel_hi:[0,1]
	v_pk_mul_f32 v[70:71], v[148:149], v[70:71] op_sel:[1,0] op_sel_hi:[0,1]
	v_pk_mul_f32 v[68:69], v[178:179], v[68:69] op_sel:[1,0] op_sel_hi:[0,1]
	v_pk_mul_f32 v[64:65], v[134:135], v[64:65] op_sel:[1,0] op_sel_hi:[0,1]
	v_pk_mul_f32 v[60:61], v[164:165], v[60:61] op_sel:[1,0] op_sel_hi:[0,1]
	v_pk_mul_f32 v[50:51], v[190:191], v[50:51] op_sel:[1,0] op_sel_hi:[0,1]
	v_pk_mul_f32 v[42:43], v[136:137], v[42:43] op_sel:[1,0] op_sel_hi:[0,1]
	v_pk_mul_f32 v[38:39], v[140:141], v[38:39] op_sel:[1,0] op_sel_hi:[0,1]
	v_pk_mul_f32 v[28:29], v[170:171], v[28:29] op_sel:[1,0] op_sel_hi:[0,1]
	v_pk_mul_f32 v[22:23], v[150:151], v[22:23] op_sel:[1,0] op_sel_hi:[0,1]
	v_pk_mul_f32 v[16:17], v[160:161], v[16:17] op_sel:[1,0] op_sel_hi:[0,1]
	v_pk_mul_f32 v[12:13], v[132:133], v[12:13] op_sel:[1,0] op_sel_hi:[0,1]
	v_pk_fma_f32 v[2:3], v[128:129], v[2:3], v[6:7] op_sel_hi:[1,0,1]
	v_pk_fma_f32 v[52:53], v[124:125], v[182:183], v[52:53] op_sel_hi:[0,1,1]
	v_pk_fma_f32 v[54:55], v[120:121], v[154:155], v[54:55] op_sel_hi:[0,1,1]
	v_pk_fma_f32 v[58:59], v[116:117], v[184:185], v[58:59] op_sel_hi:[0,1,1]
	v_pk_fma_f32 v[72:73], v[110:111], v[176:177], v[72:73] op_sel_hi:[0,1,1]
	v_pk_fma_f32 v[106:107], v[106:107], v[158:159], v[108:109] op_sel_hi:[0,1,1]
	v_pk_fma_f32 v[102:103], v[102:103], v[188:189], v[104:105] op_sel_hi:[0,1,1]
	v_pk_fma_f32 v[36:37], v[36:37], v[156:157], v[100:101] op_sel_hi:[0,1,1]
	v_pk_fma_f32 v[96:97], v[96:97], v[186:187], v[98:99] op_sel_hi:[0,1,1]
	v_pk_fma_f32 v[92:93], v[92:93], v[144:145], v[94:95] op_sel_hi:[0,1,1]
	v_pk_fma_f32 v[88:89], v[88:89], v[172:173], v[90:91] op_sel_hi:[0,1,1]
	v_pk_fma_f32 v[26:27], v[174:175], v[26:27], v[86:87] op_sel_hi:[1,0,1]
	v_pk_fma_f32 v[82:83], v[130:131], v[82:83], v[84:85] op_sel_hi:[1,0,1]
	v_pk_fma_f32 v[78:79], v[138:139], v[78:79], v[80:81] op_sel_hi:[1,0,1]
	v_pk_fma_f32 v[74:75], v[168:169], v[74:75], v[76:77] op_sel_hi:[1,0,1]
	v_pk_fma_f32 v[20:21], v[148:149], v[20:21], v[70:71] op_sel_hi:[1,0,1]
	v_pk_fma_f32 v[66:67], v[178:179], v[66:67], v[68:69] op_sel_hi:[1,0,1]
	v_pk_fma_f32 v[62:63], v[134:135], v[62:63], v[64:65] op_sel_hi:[1,0,1]
	v_pk_fma_f32 v[56:57], v[164:165], v[56:57], v[60:61] op_sel_hi:[1,0,1]
	v_pk_fma_f32 v[10:11], v[190:191], v[10:11], v[50:51] op_sel_hi:[1,0,1]
	v_pk_fma_f32 v[40:41], v[136:137], v[40:41], v[42:43] op_sel_hi:[1,0,1]
	v_pk_fma_f32 v[32:33], v[140:141], v[32:33], v[38:39] op_sel_hi:[1,0,1]
	v_pk_fma_f32 v[24:25], v[170:171], v[24:25], v[28:29] op_sel_hi:[1,0,1]
	v_pk_fma_f32 v[4:5], v[150:151], v[4:5], v[22:23] op_sel_hi:[1,0,1]
	v_pk_fma_f32 v[14:15], v[160:161], v[14:15], v[16:17] op_sel_hi:[1,0,1]
	v_pk_fma_f32 v[8:9], v[132:133], v[8:9], v[12:13] op_sel_hi:[1,0,1]
	ds_write_b64 v18, v[162:163]
	ds_write_b64 v18, v[26:27] offset:2112
	ds_write_b64 v18, v[48:49] offset:4224
	ds_write_b64 v18, v[10:11] offset:6336
	ds_write_b64 v18, v[46:47] offset:8448
	ds_write_b64 v18, v[20:21] offset:10560
	ds_write_b64 v18, v[36:37] offset:12672
	ds_write_b64 v18, v[4:5] offset:14784
	ds_write_b64 v18, v[34:35] offset:16896
	ds_write_b64 v18, v[78:79] offset:19008
	ds_write_b64 v18, v[106:107] offset:21120
	ds_write_b64 v18, v[32:33] offset:23232
	ds_write_b64 v18, v[54:55] offset:25344
	ds_write_b64 v18, v[62:63] offset:27456
	ds_write_b64 v18, v[92:93] offset:29568
	ds_write_b64 v18, v[8:9] offset:31680
	ds_write_b64 v18, v[30:31] offset:33792
	ds_write_b64 v18, v[82:83] offset:35904
	ds_write_b64 v18, v[72:73] offset:38016
	ds_write_b64 v18, v[40:41] offset:40128
	ds_write_b64 v18, v[52:53] offset:42240
	ds_write_b64 v18, v[66:67] offset:44352
	ds_write_b64 v18, v[96:97] offset:46464
	ds_write_b64 v18, v[14:15] offset:48576
	ds_write_b64 v18, v[44:45] offset:50688
	ds_write_b64 v18, v[74:75] offset:52800
	ds_write_b64 v18, v[102:103] offset:54912
	ds_write_b64 v18, v[24:25] offset:57024
	ds_write_b64 v18, v[58:59] offset:59136
	ds_write_b64 v18, v[56:57] offset:61248
	ds_write_b64 v18, v[88:89] offset:63360
	ds_write_b64 v18, v[2:3] offset:65472
	v_mov_b32_e32 v3, v210
	s_waitcnt lgkmcnt(0)
	s_barrier
	s_add_i32 s64, s62, s48
	v_and_b32_e32 v5, 15, v3
	v_cvt_f32_ubyte0_e32 v2, v5
	v_mul_f32_e32 v4, 0x3b800000, v2
	v_sin_f32_e32 v2, v4
	v_cos_f32_e32 v4, v4
	v_lshlrev_b32_e32 v64, 3, v5
	v_lshlrev_b32_e32 v18, 4, v3
	v_xor_b32_e32 v5, 0x80000000, v2
	v_mov_b32_e32 v3, v5
	v_pk_mul_f32 v[6:7], v[4:5], v[2:3] op_sel:[1,0] op_sel_hi:[0,1]
	v_pk_fma_f32 v[6:7], v[4:5], v[4:5], v[6:7] op_sel_hi:[1,0,1]
	s_ashr_i32 s65, s64, 31
	s_nop 0
	s_nop 0
	v_pk_mul_f32 v[10:11], v[6:7], v[6:7] op_sel:[1,1] op_sel_hi:[0,1] neg_lo:[0,1]
	v_pk_fma_f32 v[10:11], v[6:7], v[6:7], v[10:11] op_sel_hi:[1,0,1]
	v_pk_mul_f32 v[8:9], v[2:3], v[6:7] op_sel:[0,1] op_sel_hi:[1,0]
	v_pk_mul_f32 v[32:33], v[10:11], v[10:11] op_sel:[1,1] op_sel_hi:[0,1] neg_lo:[0,1]
	v_pk_fma_f32 v[32:33], v[10:11], v[10:11], v[32:33] op_sel_hi:[1,0,1]
	v_pk_mul_f32 v[16:17], v[2:3], v[10:11] op_sel:[0,1] op_sel_hi:[1,0]
	v_pk_mul_f32 v[48:49], v[10:11], v[32:33] op_sel:[1,1] op_sel_hi:[1,0] neg_lo:[1,0]
	v_pk_mul_f32 v[36:37], v[2:3], v[32:33] op_sel:[0,1] op_sel_hi:[1,0]
	v_pk_fma_f32 v[48:49], v[10:11], v[32:33], v[48:49] op_sel_hi:[0,1,1]
	v_pk_mul_f32 v[52:53], v[2:3], v[48:49] op_sel:[0,1] op_sel_hi:[1,0]
	v_pk_fma_f32 v[8:9], v[4:5], v[6:7], v[8:9] op_sel_hi:[0,1,1]
	v_pk_fma_f32 v[16:17], v[4:5], v[10:11], v[16:17] op_sel_hi:[0,1,1]
	v_pk_fma_f32 v[36:37], v[4:5], v[32:33], v[36:37] op_sel_hi:[0,1,1]
	v_pk_fma_f32 v[52:53], v[4:5], v[48:49], v[52:53] op_sel_hi:[0,1,1]
	v_and_b32_e32 v5, 0xffffff00, v18
	v_lshlrev_b32_e32 v18, 3, v5
	v_add3_u32 v18, 0, v64, v18
	v_ashrrev_i32_e32 v64, 2, v5
	v_add_u32_e32 v106, v18, v64
	ds_read2_b64 v[64:67], v106 offset1:16
	ds_read2_b64 v[68:71], v106 offset0:33 offset1:49
	ds_read2_b64 v[72:75], v106 offset0:66 offset1:82
	ds_read2_b64 v[76:79], v106 offset0:132 offset1:148
	ds_read2_b64 v[80:83], v106 offset0:99 offset1:115
	ds_read2_b64 v[84:87], v106 offset0:165 offset1:181
	ds_read2_b64 v[88:91], v106 offset0:198 offset1:214
	ds_read2_b64 v[92:95], v106 offset0:231 offset1:247
	s_waitcnt lgkmcnt(4)
	v_pk_add_f32 v[96:97], v[64:65], v[76:77]
	v_pk_add_f32 v[64:65], v[64:65], v[76:77] neg_lo:[0,1] neg_hi:[0,1]
	v_pk_add_f32 v[76:77], v[66:67], v[78:79]
	v_pk_add_f32 v[66:67], v[66:67], v[78:79] neg_lo:[0,1] neg_hi:[0,1]
	s_waitcnt lgkmcnt(1)
	v_pk_add_f32 v[98:99], v[74:75], v[90:91]
	v_pk_mul_f32 v[78:79], v[66:67], s[18:19]
	v_pk_add_f32 v[74:75], v[74:75], v[90:91] neg_lo:[0,1] neg_hi:[0,1]
	v_pk_fma_f32 v[66:67], v[66:67], s[16:17], v[78:79] op_sel:[0,0,1] op_sel_hi:[1,0,0]
	v_pk_add_f32 v[78:79], v[68:69], v[84:85]
	v_pk_add_f32 v[68:69], v[68:69], v[84:85] neg_lo:[0,1] neg_hi:[0,1]
	v_pk_mul_f32 v[90:91], v[74:75], s[40:41]
	v_pk_mul_f32 v[84:85], v[68:69], s[36:37]
	v_pk_fma_f32 v[74:75], v[74:75], s[68:69], v[90:91] op_sel:[0,0,1] op_sel_hi:[1,0,0] neg_lo:[1,0,0] neg_hi:[1,0,0]
	v_pk_fma_f32 v[68:69], v[68:69], s[66:67], v[84:85] op_sel:[0,0,1] op_sel_hi:[1,0,0]
	v_pk_add_f32 v[84:85], v[70:71], v[86:87]
	v_pk_add_f32 v[70:71], v[70:71], v[86:87] neg_lo:[0,1] neg_hi:[0,1]
	s_waitcnt lgkmcnt(0)
	v_pk_add_f32 v[90:91], v[80:81], v[92:93]
	v_pk_add_f32 v[80:81], v[80:81], v[92:93] neg_lo:[0,1] neg_hi:[0,1]
	v_pk_mul_f32 v[86:87], v[70:71], s[40:41]
	v_pk_mul_f32 v[92:93], v[80:81], s[36:37]
	v_pk_fma_f32 v[70:71], v[70:71], s[68:69], v[86:87] op_sel:[0,0,1] op_sel_hi:[1,0,0]
	v_pk_add_f32 v[86:87], v[72:73], v[88:89]
	v_pk_add_f32 v[88:89], v[72:73], v[88:89] neg_lo:[0,1] neg_hi:[0,1]
	v_pk_fma_f32 v[80:81], v[80:81], s[66:67], v[92:93] op_sel:[0,0,1] op_sel_hi:[1,0,0] neg_lo:[1,0,0] neg_hi:[1,0,0]
	v_pk_add_f32 v[92:93], v[82:83], v[94:95]
	v_pk_add_f32 v[82:83], v[82:83], v[94:95] neg_lo:[0,1] neg_hi:[0,1]
	s_nop 0
	v_pk_mul_f32 v[94:95], v[82:83], s[18:19]
	s_nop 0
	v_pk_fma_f32 v[82:83], v[82:83], s[16:17], v[94:95] op_sel:[0,0,1] op_sel_hi:[1,0,0] neg_lo:[1,0,0] neg_hi:[1,0,0]
	v_pk_add_f32 v[94:95], v[96:97], v[86:87]
	v_pk_add_f32 v[86:87], v[96:97], v[86:87] neg_lo:[0,1] neg_hi:[0,1]
	v_pk_add_f32 v[96:97], v[76:77], v[98:99]
	v_pk_add_f32 v[76:77], v[76:77], v[98:99] neg_lo:[0,1] neg_hi:[0,1]
	v_pk_add_f32 v[100:101], v[84:85], v[92:93]
	v_pk_add_f32 v[84:85], v[84:85], v[92:93] neg_lo:[0,1] neg_hi:[0,1]
	v_pk_add_f32 v[72:73], v[64:65], v[88:89] op_sel:[0,1] op_sel_hi:[1,0] neg_hi:[0,1]
	v_pk_add_f32 v[64:65], v[64:65], v[88:89] op_sel:[0,1] op_sel_hi:[1,0] neg_lo:[0,1]
	v_pk_add_f32 v[88:89], v[66:67], v[74:75]
	v_pk_add_f32 v[66:67], v[66:67], v[74:75] neg_lo:[0,1] neg_hi:[0,1]
	v_pk_mul_f32 v[98:99], v[76:77], s[36:37]
	v_pk_mul_f32 v[92:93], v[84:85], s[36:37]
	v_pk_mul_f32 v[74:75], v[66:67], s[36:37]
	v_pk_fma_f32 v[76:77], v[76:77], s[66:67], v[98:99] op_sel:[0,0,1] op_sel_hi:[1,0,0]
	v_pk_add_f32 v[98:99], v[78:79], v[90:91]
	v_pk_add_f32 v[90:91], v[78:79], v[90:91] neg_lo:[0,1] neg_hi:[0,1]
	v_pk_fma_f32 v[84:85], v[84:85], s[66:67], v[92:93] op_sel:[0,0,1] op_sel_hi:[1,0,0] neg_lo:[1,0,0] neg_hi:[1,0,0]
	v_pk_fma_f32 v[66:67], v[66:67], s[66:67], v[74:75] op_sel:[0,0,1] op_sel_hi:[1,0,0]
	v_pk_add_f32 v[74:75], v[68:69], v[80:81]
	v_pk_add_f32 v[92:93], v[70:71], v[82:83]
	v_pk_add_f32 v[70:71], v[70:71], v[82:83] neg_lo:[0,1] neg_hi:[0,1]
	v_pk_add_f32 v[68:69], v[68:69], v[80:81] neg_lo:[0,1] neg_hi:[0,1]
	v_pk_mul_f32 v[82:83], v[70:71], s[36:37]
	v_pk_add_f32 v[102:103], v[72:73], v[74:75]
	v_pk_add_f32 v[72:73], v[72:73], v[74:75] neg_lo:[0,1] neg_hi:[0,1]
	v_pk_add_f32 v[74:75], v[88:89], v[92:93]
	v_pk_add_f32 v[92:93], v[88:89], v[92:93] neg_lo:[0,1] neg_hi:[0,1]
	v_pk_mul_f32 v[24:25], v[6:7], v[10:11] op_sel:[1,1] op_sel_hi:[1,0] neg_lo:[1,0]
	v_xor_b32_e32 v81, 0x80000000, v68
	v_pk_fma_f32 v[70:71], v[70:71], s[66:67], v[82:83] op_sel:[0,0,1] op_sel_hi:[1,0,0] neg_lo:[1,0,0] neg_hi:[1,0,0]
	v_pk_add_f32 v[78:79], v[86:87], v[90:91] op_sel:[0,1] op_sel_hi:[1,0] neg_hi:[0,1]
	v_pk_add_f32 v[86:87], v[86:87], v[90:91] op_sel:[0,1] op_sel_hi:[1,0] neg_lo:[0,1]
	v_pk_add_f32 v[90:91], v[76:77], v[84:85]
	v_pk_add_f32 v[84:85], v[76:77], v[84:85] neg_lo:[0,1] neg_hi:[0,1]
	v_mov_b32_e32 v80, v69
	v_pk_fma_f32 v[24:25], v[6:7], v[10:11], v[24:25] op_sel_hi:[0,1,1]
	v_pk_mul_f32 v[28:29], v[10:11], v[8:9] op_sel:[1,1] op_sel_hi:[0,1] neg_lo:[0,1]
	v_pk_add_f32 v[68:69], v[64:65], v[80:81]
	v_pk_add_f32 v[64:65], v[64:65], v[80:81] neg_lo:[0,1] neg_hi:[0,1]
	v_pk_add_f32 v[80:81], v[66:67], v[70:71]
	v_pk_add_f32 v[70:71], v[66:67], v[70:71] neg_lo:[0,1] neg_hi:[0,1]
	v_pk_add_f32 v[88:89], v[72:73], v[92:93] op_sel:[0,1] op_sel_hi:[1,0] neg_hi:[0,1]
	v_pk_fma_f32 v[28:29], v[10:11], v[8:9], v[28:29] op_sel_hi:[1,0,1]
	v_pk_add_f32 v[76:77], v[86:87], v[84:85] op_sel:[0,1] op_sel_hi:[1,0] neg_hi:[0,1]
	v_pk_add_f32 v[72:73], v[72:73], v[92:93] op_sel:[0,1] op_sel_hi:[1,0] neg_lo:[0,1]
	v_pk_mul_f32 v[92:93], v[16:17], v[88:89] op_sel:[1,1] op_sel_hi:[1,0] neg_lo:[1,0]
	v_pk_add_f32 v[82:83], v[94:95], v[98:99]
	v_pk_add_f32 v[94:95], v[94:95], v[98:99] neg_lo:[0,1] neg_hi:[0,1]
	v_pk_add_f32 v[98:99], v[96:97], v[100:101]
	v_pk_add_f32 v[66:67], v[64:65], v[70:71] op_sel:[0,1] op_sel_hi:[1,0] neg_hi:[0,1]
	v_pk_fma_f32 v[88:89], v[16:17], v[88:89], v[92:93] op_sel_hi:[0,1,1]
	v_pk_mul_f32 v[92:93], v[24:25], v[76:77] op_sel:[1,1] op_sel_hi:[1,0] neg_lo:[1,0]
	v_pk_mul_f32 v[40:41], v[6:7], v[32:33] op_sel:[1,1] op_sel_hi:[1,0] neg_lo:[1,0]
	v_pk_add_f32 v[104:105], v[82:83], v[98:99]
	v_pk_add_f32 v[82:83], v[82:83], v[98:99] neg_lo:[0,1] neg_hi:[0,1]
	v_pk_fma_f32 v[76:77], v[24:25], v[76:77], v[92:93] op_sel_hi:[0,1,1]
	v_pk_mul_f32 v[92:93], v[28:29], v[66:67] op_sel:[1,1] op_sel_hi:[1,0] neg_lo:[1,0]
	v_pk_fma_f32 v[40:41], v[6:7], v[32:33], v[40:41] op_sel_hi:[0,1,1]
	v_pk_mul_f32 v[44:45], v[8:9], v[32:33] op_sel:[1,1] op_sel_hi:[1,0] neg_lo:[1,0]
	v_pk_add_f32 v[84:85], v[86:87], v[84:85] op_sel:[0,1] op_sel_hi:[1,0] neg_lo:[0,1]
	v_pk_add_f32 v[86:87], v[102:103], v[74:75]
	v_pk_add_f32 v[74:75], v[102:103], v[74:75] neg_lo:[0,1] neg_hi:[0,1]
	v_pk_fma_f32 v[66:67], v[28:29], v[66:67], v[92:93] op_sel_hi:[0,1,1]
	v_pk_mul_f32 v[92:93], v[32:33], v[82:83] op_sel:[1,1] op_sel_hi:[1,0] neg_lo:[1,0]
	v_pk_fma_f32 v[44:45], v[8:9], v[32:33], v[44:45] op_sel_hi:[0,1,1]
	v_pk_add_f32 v[100:101], v[96:97], v[100:101] neg_lo:[0,1] neg_hi:[0,1]
	v_pk_add_f32 v[98:99], v[78:79], v[90:91]
	v_pk_add_f32 v[78:79], v[78:79], v[90:91] neg_lo:[0,1] neg_hi:[0,1]
	v_pk_fma_f32 v[82:83], v[32:33], v[82:83], v[92:93] op_sel_hi:[0,1,1]
	v_pk_mul_f32 v[92:93], v[36:37], v[74:75] op_sel:[1,1] op_sel_hi:[1,0] neg_lo:[1,0]
	v_pk_add_f32 v[90:91], v[68:69], v[80:81]
	v_pk_add_f32 v[68:69], v[68:69], v[80:81] neg_lo:[0,1] neg_hi:[0,1]
	v_pk_fma_f32 v[74:75], v[36:37], v[74:75], v[92:93] op_sel_hi:[0,1,1]
	v_pk_mul_f32 v[92:93], v[40:41], v[78:79] op_sel:[1,1] op_sel_hi:[1,0] neg_lo:[1,0]
	v_pk_mul_f32 v[56:57], v[6:7], v[48:49] op_sel:[1,1] op_sel_hi:[1,0] neg_lo:[1,0]
	v_pk_add_f32 v[96:97], v[94:95], v[100:101] op_sel:[0,1] op_sel_hi:[1,0] neg_hi:[0,1]
	v_pk_add_f32 v[94:95], v[94:95], v[100:101] op_sel:[0,1] op_sel_hi:[1,0] neg_lo:[0,1]
	v_pk_fma_f32 v[78:79], v[40:41], v[78:79], v[92:93] op_sel_hi:[0,1,1]
	v_pk_mul_f32 v[92:93], v[44:45], v[68:69] op_sel:[1,1] op_sel_hi:[1,0] neg_lo:[1,0]
	v_pk_fma_f32 v[56:57], v[6:7], v[48:49], v[56:57] op_sel_hi:[0,1,1]
	v_pk_mul_f32 v[60:61], v[8:9], v[48:49] op_sel:[1,1] op_sel_hi:[1,0] neg_lo:[1,0]
	v_pk_fma_f32 v[68:69], v[44:45], v[68:69], v[92:93] op_sel_hi:[0,1,1]
	v_pk_mul_f32 v[92:93], v[48:49], v[94:95] op_sel:[1,1] op_sel_hi:[1,0] neg_lo:[1,0]
	v_pk_fma_f32 v[60:61], v[8:9], v[48:49], v[60:61] op_sel_hi:[0,1,1]
	v_pk_add_f32 v[64:65], v[64:65], v[70:71] op_sel:[0,1] op_sel_hi:[1,0] neg_lo:[0,1]
	v_pk_mul_f32 v[70:71], v[2:3], v[86:87] op_sel:[0,1] op_sel_hi:[1,0]
	v_pk_fma_f32 v[92:93], v[48:49], v[94:95], v[92:93] op_sel_hi:[0,1,1]
	v_pk_mul_f32 v[94:95], v[52:53], v[72:73] op_sel:[1,1] op_sel_hi:[1,0] neg_lo:[1,0]
	v_pk_fma_f32 v[70:71], v[4:5], v[86:87], v[70:71] op_sel_hi:[0,1,1]
	v_pk_mul_f32 v[86:87], v[8:9], v[90:91] op_sel:[1,1] op_sel_hi:[1,0] neg_lo:[1,0]
	v_pk_fma_f32 v[72:73], v[52:53], v[72:73], v[94:95] op_sel_hi:[0,1,1]
	v_pk_mul_f32 v[94:95], v[56:57], v[84:85] op_sel:[1,1] op_sel_hi:[1,0] neg_lo:[1,0]
	v_add_u32_e32 v5, 0x2000, v5
	v_pk_mul_f32 v[80:81], v[6:7], v[98:99] op_sel:[1,1] op_sel_hi:[1,0] neg_lo:[1,0]
	v_pk_fma_f32 v[86:87], v[8:9], v[90:91], v[86:87] op_sel_hi:[0,1,1]
	v_pk_mul_f32 v[90:91], v[10:11], v[96:97] op_sel:[1,1] op_sel_hi:[1,0] neg_lo:[1,0]
	v_pk_fma_f32 v[84:85], v[56:57], v[84:85], v[94:95] op_sel_hi:[0,1,1]
	v_pk_mul_f32 v[94:95], v[60:61], v[64:65] op_sel:[1,1] op_sel_hi:[1,0] neg_lo:[1,0]
	v_ashrrev_i32_e32 v5, 2, v5
	v_pk_fma_f32 v[80:81], v[6:7], v[98:99], v[80:81] op_sel_hi:[0,1,1]
	v_pk_fma_f32 v[90:91], v[10:11], v[96:97], v[90:91] op_sel_hi:[0,1,1]
	v_pk_fma_f32 v[64:65], v[60:61], v[64:65], v[94:95] op_sel_hi:[0,1,1]
	ds_write2_b64 v106, v[104:105], v[82:83] offset1:16
	ds_write2_b64 v106, v[90:91], v[92:93] offset0:33 offset1:49
	ds_write2_b64 v106, v[80:81], v[78:79] offset0:66 offset1:82
	ds_write2_b64 v106, v[76:77], v[84:85] offset0:99 offset1:115
	ds_write2_b64 v106, v[70:71], v[74:75] offset0:132 offset1:148
	ds_write2_b64 v106, v[88:89], v[72:73] offset0:165 offset1:181
	ds_write2_b64 v106, v[86:87], v[68:69] offset0:198 offset1:214
	ds_write2_b64 v106, v[66:67], v[64:65] offset0:231 offset1:247
	v_add3_u32 v18, v18, v5, s5
	ds_read2_b64 v[64:67], v18 offset1:16
	ds_read2_b64 v[68:71], v18 offset0:33 offset1:49
	ds_read2_b64 v[72:75], v18 offset0:66 offset1:82
	ds_read2_b64 v[76:79], v18 offset0:132 offset1:148
	ds_read2_b64 v[80:83], v18 offset0:99 offset1:115
	ds_read2_b64 v[84:87], v18 offset0:165 offset1:181
	ds_read2_b64 v[88:91], v18 offset0:198 offset1:214
	ds_read2_b64 v[92:95], v18 offset0:231 offset1:247
	s_waitcnt lgkmcnt(4)
	v_pk_add_f32 v[96:97], v[64:65], v[76:77]
	v_pk_add_f32 v[64:65], v[64:65], v[76:77] neg_lo:[0,1] neg_hi:[0,1]
	v_pk_add_f32 v[76:77], v[66:67], v[78:79]
	v_pk_add_f32 v[66:67], v[66:67], v[78:79] neg_lo:[0,1] neg_hi:[0,1]
	s_waitcnt lgkmcnt(1)
	v_pk_add_f32 v[98:99], v[74:75], v[90:91]
	v_pk_mul_f32 v[78:79], v[66:67], s[18:19]
	v_pk_add_f32 v[74:75], v[74:75], v[90:91] neg_lo:[0,1] neg_hi:[0,1]
	v_pk_fma_f32 v[66:67], v[66:67], s[16:17], v[78:79] op_sel:[0,0,1] op_sel_hi:[1,0,0]
	v_pk_add_f32 v[78:79], v[68:69], v[84:85]
	v_pk_add_f32 v[68:69], v[68:69], v[84:85] neg_lo:[0,1] neg_hi:[0,1]
	v_pk_mul_f32 v[90:91], v[74:75], s[40:41]
	v_pk_mul_f32 v[84:85], v[68:69], s[36:37]
	v_pk_fma_f32 v[74:75], v[74:75], s[68:69], v[90:91] op_sel:[0,0,1] op_sel_hi:[1,0,0] neg_lo:[1,0,0] neg_hi:[1,0,0]
	s_waitcnt lgkmcnt(0)
	v_pk_add_f32 v[90:91], v[80:81], v[92:93]
	v_pk_add_f32 v[80:81], v[80:81], v[92:93] neg_lo:[0,1] neg_hi:[0,1]
	v_pk_fma_f32 v[68:69], v[68:69], s[66:67], v[84:85] op_sel:[0,0,1] op_sel_hi:[1,0,0]
	v_pk_add_f32 v[84:85], v[70:71], v[86:87]
	v_pk_add_f32 v[70:71], v[70:71], v[86:87] neg_lo:[0,1] neg_hi:[0,1]
	v_pk_mul_f32 v[92:93], v[80:81], s[36:37]
	v_pk_mul_f32 v[86:87], v[70:71], s[40:41]
	v_pk_fma_f32 v[80:81], v[80:81], s[66:67], v[92:93] op_sel:[0,0,1] op_sel_hi:[1,0,0] neg_lo:[1,0,0] neg_hi:[1,0,0]
	v_pk_add_f32 v[92:93], v[82:83], v[94:95]
	v_pk_add_f32 v[82:83], v[82:83], v[94:95] neg_lo:[0,1] neg_hi:[0,1]
	v_pk_fma_f32 v[70:71], v[70:71], s[68:69], v[86:87] op_sel:[0,0,1] op_sel_hi:[1,0,0]
	v_pk_add_f32 v[86:87], v[72:73], v[88:89]
	v_pk_mul_f32 v[94:95], v[82:83], s[18:19]
	v_pk_add_f32 v[88:89], v[72:73], v[88:89] neg_lo:[0,1] neg_hi:[0,1]
	v_pk_fma_f32 v[82:83], v[82:83], s[16:17], v[94:95] op_sel:[0,0,1] op_sel_hi:[1,0,0] neg_lo:[1,0,0] neg_hi:[1,0,0]
	v_pk_add_f32 v[94:95], v[96:97], v[86:87]
	v_pk_add_f32 v[86:87], v[96:97], v[86:87] neg_lo:[0,1] neg_hi:[0,1]
	v_pk_add_f32 v[96:97], v[76:77], v[98:99]
	v_pk_add_f32 v[76:77], v[76:77], v[98:99] neg_lo:[0,1] neg_hi:[0,1]
	s_nop 0
	v_pk_mul_f32 v[98:99], v[76:77], s[36:37]
	v_pk_add_f32 v[100:101], v[84:85], v[92:93]
	v_pk_add_f32 v[84:85], v[84:85], v[92:93] neg_lo:[0,1] neg_hi:[0,1]
	v_pk_fma_f32 v[76:77], v[76:77], s[66:67], v[98:99] op_sel:[0,0,1] op_sel_hi:[1,0,0]
	v_pk_add_f32 v[98:99], v[78:79], v[90:91]
	v_pk_add_f32 v[90:91], v[78:79], v[90:91] neg_lo:[0,1] neg_hi:[0,1]
	v_pk_mul_f32 v[92:93], v[84:85], s[36:37]
	v_pk_add_f32 v[72:73], v[64:65], v[88:89] op_sel:[0,1] op_sel_hi:[1,0] neg_hi:[0,1]
	v_pk_add_f32 v[64:65], v[64:65], v[88:89] op_sel:[0,1] op_sel_hi:[1,0] neg_lo:[0,1]
	v_pk_add_f32 v[88:89], v[66:67], v[74:75]
	v_pk_add_f32 v[66:67], v[66:67], v[74:75] neg_lo:[0,1] neg_hi:[0,1]
	v_pk_fma_f32 v[84:85], v[84:85], s[66:67], v[92:93] op_sel:[0,0,1] op_sel_hi:[1,0,0] neg_lo:[1,0,0] neg_hi:[1,0,0]
	v_pk_mul_f32 v[74:75], v[66:67], s[36:37]
	s_nop 0
	v_pk_fma_f32 v[66:67], v[66:67], s[66:67], v[74:75] op_sel:[0,0,1] op_sel_hi:[1,0,0]
	v_pk_add_f32 v[74:75], v[68:69], v[80:81]
	v_pk_add_f32 v[92:93], v[70:71], v[82:83]
	v_pk_add_f32 v[70:71], v[70:71], v[82:83] neg_lo:[0,1] neg_hi:[0,1]
	v_pk_add_f32 v[78:79], v[86:87], v[90:91] op_sel:[0,1] op_sel_hi:[1,0] neg_hi:[0,1]
	v_pk_add_f32 v[86:87], v[86:87], v[90:91] op_sel:[0,1] op_sel_hi:[1,0] neg_lo:[0,1]
	v_pk_add_f32 v[90:91], v[76:77], v[84:85]
	v_pk_add_f32 v[84:85], v[76:77], v[84:85] neg_lo:[0,1] neg_hi:[0,1]
	v_pk_add_f32 v[80:81], v[68:69], v[80:81] neg_lo:[0,1] neg_hi:[0,1]
	v_pk_mul_f32 v[82:83], v[70:71], s[36:37]
	v_pk_add_f32 v[102:103], v[72:73], v[74:75]
	v_pk_add_f32 v[72:73], v[72:73], v[74:75] neg_lo:[0,1] neg_hi:[0,1]
	v_pk_add_f32 v[74:75], v[88:89], v[92:93]
	v_pk_fma_f32 v[70:71], v[70:71], s[66:67], v[82:83] op_sel:[0,0,1] op_sel_hi:[1,0,0] neg_lo:[1,0,0] neg_hi:[1,0,0]
	v_pk_add_f32 v[82:83], v[94:95], v[98:99]
	v_pk_add_f32 v[94:95], v[94:95], v[98:99] neg_lo:[0,1] neg_hi:[0,1]
	v_pk_add_f32 v[98:99], v[96:97], v[100:101]
	v_pk_add_f32 v[76:77], v[86:87], v[84:85] op_sel:[0,1] op_sel_hi:[1,0] neg_hi:[0,1]
	v_pk_add_f32 v[84:85], v[86:87], v[84:85] op_sel:[0,1] op_sel_hi:[1,0] neg_lo:[0,1]
	v_pk_add_f32 v[86:87], v[102:103], v[74:75]
	v_pk_add_f32 v[100:101], v[96:97], v[100:101] neg_lo:[0,1] neg_hi:[0,1]
	v_pk_add_f32 v[68:69], v[64:65], v[80:81] op_sel:[0,1] op_sel_hi:[1,0] neg_hi:[0,1]
	v_pk_add_f32 v[64:65], v[64:65], v[80:81] op_sel:[0,1] op_sel_hi:[1,0] neg_lo:[0,1]
	v_pk_add_f32 v[80:81], v[66:67], v[70:71]
	v_pk_add_f32 v[104:105], v[82:83], v[98:99]
	v_pk_add_f32 v[82:83], v[82:83], v[98:99] neg_lo:[0,1] neg_hi:[0,1]
	v_pk_add_f32 v[98:99], v[78:79], v[90:91]
	v_pk_mul_f32 v[2:3], v[2:3], v[86:87] op_sel:[0,1] op_sel_hi:[1,0]
	v_pk_add_f32 v[92:93], v[88:89], v[92:93] neg_lo:[0,1] neg_hi:[0,1]
	v_pk_add_f32 v[78:79], v[78:79], v[90:91] neg_lo:[0,1] neg_hi:[0,1]
	v_pk_add_f32 v[90:91], v[68:69], v[80:81]
	v_pk_fma_f32 v[2:3], v[4:5], v[86:87], v[2:3] op_sel_hi:[0,1,1]
	v_pk_mul_f32 v[4:5], v[6:7], v[98:99] op_sel:[1,1] op_sel_hi:[1,0] neg_lo:[1,0]
	v_pk_add_f32 v[70:71], v[66:67], v[70:71] neg_lo:[0,1] neg_hi:[0,1]
	v_pk_add_f32 v[96:97], v[94:95], v[100:101] op_sel:[0,1] op_sel_hi:[1,0] neg_hi:[0,1]
	v_pk_fma_f32 v[4:5], v[6:7], v[98:99], v[4:5] op_sel_hi:[0,1,1]
	v_pk_mul_f32 v[6:7], v[8:9], v[90:91] op_sel:[1,1] op_sel_hi:[1,0] neg_lo:[1,0]
	v_pk_add_f32 v[88:89], v[72:73], v[92:93] op_sel:[0,1] op_sel_hi:[1,0] neg_hi:[0,1]
	v_pk_fma_f32 v[6:7], v[8:9], v[90:91], v[6:7] op_sel_hi:[0,1,1]
	v_pk_mul_f32 v[8:9], v[10:11], v[96:97] op_sel:[1,1] op_sel_hi:[1,0] neg_lo:[1,0]
	v_pk_add_f32 v[66:67], v[64:65], v[70:71] op_sel:[0,1] op_sel_hi:[1,0] neg_hi:[0,1]
	v_pk_fma_f32 v[8:9], v[10:11], v[96:97], v[8:9] op_sel_hi:[0,1,1]
	v_pk_mul_f32 v[10:11], v[16:17], v[88:89] op_sel:[1,1] op_sel_hi:[1,0] neg_lo:[1,0]
	v_pk_add_f32 v[94:95], v[94:95], v[100:101] op_sel:[0,1] op_sel_hi:[1,0] neg_lo:[0,1]
	v_pk_add_f32 v[74:75], v[102:103], v[74:75] neg_lo:[0,1] neg_hi:[0,1]
	v_pk_add_f32 v[72:73], v[72:73], v[92:93] op_sel:[0,1] op_sel_hi:[1,0] neg_lo:[0,1]
	v_pk_add_f32 v[68:69], v[68:69], v[80:81] neg_lo:[0,1] neg_hi:[0,1]
	v_pk_add_f32 v[64:65], v[64:65], v[70:71] op_sel:[0,1] op_sel_hi:[1,0] neg_lo:[0,1]
	v_pk_fma_f32 v[10:11], v[16:17], v[88:89], v[10:11] op_sel_hi:[0,1,1]
	v_pk_mul_f32 v[12:13], v[24:25], v[76:77] op_sel:[1,1] op_sel_hi:[1,0] neg_lo:[1,0]
	v_pk_mul_f32 v[14:15], v[28:29], v[66:67] op_sel:[1,1] op_sel_hi:[1,0] neg_lo:[1,0]
	v_pk_mul_f32 v[16:17], v[32:33], v[82:83] op_sel:[1,1] op_sel_hi:[1,0] neg_lo:[1,0]
	v_pk_fma_f32 v[12:13], v[24:25], v[76:77], v[12:13] op_sel_hi:[0,1,1]
	v_pk_fma_f32 v[14:15], v[28:29], v[66:67], v[14:15] op_sel_hi:[0,1,1]
	v_pk_fma_f32 v[16:17], v[32:33], v[82:83], v[16:17] op_sel_hi:[0,1,1]
	v_pk_mul_f32 v[20:21], v[36:37], v[74:75] op_sel:[1,1] op_sel_hi:[1,0] neg_lo:[1,0]
	v_pk_mul_f32 v[22:23], v[40:41], v[78:79] op_sel:[1,1] op_sel_hi:[1,0] neg_lo:[1,0]
	v_pk_mul_f32 v[24:25], v[44:45], v[68:69] op_sel:[1,1] op_sel_hi:[1,0] neg_lo:[1,0]
	v_pk_mul_f32 v[26:27], v[48:49], v[94:95] op_sel:[1,1] op_sel_hi:[1,0] neg_lo:[1,0]
	v_pk_mul_f32 v[28:29], v[52:53], v[72:73] op_sel:[1,1] op_sel_hi:[1,0] neg_lo:[1,0]
	v_pk_mul_f32 v[30:31], v[56:57], v[84:85] op_sel:[1,1] op_sel_hi:[1,0] neg_lo:[1,0]
	v_pk_mul_f32 v[32:33], v[60:61], v[64:65] op_sel:[1,1] op_sel_hi:[1,0] neg_lo:[1,0]
	v_pk_fma_f32 v[20:21], v[36:37], v[74:75], v[20:21] op_sel_hi:[0,1,1]
	v_pk_fma_f32 v[22:23], v[40:41], v[78:79], v[22:23] op_sel_hi:[0,1,1]
	v_pk_fma_f32 v[24:25], v[44:45], v[68:69], v[24:25] op_sel_hi:[0,1,1]
	v_pk_fma_f32 v[26:27], v[48:49], v[94:95], v[26:27] op_sel_hi:[0,1,1]
	v_pk_fma_f32 v[28:29], v[52:53], v[72:73], v[28:29] op_sel_hi:[0,1,1]
	v_pk_fma_f32 v[30:31], v[56:57], v[84:85], v[30:31] op_sel_hi:[0,1,1]
	v_pk_fma_f32 v[32:33], v[60:61], v[64:65], v[32:33] op_sel_hi:[0,1,1]
	ds_write2_b64 v18, v[104:105], v[16:17] offset1:16
	ds_write2_b64 v18, v[8:9], v[26:27] offset0:33 offset1:49
	ds_write2_b64 v18, v[4:5], v[22:23] offset0:66 offset1:82
	ds_write2_b64 v18, v[12:13], v[30:31] offset0:99 offset1:115
	ds_write2_b64 v18, v[2:3], v[20:21] offset0:132 offset1:148
	ds_write2_b64 v18, v[10:11], v[28:29] offset0:165 offset1:181
	ds_write2_b64 v18, v[6:7], v[24:25] offset0:198 offset1:214
	ds_write2_b64 v18, v[14:15], v[32:33] offset0:231 offset1:247
	v_ashrrev_i32_e32 v2, 31, v210
	v_add_u32_sdwa v2, v210, v2 dst_sel:DWORD dst_unused:UNUSED_PAD src0_sel:DWORD src1_sel:BYTE_3
	s_lshl_b64 s[0:1], s[64:65], 15
	v_and_b32_e32 v2, 0xffffff00, v2
	s_add_u32 s0, s29, s0
	v_sub_u32_e32 v2, v210, v2
	s_addc_u32 s1, s85, s1
	v_ashrrev_i32_e32 v3, 31, v2
	v_lshl_add_u64 v[14:15], v[2:3], 3, s[0:1]
	s_movk_i32 s0, 0x1000
	v_add_co_u32_e32 v16, vcc, s0, v14
	s_movk_i32 s0, 0x3000
	s_nop 0
	v_addc_co_u32_e32 v17, vcc, 0, v15, vcc
	v_add_co_u32_e32 v2, vcc, s92, v14
	s_waitcnt lgkmcnt(0)
	s_nop 0
	v_addc_co_u32_e32 v3, vcc, 0, v15, vcc
	v_add_co_u32_e32 v22, vcc, s0, v14
	s_movk_i32 s0, 0x5000
	s_nop 0
	v_addc_co_u32_e32 v23, vcc, 0, v15, vcc
	v_add_co_u32_e32 v8, vcc, s95, v14
	s_barrier
	s_nop 0
	v_addc_co_u32_e32 v9, vcc, 0, v15, vcc
	v_add_co_u32_e32 v26, vcc, s0, v14
	s_nop 1
	v_addc_co_u32_e32 v27, vcc, 0, v15, vcc
	v_add_co_u32_e32 v10, vcc, s96, v14
	global_load_dwordx2 v[12:13], v[2:3], off nt
	global_load_dwordx2 v[6:7], v[2:3], off offset:2048 nt
	global_load_dwordx2 v[4:5], v[8:9], off offset:-4096 nt
	global_load_dwordx2 v[122:123], v[8:9], off nt
	v_addc_co_u32_e32 v11, vcc, 0, v15, vcc
	v_add_co_u32_e32 v28, vcc, s97, v14
	global_load_dwordx2 v[46:47], v[8:9], off offset:2048 nt
	global_load_dwordx2 v[38:39], v[10:11], off offset:-4096 nt
	global_load_dwordx2 v[20:21], v[10:11], off nt
	s_nop 0
	global_load_dwordx2 v[10:11], v[10:11], off offset:2048 nt
	v_addc_co_u32_e32 v29, vcc, 0, v15, vcc
	global_load_dwordx2 v[24:25], v[2:3], off offset:-4096 nt
	s_nop 0
	global_load_dwordx2 v[26:27], v[26:27], off offset:2048 nt
	s_nop 0
	global_load_dwordx2 v[8:9], v[28:29], off nt
	global_load_dwordx2 v[2:3], v[28:29], off offset:2048 nt
	global_load_dwordx2 v[30:31], v[14:15], off offset:2048 nt
	s_nop 0
	global_load_dwordx2 v[28:29], v[16:17], off offset:2048 nt
	s_nop 0
	global_load_dwordx2 v[16:17], v[22:23], off offset:2048 nt
	global_load_dwordx2 v[32:33], v[14:15], off nt
	v_mov_b32_e32 v14, v210
	s_waitcnt vmcnt(15)
	v_cvt_f32_f16_sdwa v164, v12 dst_sel:DWORD dst_unused:UNUSED_PAD src0_sel:WORD_1
	v_ashrrev_i32_e32 v15, 31, v14
	v_add_u32_sdwa v15, v14, v15 dst_sel:DWORD dst_unused:UNUSED_PAD src0_sel:DWORD src1_sel:BYTE_3
	v_ashrrev_i32_e32 v15, 8, v15
	v_mul_i32_i24_e32 v18, 0x100, v15
	v_sub_u32_e32 v18, v14, v18
	v_lshlrev_b32_e32 v14, 13, v15
	v_lshlrev_b32_e32 v15, 1, v18
	v_bfrev_b32_e32 v15, v15
	v_lshrrev_b32_e32 v15, 23, v15
	v_sub_u32_e32 v15, 0x200, v15
	v_bfrev_b32_e32 v15, v15
	v_lshrrev_b32_e32 v15, 19, v15
	v_and_b32_e32 v15, 0x1ff0, v15
	v_cmp_eq_u32_e64 s[0:1], 0, v18
	v_lshl_add_u32 v22, v18, 5, v14
	v_lshl_add_u32 v23, v22, 3, 0
	v_cndmask_b32_e64 v15, v15, 16, s[0:1]
	v_or_b32_e32 v14, v15, v14
	v_ashrrev_i32_e32 v22, 2, v22
	v_ashrrev_i32_e32 v15, 5, v14
	v_add_u32_e32 v211, v23, v22
	v_lshlrev_b32_e32 v14, 3, v14
	v_lshlrev_b32_e32 v15, 3, v15
	v_add3_u32 v212, 0, v14, v15
	ds_read2_b64 v[34:37], v211 offset1:1
	ds_read2_b64 v[40:43], v211 offset0:2 offset1:3
	ds_read2_b64 v[48:51], v212 offset1:1
	ds_read2_b64 v[52:55], v212 offset0:2 offset1:3
	ds_read2_b64 v[56:59], v211 offset0:4 offset1:5
	ds_read2_b64 v[60:63], v211 offset0:6 offset1:7
	ds_read2_b64 v[68:71], v212 offset0:4 offset1:5
	ds_read2_b64 v[72:75], v212 offset0:6 offset1:7
	ds_read2_b64 v[64:67], v211 offset0:8 offset1:9
	ds_read2_b64 v[76:79], v211 offset0:10 offset1:11
	ds_read2_b64 v[80:83], v212 offset0:8 offset1:9
	ds_read2_b64 v[98:101], v212 offset0:10 offset1:11
	ds_read2_b64 v[84:87], v211 offset0:12 offset1:13
	ds_read2_b64 v[88:91], v211 offset0:14 offset1:15
	ds_read2_b64 v[102:105], v212 offset0:12 offset1:13
	ds_read2_b64 v[106:109], v212 offset0:14 offset1:15
	s_waitcnt lgkmcnt(7)
	v_pk_add_f32 v[14:15], v[34:35], v[64:65]
	v_pk_add_f32 v[22:23], v[34:35], v[64:65] neg_lo:[0,1] neg_hi:[0,1]
	v_pk_add_f32 v[34:35], v[36:37], v[66:67]
	v_pk_add_f32 v[36:37], v[36:37], v[66:67] neg_lo:[0,1] neg_hi:[0,1]
	v_cmp_ne_u32_e32 vcc, 0, v18
	v_pk_mul_f32 v[44:45], v[36:37], s[18:19]
	v_bfrev_b32_e32 v18, v18
	v_pk_fma_f32 v[36:37], v[36:37], s[16:17], v[44:45] op_sel:[0,0,1] op_sel_hi:[1,0,0]
	s_waitcnt lgkmcnt(6)
	v_pk_add_f32 v[44:45], v[40:41], v[76:77]
	v_pk_add_f32 v[40:41], v[40:41], v[76:77] neg_lo:[0,1] neg_hi:[0,1]
	v_cvt_f32_ubyte3_e32 v18, v18
	v_pk_mul_f32 v[64:65], v[40:41], s[36:37]
	v_mul_f32_e32 v18, 0x38800000, v18
	v_pk_fma_f32 v[40:41], v[40:41], s[66:67], v[64:65] op_sel:[0,0,1] op_sel_hi:[1,0,0]
	v_pk_add_f32 v[64:65], v[42:43], v[78:79]
	v_pk_add_f32 v[42:43], v[42:43], v[78:79] neg_lo:[0,1] neg_hi:[0,1]
	s_waitcnt lgkmcnt(3)
	v_pk_add_f32 v[78:79], v[58:59], v[86:87]
	v_pk_mul_f32 v[66:67], v[42:43], s[40:41]
	v_pk_add_f32 v[58:59], v[58:59], v[86:87] neg_lo:[0,1] neg_hi:[0,1]
	v_pk_fma_f32 v[42:43], v[42:43], s[68:69], v[66:67] op_sel:[0,0,1] op_sel_hi:[1,0,0]
	v_pk_add_f32 v[66:67], v[56:57], v[84:85]
	v_pk_add_f32 v[76:77], v[56:57], v[84:85] neg_lo:[0,1] neg_hi:[0,1]
	v_pk_mul_f32 v[84:85], v[58:59], s[40:41]
	s_nop 0
	v_pk_fma_f32 v[58:59], v[58:59], s[68:69], v[84:85] op_sel:[0,0,1] op_sel_hi:[1,0,0] neg_lo:[1,0,0] neg_hi:[1,0,0]
	s_waitcnt lgkmcnt(2)
	v_pk_add_f32 v[84:85], v[60:61], v[88:89]
	v_pk_add_f32 v[60:61], v[60:61], v[88:89] neg_lo:[0,1] neg_hi:[0,1]
	s_nop 0
	v_pk_mul_f32 v[86:87], v[60:61], s[36:37]
	v_pk_add_f32 v[56:57], v[22:23], v[76:77] op_sel:[0,1] op_sel_hi:[1,0] neg_hi:[0,1]
	v_pk_fma_f32 v[60:61], v[60:61], s[66:67], v[86:87] op_sel:[0,0,1] op_sel_hi:[1,0,0] neg_lo:[1,0,0] neg_hi:[1,0,0]
	v_pk_add_f32 v[86:87], v[62:63], v[90:91]
	v_pk_add_f32 v[62:63], v[62:63], v[90:91] neg_lo:[0,1] neg_hi:[0,1]
	v_pk_add_f32 v[90:91], v[64:65], v[86:87]
	v_pk_mul_f32 v[88:89], v[62:63], s[18:19]
	v_pk_add_f32 v[64:65], v[64:65], v[86:87] neg_lo:[0,1] neg_hi:[0,1]
	v_pk_fma_f32 v[62:63], v[62:63], s[16:17], v[88:89] op_sel:[0,0,1] op_sel_hi:[1,0,0] neg_lo:[1,0,0] neg_hi:[1,0,0]
	v_pk_add_f32 v[88:89], v[14:15], v[66:67]
	v_pk_add_f32 v[14:15], v[14:15], v[66:67] neg_lo:[0,1] neg_hi:[0,1]
	v_pk_add_f32 v[66:67], v[34:35], v[78:79]
	v_pk_add_f32 v[34:35], v[34:35], v[78:79] neg_lo:[0,1] neg_hi:[0,1]
	v_pk_add_f32 v[22:23], v[22:23], v[76:77] op_sel:[0,1] op_sel_hi:[1,0] neg_lo:[0,1]
	v_pk_mul_f32 v[78:79], v[34:35], s[36:37]
	v_pk_add_f32 v[76:77], v[36:37], v[58:59]
	v_pk_add_f32 v[36:37], v[36:37], v[58:59] neg_lo:[0,1] neg_hi:[0,1]
	v_pk_fma_f32 v[34:35], v[34:35], s[66:67], v[78:79] op_sel:[0,0,1] op_sel_hi:[1,0,0]
	v_pk_add_f32 v[78:79], v[44:45], v[84:85]
	v_pk_add_f32 v[84:85], v[44:45], v[84:85] neg_lo:[0,1] neg_hi:[0,1]
	v_pk_mul_f32 v[86:87], v[64:65], s[36:37]
	v_pk_mul_f32 v[58:59], v[36:37], s[36:37]
	v_pk_fma_f32 v[64:65], v[64:65], s[66:67], v[86:87] op_sel:[0,0,1] op_sel_hi:[1,0,0] neg_lo:[1,0,0] neg_hi:[1,0,0]
	v_pk_fma_f32 v[36:37], v[36:37], s[66:67], v[58:59] op_sel:[0,0,1] op_sel_hi:[1,0,0]
	v_pk_add_f32 v[58:59], v[40:41], v[60:61]
	v_pk_add_f32 v[86:87], v[42:43], v[62:63]
	v_pk_add_f32 v[42:43], v[42:43], v[62:63] neg_lo:[0,1] neg_hi:[0,1]
	s_nop 0
	v_pk_mul_f32 v[62:63], v[42:43], s[36:37]
	v_pk_add_f32 v[44:45], v[14:15], v[84:85] op_sel:[0,1] op_sel_hi:[1,0] neg_hi:[0,1]
	v_pk_add_f32 v[14:15], v[14:15], v[84:85] op_sel:[0,1] op_sel_hi:[1,0] neg_lo:[0,1]
	v_pk_add_f32 v[84:85], v[34:35], v[64:65]
	v_pk_add_f32 v[64:65], v[34:35], v[64:65] neg_lo:[0,1] neg_hi:[0,1]
	v_pk_add_f32 v[94:95], v[56:57], v[58:59]
	v_pk_add_f32 v[56:57], v[56:57], v[58:59] neg_lo:[0,1] neg_hi:[0,1]
	v_pk_add_f32 v[58:59], v[76:77], v[86:87]
	v_pk_fma_f32 v[42:43], v[42:43], s[66:67], v[62:63] op_sel:[0,0,1] op_sel_hi:[1,0,0] neg_lo:[1,0,0] neg_hi:[1,0,0]
	v_pk_add_f32 v[62:63], v[88:89], v[78:79]
	v_pk_add_f32 v[78:79], v[88:89], v[78:79] neg_lo:[0,1] neg_hi:[0,1]
	v_pk_add_f32 v[88:89], v[66:67], v[90:91]
	v_pk_add_f32 v[110:111], v[76:77], v[86:87] neg_lo:[0,1] neg_hi:[0,1]
	v_pk_add_f32 v[86:87], v[94:95], v[58:59]
	v_pk_add_f32 v[34:35], v[94:95], v[58:59] neg_lo:[0,1] neg_hi:[0,1]
	v_pk_add_f32 v[58:59], v[50:51], v[82:83]
	v_pk_add_f32 v[50:51], v[50:51], v[82:83] neg_lo:[0,1] neg_hi:[0,1]
	v_pk_add_f32 v[60:61], v[40:41], v[60:61] neg_lo:[0,1] neg_hi:[0,1]
	v_pk_add_f32 v[148:149], v[62:63], v[88:89]
	v_pk_add_f32 v[138:139], v[62:63], v[88:89] neg_lo:[0,1] neg_hi:[0,1]
	v_pk_mul_f32 v[62:63], v[50:51], s[18:19]
	v_pk_add_f32 v[90:91], v[66:67], v[90:91] neg_lo:[0,1] neg_hi:[0,1]
	v_pk_fma_f32 v[50:51], v[50:51], s[16:17], v[62:63] op_sel:[0,0,1] op_sel_hi:[1,0,0]
	v_pk_add_f32 v[62:63], v[52:53], v[98:99]
	v_pk_add_f32 v[52:53], v[52:53], v[98:99] neg_lo:[0,1] neg_hi:[0,1]
	v_pk_add_f32 v[112:113], v[22:23], v[60:61] op_sel:[0,1] op_sel_hi:[1,0] neg_hi:[0,1]
	v_pk_add_f32 v[114:115], v[22:23], v[60:61] op_sel:[0,1] op_sel_hi:[1,0] neg_lo:[0,1]
	v_pk_add_f32 v[96:97], v[44:45], v[84:85]
	v_pk_add_f32 v[66:67], v[44:45], v[84:85] neg_lo:[0,1] neg_hi:[0,1]
	v_pk_add_f32 v[60:61], v[14:15], v[64:65] op_sel:[0,1] op_sel_hi:[1,0] neg_hi:[0,1]
	v_pk_add_f32 v[84:85], v[14:15], v[64:65] op_sel:[0,1] op_sel_hi:[1,0] neg_lo:[0,1]
	v_pk_mul_f32 v[64:65], v[52:53], s[36:37]
	s_nop 0
	v_pk_fma_f32 v[52:53], v[52:53], s[66:67], v[64:65] op_sel:[0,0,1] op_sel_hi:[1,0,0]
	v_pk_add_f32 v[64:65], v[54:55], v[100:101]
	v_pk_add_f32 v[54:55], v[54:55], v[100:101] neg_lo:[0,1] neg_hi:[0,1]
	s_nop 0
	v_pk_mul_f32 v[76:77], v[54:55], s[40:41]
	v_pk_add_f32 v[92:93], v[78:79], v[90:91] op_sel:[0,1] op_sel_hi:[1,0] neg_hi:[0,1]
	v_pk_fma_f32 v[54:55], v[54:55], s[68:69], v[76:77] op_sel:[0,0,1] op_sel_hi:[1,0,0]
	s_waitcnt lgkmcnt(1)
	v_pk_add_f32 v[76:77], v[68:69], v[102:103]
	v_pk_add_f32 v[68:69], v[68:69], v[102:103] neg_lo:[0,1] neg_hi:[0,1]
	v_pk_add_f32 v[88:89], v[78:79], v[90:91] op_sel:[0,1] op_sel_hi:[1,0] neg_lo:[0,1]
	v_xor_b32_e32 v79, 0x80000000, v68
	v_mov_b32_e32 v78, v69
	v_pk_add_f32 v[68:69], v[70:71], v[104:105]
	v_pk_add_f32 v[70:71], v[70:71], v[104:105] neg_lo:[0,1] neg_hi:[0,1]
	v_pk_add_f32 v[40:41], v[56:57], v[110:111] op_sel:[0,1] op_sel_hi:[1,0] neg_hi:[0,1]
	v_pk_add_f32 v[44:45], v[56:57], v[110:111] op_sel:[0,1] op_sel_hi:[1,0] neg_lo:[0,1]
	v_pk_add_f32 v[56:57], v[48:49], v[80:81]
	v_pk_add_f32 v[48:49], v[48:49], v[80:81] neg_lo:[0,1] neg_hi:[0,1]
	v_pk_mul_f32 v[80:81], v[70:71], s[40:41]
	v_cndmask_b32_e64 v18, v18, v208, s[0:1]
	v_pk_fma_f32 v[70:71], v[70:71], s[68:69], v[80:81] op_sel:[0,0,1] op_sel_hi:[1,0,0] neg_lo:[1,0,0] neg_hi:[1,0,0]
	s_waitcnt lgkmcnt(0)
	v_pk_add_f32 v[80:81], v[72:73], v[106:107]
	v_pk_add_f32 v[72:73], v[72:73], v[106:107] neg_lo:[0,1] neg_hi:[0,1]
	v_pk_add_f32 v[22:23], v[36:37], v[42:43]
	v_pk_mul_f32 v[82:83], v[72:73], s[36:37]
	v_pk_add_f32 v[116:117], v[36:37], v[42:43] neg_lo:[0,1] neg_hi:[0,1]
	v_pk_fma_f32 v[72:73], v[72:73], s[66:67], v[82:83] op_sel:[0,0,1] op_sel_hi:[1,0,0] neg_lo:[1,0,0] neg_hi:[1,0,0]
	v_pk_add_f32 v[82:83], v[74:75], v[108:109]
	v_pk_add_f32 v[74:75], v[74:75], v[108:109] neg_lo:[0,1] neg_hi:[0,1]
	s_nop 0
	v_pk_mul_f32 v[90:91], v[74:75], s[18:19]
	s_nop 0
	v_pk_fma_f32 v[74:75], v[74:75], s[16:17], v[90:91] op_sel:[0,0,1] op_sel_hi:[1,0,0] neg_lo:[1,0,0] neg_hi:[1,0,0]
	v_pk_add_f32 v[90:91], v[56:57], v[76:77]
	v_pk_add_f32 v[56:57], v[56:57], v[76:77] neg_lo:[0,1] neg_hi:[0,1]
	v_pk_add_f32 v[76:77], v[58:59], v[68:69]
	v_pk_add_f32 v[58:59], v[58:59], v[68:69] neg_lo:[0,1] neg_hi:[0,1]
	v_pk_add_f32 v[14:15], v[114:115], v[116:117] op_sel:[0,1] op_sel_hi:[1,0] neg_hi:[0,1]
	v_pk_mul_f32 v[68:69], v[58:59], s[36:37]
	v_pk_add_f32 v[36:37], v[114:115], v[116:117] op_sel:[0,1] op_sel_hi:[1,0] neg_lo:[0,1]
	v_pk_fma_f32 v[58:59], v[58:59], s[66:67], v[68:69] op_sel:[0,0,1] op_sel_hi:[1,0,0]
	v_pk_add_f32 v[68:69], v[62:63], v[80:81]
	v_pk_add_f32 v[80:81], v[62:63], v[80:81] neg_lo:[0,1] neg_hi:[0,1]
	s_waitcnt vmcnt(0)
	v_cvt_f32_f16_e32 v193, v33
	s_nop 0
	s_nop 0
	v_pk_add_f32 v[62:63], v[64:65], v[82:83]
	v_pk_add_f32 v[64:65], v[64:65], v[82:83] neg_lo:[0,1] neg_hi:[0,1]
	v_cvt_f32_f16_sdwa v192, v32 dst_sel:DWORD dst_unused:UNUSED_PAD src0_sel:WORD_1
	v_pk_mul_f32 v[82:83], v[64:65], s[36:37]
	v_cvt_f32_f16_e32 v194, v32
	v_pk_fma_f32 v[64:65], v[64:65], s[66:67], v[82:83] op_sel:[0,0,1] op_sel_hi:[1,0,0] neg_lo:[1,0,0] neg_hi:[1,0,0]
	v_pk_add_f32 v[82:83], v[48:49], v[78:79]
	v_pk_add_f32 v[48:49], v[48:49], v[78:79] neg_lo:[0,1] neg_hi:[0,1]
	v_pk_add_f32 v[78:79], v[50:51], v[70:71]
	v_pk_add_f32 v[50:51], v[50:51], v[70:71] neg_lo:[0,1] neg_hi:[0,1]
	v_cvt_f32_f16_sdwa v195, v33 dst_sel:DWORD dst_unused:UNUSED_PAD src0_sel:WORD_1
	v_pk_mul_f32 v[70:71], v[50:51], s[36:37]
	v_cvt_f32_f16_sdwa v170, v30 dst_sel:DWORD dst_unused:UNUSED_PAD src0_sel:WORD_1
	v_pk_fma_f32 v[50:51], v[50:51], s[66:67], v[70:71] op_sel:[0,0,1] op_sel_hi:[1,0,0]
	v_pk_add_f32 v[70:71], v[52:53], v[72:73]
	v_pk_add_f32 v[72:73], v[52:53], v[72:73] neg_lo:[0,1] neg_hi:[0,1]
	v_cvt_f32_f16_e32 v171, v31
	s_nop 0
	s_nop 0
	v_pk_add_f32 v[52:53], v[54:55], v[74:75]
	v_pk_add_f32 v[54:55], v[54:55], v[74:75] neg_lo:[0,1] neg_hi:[0,1]
	v_cvt_f32_f16_sdwa v185, v31 dst_sel:DWORD dst_unused:UNUSED_PAD src0_sel:WORD_1
	v_pk_mul_f32 v[74:75], v[54:55], s[36:37]
	v_cvt_f32_f16_e32 v184, v30
	v_pk_fma_f32 v[54:55], v[54:55], s[66:67], v[74:75] op_sel:[0,0,1] op_sel_hi:[1,0,0] neg_lo:[1,0,0] neg_hi:[1,0,0]
	v_pk_add_f32 v[74:75], v[90:91], v[68:69]
	v_pk_add_f32 v[68:69], v[90:91], v[68:69] neg_lo:[0,1] neg_hi:[0,1]
	v_pk_add_f32 v[90:91], v[76:77], v[62:63]
	v_pk_add_f32 v[62:63], v[76:77], v[62:63] neg_lo:[0,1] neg_hi:[0,1]
	v_cvt_f32_f16_sdwa v172, v24 dst_sel:DWORD dst_unused:UNUSED_PAD src0_sel:WORD_1
	v_xor_b32_e32 v77, 0x80000000, v62
	v_mov_b32_e32 v76, v63
	v_pk_add_f32 v[62:63], v[56:57], v[80:81] op_sel:[0,1] op_sel_hi:[1,0] neg_hi:[0,1]
	v_pk_add_f32 v[56:57], v[56:57], v[80:81] op_sel:[0,1] op_sel_hi:[1,0] neg_lo:[0,1]
	v_pk_add_f32 v[80:81], v[58:59], v[64:65]
	v_pk_add_f32 v[58:59], v[58:59], v[64:65] neg_lo:[0,1] neg_hi:[0,1]
	v_cvt_f32_f16_e32 v173, v25
	v_xor_b32_e32 v65, 0x80000000, v58
	v_mov_b32_e32 v64, v59
	v_pk_add_f32 v[58:59], v[82:83], v[70:71]
	v_pk_add_f32 v[70:71], v[82:83], v[70:71] neg_lo:[0,1] neg_hi:[0,1]
	v_pk_add_f32 v[82:83], v[78:79], v[52:53]
	v_pk_add_f32 v[52:53], v[78:79], v[52:53] neg_lo:[0,1] neg_hi:[0,1]
	v_pk_add_f32 v[118:119], v[58:59], v[82:83]
	v_pk_add_f32 v[134:135], v[58:59], v[82:83] neg_lo:[0,1] neg_hi:[0,1]
	v_cos_f32_e32 v83, v18
	v_sin_f32_e32 v82, v18
	v_cvt_f32_f16_sdwa v181, v25 dst_sel:DWORD dst_unused:UNUSED_PAD src0_sel:WORD_1
	v_cvt_f32_f16_e32 v180, v24
	v_cvt_f32_f16_sdwa v174, v28 dst_sel:DWORD dst_unused:UNUSED_PAD src0_sel:WORD_1
	v_cvt_f32_f16_e32 v175, v29
	v_cvt_f32_f16_sdwa v179, v29 dst_sel:DWORD dst_unused:UNUSED_PAD src0_sel:WORD_1
	v_cvt_f32_f16_e32 v178, v28
	v_cvt_f32_f16_e32 v165, v13
	v_cvt_f32_f16_sdwa v167, v13 dst_sel:DWORD dst_unused:UNUSED_PAD src0_sel:WORD_1
	v_cvt_f32_f16_e32 v166, v12
	v_cvt_f32_f16_e32 v154, v6
	v_cvt_f32_f16_e32 v155, v7
	v_cvt_f32_f16_sdwa v157, v7 dst_sel:DWORD dst_unused:UNUSED_PAD src0_sel:WORD_1
	v_cvt_f32_f16_sdwa v156, v6 dst_sel:DWORD dst_unused:UNUSED_PAD src0_sel:WORD_1
	v_cvt_f32_f16_sdwa v140, v4 dst_sel:DWORD dst_unused:UNUSED_PAD src0_sel:WORD_1
	v_cvt_f32_f16_e32 v141, v5
	v_cvt_f32_f16_sdwa v143, v5 dst_sel:DWORD dst_unused:UNUSED_PAD src0_sel:WORD_1
	v_cvt_f32_f16_e32 v142, v4
	v_cvt_f32_f16_e32 v124, v16
	v_cvt_f32_f16_e32 v125, v17
	v_cvt_f32_f16_sdwa v127, v17 dst_sel:DWORD dst_unused:UNUSED_PAD src0_sel:WORD_1
	v_cvt_f32_f16_sdwa v126, v16 dst_sel:DWORD dst_unused:UNUSED_PAD src0_sel:WORD_1
	v_cvt_f32_f16_sdwa v114, v122 dst_sel:DWORD dst_unused:UNUSED_PAD src0_sel:WORD_1
	v_cvt_f32_f16_e32 v115, v123
	v_cvt_f32_f16_sdwa v117, v123 dst_sel:DWORD dst_unused:UNUSED_PAD src0_sel:WORD_1
	v_cvt_f32_f16_e32 v116, v122
	v_xor_b32_e32 v79, 0x80000000, v52
	v_mov_b32_e32 v78, v53
	v_pk_add_f32 v[52:53], v[48:49], v[72:73] op_sel:[0,1] op_sel_hi:[1,0] neg_hi:[0,1]
	v_pk_add_f32 v[48:49], v[48:49], v[72:73] op_sel:[0,1] op_sel_hi:[1,0] neg_lo:[0,1]
	v_pk_add_f32 v[72:73], v[50:51], v[54:55]
	v_pk_add_f32 v[50:51], v[50:51], v[54:55] neg_lo:[0,1] neg_hi:[0,1]
	v_pk_fma_f32 v[160:161], v[82:83], 0, v[82:83] op_sel:[0,0,1] op_sel_hi:[1,0,0] neg_lo:[1,0,0] neg_hi:[1,0,0]
	v_xor_b32_e32 v55, 0x80000000, v50
	v_mov_b32_e32 v54, v51
	v_pk_fma_f32 v[198:199], v[82:83], 0, v[82:83] op_sel:[0,0,1] op_sel_hi:[1,0,0]
	v_pk_add_f32 v[42:43], v[112:113], v[22:23]
	v_pk_add_f32 v[22:23], v[112:113], v[22:23] neg_lo:[0,1] neg_hi:[0,1]
	v_pk_add_f32 v[98:99], v[74:75], v[90:91]
	v_pk_add_f32 v[100:101], v[74:75], v[90:91] neg_lo:[0,1] neg_hi:[0,1]
	v_pk_add_f32 v[102:103], v[68:69], v[76:77]
	v_pk_add_f32 v[106:107], v[68:69], v[76:77] neg_lo:[0,1] neg_hi:[0,1]
	v_pk_add_f32 v[104:105], v[62:63], v[80:81]
	v_pk_add_f32 v[108:109], v[62:63], v[80:81] neg_lo:[0,1] neg_hi:[0,1]
	v_pk_add_f32 v[110:111], v[56:57], v[64:65]
	v_pk_add_f32 v[112:113], v[56:57], v[64:65] neg_lo:[0,1] neg_hi:[0,1]
	v_pk_add_f32 v[152:153], v[70:71], v[78:79]
	v_pk_add_f32 v[162:163], v[70:71], v[78:79] neg_lo:[0,1] neg_hi:[0,1]
	v_pk_add_f32 v[176:177], v[52:53], v[72:73]
	v_pk_add_f32 v[182:183], v[52:53], v[72:73] neg_lo:[0,1] neg_hi:[0,1]
	v_pk_add_f32 v[188:189], v[48:49], v[54:55]
	v_pk_add_f32 v[196:197], v[48:49], v[54:55] neg_lo:[0,1] neg_hi:[0,1]
	v_pk_mul_f32 v[186:187], v[82:83], 0 op_sel_hi:[1,0]
	v_mov_b32_e32 v190, v160
	v_mov_b32_e32 v191, v199
	v_mul_f32_e32 v18, 0x3f3504f3, v83
	v_mul_f32_e32 v158, 0xbec3ef15, v83
	v_mul_f32_e32 v132, 0xbf6c835e, v83
	s_and_saveexec_b64 s[0:1], vcc
	s_xor_b64 s[0:1], exec, s[0:1]
	s_cbranch_execz .LBB0_536
	v_pk_add_f32 v[4:5], v[148:149], v[196:197]
	v_pk_add_f32 v[6:7], v[148:149], v[196:197] neg_lo:[0,1] neg_hi:[0,1]
	v_mul_f32_e32 v4, 0.5, v4
	v_mul_f32_e32 v12, 0.5, v7
	v_mov_b32_e32 v7, v5
	v_pk_mul_f32 v[6:7], v[6:7], s[44:45]
	v_pk_mov_b32 v[16:17], v[198:199], v[160:161] op_sel:[1,0]
	v_pk_mul_f32 v[24:25], v[190:191], v[6:7] op_sel:[0,1] op_sel_hi:[1,0]
	v_pk_mul_f32 v[6:7], v[190:191], v[6:7]
	v_pk_add_f32 v[24:25], v[24:25], v[24:25] op_sel:[0,1] op_sel_hi:[0,1]
	v_pk_add_f32 v[28:29], v[4:5], v[24:25] op_sel_hi:[0,1] neg_hi:[0,1]
	v_pk_add_f32 v[4:5], v[6:7], v[6:7] op_sel:[0,1] op_sel_hi:[0,1] neg_lo:[0,1] neg_hi:[0,1]
	v_pk_add_f32 v[6:7], v[12:13], v[4:5] op_sel_hi:[0,1] neg_hi:[0,1]
	v_pk_mul_f32 v[4:5], v[6:7], v[194:195]
	v_pk_mul_f32 v[6:7], v[6:7], v[192:193]
	v_pk_fma_f32 v[4:5], v[28:29], v[192:193], v[4:5]
	v_pk_fma_f32 v[6:7], v[28:29], v[194:195], v[6:7] neg_lo:[0,0,1] neg_hi:[0,0,1]
	s_mov_b32 s66, s19
	v_pk_add_f32 v[12:13], v[6:7], v[4:5] op_sel:[0,1] op_sel_hi:[1,0] neg_lo:[0,1]
	v_pk_add_f32 v[28:29], v[6:7], v[4:5] op_sel:[0,1] op_sel_hi:[1,0]
	v_pk_add_f32 v[4:5], v[4:5], v[6:7] op_sel:[1,0] op_sel_hi:[0,1] neg_lo:[0,1] neg_hi:[0,1]
	s_nop 0
	v_pk_mul_f32 v[12:13], v[12:13], 0.5 op_sel_hi:[1,0]
	v_mov_b32_e32 v29, v5
	v_mul_f32_e32 v24, v190, v12
	v_pk_fma_f32 v[30:31], v[190:191], v[12:13], v[24:25] op_sel_hi:[1,1,0] neg_lo:[1,0,0] neg_hi:[1,0,0]
	v_mul_f32_e32 v24, v160, v13
	v_pk_fma_f32 v[12:13], v[16:17], v[12:13], v[24:25] op_sel_hi:[1,1,0]
	v_mov_b32_e32 v16, v83
	v_mov_b32_e32 v30, v12
	v_pk_fma_f32 v[4:5], v[28:29], 0.5, v[12:13] op_sel_hi:[1,0,1] neg_lo:[0,0,1] neg_hi:[0,0,1]
	v_pk_fma_f32 v[122:123], v[28:29], 0.5, v[30:31] op_sel_hi:[1,0,1]
	v_pk_fma_f32 v[6:7], v[28:29], 0.5, v[30:31] op_sel_hi:[1,0,1] neg_lo:[1,0,0] neg_hi:[1,0,0]
	v_mov_b32_e32 v5, v123
	v_pk_mul_f32 v[24:25], v[4:5], s[46:47] op_sel_hi:[1,0]
	v_pk_add_f32 v[4:5], v[138:139], v[188:189]
	v_pk_add_f32 v[12:13], v[138:139], v[188:189] neg_lo:[0,1] neg_hi:[0,1]
	v_mov_b32_e32 v17, v82
	v_mul_f32_e32 v6, 0.5, v13
	v_pk_add_f32 v[28:29], v[186:187], v[16:17] neg_lo:[0,1] neg_hi:[0,1]
	v_pk_add_f32 v[30:31], v[186:187], v[16:17]
	v_mov_b32_e32 v13, v5
	v_pk_mov_b32 v[32:33], v[28:29], v[30:31] op_sel:[1,0]
	v_pk_mul_f32 v[12:13], v[12:13], s[44:45]
	v_mul_f32_e32 v4, 0.5, v4
	v_pk_mul_f32 v[48:49], v[32:33], v[12:13] op_sel:[0,1] op_sel_hi:[1,0]
	v_pk_mul_f32 v[12:13], v[32:33], v[12:13]
	v_pk_add_f32 v[48:49], v[48:49], v[48:49] op_sel:[0,1] op_sel_hi:[0,1]
	v_pk_add_f32 v[50:51], v[4:5], v[48:49] op_sel_hi:[0,1] neg_hi:[0,1]
	v_pk_add_f32 v[4:5], v[12:13], v[12:13] op_sel:[0,1] op_sel_hi:[0,1] neg_lo:[0,1] neg_hi:[0,1]
	v_pk_add_f32 v[12:13], v[6:7], v[4:5] op_sel_hi:[0,1] neg_hi:[0,1]
	v_pk_mul_f32 v[4:5], v[12:13], v[184:185]
	v_pk_mul_f32 v[12:13], v[12:13], v[170:171]
	v_pk_fma_f32 v[4:5], v[50:51], v[170:171], v[4:5]
	v_pk_fma_f32 v[12:13], v[50:51], v[184:185], v[12:13] neg_lo:[0,0,1] neg_hi:[0,0,1]
	v_mov_b32_e32 v31, v29
	v_pk_add_f32 v[48:49], v[12:13], v[4:5] op_sel:[0,1] op_sel_hi:[1,0] neg_lo:[0,1]
	v_pk_add_f32 v[50:51], v[12:13], v[4:5] op_sel:[0,1] op_sel_hi:[1,0]
	v_pk_add_f32 v[4:5], v[4:5], v[12:13] op_sel:[1,0] op_sel_hi:[0,1] neg_lo:[0,1] neg_hi:[0,1]
	v_pk_mul_f32 v[48:49], v[48:49], 0.5 op_sel_hi:[1,0]
	v_mov_b32_e32 v51, v5
	v_mul_f32_e32 v6, v29, v48
	v_pk_fma_f32 v[32:33], v[32:33], v[48:49], v[6:7] op_sel_hi:[1,1,0] neg_lo:[1,0,0] neg_hi:[1,0,0]
	v_mul_f32_e32 v6, v29, v49
	v_pk_fma_f32 v[28:29], v[30:31], v[48:49], v[6:7] op_sel_hi:[1,1,0]
	v_pk_mul_f32 v[12:13], v[16:17], s[36:37]
	v_mov_b32_e32 v32, v28
	v_pk_fma_f32 v[4:5], v[50:51], 0.5, v[28:29] op_sel_hi:[1,0,1] neg_lo:[0,0,1] neg_hi:[0,0,1]
	v_pk_fma_f32 v[138:139], v[50:51], 0.5, v[32:33] op_sel_hi:[1,0,1]
	v_pk_add_f32 v[16:17], v[92:93], v[182:183]
	v_mov_b32_e32 v5, v139
	v_pk_add_f32 v[28:29], v[92:93], v[182:183] neg_lo:[0,1] neg_hi:[0,1]
	v_pk_mul_f32 v[30:31], v[4:5], s[46:47] op_sel_hi:[1,0]
	v_pk_fma_f32 v[4:5], v[50:51], 0.5, v[32:33] op_sel_hi:[1,0,1] neg_lo:[1,0,0] neg_hi:[1,0,0]
	v_mul_f32_e32 v6, 0.5, v29
	v_pk_add_f32 v[32:33], v[18:19], v[12:13] op_sel:[0,1] op_sel_hi:[0,1] neg_lo:[0,1] neg_hi:[0,1]
	v_pk_add_f32 v[48:49], v[18:19], v[12:13] op_sel:[0,1] op_sel_hi:[0,1]
	v_mov_b32_e32 v29, v17
	v_mul_f32_e32 v4, 0.5, v16
	v_mov_b32_e32 v50, v32
	v_mov_b32_e32 v51, v49
	v_pk_mul_f32 v[16:17], v[28:29], s[44:45]
	v_pk_mov_b32 v[48:49], v[48:49], v[32:33] op_sel:[1,0]
	v_pk_mul_f32 v[28:29], v[50:51], v[16:17] op_sel:[0,1] op_sel_hi:[1,0]
	v_pk_mul_f32 v[16:17], v[50:51], v[16:17]
	v_pk_add_f32 v[28:29], v[28:29], v[28:29] op_sel:[0,1] op_sel_hi:[0,1]
	v_pk_add_f32 v[52:53], v[4:5], v[28:29] op_sel_hi:[0,1] neg_hi:[0,1]
	v_pk_add_f32 v[16:17], v[16:17], v[16:17] op_sel:[0,1] op_sel_hi:[0,1] neg_lo:[0,1] neg_hi:[0,1]
	v_pk_add_f32 v[28:29], v[6:7], v[16:17] op_sel_hi:[0,1] neg_hi:[0,1]
	v_pk_mul_f32 v[16:17], v[28:29], v[180:181]
	v_pk_mul_f32 v[28:29], v[28:29], v[172:173]
	v_pk_fma_f32 v[16:17], v[52:53], v[172:173], v[16:17]
	v_pk_fma_f32 v[28:29], v[52:53], v[180:181], v[28:29] neg_lo:[0,0,1] neg_hi:[0,0,1]
	v_sub_f32_e32 v6, v89, v177
	v_pk_add_f32 v[52:53], v[28:29], v[16:17] op_sel:[0,1] op_sel_hi:[1,0] neg_lo:[0,1]
	v_pk_add_f32 v[54:55], v[28:29], v[16:17] op_sel:[0,1] op_sel_hi:[1,0]
	v_pk_add_f32 v[16:17], v[16:17], v[28:29] op_sel:[1,0] op_sel_hi:[0,1] neg_lo:[0,1] neg_hi:[0,1]
	v_pk_mul_f32 v[52:53], v[52:53], 0.5 op_sel_hi:[1,0]
	v_mov_b32_e32 v55, v17
	v_mul_f32_e32 v4, v32, v52
	v_pk_fma_f32 v[56:57], v[50:51], v[52:53], v[4:5] op_sel_hi:[1,1,0] neg_lo:[1,0,0] neg_hi:[1,0,0]
	v_mul_f32_e32 v4, v32, v53
	v_pk_fma_f32 v[48:49], v[48:49], v[52:53], v[4:5] op_sel_hi:[1,1,0]
	v_pk_add_f32 v[28:29], v[88:89], v[176:177]
	v_mov_b32_e32 v56, v48
	v_pk_fma_f32 v[16:17], v[54:55], 0.5, v[48:49] op_sel_hi:[1,0,1] neg_lo:[0,0,1] neg_hi:[0,0,1]
	v_mov_b32_e32 v48, v12
	v_mov_b32_e32 v49, v88
	v_pk_mov_b32 v[12:13], v[12:13], v[176:177] op_sel:[1,0]
	v_mul_f32_e32 v18, 0.5, v29
	v_pk_add_f32 v[12:13], v[48:49], v[12:13] neg_lo:[0,1] neg_hi:[0,1]
	v_mul_f32_e32 v4, 0.5, v28
	v_pk_mul_f32 v[48:49], v[12:13], v[18:19]
	v_mov_b32_e32 v13, v32
	v_pk_fma_f32 v[50:51], v[50:51], v[48:49], v[48:49] op_sel:[0,1,0] op_sel_hi:[1,0,1]
	v_mov_b32_e32 v48, v49
	v_mov_b32_e32 v49, v18
	v_pk_mul_f32 v[48:49], v[12:13], v[48:49]
	v_pk_add_f32 v[52:53], v[4:5], v[50:51]
	v_mul_f32_e32 v6, 0.5, v6
	v_fma_f32 v53, v28, 0.5, -v50
	v_pk_add_f32 v[28:29], v[48:49], v[48:49] op_sel:[0,1] op_sel_hi:[0,1] neg_lo:[0,1] neg_hi:[0,1]
	v_pk_add_f32 v[48:49], v[6:7], v[28:29] op_sel_hi:[0,1] neg_hi:[0,1]
	v_pk_mul_f32 v[28:29], v[48:49], v[178:179]
	v_pk_mul_f32 v[48:49], v[48:49], v[174:175]
	v_pk_fma_f32 v[28:29], v[52:53], v[174:175], v[28:29]
	v_pk_fma_f32 v[48:49], v[52:53], v[178:179], v[48:49] neg_lo:[0,0,1] neg_hi:[0,0,1]
	v_pk_fma_f32 v[92:93], v[54:55], 0.5, v[56:57] op_sel_hi:[1,0,1]
	v_pk_add_f32 v[50:51], v[48:49], v[28:29] op_sel:[0,1] op_sel_hi:[1,0] neg_lo:[0,1]
	v_pk_add_f32 v[52:53], v[48:49], v[28:29] op_sel:[0,1] op_sel_hi:[1,0]
	v_mov_b32_e32 v17, v93
	v_pk_mul_f32 v[50:51], v[50:51], 0.5 op_sel_hi:[1,0]
	v_pk_mul_f32 v[64:65], v[16:17], s[46:47] op_sel_hi:[1,0]
	v_mul_f32_e32 v4, v12, v50
	v_pk_fma_f32 v[16:17], v[54:55], 0.5, v[56:57] op_sel_hi:[1,0,1] neg_lo:[1,0,0] neg_hi:[1,0,0]
	v_pk_fma_f32 v[54:55], v[12:13], v[50:51], v[4:5] op_sel_hi:[1,1,0] neg_lo:[1,0,0] neg_hi:[1,0,0]
	v_mov_b32_e32 v33, v12
	v_mul_f32_e32 v4, v12, v51
	v_pk_fma_f32 v[12:13], v[32:33], v[50:51], v[4:5] op_sel_hi:[1,1,0]
	v_pk_add_f32 v[28:29], v[28:29], v[48:49] op_sel:[1,0] op_sel_hi:[0,1] neg_lo:[0,1] neg_hi:[0,1]
	v_mov_b32_e32 v53, v29
	v_mov_b32_e32 v54, v12
	v_pk_fma_f32 v[12:13], v[52:53], 0.5, v[12:13] op_sel_hi:[1,0,1] neg_lo:[0,0,1] neg_hi:[0,0,1]
	v_pk_fma_f32 v[88:89], v[52:53], 0.5, v[54:55] op_sel_hi:[1,0,1]
	s_mov_b32 s67, s16
	v_mov_b32_e32 v13, v89
	v_pk_mul_f32 v[68:69], v[12:13], s[46:47] op_sel_hi:[1,0]
	v_pk_fma_f32 v[12:13], v[52:53], 0.5, v[54:55] op_sel_hi:[1,0,1] neg_lo:[1,0,0] neg_hi:[1,0,0]
	v_mov_b32_e32 v4, v83
	s_mov_b32 s17, s19
	v_pk_mul_f32 v[48:49], v[82:83], s[66:67] op_sel_hi:[0,1]
	v_pk_add_f32 v[28:29], v[96:97], v[162:163]
	v_pk_add_f32 v[32:33], v[96:97], v[162:163] neg_lo:[0,1] neg_hi:[0,1]
	v_pk_fma_f32 v[52:53], v[4:5], s[16:17], v[48:49] op_sel_hi:[0,1,1] neg_lo:[0,0,1] neg_hi:[0,0,1]
	v_mul_f32_e32 v12, 0.5, v33
	v_pk_fma_f32 v[50:51], v[4:5], s[16:17], v[48:49] op_sel_hi:[0,1,1]
	v_mov_b32_e32 v33, v29
	v_mul_f32_e32 v6, 0.5, v28
	v_mov_b32_e32 v54, v52
	v_mov_b32_e32 v55, v51
	v_pk_mul_f32 v[28:29], v[32:33], s[44:45]
	v_pk_mov_b32 v[56:57], v[50:51], v[52:53] op_sel:[1,0]
	v_pk_mul_f32 v[32:33], v[54:55], v[28:29] op_sel:[0,1] op_sel_hi:[1,0]
	v_pk_mul_f32 v[28:29], v[54:55], v[28:29]
	v_pk_add_f32 v[32:33], v[32:33], v[32:33] op_sel:[0,1] op_sel_hi:[0,1]
	v_pk_add_f32 v[58:59], v[6:7], v[32:33] op_sel_hi:[0,1] neg_hi:[0,1]
	v_pk_add_f32 v[28:29], v[28:29], v[28:29] op_sel:[0,1] op_sel_hi:[0,1] neg_lo:[0,1] neg_hi:[0,1]
	v_pk_add_f32 v[32:33], v[12:13], v[28:29] op_sel_hi:[0,1] neg_hi:[0,1]
	v_pk_mul_f32 v[28:29], v[32:33], v[166:167]
	v_pk_mul_f32 v[32:33], v[32:33], v[164:165]
	v_pk_fma_f32 v[28:29], v[58:59], v[164:165], v[28:29]
	v_pk_fma_f32 v[32:33], v[58:59], v[166:167], v[32:33] neg_lo:[0,0,1] neg_hi:[0,0,1]
	v_mov_b32_e32 v159, v66
	v_pk_add_f32 v[58:59], v[32:33], v[28:29] op_sel:[0,1] op_sel_hi:[1,0] neg_lo:[0,1]
	v_pk_add_f32 v[70:71], v[32:33], v[28:29] op_sel:[0,1] op_sel_hi:[1,0]
	v_pk_add_f32 v[28:29], v[28:29], v[32:33] op_sel:[1,0] op_sel_hi:[0,1] neg_lo:[0,1] neg_hi:[0,1]
	v_pk_mul_f32 v[58:59], v[58:59], 0.5 op_sel_hi:[1,0]
	v_mov_b32_e32 v71, v29
	v_mul_f32_e32 v6, v52, v58
	v_pk_fma_f32 v[72:73], v[54:55], v[58:59], v[6:7] op_sel_hi:[1,1,0] neg_lo:[1,0,0] neg_hi:[1,0,0]
	v_mul_f32_e32 v6, v52, v59
	v_pk_fma_f32 v[56:57], v[56:57], v[58:59], v[6:7] op_sel_hi:[1,1,0]
	v_sub_f32_e32 v12, v67, v153
	v_mov_b32_e32 v72, v56
	v_pk_fma_f32 v[28:29], v[70:71], 0.5, v[56:57] op_sel_hi:[1,0,1] neg_lo:[0,0,1] neg_hi:[0,0,1]
	v_pk_fma_f32 v[96:97], v[70:71], 0.5, v[72:73] op_sel_hi:[1,0,1]
	v_pk_mov_b32 v[56:57], v[48:49], v[152:153] op_sel:[1,0]
	v_mov_b32_e32 v29, v97
	v_pk_mul_f32 v[62:63], v[28:29], s[46:47] op_sel_hi:[1,0]
	v_pk_add_f32 v[28:29], v[66:67], v[152:153]
	v_pk_add_f32 v[56:57], v[158:159], v[56:57] neg_lo:[0,1] neg_hi:[0,1]
	v_mul_f32_e32 v18, 0.5, v29
	v_pk_mul_f32 v[58:59], v[56:57], v[18:19]
	v_mul_f32_e32 v6, 0.5, v28
	v_pk_fma_f32 v[54:55], v[54:55], v[58:59], v[58:59] op_sel:[0,1,0] op_sel_hi:[1,0,1]
	v_mov_b32_e32 v66, v56
	v_mov_b32_e32 v67, v52
	v_mov_b32_e32 v58, v59
	v_mov_b32_e32 v59, v18
	v_pk_mul_f32 v[58:59], v[66:67], v[58:59]
	v_pk_add_f32 v[66:67], v[6:7], v[54:55]
	v_mul_f32_e32 v12, 0.5, v12
	v_fma_f32 v67, v28, 0.5, -v54
	v_pk_add_f32 v[28:29], v[58:59], v[58:59] op_sel:[0,1] op_sel_hi:[0,1] neg_lo:[0,1] neg_hi:[0,1]
	v_pk_add_f32 v[54:55], v[12:13], v[28:29] op_sel_hi:[0,1] neg_hi:[0,1]
	v_pk_mul_f32 v[28:29], v[54:55], v[156:157]
	v_pk_mul_f32 v[54:55], v[54:55], v[154:155]
	v_pk_fma_f32 v[32:33], v[70:71], 0.5, v[72:73] op_sel_hi:[1,0,1] neg_lo:[1,0,0] neg_hi:[1,0,0]
	v_pk_fma_f32 v[58:59], v[66:67], v[154:155], v[28:29] neg_lo:[0,0,1] neg_hi:[0,0,1]
	v_pk_fma_f32 v[28:29], v[66:67], v[154:155], v[28:29]
	v_pk_fma_f32 v[70:71], v[66:67], v[156:157], v[54:55]
	v_pk_fma_f32 v[54:55], v[66:67], v[156:157], v[54:55] neg_lo:[0,0,1] neg_hi:[0,0,1]
	v_pk_add_f32 v[72:73], v[58:59], v[28:29] op_sel:[0,1] op_sel_hi:[1,0]
	v_pk_add_f32 v[66:67], v[70:71], v[54:55] op_sel_hi:[0,1] neg_lo:[0,1] neg_hi:[0,1]
	v_pk_add_f32 v[28:29], v[58:59], v[28:29] op_sel_hi:[0,1] neg_lo:[0,1] neg_hi:[0,1]
	v_pk_add_f32 v[54:55], v[70:71], v[54:55] op_sel:[0,1] op_sel_hi:[1,0]
	v_mov_b32_e32 v73, v67
	v_mov_b32_e32 v55, v29
	v_pk_mul_f32 v[28:29], v[54:55], 0.5 op_sel_hi:[1,0]
	v_mov_b32_e32 v133, v84
	v_pk_mul_f32 v[54:55], v[52:53], v[28:29] op_sel:[0,1] op_sel_hi:[0,0]
	v_pk_fma_f32 v[58:59], v[56:57], v[28:29], v[54:55] op_sel_hi:[0,1,1]
	v_pk_fma_f32 v[28:29], v[56:57], v[28:29], v[54:55] op_sel_hi:[0,1,1] neg_hi:[0,0,1]
	v_pk_fma_f32 v[54:55], v[72:73], 0.5, v[58:59] op_sel_hi:[1,0,1] neg_lo:[0,0,1] neg_hi:[0,0,1]
	v_pk_fma_f32 v[66:67], v[72:73], 0.5, v[28:29] op_sel_hi:[1,0,1]
	v_pk_add_f32 v[56:57], v[60:61], v[134:135] neg_lo:[0,1] neg_hi:[0,1]
	v_mov_b32_e32 v55, v67
	v_pk_mul_f32 v[90:91], v[54:55], s[46:47] op_sel_hi:[1,0]
	v_pk_add_f32 v[54:55], v[134:135], v[60:61]
	v_mul_f32_e32 v12, 0.5, v57
	v_mov_b32_e32 v57, v55
	v_mul_f32_e32 v6, 0.5, v54
	v_pk_mov_b32 v[58:59], v[52:53], v[50:51] op_sel:[1,0]
	v_pk_mul_f32 v[54:55], v[56:57], s[44:45]
	v_pk_fma_f32 v[28:29], v[72:73], 0.5, v[28:29] op_sel_hi:[1,0,1] neg_lo:[1,0,0] neg_hi:[1,0,0]
	v_pk_mul_f32 v[56:57], v[58:59], v[54:55] op_sel:[0,1] op_sel_hi:[1,0]
	v_pk_mul_f32 v[54:55], v[58:59], v[54:55]
	v_pk_add_f32 v[56:57], v[56:57], v[56:57] op_sel:[0,1] op_sel_hi:[0,1]
	v_pk_add_f32 v[60:61], v[6:7], v[56:57] op_sel_hi:[0,1] neg_hi:[0,1]
	v_pk_add_f32 v[54:55], v[54:55], v[54:55] op_sel:[0,1] op_sel_hi:[0,1] neg_lo:[0,1] neg_hi:[0,1]
	v_pk_add_f32 v[56:57], v[12:13], v[54:55] op_sel_hi:[0,1] neg_hi:[0,1]
	v_pk_mul_f32 v[54:55], v[56:57], v[142:143]
	v_pk_mul_f32 v[56:57], v[56:57], v[140:141]
	v_pk_fma_f32 v[54:55], v[60:61], v[140:141], v[54:55]
	v_pk_fma_f32 v[56:57], v[60:61], v[142:143], v[56:57] neg_lo:[0,0,1] neg_hi:[0,0,1]
	v_mov_b32_e32 v51, v53
	v_pk_add_f32 v[60:61], v[56:57], v[54:55] op_sel:[0,1] op_sel_hi:[1,0] neg_lo:[0,1]
	v_pk_add_f32 v[70:71], v[56:57], v[54:55] op_sel:[0,1] op_sel_hi:[1,0]
	v_pk_add_f32 v[54:55], v[54:55], v[56:57] op_sel:[1,0] op_sel_hi:[0,1] neg_lo:[0,1] neg_hi:[0,1]
	v_pk_mul_f32 v[60:61], v[60:61], 0.5 op_sel_hi:[1,0]
	v_mov_b32_e32 v71, v55
	v_mul_f32_e32 v6, v53, v60
	v_pk_fma_f32 v[72:73], v[58:59], v[60:61], v[6:7] op_sel_hi:[1,1,0] neg_lo:[1,0,0] neg_hi:[1,0,0]
	v_mul_f32_e32 v6, v53, v61
	v_pk_fma_f32 v[50:51], v[50:51], v[60:61], v[6:7] op_sel_hi:[1,1,0]
	v_pk_add_f32 v[54:55], v[118:119], v[84:85]
	v_mov_b32_e32 v72, v50
	v_mov_b32_e32 v49, v118
	v_pk_fma_f32 v[50:51], v[70:71], 0.5, v[50:51] op_sel_hi:[1,0,1] neg_lo:[0,0,1] neg_hi:[0,0,1]
	v_pk_fma_f32 v[60:61], v[70:71], 0.5, v[72:73] op_sel_hi:[1,0,1]
	v_mul_f32_e32 v18, 0.5, v55
	v_pk_add_f32 v[48:49], v[132:133], v[48:49] neg_lo:[0,1] neg_hi:[0,1]
	v_mov_b32_e32 v51, v61
	v_pk_mul_f32 v[56:57], v[48:49], v[18:19]
	v_pk_mul_f32 v[94:95], v[50:51], s[46:47] op_sel_hi:[1,0]
	v_pk_fma_f32 v[50:51], v[70:71], 0.5, v[72:73] op_sel_hi:[1,0,1] neg_lo:[1,0,0] neg_hi:[1,0,0]
	v_mul_f32_e32 v6, 0.5, v54
	v_pk_fma_f32 v[58:59], v[58:59], v[56:57], v[56:57] op_sel:[0,1,0] op_sel_hi:[1,0,1]
	v_mov_b32_e32 v70, v48
	v_mov_b32_e32 v71, v53
	v_mov_b32_e32 v56, v57
	v_mov_b32_e32 v57, v18
	v_sub_f32_e32 v12, v85, v119
	v_pk_mul_f32 v[56:57], v[70:71], v[56:57]
	v_pk_add_f32 v[70:71], v[6:7], v[58:59]
	v_mul_f32_e32 v12, 0.5, v12
	v_fma_f32 v71, v54, 0.5, -v58
	v_pk_add_f32 v[54:55], v[56:57], v[56:57] op_sel:[0,1] op_sel_hi:[0,1] neg_lo:[0,1] neg_hi:[0,1]
	v_pk_add_f32 v[56:57], v[12:13], v[54:55] op_sel_hi:[0,1] neg_hi:[0,1]
	v_pk_mul_f32 v[54:55], v[56:57], v[126:127]
	v_pk_mul_f32 v[56:57], v[56:57], v[124:125]
	v_pk_fma_f32 v[58:59], v[70:71], v[124:125], v[54:55] neg_lo:[0,0,1] neg_hi:[0,0,1]
	v_pk_fma_f32 v[54:55], v[70:71], v[124:125], v[54:55]
	v_pk_fma_f32 v[72:73], v[70:71], v[126:127], v[56:57]
	v_pk_fma_f32 v[56:57], v[70:71], v[126:127], v[56:57] neg_lo:[0,0,1] neg_hi:[0,0,1]
	v_pk_add_f32 v[70:71], v[58:59], v[54:55] op_sel:[0,1] op_sel_hi:[1,0]
	v_pk_add_f32 v[74:75], v[72:73], v[56:57] op_sel_hi:[0,1] neg_lo:[0,1] neg_hi:[0,1]
	v_pk_add_f32 v[54:55], v[58:59], v[54:55] op_sel_hi:[0,1] neg_lo:[0,1] neg_hi:[0,1]
	v_pk_add_f32 v[56:57], v[72:73], v[56:57] op_sel:[0,1] op_sel_hi:[1,0]
	v_mov_b32_e32 v71, v75
	v_mov_b32_e32 v57, v55
	v_pk_mul_f32 v[54:55], v[56:57], 0.5 op_sel_hi:[1,0]
	s_mov_b32 s66, s11
	v_pk_mul_f32 v[52:53], v[52:53], v[54:55] op_sel:[1,1] op_sel_hi:[1,0]
	s_mov_b32 s67, s8
	v_pk_fma_f32 v[56:57], v[48:49], v[54:55], v[52:53] op_sel_hi:[0,1,1]
	v_pk_fma_f32 v[48:49], v[48:49], v[54:55], v[52:53] op_sel_hi:[0,1,1] neg_hi:[0,0,1]
	s_nop 0
	v_pk_fma_f32 v[52:53], v[70:71], 0.5, v[56:57] op_sel_hi:[1,0,1] neg_lo:[0,0,1] neg_hi:[0,0,1]
	v_pk_fma_f32 v[84:85], v[70:71], 0.5, v[48:49] op_sel_hi:[1,0,1]
	s_mov_b32 s9, s11
	v_mov_b32_e32 v53, v85
	v_pk_mul_f32 v[80:81], v[52:53], s[46:47] op_sel_hi:[1,0]
	v_pk_mul_f32 v[118:119], v[82:83], s[66:67] op_sel_hi:[0,1]
	v_pk_add_f32 v[52:53], v[86:87], v[112:113]
	v_pk_add_f32 v[54:55], v[86:87], v[112:113] neg_lo:[0,1] neg_hi:[0,1]
	v_pk_fma_f32 v[58:59], v[4:5], s[8:9], v[118:119] op_sel_hi:[0,1,1] neg_lo:[0,0,1] neg_hi:[0,0,1]
	v_mul_f32_e32 v12, 0.5, v55
	v_pk_fma_f32 v[72:73], v[4:5], s[8:9], v[118:119] op_sel_hi:[0,1,1]
	v_mov_b32_e32 v55, v53
	v_mul_f32_e32 v6, 0.5, v52
	v_mov_b32_e32 v56, v58
	v_mov_b32_e32 v57, v73
	v_pk_mul_f32 v[52:53], v[54:55], s[44:45]
	v_pk_fma_f32 v[48:49], v[70:71], 0.5, v[48:49] op_sel_hi:[1,0,1] neg_lo:[1,0,0] neg_hi:[1,0,0]
	v_pk_mul_f32 v[54:55], v[56:57], v[52:53] op_sel:[0,1] op_sel_hi:[1,0]
	v_pk_mul_f32 v[52:53], v[56:57], v[52:53]
	v_pk_add_f32 v[54:55], v[54:55], v[54:55] op_sel:[0,1] op_sel_hi:[0,1]
	v_pk_add_f32 v[74:75], v[6:7], v[54:55] op_sel_hi:[0,1] neg_hi:[0,1]
	v_pk_add_f32 v[52:53], v[52:53], v[52:53] op_sel:[0,1] op_sel_hi:[0,1] neg_lo:[0,1] neg_hi:[0,1]
	v_pk_add_f32 v[54:55], v[12:13], v[52:53] op_sel_hi:[0,1] neg_hi:[0,1]
	v_pk_mul_f32 v[52:53], v[54:55], v[116:117]
	v_pk_mul_f32 v[54:55], v[54:55], v[114:115]
	v_pk_fma_f32 v[52:53], v[74:75], v[114:115], v[52:53]
	v_pk_fma_f32 v[54:55], v[74:75], v[116:117], v[54:55] neg_lo:[0,0,1] neg_hi:[0,0,1]
	v_pk_mov_b32 v[70:71], v[72:73], v[58:59] op_sel:[1,0]
	v_pk_add_f32 v[74:75], v[54:55], v[52:53] op_sel:[0,1] op_sel_hi:[1,0] neg_lo:[0,1]
	v_pk_add_f32 v[76:77], v[54:55], v[52:53] op_sel:[0,1] op_sel_hi:[1,0]
	v_pk_add_f32 v[52:53], v[52:53], v[54:55] op_sel:[1,0] op_sel_hi:[0,1] neg_lo:[0,1] neg_hi:[0,1]
	v_pk_mul_f32 v[74:75], v[74:75], 0.5 op_sel_hi:[1,0]
	v_mov_b32_e32 v77, v53
	v_mul_f32_e32 v6, v58, v74
	v_pk_fma_f32 v[112:113], v[56:57], v[74:75], v[6:7] op_sel_hi:[1,1,0] neg_lo:[1,0,0] neg_hi:[1,0,0]
	v_mul_f32_e32 v6, v58, v75
	v_pk_fma_f32 v[70:71], v[70:71], v[74:75], v[6:7] op_sel_hi:[1,1,0]
	v_pk_add_f32 v[54:55], v[34:35], v[110:111]
	v_mov_b32_e32 v112, v70
	v_pk_fma_f32 v[52:53], v[76:77], 0.5, v[70:71] op_sel_hi:[1,0,1] neg_lo:[0,0,1] neg_hi:[0,0,1]
	v_pk_fma_f32 v[86:87], v[76:77], 0.5, v[112:113] op_sel_hi:[1,0,1]
	v_sub_f32_e32 v12, v35, v111
	v_mov_b32_e32 v53, v87
	v_pk_mul_f32 v[78:79], v[52:53], s[46:47] op_sel_hi:[1,0]
	v_mul_f32_e32 v52, 0xbe47c5c2, v83
	v_mov_b32_e32 v53, v34
	v_pk_mov_b32 v[34:35], v[118:119], v[110:111] op_sel:[1,0]
	v_mul_f32_e32 v18, 0.5, v55
	v_pk_add_f32 v[34:35], v[52:53], v[34:35] neg_lo:[0,1] neg_hi:[0,1]
	v_mov_b32_e32 v71, v58
	v_pk_mul_f32 v[52:53], v[34:35], v[18:19]
	v_mov_b32_e32 v70, v34
	v_pk_fma_f32 v[56:57], v[56:57], v[52:53], v[52:53] op_sel:[0,1,0] op_sel_hi:[1,0,1]
	v_mov_b32_e32 v52, v53
	v_mov_b32_e32 v53, v18
	v_mul_f32_e32 v6, 0.5, v54
	v_pk_mul_f32 v[52:53], v[70:71], v[52:53]
	v_cvt_f32_f16_e32 v70, v46
	v_cvt_f32_f16_e32 v71, v47
	v_cvt_f32_f16_sdwa v47, v47 dst_sel:DWORD dst_unused:UNUSED_PAD src0_sel:WORD_1
	v_cvt_f32_f16_sdwa v46, v46 dst_sel:DWORD dst_unused:UNUSED_PAD src0_sel:WORD_1
	v_pk_fma_f32 v[74:75], v[76:77], 0.5, v[112:113] op_sel_hi:[1,0,1] neg_lo:[1,0,0] neg_hi:[1,0,0]
	v_mul_f32_e32 v12, 0.5, v12
	v_pk_add_f32 v[76:77], v[6:7], v[56:57]
	v_pk_add_f32 v[52:53], v[52:53], v[52:53] op_sel:[0,1] op_sel_hi:[0,1] neg_lo:[0,1] neg_hi:[0,1]
	v_fma_f32 v77, v54, 0.5, -v56
	v_pk_add_f32 v[54:55], v[12:13], v[52:53] op_sel_hi:[0,1] neg_hi:[0,1]
	v_pk_mul_f32 v[52:53], v[54:55], v[46:47]
	v_pk_mul_f32 v[54:55], v[54:55], v[70:71]
	v_pk_fma_f32 v[56:57], v[76:77], v[70:71], v[52:53] neg_lo:[0,0,1] neg_hi:[0,0,1]
	v_pk_fma_f32 v[52:53], v[76:77], v[70:71], v[52:53]
	v_pk_fma_f32 v[70:71], v[76:77], v[46:47], v[54:55]
	v_pk_fma_f32 v[46:47], v[76:77], v[46:47], v[54:55] neg_lo:[0,0,1] neg_hi:[0,0,1]
	v_pk_add_f32 v[54:55], v[56:57], v[52:53] op_sel:[0,1] op_sel_hi:[1,0]
	v_pk_add_f32 v[76:77], v[70:71], v[46:47] op_sel_hi:[0,1] neg_lo:[0,1] neg_hi:[0,1]
	v_pk_add_f32 v[52:53], v[56:57], v[52:53] op_sel_hi:[0,1] neg_lo:[0,1] neg_hi:[0,1]
	v_pk_add_f32 v[46:47], v[70:71], v[46:47] op_sel:[0,1] op_sel_hi:[1,0]
	v_mov_b32_e32 v55, v77
	v_mov_b32_e32 v47, v53
	v_pk_mul_f32 v[46:47], v[46:47], 0.5 op_sel_hi:[1,0]
	s_mov_b32 s25, s27
	v_pk_mul_f32 v[52:53], v[58:59], v[46:47] op_sel:[0,1] op_sel_hi:[0,0]
	v_pk_fma_f32 v[56:57], v[34:35], v[46:47], v[52:53] op_sel_hi:[0,1,1]
	v_pk_fma_f32 v[46:47], v[34:35], v[46:47], v[52:53] op_sel_hi:[0,1,1] neg_hi:[0,0,1]
	s_nop 0
	v_pk_fma_f32 v[52:53], v[54:55], 0.5, v[56:57] op_sel_hi:[1,0,1] neg_lo:[0,0,1] neg_hi:[0,0,1]
	v_pk_fma_f32 v[34:35], v[54:55], 0.5, v[46:47] op_sel_hi:[1,0,1]
	s_mov_b32 s66, s27
	v_mov_b32_e32 v53, v35
	v_pk_mul_f32 v[136:137], v[52:53], s[46:47] op_sel_hi:[1,0]
	v_pk_fma_f32 v[52:53], v[54:55], 0.5, v[46:47] op_sel_hi:[1,0,1] neg_lo:[1,0,0] neg_hi:[1,0,0]
	s_mov_b32 s67, s24
	v_pk_mul_f32 v[46:47], v[82:83], s[24:25] op_sel_hi:[0,1]
	v_pk_add_f32 v[54:55], v[108:109], v[40:41]
	v_pk_add_f32 v[40:41], v[40:41], v[108:109] neg_lo:[0,1] neg_hi:[0,1]
	v_pk_fma_f32 v[108:109], v[4:5], s[66:67], v[46:47] op_sel_hi:[0,1,1] neg_lo:[0,0,1] neg_hi:[0,0,1]
	v_mul_f32_e32 v12, 0.5, v41
	v_pk_fma_f32 v[70:71], v[4:5], s[66:67], v[46:47] op_sel_hi:[0,1,1]
	v_mov_b32_e32 v41, v55
	v_mov_b32_e32 v56, v108
	v_mov_b32_e32 v57, v71
	v_pk_mul_f32 v[40:41], v[40:41], s[44:45]
	v_mul_f32_e32 v6, 0.5, v54
	v_pk_mul_f32 v[54:55], v[56:57], v[40:41] op_sel:[0,1] op_sel_hi:[1,0]
	v_cvt_f32_f16_sdwa v76, v38 dst_sel:DWORD dst_unused:UNUSED_PAD src0_sel:WORD_1
	v_cvt_f32_f16_e32 v77, v39
	v_cvt_f32_f16_sdwa v39, v39 dst_sel:DWORD dst_unused:UNUSED_PAD src0_sel:WORD_1
	v_cvt_f32_f16_e32 v38, v38
	v_pk_mul_f32 v[40:41], v[56:57], v[40:41]
	v_pk_add_f32 v[54:55], v[54:55], v[54:55] op_sel:[0,1] op_sel_hi:[0,1]
	v_pk_add_f32 v[112:113], v[6:7], v[54:55] op_sel_hi:[0,1] neg_hi:[0,1]
	s_nop 0
	v_pk_add_f32 v[40:41], v[40:41], v[40:41] op_sel:[0,1] op_sel_hi:[0,1] neg_lo:[0,1] neg_hi:[0,1]
	v_pk_add_f32 v[54:55], v[12:13], v[40:41] op_sel_hi:[0,1] neg_hi:[0,1]
	v_pk_mul_f32 v[40:41], v[54:55], v[38:39]
	v_pk_mul_f32 v[54:55], v[54:55], v[76:77]
	v_pk_fma_f32 v[40:41], v[112:113], v[76:77], v[40:41]
	v_pk_fma_f32 v[38:39], v[112:113], v[38:39], v[54:55] neg_lo:[0,0,1] neg_hi:[0,0,1]
	v_pk_mov_b32 v[110:111], v[70:71], v[108:109] op_sel:[1,0]
	v_pk_add_f32 v[54:55], v[38:39], v[40:41] op_sel:[0,1] op_sel_hi:[1,0] neg_lo:[0,1]
	v_pk_add_f32 v[76:77], v[38:39], v[40:41] op_sel:[0,1] op_sel_hi:[1,0]
	v_pk_add_f32 v[38:39], v[40:41], v[38:39] op_sel:[1,0] op_sel_hi:[0,1] neg_lo:[0,1] neg_hi:[0,1]
	v_pk_mul_f32 v[54:55], v[54:55], 0.5 op_sel_hi:[1,0]
	v_mov_b32_e32 v77, v39
	v_mul_f32_e32 v4, v108, v54
	v_pk_fma_f32 v[112:113], v[56:57], v[54:55], v[4:5] op_sel_hi:[1,1,0] neg_lo:[1,0,0] neg_hi:[1,0,0]
	v_mul_f32_e32 v4, v108, v55
	v_pk_fma_f32 v[54:55], v[110:111], v[54:55], v[4:5] op_sel_hi:[1,1,0]
	v_sub_f32_e32 v6, v45, v105
	v_mov_b32_e32 v112, v54
	v_pk_fma_f32 v[40:41], v[76:77], 0.5, v[54:55] op_sel_hi:[1,0,1] neg_lo:[0,0,1] neg_hi:[0,0,1]
	v_pk_fma_f32 v[38:39], v[76:77], 0.5, v[112:113] op_sel_hi:[1,0,1]
	v_pk_add_f32 v[54:55], v[104:105], v[44:45]
	v_mov_b32_e32 v41, v39
	v_pk_mul_f32 v[130:131], v[40:41], s[46:47] op_sel_hi:[1,0]
	v_mul_f32_e32 v40, 0xbf54db31, v83
	v_mov_b32_e32 v41, v44
	v_pk_mov_b32 v[44:45], v[46:47], v[104:105] op_sel:[1,0]
	v_mul_f32_e32 v18, 0.5, v55
	v_pk_add_f32 v[40:41], v[40:41], v[44:45] neg_lo:[0,1] neg_hi:[0,1]
	v_mov_b32_e32 v105, v108
	v_pk_mul_f32 v[44:45], v[40:41], v[18:19]
	v_mov_b32_e32 v104, v40
	v_pk_fma_f32 v[56:57], v[56:57], v[44:45], v[44:45] op_sel:[0,1,0] op_sel_hi:[1,0,1]
	v_mov_b32_e32 v44, v45
	v_mov_b32_e32 v45, v18
	v_mul_f32_e32 v4, 0.5, v54
	v_pk_mul_f32 v[44:45], v[104:105], v[44:45]
	v_cvt_f32_f16_e32 v104, v26
	v_cvt_f32_f16_e32 v105, v27
	v_cvt_f32_f16_sdwa v27, v27 dst_sel:DWORD dst_unused:UNUSED_PAD src0_sel:WORD_1
	v_cvt_f32_f16_sdwa v26, v26 dst_sel:DWORD dst_unused:UNUSED_PAD src0_sel:WORD_1
	v_mul_f32_e32 v6, 0.5, v6
	v_pk_add_f32 v[110:111], v[4:5], v[56:57]
	v_pk_add_f32 v[44:45], v[44:45], v[44:45] op_sel:[0,1] op_sel_hi:[0,1] neg_lo:[0,1] neg_hi:[0,1]
	v_fma_f32 v111, v54, 0.5, -v56
	v_pk_add_f32 v[54:55], v[6:7], v[44:45] op_sel_hi:[0,1] neg_hi:[0,1]
	v_pk_mul_f32 v[44:45], v[54:55], v[26:27]
	v_pk_mul_f32 v[54:55], v[54:55], v[104:105]
	v_pk_fma_f32 v[56:57], v[110:111], v[104:105], v[44:45] neg_lo:[0,0,1] neg_hi:[0,0,1]
	v_pk_fma_f32 v[44:45], v[110:111], v[104:105], v[44:45]
	v_pk_fma_f32 v[104:105], v[110:111], v[26:27], v[54:55]
	v_pk_fma_f32 v[26:27], v[110:111], v[26:27], v[54:55] neg_lo:[0,0,1] neg_hi:[0,0,1]
	v_pk_add_f32 v[54:55], v[56:57], v[44:45] op_sel:[0,1] op_sel_hi:[1,0]
	v_pk_add_f32 v[110:111], v[104:105], v[26:27] op_sel_hi:[0,1] neg_lo:[0,1] neg_hi:[0,1]
	v_pk_add_f32 v[44:45], v[56:57], v[44:45] op_sel_hi:[0,1] neg_lo:[0,1] neg_hi:[0,1]
	v_pk_add_f32 v[26:27], v[104:105], v[26:27] op_sel:[0,1] op_sel_hi:[1,0]
	v_mov_b32_e32 v55, v111
	v_mov_b32_e32 v27, v45
	v_pk_mul_f32 v[26:27], v[26:27], 0.5 op_sel_hi:[1,0]
	v_mov_b32_e32 v47, v102
	v_pk_mul_f32 v[44:45], v[108:109], v[26:27] op_sel:[0,1] op_sel_hi:[0,0]
	v_pk_fma_f32 v[56:57], v[40:41], v[26:27], v[44:45] op_sel_hi:[0,1,1]
	v_pk_fma_f32 v[40:41], v[40:41], v[26:27], v[44:45] op_sel_hi:[0,1,1] neg_hi:[0,0,1]
	v_pk_fma_f32 v[44:45], v[54:55], 0.5, v[56:57] op_sel_hi:[1,0,1] neg_lo:[0,0,1] neg_hi:[0,0,1]
	v_pk_fma_f32 v[26:27], v[54:55], 0.5, v[40:41] op_sel_hi:[1,0,1]
	v_pk_fma_f32 v[56:57], v[54:55], 0.5, v[40:41] op_sel_hi:[1,0,1] neg_lo:[1,0,0] neg_hi:[1,0,0]
	v_pk_add_f32 v[40:41], v[106:107], v[42:43]
	v_pk_add_f32 v[42:43], v[42:43], v[106:107] neg_lo:[0,1] neg_hi:[0,1]
	v_mov_b32_e32 v45, v27
	v_mul_f32_e32 v6, 0.5, v43
	v_mov_b32_e32 v43, v41
	v_pk_mul_f32 v[120:121], v[44:45], s[46:47] op_sel_hi:[1,0]
	v_mul_f32_e32 v4, 0.5, v40
	v_pk_mov_b32 v[44:45], v[108:109], v[70:71] op_sel:[1,0]
	v_pk_mul_f32 v[40:41], v[42:43], s[44:45]
	v_cvt_f32_f16_sdwa v54, v20 dst_sel:DWORD dst_unused:UNUSED_PAD src0_sel:WORD_1
	v_pk_mul_f32 v[42:43], v[44:45], v[40:41] op_sel:[0,1] op_sel_hi:[1,0]
	v_cvt_f32_f16_e32 v55, v21
	v_cvt_f32_f16_sdwa v21, v21 dst_sel:DWORD dst_unused:UNUSED_PAD src0_sel:WORD_1
	v_cvt_f32_f16_e32 v20, v20
	v_pk_mul_f32 v[40:41], v[44:45], v[40:41]
	v_pk_add_f32 v[42:43], v[42:43], v[42:43] op_sel:[0,1] op_sel_hi:[0,1]
	v_pk_add_f32 v[104:105], v[4:5], v[42:43] op_sel_hi:[0,1] neg_hi:[0,1]
	s_nop 0
	v_pk_add_f32 v[40:41], v[40:41], v[40:41] op_sel:[0,1] op_sel_hi:[0,1] neg_lo:[0,1] neg_hi:[0,1]
	v_pk_add_f32 v[42:43], v[6:7], v[40:41] op_sel_hi:[0,1] neg_hi:[0,1]
	v_pk_mul_f32 v[40:41], v[42:43], v[20:21]
	v_pk_mul_f32 v[42:43], v[42:43], v[54:55]
	v_pk_fma_f32 v[40:41], v[104:105], v[54:55], v[40:41]
	v_pk_fma_f32 v[20:21], v[104:105], v[20:21], v[42:43] neg_lo:[0,0,1] neg_hi:[0,0,1]
	v_mov_b32_e32 v71, v109
	v_pk_add_f32 v[42:43], v[20:21], v[40:41] op_sel:[0,1] op_sel_hi:[1,0] neg_lo:[0,1]
	v_pk_add_f32 v[54:55], v[20:21], v[40:41] op_sel:[0,1] op_sel_hi:[1,0]
	v_pk_add_f32 v[20:21], v[40:41], v[20:21] op_sel:[1,0] op_sel_hi:[0,1] neg_lo:[0,1] neg_hi:[0,1]
	v_pk_mul_f32 v[42:43], v[42:43], 0.5 op_sel_hi:[1,0]
	v_mov_b32_e32 v55, v21
	v_mul_f32_e32 v4, v109, v42
	v_pk_fma_f32 v[104:105], v[44:45], v[42:43], v[4:5] op_sel_hi:[1,1,0] neg_lo:[1,0,0] neg_hi:[1,0,0]
	v_mul_f32_e32 v4, v109, v43
	v_pk_fma_f32 v[42:43], v[70:71], v[42:43], v[4:5] op_sel_hi:[1,1,0]
	v_sub_f32_e32 v6, v23, v103
	v_mov_b32_e32 v104, v42
	v_pk_fma_f32 v[40:41], v[54:55], 0.5, v[42:43] op_sel_hi:[1,0,1] neg_lo:[0,0,1] neg_hi:[0,0,1]
	v_pk_fma_f32 v[20:21], v[54:55], 0.5, v[104:105] op_sel_hi:[1,0,1]
	v_pk_add_f32 v[42:43], v[102:103], v[22:23]
	v_mov_b32_e32 v41, v21
	v_pk_mul_f32 v[128:129], v[40:41], s[46:47] op_sel_hi:[1,0]
	v_mul_f32_e32 v40, 0xbf0e39da, v83
	v_mov_b32_e32 v41, v22
	v_mul_f32_e32 v18, 0.5, v43
	v_pk_add_f32 v[22:23], v[40:41], v[46:47] neg_lo:[0,1] neg_hi:[0,1]
	v_mov_b32_e32 v47, v109
	v_pk_mul_f32 v[40:41], v[22:23], v[18:19]
	v_mov_b32_e32 v46, v22
	v_pk_fma_f32 v[44:45], v[44:45], v[40:41], v[40:41] op_sel:[0,1,0] op_sel_hi:[1,0,1]
	v_mov_b32_e32 v40, v41
	v_mov_b32_e32 v41, v18
	v_mul_f32_e32 v4, 0.5, v42
	v_pk_mul_f32 v[40:41], v[46:47], v[40:41]
	v_cvt_f32_f16_e32 v46, v10
	v_cvt_f32_f16_e32 v47, v11
	v_cvt_f32_f16_sdwa v11, v11 dst_sel:DWORD dst_unused:UNUSED_PAD src0_sel:WORD_1
	v_cvt_f32_f16_sdwa v10, v10 dst_sel:DWORD dst_unused:UNUSED_PAD src0_sel:WORD_1
	v_pk_fma_f32 v[70:71], v[54:55], 0.5, v[104:105] op_sel_hi:[1,0,1] neg_lo:[1,0,0] neg_hi:[1,0,0]
	v_mul_f32_e32 v6, 0.5, v6
	v_pk_add_f32 v[54:55], v[4:5], v[44:45]
	v_pk_add_f32 v[40:41], v[40:41], v[40:41] op_sel:[0,1] op_sel_hi:[0,1] neg_lo:[0,1] neg_hi:[0,1]
	v_fma_f32 v55, v42, 0.5, -v44
	v_pk_add_f32 v[42:43], v[6:7], v[40:41] op_sel_hi:[0,1] neg_hi:[0,1]
	v_pk_mul_f32 v[40:41], v[42:43], v[10:11]
	v_pk_mul_f32 v[42:43], v[42:43], v[46:47]
	v_pk_fma_f32 v[44:45], v[54:55], v[46:47], v[40:41] neg_lo:[0,0,1] neg_hi:[0,0,1]
	v_pk_fma_f32 v[40:41], v[54:55], v[46:47], v[40:41]
	v_pk_fma_f32 v[46:47], v[54:55], v[10:11], v[42:43]
	v_pk_fma_f32 v[10:11], v[54:55], v[10:11], v[42:43] neg_lo:[0,0,1] neg_hi:[0,0,1]
	v_pk_add_f32 v[42:43], v[44:45], v[40:41] op_sel:[0,1] op_sel_hi:[1,0]
	v_pk_add_f32 v[54:55], v[46:47], v[10:11] op_sel_hi:[0,1] neg_lo:[0,1] neg_hi:[0,1]
	v_pk_add_f32 v[40:41], v[44:45], v[40:41] op_sel_hi:[0,1] neg_lo:[0,1] neg_hi:[0,1]
	v_pk_add_f32 v[10:11], v[46:47], v[10:11] op_sel:[0,1] op_sel_hi:[1,0]
	v_mov_b32_e32 v43, v55
	v_mov_b32_e32 v11, v41
	v_pk_mul_f32 v[10:11], v[10:11], 0.5 op_sel_hi:[1,0]
	v_mov_b32_e32 v119, v98
	v_pk_mul_f32 v[40:41], v[108:109], v[10:11] op_sel:[1,1] op_sel_hi:[1,0]
	v_pk_fma_f32 v[76:77], v[76:77], 0.5, v[112:113] op_sel_hi:[1,0,1] neg_lo:[1,0,0] neg_hi:[1,0,0]
	v_pk_fma_f32 v[44:45], v[22:23], v[10:11], v[40:41] op_sel_hi:[0,1,1]
	v_pk_fma_f32 v[10:11], v[22:23], v[10:11], v[40:41] op_sel_hi:[0,1,1] neg_hi:[0,0,1]
	v_pk_fma_f32 v[22:23], v[42:43], 0.5, v[44:45] op_sel_hi:[1,0,1] neg_lo:[0,0,1] neg_hi:[0,0,1]
	v_pk_fma_f32 v[40:41], v[42:43], 0.5, v[10:11] op_sel_hi:[1,0,1]
	v_pk_fma_f32 v[54:55], v[42:43], 0.5, v[10:11] op_sel_hi:[1,0,1] neg_lo:[1,0,0] neg_hi:[1,0,0]
	v_pk_add_f32 v[10:11], v[100:101], v[14:15]
	v_pk_add_f32 v[14:15], v[14:15], v[100:101] neg_lo:[0,1] neg_hi:[0,1]
	v_mov_b32_e32 v23, v41
	v_mul_f32_e32 v6, 0.5, v15
	v_mov_b32_e32 v15, v11
	v_pk_mul_f32 v[150:151], v[22:23], s[46:47] op_sel_hi:[1,0]
	v_mul_f32_e32 v4, 0.5, v10
	v_pk_mov_b32 v[22:23], v[58:59], v[72:73] op_sel:[1,0]
	v_pk_mul_f32 v[10:11], v[14:15], s[44:45]
	v_cvt_f32_f16_sdwa v42, v8 dst_sel:DWORD dst_unused:UNUSED_PAD src0_sel:WORD_1
	v_pk_mul_f32 v[14:15], v[22:23], v[10:11] op_sel:[0,1] op_sel_hi:[1,0]
	v_cvt_f32_f16_e32 v43, v9
	v_cvt_f32_f16_sdwa v9, v9 dst_sel:DWORD dst_unused:UNUSED_PAD src0_sel:WORD_1
	v_cvt_f32_f16_e32 v8, v8
	v_pk_mul_f32 v[10:11], v[22:23], v[10:11]
	v_pk_add_f32 v[14:15], v[14:15], v[14:15] op_sel:[0,1] op_sel_hi:[0,1]
	v_pk_add_f32 v[44:45], v[4:5], v[14:15] op_sel_hi:[0,1] neg_hi:[0,1]
	s_nop 0
	v_pk_add_f32 v[10:11], v[10:11], v[10:11] op_sel:[0,1] op_sel_hi:[0,1] neg_lo:[0,1] neg_hi:[0,1]
	v_pk_add_f32 v[14:15], v[6:7], v[10:11] op_sel_hi:[0,1] neg_hi:[0,1]
	v_pk_mul_f32 v[10:11], v[14:15], v[8:9]
	v_pk_mul_f32 v[14:15], v[14:15], v[42:43]
	v_pk_fma_f32 v[10:11], v[44:45], v[42:43], v[10:11]
	v_pk_fma_f32 v[8:9], v[44:45], v[8:9], v[14:15] neg_lo:[0,0,1] neg_hi:[0,0,1]
	v_mov_b32_e32 v73, v59
	v_pk_add_f32 v[14:15], v[8:9], v[10:11] op_sel:[0,1] op_sel_hi:[1,0] neg_lo:[0,1]
	v_pk_add_f32 v[42:43], v[8:9], v[10:11] op_sel:[0,1] op_sel_hi:[1,0]
	v_pk_add_f32 v[8:9], v[10:11], v[8:9] op_sel:[1,0] op_sel_hi:[0,1] neg_lo:[0,1] neg_hi:[0,1]
	v_pk_mul_f32 v[14:15], v[14:15], 0.5 op_sel_hi:[1,0]
	v_mov_b32_e32 v43, v9
	v_mul_f32_e32 v4, v59, v14
	v_pk_fma_f32 v[44:45], v[22:23], v[14:15], v[4:5] op_sel_hi:[1,1,0] neg_lo:[1,0,0] neg_hi:[1,0,0]
	v_mul_f32_e32 v4, v59, v15
	v_pk_fma_f32 v[14:15], v[72:73], v[14:15], v[4:5] op_sel_hi:[1,1,0]
	v_sub_f32_e32 v6, v37, v99
	v_mov_b32_e32 v44, v14
	v_pk_fma_f32 v[8:9], v[42:43], 0.5, v[14:15] op_sel_hi:[1,0,1] neg_lo:[0,0,1] neg_hi:[0,0,1]
	v_pk_fma_f32 v[10:11], v[42:43], 0.5, v[44:45] op_sel_hi:[1,0,1]
	v_pk_add_f32 v[14:15], v[98:99], v[36:37]
	v_mov_b32_e32 v9, v11
	v_pk_mul_f32 v[168:169], v[8:9], s[46:47] op_sel_hi:[1,0]
	v_mul_f32_e32 v8, 0xbf7b14be, v83
	v_mov_b32_e32 v9, v36
	v_mul_f32_e32 v18, 0.5, v15
	v_pk_add_f32 v[8:9], v[8:9], v[118:119] neg_lo:[0,1] neg_hi:[0,1]
	v_pk_fma_f32 v[72:73], v[42:43], 0.5, v[44:45] op_sel_hi:[1,0,1] neg_lo:[1,0,0] neg_hi:[1,0,0]
	v_pk_mul_f32 v[36:37], v[8:9], v[18:19]
	v_mov_b32_e32 v42, v8
	v_pk_fma_f32 v[22:23], v[22:23], v[36:37], v[36:37] op_sel:[0,1,0] op_sel_hi:[1,0,1]
	v_mov_b32_e32 v43, v59
	v_mov_b32_e32 v36, v37
	v_mov_b32_e32 v37, v18
	v_mul_f32_e32 v4, 0.5, v14
	v_pk_mul_f32 v[36:37], v[42:43], v[36:37]
	v_cvt_f32_f16_e32 v44, v2
	v_cvt_f32_f16_e32 v45, v3
	v_cvt_f32_f16_sdwa v3, v3 dst_sel:DWORD dst_unused:UNUSED_PAD src0_sel:WORD_1
	v_cvt_f32_f16_sdwa v2, v2 dst_sel:DWORD dst_unused:UNUSED_PAD src0_sel:WORD_1
	v_mul_f32_e32 v6, 0.5, v6
	v_pk_add_f32 v[46:47], v[4:5], v[22:23]
	v_fma_f32 v4, v14, 0.5, -v22
	v_pk_add_f32 v[22:23], v[36:37], v[36:37] op_sel:[0,1] op_sel_hi:[0,1] neg_lo:[0,1] neg_hi:[0,1]
	v_pk_add_f32 v[36:37], v[6:7], v[22:23] op_sel_hi:[0,1] neg_hi:[0,1]
	v_mov_b32_e32 v14, v46
	v_mov_b32_e32 v15, v4
	v_pk_mul_f32 v[22:23], v[4:5], v[44:45] op_sel_hi:[0,1]
	v_pk_mul_f32 v[82:83], v[36:37], v[2:3]
	v_pk_mul_f32 v[46:47], v[46:47], v[2:3]
	v_pk_mul_f32 v[36:37], v[36:37], v[44:45]
	v_pk_fma_f32 v[98:99], v[14:15], v[44:45], v[82:83] neg_lo:[0,0,1] neg_hi:[0,0,1]
	v_pk_fma_f32 v[2:3], v[14:15], v[2:3], v[36:37] neg_lo:[0,0,1] neg_hi:[0,0,1]
	v_add_f32_e32 v4, v23, v83
	v_add_f32_e32 v6, v46, v36
	v_pk_add_f32 v[22:23], v[6:7], v[2:3] op_sel_hi:[0,1] neg_lo:[0,1] neg_hi:[0,1]
	v_pk_add_f32 v[36:37], v[98:99], v[4:5] op_sel_hi:[1,0] neg_lo:[0,1] neg_hi:[0,1]
	v_pk_add_f32 v[2:3], v[6:7], v[2:3] op_sel_hi:[0,1]
	v_mov_b32_e32 v37, v3
	v_pk_mul_f32 v[2:3], v[36:37], 0.5 op_sel_hi:[1,0]
	v_pk_add_f32 v[14:15], v[98:99], v[4:5] op_sel_hi:[1,0]
	v_mul_f32_e32 v4, v59, v3
	v_pk_fma_f32 v[36:37], v[42:43], v[2:3], v[4:5] op_sel_hi:[1,1,0] neg_lo:[0,0,1] neg_hi:[0,0,1]
	v_pk_mov_b32 v[42:43], v[58:59], v[8:9] op_sel:[1,0]
	v_mul_f32_e32 v4, v8, v3
	v_pk_fma_f32 v[2:3], v[42:43], v[2:3], v[4:5] op_sel_hi:[1,1,0]
	v_mov_b32_e32 v15, v23
	v_pk_fma_f32 v[8:9], v[14:15], 0.5, v[2:3] op_sel_hi:[1,0,1] neg_lo:[0,0,1] neg_hi:[0,0,1]
	v_pk_fma_f32 v[42:43], v[14:15], 0.5, v[36:37] op_sel_hi:[1,0,0]
	v_pk_fma_f32 v[2:3], v[14:15], 0.5, v[2:3] op_sel_hi:[1,0,1]
	v_mov_b32_e32 v9, v43
	v_pk_fma_f32 v[58:59], v[22:23], 0.5, v[36:37] op_sel_hi:[1,0,0] neg_lo:[1,0,0] neg_hi:[1,0,0]
	v_pk_mul_f32 v[144:145], v[8:9], s[46:47] op_sel_hi:[1,0]
	v_mov_b32_e32 v58, v2
	v_mov_b32_e32 v72, v10
	v_mov_b32_e32 v54, v40
	v_mov_b32_e32 v70, v20
	v_mov_b32_e32 v56, v26
	v_mov_b32_e32 v76, v38
	v_mov_b32_e32 v52, v34
	v_mov_b32_e32 v74, v86
	v_mov_b32_e32 v48, v84
	v_mov_b32_e32 v50, v60
	v_mov_b32_e32 v28, v66
	v_mov_b32_e32 v32, v96
	v_mov_b32_e32 v12, v88
	v_mov_b32_e32 v16, v92
	v_mov_b32_e32 v4, v138
	v_mov_b32_e32 v6, v122

.LBB0_546:
	s_or_b64 exec, exec, s[0:1]
	v_mov_b32_e32 v25, v210
	s_mov_b32 s62, s37
	v_and_b32_e32 v28, 0xff, v25
	v_lshlrev_b32_e32 v34, 5, v25
	v_cvt_f32_ubyte0_e32 v25, v25
	v_mul_f32_e32 v25, 0x39000000, v25
	v_sin_f32_e32 v43, v25
	v_cos_f32_e32 v42, v25
	v_and_or_b32 v28, v34, s33, v28
	v_ashrrev_i32_e32 v34, 5, v28
	s_nop 0
	s_nop 0
	v_pk_mul_f32 v[46:47], v[42:43], v[42:43] op_sel:[1,1] op_sel_hi:[0,1] neg_lo:[0,1]
	v_pk_fma_f32 v[46:47], v[42:43], v[42:43], v[46:47] op_sel_hi:[1,0,1]
	v_lshlrev_b32_e32 v28, 3, v28
	v_pk_mul_f32 v[52:53], v[46:47], v[46:47] op_sel:[1,1] op_sel_hi:[0,1] neg_lo:[0,1]
	v_pk_fma_f32 v[52:53], v[46:47], v[46:47], v[52:53] op_sel_hi:[1,0,1]
	v_lshlrev_b32_e32 v34, 3, v34
	v_pk_mul_f32 v[70:71], v[52:53], v[52:53] op_sel:[1,1] op_sel_hi:[0,1] neg_lo:[0,1]
	v_pk_fma_f32 v[70:71], v[52:53], v[52:53], v[70:71] op_sel_hi:[1,0,1]
	v_pk_mul_f32 v[48:49], v[42:43], v[46:47] op_sel:[1,1] op_sel_hi:[1,0] neg_lo:[1,0]
	v_pk_mul_f32 v[86:87], v[52:53], v[70:71] op_sel:[1,1] op_sel_hi:[1,0] neg_lo:[1,0]
	v_add3_u32 v25, 0, v28, v34
	v_pk_fma_f32 v[86:87], v[52:53], v[70:71], v[86:87] op_sel_hi:[0,1,1]
	v_pk_mul_f32 v[102:103], v[52:53], v[86:87] op_sel:[1,1] op_sel_hi:[1,0] neg_lo:[1,0]
	v_pk_fma_f32 v[48:49], v[42:43], v[46:47], v[48:49] op_sel_hi:[0,1,1]
	v_pk_fma_f32 v[102:103], v[52:53], v[86:87], v[102:103] op_sel_hi:[0,1,1]
	v_pk_mul_f32 v[118:119], v[102:103], v[52:53] op_sel:[1,1] op_sel_hi:[0,1] neg_lo:[0,1]
	v_pk_fma_f32 v[118:119], v[52:53], v[102:103], v[118:119] op_sel_hi:[0,1,1]
	v_pk_mul_f32 v[134:135], v[118:119], v[52:53] op_sel:[1,1] op_sel_hi:[0,1] neg_lo:[0,1]
	v_pk_fma_f32 v[134:135], v[52:53], v[118:119], v[134:135] op_sel_hi:[0,1,1]
	v_pk_mul_f32 v[152:153], v[52:53], v[134:135] op_sel:[1,1] op_sel_hi:[1,0] neg_lo:[1,0]
	v_pk_mul_f32 v[58:59], v[42:43], v[52:53] op_sel:[1,1] op_sel_hi:[1,0] neg_lo:[1,0]
	v_pk_fma_f32 v[152:153], v[52:53], v[134:135], v[152:153] op_sel_hi:[0,1,1]
	v_pk_mul_f32 v[74:75], v[42:43], v[70:71] op_sel:[1,1] op_sel_hi:[1,0] neg_lo:[1,0]
	v_pk_mul_f32 v[90:91], v[42:43], v[86:87] op_sel:[1,1] op_sel_hi:[1,0] neg_lo:[1,0]
	v_pk_mul_f32 v[106:107], v[42:43], v[102:103] op_sel:[1,1] op_sel_hi:[1,0] neg_lo:[1,0]
	v_pk_mul_f32 v[122:123], v[42:43], v[118:119] op_sel:[1,1] op_sel_hi:[1,0] neg_lo:[1,0]
	v_pk_mul_f32 v[138:139], v[42:43], v[134:135] op_sel:[1,1] op_sel_hi:[1,0] neg_lo:[1,0]
	v_pk_mul_f32 v[156:157], v[42:43], v[152:153] op_sel:[1,1] op_sel_hi:[1,0] neg_lo:[1,0]
	ds_read_b64 v[168:169], v25
	ds_read_b64 v[170:171], v25 offset:2112
	ds_read_b64 v[172:173], v25 offset:4224
	ds_read_b64 v[174:175], v25 offset:6336
	ds_read_b64 v[176:177], v25 offset:8448
	ds_read_b64 v[178:179], v25 offset:10560
	ds_read_b64 v[180:181], v25 offset:12672
	ds_read_b64 v[182:183], v25 offset:14784
	ds_read_b64 v[184:185], v25 offset:16896
	ds_read_b64 v[186:187], v25 offset:19008
	ds_read_b64 v[188:189], v25 offset:21120
	ds_read_b64 v[190:191], v25 offset:23232
	ds_read_b64 v[192:193], v25 offset:25344
	ds_read_b64 v[194:195], v25 offset:27456
	ds_read_b64 v[196:197], v25 offset:29568
	ds_read_b64 v[198:199], v25 offset:31680
	ds_read_b64 v[212:213], v25 offset:33792
	ds_read_b64 v[214:215], v25 offset:35904
	ds_read_b64 v[216:217], v25 offset:38016
	ds_read_b64 v[218:219], v25 offset:40128
	ds_read_b64 v[220:221], v25 offset:42240
	ds_read_b64 v[222:223], v25 offset:44352
	ds_read_b64 v[224:225], v25 offset:46464
	ds_read_b64 v[226:227], v25 offset:48576
	ds_read_b64 v[228:229], v25 offset:50688
	ds_read_b64 v[230:231], v25 offset:52800
	ds_read_b64 v[232:233], v25 offset:54912
	ds_read_b64 v[234:235], v25 offset:57024
	ds_read_b64 v[236:237], v25 offset:59136
	ds_read_b64 v[238:239], v25 offset:61248
	ds_read_b64 v[240:241], v25 offset:63360
	ds_read_b64 v[242:243], v25 offset:65472
	s_waitcnt lgkmcnt(14)
	v_pk_mul_f32 v[44:45], v[42:43], v[212:213] op_sel:[1,1] op_sel_hi:[1,0] neg_lo:[1,0]
	v_pk_fma_f32 v[58:59], v[42:43], v[52:53], v[58:59] op_sel_hi:[0,1,1]
	v_pk_mul_f32 v[62:63], v[46:47], v[52:53] op_sel:[1,1] op_sel_hi:[1,0] neg_lo:[1,0]
	v_pk_mul_f32 v[66:67], v[52:53], v[48:49] op_sel:[1,1] op_sel_hi:[0,1] neg_lo:[0,1]
	v_pk_fma_f32 v[74:75], v[42:43], v[70:71], v[74:75] op_sel_hi:[0,1,1]
	v_pk_mul_f32 v[78:79], v[46:47], v[70:71] op_sel:[1,1] op_sel_hi:[1,0] neg_lo:[1,0]
	v_pk_fma_f32 v[90:91], v[42:43], v[86:87], v[90:91] op_sel_hi:[0,1,1]
	v_pk_mul_f32 v[94:95], v[46:47], v[86:87] op_sel:[1,1] op_sel_hi:[1,0] neg_lo:[1,0]
	v_pk_fma_f32 v[106:107], v[42:43], v[102:103], v[106:107] op_sel_hi:[0,1,1]
	v_pk_mul_f32 v[110:111], v[46:47], v[102:103] op_sel:[1,1] op_sel_hi:[1,0] neg_lo:[1,0]
	v_pk_fma_f32 v[122:123], v[42:43], v[118:119], v[122:123] op_sel_hi:[0,1,1]
	v_pk_mul_f32 v[126:127], v[46:47], v[118:119] op_sel:[1,1] op_sel_hi:[1,0] neg_lo:[1,0]
	v_pk_fma_f32 v[138:139], v[42:43], v[134:135], v[138:139] op_sel_hi:[0,1,1]
	v_pk_mul_f32 v[142:143], v[46:47], v[134:135] op_sel:[1,1] op_sel_hi:[1,0] neg_lo:[1,0]
	v_pk_fma_f32 v[156:157], v[42:43], v[152:153], v[156:157] op_sel_hi:[0,1,1]
	v_pk_mul_f32 v[160:161], v[46:47], v[152:153] op_sel:[1,1] op_sel_hi:[1,0] neg_lo:[1,0]
	v_pk_fma_f32 v[42:43], v[42:43], v[212:213], v[44:45] op_sel_hi:[0,1,1]
	v_pk_mul_f32 v[44:45], v[184:185], v[46:47] op_sel:[1,1] op_sel_hi:[0,1] neg_lo:[0,1]
	v_pk_fma_f32 v[62:63], v[46:47], v[52:53], v[62:63] op_sel_hi:[0,1,1]
	v_pk_fma_f32 v[66:67], v[52:53], v[48:49], v[66:67] op_sel_hi:[1,0,1]
	v_pk_fma_f32 v[78:79], v[46:47], v[70:71], v[78:79] op_sel_hi:[0,1,1]
	v_pk_mul_f32 v[82:83], v[48:49], v[70:71] op_sel:[1,1] op_sel_hi:[1,0] neg_lo:[1,0]
	v_pk_fma_f32 v[94:95], v[46:47], v[86:87], v[94:95] op_sel_hi:[0,1,1]
	v_pk_mul_f32 v[98:99], v[48:49], v[86:87] op_sel:[1,1] op_sel_hi:[1,0] neg_lo:[1,0]
	v_pk_fma_f32 v[110:111], v[46:47], v[102:103], v[110:111] op_sel_hi:[0,1,1]
	v_pk_mul_f32 v[114:115], v[48:49], v[102:103] op_sel:[1,1] op_sel_hi:[1,0] neg_lo:[1,0]
	v_pk_fma_f32 v[126:127], v[46:47], v[118:119], v[126:127] op_sel_hi:[0,1,1]
	v_pk_mul_f32 v[130:131], v[48:49], v[118:119] op_sel:[1,1] op_sel_hi:[1,0] neg_lo:[1,0]
	v_pk_fma_f32 v[142:143], v[46:47], v[134:135], v[142:143] op_sel_hi:[0,1,1]
	v_pk_mul_f32 v[148:149], v[48:49], v[134:135] op_sel:[1,1] op_sel_hi:[1,0] neg_lo:[1,0]
	v_pk_fma_f32 v[160:161], v[46:47], v[152:153], v[160:161] op_sel_hi:[0,1,1]
	v_pk_mul_f32 v[164:165], v[48:49], v[152:153] op_sel:[1,1] op_sel_hi:[1,0] neg_lo:[1,0]
	v_pk_fma_f32 v[44:45], v[184:185], v[46:47], v[44:45] op_sel_hi:[1,0,1]
	s_waitcnt lgkmcnt(7)
	v_pk_mul_f32 v[46:47], v[48:49], v[228:229] op_sel:[1,1] op_sel_hi:[1,0] neg_lo:[1,0]
	v_xor_b32_e32 v60, 0x80000000, v59
	v_xor_b32_e32 v64, 0x80000000, v63
	v_xor_b32_e32 v68, 0x80000000, v67
	v_xor_b32_e32 v72, 0x80000000, v71
	v_pk_fma_f32 v[82:83], v[48:49], v[70:71], v[82:83] op_sel_hi:[0,1,1]
	v_pk_fma_f32 v[98:99], v[48:49], v[86:87], v[98:99] op_sel_hi:[0,1,1]
	v_pk_fma_f32 v[114:115], v[48:49], v[102:103], v[114:115] op_sel_hi:[0,1,1]
	v_pk_fma_f32 v[130:131], v[48:49], v[118:119], v[130:131] op_sel_hi:[0,1,1]
	v_pk_fma_f32 v[148:149], v[48:49], v[134:135], v[148:149] op_sel_hi:[0,1,1]
	v_pk_fma_f32 v[164:165], v[48:49], v[152:153], v[164:165] op_sel_hi:[0,1,1]
	v_mov_b32_e32 v61, v59
	v_mov_b32_e32 v65, v63
	v_mov_b32_e32 v69, v67
	v_mov_b32_e32 v73, v71
	v_pk_fma_f32 v[46:47], v[48:49], v[228:229], v[46:47] op_sel_hi:[0,1,1]
	v_pk_mul_f32 v[48:49], v[176:177], v[52:53] op_sel:[1,1] op_sel_hi:[0,1] neg_lo:[0,1]
	v_xor_b32_e32 v76, 0x80000000, v75
	v_xor_b32_e32 v80, 0x80000000, v79
	v_xor_b32_e32 v84, 0x80000000, v83
	v_xor_b32_e32 v88, 0x80000000, v87
	v_xor_b32_e32 v92, 0x80000000, v91
	v_xor_b32_e32 v96, 0x80000000, v95
	v_xor_b32_e32 v100, 0x80000000, v99
	v_xor_b32_e32 v104, 0x80000000, v103
	v_xor_b32_e32 v136, 0x80000000, v135
	v_mov_b32_e32 v77, v75
	v_mov_b32_e32 v81, v79
	v_mov_b32_e32 v85, v83
	v_mov_b32_e32 v89, v87
	v_mov_b32_e32 v93, v91
	v_mov_b32_e32 v97, v95
	v_mov_b32_e32 v101, v99
	v_mov_b32_e32 v105, v103
	v_mov_b32_e32 v137, v135
	v_pk_fma_f32 v[48:49], v[176:177], v[52:53], v[48:49] op_sel_hi:[1,0,1]
	v_pk_mul_f32 v[50:51], v[60:61], v[220:221] op_sel:[0,1] op_sel_hi:[1,0]
	v_pk_mul_f32 v[52:53], v[192:193], v[64:65] op_sel:[1,0] op_sel_hi:[0,1]
	s_waitcnt lgkmcnt(3)
	v_pk_mul_f32 v[54:55], v[68:69], v[236:237] op_sel:[0,1] op_sel_hi:[1,0]
	v_pk_mul_f32 v[56:57], v[172:173], v[72:73] op_sel:[1,0] op_sel_hi:[0,1]
	v_xor_b32_e32 v108, 0x80000000, v107
	v_xor_b32_e32 v112, 0x80000000, v111
	v_xor_b32_e32 v116, 0x80000000, v115
	v_xor_b32_e32 v120, 0x80000000, v119
	v_xor_b32_e32 v124, 0x80000000, v123
	v_xor_b32_e32 v128, 0x80000000, v127
	v_xor_b32_e32 v132, 0x80000000, v131
	v_xor_b32_e32 v140, 0x80000000, v139
	v_xor_b32_e32 v144, 0x80000000, v143
	v_xor_b32_e32 v150, 0x80000000, v149
	v_xor_b32_e32 v154, 0x80000000, v153
	v_xor_b32_e32 v158, 0x80000000, v157
	v_xor_b32_e32 v162, 0x80000000, v161
	v_xor_b32_e32 v166, 0x80000000, v165
	v_mov_b32_e32 v109, v107
	v_mov_b32_e32 v113, v111
	v_mov_b32_e32 v117, v115
	v_mov_b32_e32 v121, v119
	v_mov_b32_e32 v125, v123
	v_mov_b32_e32 v129, v127
	v_mov_b32_e32 v133, v131
	v_mov_b32_e32 v141, v139
	v_mov_b32_e32 v145, v143
	v_mov_b32_e32 v151, v149
	v_mov_b32_e32 v155, v153
	v_mov_b32_e32 v159, v157
	v_mov_b32_e32 v163, v161
	v_mov_b32_e32 v167, v165
	v_pk_fma_f32 v[50:51], v[58:59], v[220:221], v[50:51] op_sel_hi:[0,1,1]
	v_pk_fma_f32 v[52:53], v[192:193], v[62:63], v[52:53] op_sel_hi:[1,0,1]
	v_pk_fma_f32 v[54:55], v[66:67], v[236:237], v[54:55] op_sel_hi:[0,1,1]
	v_pk_fma_f32 v[56:57], v[172:173], v[70:71], v[56:57] op_sel_hi:[1,0,1]
	v_pk_mul_f32 v[58:59], v[216:217], v[76:77] op_sel:[1,0] op_sel_hi:[0,1]
	v_pk_mul_f32 v[60:61], v[188:189], v[80:81] op_sel:[1,0] op_sel_hi:[0,1]
	v_pk_mul_f32 v[62:63], v[84:85], v[232:233] op_sel:[0,1] op_sel_hi:[1,0]
	v_pk_mul_f32 v[64:65], v[180:181], v[88:89] op_sel:[1,0] op_sel_hi:[0,1]
	v_pk_mul_f32 v[66:67], v[224:225], v[92:93] op_sel:[1,0] op_sel_hi:[0,1]
	v_pk_mul_f32 v[68:69], v[196:197], v[96:97] op_sel:[1,0] op_sel_hi:[0,1]
	s_waitcnt lgkmcnt(1)
	v_pk_mul_f32 v[70:71], v[100:101], v[240:241] op_sel:[0,1] op_sel_hi:[1,0]
	v_pk_mul_f32 v[72:73], v[170:171], v[104:105] op_sel:[1,0] op_sel_hi:[0,1]
	v_pk_mul_f32 v[88:89], v[174:175], v[136:137] op_sel:[1,0] op_sel_hi:[0,1]
	v_pk_fma_f32 v[58:59], v[216:217], v[74:75], v[58:59] op_sel_hi:[1,0,1]
	v_pk_fma_f32 v[60:61], v[188:189], v[78:79], v[60:61] op_sel_hi:[1,0,1]
	v_pk_fma_f32 v[62:63], v[82:83], v[232:233], v[62:63] op_sel_hi:[0,1,1]
	v_pk_fma_f32 v[64:65], v[180:181], v[86:87], v[64:65] op_sel_hi:[1,0,1]
	v_pk_fma_f32 v[66:67], v[224:225], v[90:91], v[66:67] op_sel_hi:[1,0,1]
	v_pk_fma_f32 v[68:69], v[196:197], v[94:95], v[68:69] op_sel_hi:[1,0,1]
	v_pk_fma_f32 v[70:71], v[98:99], v[240:241], v[70:71] op_sel_hi:[0,1,1]
	v_pk_fma_f32 v[72:73], v[170:171], v[102:103], v[72:73] op_sel_hi:[1,0,1]
	v_pk_mul_f32 v[74:75], v[214:215], v[108:109] op_sel:[1,0] op_sel_hi:[0,1]
	v_pk_mul_f32 v[76:77], v[186:187], v[112:113] op_sel:[1,0] op_sel_hi:[0,1]
	v_pk_mul_f32 v[78:79], v[230:231], v[116:117] op_sel:[1,0] op_sel_hi:[0,1]
	v_pk_mul_f32 v[80:81], v[178:179], v[120:121] op_sel:[1,0] op_sel_hi:[0,1]
	v_pk_mul_f32 v[82:83], v[222:223], v[124:125] op_sel:[1,0] op_sel_hi:[0,1]
	v_pk_mul_f32 v[84:85], v[194:195], v[128:129] op_sel:[1,0] op_sel_hi:[0,1]
	v_pk_mul_f32 v[86:87], v[132:133], v[238:239] op_sel:[0,1] op_sel_hi:[1,0]
	v_pk_fma_f32 v[88:89], v[174:175], v[134:135], v[88:89] op_sel_hi:[1,0,1]
	v_pk_mul_f32 v[90:91], v[218:219], v[140:141] op_sel:[1,0] op_sel_hi:[0,1]
	v_pk_mul_f32 v[92:93], v[190:191], v[144:145] op_sel:[1,0] op_sel_hi:[0,1]
	v_pk_mul_f32 v[94:95], v[234:235], v[150:151] op_sel:[1,0] op_sel_hi:[0,1]
	v_pk_mul_f32 v[96:97], v[182:183], v[154:155] op_sel:[1,0] op_sel_hi:[0,1]
	v_pk_mul_f32 v[98:99], v[226:227], v[158:159] op_sel:[1,0] op_sel_hi:[0,1]
	v_pk_mul_f32 v[100:101], v[198:199], v[162:163] op_sel:[1,0] op_sel_hi:[0,1]
	s_waitcnt lgkmcnt(0)
	v_pk_mul_f32 v[102:103], v[242:243], v[166:167] op_sel:[1,0] op_sel_hi:[0,1]
	v_pk_fma_f32 v[74:75], v[214:215], v[106:107], v[74:75] op_sel_hi:[1,0,1]
	v_pk_fma_f32 v[76:77], v[186:187], v[110:111], v[76:77] op_sel_hi:[1,0,1]
	v_pk_fma_f32 v[78:79], v[230:231], v[114:115], v[78:79] op_sel_hi:[1,0,1]
	v_pk_fma_f32 v[80:81], v[178:179], v[118:119], v[80:81] op_sel_hi:[1,0,1]
	v_pk_fma_f32 v[82:83], v[222:223], v[122:123], v[82:83] op_sel_hi:[1,0,1]
	v_pk_fma_f32 v[84:85], v[194:195], v[126:127], v[84:85] op_sel_hi:[1,0,1]
	v_pk_fma_f32 v[86:87], v[130:131], v[238:239], v[86:87] op_sel_hi:[0,1,1]
	v_pk_fma_f32 v[90:91], v[218:219], v[138:139], v[90:91] op_sel_hi:[1,0,1]
	v_pk_fma_f32 v[92:93], v[190:191], v[142:143], v[92:93] op_sel_hi:[1,0,1]
	v_pk_fma_f32 v[94:95], v[234:235], v[148:149], v[94:95] op_sel_hi:[1,0,1]
	v_pk_fma_f32 v[96:97], v[182:183], v[152:153], v[96:97] op_sel_hi:[1,0,1]
	v_pk_fma_f32 v[98:99], v[226:227], v[156:157], v[98:99] op_sel_hi:[1,0,1]
	v_pk_fma_f32 v[100:101], v[198:199], v[160:161], v[100:101] op_sel_hi:[1,0,1]
	v_pk_fma_f32 v[102:103], v[242:243], v[164:165], v[102:103] op_sel_hi:[1,0,1]
	v_pk_add_f32 v[104:105], v[168:169], v[72:73]
	v_pk_add_f32 v[106:107], v[56:57], v[88:89]
	v_pk_add_f32 v[56:57], v[56:57], v[88:89] neg_lo:[0,1] neg_hi:[0,1]
	v_pk_add_f32 v[72:73], v[168:169], v[72:73] neg_lo:[0,1] neg_hi:[0,1]
	v_pk_add_f32 v[88:89], v[48:49], v[80:81]
	v_pk_add_f32 v[48:49], v[48:49], v[80:81] neg_lo:[0,1] neg_hi:[0,1]
	v_pk_add_f32 v[80:81], v[64:65], v[96:97]
	v_pk_add_f32 v[64:65], v[64:65], v[96:97] neg_lo:[0,1] neg_hi:[0,1]
	v_pk_add_f32 v[96:97], v[44:45], v[76:77]
	v_pk_add_f32 v[44:45], v[44:45], v[76:77] neg_lo:[0,1] neg_hi:[0,1]
	v_pk_add_f32 v[76:77], v[60:61], v[92:93]
	v_pk_add_f32 v[60:61], v[60:61], v[92:93] neg_lo:[0,1] neg_hi:[0,1]
	v_pk_add_f32 v[92:93], v[52:53], v[84:85]
	v_pk_add_f32 v[52:53], v[52:53], v[84:85] neg_lo:[0,1] neg_hi:[0,1]
	v_pk_add_f32 v[84:85], v[68:69], v[100:101]
	v_pk_add_f32 v[68:69], v[68:69], v[100:101] neg_lo:[0,1] neg_hi:[0,1]
	v_pk_add_f32 v[100:101], v[42:43], v[74:75]
	v_pk_add_f32 v[42:43], v[42:43], v[74:75] neg_lo:[0,1] neg_hi:[0,1]
	v_pk_add_f32 v[74:75], v[58:59], v[90:91]
	v_pk_add_f32 v[58:59], v[58:59], v[90:91] neg_lo:[0,1] neg_hi:[0,1]
	v_pk_add_f32 v[90:91], v[50:51], v[82:83]
	v_pk_add_f32 v[50:51], v[50:51], v[82:83] neg_lo:[0,1] neg_hi:[0,1]
	v_pk_add_f32 v[82:83], v[66:67], v[98:99]
	v_pk_add_f32 v[66:67], v[66:67], v[98:99] neg_lo:[0,1] neg_hi:[0,1]
	v_pk_add_f32 v[98:99], v[46:47], v[78:79]
	v_pk_add_f32 v[46:47], v[46:47], v[78:79] neg_lo:[0,1] neg_hi:[0,1]
	v_pk_add_f32 v[78:79], v[62:63], v[94:95]
	v_pk_add_f32 v[62:63], v[62:63], v[94:95] neg_lo:[0,1] neg_hi:[0,1]
	v_pk_add_f32 v[94:95], v[54:55], v[86:87]
	v_pk_add_f32 v[54:55], v[54:55], v[86:87] neg_lo:[0,1] neg_hi:[0,1]
	v_pk_add_f32 v[86:87], v[70:71], v[102:103]
	v_pk_add_f32 v[70:71], v[70:71], v[102:103] neg_lo:[0,1] neg_hi:[0,1]
	v_pk_add_f32 v[102:103], v[104:105], v[106:107]
	v_pk_add_f32 v[104:105], v[104:105], v[106:107] neg_lo:[0,1] neg_hi:[0,1]
	v_xor_b32_e32 v106, 0x80000000, v57
	v_mov_b32_e32 v107, v56
	v_pk_add_f32 v[56:57], v[72:73], v[106:107]
	v_pk_add_f32 v[72:73], v[72:73], v[106:107] neg_lo:[0,1] neg_hi:[0,1]
	v_pk_add_f32 v[106:107], v[88:89], v[80:81]
	v_pk_add_f32 v[80:81], v[88:89], v[80:81] neg_lo:[0,1] neg_hi:[0,1]
	v_xor_b32_e32 v88, 0x80000000, v65
	v_mov_b32_e32 v89, v64
	v_pk_add_f32 v[64:65], v[48:49], v[88:89]
	v_pk_add_f32 v[48:49], v[48:49], v[88:89] neg_lo:[0,1] neg_hi:[0,1]
	v_pk_add_f32 v[88:89], v[96:97], v[76:77]
	v_pk_add_f32 v[76:77], v[96:97], v[76:77] neg_lo:[0,1] neg_hi:[0,1]
	v_xor_b32_e32 v96, 0x80000000, v61
	v_mov_b32_e32 v97, v60
	v_pk_add_f32 v[60:61], v[44:45], v[96:97]
	v_pk_add_f32 v[44:45], v[44:45], v[96:97] neg_lo:[0,1] neg_hi:[0,1]
	v_pk_add_f32 v[96:97], v[92:93], v[84:85]
	v_pk_add_f32 v[84:85], v[92:93], v[84:85] neg_lo:[0,1] neg_hi:[0,1]
	v_xor_b32_e32 v92, 0x80000000, v69
	v_mov_b32_e32 v93, v68
	v_pk_add_f32 v[68:69], v[52:53], v[92:93]
	v_pk_add_f32 v[52:53], v[52:53], v[92:93] neg_lo:[0,1] neg_hi:[0,1]
	v_pk_add_f32 v[92:93], v[100:101], v[74:75]
	v_pk_add_f32 v[74:75], v[100:101], v[74:75] neg_lo:[0,1] neg_hi:[0,1]
	v_xor_b32_e32 v100, 0x80000000, v59
	v_mov_b32_e32 v101, v58
	v_pk_add_f32 v[58:59], v[42:43], v[100:101]
	v_pk_add_f32 v[42:43], v[42:43], v[100:101] neg_lo:[0,1] neg_hi:[0,1]
	v_pk_add_f32 v[100:101], v[90:91], v[82:83]
	v_pk_add_f32 v[82:83], v[90:91], v[82:83] neg_lo:[0,1] neg_hi:[0,1]
	v_xor_b32_e32 v90, 0x80000000, v67
	v_mov_b32_e32 v91, v66
	v_pk_add_f32 v[66:67], v[50:51], v[90:91]
	v_pk_add_f32 v[50:51], v[50:51], v[90:91] neg_lo:[0,1] neg_hi:[0,1]
	v_pk_add_f32 v[90:91], v[98:99], v[78:79]
	v_pk_add_f32 v[78:79], v[98:99], v[78:79] neg_lo:[0,1] neg_hi:[0,1]
	v_xor_b32_e32 v98, 0x80000000, v63
	v_mov_b32_e32 v99, v62
	v_pk_add_f32 v[62:63], v[46:47], v[98:99]
	v_pk_add_f32 v[46:47], v[46:47], v[98:99] neg_lo:[0,1] neg_hi:[0,1]
	v_pk_add_f32 v[98:99], v[94:95], v[86:87]
	v_pk_add_f32 v[86:87], v[94:95], v[86:87] neg_lo:[0,1] neg_hi:[0,1]
	v_xor_b32_e32 v94, 0x80000000, v71
	v_mov_b32_e32 v95, v70
	s_mov_b32 s63, s36
	v_pk_add_f32 v[70:71], v[54:55], v[94:95]
	v_pk_add_f32 v[54:55], v[54:55], v[94:95] neg_lo:[0,1] neg_hi:[0,1]
	v_pk_add_f32 v[94:95], v[102:103], v[106:107]
	v_pk_add_f32 v[102:103], v[102:103], v[106:107] neg_lo:[0,1] neg_hi:[0,1]
	s_mov_b32 s0, s37
	v_pk_mul_f32 v[106:107], v[64:65], s[62:63]
	s_mov_b32 s64, s19
	v_pk_fma_f32 v[64:65], v[64:65], s[0:1], v[106:107] op_sel:[0,0,1] op_sel_hi:[1,0,0]
	s_mov_b32 s65, s18
	v_pk_add_f32 v[106:107], v[56:57], v[64:65]
	v_pk_add_f32 v[56:57], v[56:57], v[64:65] neg_lo:[0,1] neg_hi:[0,1]
	v_xor_b32_e32 v64, 0x80000000, v81
	v_mov_b32_e32 v65, v80
	v_pk_add_f32 v[80:81], v[104:105], v[64:65]
	v_pk_add_f32 v[64:65], v[104:105], v[64:65] neg_lo:[0,1] neg_hi:[0,1]
	v_pk_mul_f32 v[104:105], v[48:49], s[62:63]
	s_mov_b32 s66, s19
	v_pk_fma_f32 v[48:49], v[48:49], s[0:1], v[104:105] op_sel:[0,0,1] op_sel_hi:[1,0,0] neg_lo:[1,0,0] neg_hi:[1,0,0]
	s_mov_b32 s68, s11
	v_pk_add_f32 v[104:105], v[72:73], v[48:49]
	v_pk_add_f32 v[48:49], v[72:73], v[48:49] neg_lo:[0,1] neg_hi:[0,1]
	v_pk_add_f32 v[72:73], v[88:89], v[96:97]
	v_pk_add_f32 v[88:89], v[88:89], v[96:97] neg_lo:[0,1] neg_hi:[0,1]
	v_pk_mul_f32 v[96:97], v[68:69], s[62:63]
	s_mov_b32 s69, s10
	v_pk_fma_f32 v[68:69], v[68:69], s[0:1], v[96:97] op_sel:[0,0,1] op_sel_hi:[1,0,0]
	s_mov_b32 s72, s27
	v_pk_add_f32 v[96:97], v[60:61], v[68:69]
	v_pk_add_f32 v[60:61], v[60:61], v[68:69] neg_lo:[0,1] neg_hi:[0,1]
	v_xor_b32_e32 v68, 0x80000000, v85
	v_mov_b32_e32 v69, v84
	v_pk_add_f32 v[84:85], v[76:77], v[68:69]
	v_pk_add_f32 v[68:69], v[76:77], v[68:69] neg_lo:[0,1] neg_hi:[0,1]
	v_pk_mul_f32 v[76:77], v[52:53], s[62:63]
	v_pk_mul_f32 v[108:109], v[96:97], s[64:65]
	v_pk_fma_f32 v[52:53], v[52:53], s[0:1], v[76:77] op_sel:[0,0,1] op_sel_hi:[1,0,0] neg_lo:[1,0,0] neg_hi:[1,0,0]
	v_pk_fma_f32 v[96:97], v[96:97], s[16:17], v[108:109] op_sel:[0,0,1] op_sel_hi:[1,0,0]
	v_pk_add_f32 v[76:77], v[44:45], v[52:53]
	v_pk_add_f32 v[44:45], v[44:45], v[52:53] neg_lo:[0,1] neg_hi:[0,1]
	v_pk_add_f32 v[52:53], v[92:93], v[100:101]
	v_pk_add_f32 v[92:93], v[92:93], v[100:101] neg_lo:[0,1] neg_hi:[0,1]
	v_pk_mul_f32 v[100:101], v[66:67], s[62:63]
	s_mov_b32 s17, s40
	v_pk_fma_f32 v[66:67], v[66:67], s[0:1], v[100:101] op_sel:[0,0,1] op_sel_hi:[1,0,0]
	v_pk_add_f32 v[108:109], v[106:107], v[96:97]
	v_pk_add_f32 v[100:101], v[58:59], v[66:67]
	v_pk_add_f32 v[58:59], v[58:59], v[66:67] neg_lo:[0,1] neg_hi:[0,1]
	v_xor_b32_e32 v66, 0x80000000, v83
	v_mov_b32_e32 v67, v82
	v_pk_add_f32 v[82:83], v[74:75], v[66:67]
	v_pk_add_f32 v[66:67], v[74:75], v[66:67] neg_lo:[0,1] neg_hi:[0,1]
	v_pk_mul_f32 v[74:75], v[50:51], s[62:63]
	v_pk_add_f32 v[96:97], v[106:107], v[96:97] neg_lo:[0,1] neg_hi:[0,1]
	v_pk_fma_f32 v[50:51], v[50:51], s[0:1], v[74:75] op_sel:[0,0,1] op_sel_hi:[1,0,0] neg_lo:[1,0,0] neg_hi:[1,0,0]
	v_pk_mul_f32 v[106:107], v[84:85], s[62:63]
	v_pk_add_f32 v[74:75], v[42:43], v[50:51]
	v_pk_add_f32 v[42:43], v[42:43], v[50:51] neg_lo:[0,1] neg_hi:[0,1]
	v_pk_add_f32 v[50:51], v[90:91], v[98:99]
	v_pk_add_f32 v[90:91], v[90:91], v[98:99] neg_lo:[0,1] neg_hi:[0,1]
	v_pk_mul_f32 v[98:99], v[70:71], s[62:63]
	v_pk_fma_f32 v[84:85], v[84:85], s[0:1], v[106:107] op_sel:[0,0,1] op_sel_hi:[1,0,0]
	v_pk_fma_f32 v[70:71], v[70:71], s[0:1], v[98:99] op_sel:[0,0,1] op_sel_hi:[1,0,0]
	v_pk_add_f32 v[106:107], v[80:81], v[84:85]
	v_pk_add_f32 v[98:99], v[62:63], v[70:71]
	v_pk_add_f32 v[62:63], v[62:63], v[70:71] neg_lo:[0,1] neg_hi:[0,1]
	v_xor_b32_e32 v70, 0x80000000, v87
	v_mov_b32_e32 v71, v86
	v_pk_mul_f32 v[110:111], v[98:99], s[64:65]
	v_pk_add_f32 v[86:87], v[78:79], v[70:71]
	v_pk_add_f32 v[70:71], v[78:79], v[70:71] neg_lo:[0,1] neg_hi:[0,1]
	v_pk_mul_f32 v[78:79], v[54:55], s[62:63]
	v_pk_fma_f32 v[98:99], v[98:99], s[16:17], v[110:111] op_sel:[0,0,1] op_sel_hi:[1,0,0]
	v_pk_fma_f32 v[54:55], v[54:55], s[0:1], v[78:79] op_sel:[0,0,1] op_sel_hi:[1,0,0] neg_lo:[1,0,0] neg_hi:[1,0,0]
	v_pk_add_f32 v[110:111], v[100:101], v[98:99]
	v_pk_add_f32 v[98:99], v[100:101], v[98:99] neg_lo:[0,1] neg_hi:[0,1]
	v_pk_mul_f32 v[100:101], v[86:87], s[62:63]
	v_pk_add_f32 v[78:79], v[46:47], v[54:55]
	v_pk_fma_f32 v[86:87], v[86:87], s[0:1], v[100:101] op_sel:[0,0,1] op_sel_hi:[1,0,0]
	v_pk_add_f32 v[46:47], v[46:47], v[54:55] neg_lo:[0,1] neg_hi:[0,1]
	v_pk_add_f32 v[100:101], v[82:83], v[86:87]
	v_pk_add_f32 v[82:83], v[82:83], v[86:87] neg_lo:[0,1] neg_hi:[0,1]
	v_pk_mul_f32 v[86:87], v[78:79], s[16:17]
	v_pk_add_f32 v[80:81], v[80:81], v[84:85] neg_lo:[0,1] neg_hi:[0,1]
	v_pk_fma_f32 v[78:79], v[78:79], s[66:67], v[86:87] op_sel:[0,0,1] op_sel_hi:[1,0,0]
	v_pk_mul_f32 v[84:85], v[76:77], s[16:17]
	v_pk_add_f32 v[86:87], v[74:75], v[78:79]
	v_pk_add_f32 v[74:75], v[74:75], v[78:79] neg_lo:[0,1] neg_hi:[0,1]
	v_xor_b32_e32 v78, 0x80000000, v91
	v_mov_b32_e32 v79, v90
	v_pk_add_f32 v[90:91], v[92:93], v[78:79]
	v_pk_add_f32 v[78:79], v[92:93], v[78:79] neg_lo:[0,1] neg_hi:[0,1]
	v_pk_mul_f32 v[92:93], v[62:63], s[16:17]
	v_pk_fma_f32 v[76:77], v[76:77], s[66:67], v[84:85] op_sel:[0,0,1] op_sel_hi:[1,0,0]
	v_pk_fma_f32 v[62:63], v[62:63], s[66:67], v[92:93] op_sel:[0,0,1] op_sel_hi:[1,0,0] neg_lo:[1,0,0] neg_hi:[1,0,0]
	v_pk_add_f32 v[84:85], v[104:105], v[76:77]
	v_pk_add_f32 v[92:93], v[58:59], v[62:63]
	v_pk_add_f32 v[58:59], v[58:59], v[62:63] neg_lo:[0,1] neg_hi:[0,1]
	v_pk_mul_f32 v[62:63], v[70:71], s[62:63]
	v_pk_add_f32 v[76:77], v[104:105], v[76:77] neg_lo:[0,1] neg_hi:[0,1]
	v_pk_fma_f32 v[62:63], v[70:71], s[0:1], v[62:63] op_sel:[0,0,1] op_sel_hi:[1,0,0] neg_lo:[1,0,0] neg_hi:[1,0,0]
	v_xor_b32_e32 v104, 0x80000000, v89
	v_pk_add_f32 v[70:71], v[66:67], v[62:63]
	v_pk_add_f32 v[62:63], v[66:67], v[62:63] neg_lo:[0,1] neg_hi:[0,1]
	v_pk_mul_f32 v[66:67], v[46:47], s[64:65]
	v_mov_b32_e32 v105, v88
	v_pk_fma_f32 v[46:47], v[46:47], s[16:17], v[66:67] op_sel:[0,0,1] op_sel_hi:[1,0,0] neg_lo:[1,0,0] neg_hi:[1,0,0]
	s_mov_b32 s73, s26
	v_pk_add_f32 v[66:67], v[42:43], v[46:47]
	v_pk_add_f32 v[42:43], v[42:43], v[46:47] neg_lo:[0,1] neg_hi:[0,1]
	v_pk_mul_f32 v[46:47], v[110:111], s[68:69]
	v_pk_add_f32 v[88:89], v[102:103], v[104:105]
	v_pk_fma_f32 v[46:47], v[110:111], s[8:9], v[46:47] op_sel:[0,0,1] op_sel_hi:[1,0,0]
	v_pk_add_f32 v[102:103], v[102:103], v[104:105] neg_lo:[0,1] neg_hi:[0,1]
	v_pk_add_f32 v[46:47], v[108:109], v[46:47]
	v_pk_mul_f32 v[108:109], v[100:101], s[64:65]
	v_pk_mul_f32 v[104:105], v[60:61], s[16:17]
	v_pk_fma_f32 v[100:101], v[100:101], s[16:17], v[108:109] op_sel:[0,0,1] op_sel_hi:[1,0,0]
	v_pk_fma_f32 v[60:61], v[60:61], s[66:67], v[104:105] op_sel:[0,0,1] op_sel_hi:[1,0,0] neg_lo:[1,0,0] neg_hi:[1,0,0]
	v_pk_add_f32 v[100:101], v[106:107], v[100:101]
	v_pk_mul_f32 v[106:107], v[86:87], s[72:73]
	v_pk_add_f32 v[104:105], v[56:57], v[60:61]
	v_pk_fma_f32 v[86:87], v[86:87], s[24:25], v[106:107] op_sel:[0,0,1] op_sel_hi:[1,0,0]
	v_pk_add_f32 v[56:57], v[56:57], v[60:61] neg_lo:[0,1] neg_hi:[0,1]
	v_pk_mul_f32 v[60:61], v[68:69], s[62:63]
	v_pk_add_f32 v[84:85], v[84:85], v[86:87]
	v_pk_mul_f32 v[86:87], v[90:91], s[62:63]
	v_pk_fma_f32 v[60:61], v[68:69], s[0:1], v[60:61] op_sel:[0,0,1] op_sel_hi:[1,0,0] neg_lo:[1,0,0] neg_hi:[1,0,0]
	v_pk_fma_f32 v[86:87], v[90:91], s[0:1], v[86:87] op_sel:[0,0,1] op_sel_hi:[1,0,0]
	v_pk_mul_f32 v[90:91], v[70:71], s[16:17]
	v_pk_add_f32 v[68:69], v[64:65], v[60:61]
	v_pk_fma_f32 v[70:71], v[70:71], s[66:67], v[90:91] op_sel:[0,0,1] op_sel_hi:[1,0,0]
	s_mov_b32 s9, s42
	s_mov_b32 s25, s38
	v_pk_add_f32 v[68:69], v[68:69], v[70:71]
	s_mov_b32 s76, s11
	v_pk_mul_f32 v[70:71], v[66:67], s[8:9]
	s_mov_b32 s74, s27
	v_pk_fma_f32 v[66:67], v[66:67], s[76:77], v[70:71] op_sel:[0,0,1] op_sel_hi:[1,0,0]
	v_pk_mul_f32 v[70:71], v[74:75], s[24:25]
	v_pk_add_f32 v[60:61], v[64:65], v[60:61] neg_lo:[0,1] neg_hi:[0,1]
	v_pk_fma_f32 v[70:71], v[74:75], s[74:75], v[70:71] op_sel:[0,0,1] op_sel_hi:[1,0,0] neg_lo:[1,0,0] neg_hi:[1,0,0]
	v_pk_mul_f32 v[64:65], v[44:45], s[64:65]
	v_pk_add_f32 v[70:71], v[76:77], v[70:71]
	v_pk_mul_f32 v[76:77], v[58:59], s[72:73]
	v_pk_fma_f32 v[44:45], v[44:45], s[16:17], v[64:65] op_sel:[0,0,1] op_sel_hi:[1,0,0] neg_lo:[1,0,0] neg_hi:[1,0,0]
	v_pk_fma_f32 v[58:59], v[58:59], s[24:25], v[76:77] op_sel:[0,0,1] op_sel_hi:[1,0,0] neg_lo:[1,0,0] neg_hi:[1,0,0]
	v_pk_add_f32 v[64:65], v[48:49], v[44:45]
	v_pk_add_f32 v[56:57], v[56:57], v[58:59]
	v_pk_mul_f32 v[58:59], v[62:63], s[64:65]
	v_pk_add_f32 v[44:45], v[48:49], v[44:45] neg_lo:[0,1] neg_hi:[0,1]
	v_pk_fma_f32 v[58:59], v[62:63], s[16:17], v[58:59] op_sel:[0,0,1] op_sel_hi:[1,0,0] neg_lo:[1,0,0] neg_hi:[1,0,0]
	v_pk_add_f32 v[48:49], v[52:53], v[50:51] neg_lo:[0,1] neg_hi:[0,1]
	v_pk_add_f32 v[58:59], v[60:61], v[58:59]
	v_pk_mul_f32 v[60:61], v[42:43], s[68:69]
	v_pk_add_f32 v[54:55], v[94:95], v[72:73] neg_lo:[0,1] neg_hi:[0,1]
	v_pk_add_f32 v[64:65], v[64:65], v[66:67]
	v_xor_b32_e32 v66, 0x80000000, v49
	v_mov_b32_e32 v67, v48
	v_pk_fma_f32 v[42:43], v[42:43], s[8:9], v[60:61] op_sel:[0,0,1] op_sel_hi:[1,0,0] neg_lo:[1,0,0] neg_hi:[1,0,0]
	v_pk_add_f32 v[86:87], v[88:89], v[86:87]
	v_pk_mul_f32 v[88:89], v[92:93], s[24:25]
	v_pk_add_f32 v[48:49], v[54:55], v[66:67]
	v_pk_mul_f32 v[54:55], v[98:99], s[8:9]
	v_pk_mul_f32 v[66:67], v[82:83], s[16:17]
	v_pk_mul_f32 v[74:75], v[78:79], s[62:63]
	v_pk_add_f32 v[42:43], v[44:45], v[42:43]
	v_pk_add_f32 v[44:45], v[94:95], v[72:73]
	v_pk_add_f32 v[50:51], v[52:53], v[50:51]
	v_pk_fma_f32 v[88:89], v[92:93], s[74:75], v[88:89] op_sel:[0,0,1] op_sel_hi:[1,0,0]
	v_pk_fma_f32 v[54:55], v[98:99], s[76:77], v[54:55] op_sel:[0,0,1] op_sel_hi:[1,0,0] neg_lo:[1,0,0] neg_hi:[1,0,0]
	v_pk_fma_f32 v[66:67], v[82:83], s[66:67], v[66:67] op_sel:[0,0,1] op_sel_hi:[1,0,0] neg_lo:[1,0,0] neg_hi:[1,0,0]
	v_pk_fma_f32 v[74:75], v[78:79], s[0:1], v[74:75] op_sel:[0,0,1] op_sel_hi:[1,0,0] neg_lo:[1,0,0] neg_hi:[1,0,0]
	v_pk_add_f32 v[44:45], v[44:45], v[50:51]
	v_lshl_add_u32 v21, v21, 3, v36
	v_pk_add_f32 v[88:89], v[104:105], v[88:89]
	v_pk_add_f32 v[54:55], v[96:97], v[54:55]
	v_pk_add_f32 v[66:67], v[80:81], v[66:67]
	v_pk_add_f32 v[74:75], v[102:103], v[74:75]
	ds_write_b64 v25, v[44:45]
	ds_write_b64 v25, v[46:47] offset:2112
	ds_write_b64 v25, v[100:101] offset:4224
	ds_write_b64 v25, v[84:85] offset:6336
	ds_write_b64 v25, v[86:87] offset:8448
	ds_write_b64 v25, v[88:89] offset:10560
	ds_write_b64 v25, v[68:69] offset:12672
	ds_write_b64 v25, v[64:65] offset:14784
	ds_write_b64 v25, v[48:49] offset:16896
	ds_write_b64 v25, v[54:55] offset:19008
	ds_write_b64 v25, v[66:67] offset:21120
	ds_write_b64 v25, v[70:71] offset:23232
	ds_write_b64 v25, v[74:75] offset:25344
	ds_write_b64 v25, v[56:57] offset:27456
	ds_write_b64 v25, v[58:59] offset:29568
	ds_write_b64 v25, v[42:43] offset:31680
	v_ashrrev_i32_e32 v25, 5, v21
	v_lshlrev_b32_e32 v21, 3, v21
	v_lshlrev_b32_e32 v25, 3, v25
	s_waitcnt vmcnt(0)
	v_lshlrev_b32_e32 v41, 16, v41
	v_lshlrev_b32_e32 v39, 16, v39
	v_lshlrev_b32_e32 v35, 16, v35
	v_lshlrev_b32_e32 v29, 16, v29
	v_and_b32_e32 v48, 0xffff0000, v14
	v_add3_u32 v21, 0, v21, v25
	v_mov_b32_e32 v40, v48
	s_waitcnt lgkmcnt(0)
	s_barrier
	v_pk_mul_f32 v[44:45], v[30:31], v[40:41]
	ds_read2_b64 v[40:43], v21 offset1:1
	v_lshlrev_b32_e32 v28, 16, v14
	v_lshlrev_b32_e32 v49, 16, v15
	v_pk_fma_f32 v[44:45], v[30:31], v[28:29], v[44:45] op_sel:[0,0,1] op_sel_hi:[1,0,0]
	v_mov_b32_e32 v28, v31
	v_pk_fma_f32 v[44:45], v[20:21], v[48:49], v[44:45] op_sel_hi:[0,1,1]
	v_pk_add_f32 v[50:51], v[24:25], v[44:45] op_sel_hi:[0,1]
	ds_read2_b64 v[44:47], v21 offset0:2 offset1:3
	s_waitcnt lgkmcnt(1)
	v_pk_mul_f32 v[40:41], v[50:51], v[40:41]
	v_and_b32_e32 v51, 16, v16
	v_and_b32_e32 v50, 0xffff0000, v15
	v_pk_mov_b32 v[14:15], v[48:49], v[50:51] op_sel:[1,0]
	v_lshlrev_b32_e32 v53, 16, v16
	v_pk_mul_f32 v[14:15], v[30:31], v[14:15] op_sel_hi:[0,1]
	v_mov_b32_e32 v52, v50
	v_pk_fma_f32 v[14:15], v[28:29], v[48:49], v[14:15] op_sel_hi:[0,1,1]
	v_pk_fma_f32 v[14:15], v[20:21], v[52:53], v[14:15] op_sel_hi:[0,1,1]
	v_pk_add_f32 v[14:15], v[24:25], v[14:15] op_sel_hi:[0,1]
	v_pk_mul_f32 v[14:15], v[14:15], v[42:43]
	v_and_b32_e32 v43, 16, v17
	v_and_b32_e32 v42, 0xffff0000, v16
	v_lshlrev_b32_e32 v49, 16, v17
	v_mov_b32_e32 v48, v42
	v_pk_mov_b32 v[42:43], v[52:53], v[42:43] op_sel:[1,0]
	v_pk_mov_b32 v[16:17], v[16:17], v[10:11] op_sel:[1,0]
	v_pk_mul_f32 v[42:43], v[30:31], v[42:43] op_sel_hi:[0,1]
	v_and_b32_e32 v17, 16, v17
	v_and_b32_e32 v16, 0xffff0000, v16
	v_pk_fma_f32 v[42:43], v[28:29], v[52:53], v[42:43] op_sel_hi:[0,1,1]
	v_mov_b32_e32 v50, v16
	v_pk_mov_b32 v[16:17], v[48:49], v[16:17] op_sel:[1,0]
	v_pk_fma_f32 v[42:43], v[20:21], v[48:49], v[42:43] op_sel_hi:[0,1,1]
	v_pk_mul_f32 v[16:17], v[30:31], v[16:17] op_sel_hi:[0,1]
	v_pk_add_f32 v[42:43], v[24:25], v[42:43] op_sel_hi:[0,1]
	v_lshlrev_b32_e32 v51, 16, v10
	v_pk_fma_f32 v[16:17], v[28:29], v[48:49], v[16:17] op_sel_hi:[0,1,1]
	s_waitcnt lgkmcnt(0)
	v_pk_mul_f32 v[42:43], v[42:43], v[44:45]
	v_pk_fma_f32 v[16:17], v[20:21], v[50:51], v[16:17] op_sel_hi:[0,1,1]
	v_and_b32_e32 v45, 16, v11
	v_and_b32_e32 v44, 0xffff0000, v10
	v_pk_add_f32 v[16:17], v[24:25], v[16:17] op_sel_hi:[0,1]
	v_mov_b32_e32 v52, v44
	v_pk_mov_b32 v[44:45], v[50:51], v[44:45] op_sel:[1,0]
	v_pk_mul_f32 v[16:17], v[16:17], v[46:47]
	v_pk_mul_f32 v[48:49], v[30:31], v[44:45] op_sel_hi:[0,1]
	ds_read2_b64 v[44:47], v21 offset0:4 offset1:5
	v_lshlrev_b32_e32 v53, 16, v11
	v_pk_fma_f32 v[48:49], v[28:29], v[50:51], v[48:49] op_sel_hi:[0,1,1]
	v_pk_fma_f32 v[48:49], v[20:21], v[52:53], v[48:49] op_sel_hi:[0,1,1]
	v_pk_add_f32 v[54:55], v[24:25], v[48:49] op_sel_hi:[0,1]
	ds_read2_b64 v[48:51], v21 offset0:6 offset1:7
	s_waitcnt lgkmcnt(1)
	v_pk_mul_f32 v[44:45], v[54:55], v[44:45]
	v_and_b32_e32 v55, 16, v12
	v_and_b32_e32 v54, 0xffff0000, v11
	v_pk_mov_b32 v[10:11], v[52:53], v[54:55] op_sel:[1,0]
	v_lshlrev_b32_e32 v57, 16, v12
	v_pk_mul_f32 v[10:11], v[30:31], v[10:11] op_sel_hi:[0,1]
	v_mov_b32_e32 v56, v54
	v_pk_fma_f32 v[10:11], v[28:29], v[52:53], v[10:11] op_sel_hi:[0,1,1]
	v_pk_fma_f32 v[10:11], v[20:21], v[56:57], v[10:11] op_sel_hi:[0,1,1]
	v_pk_add_f32 v[10:11], v[24:25], v[10:11] op_sel_hi:[0,1]
	v_and_b32_e32 v38, 0xffff0000, v13
	v_pk_mul_f32 v[10:11], v[10:11], v[46:47]
	v_and_b32_e32 v47, 16, v13
	v_and_b32_e32 v46, 0xffff0000, v12
	v_lshlrev_b32_e32 v53, 16, v13
	v_mov_b32_e32 v52, v46
	v_pk_mov_b32 v[12:13], v[56:57], v[46:47] op_sel:[1,0]
	v_mov_b32_e32 v46, v53
	v_mov_b32_e32 v47, v38
	v_pk_mul_f32 v[12:13], v[30:31], v[12:13] op_sel_hi:[0,1]
	v_pk_mul_f32 v[46:47], v[30:31], v[46:47] op_sel_hi:[0,1]
	v_pk_fma_f32 v[12:13], v[28:29], v[56:57], v[12:13] op_sel_hi:[0,1,1]
	v_pk_fma_f32 v[46:47], v[28:29], v[52:53], v[46:47] op_sel_hi:[0,1,1]
	v_pk_fma_f32 v[12:13], v[20:21], v[52:53], v[12:13] op_sel_hi:[0,1,1]
	v_pk_fma_f32 v[38:39], v[20:21], v[38:39], v[46:47] op_sel_hi:[0,1,1]
	s_xor_b64 s[50:51], s[50:51], -1
	v_pk_add_f32 v[12:13], v[24:25], v[12:13] op_sel_hi:[0,1]
	v_pk_add_f32 v[38:39], v[24:25], v[38:39] op_sel_hi:[0,1]
	s_waitcnt lgkmcnt(0)
	v_pk_mul_f32 v[12:13], v[12:13], v[48:49]
	v_pk_mul_f32 v[38:39], v[38:39], v[50:51]
	s_mov_b64 s[0:1], -1
	s_and_b64 vcc, exec, s[50:51]
	s_cbranch_vccz .LBB0_548
	v_bfe_u32 v46, v15, 16, 1
	v_add3_u32 v47, v15, v46, s4
	v_bfe_u32 v46, v14, 16, 1
	v_bfe_u32 v48, v16, 16, 1
	v_bfe_u32 v50, v42, 16, 1
	v_bfe_u32 v34, v17, 16, 1
	v_bfe_u32 v49, v40, 16, 1
	v_add3_u32 v50, v42, v50, s4
	v_add3_u32 v48, v16, v48, s4
	v_add3_u32 v46, v14, v46, s4
	v_bfe_u32 v25, v43, 16, 1
	v_bfe_u32 v28, v41, 16, 1
	v_add3_u32 v34, v17, v34, s4
	v_add3_u32 v49, v40, v49, s4
	v_lshrrev_b32_e32 v51, 16, v46
	v_lshrrev_b32_e32 v52, 16, v48
	v_lshrrev_b32_e32 v48, 16, v50
	v_bfe_u32 v50, v11, 16, 1
	v_add3_u32 v28, v41, v28, s4
	v_add3_u32 v25, v43, v25, s4
	v_lshrrev_b32_e32 v46, 16, v49
	v_and_or_b32 v49, v34, s91, v52
	v_and_or_b32 v47, v47, s91, v51
	v_add3_u32 v51, v11, v50, s4
	v_bfe_u32 v50, v10, 16, 1
	v_bfe_u32 v52, v38, 16, 1
	v_bfe_u32 v53, v44, 16, 1
	v_bfe_u32 v54, v12, 16, 1
	v_lshl_add_u64 v[36:37], v[36:37], 1, s[70:71]
	v_and_or_b32 v48, v25, s91, v48
	v_and_or_b32 v46, v28, s91, v46
	v_bfe_u32 v25, v13, 16, 1
	v_bfe_u32 v28, v45, 16, 1
	v_bfe_u32 v34, v39, 16, 1
	v_add3_u32 v54, v12, v54, s4
	v_add3_u32 v53, v44, v53, s4
	v_add3_u32 v52, v38, v52, s4
	v_add3_u32 v50, v10, v50, s4
	v_add3_u32 v34, v39, v34, s4
	v_add3_u32 v28, v45, v28, s4
	v_add3_u32 v25, v13, v25, s4
	v_lshrrev_b32_e32 v55, 16, v50
	v_lshrrev_b32_e32 v56, 16, v52
	v_lshrrev_b32_e32 v50, 16, v53
	v_lshrrev_b32_e32 v52, 16, v54
	v_lshl_add_u64 v[32:33], v[32:33], 1, v[36:37]
	v_and_or_b32 v52, v25, s91, v52
	v_and_or_b32 v50, v28, s91, v50
	v_and_or_b32 v53, v34, s91, v56
	v_and_or_b32 v51, v51, s91, v55
	global_store_dwordx4 v[32:33], v[46:49], off
	global_store_dwordx4 v[32:33], v[50:53], off offset:16
	s_mov_b64 s[0:1], 0

.LBB0_560:
	s_or_b64 exec, exec, s[0:1]
	v_mov_b32_e32 v2, v142
	s_waitcnt lgkmcnt(0)
	s_barrier
	s_mov_b32 s41, s38
	v_and_b32_e32 v4, 0x1ff, v2
	v_lshlrev_b32_e32 v2, 5, v2
	v_and_or_b32 v2, v2, s34, v4
	v_ashrrev_i32_e32 v6, 5, v2
	v_lshlrev_b32_e32 v2, 3, v2
	v_lshlrev_b32_e32 v7, 3, v6
	v_add3_u32 v2, 0, v2, v7
	v_add_u32_e32 v143, 0x10800, v2
	ds_read_b64 v[128:129], v2
	ds_read_b64 v[130:131], v2 offset:4224
	ds_read_b64 v[144:145], v2 offset:8448
	ds_read_b64 v[148:149], v2 offset:12672
	ds_read_b64 v[150:151], v2 offset:16896
	ds_read_b64 v[152:153], v2 offset:21120
	ds_read_b64 v[154:155], v2 offset:25344
	ds_read_b64 v[156:157], v2 offset:29568
	ds_read_b64 v[158:159], v2 offset:33792
	ds_read_b64 v[160:161], v2 offset:38016
	ds_read_b64 v[162:163], v2 offset:42240
	ds_read_b64 v[164:165], v2 offset:46464
	ds_read_b64 v[166:167], v2 offset:50688
	ds_read_b64 v[168:169], v2 offset:54912
	ds_read_b64 v[170:171], v2 offset:59136
	ds_read_b64 v[172:173], v2 offset:63360
	v_add_u32_e32 v212, 0x11880, v2
	v_add_u32_e32 v213, 0x12900, v2
	v_add_u32_e32 v214, 0x13980, v2
	ds_read_b64 v[174:175], v143
	ds_read_b64 v[176:177], v212
	ds_read_b64 v[178:179], v213
	ds_read_b64 v[180:181], v214
	v_add_u32_e32 v215, 0x14a00, v2
	s_waitcnt lgkmcnt(3)
	v_pk_add_f32 v[210:211], v[128:129], v[174:175]
	v_pk_add_f32 v[128:129], v[128:129], v[174:175] neg_lo:[0,1] neg_hi:[0,1]
	s_waitcnt lgkmcnt(2)
	v_pk_add_f32 v[174:175], v[130:131], v[176:177]
	v_pk_add_f32 v[130:131], v[130:131], v[176:177] neg_lo:[0,1] neg_hi:[0,1]
	v_add_u32_e32 v216, 0x15a80, v2
	v_pk_mul_f32 v[176:177], v[130:131], s[20:21]
	v_add_u32_e32 v217, 0x16b00, v2
	v_pk_fma_f32 v[130:131], v[130:131], s[10:11], v[176:177] op_sel:[0,0,1] op_sel_hi:[1,0,0]
	s_waitcnt lgkmcnt(1)
	v_pk_add_f32 v[176:177], v[144:145], v[178:179]
	v_pk_add_f32 v[144:145], v[144:145], v[178:179] neg_lo:[0,1] neg_hi:[0,1]
	v_add_u32_e32 v218, 0x17b80, v2
	v_pk_mul_f32 v[178:179], v[144:145], s[24:25]
	ds_read_b64 v[182:183], v215
	ds_read_b64 v[184:185], v216
	ds_read_b64 v[186:187], v217
	ds_read_b64 v[188:189], v218
	v_pk_fma_f32 v[144:145], v[144:145], s[22:23], v[178:179] op_sel:[0,0,1] op_sel_hi:[1,0,0]
	s_waitcnt lgkmcnt(4)
	v_pk_add_f32 v[178:179], v[148:149], v[180:181]
	v_pk_add_f32 v[148:149], v[148:149], v[180:181] neg_lo:[0,1] neg_hi:[0,1]
	s_mov_b32 s43, s26
	v_pk_mul_f32 v[180:181], v[148:149], s[36:37]
	s_mov_b32 s0, s37
	v_pk_fma_f32 v[148:149], v[148:149], s[26:27], v[180:181] op_sel:[0,0,1] op_sel_hi:[1,0,0]
	s_waitcnt lgkmcnt(3)
	v_pk_add_f32 v[180:181], v[150:151], v[182:183]
	v_pk_add_f32 v[150:151], v[150:151], v[182:183] neg_lo:[0,1] neg_hi:[0,1]
	s_mov_b32 s45, s22
	v_pk_mul_f32 v[182:183], v[150:151], s[40:41]
	v_add_u32_e32 v219, 0x18c00, v2
	v_pk_fma_f32 v[150:151], v[150:151], s[38:39], v[182:183] op_sel:[0,0,1] op_sel_hi:[1,0,0]
	s_waitcnt lgkmcnt(2)
	v_pk_add_f32 v[182:183], v[152:153], v[184:185]
	v_pk_add_f32 v[152:153], v[152:153], v[184:185] neg_lo:[0,1] neg_hi:[0,1]
	s_mov_b32 s50, s25
	v_pk_mul_f32 v[184:185], v[152:153], s[42:43]
	v_add_u32_e32 v220, 0x19c80, v2
	v_pk_fma_f32 v[152:153], v[152:153], s[0:1], v[184:185] op_sel:[0,0,1] op_sel_hi:[1,0,0]
	s_waitcnt lgkmcnt(1)
	v_pk_add_f32 v[184:185], v[154:155], v[186:187]
	v_pk_add_f32 v[154:155], v[154:155], v[186:187] neg_lo:[0,1] neg_hi:[0,1]
	v_add_u32_e32 v221, 0x1ad00, v2
	v_pk_mul_f32 v[186:187], v[154:155], s[44:45]
	v_add_u32_e32 v222, 0x1bd80, v2
	ds_read_b64 v[190:191], v219
	ds_read_b64 v[192:193], v220
	ds_read_b64 v[194:195], v221
	ds_read_b64 v[196:197], v222
	v_pk_fma_f32 v[154:155], v[154:155], s[50:51], v[186:187] op_sel:[0,0,1] op_sel_hi:[1,0,0]
	s_waitcnt lgkmcnt(4)
	v_pk_add_f32 v[186:187], v[156:157], v[188:189]
	v_pk_add_f32 v[156:157], v[156:157], v[188:189] neg_lo:[0,1] neg_hi:[0,1]
	v_add_u32_e32 v223, 0x1ce00, v2
	v_pk_mul_f32 v[188:189], v[156:157], s[8:9]
	v_add_u32_e32 v224, 0x1de80, v2
	v_pk_fma_f32 v[156:157], v[156:157], s[16:17], v[188:189] op_sel:[0,0,1] op_sel_hi:[1,0,0]
	s_waitcnt lgkmcnt(3)
	v_pk_add_f32 v[188:189], v[158:159], v[190:191]
	v_pk_add_f32 v[190:191], v[158:159], v[190:191] neg_lo:[0,1] neg_hi:[0,1]
	v_add_u32_e32 v225, 0x1ef00, v2
	s_waitcnt lgkmcnt(2)
	v_pk_add_f32 v[158:159], v[160:161], v[192:193]
	v_pk_add_f32 v[160:161], v[160:161], v[192:193] neg_lo:[0,1] neg_hi:[0,1]
	v_add_u32_e32 v226, 0x1ff80, v2
	v_pk_mul_f32 v[192:193], v[160:161], s[8:9]
	ds_read_b64 v[198:199], v223
	ds_read_b64 v[204:205], v224
	ds_read_b64 v[206:207], v225
	ds_read_b64 v[208:209], v226
	v_pk_fma_f32 v[160:161], v[160:161], s[16:17], v[192:193] op_sel:[0,0,1] op_sel_hi:[1,0,0] neg_lo:[1,0,0] neg_hi:[1,0,0]
	s_waitcnt lgkmcnt(5)
	v_pk_add_f32 v[192:193], v[162:163], v[194:195]
	v_pk_add_f32 v[162:163], v[162:163], v[194:195] neg_lo:[0,1] neg_hi:[0,1]
	v_cvt_f32_u32_e32 v5, v4
	v_pk_mul_f32 v[194:195], v[162:163], s[44:45]
	v_mul_f32_e32 v5, 0x38800000, v5
	v_pk_fma_f32 v[162:163], v[162:163], s[50:51], v[194:195] op_sel:[0,0,1] op_sel_hi:[1,0,0] neg_lo:[1,0,0] neg_hi:[1,0,0]
	s_waitcnt lgkmcnt(4)
	v_pk_add_f32 v[194:195], v[164:165], v[196:197]
	v_pk_add_f32 v[164:165], v[164:165], v[196:197] neg_lo:[0,1] neg_hi:[0,1]
	v_sin_f32_e32 v4, v5
	v_pk_mul_f32 v[196:197], v[164:165], s[42:43]
	v_cos_f32_e32 v6, v5
	v_pk_fma_f32 v[164:165], v[164:165], s[0:1], v[196:197] op_sel:[0,0,1] op_sel_hi:[1,0,0] neg_lo:[1,0,0] neg_hi:[1,0,0]
	s_waitcnt lgkmcnt(3)
	v_pk_add_f32 v[196:197], v[166:167], v[198:199]
	v_pk_add_f32 v[166:167], v[166:167], v[198:199] neg_lo:[0,1] neg_hi:[0,1]
	v_xor_b32_e32 v7, 0x80000000, v4
	v_pk_mul_f32 v[198:199], v[166:167], s[40:41]
	v_mov_b32_e32 v5, v7
	v_pk_fma_f32 v[166:167], v[166:167], s[38:39], v[198:199] op_sel:[0,0,1] op_sel_hi:[1,0,0] neg_lo:[1,0,0] neg_hi:[1,0,0]
	s_waitcnt lgkmcnt(2)
	v_pk_add_f32 v[198:199], v[168:169], v[204:205]
	v_pk_add_f32 v[168:169], v[168:169], v[204:205] neg_lo:[0,1] neg_hi:[0,1]
	v_pk_mul_f32 v[8:9], v[6:7], v[4:5] op_sel:[1,0] op_sel_hi:[0,1]
	v_pk_mul_f32 v[204:205], v[168:169], s[36:37]
	v_pk_fma_f32 v[8:9], v[6:7], v[6:7], v[8:9] op_sel_hi:[1,0,1]
	v_pk_fma_f32 v[168:169], v[168:169], s[26:27], v[204:205] op_sel:[0,0,1] op_sel_hi:[1,0,0] neg_lo:[1,0,0] neg_hi:[1,0,0]
	s_waitcnt lgkmcnt(1)
	v_pk_add_f32 v[204:205], v[170:171], v[206:207]
	v_pk_add_f32 v[170:171], v[170:171], v[206:207] neg_lo:[0,1] neg_hi:[0,1]
	s_nop 0
	v_pk_mul_f32 v[206:207], v[170:171], s[24:25]
	s_nop 0
	v_pk_fma_f32 v[170:171], v[170:171], s[22:23], v[206:207] op_sel:[0,0,1] op_sel_hi:[1,0,0] neg_lo:[1,0,0] neg_hi:[1,0,0]
	s_waitcnt lgkmcnt(0)
	v_pk_add_f32 v[206:207], v[172:173], v[208:209]
	v_pk_add_f32 v[172:173], v[172:173], v[208:209] neg_lo:[0,1] neg_hi:[0,1]
	v_pk_mul_f32 v[12:13], v[8:9], v[8:9] op_sel:[1,1] op_sel_hi:[0,1] neg_lo:[0,1]
	v_pk_mul_f32 v[208:209], v[172:173], s[20:21]
	v_pk_fma_f32 v[12:13], v[8:9], v[8:9], v[12:13] op_sel_hi:[1,0,1]
	v_pk_fma_f32 v[172:173], v[172:173], s[10:11], v[208:209] op_sel:[0,0,1] op_sel_hi:[1,0,0] neg_lo:[1,0,0] neg_hi:[1,0,0]
	v_pk_add_f32 v[208:209], v[210:211], v[188:189]
	v_pk_add_f32 v[188:189], v[210:211], v[188:189] neg_lo:[0,1] neg_hi:[0,1]
	v_pk_add_f32 v[210:211], v[174:175], v[158:159]
	v_pk_add_f32 v[158:159], v[174:175], v[158:159] neg_lo:[0,1] neg_hi:[0,1]
	s_nop 0
	v_pk_mul_f32 v[174:175], v[158:159], s[24:25]
	s_nop 0
	v_pk_fma_f32 v[158:159], v[158:159], s[22:23], v[174:175] op_sel:[0,0,1] op_sel_hi:[1,0,0]
	v_pk_add_f32 v[174:175], v[176:177], v[192:193]
	v_pk_add_f32 v[176:177], v[176:177], v[192:193] neg_lo:[0,1] neg_hi:[0,1]
	v_pk_mul_f32 v[28:29], v[12:13], v[12:13] op_sel:[1,1] op_sel_hi:[0,1] neg_lo:[0,1]
	v_pk_mul_f32 v[192:193], v[176:177], s[40:41]
	v_pk_fma_f32 v[28:29], v[12:13], v[12:13], v[28:29] op_sel_hi:[1,0,1]
	v_pk_fma_f32 v[176:177], v[176:177], s[38:39], v[192:193] op_sel:[0,0,1] op_sel_hi:[1,0,0]
	v_pk_add_f32 v[192:193], v[178:179], v[194:195]
	v_pk_add_f32 v[178:179], v[178:179], v[194:195] neg_lo:[0,1] neg_hi:[0,1]
	v_pk_mul_f32 v[44:45], v[12:13], v[28:29] op_sel:[1,1] op_sel_hi:[1,0] neg_lo:[1,0]
	v_pk_mul_f32 v[194:195], v[178:179], s[44:45]
	v_pk_fma_f32 v[44:45], v[12:13], v[28:29], v[44:45] op_sel_hi:[0,1,1]
	v_pk_fma_f32 v[178:179], v[178:179], s[50:51], v[194:195] op_sel:[0,0,1] op_sel_hi:[1,0,0]
	v_pk_add_f32 v[194:195], v[180:181], v[196:197]
	v_pk_add_f32 v[196:197], v[180:181], v[196:197] neg_lo:[0,1] neg_hi:[0,1]
	v_pk_mul_f32 v[60:61], v[12:13], v[44:45] op_sel:[1,1] op_sel_hi:[1,0] neg_lo:[1,0]
	v_pk_add_f32 v[180:181], v[182:183], v[198:199]
	v_pk_add_f32 v[182:183], v[182:183], v[198:199] neg_lo:[0,1] neg_hi:[0,1]
	v_pk_fma_f32 v[60:61], v[12:13], v[44:45], v[60:61] op_sel_hi:[0,1,1]
	v_pk_mul_f32 v[198:199], v[182:183], s[44:45]
	v_pk_mul_f32 v[76:77], v[12:13], v[60:61] op_sel:[1,1] op_sel_hi:[1,0] neg_lo:[1,0]
	v_pk_fma_f32 v[182:183], v[182:183], s[50:51], v[198:199] op_sel:[0,0,1] op_sel_hi:[1,0,0] neg_lo:[1,0,0] neg_hi:[1,0,0]
	v_pk_add_f32 v[198:199], v[184:185], v[204:205]
	v_pk_add_f32 v[184:185], v[184:185], v[204:205] neg_lo:[0,1] neg_hi:[0,1]
	v_pk_fma_f32 v[76:77], v[12:13], v[60:61], v[76:77] op_sel_hi:[0,1,1]
	v_pk_mul_f32 v[204:205], v[184:185], s[40:41]
	v_pk_mul_f32 v[92:93], v[12:13], v[76:77] op_sel:[1,1] op_sel_hi:[1,0] neg_lo:[1,0]
	v_pk_fma_f32 v[184:185], v[184:185], s[38:39], v[204:205] op_sel:[0,0,1] op_sel_hi:[1,0,0] neg_lo:[1,0,0] neg_hi:[1,0,0]
	v_pk_add_f32 v[204:205], v[186:187], v[206:207]
	v_pk_add_f32 v[186:187], v[186:187], v[206:207] neg_lo:[0,1] neg_hi:[0,1]
	v_pk_fma_f32 v[92:93], v[12:13], v[76:77], v[92:93] op_sel_hi:[0,1,1]
	v_pk_mul_f32 v[206:207], v[186:187], s[24:25]
	v_pk_mul_f32 v[108:109], v[12:13], v[92:93] op_sel:[1,1] op_sel_hi:[1,0] neg_lo:[1,0]
	v_pk_fma_f32 v[186:187], v[186:187], s[22:23], v[206:207] op_sel:[0,0,1] op_sel_hi:[1,0,0] neg_lo:[1,0,0] neg_hi:[1,0,0]
	v_pk_add_f32 v[206:207], v[128:129], v[190:191] op_sel:[0,1] op_sel_hi:[1,0] neg_hi:[0,1]
	v_pk_add_f32 v[128:129], v[128:129], v[190:191] op_sel:[0,1] op_sel_hi:[1,0] neg_lo:[0,1]
	v_pk_add_f32 v[190:191], v[130:131], v[160:161]
	v_pk_add_f32 v[130:131], v[130:131], v[160:161] neg_lo:[0,1] neg_hi:[0,1]
	v_pk_mul_f32 v[10:11], v[4:5], v[8:9] op_sel:[0,1] op_sel_hi:[1,0]
	v_pk_mul_f32 v[160:161], v[130:131], s[24:25]
	v_pk_fma_f32 v[108:109], v[12:13], v[92:93], v[108:109] op_sel_hi:[0,1,1]
	v_pk_fma_f32 v[130:131], v[130:131], s[22:23], v[160:161] op_sel:[0,0,1] op_sel_hi:[1,0,0]
	v_pk_add_f32 v[160:161], v[144:145], v[162:163]
	v_pk_add_f32 v[144:145], v[144:145], v[162:163] neg_lo:[0,1] neg_hi:[0,1]
	v_pk_fma_f32 v[10:11], v[6:7], v[8:9], v[10:11] op_sel_hi:[0,1,1]
	v_pk_mul_f32 v[162:163], v[144:145], s[40:41]
	v_pk_mul_f32 v[18:19], v[4:5], v[12:13] op_sel:[0,1] op_sel_hi:[1,0]
	v_pk_fma_f32 v[144:145], v[144:145], s[38:39], v[162:163] op_sel:[0,0,1] op_sel_hi:[1,0,0]
	v_pk_add_f32 v[162:163], v[148:149], v[164:165]
	v_pk_add_f32 v[148:149], v[148:149], v[164:165] neg_lo:[0,1] neg_hi:[0,1]
	v_pk_mul_f32 v[32:33], v[4:5], v[28:29] op_sel:[0,1] op_sel_hi:[1,0]
	v_pk_mul_f32 v[164:165], v[148:149], s[44:45]
	v_pk_mul_f32 v[48:49], v[4:5], v[44:45] op_sel:[0,1] op_sel_hi:[1,0]
	v_pk_fma_f32 v[148:149], v[148:149], s[50:51], v[164:165] op_sel:[0,0,1] op_sel_hi:[1,0,0]
	v_pk_add_f32 v[164:165], v[150:151], v[166:167]
	v_pk_add_f32 v[166:167], v[150:151], v[166:167] neg_lo:[0,1] neg_hi:[0,1]
	v_pk_mul_f32 v[64:65], v[4:5], v[60:61] op_sel:[0,1] op_sel_hi:[1,0]
	v_pk_add_f32 v[150:151], v[152:153], v[168:169]
	v_pk_add_f32 v[152:153], v[152:153], v[168:169] neg_lo:[0,1] neg_hi:[0,1]
	v_pk_mul_f32 v[80:81], v[4:5], v[76:77] op_sel:[0,1] op_sel_hi:[1,0]
	v_pk_mul_f32 v[168:169], v[152:153], s[44:45]
	v_pk_mul_f32 v[96:97], v[4:5], v[92:93] op_sel:[0,1] op_sel_hi:[1,0]
	v_pk_fma_f32 v[152:153], v[152:153], s[50:51], v[168:169] op_sel:[0,0,1] op_sel_hi:[1,0,0] neg_lo:[1,0,0] neg_hi:[1,0,0]
	v_pk_add_f32 v[168:169], v[154:155], v[170:171]
	v_pk_add_f32 v[154:155], v[154:155], v[170:171] neg_lo:[0,1] neg_hi:[0,1]
	v_pk_mul_f32 v[112:113], v[4:5], v[108:109] op_sel:[0,1] op_sel_hi:[1,0]
	v_pk_mul_f32 v[170:171], v[154:155], s[40:41]
	s_nop 0
	v_pk_fma_f32 v[154:155], v[154:155], s[38:39], v[170:171] op_sel:[0,0,1] op_sel_hi:[1,0,0] neg_lo:[1,0,0] neg_hi:[1,0,0]
	v_pk_add_f32 v[170:171], v[156:157], v[172:173]
	v_pk_add_f32 v[156:157], v[156:157], v[172:173] neg_lo:[0,1] neg_hi:[0,1]
	s_nop 0
	v_pk_mul_f32 v[172:173], v[156:157], s[24:25]
	v_pk_fma_f32 v[18:19], v[6:7], v[12:13], v[18:19] op_sel_hi:[0,1,1]
	v_pk_fma_f32 v[156:157], v[156:157], s[22:23], v[172:173] op_sel:[0,0,1] op_sel_hi:[1,0,0] neg_lo:[1,0,0] neg_hi:[1,0,0]
	v_pk_add_f32 v[172:173], v[208:209], v[194:195]
	v_pk_add_f32 v[194:195], v[208:209], v[194:195] neg_lo:[0,1] neg_hi:[0,1]
	v_pk_add_f32 v[208:209], v[210:211], v[180:181]
	v_pk_add_f32 v[180:181], v[210:211], v[180:181] neg_lo:[0,1] neg_hi:[0,1]
	v_pk_mul_f32 v[20:21], v[8:9], v[12:13] op_sel:[1,1] op_sel_hi:[1,0] neg_lo:[1,0]
	v_pk_mul_f32 v[210:211], v[180:181], s[40:41]
	v_pk_fma_f32 v[32:33], v[6:7], v[28:29], v[32:33] op_sel_hi:[0,1,1]
	v_pk_fma_f32 v[180:181], v[180:181], s[38:39], v[210:211] op_sel:[0,0,1] op_sel_hi:[1,0,0]
	v_pk_add_f32 v[210:211], v[174:175], v[198:199]
	v_pk_add_f32 v[198:199], v[174:175], v[198:199] neg_lo:[0,1] neg_hi:[0,1]
	v_pk_mul_f32 v[36:37], v[8:9], v[28:29] op_sel:[1,1] op_sel_hi:[1,0] neg_lo:[1,0]
	v_pk_add_f32 v[174:175], v[192:193], v[204:205]
	v_pk_add_f32 v[192:193], v[192:193], v[204:205] neg_lo:[0,1] neg_hi:[0,1]
	v_pk_fma_f32 v[48:49], v[6:7], v[44:45], v[48:49] op_sel_hi:[0,1,1]
	v_pk_mul_f32 v[204:205], v[192:193], s[40:41]
	v_pk_mul_f32 v[52:53], v[8:9], v[44:45] op_sel:[1,1] op_sel_hi:[1,0] neg_lo:[1,0]
	v_pk_fma_f32 v[192:193], v[192:193], s[38:39], v[204:205] op_sel:[0,0,1] op_sel_hi:[1,0,0] neg_lo:[1,0,0] neg_hi:[1,0,0]
	v_pk_add_f32 v[204:205], v[188:189], v[196:197] op_sel:[0,1] op_sel_hi:[1,0] neg_hi:[0,1]
	v_pk_add_f32 v[188:189], v[188:189], v[196:197] op_sel:[0,1] op_sel_hi:[1,0] neg_lo:[0,1]
	v_pk_add_f32 v[196:197], v[158:159], v[182:183]
	v_pk_add_f32 v[158:159], v[158:159], v[182:183] neg_lo:[0,1] neg_hi:[0,1]
	v_pk_fma_f32 v[64:65], v[6:7], v[60:61], v[64:65] op_sel_hi:[0,1,1]
	v_pk_mul_f32 v[182:183], v[158:159], s[40:41]
	v_pk_mul_f32 v[68:69], v[8:9], v[60:61] op_sel:[1,1] op_sel_hi:[1,0] neg_lo:[1,0]
	v_pk_fma_f32 v[158:159], v[158:159], s[38:39], v[182:183] op_sel:[0,0,1] op_sel_hi:[1,0,0]
	v_pk_add_f32 v[182:183], v[176:177], v[184:185]
	v_pk_add_f32 v[184:185], v[176:177], v[184:185] neg_lo:[0,1] neg_hi:[0,1]
	v_pk_fma_f32 v[80:81], v[6:7], v[76:77], v[80:81] op_sel_hi:[0,1,1]
	v_pk_add_f32 v[176:177], v[178:179], v[186:187]
	v_pk_add_f32 v[178:179], v[178:179], v[186:187] neg_lo:[0,1] neg_hi:[0,1]
	v_pk_mul_f32 v[84:85], v[8:9], v[76:77] op_sel:[1,1] op_sel_hi:[1,0] neg_lo:[1,0]
	v_pk_mul_f32 v[186:187], v[178:179], s[40:41]
	v_pk_fma_f32 v[96:97], v[6:7], v[92:93], v[96:97] op_sel_hi:[0,1,1]
	v_pk_fma_f32 v[178:179], v[178:179], s[38:39], v[186:187] op_sel:[0,0,1] op_sel_hi:[1,0,0] neg_lo:[1,0,0] neg_hi:[1,0,0]
	v_pk_add_f32 v[186:187], v[206:207], v[164:165]
	v_pk_add_f32 v[164:165], v[206:207], v[164:165] neg_lo:[0,1] neg_hi:[0,1]
	v_pk_add_f32 v[206:207], v[190:191], v[150:151]
	v_pk_add_f32 v[150:151], v[190:191], v[150:151] neg_lo:[0,1] neg_hi:[0,1]
	v_pk_mul_f32 v[100:101], v[8:9], v[92:93] op_sel:[1,1] op_sel_hi:[1,0] neg_lo:[1,0]
	v_pk_mul_f32 v[190:191], v[150:151], s[40:41]
	v_pk_fma_f32 v[112:113], v[6:7], v[108:109], v[112:113] op_sel_hi:[0,1,1]
	v_pk_fma_f32 v[150:151], v[150:151], s[38:39], v[190:191] op_sel:[0,0,1] op_sel_hi:[1,0,0]
	v_pk_add_f32 v[190:191], v[160:161], v[168:169]
	v_pk_add_f32 v[168:169], v[160:161], v[168:169] neg_lo:[0,1] neg_hi:[0,1]
	v_pk_mul_f32 v[116:117], v[8:9], v[108:109] op_sel:[1,1] op_sel_hi:[1,0] neg_lo:[1,0]
	v_pk_add_f32 v[160:161], v[162:163], v[170:171]
	v_pk_add_f32 v[162:163], v[162:163], v[170:171] neg_lo:[0,1] neg_hi:[0,1]
	v_pk_fma_f32 v[20:21], v[8:9], v[12:13], v[20:21] op_sel_hi:[0,1,1]
	v_pk_mul_f32 v[170:171], v[162:163], s[40:41]
	v_pk_mul_f32 v[24:25], v[12:13], v[10:11] op_sel:[1,1] op_sel_hi:[0,1] neg_lo:[0,1]
	v_pk_fma_f32 v[162:163], v[162:163], s[38:39], v[170:171] op_sel:[0,0,1] op_sel_hi:[1,0,0] neg_lo:[1,0,0] neg_hi:[1,0,0]
	v_pk_add_f32 v[170:171], v[128:129], v[166:167] op_sel:[0,1] op_sel_hi:[1,0] neg_hi:[0,1]
	v_pk_add_f32 v[128:129], v[128:129], v[166:167] op_sel:[0,1] op_sel_hi:[1,0] neg_lo:[0,1]
	v_pk_add_f32 v[166:167], v[130:131], v[152:153]
	v_pk_add_f32 v[130:131], v[130:131], v[152:153] neg_lo:[0,1] neg_hi:[0,1]
	v_pk_fma_f32 v[36:37], v[8:9], v[28:29], v[36:37] op_sel_hi:[0,1,1]
	v_pk_mul_f32 v[152:153], v[130:131], s[40:41]
	v_pk_mul_f32 v[40:41], v[10:11], v[28:29] op_sel:[1,1] op_sel_hi:[1,0] neg_lo:[1,0]
	v_pk_fma_f32 v[130:131], v[130:131], s[38:39], v[152:153] op_sel:[0,0,1] op_sel_hi:[1,0,0]
	v_pk_add_f32 v[152:153], v[144:145], v[154:155]
	v_pk_add_f32 v[154:155], v[144:145], v[154:155] neg_lo:[0,1] neg_hi:[0,1]
	v_pk_fma_f32 v[52:53], v[8:9], v[44:45], v[52:53] op_sel_hi:[0,1,1]
	v_pk_add_f32 v[144:145], v[148:149], v[156:157]
	v_pk_add_f32 v[148:149], v[148:149], v[156:157] neg_lo:[0,1] neg_hi:[0,1]
	v_pk_mul_f32 v[56:57], v[10:11], v[44:45] op_sel:[1,1] op_sel_hi:[1,0] neg_lo:[1,0]
	v_pk_mul_f32 v[156:157], v[148:149], s[40:41]
	v_pk_fma_f32 v[68:69], v[8:9], v[60:61], v[68:69] op_sel_hi:[0,1,1]
	v_pk_fma_f32 v[148:149], v[148:149], s[38:39], v[156:157] op_sel:[0,0,1] op_sel_hi:[1,0,0] neg_lo:[1,0,0] neg_hi:[1,0,0]
	v_pk_add_f32 v[156:157], v[172:173], v[210:211]
	v_pk_add_f32 v[172:173], v[172:173], v[210:211] neg_lo:[0,1] neg_hi:[0,1]
	v_pk_add_f32 v[210:211], v[208:209], v[174:175]
	v_pk_add_f32 v[208:209], v[208:209], v[174:175] neg_lo:[0,1] neg_hi:[0,1]
	v_pk_mul_f32 v[72:73], v[10:11], v[60:61] op_sel:[1,1] op_sel_hi:[1,0] neg_lo:[1,0]
	v_pk_add_f32 v[174:175], v[194:195], v[198:199] op_sel:[0,1] op_sel_hi:[1,0] neg_hi:[0,1]
	v_pk_add_f32 v[194:195], v[194:195], v[198:199] op_sel:[0,1] op_sel_hi:[1,0] neg_lo:[0,1]
	v_pk_add_f32 v[198:199], v[180:181], v[192:193]
	v_pk_add_f32 v[192:193], v[180:181], v[192:193] neg_lo:[0,1] neg_hi:[0,1]
	v_pk_fma_f32 v[84:85], v[8:9], v[76:77], v[84:85] op_sel_hi:[0,1,1]
	v_pk_add_f32 v[180:181], v[204:205], v[182:183]
	v_pk_add_f32 v[182:183], v[204:205], v[182:183] neg_lo:[0,1] neg_hi:[0,1]
	v_pk_add_f32 v[204:205], v[196:197], v[176:177]
	v_pk_add_f32 v[196:197], v[196:197], v[176:177] neg_lo:[0,1] neg_hi:[0,1]
	v_pk_mul_f32 v[88:89], v[10:11], v[76:77] op_sel:[1,1] op_sel_hi:[1,0] neg_lo:[1,0]
	v_pk_add_f32 v[176:177], v[188:189], v[184:185] op_sel:[0,1] op_sel_hi:[1,0] neg_hi:[0,1]
	v_pk_add_f32 v[184:185], v[188:189], v[184:185] op_sel:[0,1] op_sel_hi:[1,0] neg_lo:[0,1]
	v_pk_add_f32 v[188:189], v[158:159], v[178:179]
	v_pk_add_f32 v[178:179], v[158:159], v[178:179] neg_lo:[0,1] neg_hi:[0,1]
	v_pk_fma_f32 v[100:101], v[8:9], v[92:93], v[100:101] op_sel_hi:[0,1,1]
	v_pk_add_f32 v[158:159], v[186:187], v[190:191]
	v_pk_add_f32 v[186:187], v[186:187], v[190:191] neg_lo:[0,1] neg_hi:[0,1]
	v_pk_add_f32 v[190:191], v[206:207], v[160:161]
	v_pk_add_f32 v[206:207], v[206:207], v[160:161] neg_lo:[0,1] neg_hi:[0,1]
	v_pk_mul_f32 v[104:105], v[10:11], v[92:93] op_sel:[1,1] op_sel_hi:[1,0] neg_lo:[1,0]
	v_pk_add_f32 v[160:161], v[164:165], v[168:169] op_sel:[0,1] op_sel_hi:[1,0] neg_hi:[0,1]
	v_pk_add_f32 v[164:165], v[164:165], v[168:169] op_sel:[0,1] op_sel_hi:[1,0] neg_lo:[0,1]
	v_pk_add_f32 v[168:169], v[150:151], v[162:163]
	v_pk_add_f32 v[162:163], v[150:151], v[162:163] neg_lo:[0,1] neg_hi:[0,1]
	v_pk_fma_f32 v[116:117], v[8:9], v[108:109], v[116:117] op_sel_hi:[0,1,1]
	v_pk_add_f32 v[150:151], v[170:171], v[152:153]
	v_pk_add_f32 v[152:153], v[170:171], v[152:153] neg_lo:[0,1] neg_hi:[0,1]
	v_pk_add_f32 v[170:171], v[166:167], v[144:145]
	v_pk_add_f32 v[166:167], v[166:167], v[144:145] neg_lo:[0,1] neg_hi:[0,1]
	v_pk_mul_f32 v[120:121], v[10:11], v[108:109] op_sel:[1,1] op_sel_hi:[1,0] neg_lo:[1,0]
	v_pk_add_f32 v[144:145], v[128:129], v[154:155] op_sel:[0,1] op_sel_hi:[1,0] neg_hi:[0,1]
	v_pk_add_f32 v[128:129], v[128:129], v[154:155] op_sel:[0,1] op_sel_hi:[1,0] neg_lo:[0,1]
	v_pk_add_f32 v[154:155], v[130:131], v[148:149]
	v_pk_add_f32 v[148:149], v[130:131], v[148:149] neg_lo:[0,1] neg_hi:[0,1]
	v_xor_b32_e32 v26, 0x80000000, v19
	v_pk_add_f32 v[130:131], v[156:157], v[210:211]
	v_pk_add_f32 v[156:157], v[156:157], v[210:211] neg_lo:[0,1] neg_hi:[0,1]
	v_pk_add_f32 v[210:211], v[172:173], v[208:209] op_sel:[0,1] op_sel_hi:[1,0] neg_hi:[0,1]
	v_pk_add_f32 v[172:173], v[172:173], v[208:209] op_sel:[0,1] op_sel_hi:[1,0] neg_lo:[0,1]
	v_pk_add_f32 v[208:209], v[174:175], v[198:199]
	v_pk_add_f32 v[174:175], v[174:175], v[198:199] neg_lo:[0,1] neg_hi:[0,1]
	v_pk_add_f32 v[198:199], v[194:195], v[192:193] op_sel:[0,1] op_sel_hi:[1,0] neg_hi:[0,1]
	v_pk_add_f32 v[192:193], v[194:195], v[192:193] op_sel:[0,1] op_sel_hi:[1,0] neg_lo:[0,1]
	v_pk_add_f32 v[194:195], v[180:181], v[204:205]
	v_pk_add_f32 v[180:181], v[180:181], v[204:205] neg_lo:[0,1] neg_hi:[0,1]
	v_pk_add_f32 v[204:205], v[182:183], v[196:197] op_sel:[0,1] op_sel_hi:[1,0] neg_hi:[0,1]
	v_pk_add_f32 v[182:183], v[182:183], v[196:197] op_sel:[0,1] op_sel_hi:[1,0] neg_lo:[0,1]
	v_pk_add_f32 v[196:197], v[176:177], v[188:189]
	v_pk_add_f32 v[176:177], v[176:177], v[188:189] neg_lo:[0,1] neg_hi:[0,1]
	v_pk_add_f32 v[188:189], v[184:185], v[178:179] op_sel:[0,1] op_sel_hi:[1,0] neg_hi:[0,1]
	v_pk_add_f32 v[178:179], v[184:185], v[178:179] op_sel:[0,1] op_sel_hi:[1,0] neg_lo:[0,1]
	v_pk_add_f32 v[184:185], v[158:159], v[190:191]
	v_pk_add_f32 v[158:159], v[158:159], v[190:191] neg_lo:[0,1] neg_hi:[0,1]
	v_pk_mul_f32 v[4:5], v[4:5], v[184:185] op_sel:[0,1] op_sel_hi:[1,0]
	v_pk_add_f32 v[190:191], v[186:187], v[206:207] op_sel:[0,1] op_sel_hi:[1,0] neg_hi:[0,1]
	v_pk_add_f32 v[186:187], v[186:187], v[206:207] op_sel:[0,1] op_sel_hi:[1,0] neg_lo:[0,1]
	v_pk_add_f32 v[206:207], v[160:161], v[168:169]
	v_pk_add_f32 v[160:161], v[160:161], v[168:169] neg_lo:[0,1] neg_hi:[0,1]
	v_pk_add_f32 v[168:169], v[164:165], v[162:163] op_sel:[0,1] op_sel_hi:[1,0] neg_hi:[0,1]
	v_pk_add_f32 v[162:163], v[164:165], v[162:163] op_sel:[0,1] op_sel_hi:[1,0] neg_lo:[0,1]
	v_pk_add_f32 v[164:165], v[150:151], v[170:171]
	v_pk_fma_f32 v[4:5], v[6:7], v[184:185], v[4:5] op_sel_hi:[0,1,1]
	v_pk_mul_f32 v[6:7], v[8:9], v[194:195] op_sel:[1,1] op_sel_hi:[1,0] neg_lo:[1,0]
	v_xor_b32_e32 v30, 0x80000000, v21
	v_pk_fma_f32 v[6:7], v[8:9], v[194:195], v[6:7] op_sel_hi:[0,1,1]
	v_pk_mul_f32 v[8:9], v[10:11], v[164:165] op_sel:[1,1] op_sel_hi:[1,0] neg_lo:[1,0]
	v_pk_fma_f32 v[24:25], v[12:13], v[10:11], v[24:25] op_sel_hi:[1,0,1]
	v_pk_fma_f32 v[40:41], v[10:11], v[28:29], v[40:41] op_sel_hi:[0,1,1]
	v_pk_fma_f32 v[56:57], v[10:11], v[44:45], v[56:57] op_sel_hi:[0,1,1]
	v_pk_fma_f32 v[72:73], v[10:11], v[60:61], v[72:73] op_sel_hi:[0,1,1]
	v_pk_fma_f32 v[88:89], v[10:11], v[76:77], v[88:89] op_sel_hi:[0,1,1]
	v_pk_fma_f32 v[104:105], v[10:11], v[92:93], v[104:105] op_sel_hi:[0,1,1]
	v_pk_fma_f32 v[120:121], v[10:11], v[108:109], v[120:121] op_sel_hi:[0,1,1]
	v_mov_b32_e32 v27, v19
	v_mov_b32_e32 v31, v21
	v_pk_fma_f32 v[8:9], v[10:11], v[164:165], v[8:9] op_sel_hi:[0,1,1]
	v_pk_mul_f32 v[10:11], v[12:13], v[208:209] op_sel:[1,1] op_sel_hi:[1,0] neg_lo:[1,0]
	v_pk_add_f32 v[150:151], v[150:151], v[170:171] neg_lo:[0,1] neg_hi:[0,1]
	v_pk_add_f32 v[170:171], v[152:153], v[166:167] op_sel:[0,1] op_sel_hi:[1,0] neg_hi:[0,1]
	v_pk_add_f32 v[152:153], v[152:153], v[166:167] op_sel:[0,1] op_sel_hi:[1,0] neg_lo:[0,1]
	v_pk_add_f32 v[166:167], v[144:145], v[154:155]
	v_pk_fma_f32 v[10:11], v[12:13], v[208:209], v[10:11] op_sel_hi:[0,1,1]
	v_pk_mul_f32 v[12:13], v[26:27], v[206:207] op_sel:[0,1] op_sel_hi:[1,0]
	v_pk_mul_f32 v[14:15], v[30:31], v[196:197] op_sel:[0,1] op_sel_hi:[1,0]
	v_pk_add_f32 v[144:145], v[144:145], v[154:155] neg_lo:[0,1] neg_hi:[0,1]
	v_pk_add_f32 v[154:155], v[128:129], v[148:149] op_sel:[0,1] op_sel_hi:[1,0] neg_hi:[0,1]
	v_pk_fma_f32 v[12:13], v[18:19], v[206:207], v[12:13] op_sel_hi:[0,1,1]
	v_pk_fma_f32 v[14:15], v[20:21], v[196:197], v[14:15] op_sel_hi:[0,1,1]
	v_pk_mul_f32 v[16:17], v[24:25], v[166:167] op_sel:[1,1] op_sel_hi:[1,0] neg_lo:[1,0]
	v_pk_mul_f32 v[18:19], v[28:29], v[210:211] op_sel:[1,1] op_sel_hi:[1,0] neg_lo:[1,0]
	v_pk_mul_f32 v[20:21], v[32:33], v[190:191] op_sel:[1,1] op_sel_hi:[1,0] neg_lo:[1,0]
	v_pk_mul_f32 v[22:23], v[36:37], v[204:205] op_sel:[1,1] op_sel_hi:[1,0] neg_lo:[1,0]
	v_xor_b32_e32 v78, 0x80000000, v69
	v_xor_b32_e32 v82, 0x80000000, v73
	v_xor_b32_e32 v86, 0x80000000, v77
	v_xor_b32_e32 v90, 0x80000000, v81
	v_xor_b32_e32 v94, 0x80000000, v85
	v_xor_b32_e32 v98, 0x80000000, v89
	v_xor_b32_e32 v102, 0x80000000, v93
	v_xor_b32_e32 v106, 0x80000000, v97
	v_xor_b32_e32 v110, 0x80000000, v101
	v_xor_b32_e32 v114, 0x80000000, v105
	v_xor_b32_e32 v118, 0x80000000, v109
	v_xor_b32_e32 v122, 0x80000000, v113
	v_xor_b32_e32 v124, 0x80000000, v117
	v_xor_b32_e32 v126, 0x80000000, v121
	v_mov_b32_e32 v79, v69
	v_mov_b32_e32 v83, v73
	v_mov_b32_e32 v87, v77
	v_mov_b32_e32 v91, v81
	v_mov_b32_e32 v95, v85
	v_mov_b32_e32 v99, v89
	v_mov_b32_e32 v103, v93
	v_mov_b32_e32 v107, v97
	v_mov_b32_e32 v111, v101
	v_mov_b32_e32 v115, v105
	v_mov_b32_e32 v119, v109
	v_mov_b32_e32 v123, v113
	v_mov_b32_e32 v125, v117
	v_mov_b32_e32 v127, v121
	v_pk_add_f32 v[128:129], v[128:129], v[148:149] op_sel:[0,1] op_sel_hi:[1,0] neg_lo:[0,1]
	v_pk_fma_f32 v[16:17], v[24:25], v[166:167], v[16:17] op_sel_hi:[0,1,1]
	v_pk_fma_f32 v[18:19], v[28:29], v[210:211], v[18:19] op_sel_hi:[0,1,1]
	v_pk_fma_f32 v[20:21], v[32:33], v[190:191], v[20:21] op_sel_hi:[0,1,1]
	v_pk_fma_f32 v[22:23], v[36:37], v[204:205], v[22:23] op_sel_hi:[0,1,1]
	v_pk_mul_f32 v[24:25], v[40:41], v[170:171] op_sel:[1,1] op_sel_hi:[1,0] neg_lo:[1,0]
	v_pk_mul_f32 v[26:27], v[44:45], v[198:199] op_sel:[1,1] op_sel_hi:[1,0] neg_lo:[1,0]
	v_pk_mul_f32 v[28:29], v[48:49], v[168:169] op_sel:[1,1] op_sel_hi:[1,0] neg_lo:[1,0]
	v_pk_mul_f32 v[30:31], v[52:53], v[188:189] op_sel:[1,1] op_sel_hi:[1,0] neg_lo:[1,0]
	v_pk_mul_f32 v[32:33], v[56:57], v[154:155] op_sel:[1,1] op_sel_hi:[1,0] neg_lo:[1,0]
	v_pk_mul_f32 v[34:35], v[60:61], v[156:157] op_sel:[1,1] op_sel_hi:[1,0] neg_lo:[1,0]
	v_pk_mul_f32 v[36:37], v[64:65], v[158:159] op_sel:[1,1] op_sel_hi:[1,0] neg_lo:[1,0]
	v_pk_fma_f32 v[24:25], v[40:41], v[170:171], v[24:25] op_sel_hi:[0,1,1]
	v_pk_fma_f32 v[26:27], v[44:45], v[198:199], v[26:27] op_sel_hi:[0,1,1]
	v_pk_fma_f32 v[28:29], v[48:49], v[168:169], v[28:29] op_sel_hi:[0,1,1]
	v_pk_fma_f32 v[30:31], v[52:53], v[188:189], v[30:31] op_sel_hi:[0,1,1]
	v_pk_fma_f32 v[32:33], v[56:57], v[154:155], v[32:33] op_sel_hi:[0,1,1]
	v_pk_fma_f32 v[34:35], v[60:61], v[156:157], v[34:35] op_sel_hi:[0,1,1]
	v_pk_fma_f32 v[36:37], v[64:65], v[158:159], v[36:37] op_sel_hi:[0,1,1]
	v_pk_mul_f32 v[38:39], v[78:79], v[180:181] op_sel:[0,1] op_sel_hi:[1,0]
	v_pk_mul_f32 v[40:41], v[82:83], v[150:151] op_sel:[0,1] op_sel_hi:[1,0]
	v_pk_mul_f32 v[42:43], v[86:87], v[174:175] op_sel:[0,1] op_sel_hi:[1,0]
	v_pk_mul_f32 v[44:45], v[90:91], v[160:161] op_sel:[0,1] op_sel_hi:[1,0]
	v_pk_mul_f32 v[46:47], v[94:95], v[176:177] op_sel:[0,1] op_sel_hi:[1,0]
	v_pk_mul_f32 v[48:49], v[98:99], v[144:145] op_sel:[0,1] op_sel_hi:[1,0]
	v_pk_mul_f32 v[50:51], v[102:103], v[172:173] op_sel:[0,1] op_sel_hi:[1,0]
	v_pk_mul_f32 v[52:53], v[106:107], v[186:187] op_sel:[0,1] op_sel_hi:[1,0]
	v_pk_mul_f32 v[54:55], v[110:111], v[182:183] op_sel:[0,1] op_sel_hi:[1,0]
	v_pk_mul_f32 v[56:57], v[114:115], v[152:153] op_sel:[0,1] op_sel_hi:[1,0]
	v_pk_mul_f32 v[58:59], v[118:119], v[192:193] op_sel:[0,1] op_sel_hi:[1,0]
	v_pk_mul_f32 v[60:61], v[122:123], v[162:163] op_sel:[0,1] op_sel_hi:[1,0]
	v_pk_mul_f32 v[62:63], v[124:125], v[178:179] op_sel:[0,1] op_sel_hi:[1,0]
	v_pk_mul_f32 v[64:65], v[126:127], v[128:129] op_sel:[0,1] op_sel_hi:[1,0]
	v_pk_fma_f32 v[38:39], v[68:69], v[180:181], v[38:39] op_sel_hi:[0,1,1]
	v_pk_fma_f32 v[40:41], v[72:73], v[150:151], v[40:41] op_sel_hi:[0,1,1]
	v_pk_fma_f32 v[42:43], v[76:77], v[174:175], v[42:43] op_sel_hi:[0,1,1]
	v_pk_fma_f32 v[44:45], v[80:81], v[160:161], v[44:45] op_sel_hi:[0,1,1]
	v_pk_fma_f32 v[46:47], v[84:85], v[176:177], v[46:47] op_sel_hi:[0,1,1]
	v_pk_fma_f32 v[48:49], v[88:89], v[144:145], v[48:49] op_sel_hi:[0,1,1]
	v_pk_fma_f32 v[50:51], v[92:93], v[172:173], v[50:51] op_sel_hi:[0,1,1]
	v_pk_fma_f32 v[52:53], v[96:97], v[186:187], v[52:53] op_sel_hi:[0,1,1]
	v_pk_fma_f32 v[54:55], v[100:101], v[182:183], v[54:55] op_sel_hi:[0,1,1]
	v_pk_fma_f32 v[56:57], v[104:105], v[152:153], v[56:57] op_sel_hi:[0,1,1]
	v_pk_fma_f32 v[58:59], v[108:109], v[192:193], v[58:59] op_sel_hi:[0,1,1]
	v_pk_fma_f32 v[60:61], v[112:113], v[162:163], v[60:61] op_sel_hi:[0,1,1]
	v_pk_fma_f32 v[62:63], v[116:117], v[178:179], v[62:63] op_sel_hi:[0,1,1]
	v_pk_fma_f32 v[64:65], v[120:121], v[128:129], v[64:65] op_sel_hi:[0,1,1]
	ds_write_b64 v2, v[130:131]
	ds_write_b64 v2, v[34:35] offset:4224
	ds_write_b64 v2, v[18:19] offset:8448
	ds_write_b64 v2, v[50:51] offset:12672
	ds_write_b64 v2, v[10:11] offset:16896
	ds_write_b64 v2, v[42:43] offset:21120
	ds_write_b64 v2, v[26:27] offset:25344
	ds_write_b64 v2, v[58:59] offset:29568
	ds_write_b64 v2, v[6:7] offset:33792
	ds_write_b64 v2, v[38:39] offset:38016
	ds_write_b64 v2, v[22:23] offset:42240
	ds_write_b64 v2, v[54:55] offset:46464
	ds_write_b64 v2, v[14:15] offset:50688
	ds_write_b64 v2, v[46:47] offset:54912
	ds_write_b64 v2, v[30:31] offset:59136
	ds_write_b64 v2, v[62:63] offset:63360
	ds_write_b64 v143, v[4:5]
	ds_write_b64 v212, v[36:37]
	ds_write_b64 v213, v[20:21]
	ds_write_b64 v214, v[52:53]
	ds_write_b64 v215, v[12:13]
	ds_write_b64 v216, v[44:45]
	ds_write_b64 v217, v[28:29]
	ds_write_b64 v218, v[60:61]
	ds_write_b64 v219, v[8:9]
	ds_write_b64 v220, v[40:41]
	ds_write_b64 v221, v[24:25]
	ds_write_b64 v222, v[56:57]
	ds_write_b64 v223, v[16:17]
	ds_write_b64 v224, v[48:49]
	ds_write_b64 v225, v[32:33]
	ds_write_b64 v226, v[64:65]
	v_mov_b32_e32 v2, v142
	s_waitcnt lgkmcnt(0)
	s_barrier
	s_nop 0
	v_and_b32_e32 v4, 15, v2
	v_lshlrev_b32_e32 v2, 5, v2
	v_and_b32_e32 v2, 0xfffffe00, v2
	v_lshl_add_u32 v5, v2, 3, 0
	v_lshlrev_b32_e32 v7, 3, v4
	v_ashrrev_i32_e32 v2, 2, v2
	v_add3_u32 v2, v5, v7, v2
	v_add_u32_e32 v143, 0x800, v2
	ds_read2_b64 v[128:131], v2 offset1:16
	ds_read2_b64 v[148:151], v2 offset0:33 offset1:49
	ds_read2_b64 v[152:155], v2 offset0:66 offset1:82
	ds_read2_b64 v[156:159], v2 offset0:99 offset1:115
	ds_read2_b64 v[160:163], v2 offset0:132 offset1:148
	ds_read2_b64 v[164:167], v2 offset0:165 offset1:181
	ds_read2_b64 v[168:171], v2 offset0:198 offset1:214
	ds_read2_b64 v[172:175], v2 offset0:231 offset1:247
	ds_read2_b64 v[176:179], v143 offset0:8 offset1:24
	ds_read2_b64 v[180:183], v143 offset0:41 offset1:57
	ds_read2_b64 v[184:187], v143 offset0:74 offset1:90
	ds_read2_b64 v[188:191], v143 offset0:107 offset1:123
	ds_read2_b64 v[192:195], v143 offset0:140 offset1:156
	ds_read2_b64 v[196:199], v143 offset0:173 offset1:189
	ds_read2_b64 v[204:207], v143 offset0:206 offset1:222
	ds_read2_b64 v[208:211], v143 offset0:239 offset1:255
	s_waitcnt lgkmcnt(7)
	v_pk_add_f32 v[144:145], v[128:129], v[176:177]
	v_pk_add_f32 v[128:129], v[128:129], v[176:177] neg_lo:[0,1] neg_hi:[0,1]
	v_pk_add_f32 v[176:177], v[130:131], v[178:179]
	v_pk_add_f32 v[130:131], v[130:131], v[178:179] neg_lo:[0,1] neg_hi:[0,1]
	v_cvt_f32_ubyte0_e32 v4, v4
	v_pk_mul_f32 v[178:179], v[130:131], s[20:21]
	v_mul_f32_e32 v6, 0x3b000000, v4
	v_pk_fma_f32 v[130:131], v[130:131], s[10:11], v[178:179] op_sel:[0,0,1] op_sel_hi:[1,0,0]
	s_waitcnt lgkmcnt(6)
	v_pk_add_f32 v[178:179], v[148:149], v[180:181]
	v_pk_add_f32 v[148:149], v[148:149], v[180:181] neg_lo:[0,1] neg_hi:[0,1]
	v_sin_f32_e32 v4, v6
	v_pk_mul_f32 v[180:181], v[148:149], s[24:25]
	v_cos_f32_e32 v6, v6
	v_pk_fma_f32 v[148:149], v[148:149], s[22:23], v[180:181] op_sel:[0,0,1] op_sel_hi:[1,0,0]
	v_pk_add_f32 v[180:181], v[150:151], v[182:183]
	v_pk_add_f32 v[150:151], v[150:151], v[182:183] neg_lo:[0,1] neg_hi:[0,1]
	v_xor_b32_e32 v7, 0x80000000, v4
	v_pk_mul_f32 v[182:183], v[150:151], s[36:37]
	v_mov_b32_e32 v5, v7
	v_pk_fma_f32 v[150:151], v[150:151], s[26:27], v[182:183] op_sel:[0,0,1] op_sel_hi:[1,0,0]
	s_waitcnt lgkmcnt(5)
	v_pk_add_f32 v[182:183], v[152:153], v[184:185]
	v_pk_add_f32 v[152:153], v[152:153], v[184:185] neg_lo:[0,1] neg_hi:[0,1]
	v_pk_mul_f32 v[8:9], v[6:7], v[4:5] op_sel:[1,0] op_sel_hi:[0,1]
	v_pk_mul_f32 v[184:185], v[152:153], s[40:41]
	v_pk_fma_f32 v[8:9], v[6:7], v[6:7], v[8:9] op_sel_hi:[1,0,1]
	v_pk_fma_f32 v[152:153], v[152:153], s[38:39], v[184:185] op_sel:[0,0,1] op_sel_hi:[1,0,0]
	v_pk_add_f32 v[184:185], v[154:155], v[186:187]
	v_pk_add_f32 v[154:155], v[154:155], v[186:187] neg_lo:[0,1] neg_hi:[0,1]
	s_nop 0
	v_pk_mul_f32 v[186:187], v[154:155], s[42:43]
	s_nop 0
	v_pk_fma_f32 v[154:155], v[154:155], s[0:1], v[186:187] op_sel:[0,0,1] op_sel_hi:[1,0,0]
	s_waitcnt lgkmcnt(4)
	v_pk_add_f32 v[186:187], v[156:157], v[188:189]
	v_pk_add_f32 v[156:157], v[156:157], v[188:189] neg_lo:[0,1] neg_hi:[0,1]
	v_pk_mul_f32 v[12:13], v[8:9], v[8:9] op_sel:[1,1] op_sel_hi:[0,1] neg_lo:[0,1]
	v_pk_mul_f32 v[188:189], v[156:157], s[44:45]
	v_pk_fma_f32 v[12:13], v[8:9], v[8:9], v[12:13] op_sel_hi:[1,0,1]
	v_pk_fma_f32 v[156:157], v[156:157], s[50:51], v[188:189] op_sel:[0,0,1] op_sel_hi:[1,0,0]
	v_pk_add_f32 v[188:189], v[158:159], v[190:191]
	v_pk_add_f32 v[158:159], v[158:159], v[190:191] neg_lo:[0,1] neg_hi:[0,1]
	s_nop 0
	v_pk_mul_f32 v[190:191], v[158:159], s[8:9]
	s_nop 0
	v_pk_fma_f32 v[158:159], v[158:159], s[16:17], v[190:191] op_sel:[0,0,1] op_sel_hi:[1,0,0]
	s_waitcnt lgkmcnt(3)
	v_pk_add_f32 v[190:191], v[160:161], v[192:193]
	v_pk_add_f32 v[192:193], v[160:161], v[192:193] neg_lo:[0,1] neg_hi:[0,1]
	v_pk_mul_f32 v[28:29], v[12:13], v[12:13] op_sel:[1,1] op_sel_hi:[0,1] neg_lo:[0,1]
	v_pk_add_f32 v[160:161], v[162:163], v[194:195]
	v_pk_add_f32 v[162:163], v[162:163], v[194:195] neg_lo:[0,1] neg_hi:[0,1]
	v_pk_fma_f32 v[28:29], v[12:13], v[12:13], v[28:29] op_sel_hi:[1,0,1]
	v_pk_mul_f32 v[194:195], v[162:163], s[8:9]
	v_pk_mul_f32 v[44:45], v[12:13], v[28:29] op_sel:[1,1] op_sel_hi:[1,0] neg_lo:[1,0]
	v_pk_fma_f32 v[162:163], v[162:163], s[16:17], v[194:195] op_sel:[0,0,1] op_sel_hi:[1,0,0] neg_lo:[1,0,0] neg_hi:[1,0,0]
	s_waitcnt lgkmcnt(2)
	v_pk_add_f32 v[194:195], v[164:165], v[196:197]
	v_pk_add_f32 v[164:165], v[164:165], v[196:197] neg_lo:[0,1] neg_hi:[0,1]
	v_pk_fma_f32 v[44:45], v[12:13], v[28:29], v[44:45] op_sel_hi:[0,1,1]
	v_pk_mul_f32 v[196:197], v[164:165], s[44:45]
	v_pk_mul_f32 v[60:61], v[12:13], v[44:45] op_sel:[1,1] op_sel_hi:[1,0] neg_lo:[1,0]
	v_pk_fma_f32 v[164:165], v[164:165], s[50:51], v[196:197] op_sel:[0,0,1] op_sel_hi:[1,0,0] neg_lo:[1,0,0] neg_hi:[1,0,0]
	v_pk_add_f32 v[196:197], v[166:167], v[198:199]
	v_pk_add_f32 v[166:167], v[166:167], v[198:199] neg_lo:[0,1] neg_hi:[0,1]
	v_pk_fma_f32 v[60:61], v[12:13], v[44:45], v[60:61] op_sel_hi:[0,1,1]
	v_pk_mul_f32 v[198:199], v[166:167], s[42:43]
	v_pk_mul_f32 v[76:77], v[12:13], v[60:61] op_sel:[1,1] op_sel_hi:[1,0] neg_lo:[1,0]
	v_pk_fma_f32 v[166:167], v[166:167], s[0:1], v[198:199] op_sel:[0,0,1] op_sel_hi:[1,0,0] neg_lo:[1,0,0] neg_hi:[1,0,0]
	s_waitcnt lgkmcnt(1)
	v_pk_add_f32 v[198:199], v[168:169], v[204:205]
	v_pk_add_f32 v[168:169], v[168:169], v[204:205] neg_lo:[0,1] neg_hi:[0,1]
	v_pk_fma_f32 v[76:77], v[12:13], v[60:61], v[76:77] op_sel_hi:[0,1,1]
	v_pk_mul_f32 v[204:205], v[168:169], s[40:41]
	v_pk_mul_f32 v[92:93], v[12:13], v[76:77] op_sel:[1,1] op_sel_hi:[1,0] neg_lo:[1,0]
	v_pk_fma_f32 v[168:169], v[168:169], s[38:39], v[204:205] op_sel:[0,0,1] op_sel_hi:[1,0,0] neg_lo:[1,0,0] neg_hi:[1,0,0]
	v_pk_add_f32 v[204:205], v[170:171], v[206:207]
	v_pk_add_f32 v[170:171], v[170:171], v[206:207] neg_lo:[0,1] neg_hi:[0,1]
	v_pk_fma_f32 v[92:93], v[12:13], v[76:77], v[92:93] op_sel_hi:[0,1,1]
	v_pk_mul_f32 v[206:207], v[170:171], s[36:37]
	v_pk_mul_f32 v[108:109], v[12:13], v[92:93] op_sel:[1,1] op_sel_hi:[1,0] neg_lo:[1,0]
	v_pk_fma_f32 v[170:171], v[170:171], s[26:27], v[206:207] op_sel:[0,0,1] op_sel_hi:[1,0,0] neg_lo:[1,0,0] neg_hi:[1,0,0]
	s_waitcnt lgkmcnt(0)
	v_pk_add_f32 v[206:207], v[172:173], v[208:209]
	v_pk_add_f32 v[172:173], v[172:173], v[208:209] neg_lo:[0,1] neg_hi:[0,1]
	v_pk_mul_f32 v[10:11], v[4:5], v[8:9] op_sel:[0,1] op_sel_hi:[1,0]
	v_pk_mul_f32 v[208:209], v[172:173], s[24:25]
	v_pk_fma_f32 v[108:109], v[12:13], v[92:93], v[108:109] op_sel_hi:[0,1,1]
	v_pk_fma_f32 v[172:173], v[172:173], s[22:23], v[208:209] op_sel:[0,0,1] op_sel_hi:[1,0,0] neg_lo:[1,0,0] neg_hi:[1,0,0]
	v_pk_add_f32 v[208:209], v[174:175], v[210:211]
	v_pk_add_f32 v[174:175], v[174:175], v[210:211] neg_lo:[0,1] neg_hi:[0,1]
	v_pk_fma_f32 v[10:11], v[6:7], v[8:9], v[10:11] op_sel_hi:[0,1,1]
	v_pk_mul_f32 v[210:211], v[174:175], s[20:21]
	v_pk_mul_f32 v[18:19], v[4:5], v[12:13] op_sel:[0,1] op_sel_hi:[1,0]
	v_pk_fma_f32 v[174:175], v[174:175], s[10:11], v[210:211] op_sel:[0,0,1] op_sel_hi:[1,0,0] neg_lo:[1,0,0] neg_hi:[1,0,0]
	v_pk_add_f32 v[210:211], v[144:145], v[190:191]
	v_pk_add_f32 v[144:145], v[144:145], v[190:191] neg_lo:[0,1] neg_hi:[0,1]
	v_pk_add_f32 v[190:191], v[176:177], v[160:161]
	v_pk_add_f32 v[160:161], v[176:177], v[160:161] neg_lo:[0,1] neg_hi:[0,1]
	v_pk_mul_f32 v[32:33], v[4:5], v[28:29] op_sel:[0,1] op_sel_hi:[1,0]
	v_pk_mul_f32 v[176:177], v[160:161], s[24:25]
	v_pk_mul_f32 v[48:49], v[4:5], v[44:45] op_sel:[0,1] op_sel_hi:[1,0]
	v_pk_fma_f32 v[160:161], v[160:161], s[22:23], v[176:177] op_sel:[0,0,1] op_sel_hi:[1,0,0]
	v_pk_add_f32 v[176:177], v[178:179], v[194:195]
	v_pk_add_f32 v[178:179], v[178:179], v[194:195] neg_lo:[0,1] neg_hi:[0,1]
	v_pk_mul_f32 v[64:65], v[4:5], v[60:61] op_sel:[0,1] op_sel_hi:[1,0]
	v_pk_mul_f32 v[194:195], v[178:179], s[40:41]
	v_pk_mul_f32 v[80:81], v[4:5], v[76:77] op_sel:[0,1] op_sel_hi:[1,0]
	v_pk_fma_f32 v[178:179], v[178:179], s[38:39], v[194:195] op_sel:[0,0,1] op_sel_hi:[1,0,0]
	v_pk_add_f32 v[194:195], v[180:181], v[196:197]
	v_pk_add_f32 v[180:181], v[180:181], v[196:197] neg_lo:[0,1] neg_hi:[0,1]
	v_pk_mul_f32 v[96:97], v[4:5], v[92:93] op_sel:[0,1] op_sel_hi:[1,0]
	v_pk_mul_f32 v[196:197], v[180:181], s[44:45]
	v_pk_mul_f32 v[112:113], v[4:5], v[108:109] op_sel:[0,1] op_sel_hi:[1,0]
	v_pk_fma_f32 v[180:181], v[180:181], s[50:51], v[196:197] op_sel:[0,0,1] op_sel_hi:[1,0,0]
	v_pk_add_f32 v[196:197], v[182:183], v[198:199]
	v_pk_add_f32 v[198:199], v[182:183], v[198:199] neg_lo:[0,1] neg_hi:[0,1]
	v_pk_add_f32 v[182:183], v[184:185], v[204:205]
	v_pk_add_f32 v[184:185], v[184:185], v[204:205] neg_lo:[0,1] neg_hi:[0,1]
	s_nop 0
	v_pk_mul_f32 v[204:205], v[184:185], s[44:45]
	v_pk_fma_f32 v[18:19], v[6:7], v[12:13], v[18:19] op_sel_hi:[0,1,1]
	v_pk_fma_f32 v[184:185], v[184:185], s[50:51], v[204:205] op_sel:[0,0,1] op_sel_hi:[1,0,0] neg_lo:[1,0,0] neg_hi:[1,0,0]
	v_pk_add_f32 v[204:205], v[186:187], v[206:207]
	v_pk_add_f32 v[186:187], v[186:187], v[206:207] neg_lo:[0,1] neg_hi:[0,1]
	v_pk_mul_f32 v[20:21], v[8:9], v[12:13] op_sel:[1,1] op_sel_hi:[1,0] neg_lo:[1,0]
	v_pk_mul_f32 v[206:207], v[186:187], s[40:41]
	v_pk_fma_f32 v[32:33], v[6:7], v[28:29], v[32:33] op_sel_hi:[0,1,1]
	v_pk_fma_f32 v[186:187], v[186:187], s[38:39], v[206:207] op_sel:[0,0,1] op_sel_hi:[1,0,0] neg_lo:[1,0,0] neg_hi:[1,0,0]
	v_pk_add_f32 v[206:207], v[188:189], v[208:209]
	v_pk_add_f32 v[188:189], v[188:189], v[208:209] neg_lo:[0,1] neg_hi:[0,1]
	v_pk_mul_f32 v[36:37], v[8:9], v[28:29] op_sel:[1,1] op_sel_hi:[1,0] neg_lo:[1,0]
	v_pk_mul_f32 v[208:209], v[188:189], s[24:25]
	v_pk_fma_f32 v[48:49], v[6:7], v[44:45], v[48:49] op_sel_hi:[0,1,1]
	v_pk_fma_f32 v[188:189], v[188:189], s[22:23], v[208:209] op_sel:[0,0,1] op_sel_hi:[1,0,0] neg_lo:[1,0,0] neg_hi:[1,0,0]
	v_pk_add_f32 v[208:209], v[128:129], v[192:193] op_sel:[0,1] op_sel_hi:[1,0] neg_hi:[0,1]
	v_pk_add_f32 v[128:129], v[128:129], v[192:193] op_sel:[0,1] op_sel_hi:[1,0] neg_lo:[0,1]
	v_pk_add_f32 v[192:193], v[130:131], v[162:163]
	v_pk_add_f32 v[130:131], v[130:131], v[162:163] neg_lo:[0,1] neg_hi:[0,1]
	v_pk_mul_f32 v[52:53], v[8:9], v[44:45] op_sel:[1,1] op_sel_hi:[1,0] neg_lo:[1,0]
	v_pk_mul_f32 v[162:163], v[130:131], s[24:25]
	v_pk_fma_f32 v[64:65], v[6:7], v[60:61], v[64:65] op_sel_hi:[0,1,1]
	v_pk_fma_f32 v[130:131], v[130:131], s[22:23], v[162:163] op_sel:[0,0,1] op_sel_hi:[1,0,0]
	v_pk_add_f32 v[162:163], v[148:149], v[164:165]
	v_pk_add_f32 v[148:149], v[148:149], v[164:165] neg_lo:[0,1] neg_hi:[0,1]
	v_pk_mul_f32 v[68:69], v[8:9], v[60:61] op_sel:[1,1] op_sel_hi:[1,0] neg_lo:[1,0]
	v_pk_mul_f32 v[164:165], v[148:149], s[40:41]
	v_pk_fma_f32 v[80:81], v[6:7], v[76:77], v[80:81] op_sel_hi:[0,1,1]
	v_pk_fma_f32 v[148:149], v[148:149], s[38:39], v[164:165] op_sel:[0,0,1] op_sel_hi:[1,0,0]
	v_pk_add_f32 v[164:165], v[150:151], v[166:167]
	v_pk_add_f32 v[150:151], v[150:151], v[166:167] neg_lo:[0,1] neg_hi:[0,1]
	v_pk_mul_f32 v[84:85], v[8:9], v[76:77] op_sel:[1,1] op_sel_hi:[1,0] neg_lo:[1,0]
	v_pk_mul_f32 v[166:167], v[150:151], s[44:45]
	v_pk_fma_f32 v[96:97], v[6:7], v[92:93], v[96:97] op_sel_hi:[0,1,1]
	v_pk_fma_f32 v[150:151], v[150:151], s[50:51], v[166:167] op_sel:[0,0,1] op_sel_hi:[1,0,0]
	v_pk_add_f32 v[166:167], v[152:153], v[168:169]
	v_pk_add_f32 v[168:169], v[152:153], v[168:169] neg_lo:[0,1] neg_hi:[0,1]
	v_pk_mul_f32 v[100:101], v[8:9], v[92:93] op_sel:[1,1] op_sel_hi:[1,0] neg_lo:[1,0]
	v_pk_add_f32 v[152:153], v[154:155], v[170:171]
	v_pk_add_f32 v[154:155], v[154:155], v[170:171] neg_lo:[0,1] neg_hi:[0,1]
	v_pk_fma_f32 v[112:113], v[6:7], v[108:109], v[112:113] op_sel_hi:[0,1,1]
	v_pk_mul_f32 v[170:171], v[154:155], s[44:45]
	v_pk_mul_f32 v[116:117], v[8:9], v[108:109] op_sel:[1,1] op_sel_hi:[1,0] neg_lo:[1,0]
	v_pk_fma_f32 v[154:155], v[154:155], s[50:51], v[170:171] op_sel:[0,0,1] op_sel_hi:[1,0,0] neg_lo:[1,0,0] neg_hi:[1,0,0]
	v_pk_add_f32 v[170:171], v[156:157], v[172:173]
	v_pk_add_f32 v[156:157], v[156:157], v[172:173] neg_lo:[0,1] neg_hi:[0,1]
	v_pk_fma_f32 v[20:21], v[8:9], v[12:13], v[20:21] op_sel_hi:[0,1,1]
	v_pk_mul_f32 v[172:173], v[156:157], s[40:41]
	v_pk_mul_f32 v[24:25], v[12:13], v[10:11] op_sel:[1,1] op_sel_hi:[0,1] neg_lo:[0,1]
	v_pk_fma_f32 v[156:157], v[156:157], s[38:39], v[172:173] op_sel:[0,0,1] op_sel_hi:[1,0,0] neg_lo:[1,0,0] neg_hi:[1,0,0]
	v_pk_add_f32 v[172:173], v[158:159], v[174:175]
	v_pk_add_f32 v[158:159], v[158:159], v[174:175] neg_lo:[0,1] neg_hi:[0,1]
	v_pk_fma_f32 v[36:37], v[8:9], v[28:29], v[36:37] op_sel_hi:[0,1,1]
	v_pk_mul_f32 v[174:175], v[158:159], s[24:25]
	v_pk_mul_f32 v[40:41], v[10:11], v[28:29] op_sel:[1,1] op_sel_hi:[1,0] neg_lo:[1,0]
	v_pk_fma_f32 v[158:159], v[158:159], s[22:23], v[174:175] op_sel:[0,0,1] op_sel_hi:[1,0,0] neg_lo:[1,0,0] neg_hi:[1,0,0]
	v_pk_add_f32 v[174:175], v[210:211], v[196:197]
	v_pk_add_f32 v[196:197], v[210:211], v[196:197] neg_lo:[0,1] neg_hi:[0,1]
	v_pk_add_f32 v[210:211], v[190:191], v[182:183]
	v_pk_add_f32 v[182:183], v[190:191], v[182:183] neg_lo:[0,1] neg_hi:[0,1]
	v_pk_fma_f32 v[52:53], v[8:9], v[44:45], v[52:53] op_sel_hi:[0,1,1]
	v_pk_mul_f32 v[190:191], v[182:183], s[40:41]
	v_pk_mul_f32 v[56:57], v[10:11], v[44:45] op_sel:[1,1] op_sel_hi:[1,0] neg_lo:[1,0]
	v_pk_fma_f32 v[182:183], v[182:183], s[38:39], v[190:191] op_sel:[0,0,1] op_sel_hi:[1,0,0]
	v_pk_add_f32 v[190:191], v[176:177], v[204:205]
	v_pk_add_f32 v[204:205], v[176:177], v[204:205] neg_lo:[0,1] neg_hi:[0,1]
	v_pk_fma_f32 v[68:69], v[8:9], v[60:61], v[68:69] op_sel_hi:[0,1,1]
	v_pk_add_f32 v[176:177], v[194:195], v[206:207]
	v_pk_add_f32 v[194:195], v[194:195], v[206:207] neg_lo:[0,1] neg_hi:[0,1]
	v_pk_mul_f32 v[72:73], v[10:11], v[60:61] op_sel:[1,1] op_sel_hi:[1,0] neg_lo:[1,0]
	v_pk_mul_f32 v[206:207], v[194:195], s[40:41]
	v_pk_fma_f32 v[84:85], v[8:9], v[76:77], v[84:85] op_sel_hi:[0,1,1]
	v_pk_fma_f32 v[194:195], v[194:195], s[38:39], v[206:207] op_sel:[0,0,1] op_sel_hi:[1,0,0] neg_lo:[1,0,0] neg_hi:[1,0,0]
	v_pk_add_f32 v[206:207], v[144:145], v[198:199] op_sel:[0,1] op_sel_hi:[1,0] neg_hi:[0,1]
	v_pk_add_f32 v[144:145], v[144:145], v[198:199] op_sel:[0,1] op_sel_hi:[1,0] neg_lo:[0,1]
	v_pk_add_f32 v[198:199], v[160:161], v[184:185]
	v_pk_add_f32 v[160:161], v[160:161], v[184:185] neg_lo:[0,1] neg_hi:[0,1]
	v_pk_mul_f32 v[88:89], v[10:11], v[76:77] op_sel:[1,1] op_sel_hi:[1,0] neg_lo:[1,0]
	v_pk_mul_f32 v[184:185], v[160:161], s[40:41]
	v_pk_fma_f32 v[100:101], v[8:9], v[92:93], v[100:101] op_sel_hi:[0,1,1]
	v_pk_fma_f32 v[160:161], v[160:161], s[38:39], v[184:185] op_sel:[0,0,1] op_sel_hi:[1,0,0]
	v_pk_add_f32 v[184:185], v[178:179], v[186:187]
	v_pk_add_f32 v[186:187], v[178:179], v[186:187] neg_lo:[0,1] neg_hi:[0,1]
	v_pk_mul_f32 v[104:105], v[10:11], v[92:93] op_sel:[1,1] op_sel_hi:[1,0] neg_lo:[1,0]
	v_pk_add_f32 v[178:179], v[180:181], v[188:189]
	v_pk_add_f32 v[180:181], v[180:181], v[188:189] neg_lo:[0,1] neg_hi:[0,1]
	v_pk_fma_f32 v[116:117], v[8:9], v[108:109], v[116:117] op_sel_hi:[0,1,1]
	v_pk_mul_f32 v[188:189], v[180:181], s[40:41]
	v_pk_mul_f32 v[120:121], v[10:11], v[108:109] op_sel:[1,1] op_sel_hi:[1,0] neg_lo:[1,0]
	v_pk_fma_f32 v[180:181], v[180:181], s[38:39], v[188:189] op_sel:[0,0,1] op_sel_hi:[1,0,0] neg_lo:[1,0,0] neg_hi:[1,0,0]
	v_pk_add_f32 v[188:189], v[208:209], v[166:167]
	v_pk_add_f32 v[166:167], v[208:209], v[166:167] neg_lo:[0,1] neg_hi:[0,1]
	v_pk_add_f32 v[208:209], v[192:193], v[152:153]
	v_pk_add_f32 v[152:153], v[192:193], v[152:153] neg_lo:[0,1] neg_hi:[0,1]
	v_xor_b32_e32 v26, 0x80000000, v19
	v_pk_mul_f32 v[192:193], v[152:153], s[40:41]
	v_xor_b32_e32 v30, 0x80000000, v21
	v_pk_fma_f32 v[152:153], v[152:153], s[38:39], v[192:193] op_sel:[0,0,1] op_sel_hi:[1,0,0]
	v_pk_add_f32 v[192:193], v[162:163], v[170:171]
	v_pk_add_f32 v[170:171], v[162:163], v[170:171] neg_lo:[0,1] neg_hi:[0,1]
	v_pk_fma_f32 v[24:25], v[12:13], v[10:11], v[24:25] op_sel_hi:[1,0,1]
	v_pk_add_f32 v[162:163], v[164:165], v[172:173]
	v_pk_add_f32 v[164:165], v[164:165], v[172:173] neg_lo:[0,1] neg_hi:[0,1]
	v_pk_fma_f32 v[40:41], v[10:11], v[28:29], v[40:41] op_sel_hi:[0,1,1]
	v_pk_mul_f32 v[172:173], v[164:165], s[40:41]
	v_pk_fma_f32 v[56:57], v[10:11], v[44:45], v[56:57] op_sel_hi:[0,1,1]
	v_pk_fma_f32 v[164:165], v[164:165], s[38:39], v[172:173] op_sel:[0,0,1] op_sel_hi:[1,0,0] neg_lo:[1,0,0] neg_hi:[1,0,0]
	v_pk_add_f32 v[172:173], v[128:129], v[168:169] op_sel:[0,1] op_sel_hi:[1,0] neg_hi:[0,1]
	v_pk_add_f32 v[128:129], v[128:129], v[168:169] op_sel:[0,1] op_sel_hi:[1,0] neg_lo:[0,1]
	v_pk_add_f32 v[168:169], v[130:131], v[154:155]
	v_pk_add_f32 v[130:131], v[130:131], v[154:155] neg_lo:[0,1] neg_hi:[0,1]
	v_pk_fma_f32 v[72:73], v[10:11], v[60:61], v[72:73] op_sel_hi:[0,1,1]
	v_pk_mul_f32 v[154:155], v[130:131], s[40:41]
	v_pk_fma_f32 v[88:89], v[10:11], v[76:77], v[88:89] op_sel_hi:[0,1,1]
	v_pk_fma_f32 v[130:131], v[130:131], s[38:39], v[154:155] op_sel:[0,0,1] op_sel_hi:[1,0,0]
	v_pk_add_f32 v[154:155], v[148:149], v[156:157]
	v_pk_add_f32 v[156:157], v[148:149], v[156:157] neg_lo:[0,1] neg_hi:[0,1]
	v_pk_fma_f32 v[104:105], v[10:11], v[92:93], v[104:105] op_sel_hi:[0,1,1]
	v_pk_add_f32 v[148:149], v[150:151], v[158:159]
	v_pk_add_f32 v[150:151], v[150:151], v[158:159] neg_lo:[0,1] neg_hi:[0,1]
	v_pk_fma_f32 v[120:121], v[10:11], v[108:109], v[120:121] op_sel_hi:[0,1,1]
	v_pk_mul_f32 v[158:159], v[150:151], s[40:41]
	v_mov_b32_e32 v27, v19
	v_pk_fma_f32 v[150:151], v[150:151], s[38:39], v[158:159] op_sel:[0,0,1] op_sel_hi:[1,0,0] neg_lo:[1,0,0] neg_hi:[1,0,0]
	v_pk_add_f32 v[158:159], v[174:175], v[190:191]
	v_pk_add_f32 v[174:175], v[174:175], v[190:191] neg_lo:[0,1] neg_hi:[0,1]
	v_pk_add_f32 v[190:191], v[210:211], v[176:177]
	v_pk_add_f32 v[210:211], v[210:211], v[176:177] neg_lo:[0,1] neg_hi:[0,1]
	v_mov_b32_e32 v31, v21
	v_pk_add_f32 v[176:177], v[196:197], v[204:205] op_sel:[0,1] op_sel_hi:[1,0] neg_hi:[0,1]
	v_pk_add_f32 v[196:197], v[196:197], v[204:205] op_sel:[0,1] op_sel_hi:[1,0] neg_lo:[0,1]
	v_pk_add_f32 v[204:205], v[182:183], v[194:195]
	v_pk_add_f32 v[194:195], v[182:183], v[194:195] neg_lo:[0,1] neg_hi:[0,1]
	v_xor_b32_e32 v34, 0x80000000, v25
	v_pk_add_f32 v[182:183], v[206:207], v[184:185]
	v_pk_add_f32 v[184:185], v[206:207], v[184:185] neg_lo:[0,1] neg_hi:[0,1]
	v_pk_add_f32 v[206:207], v[198:199], v[178:179]
	v_pk_add_f32 v[198:199], v[198:199], v[178:179] neg_lo:[0,1] neg_hi:[0,1]
	v_xor_b32_e32 v38, 0x80000000, v29
	v_pk_add_f32 v[178:179], v[144:145], v[186:187] op_sel:[0,1] op_sel_hi:[1,0] neg_hi:[0,1]
	v_pk_add_f32 v[144:145], v[144:145], v[186:187] op_sel:[0,1] op_sel_hi:[1,0] neg_lo:[0,1]
	v_pk_add_f32 v[186:187], v[160:161], v[180:181]
	v_pk_add_f32 v[180:181], v[160:161], v[180:181] neg_lo:[0,1] neg_hi:[0,1]
	v_xor_b32_e32 v42, 0x80000000, v33
	v_pk_add_f32 v[160:161], v[188:189], v[192:193]
	v_pk_add_f32 v[188:189], v[188:189], v[192:193] neg_lo:[0,1] neg_hi:[0,1]
	v_pk_add_f32 v[192:193], v[208:209], v[162:163]
	v_pk_add_f32 v[208:209], v[208:209], v[162:163] neg_lo:[0,1] neg_hi:[0,1]
	v_xor_b32_e32 v46, 0x80000000, v37
	v_pk_add_f32 v[162:163], v[166:167], v[170:171] op_sel:[0,1] op_sel_hi:[1,0] neg_hi:[0,1]
	v_pk_add_f32 v[166:167], v[166:167], v[170:171] op_sel:[0,1] op_sel_hi:[1,0] neg_lo:[0,1]
	v_pk_add_f32 v[170:171], v[152:153], v[164:165]
	v_pk_add_f32 v[164:165], v[152:153], v[164:165] neg_lo:[0,1] neg_hi:[0,1]
	v_mov_b32_e32 v35, v25
	v_pk_add_f32 v[152:153], v[172:173], v[154:155]
	v_pk_add_f32 v[154:155], v[172:173], v[154:155] neg_lo:[0,1] neg_hi:[0,1]
	v_pk_add_f32 v[172:173], v[168:169], v[148:149]
	v_pk_add_f32 v[168:169], v[168:169], v[148:149] neg_lo:[0,1] neg_hi:[0,1]
	v_mov_b32_e32 v39, v29
	v_pk_add_f32 v[148:149], v[128:129], v[156:157] op_sel:[0,1] op_sel_hi:[1,0] neg_hi:[0,1]
	v_pk_add_f32 v[128:129], v[128:129], v[156:157] op_sel:[0,1] op_sel_hi:[1,0] neg_lo:[0,1]
	v_pk_add_f32 v[156:157], v[130:131], v[150:151]
	v_pk_add_f32 v[130:131], v[130:131], v[150:151] neg_lo:[0,1] neg_hi:[0,1]
	v_mov_b32_e32 v43, v33
	v_xor_b32_e32 v151, 0x80000000, v130
	v_mov_b32_e32 v150, v131
	v_pk_add_f32 v[130:131], v[158:159], v[190:191]
	v_pk_add_f32 v[158:159], v[158:159], v[190:191] neg_lo:[0,1] neg_hi:[0,1]
	v_pk_add_f32 v[190:191], v[174:175], v[210:211] op_sel:[0,1] op_sel_hi:[1,0] neg_hi:[0,1]
	v_pk_add_f32 v[174:175], v[174:175], v[210:211] op_sel:[0,1] op_sel_hi:[1,0] neg_lo:[0,1]
	v_pk_add_f32 v[210:211], v[176:177], v[204:205]
	v_pk_add_f32 v[176:177], v[176:177], v[204:205] neg_lo:[0,1] neg_hi:[0,1]
	v_pk_add_f32 v[204:205], v[196:197], v[194:195] op_sel:[0,1] op_sel_hi:[1,0] neg_hi:[0,1]
	v_pk_add_f32 v[194:195], v[196:197], v[194:195] op_sel:[0,1] op_sel_hi:[1,0] neg_lo:[0,1]
	v_pk_add_f32 v[196:197], v[182:183], v[206:207]
	v_pk_add_f32 v[182:183], v[182:183], v[206:207] neg_lo:[0,1] neg_hi:[0,1]
	v_pk_add_f32 v[206:207], v[184:185], v[198:199] op_sel:[0,1] op_sel_hi:[1,0] neg_hi:[0,1]
	v_pk_add_f32 v[184:185], v[184:185], v[198:199] op_sel:[0,1] op_sel_hi:[1,0] neg_lo:[0,1]
	v_pk_add_f32 v[198:199], v[178:179], v[186:187]
	v_pk_add_f32 v[178:179], v[178:179], v[186:187] neg_lo:[0,1] neg_hi:[0,1]
	v_pk_add_f32 v[186:187], v[144:145], v[180:181] op_sel:[0,1] op_sel_hi:[1,0] neg_hi:[0,1]
	v_pk_add_f32 v[144:145], v[144:145], v[180:181] op_sel:[0,1] op_sel_hi:[1,0] neg_lo:[0,1]
	v_pk_add_f32 v[180:181], v[160:161], v[192:193]
	v_pk_add_f32 v[160:161], v[160:161], v[192:193] neg_lo:[0,1] neg_hi:[0,1]
	v_pk_mul_f32 v[4:5], v[4:5], v[180:181] op_sel:[0,1] op_sel_hi:[1,0]
	v_pk_add_f32 v[192:193], v[188:189], v[208:209] op_sel:[0,1] op_sel_hi:[1,0] neg_hi:[0,1]
	v_pk_add_f32 v[188:189], v[188:189], v[208:209] op_sel:[0,1] op_sel_hi:[1,0] neg_lo:[0,1]
	v_pk_add_f32 v[208:209], v[162:163], v[170:171]
	v_pk_add_f32 v[162:163], v[162:163], v[170:171] neg_lo:[0,1] neg_hi:[0,1]
	v_pk_add_f32 v[170:171], v[166:167], v[164:165] op_sel:[0,1] op_sel_hi:[1,0] neg_hi:[0,1]
	v_pk_add_f32 v[164:165], v[166:167], v[164:165] op_sel:[0,1] op_sel_hi:[1,0] neg_lo:[0,1]
	v_pk_add_f32 v[166:167], v[152:153], v[172:173]
	v_pk_fma_f32 v[4:5], v[6:7], v[180:181], v[4:5] op_sel_hi:[0,1,1]
	v_pk_mul_f32 v[6:7], v[8:9], v[196:197] op_sel:[1,1] op_sel_hi:[1,0] neg_lo:[1,0]
	v_mov_b32_e32 v47, v37
	v_pk_fma_f32 v[6:7], v[8:9], v[196:197], v[6:7] op_sel_hi:[0,1,1]
	v_pk_mul_f32 v[8:9], v[10:11], v[166:167] op_sel:[1,1] op_sel_hi:[1,0] neg_lo:[1,0]
	v_pk_add_f32 v[152:153], v[152:153], v[172:173] neg_lo:[0,1] neg_hi:[0,1]
	v_pk_fma_f32 v[8:9], v[10:11], v[166:167], v[8:9] op_sel_hi:[0,1,1]
	v_pk_mul_f32 v[10:11], v[12:13], v[210:211] op_sel:[1,1] op_sel_hi:[1,0] neg_lo:[1,0]
	v_pk_add_f32 v[172:173], v[154:155], v[168:169] op_sel:[0,1] op_sel_hi:[1,0] neg_hi:[0,1]
	v_pk_add_f32 v[154:155], v[154:155], v[168:169] op_sel:[0,1] op_sel_hi:[1,0] neg_lo:[0,1]
	v_pk_add_f32 v[168:169], v[148:149], v[156:157]
	v_pk_fma_f32 v[10:11], v[12:13], v[210:211], v[10:11] op_sel_hi:[0,1,1]
	v_pk_mul_f32 v[12:13], v[26:27], v[208:209] op_sel:[0,1] op_sel_hi:[1,0]
	v_pk_mul_f32 v[14:15], v[30:31], v[198:199] op_sel:[0,1] op_sel_hi:[1,0]
	v_pk_add_f32 v[148:149], v[148:149], v[156:157] neg_lo:[0,1] neg_hi:[0,1]
	v_pk_add_f32 v[156:157], v[128:129], v[150:151]
	v_pk_fma_f32 v[12:13], v[18:19], v[208:209], v[12:13] op_sel_hi:[0,1,1]
	v_pk_fma_f32 v[14:15], v[20:21], v[198:199], v[14:15] op_sel_hi:[0,1,1]
	v_pk_mul_f32 v[16:17], v[34:35], v[168:169] op_sel:[0,1] op_sel_hi:[1,0]
	v_pk_mul_f32 v[18:19], v[38:39], v[190:191] op_sel:[0,1] op_sel_hi:[1,0]
	v_pk_mul_f32 v[20:21], v[42:43], v[192:193] op_sel:[0,1] op_sel_hi:[1,0]
	v_pk_mul_f32 v[22:23], v[46:47], v[206:207] op_sel:[0,1] op_sel_hi:[1,0]
	v_xor_b32_e32 v78, 0x80000000, v69
	v_xor_b32_e32 v82, 0x80000000, v73
	v_xor_b32_e32 v86, 0x80000000, v77
	v_xor_b32_e32 v90, 0x80000000, v81
	v_xor_b32_e32 v94, 0x80000000, v85
	v_xor_b32_e32 v98, 0x80000000, v89
	v_xor_b32_e32 v102, 0x80000000, v93
	v_xor_b32_e32 v106, 0x80000000, v97
	v_xor_b32_e32 v110, 0x80000000, v101
	v_xor_b32_e32 v114, 0x80000000, v105
	v_xor_b32_e32 v118, 0x80000000, v109
	v_xor_b32_e32 v122, 0x80000000, v113
	v_xor_b32_e32 v124, 0x80000000, v117
	v_xor_b32_e32 v126, 0x80000000, v121
	v_mov_b32_e32 v79, v69
	v_mov_b32_e32 v83, v73
	v_mov_b32_e32 v87, v77
	v_mov_b32_e32 v91, v81
	v_mov_b32_e32 v95, v85
	v_mov_b32_e32 v99, v89
	v_mov_b32_e32 v103, v93
	v_mov_b32_e32 v107, v97
	v_mov_b32_e32 v111, v101
	v_mov_b32_e32 v115, v105
	v_mov_b32_e32 v119, v109
	v_mov_b32_e32 v123, v113
	v_mov_b32_e32 v125, v117
	v_mov_b32_e32 v127, v121
	v_pk_add_f32 v[128:129], v[128:129], v[150:151] neg_lo:[0,1] neg_hi:[0,1]
	v_pk_fma_f32 v[16:17], v[24:25], v[168:169], v[16:17] op_sel_hi:[0,1,1]
	v_pk_fma_f32 v[18:19], v[28:29], v[190:191], v[18:19] op_sel_hi:[0,1,1]
	v_pk_fma_f32 v[20:21], v[32:33], v[192:193], v[20:21] op_sel_hi:[0,1,1]
	v_pk_fma_f32 v[22:23], v[36:37], v[206:207], v[22:23] op_sel_hi:[0,1,1]
	v_pk_mul_f32 v[24:25], v[40:41], v[172:173] op_sel:[1,1] op_sel_hi:[1,0] neg_lo:[1,0]
	v_pk_mul_f32 v[26:27], v[44:45], v[204:205] op_sel:[1,1] op_sel_hi:[1,0] neg_lo:[1,0]
	v_pk_mul_f32 v[28:29], v[48:49], v[170:171] op_sel:[1,1] op_sel_hi:[1,0] neg_lo:[1,0]
	v_pk_mul_f32 v[30:31], v[52:53], v[186:187] op_sel:[1,1] op_sel_hi:[1,0] neg_lo:[1,0]
	v_pk_mul_f32 v[32:33], v[56:57], v[156:157] op_sel:[1,1] op_sel_hi:[1,0] neg_lo:[1,0]
	v_pk_mul_f32 v[34:35], v[60:61], v[158:159] op_sel:[1,1] op_sel_hi:[1,0] neg_lo:[1,0]
	v_pk_mul_f32 v[36:37], v[64:65], v[160:161] op_sel:[1,1] op_sel_hi:[1,0] neg_lo:[1,0]
	v_pk_fma_f32 v[24:25], v[40:41], v[172:173], v[24:25] op_sel_hi:[0,1,1]
	v_pk_fma_f32 v[26:27], v[44:45], v[204:205], v[26:27] op_sel_hi:[0,1,1]
	v_pk_fma_f32 v[28:29], v[48:49], v[170:171], v[28:29] op_sel_hi:[0,1,1]
	v_pk_fma_f32 v[30:31], v[52:53], v[186:187], v[30:31] op_sel_hi:[0,1,1]
	v_pk_fma_f32 v[32:33], v[56:57], v[156:157], v[32:33] op_sel_hi:[0,1,1]
	v_pk_fma_f32 v[34:35], v[60:61], v[158:159], v[34:35] op_sel_hi:[0,1,1]
	v_pk_fma_f32 v[36:37], v[64:65], v[160:161], v[36:37] op_sel_hi:[0,1,1]
	v_pk_mul_f32 v[38:39], v[78:79], v[182:183] op_sel:[0,1] op_sel_hi:[1,0]
	v_pk_mul_f32 v[40:41], v[82:83], v[152:153] op_sel:[0,1] op_sel_hi:[1,0]
	v_pk_mul_f32 v[42:43], v[86:87], v[176:177] op_sel:[0,1] op_sel_hi:[1,0]
	v_pk_mul_f32 v[44:45], v[90:91], v[162:163] op_sel:[0,1] op_sel_hi:[1,0]
	v_pk_mul_f32 v[46:47], v[94:95], v[178:179] op_sel:[0,1] op_sel_hi:[1,0]
	v_pk_mul_f32 v[48:49], v[98:99], v[148:149] op_sel:[0,1] op_sel_hi:[1,0]
	v_pk_mul_f32 v[50:51], v[102:103], v[174:175] op_sel:[0,1] op_sel_hi:[1,0]
	v_pk_mul_f32 v[52:53], v[106:107], v[188:189] op_sel:[0,1] op_sel_hi:[1,0]
	v_pk_mul_f32 v[54:55], v[110:111], v[184:185] op_sel:[0,1] op_sel_hi:[1,0]
	v_pk_mul_f32 v[56:57], v[114:115], v[154:155] op_sel:[0,1] op_sel_hi:[1,0]
	v_pk_mul_f32 v[58:59], v[118:119], v[194:195] op_sel:[0,1] op_sel_hi:[1,0]
	v_pk_mul_f32 v[60:61], v[122:123], v[164:165] op_sel:[0,1] op_sel_hi:[1,0]
	v_pk_mul_f32 v[62:63], v[124:125], v[144:145] op_sel:[0,1] op_sel_hi:[1,0]
	v_pk_mul_f32 v[64:65], v[126:127], v[128:129] op_sel:[0,1] op_sel_hi:[1,0]
	v_pk_fma_f32 v[38:39], v[68:69], v[182:183], v[38:39] op_sel_hi:[0,1,1]
	v_pk_fma_f32 v[40:41], v[72:73], v[152:153], v[40:41] op_sel_hi:[0,1,1]
	v_pk_fma_f32 v[42:43], v[76:77], v[176:177], v[42:43] op_sel_hi:[0,1,1]
	v_pk_fma_f32 v[44:45], v[80:81], v[162:163], v[44:45] op_sel_hi:[0,1,1]
	v_pk_fma_f32 v[46:47], v[84:85], v[178:179], v[46:47] op_sel_hi:[0,1,1]
	v_pk_fma_f32 v[48:49], v[88:89], v[148:149], v[48:49] op_sel_hi:[0,1,1]
	v_pk_fma_f32 v[50:51], v[92:93], v[174:175], v[50:51] op_sel_hi:[0,1,1]
	v_pk_fma_f32 v[52:53], v[96:97], v[188:189], v[52:53] op_sel_hi:[0,1,1]
	v_pk_fma_f32 v[54:55], v[100:101], v[184:185], v[54:55] op_sel_hi:[0,1,1]
	v_pk_fma_f32 v[56:57], v[104:105], v[154:155], v[56:57] op_sel_hi:[0,1,1]
	v_pk_fma_f32 v[58:59], v[108:109], v[194:195], v[58:59] op_sel_hi:[0,1,1]
	v_pk_fma_f32 v[60:61], v[112:113], v[164:165], v[60:61] op_sel_hi:[0,1,1]
	v_pk_fma_f32 v[62:63], v[116:117], v[144:145], v[62:63] op_sel_hi:[0,1,1]
	v_pk_fma_f32 v[64:65], v[120:121], v[128:129], v[64:65] op_sel_hi:[0,1,1]
	ds_write2_b64 v2, v[130:131], v[34:35] offset1:16
	ds_write2_b64 v2, v[18:19], v[50:51] offset0:33 offset1:49
	ds_write2_b64 v2, v[10:11], v[42:43] offset0:66 offset1:82
	ds_write2_b64 v2, v[26:27], v[58:59] offset0:99 offset1:115
	ds_write2_b64 v2, v[6:7], v[38:39] offset0:132 offset1:148
	ds_write2_b64 v2, v[22:23], v[54:55] offset0:165 offset1:181
	ds_write2_b64 v2, v[14:15], v[46:47] offset0:198 offset1:214
	ds_write2_b64 v2, v[30:31], v[62:63] offset0:231 offset1:247
	ds_write2_b64 v143, v[4:5], v[36:37] offset0:8 offset1:24
	ds_write2_b64 v143, v[20:21], v[52:53] offset0:41 offset1:57
	ds_write2_b64 v143, v[12:13], v[44:45] offset0:74 offset1:90
	ds_write2_b64 v143, v[28:29], v[60:61] offset0:107 offset1:123
	ds_write2_b64 v143, v[8:9], v[40:41] offset0:140 offset1:156
	ds_write2_b64 v143, v[24:25], v[56:57] offset0:173 offset1:189
	ds_write2_b64 v143, v[16:17], v[48:49] offset0:206 offset1:222
	ds_write2_b64 v143, v[32:33], v[64:65] offset0:239 offset1:255
	s_waitcnt lgkmcnt(0)
	s_barrier
	s_nop 0
	v_ashrrev_i32_e32 v2, 31, v142
	v_lshrrev_b32_e32 v2, 23, v2
	v_add_u32_e32 v2, v142, v2
	v_ashrrev_i32_e32 v2, 9, v2
	v_mul_i32_i24_e32 v4, 0x200, v2
	v_sub_u32_e32 v144, v142, v4
	v_lshlrev_b32_e32 v143, 14, v2
	v_lshlrev_b32_e32 v2, 1, v144
	v_bfrev_b32_e32 v2, v2
	v_lshrrev_b32_e32 v2, 22, v2
	v_sub_u32_e32 v2, 0x400, v2
	v_bfrev_b32_e32 v2, v2
	v_lshrrev_b32_e32 v2, 18, v2
	v_and_b32_e32 v2, 0x3ff0, v2
	v_cmp_eq_u32_e32 vcc, 0, v144
	v_lshl_add_u32 v4, v144, 5, v143
	v_lshlrev_b32_e32 v5, 3, v4
	v_cndmask_b32_e64 v2, v2, 16, vcc
	v_ashrrev_i32_e32 v4, 2, v4
	v_or_b32_e32 v2, v2, v143
	v_add3_u32 v56, 0, v5, v4
	v_ashrrev_i32_e32 v4, 5, v2
	v_lshlrev_b32_e32 v2, 3, v2
	v_lshlrev_b32_e32 v4, 3, v4
	v_add3_u32 v2, 0, v2, v4
	ds_read2_b64 v[4:7], v56 offset1:1
	ds_read2_b64 v[8:11], v56 offset0:2 offset1:3
	ds_read2_b64 v[12:15], v2 offset1:1
	ds_read2_b64 v[16:19], v2 offset0:2 offset1:3
	ds_read2_b64 v[20:23], v56 offset0:4 offset1:5
	ds_read2_b64 v[24:27], v56 offset0:6 offset1:7
	ds_read2_b64 v[28:31], v2 offset0:4 offset1:5
	ds_read2_b64 v[32:35], v2 offset0:6 offset1:7
	ds_read2_b64 v[36:39], v56 offset0:8 offset1:9
	ds_read2_b64 v[40:43], v56 offset0:10 offset1:11
	ds_read2_b64 v[48:51], v2 offset0:8 offset1:9
	ds_read2_b64 v[52:55], v2 offset0:10 offset1:11
	ds_read2_b64 v[44:47], v56 offset0:12 offset1:13
	ds_read2_b64 v[56:59], v56 offset0:14 offset1:15
	ds_read2_b64 v[70:73], v2 offset0:12 offset1:13
	ds_read2_b64 v[98:101], v2 offset0:14 offset1:15
	s_waitcnt lgkmcnt(7)
	v_pk_add_f32 v[60:61], v[4:5], v[36:37]
	v_pk_add_f32 v[4:5], v[4:5], v[36:37] neg_lo:[0,1] neg_hi:[0,1]
	v_pk_add_f32 v[36:37], v[6:7], v[38:39]
	v_pk_add_f32 v[6:7], v[6:7], v[38:39] neg_lo:[0,1] neg_hi:[0,1]
	s_waitcnt lgkmcnt(3)
	v_pk_add_f32 v[62:63], v[22:23], v[46:47]
	v_pk_mul_f32 v[38:39], v[6:7], s[24:25]
	v_pk_add_f32 v[22:23], v[22:23], v[46:47] neg_lo:[0,1] neg_hi:[0,1]
	v_pk_fma_f32 v[6:7], v[6:7], s[22:23], v[38:39] op_sel:[0,0,1] op_sel_hi:[1,0,0]
	v_pk_add_f32 v[38:39], v[8:9], v[40:41]
	v_pk_add_f32 v[8:9], v[8:9], v[40:41] neg_lo:[0,1] neg_hi:[0,1]
	v_pk_mul_f32 v[46:47], v[22:23], s[44:45]
	v_pk_mul_f32 v[40:41], v[8:9], s[40:41]
	v_pk_fma_f32 v[22:23], v[22:23], s[50:51], v[46:47] op_sel:[0,0,1] op_sel_hi:[1,0,0] neg_lo:[1,0,0] neg_hi:[1,0,0]
	v_pk_fma_f32 v[8:9], v[8:9], s[38:39], v[40:41] op_sel:[0,0,1] op_sel_hi:[1,0,0]
	v_pk_add_f32 v[40:41], v[10:11], v[42:43]
	v_pk_add_f32 v[10:11], v[10:11], v[42:43] neg_lo:[0,1] neg_hi:[0,1]
	s_waitcnt lgkmcnt(2)
	v_pk_add_f32 v[46:47], v[24:25], v[56:57]
	v_pk_add_f32 v[24:25], v[24:25], v[56:57] neg_lo:[0,1] neg_hi:[0,1]
	v_pk_mul_f32 v[42:43], v[10:11], s[44:45]
	v_pk_mul_f32 v[56:57], v[24:25], s[40:41]
	v_pk_fma_f32 v[10:11], v[10:11], s[50:51], v[42:43] op_sel:[0,0,1] op_sel_hi:[1,0,0]
	v_pk_add_f32 v[42:43], v[20:21], v[44:45]
	v_pk_add_f32 v[44:45], v[20:21], v[44:45] neg_lo:[0,1] neg_hi:[0,1]
	v_pk_fma_f32 v[24:25], v[24:25], s[38:39], v[56:57] op_sel:[0,0,1] op_sel_hi:[1,0,0] neg_lo:[1,0,0] neg_hi:[1,0,0]
	v_pk_add_f32 v[56:57], v[26:27], v[58:59]
	v_pk_add_f32 v[26:27], v[26:27], v[58:59] neg_lo:[0,1] neg_hi:[0,1]
	s_nop 0
	v_pk_mul_f32 v[58:59], v[26:27], s[24:25]
	v_pk_add_f32 v[64:65], v[40:41], v[56:57]
	v_pk_add_f32 v[40:41], v[40:41], v[56:57] neg_lo:[0,1] neg_hi:[0,1]
	v_pk_fma_f32 v[26:27], v[26:27], s[22:23], v[58:59] op_sel:[0,0,1] op_sel_hi:[1,0,0] neg_lo:[1,0,0] neg_hi:[1,0,0]
	v_pk_mul_f32 v[56:57], v[40:41], s[40:41]
	v_pk_add_f32 v[20:21], v[4:5], v[44:45] op_sel:[0,1] op_sel_hi:[1,0] neg_hi:[0,1]
	v_pk_add_f32 v[4:5], v[4:5], v[44:45] op_sel:[0,1] op_sel_hi:[1,0] neg_lo:[0,1]
	v_pk_add_f32 v[44:45], v[6:7], v[22:23]
	v_pk_add_f32 v[6:7], v[6:7], v[22:23] neg_lo:[0,1] neg_hi:[0,1]
	v_pk_fma_f32 v[40:41], v[40:41], s[38:39], v[56:57] op_sel:[0,0,1] op_sel_hi:[1,0,0] neg_lo:[1,0,0] neg_hi:[1,0,0]
	v_pk_mul_f32 v[22:23], v[6:7], s[40:41]
	v_pk_add_f32 v[56:57], v[10:11], v[26:27]
	v_pk_add_f32 v[10:11], v[10:11], v[26:27] neg_lo:[0,1] neg_hi:[0,1]
	v_pk_add_f32 v[58:59], v[60:61], v[42:43]
	v_pk_add_f32 v[42:43], v[60:61], v[42:43] neg_lo:[0,1] neg_hi:[0,1]
	v_pk_add_f32 v[60:61], v[36:37], v[62:63]
	v_pk_add_f32 v[36:37], v[36:37], v[62:63] neg_lo:[0,1] neg_hi:[0,1]
	v_pk_fma_f32 v[6:7], v[6:7], s[38:39], v[22:23] op_sel:[0,0,1] op_sel_hi:[1,0,0]
	v_pk_add_f32 v[22:23], v[8:9], v[24:25]
	v_pk_add_f32 v[24:25], v[8:9], v[24:25] neg_lo:[0,1] neg_hi:[0,1]
	v_pk_mul_f32 v[26:27], v[10:11], s[40:41]
	v_pk_mul_f32 v[62:63], v[36:37], s[40:41]
	v_pk_fma_f32 v[10:11], v[10:11], s[38:39], v[26:27] op_sel:[0,0,1] op_sel_hi:[1,0,0] neg_lo:[1,0,0] neg_hi:[1,0,0]
	v_pk_fma_f32 v[36:37], v[36:37], s[38:39], v[62:63] op_sel:[0,0,1] op_sel_hi:[1,0,0]
	v_pk_add_f32 v[62:63], v[38:39], v[46:47]
	v_pk_add_f32 v[66:67], v[20:21], v[22:23]
	v_pk_add_f32 v[20:21], v[20:21], v[22:23] neg_lo:[0,1] neg_hi:[0,1]
	v_pk_add_f32 v[22:23], v[44:45], v[56:57]
	v_pk_add_f32 v[44:45], v[44:45], v[56:57] neg_lo:[0,1] neg_hi:[0,1]
	v_pk_add_f32 v[8:9], v[4:5], v[24:25] op_sel:[0,1] op_sel_hi:[1,0] neg_hi:[0,1]
	v_pk_add_f32 v[4:5], v[4:5], v[24:25] op_sel:[0,1] op_sel_hi:[1,0] neg_lo:[0,1]
	v_pk_add_f32 v[24:25], v[6:7], v[10:11]
	v_pk_add_f32 v[10:11], v[6:7], v[10:11] neg_lo:[0,1] neg_hi:[0,1]
	v_pk_add_f32 v[26:27], v[58:59], v[62:63]
	v_pk_add_f32 v[58:59], v[58:59], v[62:63] neg_lo:[0,1] neg_hi:[0,1]
	v_pk_add_f32 v[62:63], v[60:61], v[64:65]
	v_pk_add_f32 v[60:61], v[60:61], v[64:65] neg_lo:[0,1] neg_hi:[0,1]
	v_xor_b32_e32 v57, 0x80000000, v44
	v_mov_b32_e32 v56, v45
	v_xor_b32_e32 v65, 0x80000000, v60
	v_pk_add_f32 v[130:131], v[26:27], v[62:63]
	v_pk_add_f32 v[92:93], v[26:27], v[62:63] neg_lo:[0,1] neg_hi:[0,1]
	v_mov_b32_e32 v64, v61
	v_pk_add_f32 v[62:63], v[20:21], v[56:57]
	v_pk_add_f32 v[78:79], v[20:21], v[56:57] neg_lo:[0,1] neg_hi:[0,1]
	v_pk_add_f32 v[56:57], v[4:5], v[10:11] op_sel:[0,1] op_sel_hi:[1,0] neg_hi:[0,1]
	v_pk_add_f32 v[90:91], v[4:5], v[10:11] op_sel:[0,1] op_sel_hi:[1,0] neg_lo:[0,1]
	v_pk_add_f32 v[10:11], v[14:15], v[50:51] neg_lo:[0,1] neg_hi:[0,1]
	v_pk_add_f32 v[46:47], v[38:39], v[46:47] neg_lo:[0,1] neg_hi:[0,1]
	v_pk_add_f32 v[84:85], v[58:59], v[64:65]
	v_pk_add_f32 v[86:87], v[58:59], v[64:65] neg_lo:[0,1] neg_hi:[0,1]
	v_pk_add_f32 v[80:81], v[8:9], v[24:25]
	v_pk_add_f32 v[64:65], v[8:9], v[24:25] neg_lo:[0,1] neg_hi:[0,1]
	v_pk_add_f32 v[4:5], v[12:13], v[48:49]
	v_pk_add_f32 v[6:7], v[12:13], v[48:49] neg_lo:[0,1] neg_hi:[0,1]
	v_pk_add_f32 v[8:9], v[14:15], v[50:51]
	v_pk_mul_f32 v[12:13], v[10:11], s[24:25]
	v_pk_add_f32 v[14:15], v[16:17], v[52:53] neg_lo:[0,1] neg_hi:[0,1]
	v_pk_fma_f32 v[10:11], v[10:11], s[22:23], v[12:13] op_sel:[0,0,1] op_sel_hi:[1,0,0]
	v_pk_add_f32 v[12:13], v[16:17], v[52:53]
	v_pk_mul_f32 v[16:17], v[14:15], s[40:41]
	v_pk_add_f32 v[38:39], v[42:43], v[46:47] op_sel:[0,1] op_sel_hi:[1,0] neg_hi:[0,1]
	v_pk_add_f32 v[42:43], v[42:43], v[46:47] op_sel:[0,1] op_sel_hi:[1,0] neg_lo:[0,1]
	v_pk_add_f32 v[46:47], v[36:37], v[40:41]
	v_pk_fma_f32 v[14:15], v[14:15], s[38:39], v[16:17] op_sel:[0,0,1] op_sel_hi:[1,0,0]
	v_pk_add_f32 v[16:17], v[18:19], v[54:55]
	v_pk_add_f32 v[18:19], v[18:19], v[54:55] neg_lo:[0,1] neg_hi:[0,1]
	v_pk_add_f32 v[88:89], v[38:39], v[46:47]
	v_pk_add_f32 v[68:69], v[38:39], v[46:47] neg_lo:[0,1] neg_hi:[0,1]
	v_pk_add_f32 v[96:97], v[66:67], v[22:23]
	v_pk_add_f32 v[46:47], v[66:67], v[22:23] neg_lo:[0,1] neg_hi:[0,1]
	v_pk_mul_f32 v[20:21], v[18:19], s[44:45]
	s_waitcnt lgkmcnt(1)
	v_pk_add_f32 v[24:25], v[28:29], v[70:71] neg_lo:[0,1] neg_hi:[0,1]
	v_pk_add_f32 v[26:27], v[30:31], v[72:73] neg_lo:[0,1] neg_hi:[0,1]
	v_pk_fma_f32 v[18:19], v[18:19], s[50:51], v[20:21] op_sel:[0,0,1] op_sel_hi:[1,0,0]
	v_pk_add_f32 v[20:21], v[28:29], v[70:71]
	v_pk_add_f32 v[22:23], v[30:31], v[72:73]
	v_pk_mul_f32 v[28:29], v[26:27], s[44:45]
	s_waitcnt lgkmcnt(0)
	v_pk_add_f32 v[30:31], v[32:33], v[98:99] neg_lo:[0,1] neg_hi:[0,1]
	v_pk_fma_f32 v[26:27], v[26:27], s[50:51], v[28:29] op_sel:[0,0,1] op_sel_hi:[1,0,0] neg_lo:[1,0,0] neg_hi:[1,0,0]
	v_pk_add_f32 v[28:29], v[32:33], v[98:99]
	v_pk_mul_f32 v[32:33], v[30:31], s[40:41]
	v_pk_add_f32 v[36:37], v[36:37], v[40:41] neg_lo:[0,1] neg_hi:[0,1]
	v_pk_fma_f32 v[30:31], v[30:31], s[38:39], v[32:33] op_sel:[0,0,1] op_sel_hi:[1,0,0] neg_lo:[1,0,0] neg_hi:[1,0,0]
	v_pk_add_f32 v[32:33], v[34:35], v[100:101]
	v_pk_add_f32 v[34:35], v[34:35], v[100:101] neg_lo:[0,1] neg_hi:[0,1]
	v_xor_b32_e32 v41, 0x80000000, v36
	v_mov_b32_e32 v40, v37
	v_pk_mul_f32 v[36:37], v[34:35], s[24:25]
	v_mov_b32_e32 v2, v130
	v_pk_fma_f32 v[34:35], v[34:35], s[22:23], v[36:37] op_sel:[0,0,1] op_sel_hi:[1,0,0] neg_lo:[1,0,0] neg_hi:[1,0,0]
	v_pk_add_f32 v[36:37], v[4:5], v[20:21]
	v_pk_add_f32 v[4:5], v[4:5], v[20:21] neg_lo:[0,1] neg_hi:[0,1]
	v_pk_add_f32 v[20:21], v[8:9], v[22:23]
	v_pk_add_f32 v[8:9], v[8:9], v[22:23] neg_lo:[0,1] neg_hi:[0,1]
	v_cmp_ne_u32_e64 s[0:1], 0, v144
	v_pk_mul_f32 v[22:23], v[8:9], s[40:41]
	v_pk_add_f32 v[74:75], v[42:43], v[40:41]
	v_pk_fma_f32 v[8:9], v[8:9], s[38:39], v[22:23] op_sel:[0,0,1] op_sel_hi:[1,0,0]
	v_pk_add_f32 v[22:23], v[12:13], v[28:29]
	v_pk_add_f32 v[28:29], v[12:13], v[28:29] neg_lo:[0,1] neg_hi:[0,1]
	v_pk_add_f32 v[94:95], v[42:43], v[40:41] neg_lo:[0,1] neg_hi:[0,1]
	v_pk_add_f32 v[12:13], v[16:17], v[32:33]
	v_pk_add_f32 v[16:17], v[16:17], v[32:33] neg_lo:[0,1] neg_hi:[0,1]
	s_nop 0
	v_pk_mul_f32 v[32:33], v[16:17], s[40:41]
	s_nop 0
	v_pk_fma_f32 v[16:17], v[16:17], s[38:39], v[32:33] op_sel:[0,0,1] op_sel_hi:[1,0,0] neg_lo:[1,0,0] neg_hi:[1,0,0]
	v_pk_add_f32 v[32:33], v[6:7], v[24:25] op_sel:[0,1] op_sel_hi:[1,0] neg_hi:[0,1]
	v_pk_add_f32 v[6:7], v[6:7], v[24:25] op_sel:[0,1] op_sel_hi:[1,0] neg_lo:[0,1]
	v_pk_add_f32 v[24:25], v[10:11], v[26:27]
	v_pk_add_f32 v[10:11], v[10:11], v[26:27] neg_lo:[0,1] neg_hi:[0,1]
	s_nop 0
	v_pk_mul_f32 v[26:27], v[10:11], s[40:41]
	s_nop 0
	v_pk_fma_f32 v[10:11], v[10:11], s[38:39], v[26:27] op_sel:[0,0,1] op_sel_hi:[1,0,0]
	v_pk_add_f32 v[26:27], v[14:15], v[30:31]
	v_pk_add_f32 v[30:31], v[14:15], v[30:31] neg_lo:[0,1] neg_hi:[0,1]
	s_nop 0
	v_pk_add_f32 v[14:15], v[18:19], v[34:35]
	v_pk_add_f32 v[18:19], v[18:19], v[34:35] neg_lo:[0,1] neg_hi:[0,1]
	s_nop 0
	v_pk_mul_f32 v[34:35], v[18:19], s[40:41]
	s_nop 0
	v_pk_fma_f32 v[18:19], v[18:19], s[38:39], v[34:35] op_sel:[0,0,1] op_sel_hi:[1,0,0] neg_lo:[1,0,0] neg_hi:[1,0,0]
	v_pk_add_f32 v[34:35], v[36:37], v[22:23]
	v_pk_add_f32 v[22:23], v[36:37], v[22:23] neg_lo:[0,1] neg_hi:[0,1]
	v_pk_add_f32 v[36:37], v[20:21], v[12:13]
	v_pk_add_f32 v[12:13], v[20:21], v[12:13] neg_lo:[0,1] neg_hi:[0,1]
	v_pk_add_f32 v[98:99], v[34:35], v[36:37]
	v_xor_b32_e32 v21, 0x80000000, v12
	v_mov_b32_e32 v20, v13
	v_pk_add_f32 v[12:13], v[4:5], v[28:29] op_sel:[0,1] op_sel_hi:[1,0] neg_hi:[0,1]
	v_pk_add_f32 v[4:5], v[4:5], v[28:29] op_sel:[0,1] op_sel_hi:[1,0] neg_lo:[0,1]
	v_pk_add_f32 v[28:29], v[8:9], v[16:17]
	v_pk_add_f32 v[8:9], v[8:9], v[16:17] neg_lo:[0,1] neg_hi:[0,1]
	v_pk_add_f32 v[100:101], v[34:35], v[36:37] neg_lo:[0,1] neg_hi:[0,1]
	v_xor_b32_e32 v17, 0x80000000, v8
	v_mov_b32_e32 v16, v9
	v_pk_add_f32 v[8:9], v[32:33], v[26:27]
	v_pk_add_f32 v[26:27], v[32:33], v[26:27] neg_lo:[0,1] neg_hi:[0,1]
	v_pk_add_f32 v[32:33], v[24:25], v[14:15]
	v_pk_add_f32 v[14:15], v[24:25], v[14:15] neg_lo:[0,1] neg_hi:[0,1]
	v_pk_add_f32 v[102:103], v[22:23], v[20:21]
	v_xor_b32_e32 v25, 0x80000000, v14
	v_mov_b32_e32 v24, v15
	v_pk_add_f32 v[14:15], v[6:7], v[30:31] op_sel:[0,1] op_sel_hi:[1,0] neg_hi:[0,1]
	v_pk_add_f32 v[6:7], v[6:7], v[30:31] op_sel:[0,1] op_sel_hi:[1,0] neg_lo:[0,1]
	v_pk_add_f32 v[30:31], v[10:11], v[18:19]
	v_pk_add_f32 v[10:11], v[10:11], v[18:19] neg_lo:[0,1] neg_hi:[0,1]
	v_pk_add_f32 v[104:105], v[22:23], v[20:21] neg_lo:[0,1] neg_hi:[0,1]
	v_xor_b32_e32 v19, 0x80000000, v10
	v_mov_b32_e32 v18, v11
	v_pk_add_f32 v[106:107], v[12:13], v[28:29]
	v_pk_add_f32 v[108:109], v[12:13], v[28:29] neg_lo:[0,1] neg_hi:[0,1]
	v_pk_add_f32 v[110:111], v[4:5], v[16:17]
	v_pk_add_f32 v[112:113], v[4:5], v[16:17] neg_lo:[0,1] neg_hi:[0,1]
	v_pk_add_f32 v[114:115], v[8:9], v[32:33]
	v_pk_add_f32 v[116:117], v[8:9], v[32:33] neg_lo:[0,1] neg_hi:[0,1]
	v_pk_add_f32 v[118:119], v[26:27], v[24:25]
	v_pk_add_f32 v[120:121], v[26:27], v[24:25] neg_lo:[0,1] neg_hi:[0,1]
	v_pk_add_f32 v[122:123], v[14:15], v[30:31]
	v_pk_add_f32 v[124:125], v[14:15], v[30:31] neg_lo:[0,1] neg_hi:[0,1]
	v_pk_add_f32 v[126:127], v[6:7], v[18:19]
	v_pk_add_f32 v[128:129], v[6:7], v[18:19] neg_lo:[0,1] neg_hi:[0,1]
	v_mov_b32_e32 v4, v131
	v_mov_b32_e32 v5, v3
	v_mov_b64_e32 v[6:7], v[2:3]
	s_and_saveexec_b64 s[50:51], s[0:1]
	s_xor_b64 s[0:1], exec, s[50:51]
	s_cbranch_execz .LBB0_562
	v_pk_add_f32 v[4:5], v[96:97], v[112:113]
	v_pk_add_f32 v[24:25], v[96:97], v[112:113] neg_lo:[0,1] neg_hi:[0,1]
	v_pk_add_f32 v[148:149], v[130:131], v[128:129]
	v_pk_add_f32 v[8:9], v[130:131], v[128:129] neg_lo:[0,1] neg_hi:[0,1]
	v_pk_add_f32 v[128:129], v[126:127], v[92:93]
	v_pk_add_f32 v[10:11], v[126:127], v[92:93] neg_lo:[0,1] neg_hi:[0,1]
	v_pk_add_f32 v[92:93], v[84:85], v[124:125]
	v_pk_add_f32 v[12:13], v[84:85], v[124:125] neg_lo:[0,1] neg_hi:[0,1]
	v_pk_add_f32 v[84:85], v[122:123], v[86:87]
	v_pk_add_f32 v[14:15], v[122:123], v[86:87] neg_lo:[0,1] neg_hi:[0,1]
	v_pk_add_f32 v[86:87], v[88:89], v[120:121]
	v_pk_add_f32 v[16:17], v[88:89], v[120:121] neg_lo:[0,1] neg_hi:[0,1]
	v_pk_add_f32 v[88:89], v[118:119], v[68:69]
	v_pk_add_f32 v[18:19], v[118:119], v[68:69] neg_lo:[0,1] neg_hi:[0,1]
	v_pk_add_f32 v[68:69], v[74:75], v[116:117]
	v_pk_add_f32 v[20:21], v[74:75], v[116:117] neg_lo:[0,1] neg_hi:[0,1]
	v_pk_add_f32 v[74:75], v[114:115], v[94:95]
	v_pk_add_f32 v[22:23], v[114:115], v[94:95] neg_lo:[0,1] neg_hi:[0,1]
	v_mov_b32_e32 v6, v4
	v_mov_b32_e32 v7, v25
	v_pk_mov_b32 v[4:5], v[4:5], v[24:25] op_sel:[1,0]
	v_pk_add_f32 v[94:95], v[110:111], v[46:47]
	v_pk_add_f32 v[24:25], v[110:111], v[46:47] neg_lo:[0,1] neg_hi:[0,1]
	v_pk_add_f32 v[46:47], v[62:63], v[108:109]
	v_pk_add_f32 v[26:27], v[62:63], v[108:109] neg_lo:[0,1] neg_hi:[0,1]
	v_pk_add_f32 v[62:63], v[106:107], v[78:79]
	v_pk_add_f32 v[28:29], v[106:107], v[78:79] neg_lo:[0,1] neg_hi:[0,1]
	v_pk_add_f32 v[78:79], v[80:81], v[104:105]
	v_pk_add_f32 v[30:31], v[80:81], v[104:105] neg_lo:[0,1] neg_hi:[0,1]
	v_pk_add_f32 v[80:81], v[102:103], v[64:65]
	v_pk_add_f32 v[32:33], v[102:103], v[64:65] neg_lo:[0,1] neg_hi:[0,1]
	v_pk_add_f32 v[64:65], v[56:57], v[100:101]
	v_pk_add_f32 v[34:35], v[56:57], v[100:101] neg_lo:[0,1] neg_hi:[0,1]
	v_pk_add_f32 v[56:57], v[98:99], v[90:91]
	v_pk_add_f32 v[36:37], v[98:99], v[90:91] neg_lo:[0,1] neg_hi:[0,1]
	v_pk_mul_f32 v[6:7], v[6:7], 0.5 op_sel_hi:[1,0]
	v_pk_mul_f32 v[4:5], v[4:5], s[46:47]
	v_mov_b32_e32 v39, v8
	v_mov_b32_e32 v38, v149
	v_mov_b32_e32 v41, v10
	v_mov_b32_e32 v40, v129
	v_mov_b32_e32 v43, v12
	v_mov_b32_e32 v42, v93
	v_mov_b32_e32 v45, v14
	v_mov_b32_e32 v44, v85
	v_mov_b32_e32 v49, v16
	v_mov_b32_e32 v48, v87
	v_mov_b32_e32 v51, v18
	v_mov_b32_e32 v50, v89
	v_mov_b32_e32 v53, v20
	v_mov_b32_e32 v52, v69
	v_mov_b32_e32 v55, v22
	v_mov_b32_e32 v54, v75
	v_mov_b32_e32 v59, v24
	v_mov_b32_e32 v58, v95
	v_mov_b32_e32 v61, v26
	v_mov_b32_e32 v60, v47
	v_mov_b32_e32 v67, v28
	v_mov_b32_e32 v66, v63
	v_mov_b32_e32 v71, v30
	v_mov_b32_e32 v70, v79
	v_mov_b32_e32 v73, v32
	v_mov_b32_e32 v72, v81
	v_mov_b32_e32 v77, v34
	v_mov_b32_e32 v76, v65
	v_mov_b32_e32 v83, v36
	v_mov_b32_e32 v82, v57
	v_mov_b32_e32 v8, v148
	v_mov_b32_e32 v10, v128
	v_mov_b32_e32 v12, v92
	v_mov_b32_e32 v14, v84
	v_mov_b32_e32 v16, v86
	v_mov_b32_e32 v18, v88
	v_mov_b32_e32 v20, v68
	v_mov_b32_e32 v22, v74
	v_mov_b32_e32 v24, v94
	v_mov_b32_e32 v26, v46
	v_mov_b32_e32 v28, v62
	v_mov_b32_e32 v30, v78
	v_mov_b32_e32 v32, v80
	v_mov_b32_e32 v34, v64
	v_mov_b32_e32 v36, v56

.LBB0_574:
	s_or_b64 exec, exec, s[0:1]
	v_mov_b32_e32 v2, v142
	s_waitcnt lgkmcnt(0)
	s_barrier
	s_mov_b32 s19, s16
	v_and_b32_e32 v4, 0xff, v2
	v_lshlrev_b32_e32 v5, 5, v2
	v_and_or_b32 v4, v5, s68, v4
	v_ashrrev_i32_e32 v5, 5, v4
	v_cvt_f32_ubyte0_e32 v2, v2
	v_lshlrev_b32_e32 v7, 3, v4
	v_mul_f32_e32 v2, 0x39000000, v2
	v_lshlrev_b32_e32 v5, 3, v5
	v_sin_f32_e32 v4, v2
	v_cos_f32_e32 v6, v2
	v_add3_u32 v2, 0, v7, v5
	ds_read_b64 v[128:129], v2
	ds_read_b64 v[130:131], v2 offset:2112
	ds_read_b64 v[144:145], v2 offset:4224
	ds_read_b64 v[148:149], v2 offset:6336
	ds_read_b64 v[150:151], v2 offset:8448
	ds_read_b64 v[152:153], v2 offset:10560
	ds_read_b64 v[154:155], v2 offset:12672
	ds_read_b64 v[156:157], v2 offset:14784
	ds_read_b64 v[158:159], v2 offset:16896
	ds_read_b64 v[160:161], v2 offset:19008
	ds_read_b64 v[162:163], v2 offset:21120
	ds_read_b64 v[164:165], v2 offset:23232
	ds_read_b64 v[166:167], v2 offset:25344
	ds_read_b64 v[168:169], v2 offset:27456
	ds_read_b64 v[170:171], v2 offset:29568
	ds_read_b64 v[172:173], v2 offset:31680
	ds_read_b64 v[174:175], v2 offset:33792
	ds_read_b64 v[176:177], v2 offset:35904
	ds_read_b64 v[178:179], v2 offset:38016
	ds_read_b64 v[180:181], v2 offset:40128
	ds_read_b64 v[182:183], v2 offset:42240
	ds_read_b64 v[184:185], v2 offset:44352
	ds_read_b64 v[186:187], v2 offset:46464
	ds_read_b64 v[188:189], v2 offset:48576
	ds_read_b64 v[190:191], v2 offset:50688
	ds_read_b64 v[192:193], v2 offset:52800
	ds_read_b64 v[194:195], v2 offset:54912
	ds_read_b64 v[196:197], v2 offset:57024
	ds_read_b64 v[198:199], v2 offset:59136
	ds_read_b64 v[204:205], v2 offset:61248
	ds_read_b64 v[206:207], v2 offset:63360
	ds_read_b64 v[208:209], v2 offset:65472
	s_waitcnt lgkmcnt(14)
	v_pk_add_f32 v[210:211], v[128:129], v[174:175]
	v_pk_add_f32 v[128:129], v[128:129], v[174:175] neg_lo:[0,1] neg_hi:[0,1]
	v_pk_add_f32 v[174:175], v[130:131], v[176:177]
	v_pk_add_f32 v[130:131], v[130:131], v[176:177] neg_lo:[0,1] neg_hi:[0,1]
	s_mov_b32 s0, s9
	v_pk_mul_f32 v[176:177], v[130:131], s[18:19]
	s_mov_b32 s41, s38
	v_pk_fma_f32 v[130:131], v[130:131], s[0:1], v[176:177] op_sel:[0,0,1] op_sel_hi:[1,0,0]
	s_waitcnt lgkmcnt(13)
	v_pk_add_f32 v[176:177], v[144:145], v[178:179]
	v_pk_add_f32 v[144:145], v[144:145], v[178:179] neg_lo:[0,1] neg_hi:[0,1]
	s_mov_b32 s43, s26
	v_pk_mul_f32 v[178:179], v[144:145], s[24:25]
	s_mov_b32 s62, s37
	v_pk_fma_f32 v[144:145], v[144:145], s[22:23], v[178:179] op_sel:[0,0,1] op_sel_hi:[1,0,0]
	s_waitcnt lgkmcnt(12)
	v_pk_add_f32 v[178:179], v[148:149], v[180:181]
	v_pk_add_f32 v[148:149], v[148:149], v[180:181] neg_lo:[0,1] neg_hi:[0,1]
	s_mov_b32 s45, s22
	v_pk_mul_f32 v[180:181], v[148:149], s[36:37]
	s_mov_b32 s50, s25
	v_pk_fma_f32 v[148:149], v[148:149], s[26:27], v[180:181] op_sel:[0,0,1] op_sel_hi:[1,0,0]
	s_waitcnt lgkmcnt(11)
	v_pk_add_f32 v[180:181], v[150:151], v[182:183]
	v_pk_add_f32 v[150:151], v[150:151], v[182:183] neg_lo:[0,1] neg_hi:[0,1]
	v_xor_b32_e32 v7, 0x80000000, v4
	v_pk_mul_f32 v[182:183], v[150:151], s[40:41]
	v_mov_b32_e32 v5, v7
	v_pk_fma_f32 v[150:151], v[150:151], s[38:39], v[182:183] op_sel:[0,0,1] op_sel_hi:[1,0,0]
	s_waitcnt lgkmcnt(10)
	v_pk_add_f32 v[182:183], v[152:153], v[184:185]
	v_pk_add_f32 v[152:153], v[152:153], v[184:185] neg_lo:[0,1] neg_hi:[0,1]
	v_pk_mul_f32 v[8:9], v[6:7], v[4:5] op_sel:[1,0] op_sel_hi:[0,1]
	v_pk_mul_f32 v[184:185], v[152:153], s[42:43]
	v_pk_fma_f32 v[8:9], v[6:7], v[6:7], v[8:9] op_sel_hi:[1,0,1]
	v_pk_fma_f32 v[152:153], v[152:153], s[62:63], v[184:185] op_sel:[0,0,1] op_sel_hi:[1,0,0]
	s_waitcnt lgkmcnt(9)
	v_pk_add_f32 v[184:185], v[154:155], v[186:187]
	v_pk_add_f32 v[154:155], v[154:155], v[186:187] neg_lo:[0,1] neg_hi:[0,1]
	s_nop 0
	v_pk_mul_f32 v[186:187], v[154:155], s[44:45]
	s_nop 0
	v_pk_fma_f32 v[154:155], v[154:155], s[50:51], v[186:187] op_sel:[0,0,1] op_sel_hi:[1,0,0]
	s_waitcnt lgkmcnt(8)
	v_pk_add_f32 v[186:187], v[156:157], v[188:189]
	v_pk_add_f32 v[156:157], v[156:157], v[188:189] neg_lo:[0,1] neg_hi:[0,1]
	v_pk_mul_f32 v[12:13], v[8:9], v[8:9] op_sel:[1,1] op_sel_hi:[0,1] neg_lo:[0,1]
	v_pk_mul_f32 v[188:189], v[156:157], s[8:9]
	v_pk_fma_f32 v[12:13], v[8:9], v[8:9], v[12:13] op_sel_hi:[1,0,1]
	v_pk_fma_f32 v[156:157], v[156:157], s[16:17], v[188:189] op_sel:[0,0,1] op_sel_hi:[1,0,0]
	s_waitcnt lgkmcnt(7)
	v_pk_add_f32 v[188:189], v[158:159], v[190:191]
	v_pk_add_f32 v[190:191], v[158:159], v[190:191] neg_lo:[0,1] neg_hi:[0,1]
	s_waitcnt lgkmcnt(6)
	v_pk_add_f32 v[158:159], v[160:161], v[192:193]
	v_pk_add_f32 v[160:161], v[160:161], v[192:193] neg_lo:[0,1] neg_hi:[0,1]
	s_nop 0
	v_pk_mul_f32 v[192:193], v[160:161], s[8:9]
	v_pk_mul_f32 v[28:29], v[12:13], v[12:13] op_sel:[1,1] op_sel_hi:[0,1] neg_lo:[0,1]
	v_pk_fma_f32 v[160:161], v[160:161], s[16:17], v[192:193] op_sel:[0,0,1] op_sel_hi:[1,0,0] neg_lo:[1,0,0] neg_hi:[1,0,0]
	s_waitcnt lgkmcnt(5)
	v_pk_add_f32 v[192:193], v[162:163], v[194:195]
	v_pk_add_f32 v[162:163], v[162:163], v[194:195] neg_lo:[0,1] neg_hi:[0,1]
	v_pk_fma_f32 v[28:29], v[12:13], v[12:13], v[28:29] op_sel_hi:[1,0,1]
	v_pk_mul_f32 v[194:195], v[162:163], s[44:45]
	v_pk_mul_f32 v[44:45], v[12:13], v[28:29] op_sel:[1,1] op_sel_hi:[1,0] neg_lo:[1,0]
	v_pk_fma_f32 v[162:163], v[162:163], s[50:51], v[194:195] op_sel:[0,0,1] op_sel_hi:[1,0,0] neg_lo:[1,0,0] neg_hi:[1,0,0]
	s_waitcnt lgkmcnt(4)
	v_pk_add_f32 v[194:195], v[164:165], v[196:197]
	v_pk_add_f32 v[164:165], v[164:165], v[196:197] neg_lo:[0,1] neg_hi:[0,1]
	v_pk_fma_f32 v[44:45], v[12:13], v[28:29], v[44:45] op_sel_hi:[0,1,1]
	v_pk_mul_f32 v[196:197], v[164:165], s[42:43]
	v_pk_mul_f32 v[60:61], v[12:13], v[44:45] op_sel:[1,1] op_sel_hi:[1,0] neg_lo:[1,0]
	v_pk_fma_f32 v[164:165], v[164:165], s[62:63], v[196:197] op_sel:[0,0,1] op_sel_hi:[1,0,0] neg_lo:[1,0,0] neg_hi:[1,0,0]
	s_waitcnt lgkmcnt(3)
	v_pk_add_f32 v[196:197], v[166:167], v[198:199]
	v_pk_add_f32 v[166:167], v[166:167], v[198:199] neg_lo:[0,1] neg_hi:[0,1]
	v_pk_fma_f32 v[60:61], v[12:13], v[44:45], v[60:61] op_sel_hi:[0,1,1]
	v_pk_mul_f32 v[198:199], v[166:167], s[40:41]
	v_pk_mul_f32 v[76:77], v[12:13], v[60:61] op_sel:[1,1] op_sel_hi:[1,0] neg_lo:[1,0]
	v_pk_fma_f32 v[166:167], v[166:167], s[38:39], v[198:199] op_sel:[0,0,1] op_sel_hi:[1,0,0] neg_lo:[1,0,0] neg_hi:[1,0,0]
	s_waitcnt lgkmcnt(2)
	v_pk_add_f32 v[198:199], v[168:169], v[204:205]
	v_pk_add_f32 v[168:169], v[168:169], v[204:205] neg_lo:[0,1] neg_hi:[0,1]
	v_pk_fma_f32 v[76:77], v[12:13], v[60:61], v[76:77] op_sel_hi:[0,1,1]
	v_pk_mul_f32 v[204:205], v[168:169], s[36:37]
	v_pk_mul_f32 v[92:93], v[12:13], v[76:77] op_sel:[1,1] op_sel_hi:[1,0] neg_lo:[1,0]
	v_pk_fma_f32 v[168:169], v[168:169], s[26:27], v[204:205] op_sel:[0,0,1] op_sel_hi:[1,0,0] neg_lo:[1,0,0] neg_hi:[1,0,0]
	s_waitcnt lgkmcnt(1)
	v_pk_add_f32 v[204:205], v[170:171], v[206:207]
	v_pk_add_f32 v[170:171], v[170:171], v[206:207] neg_lo:[0,1] neg_hi:[0,1]
	v_pk_fma_f32 v[92:93], v[12:13], v[76:77], v[92:93] op_sel_hi:[0,1,1]
	v_pk_mul_f32 v[206:207], v[170:171], s[24:25]
	v_pk_mul_f32 v[108:109], v[12:13], v[92:93] op_sel:[1,1] op_sel_hi:[1,0] neg_lo:[1,0]
	v_pk_fma_f32 v[170:171], v[170:171], s[22:23], v[206:207] op_sel:[0,0,1] op_sel_hi:[1,0,0] neg_lo:[1,0,0] neg_hi:[1,0,0]
	s_waitcnt lgkmcnt(0)
	v_pk_add_f32 v[206:207], v[172:173], v[208:209]
	v_pk_add_f32 v[172:173], v[172:173], v[208:209] neg_lo:[0,1] neg_hi:[0,1]
	v_pk_mul_f32 v[10:11], v[4:5], v[8:9] op_sel:[0,1] op_sel_hi:[1,0]
	v_pk_mul_f32 v[208:209], v[172:173], s[18:19]
	v_pk_fma_f32 v[108:109], v[12:13], v[92:93], v[108:109] op_sel_hi:[0,1,1]
	v_pk_fma_f32 v[172:173], v[172:173], s[0:1], v[208:209] op_sel:[0,0,1] op_sel_hi:[1,0,0] neg_lo:[1,0,0] neg_hi:[1,0,0]
	v_pk_add_f32 v[208:209], v[210:211], v[188:189]
	v_pk_add_f32 v[188:189], v[210:211], v[188:189] neg_lo:[0,1] neg_hi:[0,1]
	v_pk_add_f32 v[210:211], v[174:175], v[158:159]
	v_pk_add_f32 v[158:159], v[174:175], v[158:159] neg_lo:[0,1] neg_hi:[0,1]
	v_pk_fma_f32 v[10:11], v[6:7], v[8:9], v[10:11] op_sel_hi:[0,1,1]
	v_pk_mul_f32 v[174:175], v[158:159], s[24:25]
	v_pk_mul_f32 v[18:19], v[4:5], v[12:13] op_sel:[0,1] op_sel_hi:[1,0]
	v_pk_fma_f32 v[158:159], v[158:159], s[22:23], v[174:175] op_sel:[0,0,1] op_sel_hi:[1,0,0]
	v_pk_add_f32 v[174:175], v[176:177], v[192:193]
	v_pk_add_f32 v[176:177], v[176:177], v[192:193] neg_lo:[0,1] neg_hi:[0,1]
	v_pk_mul_f32 v[32:33], v[4:5], v[28:29] op_sel:[0,1] op_sel_hi:[1,0]
	v_pk_mul_f32 v[192:193], v[176:177], s[40:41]
	v_pk_mul_f32 v[48:49], v[4:5], v[44:45] op_sel:[0,1] op_sel_hi:[1,0]
	v_pk_fma_f32 v[176:177], v[176:177], s[38:39], v[192:193] op_sel:[0,0,1] op_sel_hi:[1,0,0]
	v_pk_add_f32 v[192:193], v[178:179], v[194:195]
	v_pk_add_f32 v[178:179], v[178:179], v[194:195] neg_lo:[0,1] neg_hi:[0,1]
	v_pk_mul_f32 v[64:65], v[4:5], v[60:61] op_sel:[0,1] op_sel_hi:[1,0]
	v_pk_mul_f32 v[194:195], v[178:179], s[44:45]
	v_pk_mul_f32 v[80:81], v[4:5], v[76:77] op_sel:[0,1] op_sel_hi:[1,0]
	v_pk_fma_f32 v[178:179], v[178:179], s[50:51], v[194:195] op_sel:[0,0,1] op_sel_hi:[1,0,0]
	v_pk_add_f32 v[194:195], v[180:181], v[196:197]
	v_pk_add_f32 v[196:197], v[180:181], v[196:197] neg_lo:[0,1] neg_hi:[0,1]
	v_pk_mul_f32 v[96:97], v[4:5], v[92:93] op_sel:[0,1] op_sel_hi:[1,0]
	v_pk_add_f32 v[180:181], v[182:183], v[198:199]
	v_pk_add_f32 v[182:183], v[182:183], v[198:199] neg_lo:[0,1] neg_hi:[0,1]
	v_pk_mul_f32 v[112:113], v[4:5], v[108:109] op_sel:[0,1] op_sel_hi:[1,0]
	v_pk_mul_f32 v[198:199], v[182:183], s[44:45]
	s_nop 0
	v_pk_fma_f32 v[182:183], v[182:183], s[50:51], v[198:199] op_sel:[0,0,1] op_sel_hi:[1,0,0] neg_lo:[1,0,0] neg_hi:[1,0,0]
	v_pk_add_f32 v[198:199], v[184:185], v[204:205]
	v_pk_add_f32 v[184:185], v[184:185], v[204:205] neg_lo:[0,1] neg_hi:[0,1]
	s_nop 0
	v_pk_mul_f32 v[204:205], v[184:185], s[40:41]
	v_pk_fma_f32 v[18:19], v[6:7], v[12:13], v[18:19] op_sel_hi:[0,1,1]
	v_pk_fma_f32 v[184:185], v[184:185], s[38:39], v[204:205] op_sel:[0,0,1] op_sel_hi:[1,0,0] neg_lo:[1,0,0] neg_hi:[1,0,0]
	v_pk_add_f32 v[204:205], v[186:187], v[206:207]
	v_pk_add_f32 v[186:187], v[186:187], v[206:207] neg_lo:[0,1] neg_hi:[0,1]
	v_pk_mul_f32 v[20:21], v[8:9], v[12:13] op_sel:[1,1] op_sel_hi:[1,0] neg_lo:[1,0]
	v_pk_mul_f32 v[206:207], v[186:187], s[24:25]
	v_pk_fma_f32 v[32:33], v[6:7], v[28:29], v[32:33] op_sel_hi:[0,1,1]
	v_pk_fma_f32 v[186:187], v[186:187], s[22:23], v[206:207] op_sel:[0,0,1] op_sel_hi:[1,0,0] neg_lo:[1,0,0] neg_hi:[1,0,0]
	v_pk_add_f32 v[206:207], v[128:129], v[190:191] op_sel:[0,1] op_sel_hi:[1,0] neg_hi:[0,1]
	v_pk_add_f32 v[128:129], v[128:129], v[190:191] op_sel:[0,1] op_sel_hi:[1,0] neg_lo:[0,1]
	v_pk_add_f32 v[190:191], v[130:131], v[160:161]
	v_pk_add_f32 v[130:131], v[130:131], v[160:161] neg_lo:[0,1] neg_hi:[0,1]
	v_pk_mul_f32 v[36:37], v[8:9], v[28:29] op_sel:[1,1] op_sel_hi:[1,0] neg_lo:[1,0]
	v_pk_mul_f32 v[160:161], v[130:131], s[24:25]
	v_pk_fma_f32 v[48:49], v[6:7], v[44:45], v[48:49] op_sel_hi:[0,1,1]
	v_pk_fma_f32 v[130:131], v[130:131], s[22:23], v[160:161] op_sel:[0,0,1] op_sel_hi:[1,0,0]
	v_pk_add_f32 v[160:161], v[144:145], v[162:163]
	v_pk_add_f32 v[144:145], v[144:145], v[162:163] neg_lo:[0,1] neg_hi:[0,1]
	v_pk_mul_f32 v[52:53], v[8:9], v[44:45] op_sel:[1,1] op_sel_hi:[1,0] neg_lo:[1,0]
	v_pk_mul_f32 v[162:163], v[144:145], s[40:41]
	v_pk_fma_f32 v[64:65], v[6:7], v[60:61], v[64:65] op_sel_hi:[0,1,1]
	v_pk_fma_f32 v[144:145], v[144:145], s[38:39], v[162:163] op_sel:[0,0,1] op_sel_hi:[1,0,0]
	v_pk_add_f32 v[162:163], v[148:149], v[164:165]
	v_pk_add_f32 v[148:149], v[148:149], v[164:165] neg_lo:[0,1] neg_hi:[0,1]
	v_pk_mul_f32 v[68:69], v[8:9], v[60:61] op_sel:[1,1] op_sel_hi:[1,0] neg_lo:[1,0]
	v_pk_mul_f32 v[164:165], v[148:149], s[44:45]
	v_pk_fma_f32 v[80:81], v[6:7], v[76:77], v[80:81] op_sel_hi:[0,1,1]
	v_pk_fma_f32 v[148:149], v[148:149], s[50:51], v[164:165] op_sel:[0,0,1] op_sel_hi:[1,0,0]
	v_pk_add_f32 v[164:165], v[150:151], v[166:167]
	v_pk_add_f32 v[166:167], v[150:151], v[166:167] neg_lo:[0,1] neg_hi:[0,1]
	v_pk_mul_f32 v[84:85], v[8:9], v[76:77] op_sel:[1,1] op_sel_hi:[1,0] neg_lo:[1,0]
	v_pk_add_f32 v[150:151], v[152:153], v[168:169]
	v_pk_add_f32 v[152:153], v[152:153], v[168:169] neg_lo:[0,1] neg_hi:[0,1]
	v_pk_fma_f32 v[96:97], v[6:7], v[92:93], v[96:97] op_sel_hi:[0,1,1]
	v_pk_mul_f32 v[168:169], v[152:153], s[44:45]
	v_pk_mul_f32 v[100:101], v[8:9], v[92:93] op_sel:[1,1] op_sel_hi:[1,0] neg_lo:[1,0]
	v_pk_fma_f32 v[152:153], v[152:153], s[50:51], v[168:169] op_sel:[0,0,1] op_sel_hi:[1,0,0] neg_lo:[1,0,0] neg_hi:[1,0,0]
	v_pk_add_f32 v[168:169], v[154:155], v[170:171]
	v_pk_add_f32 v[154:155], v[154:155], v[170:171] neg_lo:[0,1] neg_hi:[0,1]
	v_pk_fma_f32 v[112:113], v[6:7], v[108:109], v[112:113] op_sel_hi:[0,1,1]
	v_pk_mul_f32 v[170:171], v[154:155], s[40:41]
	v_pk_mul_f32 v[116:117], v[8:9], v[108:109] op_sel:[1,1] op_sel_hi:[1,0] neg_lo:[1,0]
	v_pk_fma_f32 v[154:155], v[154:155], s[38:39], v[170:171] op_sel:[0,0,1] op_sel_hi:[1,0,0] neg_lo:[1,0,0] neg_hi:[1,0,0]
	v_pk_add_f32 v[170:171], v[156:157], v[172:173]
	v_pk_add_f32 v[156:157], v[156:157], v[172:173] neg_lo:[0,1] neg_hi:[0,1]
	v_pk_fma_f32 v[20:21], v[8:9], v[12:13], v[20:21] op_sel_hi:[0,1,1]
	v_pk_mul_f32 v[172:173], v[156:157], s[24:25]
	v_pk_mul_f32 v[24:25], v[12:13], v[10:11] op_sel:[1,1] op_sel_hi:[0,1] neg_lo:[0,1]
	v_pk_fma_f32 v[156:157], v[156:157], s[22:23], v[172:173] op_sel:[0,0,1] op_sel_hi:[1,0,0] neg_lo:[1,0,0] neg_hi:[1,0,0]
	v_pk_add_f32 v[172:173], v[208:209], v[194:195]
	v_pk_add_f32 v[194:195], v[208:209], v[194:195] neg_lo:[0,1] neg_hi:[0,1]
	v_pk_add_f32 v[208:209], v[210:211], v[180:181]
	v_pk_add_f32 v[180:181], v[210:211], v[180:181] neg_lo:[0,1] neg_hi:[0,1]
	v_pk_fma_f32 v[36:37], v[8:9], v[28:29], v[36:37] op_sel_hi:[0,1,1]
	v_pk_mul_f32 v[210:211], v[180:181], s[40:41]
	v_pk_mul_f32 v[40:41], v[10:11], v[28:29] op_sel:[1,1] op_sel_hi:[1,0] neg_lo:[1,0]
	v_pk_fma_f32 v[180:181], v[180:181], s[38:39], v[210:211] op_sel:[0,0,1] op_sel_hi:[1,0,0]
	v_pk_add_f32 v[210:211], v[174:175], v[198:199]
	v_pk_add_f32 v[198:199], v[174:175], v[198:199] neg_lo:[0,1] neg_hi:[0,1]
	v_pk_fma_f32 v[52:53], v[8:9], v[44:45], v[52:53] op_sel_hi:[0,1,1]
	v_pk_add_f32 v[174:175], v[192:193], v[204:205]
	v_pk_add_f32 v[192:193], v[192:193], v[204:205] neg_lo:[0,1] neg_hi:[0,1]
	v_pk_mul_f32 v[56:57], v[10:11], v[44:45] op_sel:[1,1] op_sel_hi:[1,0] neg_lo:[1,0]
	v_pk_mul_f32 v[204:205], v[192:193], s[40:41]
	v_pk_fma_f32 v[68:69], v[8:9], v[60:61], v[68:69] op_sel_hi:[0,1,1]
	v_pk_fma_f32 v[192:193], v[192:193], s[38:39], v[204:205] op_sel:[0,0,1] op_sel_hi:[1,0,0] neg_lo:[1,0,0] neg_hi:[1,0,0]
	v_pk_add_f32 v[204:205], v[188:189], v[196:197] op_sel:[0,1] op_sel_hi:[1,0] neg_hi:[0,1]
	v_pk_add_f32 v[188:189], v[188:189], v[196:197] op_sel:[0,1] op_sel_hi:[1,0] neg_lo:[0,1]
	v_pk_add_f32 v[196:197], v[158:159], v[182:183]
	v_pk_add_f32 v[158:159], v[158:159], v[182:183] neg_lo:[0,1] neg_hi:[0,1]
	v_pk_mul_f32 v[72:73], v[10:11], v[60:61] op_sel:[1,1] op_sel_hi:[1,0] neg_lo:[1,0]
	v_pk_mul_f32 v[182:183], v[158:159], s[40:41]
	v_pk_fma_f32 v[84:85], v[8:9], v[76:77], v[84:85] op_sel_hi:[0,1,1]
	v_pk_fma_f32 v[158:159], v[158:159], s[38:39], v[182:183] op_sel:[0,0,1] op_sel_hi:[1,0,0]
	v_pk_add_f32 v[182:183], v[176:177], v[184:185]
	v_pk_add_f32 v[184:185], v[176:177], v[184:185] neg_lo:[0,1] neg_hi:[0,1]
	v_pk_mul_f32 v[88:89], v[10:11], v[76:77] op_sel:[1,1] op_sel_hi:[1,0] neg_lo:[1,0]
	v_pk_add_f32 v[176:177], v[178:179], v[186:187]
	v_pk_add_f32 v[178:179], v[178:179], v[186:187] neg_lo:[0,1] neg_hi:[0,1]
	v_pk_fma_f32 v[100:101], v[8:9], v[92:93], v[100:101] op_sel_hi:[0,1,1]
	v_pk_mul_f32 v[186:187], v[178:179], s[40:41]
	v_pk_mul_f32 v[104:105], v[10:11], v[92:93] op_sel:[1,1] op_sel_hi:[1,0] neg_lo:[1,0]
	v_pk_fma_f32 v[178:179], v[178:179], s[38:39], v[186:187] op_sel:[0,0,1] op_sel_hi:[1,0,0] neg_lo:[1,0,0] neg_hi:[1,0,0]
	v_pk_add_f32 v[186:187], v[206:207], v[164:165]
	v_pk_add_f32 v[164:165], v[206:207], v[164:165] neg_lo:[0,1] neg_hi:[0,1]
	v_pk_add_f32 v[206:207], v[190:191], v[150:151]
	v_pk_add_f32 v[150:151], v[190:191], v[150:151] neg_lo:[0,1] neg_hi:[0,1]
	v_pk_fma_f32 v[116:117], v[8:9], v[108:109], v[116:117] op_sel_hi:[0,1,1]
	v_pk_mul_f32 v[190:191], v[150:151], s[40:41]
	v_pk_mul_f32 v[120:121], v[10:11], v[108:109] op_sel:[1,1] op_sel_hi:[1,0] neg_lo:[1,0]
	v_pk_fma_f32 v[150:151], v[150:151], s[38:39], v[190:191] op_sel:[0,0,1] op_sel_hi:[1,0,0]
	v_pk_add_f32 v[190:191], v[160:161], v[168:169]
	v_pk_add_f32 v[168:169], v[160:161], v[168:169] neg_lo:[0,1] neg_hi:[0,1]
	v_xor_b32_e32 v26, 0x80000000, v19
	v_pk_add_f32 v[160:161], v[162:163], v[170:171]
	v_pk_add_f32 v[162:163], v[162:163], v[170:171] neg_lo:[0,1] neg_hi:[0,1]
	v_xor_b32_e32 v30, 0x80000000, v21
	v_pk_mul_f32 v[170:171], v[162:163], s[40:41]
	v_pk_fma_f32 v[24:25], v[12:13], v[10:11], v[24:25] op_sel_hi:[1,0,1]
	v_pk_fma_f32 v[162:163], v[162:163], s[38:39], v[170:171] op_sel:[0,0,1] op_sel_hi:[1,0,0] neg_lo:[1,0,0] neg_hi:[1,0,0]
	v_pk_add_f32 v[170:171], v[128:129], v[166:167] op_sel:[0,1] op_sel_hi:[1,0] neg_hi:[0,1]
	v_pk_add_f32 v[128:129], v[128:129], v[166:167] op_sel:[0,1] op_sel_hi:[1,0] neg_lo:[0,1]
	v_pk_add_f32 v[166:167], v[130:131], v[152:153]
	v_pk_add_f32 v[130:131], v[130:131], v[152:153] neg_lo:[0,1] neg_hi:[0,1]
	v_pk_fma_f32 v[40:41], v[10:11], v[28:29], v[40:41] op_sel_hi:[0,1,1]
	v_pk_mul_f32 v[152:153], v[130:131], s[40:41]
	v_pk_fma_f32 v[56:57], v[10:11], v[44:45], v[56:57] op_sel_hi:[0,1,1]
	v_pk_fma_f32 v[130:131], v[130:131], s[38:39], v[152:153] op_sel:[0,0,1] op_sel_hi:[1,0,0]
	v_pk_add_f32 v[152:153], v[144:145], v[154:155]
	v_pk_add_f32 v[154:155], v[144:145], v[154:155] neg_lo:[0,1] neg_hi:[0,1]
	v_pk_fma_f32 v[72:73], v[10:11], v[60:61], v[72:73] op_sel_hi:[0,1,1]
	v_pk_add_f32 v[144:145], v[148:149], v[156:157]
	v_pk_add_f32 v[148:149], v[148:149], v[156:157] neg_lo:[0,1] neg_hi:[0,1]
	v_pk_fma_f32 v[88:89], v[10:11], v[76:77], v[88:89] op_sel_hi:[0,1,1]
	v_pk_mul_f32 v[156:157], v[148:149], s[40:41]
	v_pk_fma_f32 v[104:105], v[10:11], v[92:93], v[104:105] op_sel_hi:[0,1,1]
	v_pk_fma_f32 v[148:149], v[148:149], s[38:39], v[156:157] op_sel:[0,0,1] op_sel_hi:[1,0,0] neg_lo:[1,0,0] neg_hi:[1,0,0]
	v_pk_add_f32 v[156:157], v[172:173], v[210:211]
	v_pk_add_f32 v[172:173], v[172:173], v[210:211] neg_lo:[0,1] neg_hi:[0,1]
	v_pk_add_f32 v[210:211], v[208:209], v[174:175]
	v_pk_add_f32 v[208:209], v[208:209], v[174:175] neg_lo:[0,1] neg_hi:[0,1]
	v_pk_fma_f32 v[120:121], v[10:11], v[108:109], v[120:121] op_sel_hi:[0,1,1]
	v_pk_add_f32 v[174:175], v[194:195], v[198:199] op_sel:[0,1] op_sel_hi:[1,0] neg_hi:[0,1]
	v_pk_add_f32 v[194:195], v[194:195], v[198:199] op_sel:[0,1] op_sel_hi:[1,0] neg_lo:[0,1]
	v_pk_add_f32 v[198:199], v[180:181], v[192:193]
	v_pk_add_f32 v[192:193], v[180:181], v[192:193] neg_lo:[0,1] neg_hi:[0,1]
	v_mov_b32_e32 v27, v19
	v_pk_add_f32 v[180:181], v[204:205], v[182:183]
	v_pk_add_f32 v[182:183], v[204:205], v[182:183] neg_lo:[0,1] neg_hi:[0,1]
	v_pk_add_f32 v[204:205], v[196:197], v[176:177]
	v_pk_add_f32 v[196:197], v[196:197], v[176:177] neg_lo:[0,1] neg_hi:[0,1]
	v_mov_b32_e32 v31, v21
	v_pk_add_f32 v[176:177], v[188:189], v[184:185] op_sel:[0,1] op_sel_hi:[1,0] neg_hi:[0,1]
	v_pk_add_f32 v[184:185], v[188:189], v[184:185] op_sel:[0,1] op_sel_hi:[1,0] neg_lo:[0,1]
	v_pk_add_f32 v[188:189], v[158:159], v[178:179]
	v_pk_add_f32 v[178:179], v[158:159], v[178:179] neg_lo:[0,1] neg_hi:[0,1]
	v_xor_b32_e32 v34, 0x80000000, v25
	v_pk_add_f32 v[158:159], v[186:187], v[190:191]
	v_pk_add_f32 v[186:187], v[186:187], v[190:191] neg_lo:[0,1] neg_hi:[0,1]
	v_pk_add_f32 v[190:191], v[206:207], v[160:161]
	v_pk_add_f32 v[206:207], v[206:207], v[160:161] neg_lo:[0,1] neg_hi:[0,1]
	v_xor_b32_e32 v38, 0x80000000, v29
	v_pk_add_f32 v[160:161], v[164:165], v[168:169] op_sel:[0,1] op_sel_hi:[1,0] neg_hi:[0,1]
	v_pk_add_f32 v[164:165], v[164:165], v[168:169] op_sel:[0,1] op_sel_hi:[1,0] neg_lo:[0,1]
	v_pk_add_f32 v[168:169], v[150:151], v[162:163]
	v_pk_add_f32 v[162:163], v[150:151], v[162:163] neg_lo:[0,1] neg_hi:[0,1]
	v_xor_b32_e32 v42, 0x80000000, v33
	v_pk_add_f32 v[150:151], v[170:171], v[152:153]
	v_pk_add_f32 v[152:153], v[170:171], v[152:153] neg_lo:[0,1] neg_hi:[0,1]
	v_pk_add_f32 v[170:171], v[166:167], v[144:145]
	v_pk_add_f32 v[166:167], v[166:167], v[144:145] neg_lo:[0,1] neg_hi:[0,1]
	v_xor_b32_e32 v46, 0x80000000, v37
	v_pk_add_f32 v[144:145], v[128:129], v[154:155] op_sel:[0,1] op_sel_hi:[1,0] neg_hi:[0,1]
	v_pk_add_f32 v[128:129], v[128:129], v[154:155] op_sel:[0,1] op_sel_hi:[1,0] neg_lo:[0,1]
	v_pk_add_f32 v[154:155], v[130:131], v[148:149]
	v_pk_add_f32 v[130:131], v[130:131], v[148:149] neg_lo:[0,1] neg_hi:[0,1]
	v_mov_b32_e32 v35, v25
	v_xor_b32_e32 v149, 0x80000000, v130
	v_mov_b32_e32 v148, v131
	v_pk_add_f32 v[130:131], v[156:157], v[210:211]
	v_pk_add_f32 v[156:157], v[156:157], v[210:211] neg_lo:[0,1] neg_hi:[0,1]
	v_pk_add_f32 v[210:211], v[172:173], v[208:209] op_sel:[0,1] op_sel_hi:[1,0] neg_hi:[0,1]
	v_pk_add_f32 v[172:173], v[172:173], v[208:209] op_sel:[0,1] op_sel_hi:[1,0] neg_lo:[0,1]
	v_pk_add_f32 v[208:209], v[174:175], v[198:199]
	v_pk_add_f32 v[174:175], v[174:175], v[198:199] neg_lo:[0,1] neg_hi:[0,1]
	v_pk_add_f32 v[198:199], v[194:195], v[192:193] op_sel:[0,1] op_sel_hi:[1,0] neg_hi:[0,1]
	v_pk_add_f32 v[192:193], v[194:195], v[192:193] op_sel:[0,1] op_sel_hi:[1,0] neg_lo:[0,1]
	v_pk_add_f32 v[194:195], v[180:181], v[204:205]
	v_pk_add_f32 v[180:181], v[180:181], v[204:205] neg_lo:[0,1] neg_hi:[0,1]
	v_pk_add_f32 v[204:205], v[182:183], v[196:197] op_sel:[0,1] op_sel_hi:[1,0] neg_hi:[0,1]
	v_pk_add_f32 v[182:183], v[182:183], v[196:197] op_sel:[0,1] op_sel_hi:[1,0] neg_lo:[0,1]
	v_pk_add_f32 v[196:197], v[176:177], v[188:189]
	v_pk_add_f32 v[176:177], v[176:177], v[188:189] neg_lo:[0,1] neg_hi:[0,1]
	v_pk_add_f32 v[188:189], v[184:185], v[178:179] op_sel:[0,1] op_sel_hi:[1,0] neg_hi:[0,1]
	v_pk_add_f32 v[178:179], v[184:185], v[178:179] op_sel:[0,1] op_sel_hi:[1,0] neg_lo:[0,1]
	v_pk_add_f32 v[184:185], v[158:159], v[190:191]
	v_pk_add_f32 v[158:159], v[158:159], v[190:191] neg_lo:[0,1] neg_hi:[0,1]
	v_pk_mul_f32 v[4:5], v[4:5], v[184:185] op_sel:[0,1] op_sel_hi:[1,0]
	v_pk_add_f32 v[190:191], v[186:187], v[206:207] op_sel:[0,1] op_sel_hi:[1,0] neg_hi:[0,1]
	v_pk_add_f32 v[186:187], v[186:187], v[206:207] op_sel:[0,1] op_sel_hi:[1,0] neg_lo:[0,1]
	v_pk_add_f32 v[206:207], v[160:161], v[168:169]
	v_pk_add_f32 v[160:161], v[160:161], v[168:169] neg_lo:[0,1] neg_hi:[0,1]
	v_pk_add_f32 v[168:169], v[164:165], v[162:163] op_sel:[0,1] op_sel_hi:[1,0] neg_hi:[0,1]
	v_pk_add_f32 v[162:163], v[164:165], v[162:163] op_sel:[0,1] op_sel_hi:[1,0] neg_lo:[0,1]
	v_pk_add_f32 v[164:165], v[150:151], v[170:171]
	v_pk_fma_f32 v[4:5], v[6:7], v[184:185], v[4:5] op_sel_hi:[0,1,1]
	v_pk_mul_f32 v[6:7], v[8:9], v[194:195] op_sel:[1,1] op_sel_hi:[1,0] neg_lo:[1,0]
	v_mov_b32_e32 v39, v29
	v_pk_fma_f32 v[6:7], v[8:9], v[194:195], v[6:7] op_sel_hi:[0,1,1]
	v_pk_mul_f32 v[8:9], v[10:11], v[164:165] op_sel:[1,1] op_sel_hi:[1,0] neg_lo:[1,0]
	v_mov_b32_e32 v43, v33
	v_pk_fma_f32 v[8:9], v[10:11], v[164:165], v[8:9] op_sel_hi:[0,1,1]
	v_pk_mul_f32 v[10:11], v[12:13], v[208:209] op_sel:[1,1] op_sel_hi:[1,0] neg_lo:[1,0]
	v_mov_b32_e32 v47, v37
	v_pk_add_f32 v[150:151], v[150:151], v[170:171] neg_lo:[0,1] neg_hi:[0,1]
	v_pk_add_f32 v[170:171], v[152:153], v[166:167] op_sel:[0,1] op_sel_hi:[1,0] neg_hi:[0,1]
	v_pk_add_f32 v[152:153], v[152:153], v[166:167] op_sel:[0,1] op_sel_hi:[1,0] neg_lo:[0,1]
	v_pk_add_f32 v[166:167], v[144:145], v[154:155]
	v_pk_fma_f32 v[10:11], v[12:13], v[208:209], v[10:11] op_sel_hi:[0,1,1]
	v_pk_mul_f32 v[12:13], v[26:27], v[206:207] op_sel:[0,1] op_sel_hi:[1,0]
	v_pk_mul_f32 v[14:15], v[30:31], v[196:197] op_sel:[0,1] op_sel_hi:[1,0]
	v_pk_add_f32 v[144:145], v[144:145], v[154:155] neg_lo:[0,1] neg_hi:[0,1]
	v_pk_add_f32 v[154:155], v[128:129], v[148:149]
	v_pk_fma_f32 v[12:13], v[18:19], v[206:207], v[12:13] op_sel_hi:[0,1,1]
	v_pk_fma_f32 v[14:15], v[20:21], v[196:197], v[14:15] op_sel_hi:[0,1,1]
	v_pk_mul_f32 v[16:17], v[34:35], v[166:167] op_sel:[0,1] op_sel_hi:[1,0]
	v_pk_mul_f32 v[18:19], v[38:39], v[210:211] op_sel:[0,1] op_sel_hi:[1,0]
	v_pk_mul_f32 v[20:21], v[42:43], v[190:191] op_sel:[0,1] op_sel_hi:[1,0]
	v_pk_mul_f32 v[22:23], v[46:47], v[204:205] op_sel:[0,1] op_sel_hi:[1,0]
	v_xor_b32_e32 v78, 0x80000000, v69
	v_xor_b32_e32 v82, 0x80000000, v73
	v_xor_b32_e32 v86, 0x80000000, v77
	v_xor_b32_e32 v90, 0x80000000, v81
	v_xor_b32_e32 v94, 0x80000000, v85
	v_xor_b32_e32 v98, 0x80000000, v89
	v_xor_b32_e32 v102, 0x80000000, v93
	v_xor_b32_e32 v106, 0x80000000, v97
	v_xor_b32_e32 v110, 0x80000000, v101
	v_xor_b32_e32 v114, 0x80000000, v105
	v_xor_b32_e32 v118, 0x80000000, v109
	v_xor_b32_e32 v122, 0x80000000, v113
	v_xor_b32_e32 v124, 0x80000000, v117
	v_xor_b32_e32 v126, 0x80000000, v121
	v_mov_b32_e32 v79, v69
	v_mov_b32_e32 v83, v73
	v_mov_b32_e32 v87, v77
	v_mov_b32_e32 v91, v81
	v_mov_b32_e32 v95, v85
	v_mov_b32_e32 v99, v89
	v_mov_b32_e32 v103, v93
	v_mov_b32_e32 v107, v97
	v_mov_b32_e32 v111, v101
	v_mov_b32_e32 v115, v105
	v_mov_b32_e32 v119, v109
	v_mov_b32_e32 v123, v113
	v_mov_b32_e32 v125, v117
	v_mov_b32_e32 v127, v121
	v_pk_add_f32 v[128:129], v[128:129], v[148:149] neg_lo:[0,1] neg_hi:[0,1]
	v_pk_fma_f32 v[16:17], v[24:25], v[166:167], v[16:17] op_sel_hi:[0,1,1]
	v_pk_fma_f32 v[18:19], v[28:29], v[210:211], v[18:19] op_sel_hi:[0,1,1]
	v_pk_fma_f32 v[20:21], v[32:33], v[190:191], v[20:21] op_sel_hi:[0,1,1]
	v_pk_fma_f32 v[22:23], v[36:37], v[204:205], v[22:23] op_sel_hi:[0,1,1]
	v_pk_mul_f32 v[24:25], v[40:41], v[170:171] op_sel:[1,1] op_sel_hi:[1,0] neg_lo:[1,0]
	v_pk_mul_f32 v[26:27], v[44:45], v[198:199] op_sel:[1,1] op_sel_hi:[1,0] neg_lo:[1,0]
	v_pk_mul_f32 v[28:29], v[48:49], v[168:169] op_sel:[1,1] op_sel_hi:[1,0] neg_lo:[1,0]
	v_pk_mul_f32 v[30:31], v[52:53], v[188:189] op_sel:[1,1] op_sel_hi:[1,0] neg_lo:[1,0]
	v_pk_mul_f32 v[32:33], v[56:57], v[154:155] op_sel:[1,1] op_sel_hi:[1,0] neg_lo:[1,0]
	v_pk_mul_f32 v[34:35], v[60:61], v[156:157] op_sel:[1,1] op_sel_hi:[1,0] neg_lo:[1,0]
	v_pk_mul_f32 v[36:37], v[64:65], v[158:159] op_sel:[1,1] op_sel_hi:[1,0] neg_lo:[1,0]
	v_pk_fma_f32 v[24:25], v[40:41], v[170:171], v[24:25] op_sel_hi:[0,1,1]
	v_pk_fma_f32 v[26:27], v[44:45], v[198:199], v[26:27] op_sel_hi:[0,1,1]
	v_pk_fma_f32 v[28:29], v[48:49], v[168:169], v[28:29] op_sel_hi:[0,1,1]
	v_pk_fma_f32 v[30:31], v[52:53], v[188:189], v[30:31] op_sel_hi:[0,1,1]
	v_pk_fma_f32 v[32:33], v[56:57], v[154:155], v[32:33] op_sel_hi:[0,1,1]
	v_pk_fma_f32 v[34:35], v[60:61], v[156:157], v[34:35] op_sel_hi:[0,1,1]
	v_pk_fma_f32 v[36:37], v[64:65], v[158:159], v[36:37] op_sel_hi:[0,1,1]
	v_pk_mul_f32 v[38:39], v[78:79], v[180:181] op_sel:[0,1] op_sel_hi:[1,0]
	v_pk_mul_f32 v[40:41], v[82:83], v[150:151] op_sel:[0,1] op_sel_hi:[1,0]
	v_pk_mul_f32 v[42:43], v[86:87], v[174:175] op_sel:[0,1] op_sel_hi:[1,0]
	v_pk_mul_f32 v[44:45], v[90:91], v[160:161] op_sel:[0,1] op_sel_hi:[1,0]
	v_pk_mul_f32 v[46:47], v[94:95], v[176:177] op_sel:[0,1] op_sel_hi:[1,0]
	v_pk_mul_f32 v[48:49], v[98:99], v[144:145] op_sel:[0,1] op_sel_hi:[1,0]
	v_pk_mul_f32 v[50:51], v[102:103], v[172:173] op_sel:[0,1] op_sel_hi:[1,0]
	v_pk_mul_f32 v[52:53], v[106:107], v[186:187] op_sel:[0,1] op_sel_hi:[1,0]
	v_pk_mul_f32 v[54:55], v[110:111], v[182:183] op_sel:[0,1] op_sel_hi:[1,0]
	v_pk_mul_f32 v[56:57], v[114:115], v[152:153] op_sel:[0,1] op_sel_hi:[1,0]
	v_pk_mul_f32 v[58:59], v[118:119], v[192:193] op_sel:[0,1] op_sel_hi:[1,0]
	v_pk_mul_f32 v[60:61], v[122:123], v[162:163] op_sel:[0,1] op_sel_hi:[1,0]
	v_pk_mul_f32 v[62:63], v[124:125], v[178:179] op_sel:[0,1] op_sel_hi:[1,0]
	v_pk_mul_f32 v[64:65], v[126:127], v[128:129] op_sel:[0,1] op_sel_hi:[1,0]
	v_pk_fma_f32 v[38:39], v[68:69], v[180:181], v[38:39] op_sel_hi:[0,1,1]
	v_pk_fma_f32 v[40:41], v[72:73], v[150:151], v[40:41] op_sel_hi:[0,1,1]
	v_pk_fma_f32 v[42:43], v[76:77], v[174:175], v[42:43] op_sel_hi:[0,1,1]
	v_pk_fma_f32 v[44:45], v[80:81], v[160:161], v[44:45] op_sel_hi:[0,1,1]
	v_pk_fma_f32 v[46:47], v[84:85], v[176:177], v[46:47] op_sel_hi:[0,1,1]
	v_pk_fma_f32 v[48:49], v[88:89], v[144:145], v[48:49] op_sel_hi:[0,1,1]
	v_pk_fma_f32 v[50:51], v[92:93], v[172:173], v[50:51] op_sel_hi:[0,1,1]
	v_pk_fma_f32 v[52:53], v[96:97], v[186:187], v[52:53] op_sel_hi:[0,1,1]
	v_pk_fma_f32 v[54:55], v[100:101], v[182:183], v[54:55] op_sel_hi:[0,1,1]
	v_pk_fma_f32 v[56:57], v[104:105], v[152:153], v[56:57] op_sel_hi:[0,1,1]
	v_pk_fma_f32 v[58:59], v[108:109], v[192:193], v[58:59] op_sel_hi:[0,1,1]
	v_pk_fma_f32 v[60:61], v[112:113], v[162:163], v[60:61] op_sel_hi:[0,1,1]
	v_pk_fma_f32 v[62:63], v[116:117], v[178:179], v[62:63] op_sel_hi:[0,1,1]
	v_pk_fma_f32 v[64:65], v[120:121], v[128:129], v[64:65] op_sel_hi:[0,1,1]
	ds_write_b64 v2, v[130:131]
	ds_write_b64 v2, v[34:35] offset:2112
	ds_write_b64 v2, v[18:19] offset:4224
	ds_write_b64 v2, v[50:51] offset:6336
	ds_write_b64 v2, v[10:11] offset:8448
	ds_write_b64 v2, v[42:43] offset:10560
	ds_write_b64 v2, v[26:27] offset:12672
	ds_write_b64 v2, v[58:59] offset:14784
	ds_write_b64 v2, v[6:7] offset:16896
	ds_write_b64 v2, v[38:39] offset:19008
	ds_write_b64 v2, v[22:23] offset:21120
	ds_write_b64 v2, v[54:55] offset:23232
	ds_write_b64 v2, v[14:15] offset:25344
	ds_write_b64 v2, v[46:47] offset:27456
	ds_write_b64 v2, v[30:31] offset:29568
	ds_write_b64 v2, v[62:63] offset:31680
	ds_write_b64 v2, v[4:5] offset:33792
	ds_write_b64 v2, v[36:37] offset:35904
	ds_write_b64 v2, v[20:21] offset:38016
	ds_write_b64 v2, v[52:53] offset:40128
	ds_write_b64 v2, v[12:13] offset:42240
	ds_write_b64 v2, v[44:45] offset:44352
	ds_write_b64 v2, v[28:29] offset:46464
	ds_write_b64 v2, v[60:61] offset:48576
	ds_write_b64 v2, v[8:9] offset:50688
	ds_write_b64 v2, v[40:41] offset:52800
	ds_write_b64 v2, v[24:25] offset:54912
	ds_write_b64 v2, v[56:57] offset:57024
	ds_write_b64 v2, v[16:17] offset:59136
	ds_write_b64 v2, v[48:49] offset:61248
	ds_write_b64 v2, v[32:33] offset:63360
	ds_write_b64 v2, v[64:65] offset:65472
	v_mov_b32_e32 v2, v142
	s_waitcnt lgkmcnt(0)
	s_barrier
	s_nop 0
	v_and_b32_e32 v5, 15, v2
	v_cvt_f32_ubyte0_e32 v4, v5
	v_mul_f32_e32 v6, 0x3b800000, v4
	v_sin_f32_e32 v4, v6
	v_cos_f32_e32 v6, v6
	v_lshlrev_b32_e32 v64, 3, v5
	v_lshlrev_b32_e32 v2, 4, v2
	v_xor_b32_e32 v7, 0x80000000, v4
	v_mov_b32_e32 v5, v7
	v_pk_mul_f32 v[8:9], v[6:7], v[4:5] op_sel:[1,0] op_sel_hi:[0,1]
	v_pk_fma_f32 v[8:9], v[6:7], v[6:7], v[8:9] op_sel_hi:[1,0,1]
	v_and_b32_e32 v2, 0xffffff00, v2
	v_pk_mul_f32 v[12:13], v[8:9], v[8:9] op_sel:[1,1] op_sel_hi:[0,1] neg_lo:[0,1]
	v_pk_fma_f32 v[12:13], v[8:9], v[8:9], v[12:13] op_sel_hi:[1,0,1]
	v_pk_mul_f32 v[10:11], v[4:5], v[8:9] op_sel:[0,1] op_sel_hi:[1,0]
	v_pk_mul_f32 v[32:33], v[12:13], v[12:13] op_sel:[1,1] op_sel_hi:[0,1] neg_lo:[0,1]
	v_pk_fma_f32 v[32:33], v[12:13], v[12:13], v[32:33] op_sel_hi:[1,0,1]
	v_pk_mul_f32 v[18:19], v[4:5], v[12:13] op_sel:[0,1] op_sel_hi:[1,0]
	v_pk_mul_f32 v[48:49], v[12:13], v[32:33] op_sel:[1,1] op_sel_hi:[1,0] neg_lo:[1,0]
	v_pk_mul_f32 v[36:37], v[4:5], v[32:33] op_sel:[0,1] op_sel_hi:[1,0]
	v_pk_fma_f32 v[48:49], v[12:13], v[32:33], v[48:49] op_sel_hi:[0,1,1]
	v_pk_mul_f32 v[52:53], v[4:5], v[48:49] op_sel:[0,1] op_sel_hi:[1,0]
	v_pk_fma_f32 v[10:11], v[6:7], v[8:9], v[10:11] op_sel_hi:[0,1,1]
	v_pk_fma_f32 v[18:19], v[6:7], v[12:13], v[18:19] op_sel_hi:[0,1,1]
	v_pk_fma_f32 v[36:37], v[6:7], v[32:33], v[36:37] op_sel_hi:[0,1,1]
	v_pk_fma_f32 v[52:53], v[6:7], v[48:49], v[52:53] op_sel_hi:[0,1,1]
	v_lshlrev_b32_e32 v7, 3, v2
	v_add3_u32 v7, 0, v64, v7
	v_ashrrev_i32_e32 v64, 2, v2
	v_add_u32_e32 v106, v7, v64
	ds_read2_b64 v[64:67], v106 offset1:16
	ds_read2_b64 v[68:71], v106 offset0:33 offset1:49
	ds_read2_b64 v[72:75], v106 offset0:66 offset1:82
	ds_read2_b64 v[76:79], v106 offset0:132 offset1:148
	ds_read2_b64 v[80:83], v106 offset0:99 offset1:115
	ds_read2_b64 v[84:87], v106 offset0:165 offset1:181
	ds_read2_b64 v[88:91], v106 offset0:198 offset1:214
	ds_read2_b64 v[92:95], v106 offset0:231 offset1:247
	s_waitcnt lgkmcnt(4)
	v_pk_add_f32 v[96:97], v[64:65], v[76:77]
	v_pk_add_f32 v[64:65], v[64:65], v[76:77] neg_lo:[0,1] neg_hi:[0,1]
	v_pk_add_f32 v[76:77], v[66:67], v[78:79]
	v_pk_add_f32 v[66:67], v[66:67], v[78:79] neg_lo:[0,1] neg_hi:[0,1]
	s_waitcnt lgkmcnt(1)
	v_pk_add_f32 v[98:99], v[74:75], v[90:91]
	v_pk_mul_f32 v[78:79], v[66:67], s[24:25]
	v_pk_add_f32 v[74:75], v[74:75], v[90:91] neg_lo:[0,1] neg_hi:[0,1]
	v_pk_fma_f32 v[66:67], v[66:67], s[22:23], v[78:79] op_sel:[0,0,1] op_sel_hi:[1,0,0]
	v_pk_add_f32 v[78:79], v[68:69], v[84:85]
	v_pk_add_f32 v[68:69], v[68:69], v[84:85] neg_lo:[0,1] neg_hi:[0,1]
	v_pk_mul_f32 v[90:91], v[74:75], s[44:45]
	v_pk_mul_f32 v[84:85], v[68:69], s[40:41]
	v_pk_fma_f32 v[74:75], v[74:75], s[50:51], v[90:91] op_sel:[0,0,1] op_sel_hi:[1,0,0] neg_lo:[1,0,0] neg_hi:[1,0,0]
	v_pk_fma_f32 v[68:69], v[68:69], s[38:39], v[84:85] op_sel:[0,0,1] op_sel_hi:[1,0,0]
	v_pk_add_f32 v[84:85], v[70:71], v[86:87]
	v_pk_add_f32 v[70:71], v[70:71], v[86:87] neg_lo:[0,1] neg_hi:[0,1]
	s_waitcnt lgkmcnt(0)
	v_pk_add_f32 v[90:91], v[80:81], v[92:93]
	v_pk_add_f32 v[80:81], v[80:81], v[92:93] neg_lo:[0,1] neg_hi:[0,1]
	v_pk_mul_f32 v[86:87], v[70:71], s[44:45]
	v_pk_mul_f32 v[92:93], v[80:81], s[40:41]
	v_pk_fma_f32 v[70:71], v[70:71], s[50:51], v[86:87] op_sel:[0,0,1] op_sel_hi:[1,0,0]
	v_pk_add_f32 v[86:87], v[72:73], v[88:89]
	v_pk_add_f32 v[88:89], v[72:73], v[88:89] neg_lo:[0,1] neg_hi:[0,1]
	v_pk_fma_f32 v[80:81], v[80:81], s[38:39], v[92:93] op_sel:[0,0,1] op_sel_hi:[1,0,0] neg_lo:[1,0,0] neg_hi:[1,0,0]
	v_pk_add_f32 v[92:93], v[82:83], v[94:95]
	v_pk_add_f32 v[82:83], v[82:83], v[94:95] neg_lo:[0,1] neg_hi:[0,1]
	s_nop 0
	v_pk_mul_f32 v[94:95], v[82:83], s[24:25]
	s_nop 0
	v_pk_fma_f32 v[82:83], v[82:83], s[22:23], v[94:95] op_sel:[0,0,1] op_sel_hi:[1,0,0] neg_lo:[1,0,0] neg_hi:[1,0,0]
	v_pk_add_f32 v[94:95], v[96:97], v[86:87]
	v_pk_add_f32 v[86:87], v[96:97], v[86:87] neg_lo:[0,1] neg_hi:[0,1]
	v_pk_add_f32 v[96:97], v[76:77], v[98:99]
	v_pk_add_f32 v[76:77], v[76:77], v[98:99] neg_lo:[0,1] neg_hi:[0,1]
	v_pk_add_f32 v[100:101], v[84:85], v[92:93]
	v_pk_add_f32 v[84:85], v[84:85], v[92:93] neg_lo:[0,1] neg_hi:[0,1]
	v_pk_add_f32 v[72:73], v[64:65], v[88:89] op_sel:[0,1] op_sel_hi:[1,0] neg_hi:[0,1]
	v_pk_add_f32 v[64:65], v[64:65], v[88:89] op_sel:[0,1] op_sel_hi:[1,0] neg_lo:[0,1]
	v_pk_add_f32 v[88:89], v[66:67], v[74:75]
	v_pk_add_f32 v[66:67], v[66:67], v[74:75] neg_lo:[0,1] neg_hi:[0,1]
	v_pk_mul_f32 v[98:99], v[76:77], s[40:41]
	v_pk_mul_f32 v[92:93], v[84:85], s[40:41]
	v_pk_mul_f32 v[74:75], v[66:67], s[40:41]
	v_pk_fma_f32 v[76:77], v[76:77], s[38:39], v[98:99] op_sel:[0,0,1] op_sel_hi:[1,0,0]
	v_pk_add_f32 v[98:99], v[78:79], v[90:91]
	v_pk_add_f32 v[90:91], v[78:79], v[90:91] neg_lo:[0,1] neg_hi:[0,1]
	v_pk_fma_f32 v[84:85], v[84:85], s[38:39], v[92:93] op_sel:[0,0,1] op_sel_hi:[1,0,0] neg_lo:[1,0,0] neg_hi:[1,0,0]
	v_pk_fma_f32 v[66:67], v[66:67], s[38:39], v[74:75] op_sel:[0,0,1] op_sel_hi:[1,0,0]
	v_pk_add_f32 v[74:75], v[68:69], v[80:81]
	v_pk_add_f32 v[92:93], v[70:71], v[82:83]
	v_pk_add_f32 v[70:71], v[70:71], v[82:83] neg_lo:[0,1] neg_hi:[0,1]
	v_pk_add_f32 v[68:69], v[68:69], v[80:81] neg_lo:[0,1] neg_hi:[0,1]
	v_pk_mul_f32 v[82:83], v[70:71], s[40:41]
	v_pk_add_f32 v[102:103], v[72:73], v[74:75]
	v_pk_add_f32 v[72:73], v[72:73], v[74:75] neg_lo:[0,1] neg_hi:[0,1]
	v_pk_add_f32 v[74:75], v[88:89], v[92:93]
	v_pk_add_f32 v[92:93], v[88:89], v[92:93] neg_lo:[0,1] neg_hi:[0,1]
	v_pk_mul_f32 v[24:25], v[8:9], v[12:13] op_sel:[1,1] op_sel_hi:[1,0] neg_lo:[1,0]
	v_xor_b32_e32 v81, 0x80000000, v68
	v_pk_fma_f32 v[70:71], v[70:71], s[38:39], v[82:83] op_sel:[0,0,1] op_sel_hi:[1,0,0] neg_lo:[1,0,0] neg_hi:[1,0,0]
	v_pk_add_f32 v[78:79], v[86:87], v[90:91] op_sel:[0,1] op_sel_hi:[1,0] neg_hi:[0,1]
	v_pk_add_f32 v[86:87], v[86:87], v[90:91] op_sel:[0,1] op_sel_hi:[1,0] neg_lo:[0,1]
	v_pk_add_f32 v[90:91], v[76:77], v[84:85]
	v_pk_add_f32 v[84:85], v[76:77], v[84:85] neg_lo:[0,1] neg_hi:[0,1]
	v_mov_b32_e32 v80, v69
	v_pk_fma_f32 v[24:25], v[8:9], v[12:13], v[24:25] op_sel_hi:[0,1,1]
	v_pk_mul_f32 v[28:29], v[12:13], v[10:11] op_sel:[1,1] op_sel_hi:[0,1] neg_lo:[0,1]
	v_pk_add_f32 v[68:69], v[64:65], v[80:81]
	v_pk_add_f32 v[64:65], v[64:65], v[80:81] neg_lo:[0,1] neg_hi:[0,1]
	v_pk_add_f32 v[80:81], v[66:67], v[70:71]
	v_pk_add_f32 v[70:71], v[66:67], v[70:71] neg_lo:[0,1] neg_hi:[0,1]
	v_pk_add_f32 v[88:89], v[72:73], v[92:93] op_sel:[0,1] op_sel_hi:[1,0] neg_hi:[0,1]
	v_pk_fma_f32 v[28:29], v[12:13], v[10:11], v[28:29] op_sel_hi:[1,0,1]
	v_pk_add_f32 v[76:77], v[86:87], v[84:85] op_sel:[0,1] op_sel_hi:[1,0] neg_hi:[0,1]
	v_pk_add_f32 v[72:73], v[72:73], v[92:93] op_sel:[0,1] op_sel_hi:[1,0] neg_lo:[0,1]
	v_pk_mul_f32 v[92:93], v[18:19], v[88:89] op_sel:[1,1] op_sel_hi:[1,0] neg_lo:[1,0]
	v_pk_add_f32 v[82:83], v[94:95], v[98:99]
	v_pk_add_f32 v[94:95], v[94:95], v[98:99] neg_lo:[0,1] neg_hi:[0,1]
	v_pk_add_f32 v[98:99], v[96:97], v[100:101]
	v_pk_add_f32 v[66:67], v[64:65], v[70:71] op_sel:[0,1] op_sel_hi:[1,0] neg_hi:[0,1]
	v_pk_fma_f32 v[88:89], v[18:19], v[88:89], v[92:93] op_sel_hi:[0,1,1]
	v_pk_mul_f32 v[92:93], v[24:25], v[76:77] op_sel:[1,1] op_sel_hi:[1,0] neg_lo:[1,0]
	v_pk_mul_f32 v[40:41], v[8:9], v[32:33] op_sel:[1,1] op_sel_hi:[1,0] neg_lo:[1,0]
	v_pk_add_f32 v[104:105], v[82:83], v[98:99]
	v_pk_add_f32 v[82:83], v[82:83], v[98:99] neg_lo:[0,1] neg_hi:[0,1]
	v_pk_fma_f32 v[76:77], v[24:25], v[76:77], v[92:93] op_sel_hi:[0,1,1]
	v_pk_mul_f32 v[92:93], v[28:29], v[66:67] op_sel:[1,1] op_sel_hi:[1,0] neg_lo:[1,0]
	v_pk_fma_f32 v[40:41], v[8:9], v[32:33], v[40:41] op_sel_hi:[0,1,1]
	v_pk_mul_f32 v[44:45], v[10:11], v[32:33] op_sel:[1,1] op_sel_hi:[1,0] neg_lo:[1,0]
	v_pk_add_f32 v[84:85], v[86:87], v[84:85] op_sel:[0,1] op_sel_hi:[1,0] neg_lo:[0,1]
	v_pk_add_f32 v[86:87], v[102:103], v[74:75]
	v_pk_add_f32 v[74:75], v[102:103], v[74:75] neg_lo:[0,1] neg_hi:[0,1]
	v_pk_fma_f32 v[66:67], v[28:29], v[66:67], v[92:93] op_sel_hi:[0,1,1]
	v_pk_mul_f32 v[92:93], v[32:33], v[82:83] op_sel:[1,1] op_sel_hi:[1,0] neg_lo:[1,0]
	v_pk_fma_f32 v[44:45], v[10:11], v[32:33], v[44:45] op_sel_hi:[0,1,1]
	v_pk_add_f32 v[100:101], v[96:97], v[100:101] neg_lo:[0,1] neg_hi:[0,1]
	v_pk_add_f32 v[98:99], v[78:79], v[90:91]
	v_pk_add_f32 v[78:79], v[78:79], v[90:91] neg_lo:[0,1] neg_hi:[0,1]
	v_pk_fma_f32 v[82:83], v[32:33], v[82:83], v[92:93] op_sel_hi:[0,1,1]
	v_pk_mul_f32 v[92:93], v[36:37], v[74:75] op_sel:[1,1] op_sel_hi:[1,0] neg_lo:[1,0]
	v_pk_add_f32 v[90:91], v[68:69], v[80:81]
	v_pk_add_f32 v[68:69], v[68:69], v[80:81] neg_lo:[0,1] neg_hi:[0,1]
	v_pk_fma_f32 v[74:75], v[36:37], v[74:75], v[92:93] op_sel_hi:[0,1,1]
	v_pk_mul_f32 v[92:93], v[40:41], v[78:79] op_sel:[1,1] op_sel_hi:[1,0] neg_lo:[1,0]
	v_pk_mul_f32 v[56:57], v[8:9], v[48:49] op_sel:[1,1] op_sel_hi:[1,0] neg_lo:[1,0]
	v_pk_add_f32 v[96:97], v[94:95], v[100:101] op_sel:[0,1] op_sel_hi:[1,0] neg_hi:[0,1]
	v_pk_add_f32 v[94:95], v[94:95], v[100:101] op_sel:[0,1] op_sel_hi:[1,0] neg_lo:[0,1]
	v_pk_fma_f32 v[78:79], v[40:41], v[78:79], v[92:93] op_sel_hi:[0,1,1]
	v_pk_mul_f32 v[92:93], v[44:45], v[68:69] op_sel:[1,1] op_sel_hi:[1,0] neg_lo:[1,0]
	v_pk_fma_f32 v[56:57], v[8:9], v[48:49], v[56:57] op_sel_hi:[0,1,1]
	v_pk_mul_f32 v[60:61], v[10:11], v[48:49] op_sel:[1,1] op_sel_hi:[1,0] neg_lo:[1,0]
	v_pk_fma_f32 v[68:69], v[44:45], v[68:69], v[92:93] op_sel_hi:[0,1,1]
	v_pk_mul_f32 v[92:93], v[48:49], v[94:95] op_sel:[1,1] op_sel_hi:[1,0] neg_lo:[1,0]
	v_pk_fma_f32 v[60:61], v[10:11], v[48:49], v[60:61] op_sel_hi:[0,1,1]
	v_pk_add_f32 v[64:65], v[64:65], v[70:71] op_sel:[0,1] op_sel_hi:[1,0] neg_lo:[0,1]
	v_pk_mul_f32 v[70:71], v[4:5], v[86:87] op_sel:[0,1] op_sel_hi:[1,0]
	v_pk_fma_f32 v[92:93], v[48:49], v[94:95], v[92:93] op_sel_hi:[0,1,1]
	v_pk_mul_f32 v[94:95], v[52:53], v[72:73] op_sel:[1,1] op_sel_hi:[1,0] neg_lo:[1,0]
	v_pk_fma_f32 v[70:71], v[6:7], v[86:87], v[70:71] op_sel_hi:[0,1,1]
	v_pk_mul_f32 v[86:87], v[10:11], v[90:91] op_sel:[1,1] op_sel_hi:[1,0] neg_lo:[1,0]
	v_pk_fma_f32 v[72:73], v[52:53], v[72:73], v[94:95] op_sel_hi:[0,1,1]
	v_pk_mul_f32 v[94:95], v[56:57], v[84:85] op_sel:[1,1] op_sel_hi:[1,0] neg_lo:[1,0]
	v_add_u32_e32 v2, 0x2000, v2
	v_pk_mul_f32 v[80:81], v[8:9], v[98:99] op_sel:[1,1] op_sel_hi:[1,0] neg_lo:[1,0]
	v_pk_fma_f32 v[86:87], v[10:11], v[90:91], v[86:87] op_sel_hi:[0,1,1]
	v_pk_mul_f32 v[90:91], v[12:13], v[96:97] op_sel:[1,1] op_sel_hi:[1,0] neg_lo:[1,0]
	v_pk_fma_f32 v[84:85], v[56:57], v[84:85], v[94:95] op_sel_hi:[0,1,1]
	v_pk_mul_f32 v[94:95], v[60:61], v[64:65] op_sel:[1,1] op_sel_hi:[1,0] neg_lo:[1,0]
	v_ashrrev_i32_e32 v2, 2, v2
	v_pk_fma_f32 v[80:81], v[8:9], v[98:99], v[80:81] op_sel_hi:[0,1,1]
	v_pk_fma_f32 v[90:91], v[12:13], v[96:97], v[90:91] op_sel_hi:[0,1,1]
	v_pk_fma_f32 v[64:65], v[60:61], v[64:65], v[94:95] op_sel_hi:[0,1,1]
	ds_write2_b64 v106, v[104:105], v[82:83] offset1:16
	ds_write2_b64 v106, v[90:91], v[92:93] offset0:33 offset1:49
	ds_write2_b64 v106, v[80:81], v[78:79] offset0:66 offset1:82
	ds_write2_b64 v106, v[76:77], v[84:85] offset0:99 offset1:115
	ds_write2_b64 v106, v[70:71], v[74:75] offset0:132 offset1:148
	ds_write2_b64 v106, v[88:89], v[72:73] offset0:165 offset1:181
	ds_write2_b64 v106, v[86:87], v[68:69] offset0:198 offset1:214
	ds_write2_b64 v106, v[66:67], v[64:65] offset0:231 offset1:247
	v_add3_u32 v2, v7, v2, s60
	ds_read2_b64 v[64:67], v2 offset1:16
	ds_read2_b64 v[68:71], v2 offset0:33 offset1:49
	ds_read2_b64 v[72:75], v2 offset0:66 offset1:82
	ds_read2_b64 v[76:79], v2 offset0:132 offset1:148
	ds_read2_b64 v[80:83], v2 offset0:99 offset1:115
	ds_read2_b64 v[84:87], v2 offset0:165 offset1:181
	ds_read2_b64 v[88:91], v2 offset0:198 offset1:214
	ds_read2_b64 v[92:95], v2 offset0:231 offset1:247
	s_waitcnt lgkmcnt(4)
	v_pk_add_f32 v[96:97], v[64:65], v[76:77]
	v_pk_add_f32 v[64:65], v[64:65], v[76:77] neg_lo:[0,1] neg_hi:[0,1]
	v_pk_add_f32 v[76:77], v[66:67], v[78:79]
	v_pk_add_f32 v[66:67], v[66:67], v[78:79] neg_lo:[0,1] neg_hi:[0,1]
	s_waitcnt lgkmcnt(1)
	v_pk_add_f32 v[98:99], v[74:75], v[90:91]
	v_pk_mul_f32 v[78:79], v[66:67], s[24:25]
	v_pk_add_f32 v[74:75], v[74:75], v[90:91] neg_lo:[0,1] neg_hi:[0,1]
	v_pk_fma_f32 v[66:67], v[66:67], s[22:23], v[78:79] op_sel:[0,0,1] op_sel_hi:[1,0,0]
	v_pk_add_f32 v[78:79], v[68:69], v[84:85]
	v_pk_add_f32 v[68:69], v[68:69], v[84:85] neg_lo:[0,1] neg_hi:[0,1]
	v_pk_mul_f32 v[90:91], v[74:75], s[44:45]
	v_pk_mul_f32 v[84:85], v[68:69], s[40:41]
	v_pk_fma_f32 v[74:75], v[74:75], s[50:51], v[90:91] op_sel:[0,0,1] op_sel_hi:[1,0,0] neg_lo:[1,0,0] neg_hi:[1,0,0]
	s_waitcnt lgkmcnt(0)
	v_pk_add_f32 v[90:91], v[80:81], v[92:93]
	v_pk_add_f32 v[80:81], v[80:81], v[92:93] neg_lo:[0,1] neg_hi:[0,1]
	v_pk_fma_f32 v[68:69], v[68:69], s[38:39], v[84:85] op_sel:[0,0,1] op_sel_hi:[1,0,0]
	v_pk_add_f32 v[84:85], v[70:71], v[86:87]
	v_pk_add_f32 v[70:71], v[70:71], v[86:87] neg_lo:[0,1] neg_hi:[0,1]
	v_pk_mul_f32 v[92:93], v[80:81], s[40:41]
	v_pk_mul_f32 v[86:87], v[70:71], s[44:45]
	v_pk_fma_f32 v[80:81], v[80:81], s[38:39], v[92:93] op_sel:[0,0,1] op_sel_hi:[1,0,0] neg_lo:[1,0,0] neg_hi:[1,0,0]
	v_pk_add_f32 v[92:93], v[82:83], v[94:95]
	v_pk_add_f32 v[82:83], v[82:83], v[94:95] neg_lo:[0,1] neg_hi:[0,1]
	v_pk_fma_f32 v[70:71], v[70:71], s[50:51], v[86:87] op_sel:[0,0,1] op_sel_hi:[1,0,0]
	v_pk_add_f32 v[86:87], v[72:73], v[88:89]
	v_pk_mul_f32 v[94:95], v[82:83], s[24:25]
	v_pk_add_f32 v[88:89], v[72:73], v[88:89] neg_lo:[0,1] neg_hi:[0,1]
	v_pk_fma_f32 v[82:83], v[82:83], s[22:23], v[94:95] op_sel:[0,0,1] op_sel_hi:[1,0,0] neg_lo:[1,0,0] neg_hi:[1,0,0]
	v_pk_add_f32 v[94:95], v[96:97], v[86:87]
	v_pk_add_f32 v[86:87], v[96:97], v[86:87] neg_lo:[0,1] neg_hi:[0,1]
	v_pk_add_f32 v[96:97], v[76:77], v[98:99]
	v_pk_add_f32 v[76:77], v[76:77], v[98:99] neg_lo:[0,1] neg_hi:[0,1]
	s_nop 0
	v_pk_mul_f32 v[98:99], v[76:77], s[40:41]
	v_pk_add_f32 v[100:101], v[84:85], v[92:93]
	v_pk_add_f32 v[84:85], v[84:85], v[92:93] neg_lo:[0,1] neg_hi:[0,1]
	v_pk_fma_f32 v[76:77], v[76:77], s[38:39], v[98:99] op_sel:[0,0,1] op_sel_hi:[1,0,0]
	v_pk_add_f32 v[98:99], v[78:79], v[90:91]
	v_pk_add_f32 v[90:91], v[78:79], v[90:91] neg_lo:[0,1] neg_hi:[0,1]
	v_pk_mul_f32 v[92:93], v[84:85], s[40:41]
	v_pk_add_f32 v[72:73], v[64:65], v[88:89] op_sel:[0,1] op_sel_hi:[1,0] neg_hi:[0,1]
	v_pk_add_f32 v[64:65], v[64:65], v[88:89] op_sel:[0,1] op_sel_hi:[1,0] neg_lo:[0,1]
	v_pk_add_f32 v[88:89], v[66:67], v[74:75]
	v_pk_add_f32 v[66:67], v[66:67], v[74:75] neg_lo:[0,1] neg_hi:[0,1]
	v_pk_fma_f32 v[84:85], v[84:85], s[38:39], v[92:93] op_sel:[0,0,1] op_sel_hi:[1,0,0] neg_lo:[1,0,0] neg_hi:[1,0,0]
	v_pk_mul_f32 v[74:75], v[66:67], s[40:41]
	s_nop 0
	v_pk_fma_f32 v[66:67], v[66:67], s[38:39], v[74:75] op_sel:[0,0,1] op_sel_hi:[1,0,0]
	v_pk_add_f32 v[74:75], v[68:69], v[80:81]
	v_pk_add_f32 v[92:93], v[70:71], v[82:83]
	v_pk_add_f32 v[70:71], v[70:71], v[82:83] neg_lo:[0,1] neg_hi:[0,1]
	v_pk_add_f32 v[78:79], v[86:87], v[90:91] op_sel:[0,1] op_sel_hi:[1,0] neg_hi:[0,1]
	v_pk_add_f32 v[86:87], v[86:87], v[90:91] op_sel:[0,1] op_sel_hi:[1,0] neg_lo:[0,1]
	v_pk_add_f32 v[90:91], v[76:77], v[84:85]
	v_pk_add_f32 v[84:85], v[76:77], v[84:85] neg_lo:[0,1] neg_hi:[0,1]
	v_pk_add_f32 v[80:81], v[68:69], v[80:81] neg_lo:[0,1] neg_hi:[0,1]
	v_pk_mul_f32 v[82:83], v[70:71], s[40:41]
	v_pk_add_f32 v[102:103], v[72:73], v[74:75]
	v_pk_add_f32 v[72:73], v[72:73], v[74:75] neg_lo:[0,1] neg_hi:[0,1]
	v_pk_add_f32 v[74:75], v[88:89], v[92:93]
	v_pk_fma_f32 v[70:71], v[70:71], s[38:39], v[82:83] op_sel:[0,0,1] op_sel_hi:[1,0,0] neg_lo:[1,0,0] neg_hi:[1,0,0]
	v_pk_add_f32 v[82:83], v[94:95], v[98:99]
	v_pk_add_f32 v[94:95], v[94:95], v[98:99] neg_lo:[0,1] neg_hi:[0,1]
	v_pk_add_f32 v[98:99], v[96:97], v[100:101]
	v_pk_add_f32 v[76:77], v[86:87], v[84:85] op_sel:[0,1] op_sel_hi:[1,0] neg_hi:[0,1]
	v_pk_add_f32 v[84:85], v[86:87], v[84:85] op_sel:[0,1] op_sel_hi:[1,0] neg_lo:[0,1]
	v_pk_add_f32 v[86:87], v[102:103], v[74:75]
	v_pk_add_f32 v[100:101], v[96:97], v[100:101] neg_lo:[0,1] neg_hi:[0,1]
	v_pk_add_f32 v[68:69], v[64:65], v[80:81] op_sel:[0,1] op_sel_hi:[1,0] neg_hi:[0,1]
	v_pk_add_f32 v[64:65], v[64:65], v[80:81] op_sel:[0,1] op_sel_hi:[1,0] neg_lo:[0,1]
	v_pk_add_f32 v[80:81], v[66:67], v[70:71]
	v_pk_add_f32 v[104:105], v[82:83], v[98:99]
	v_pk_add_f32 v[82:83], v[82:83], v[98:99] neg_lo:[0,1] neg_hi:[0,1]
	v_pk_add_f32 v[98:99], v[78:79], v[90:91]
	v_pk_mul_f32 v[4:5], v[4:5], v[86:87] op_sel:[0,1] op_sel_hi:[1,0]
	v_pk_add_f32 v[92:93], v[88:89], v[92:93] neg_lo:[0,1] neg_hi:[0,1]
	v_pk_add_f32 v[78:79], v[78:79], v[90:91] neg_lo:[0,1] neg_hi:[0,1]
	v_pk_add_f32 v[90:91], v[68:69], v[80:81]
	v_pk_fma_f32 v[4:5], v[6:7], v[86:87], v[4:5] op_sel_hi:[0,1,1]
	v_pk_mul_f32 v[6:7], v[8:9], v[98:99] op_sel:[1,1] op_sel_hi:[1,0] neg_lo:[1,0]
	v_pk_add_f32 v[70:71], v[66:67], v[70:71] neg_lo:[0,1] neg_hi:[0,1]
	v_pk_add_f32 v[96:97], v[94:95], v[100:101] op_sel:[0,1] op_sel_hi:[1,0] neg_hi:[0,1]
	v_pk_fma_f32 v[6:7], v[8:9], v[98:99], v[6:7] op_sel_hi:[0,1,1]
	v_pk_mul_f32 v[8:9], v[10:11], v[90:91] op_sel:[1,1] op_sel_hi:[1,0] neg_lo:[1,0]
	v_pk_add_f32 v[88:89], v[72:73], v[92:93] op_sel:[0,1] op_sel_hi:[1,0] neg_hi:[0,1]
	v_pk_fma_f32 v[8:9], v[10:11], v[90:91], v[8:9] op_sel_hi:[0,1,1]
	v_pk_mul_f32 v[10:11], v[12:13], v[96:97] op_sel:[1,1] op_sel_hi:[1,0] neg_lo:[1,0]
	v_pk_add_f32 v[66:67], v[64:65], v[70:71] op_sel:[0,1] op_sel_hi:[1,0] neg_hi:[0,1]
	v_pk_fma_f32 v[10:11], v[12:13], v[96:97], v[10:11] op_sel_hi:[0,1,1]
	v_pk_mul_f32 v[12:13], v[18:19], v[88:89] op_sel:[1,1] op_sel_hi:[1,0] neg_lo:[1,0]
	v_pk_add_f32 v[94:95], v[94:95], v[100:101] op_sel:[0,1] op_sel_hi:[1,0] neg_lo:[0,1]
	v_pk_add_f32 v[74:75], v[102:103], v[74:75] neg_lo:[0,1] neg_hi:[0,1]
	v_pk_add_f32 v[72:73], v[72:73], v[92:93] op_sel:[0,1] op_sel_hi:[1,0] neg_lo:[0,1]
	v_pk_add_f32 v[68:69], v[68:69], v[80:81] neg_lo:[0,1] neg_hi:[0,1]
	v_pk_add_f32 v[64:65], v[64:65], v[70:71] op_sel:[0,1] op_sel_hi:[1,0] neg_lo:[0,1]
	v_pk_fma_f32 v[12:13], v[18:19], v[88:89], v[12:13] op_sel_hi:[0,1,1]
	v_pk_mul_f32 v[14:15], v[24:25], v[76:77] op_sel:[1,1] op_sel_hi:[1,0] neg_lo:[1,0]
	v_pk_mul_f32 v[16:17], v[28:29], v[66:67] op_sel:[1,1] op_sel_hi:[1,0] neg_lo:[1,0]
	v_pk_mul_f32 v[18:19], v[32:33], v[82:83] op_sel:[1,1] op_sel_hi:[1,0] neg_lo:[1,0]
	v_pk_fma_f32 v[14:15], v[24:25], v[76:77], v[14:15] op_sel_hi:[0,1,1]
	v_pk_fma_f32 v[16:17], v[28:29], v[66:67], v[16:17] op_sel_hi:[0,1,1]
	v_pk_fma_f32 v[18:19], v[32:33], v[82:83], v[18:19] op_sel_hi:[0,1,1]
	v_pk_mul_f32 v[20:21], v[36:37], v[74:75] op_sel:[1,1] op_sel_hi:[1,0] neg_lo:[1,0]
	v_pk_mul_f32 v[22:23], v[40:41], v[78:79] op_sel:[1,1] op_sel_hi:[1,0] neg_lo:[1,0]
	v_pk_mul_f32 v[24:25], v[44:45], v[68:69] op_sel:[1,1] op_sel_hi:[1,0] neg_lo:[1,0]
	v_pk_mul_f32 v[26:27], v[48:49], v[94:95] op_sel:[1,1] op_sel_hi:[1,0] neg_lo:[1,0]
	v_pk_mul_f32 v[28:29], v[52:53], v[72:73] op_sel:[1,1] op_sel_hi:[1,0] neg_lo:[1,0]
	v_pk_mul_f32 v[30:31], v[56:57], v[84:85] op_sel:[1,1] op_sel_hi:[1,0] neg_lo:[1,0]
	v_pk_mul_f32 v[32:33], v[60:61], v[64:65] op_sel:[1,1] op_sel_hi:[1,0] neg_lo:[1,0]
	v_pk_fma_f32 v[20:21], v[36:37], v[74:75], v[20:21] op_sel_hi:[0,1,1]
	v_pk_fma_f32 v[22:23], v[40:41], v[78:79], v[22:23] op_sel_hi:[0,1,1]
	v_pk_fma_f32 v[24:25], v[44:45], v[68:69], v[24:25] op_sel_hi:[0,1,1]
	v_pk_fma_f32 v[26:27], v[48:49], v[94:95], v[26:27] op_sel_hi:[0,1,1]
	v_pk_fma_f32 v[28:29], v[52:53], v[72:73], v[28:29] op_sel_hi:[0,1,1]
	v_pk_fma_f32 v[30:31], v[56:57], v[84:85], v[30:31] op_sel_hi:[0,1,1]
	v_pk_fma_f32 v[32:33], v[60:61], v[64:65], v[32:33] op_sel_hi:[0,1,1]
	ds_write2_b64 v2, v[104:105], v[18:19] offset1:16
	ds_write2_b64 v2, v[10:11], v[26:27] offset0:33 offset1:49
	ds_write2_b64 v2, v[6:7], v[22:23] offset0:66 offset1:82
	ds_write2_b64 v2, v[14:15], v[30:31] offset0:99 offset1:115
	ds_write2_b64 v2, v[4:5], v[20:21] offset0:132 offset1:148
	ds_write2_b64 v2, v[12:13], v[28:29] offset0:165 offset1:181
	ds_write2_b64 v2, v[8:9], v[24:25] offset0:198 offset1:214
	ds_write2_b64 v2, v[16:17], v[32:33] offset0:231 offset1:247
	s_waitcnt lgkmcnt(0)
	s_barrier
	s_nop 0
	v_ashrrev_i32_e32 v2, 31, v142
	v_add_u32_sdwa v2, v142, v2 dst_sel:DWORD dst_unused:UNUSED_PAD src0_sel:DWORD src1_sel:BYTE_3
	v_ashrrev_i32_e32 v145, 8, v2
	v_mul_i32_i24_e32 v2, 0x100, v145
	v_sub_u32_e32 v144, v142, v2
	v_lshlrev_b32_e32 v2, 1, v144
	v_bfrev_b32_e32 v2, v2
	v_lshrrev_b32_e32 v2, 23, v2
	v_sub_u32_e32 v2, 0x200, v2
	v_bfrev_b32_e32 v2, v2
	v_lshrrev_b32_e32 v2, 19, v2
	v_lshlrev_b32_e32 v143, 13, v145
	v_and_b32_e32 v2, 0x1ff0, v2
	v_cmp_eq_u32_e32 vcc, 0, v144
	v_lshl_add_u32 v4, v144, 5, v143
	v_lshlrev_b32_e32 v5, 3, v4
	v_cndmask_b32_e64 v2, v2, 16, vcc
	v_ashrrev_i32_e32 v4, 2, v4
	v_or_b32_e32 v2, v2, v143
	v_add3_u32 v56, 0, v5, v4
	v_ashrrev_i32_e32 v4, 5, v2
	v_lshlrev_b32_e32 v2, 3, v2
	v_lshlrev_b32_e32 v4, 3, v4
	v_add3_u32 v2, 0, v2, v4
	ds_read2_b64 v[4:7], v56 offset1:1
	ds_read2_b64 v[8:11], v56 offset0:2 offset1:3
	ds_read2_b64 v[12:15], v2 offset1:1
	ds_read2_b64 v[16:19], v2 offset0:2 offset1:3
	ds_read2_b64 v[20:23], v56 offset0:4 offset1:5
	ds_read2_b64 v[24:27], v56 offset0:6 offset1:7
	ds_read2_b64 v[28:31], v2 offset0:4 offset1:5
	ds_read2_b64 v[32:35], v2 offset0:6 offset1:7
	ds_read2_b64 v[36:39], v56 offset0:8 offset1:9
	ds_read2_b64 v[40:43], v56 offset0:10 offset1:11
	ds_read2_b64 v[44:47], v2 offset0:8 offset1:9
	ds_read2_b64 v[52:55], v2 offset0:10 offset1:11
	ds_read2_b64 v[48:51], v56 offset0:12 offset1:13
	ds_read2_b64 v[56:59], v56 offset0:14 offset1:15
	ds_read2_b64 v[62:65], v2 offset0:12 offset1:13
	ds_read2_b64 v[74:77], v2 offset0:14 offset1:15
	s_waitcnt lgkmcnt(7)
	v_pk_add_f32 v[60:61], v[4:5], v[36:37]
	v_pk_add_f32 v[4:5], v[4:5], v[36:37] neg_lo:[0,1] neg_hi:[0,1]
	v_pk_add_f32 v[36:37], v[6:7], v[38:39]
	v_pk_add_f32 v[6:7], v[6:7], v[38:39] neg_lo:[0,1] neg_hi:[0,1]
	s_waitcnt lgkmcnt(3)
	v_pk_add_f32 v[66:67], v[22:23], v[50:51]
	v_pk_mul_f32 v[38:39], v[6:7], s[24:25]
	v_pk_add_f32 v[22:23], v[22:23], v[50:51] neg_lo:[0,1] neg_hi:[0,1]
	v_pk_fma_f32 v[6:7], v[6:7], s[22:23], v[38:39] op_sel:[0,0,1] op_sel_hi:[1,0,0]
	v_pk_add_f32 v[38:39], v[8:9], v[40:41]
	v_pk_add_f32 v[8:9], v[8:9], v[40:41] neg_lo:[0,1] neg_hi:[0,1]
	v_pk_mul_f32 v[50:51], v[22:23], s[44:45]
	v_pk_mul_f32 v[40:41], v[8:9], s[40:41]
	v_pk_fma_f32 v[22:23], v[22:23], s[50:51], v[50:51] op_sel:[0,0,1] op_sel_hi:[1,0,0] neg_lo:[1,0,0] neg_hi:[1,0,0]
	v_pk_fma_f32 v[8:9], v[8:9], s[38:39], v[40:41] op_sel:[0,0,1] op_sel_hi:[1,0,0]
	v_pk_add_f32 v[40:41], v[10:11], v[42:43]
	v_pk_add_f32 v[10:11], v[10:11], v[42:43] neg_lo:[0,1] neg_hi:[0,1]
	s_waitcnt lgkmcnt(2)
	v_pk_add_f32 v[50:51], v[24:25], v[56:57]
	v_pk_add_f32 v[24:25], v[24:25], v[56:57] neg_lo:[0,1] neg_hi:[0,1]
	v_pk_mul_f32 v[42:43], v[10:11], s[44:45]
	v_pk_mul_f32 v[56:57], v[24:25], s[40:41]
	v_pk_fma_f32 v[10:11], v[10:11], s[50:51], v[42:43] op_sel:[0,0,1] op_sel_hi:[1,0,0]
	v_pk_add_f32 v[42:43], v[20:21], v[48:49]
	v_pk_add_f32 v[48:49], v[20:21], v[48:49] neg_lo:[0,1] neg_hi:[0,1]
	v_pk_fma_f32 v[24:25], v[24:25], s[38:39], v[56:57] op_sel:[0,0,1] op_sel_hi:[1,0,0] neg_lo:[1,0,0] neg_hi:[1,0,0]
	v_pk_add_f32 v[56:57], v[26:27], v[58:59]
	v_pk_add_f32 v[26:27], v[26:27], v[58:59] neg_lo:[0,1] neg_hi:[0,1]
	s_nop 0
	v_pk_mul_f32 v[58:59], v[26:27], s[24:25]
	v_pk_add_f32 v[68:69], v[40:41], v[56:57]
	v_pk_add_f32 v[40:41], v[40:41], v[56:57] neg_lo:[0,1] neg_hi:[0,1]
	v_pk_fma_f32 v[26:27], v[26:27], s[22:23], v[58:59] op_sel:[0,0,1] op_sel_hi:[1,0,0] neg_lo:[1,0,0] neg_hi:[1,0,0]
	v_pk_mul_f32 v[56:57], v[40:41], s[40:41]
	v_pk_add_f32 v[20:21], v[4:5], v[48:49] op_sel:[0,1] op_sel_hi:[1,0] neg_hi:[0,1]
	v_pk_add_f32 v[4:5], v[4:5], v[48:49] op_sel:[0,1] op_sel_hi:[1,0] neg_lo:[0,1]
	v_pk_add_f32 v[48:49], v[6:7], v[22:23]
	v_pk_add_f32 v[6:7], v[6:7], v[22:23] neg_lo:[0,1] neg_hi:[0,1]
	v_pk_fma_f32 v[40:41], v[40:41], s[38:39], v[56:57] op_sel:[0,0,1] op_sel_hi:[1,0,0] neg_lo:[1,0,0] neg_hi:[1,0,0]
	v_pk_mul_f32 v[22:23], v[6:7], s[40:41]
	v_pk_add_f32 v[56:57], v[10:11], v[26:27]
	v_pk_add_f32 v[10:11], v[10:11], v[26:27] neg_lo:[0,1] neg_hi:[0,1]
	v_pk_add_f32 v[58:59], v[60:61], v[42:43]
	v_pk_add_f32 v[42:43], v[60:61], v[42:43] neg_lo:[0,1] neg_hi:[0,1]
	v_pk_add_f32 v[60:61], v[36:37], v[66:67]
	v_pk_add_f32 v[36:37], v[36:37], v[66:67] neg_lo:[0,1] neg_hi:[0,1]
	v_pk_fma_f32 v[6:7], v[6:7], s[38:39], v[22:23] op_sel:[0,0,1] op_sel_hi:[1,0,0]
	v_pk_add_f32 v[22:23], v[8:9], v[24:25]
	v_pk_add_f32 v[24:25], v[8:9], v[24:25] neg_lo:[0,1] neg_hi:[0,1]
	v_pk_mul_f32 v[26:27], v[10:11], s[40:41]
	v_pk_mul_f32 v[66:67], v[36:37], s[40:41]
	v_pk_fma_f32 v[10:11], v[10:11], s[38:39], v[26:27] op_sel:[0,0,1] op_sel_hi:[1,0,0] neg_lo:[1,0,0] neg_hi:[1,0,0]
	v_pk_fma_f32 v[36:37], v[36:37], s[38:39], v[66:67] op_sel:[0,0,1] op_sel_hi:[1,0,0]
	v_pk_add_f32 v[66:67], v[38:39], v[50:51]
	v_pk_add_f32 v[8:9], v[4:5], v[24:25] op_sel:[0,1] op_sel_hi:[1,0] neg_hi:[0,1]
	v_pk_add_f32 v[4:5], v[4:5], v[24:25] op_sel:[0,1] op_sel_hi:[1,0] neg_lo:[0,1]
	v_pk_add_f32 v[24:25], v[6:7], v[10:11]
	v_pk_add_f32 v[10:11], v[6:7], v[10:11] neg_lo:[0,1] neg_hi:[0,1]
	v_pk_add_f32 v[26:27], v[58:59], v[66:67]
	v_pk_add_f32 v[58:59], v[58:59], v[66:67] neg_lo:[0,1] neg_hi:[0,1]
	v_pk_add_f32 v[66:67], v[60:61], v[68:69]
	v_pk_add_f32 v[68:69], v[60:61], v[68:69] neg_lo:[0,1] neg_hi:[0,1]
	v_pk_add_f32 v[60:61], v[4:5], v[10:11] op_sel:[0,1] op_sel_hi:[1,0] neg_hi:[0,1]
	v_pk_add_f32 v[90:91], v[4:5], v[10:11] op_sel:[0,1] op_sel_hi:[1,0] neg_lo:[0,1]
	v_pk_add_f32 v[10:11], v[14:15], v[46:47] neg_lo:[0,1] neg_hi:[0,1]
	v_pk_add_f32 v[50:51], v[38:39], v[50:51] neg_lo:[0,1] neg_hi:[0,1]
	v_pk_add_f32 v[84:85], v[58:59], v[68:69] op_sel:[0,1] op_sel_hi:[1,0] neg_hi:[0,1]
	v_pk_add_f32 v[86:87], v[58:59], v[68:69] op_sel:[0,1] op_sel_hi:[1,0] neg_lo:[0,1]
	v_pk_add_f32 v[82:83], v[8:9], v[24:25]
	v_pk_add_f32 v[68:69], v[8:9], v[24:25] neg_lo:[0,1] neg_hi:[0,1]
	v_pk_add_f32 v[4:5], v[12:13], v[44:45]
	v_pk_add_f32 v[6:7], v[12:13], v[44:45] neg_lo:[0,1] neg_hi:[0,1]
	v_pk_add_f32 v[8:9], v[14:15], v[46:47]
	v_pk_mul_f32 v[12:13], v[10:11], s[24:25]
	v_pk_add_f32 v[14:15], v[16:17], v[52:53] neg_lo:[0,1] neg_hi:[0,1]
	v_pk_add_f32 v[70:71], v[20:21], v[22:23]
	v_pk_add_f32 v[20:21], v[20:21], v[22:23] neg_lo:[0,1] neg_hi:[0,1]
	v_pk_add_f32 v[22:23], v[48:49], v[56:57]
	v_pk_add_f32 v[48:49], v[48:49], v[56:57] neg_lo:[0,1] neg_hi:[0,1]
	v_pk_fma_f32 v[10:11], v[10:11], s[22:23], v[12:13] op_sel:[0,0,1] op_sel_hi:[1,0,0]
	v_pk_add_f32 v[12:13], v[16:17], v[52:53]
	v_pk_mul_f32 v[16:17], v[14:15], s[40:41]
	v_pk_add_f32 v[38:39], v[42:43], v[50:51] op_sel:[0,1] op_sel_hi:[1,0] neg_hi:[0,1]
	v_pk_add_f32 v[42:43], v[42:43], v[50:51] op_sel:[0,1] op_sel_hi:[1,0] neg_lo:[0,1]
	v_pk_add_f32 v[50:51], v[36:37], v[40:41]
	v_xor_b32_e32 v57, 0x80000000, v48
	v_mov_b32_e32 v56, v49
	v_pk_fma_f32 v[14:15], v[14:15], s[38:39], v[16:17] op_sel:[0,0,1] op_sel_hi:[1,0,0]
	v_pk_add_f32 v[16:17], v[18:19], v[54:55]
	v_pk_add_f32 v[18:19], v[18:19], v[54:55] neg_lo:[0,1] neg_hi:[0,1]
	v_pk_add_f32 v[130:131], v[26:27], v[66:67]
	v_pk_add_f32 v[92:93], v[26:27], v[66:67] neg_lo:[0,1] neg_hi:[0,1]
	v_pk_add_f32 v[88:89], v[38:39], v[50:51]
	v_pk_add_f32 v[72:73], v[38:39], v[50:51] neg_lo:[0,1] neg_hi:[0,1]
	v_pk_add_f32 v[96:97], v[70:71], v[22:23]
	v_pk_add_f32 v[50:51], v[70:71], v[22:23] neg_lo:[0,1] neg_hi:[0,1]
	v_pk_add_f32 v[66:67], v[20:21], v[56:57]
	v_pk_add_f32 v[80:81], v[20:21], v[56:57] neg_lo:[0,1] neg_hi:[0,1]
	v_pk_mul_f32 v[20:21], v[18:19], s[44:45]
	s_waitcnt lgkmcnt(1)
	v_pk_add_f32 v[24:25], v[28:29], v[62:63] neg_lo:[0,1] neg_hi:[0,1]
	v_pk_add_f32 v[26:27], v[30:31], v[64:65] neg_lo:[0,1] neg_hi:[0,1]
	v_pk_fma_f32 v[18:19], v[18:19], s[50:51], v[20:21] op_sel:[0,0,1] op_sel_hi:[1,0,0]
	v_pk_add_f32 v[20:21], v[28:29], v[62:63]
	v_pk_add_f32 v[22:23], v[30:31], v[64:65]
	v_pk_mul_f32 v[28:29], v[26:27], s[44:45]
	s_waitcnt lgkmcnt(0)
	v_pk_add_f32 v[30:31], v[32:33], v[74:75] neg_lo:[0,1] neg_hi:[0,1]
	v_pk_fma_f32 v[26:27], v[26:27], s[50:51], v[28:29] op_sel:[0,0,1] op_sel_hi:[1,0,0] neg_lo:[1,0,0] neg_hi:[1,0,0]
	v_pk_add_f32 v[28:29], v[32:33], v[74:75]
	v_pk_mul_f32 v[32:33], v[30:31], s[40:41]
	v_pk_add_f32 v[36:37], v[36:37], v[40:41] neg_lo:[0,1] neg_hi:[0,1]
	v_pk_fma_f32 v[30:31], v[30:31], s[38:39], v[32:33] op_sel:[0,0,1] op_sel_hi:[1,0,0] neg_lo:[1,0,0] neg_hi:[1,0,0]
	v_pk_add_f32 v[32:33], v[34:35], v[76:77]
	v_pk_add_f32 v[34:35], v[34:35], v[76:77] neg_lo:[0,1] neg_hi:[0,1]
	v_xor_b32_e32 v41, 0x80000000, v36
	v_mov_b32_e32 v40, v37
	v_pk_mul_f32 v[36:37], v[34:35], s[24:25]
	v_mov_b32_e32 v2, v130
	v_pk_fma_f32 v[34:35], v[34:35], s[22:23], v[36:37] op_sel:[0,0,1] op_sel_hi:[1,0,0] neg_lo:[1,0,0] neg_hi:[1,0,0]
	v_pk_add_f32 v[36:37], v[4:5], v[20:21]
	v_pk_add_f32 v[4:5], v[4:5], v[20:21] neg_lo:[0,1] neg_hi:[0,1]
	v_pk_add_f32 v[20:21], v[8:9], v[22:23]
	v_pk_add_f32 v[8:9], v[8:9], v[22:23] neg_lo:[0,1] neg_hi:[0,1]
	v_cmp_ne_u32_e64 s[0:1], 0, v144
	v_pk_mul_f32 v[22:23], v[8:9], s[40:41]
	v_pk_add_f32 v[78:79], v[42:43], v[40:41]
	v_pk_fma_f32 v[8:9], v[8:9], s[38:39], v[22:23] op_sel:[0,0,1] op_sel_hi:[1,0,0]
	v_pk_add_f32 v[22:23], v[12:13], v[28:29]
	v_pk_add_f32 v[28:29], v[12:13], v[28:29] neg_lo:[0,1] neg_hi:[0,1]
	v_pk_add_f32 v[94:95], v[42:43], v[40:41] neg_lo:[0,1] neg_hi:[0,1]
	v_pk_add_f32 v[12:13], v[16:17], v[32:33]
	v_pk_add_f32 v[16:17], v[16:17], v[32:33] neg_lo:[0,1] neg_hi:[0,1]
	s_nop 0
	v_pk_mul_f32 v[32:33], v[16:17], s[40:41]
	s_nop 0
	v_pk_fma_f32 v[16:17], v[16:17], s[38:39], v[32:33] op_sel:[0,0,1] op_sel_hi:[1,0,0] neg_lo:[1,0,0] neg_hi:[1,0,0]
	v_pk_add_f32 v[32:33], v[6:7], v[24:25] op_sel:[0,1] op_sel_hi:[1,0] neg_hi:[0,1]
	v_pk_add_f32 v[6:7], v[6:7], v[24:25] op_sel:[0,1] op_sel_hi:[1,0] neg_lo:[0,1]
	v_pk_add_f32 v[24:25], v[10:11], v[26:27]
	v_pk_add_f32 v[10:11], v[10:11], v[26:27] neg_lo:[0,1] neg_hi:[0,1]
	s_nop 0
	v_pk_mul_f32 v[26:27], v[10:11], s[40:41]
	s_nop 0
	v_pk_fma_f32 v[10:11], v[10:11], s[38:39], v[26:27] op_sel:[0,0,1] op_sel_hi:[1,0,0]
	v_pk_add_f32 v[26:27], v[14:15], v[30:31]
	v_pk_add_f32 v[30:31], v[14:15], v[30:31] neg_lo:[0,1] neg_hi:[0,1]
	s_nop 0
	v_pk_add_f32 v[14:15], v[18:19], v[34:35]
	v_pk_add_f32 v[18:19], v[18:19], v[34:35] neg_lo:[0,1] neg_hi:[0,1]
	s_nop 0
	v_pk_mul_f32 v[34:35], v[18:19], s[40:41]
	s_nop 0
	v_pk_fma_f32 v[18:19], v[18:19], s[38:39], v[34:35] op_sel:[0,0,1] op_sel_hi:[1,0,0] neg_lo:[1,0,0] neg_hi:[1,0,0]
	v_pk_add_f32 v[34:35], v[36:37], v[22:23]
	v_pk_add_f32 v[22:23], v[36:37], v[22:23] neg_lo:[0,1] neg_hi:[0,1]
	v_pk_add_f32 v[36:37], v[20:21], v[12:13]
	v_pk_add_f32 v[12:13], v[20:21], v[12:13] neg_lo:[0,1] neg_hi:[0,1]
	v_pk_add_f32 v[98:99], v[34:35], v[36:37]
	v_xor_b32_e32 v21, 0x80000000, v12
	v_mov_b32_e32 v20, v13
	v_pk_add_f32 v[12:13], v[4:5], v[28:29] op_sel:[0,1] op_sel_hi:[1,0] neg_hi:[0,1]
	v_pk_add_f32 v[4:5], v[4:5], v[28:29] op_sel:[0,1] op_sel_hi:[1,0] neg_lo:[0,1]
	v_pk_add_f32 v[28:29], v[8:9], v[16:17]
	v_pk_add_f32 v[8:9], v[8:9], v[16:17] neg_lo:[0,1] neg_hi:[0,1]
	v_pk_add_f32 v[100:101], v[34:35], v[36:37] neg_lo:[0,1] neg_hi:[0,1]
	v_xor_b32_e32 v17, 0x80000000, v8
	v_mov_b32_e32 v16, v9
	v_pk_add_f32 v[8:9], v[32:33], v[26:27]
	v_pk_add_f32 v[26:27], v[32:33], v[26:27] neg_lo:[0,1] neg_hi:[0,1]
	v_pk_add_f32 v[32:33], v[24:25], v[14:15]
	v_pk_add_f32 v[14:15], v[24:25], v[14:15] neg_lo:[0,1] neg_hi:[0,1]
	v_pk_add_f32 v[102:103], v[22:23], v[20:21]
	v_xor_b32_e32 v25, 0x80000000, v14
	v_mov_b32_e32 v24, v15
	v_pk_add_f32 v[14:15], v[6:7], v[30:31] op_sel:[0,1] op_sel_hi:[1,0] neg_hi:[0,1]
	v_pk_add_f32 v[6:7], v[6:7], v[30:31] op_sel:[0,1] op_sel_hi:[1,0] neg_lo:[0,1]
	v_pk_add_f32 v[30:31], v[10:11], v[18:19]
	v_pk_add_f32 v[10:11], v[10:11], v[18:19] neg_lo:[0,1] neg_hi:[0,1]
	v_pk_add_f32 v[104:105], v[22:23], v[20:21] neg_lo:[0,1] neg_hi:[0,1]
	v_xor_b32_e32 v19, 0x80000000, v10
	v_mov_b32_e32 v18, v11
	v_pk_add_f32 v[106:107], v[12:13], v[28:29]
	v_pk_add_f32 v[108:109], v[12:13], v[28:29] neg_lo:[0,1] neg_hi:[0,1]
	v_pk_add_f32 v[110:111], v[4:5], v[16:17]
	v_pk_add_f32 v[112:113], v[4:5], v[16:17] neg_lo:[0,1] neg_hi:[0,1]
	v_pk_add_f32 v[114:115], v[8:9], v[32:33]
	v_pk_add_f32 v[116:117], v[8:9], v[32:33] neg_lo:[0,1] neg_hi:[0,1]
	v_pk_add_f32 v[118:119], v[26:27], v[24:25]
	v_pk_add_f32 v[120:121], v[26:27], v[24:25] neg_lo:[0,1] neg_hi:[0,1]
	v_pk_add_f32 v[122:123], v[14:15], v[30:31]
	v_pk_add_f32 v[124:125], v[14:15], v[30:31] neg_lo:[0,1] neg_hi:[0,1]
	v_pk_add_f32 v[126:127], v[6:7], v[18:19]
	v_pk_add_f32 v[128:129], v[6:7], v[18:19] neg_lo:[0,1] neg_hi:[0,1]
	v_mov_b32_e32 v4, v131
	v_mov_b32_e32 v5, v3
	v_mov_b64_e32 v[6:7], v[2:3]
	s_and_saveexec_b64 s[50:51], s[0:1]
	s_xor_b64 s[0:1], exec, s[50:51]
	s_cbranch_execz .LBB0_576
	v_pk_add_f32 v[4:5], v[96:97], v[112:113]
	v_pk_add_f32 v[24:25], v[96:97], v[112:113] neg_lo:[0,1] neg_hi:[0,1]
	v_pk_add_f32 v[148:149], v[130:131], v[128:129]
	v_pk_add_f32 v[8:9], v[130:131], v[128:129] neg_lo:[0,1] neg_hi:[0,1]
	v_pk_add_f32 v[128:129], v[126:127], v[92:93]
	v_pk_add_f32 v[10:11], v[126:127], v[92:93] neg_lo:[0,1] neg_hi:[0,1]
	v_pk_add_f32 v[92:93], v[84:85], v[124:125]
	v_pk_add_f32 v[12:13], v[84:85], v[124:125] neg_lo:[0,1] neg_hi:[0,1]
	v_pk_add_f32 v[84:85], v[122:123], v[86:87]
	v_pk_add_f32 v[14:15], v[122:123], v[86:87] neg_lo:[0,1] neg_hi:[0,1]
	v_pk_add_f32 v[86:87], v[88:89], v[120:121]
	v_pk_add_f32 v[16:17], v[88:89], v[120:121] neg_lo:[0,1] neg_hi:[0,1]
	v_pk_add_f32 v[88:89], v[118:119], v[72:73]
	v_pk_add_f32 v[18:19], v[118:119], v[72:73] neg_lo:[0,1] neg_hi:[0,1]
	v_pk_add_f32 v[72:73], v[78:79], v[116:117]
	v_pk_add_f32 v[20:21], v[78:79], v[116:117] neg_lo:[0,1] neg_hi:[0,1]
	v_pk_add_f32 v[78:79], v[114:115], v[94:95]
	v_pk_add_f32 v[22:23], v[114:115], v[94:95] neg_lo:[0,1] neg_hi:[0,1]
	v_mov_b32_e32 v6, v4
	v_mov_b32_e32 v7, v25
	v_pk_mov_b32 v[4:5], v[4:5], v[24:25] op_sel:[1,0]
	v_pk_add_f32 v[94:95], v[110:111], v[50:51]
	v_pk_add_f32 v[24:25], v[110:111], v[50:51] neg_lo:[0,1] neg_hi:[0,1]
	v_pk_add_f32 v[50:51], v[66:67], v[108:109]
	v_pk_add_f32 v[26:27], v[66:67], v[108:109] neg_lo:[0,1] neg_hi:[0,1]
	v_pk_add_f32 v[66:67], v[106:107], v[80:81]
	v_pk_add_f32 v[28:29], v[106:107], v[80:81] neg_lo:[0,1] neg_hi:[0,1]
	v_pk_add_f32 v[80:81], v[82:83], v[104:105]
	v_pk_add_f32 v[30:31], v[82:83], v[104:105] neg_lo:[0,1] neg_hi:[0,1]
	v_pk_add_f32 v[82:83], v[102:103], v[68:69]
	v_pk_add_f32 v[32:33], v[102:103], v[68:69] neg_lo:[0,1] neg_hi:[0,1]
	v_pk_add_f32 v[68:69], v[60:61], v[100:101]
	v_pk_add_f32 v[34:35], v[60:61], v[100:101] neg_lo:[0,1] neg_hi:[0,1]
	v_pk_add_f32 v[60:61], v[98:99], v[90:91]
	v_pk_add_f32 v[36:37], v[98:99], v[90:91] neg_lo:[0,1] neg_hi:[0,1]
	v_pk_mul_f32 v[6:7], v[6:7], 0.5 op_sel_hi:[1,0]
	v_pk_mul_f32 v[4:5], v[4:5], s[46:47]
	v_mov_b32_e32 v39, v8
	v_mov_b32_e32 v38, v149
	v_mov_b32_e32 v41, v10
	v_mov_b32_e32 v40, v129
	v_mov_b32_e32 v43, v12
	v_mov_b32_e32 v42, v93
	v_mov_b32_e32 v45, v14
	v_mov_b32_e32 v44, v85
	v_mov_b32_e32 v47, v16
	v_mov_b32_e32 v46, v87
	v_mov_b32_e32 v49, v18
	v_mov_b32_e32 v48, v89
	v_mov_b32_e32 v53, v20
	v_mov_b32_e32 v52, v73
	v_mov_b32_e32 v55, v22
	v_mov_b32_e32 v54, v79
	v_mov_b32_e32 v57, v24
	v_mov_b32_e32 v56, v95
	v_mov_b32_e32 v59, v26
	v_mov_b32_e32 v58, v51
	v_mov_b32_e32 v63, v28
	v_mov_b32_e32 v62, v67
	v_mov_b32_e32 v65, v30
	v_mov_b32_e32 v64, v81
	v_mov_b32_e32 v71, v32
	v_mov_b32_e32 v70, v83
	v_mov_b32_e32 v75, v34
	v_mov_b32_e32 v74, v69
	v_mov_b32_e32 v77, v36
	v_mov_b32_e32 v76, v61
	v_mov_b32_e32 v8, v148
	v_mov_b32_e32 v10, v128
	v_mov_b32_e32 v12, v92
	v_mov_b32_e32 v14, v84
	v_mov_b32_e32 v16, v86
	v_mov_b32_e32 v18, v88
	v_mov_b32_e32 v20, v72
	v_mov_b32_e32 v22, v78
	v_mov_b32_e32 v24, v94
	v_mov_b32_e32 v26, v50
	v_mov_b32_e32 v28, v66
	v_mov_b32_e32 v30, v80
	v_mov_b32_e32 v32, v82
	v_mov_b32_e32 v34, v68
	v_mov_b32_e32 v36, v60
